# plus: GEMM K-loops: next k-step's LDS staging writes and fragment reads issued under the current k-step's last 4 MFMAs (software pipelining inside each barrier interval)
# speedup vs baseline: 1.0325x; 1.0063x over previous
; template <bool trans>
; DI void gemm_core(const GTile& tl, const GTile& nx, bool has_next  , bool chain  , bool pre, u32x4 (&ra)[4], u32x4 (&rb)[4], char* smem, f32x16 (&acc)[2][4]) {
;     ...
;   const int nk = K / 64;
;   if (!pre) { G_LOAD(0); G_STORE(0); G_LOAD(1); }
;   for (int kt = 0; kt < nk; ++kt) {
;     __syncthreads();
;     G_COMPUTE(kt & 1, kt);
;   }
.LBB0_103:
	v_lshl_add_u64 v[190:191], s[0:1], 0, v[192:193]
	v_lshl_add_u64 v[188:189], s[6:7], 0, v[192:193]
	s_waitcnt lgkmcnt(0)
	s_barrier
	global_load_dwordx4 v[218:221], v[190:191], off offset:256
	global_load_dwordx4 v[222:225], v[188:189], off offset:256
	s_lshr_b32 s1, s33, 1
	s_and_b32 s0, s33, 0xc0
	v_and_b32_e32 v10, 31, v8
	s_and_b32 s1, s1, 0xfffff80
	v_or_b32_e32 v12, s1, v10
	v_or_b32_e32 v10, s0, v10
	v_add3_u32 v215, 16, v11, v9
	v_lshrrev_b32_e32 v8, 1, v8
	v_mul_u32_u24_e32 v242, 0x90, v10
	v_and_b32_e32 v243, 16, v8
	v_add_u32_e32 v209, 0x12000, v215
	v_mul_lo_u32 v208, v12, s45
	v_add3_u32 v205, 16, v242, v243
	v_add_u32_e32 v210, 0x1b000, v215
	ds_write_b128 v209, v[0:3]
	s_waitcnt vmcnt(6)
	ds_write_b128 v210, v[4:7]
	v_add3_u32 v204, 16, v208, v243
	ds_read_b128 v[0:3], v205 offset:36864
	ds_read_b128 v[4:7], v205 offset:41472
	ds_read_b128 v[8:11], v204
	ds_read_b128 v[12:15], v204 offset:4608
	v_lshl_add_u64 v[184:185], v[190:191], 0, s[42:43]
	v_lshl_add_u64 v[186:187], s[28:29], 0, v[192:193]
	v_lshl_add_u64 v[194:195], v[190:191], 0, s[34:35]
	v_lshl_add_u64 v[196:197], s[26:27], 0, v[192:193]
	s_setprio 1
	s_waitcnt lgkmcnt(1)
	v_mfma_f32_32x32x16_bf16 v[112:127], v[8:11], v[0:3], 0
	v_mfma_f32_32x32x16_bf16 v[48:63], v[8:11], v[4:7], 0
	s_waitcnt lgkmcnt(0)
	v_mfma_f32_32x32x16_bf16 v[96:111], v[12:15], v[0:3], 0
	v_mfma_f32_32x32x16_bf16 v[32:47], v[12:15], v[4:7], 0
	ds_read_b128 v[8:11], v204 offset:9216
	ds_read_b128 v[12:15], v204 offset:13824
	s_waitcnt lgkmcnt(1)
	v_mfma_f32_32x32x16_bf16 v[80:95], v[8:11], v[0:3], 0
	v_mfma_f32_32x32x16_bf16 v[16:31], v[8:11], v[4:7], 0
	s_waitcnt lgkmcnt(0)
	v_mfma_f32_32x32x16_bf16 v[64:79], v[12:15], v[0:3], 0
	v_mfma_f32_32x32x16_bf16 v[0:15], v[12:15], v[4:7], 0
	s_setprio 0
	global_load_dwordx4 v[226:229], v[194:195], off offset:256
	global_load_dwordx4 v[230:233], v[196:197], off offset:256
	v_add_u32_e32 v212, 0x14400, v215
	v_add_u32_e32 v211, 0x1d400, v215
	ds_write_b128 v212, v[176:179]
	s_waitcnt vmcnt(7)
	ds_write_b128 v211, v[180:183]
	ds_read_b128 v[176:179], v205 offset:36896
	ds_read_b128 v[180:183], v205 offset:41504
	ds_read_b128 v[198:201], v204 offset:32
	ds_read_b128 v[234:237], v204 offset:4640
	s_setprio 1
	s_waitcnt lgkmcnt(1)
	v_mfma_f32_32x32x16_bf16 v[112:127], v[198:201], v[176:179], v[112:127]
	v_mfma_f32_32x32x16_bf16 v[48:63], v[198:201], v[180:183], v[48:63]
	s_waitcnt lgkmcnt(0)
	v_mfma_f32_32x32x16_bf16 v[96:111], v[234:237], v[176:179], v[96:111]
	v_mfma_f32_32x32x16_bf16 v[32:47], v[234:237], v[180:183], v[32:47]
	ds_read_b128 v[198:201], v204 offset:9248
	ds_read_b128 v[234:237], v204 offset:13856
	s_waitcnt lgkmcnt(1)
	v_mfma_f32_32x32x16_bf16 v[80:95], v[198:201], v[176:179], v[80:95]
	v_mfma_f32_32x32x16_bf16 v[16:31], v[198:201], v[180:183], v[16:31]
	s_waitcnt lgkmcnt(0)
	v_mfma_f32_32x32x16_bf16 v[64:79], v[234:237], v[176:179], v[64:79]
	v_mfma_f32_32x32x16_bf16 v[0:15], v[234:237], v[180:183], v[0:15]
	s_setprio 0
	global_load_dwordx4 v[176:179], v[184:185], off offset:256
	global_load_dwordx4 v[180:183], v[186:187], off offset:256
	v_add_u32_e32 v214, 0x16800, v215
	v_add_u32_e32 v213, 0x1f800, v215
	ds_write_b128 v214, v[168:171]
	s_waitcnt vmcnt(8)
	ds_write_b128 v213, v[172:175]
	ds_read_b128 v[168:171], v205 offset:36928
	ds_read_b128 v[172:175], v205 offset:41536
	ds_read_b128 v[198:201], v204 offset:64
	ds_read_b128 v[234:237], v204 offset:4672
	s_setprio 1
	s_waitcnt lgkmcnt(1)
	v_mfma_f32_32x32x16_bf16 v[112:127], v[198:201], v[168:171], v[112:127]
	v_mfma_f32_32x32x16_bf16 v[48:63], v[198:201], v[172:175], v[48:63]
	s_waitcnt lgkmcnt(0)
	v_mfma_f32_32x32x16_bf16 v[96:111], v[234:237], v[168:171], v[96:111]
	v_mfma_f32_32x32x16_bf16 v[32:47], v[234:237], v[172:175], v[32:47]
	ds_read_b128 v[198:201], v204 offset:9280
	ds_read_b128 v[234:237], v204 offset:13888
	s_waitcnt lgkmcnt(1)
	v_mfma_f32_32x32x16_bf16 v[80:95], v[198:201], v[168:171], v[80:95]
	v_mfma_f32_32x32x16_bf16 v[16:31], v[198:201], v[172:175], v[16:31]
	s_waitcnt lgkmcnt(0)
	v_mfma_f32_32x32x16_bf16 v[64:79], v[234:237], v[168:171], v[64:79]
	v_mfma_f32_32x32x16_bf16 v[0:15], v[234:237], v[172:175], v[0:15]
	s_setprio 0
	v_add_co_u32_e32 v198, vcc, s44, v190
	v_add_u32_e32 v217, 0x18c00, v215
	s_nop 0
	v_addc_co_u32_e32 v199, vcc, 0, v191, vcc
	v_add_co_u32_e32 v200, vcc, s44, v188
	v_add_u32_e32 v216, 0x21c00, v215
	s_nop 0
	v_addc_co_u32_e32 v201, vcc, 0, v189, vcc
	global_load_dwordx4 v[168:171], v[198:199], off offset:256
	global_load_dwordx4 v[172:175], v[200:201], off offset:256
	s_waitcnt vmcnt(8)
	ds_write_b128 v217, v[164:167]
	ds_write_b128 v216, v[160:163]
	ds_read_b128 v[160:163], v205 offset:36960
	ds_read_b128 v[164:167], v205 offset:41568
	ds_read_b128 v[234:237], v204 offset:96
	ds_read_b128 v[238:241], v204 offset:4704
	s_setprio 1
	s_waitcnt lgkmcnt(1)
	v_mfma_f32_32x32x16_bf16 v[112:127], v[234:237], v[160:163], v[112:127]
	v_mfma_f32_32x32x16_bf16 v[48:63], v[234:237], v[164:167], v[48:63]
	s_waitcnt lgkmcnt(0)
	v_mfma_f32_32x32x16_bf16 v[96:111], v[238:241], v[160:163], v[96:111]
	v_mfma_f32_32x32x16_bf16 v[32:47], v[238:241], v[164:167], v[32:47]
	ds_read_b128 v[234:237], v204 offset:9312
	ds_read_b128 v[238:241], v204 offset:13920
	s_waitcnt lgkmcnt(1)
	v_mfma_f32_32x32x16_bf16 v[80:95], v[234:237], v[160:163], v[80:95]
	v_mfma_f32_32x32x16_bf16 v[16:31], v[234:237], v[164:167], v[16:31]
	s_waitcnt lgkmcnt(0)
	v_mfma_f32_32x32x16_bf16 v[64:79], v[238:241], v[160:163], v[64:79]
	v_mfma_f32_32x32x16_bf16 v[0:15], v[238:241], v[164:167], v[0:15]
	s_setprio 0
	s_barrier
	global_load_dwordx4 v[160:163], v[190:191], off offset:384
	global_load_dwordx4 v[164:167], v[188:189], off offset:384
	s_add_i32 s0, 16, 0x12000
	v_add3_u32 v192, s0, v208, v243
	s_add_i32 s0, 16, 0x1b000
	v_add3_u32 v208, s0, v242, v243
	s_waitcnt vmcnt(9)
	ds_write_b128 v215, v[218:221]
	s_waitcnt vmcnt(8)
	ds_write_b128 v215, v[222:225] offset:36864
	ds_read_b128 v[218:221], v208
	ds_read_b128 v[222:225], v208 offset:4608
	ds_read_b128 v[234:237], v192
	ds_read_b128 v[238:241], v192 offset:4608
	s_setprio 1
	s_waitcnt lgkmcnt(1)
	v_mfma_f32_32x32x16_bf16 v[112:127], v[234:237], v[218:221], v[112:127]
	v_mfma_f32_32x32x16_bf16 v[48:63], v[234:237], v[222:225], v[48:63]
	s_waitcnt lgkmcnt(0)
	v_mfma_f32_32x32x16_bf16 v[96:111], v[238:241], v[218:221], v[96:111]
	v_mfma_f32_32x32x16_bf16 v[32:47], v[238:241], v[222:225], v[32:47]
	ds_read_b128 v[234:237], v192 offset:9216
	ds_read_b128 v[238:241], v192 offset:13824
	s_waitcnt lgkmcnt(1)
	v_mfma_f32_32x32x16_bf16 v[80:95], v[234:237], v[218:221], v[80:95]
	v_mfma_f32_32x32x16_bf16 v[16:31], v[234:237], v[222:225], v[16:31]
	s_waitcnt lgkmcnt(0)
	v_mfma_f32_32x32x16_bf16 v[64:79], v[238:241], v[218:221], v[64:79]
	v_mfma_f32_32x32x16_bf16 v[0:15], v[238:241], v[222:225], v[0:15]
	s_setprio 0
	global_load_dwordx4 v[218:221], v[194:195], off offset:384
	global_load_dwordx4 v[222:225], v[196:197], off offset:384
	s_waitcnt vmcnt(9)
	ds_write_b128 v215, v[226:229] offset:9216
	s_waitcnt vmcnt(8)
	ds_write_b128 v215, v[230:233] offset:46080
	ds_read_b128 v[226:229], v208 offset:32
	ds_read_b128 v[230:233], v208 offset:4640
	ds_read_b128 v[234:237], v192 offset:32
	ds_read_b128 v[238:241], v192 offset:4640
	s_setprio 1
	s_waitcnt lgkmcnt(1)
	v_mfma_f32_32x32x16_bf16 v[112:127], v[234:237], v[226:229], v[112:127]
	v_mfma_f32_32x32x16_bf16 v[48:63], v[234:237], v[230:233], v[48:63]
	s_waitcnt lgkmcnt(0)
	v_mfma_f32_32x32x16_bf16 v[96:111], v[238:241], v[226:229], v[96:111]
	v_mfma_f32_32x32x16_bf16 v[32:47], v[238:241], v[230:233], v[32:47]
	ds_read_b128 v[234:237], v192 offset:9248
	ds_read_b128 v[238:241], v192 offset:13856
	s_waitcnt lgkmcnt(1)
	v_mfma_f32_32x32x16_bf16 v[80:95], v[234:237], v[226:229], v[80:95]
	v_mfma_f32_32x32x16_bf16 v[16:31], v[234:237], v[230:233], v[16:31]
	s_waitcnt lgkmcnt(0)
	v_mfma_f32_32x32x16_bf16 v[64:79], v[238:241], v[226:229], v[64:79]
	v_mfma_f32_32x32x16_bf16 v[0:15], v[238:241], v[230:233], v[0:15]
	s_setprio 0
	global_load_dwordx4 v[226:229], v[184:185], off offset:384
	global_load_dwordx4 v[230:233], v[186:187], off offset:384
	s_waitcnt vmcnt(9)
	ds_write_b128 v215, v[176:179] offset:18432
	s_waitcnt vmcnt(8)
	ds_write_b128 v215, v[180:183] offset:55296
	ds_read_b128 v[176:179], v208 offset:64
	ds_read_b128 v[180:183], v208 offset:4672
	ds_read_b128 v[234:237], v192 offset:64
	ds_read_b128 v[238:241], v192 offset:4672
	s_setprio 1
	s_waitcnt lgkmcnt(1)
	v_mfma_f32_32x32x16_bf16 v[112:127], v[234:237], v[176:179], v[112:127]
	v_mfma_f32_32x32x16_bf16 v[48:63], v[234:237], v[180:183], v[48:63]
	s_waitcnt lgkmcnt(0)
	v_mfma_f32_32x32x16_bf16 v[96:111], v[238:241], v[176:179], v[96:111]
	v_mfma_f32_32x32x16_bf16 v[32:47], v[238:241], v[180:183], v[32:47]
	ds_read_b128 v[234:237], v192 offset:9280
	ds_read_b128 v[238:241], v192 offset:13888
	s_waitcnt lgkmcnt(1)
	v_mfma_f32_32x32x16_bf16 v[80:95], v[234:237], v[176:179], v[80:95]
	v_mfma_f32_32x32x16_bf16 v[16:31], v[234:237], v[180:183], v[16:31]
	s_waitcnt lgkmcnt(0)
	v_mfma_f32_32x32x16_bf16 v[64:79], v[238:241], v[176:179], v[64:79]
	v_mfma_f32_32x32x16_bf16 v[0:15], v[238:241], v[180:183], v[0:15]
	s_setprio 0
	global_load_dwordx4 v[176:179], v[198:199], off offset:384
	global_load_dwordx4 v[180:183], v[200:201], off offset:384
	s_waitcnt vmcnt(9)
	ds_write_b128 v215, v[168:171] offset:27648
	s_waitcnt vmcnt(8)
	ds_write_b128 v215, v[172:175] offset:64512
	ds_read_b128 v[168:171], v208 offset:96
	ds_read_b128 v[172:175], v208 offset:4704
	ds_read_b128 v[234:237], v192 offset:96
	ds_read_b128 v[238:241], v192 offset:4704
	s_setprio 1
	s_waitcnt lgkmcnt(1)
	v_mfma_f32_32x32x16_bf16 v[112:127], v[234:237], v[168:171], v[112:127]
	v_mfma_f32_32x32x16_bf16 v[48:63], v[234:237], v[172:175], v[48:63]
	s_waitcnt lgkmcnt(0)
	v_mfma_f32_32x32x16_bf16 v[96:111], v[238:241], v[168:171], v[96:111]
	v_mfma_f32_32x32x16_bf16 v[32:47], v[238:241], v[172:175], v[32:47]
	ds_read_b128 v[234:237], v192 offset:9312
	ds_read_b128 v[238:241], v192 offset:13920
	s_waitcnt lgkmcnt(1)
	v_mfma_f32_32x32x16_bf16 v[80:95], v[234:237], v[168:171], v[80:95]
	v_mfma_f32_32x32x16_bf16 v[16:31], v[234:237], v[172:175], v[16:31]
	s_waitcnt lgkmcnt(0)
	v_mfma_f32_32x32x16_bf16 v[64:79], v[238:241], v[168:171], v[64:79]
	v_mfma_f32_32x32x16_bf16 v[0:15], v[238:241], v[172:175], v[0:15]
	s_setprio 0
	s_barrier
	global_load_dwordx4 v[168:171], v[190:191], off offset:512
	global_load_dwordx4 v[172:175], v[188:189], off offset:512
	s_waitcnt vmcnt(9)
	ds_write_b128 v209, v[160:163]
	s_waitcnt vmcnt(8)
	ds_write_b128 v210, v[164:167]
	ds_read_b128 v[160:163], v205 offset:36864
	ds_read_b128 v[164:167], v205 offset:41472
	ds_read_b128 v[234:237], v204
	ds_read_b128 v[238:241], v204 offset:4608
	s_setprio 1
	s_waitcnt lgkmcnt(1)
	v_mfma_f32_32x32x16_bf16 v[112:127], v[234:237], v[160:163], v[112:127]
	v_mfma_f32_32x32x16_bf16 v[48:63], v[234:237], v[164:167], v[48:63]
	s_waitcnt lgkmcnt(0)
	v_mfma_f32_32x32x16_bf16 v[96:111], v[238:241], v[160:163], v[96:111]
	v_mfma_f32_32x32x16_bf16 v[32:47], v[238:241], v[164:167], v[32:47]
	ds_read_b128 v[234:237], v204 offset:9216
	ds_read_b128 v[238:241], v204 offset:13824
	s_waitcnt vmcnt(7)
	ds_write_b128 v212, v[218:221]
	s_waitcnt vmcnt(6)
	ds_write_b128 v211, v[222:225]
	ds_read_b128 v[218:221], v205 offset:36896
	ds_read_b128 v[222:225], v205 offset:41504
	s_waitcnt lgkmcnt(5)
	v_mfma_f32_32x32x16_bf16 v[80:95], v[234:237], v[160:163], v[80:95]
	v_mfma_f32_32x32x16_bf16 v[16:31], v[234:237], v[164:167], v[16:31]
	ds_read_b128 v[234:237], v204 offset:32
	s_waitcnt lgkmcnt(5)
	v_mfma_f32_32x32x16_bf16 v[64:79], v[238:241], v[160:163], v[64:79]
	v_mfma_f32_32x32x16_bf16 v[0:15], v[238:241], v[164:167], v[0:15]
	ds_read_b128 v[238:241], v204 offset:4640
	s_setprio 0
	global_load_dwordx4 v[160:163], v[194:195], off offset:512
	global_load_dwordx4 v[164:167], v[196:197], off offset:512
	s_setprio 1
	s_waitcnt lgkmcnt(1)
	v_mfma_f32_32x32x16_bf16 v[112:127], v[234:237], v[218:221], v[112:127]
	v_mfma_f32_32x32x16_bf16 v[48:63], v[234:237], v[222:225], v[48:63]
	s_waitcnt lgkmcnt(0)
	v_mfma_f32_32x32x16_bf16 v[96:111], v[238:241], v[218:221], v[96:111]
	v_mfma_f32_32x32x16_bf16 v[32:47], v[238:241], v[222:225], v[32:47]
	ds_read_b128 v[234:237], v204 offset:9248
	ds_read_b128 v[238:241], v204 offset:13856
	s_waitcnt vmcnt(7)
	ds_write_b128 v214, v[226:229]
	s_waitcnt vmcnt(6)
	ds_write_b128 v213, v[230:233]
	ds_read_b128 v[226:229], v205 offset:36928
	ds_read_b128 v[230:233], v205 offset:41536
	s_waitcnt lgkmcnt(5)
	v_mfma_f32_32x32x16_bf16 v[80:95], v[234:237], v[218:221], v[80:95]
	v_mfma_f32_32x32x16_bf16 v[16:31], v[234:237], v[222:225], v[16:31]
	ds_read_b128 v[234:237], v204 offset:64
	s_waitcnt lgkmcnt(5)
	v_mfma_f32_32x32x16_bf16 v[64:79], v[238:241], v[218:221], v[64:79]
	v_mfma_f32_32x32x16_bf16 v[0:15], v[238:241], v[222:225], v[0:15]
	ds_read_b128 v[238:241], v204 offset:4672
	s_setprio 0
	global_load_dwordx4 v[218:221], v[184:185], off offset:512
	global_load_dwordx4 v[222:225], v[186:187], off offset:512
	s_setprio 1
	s_waitcnt lgkmcnt(1)
	v_mfma_f32_32x32x16_bf16 v[112:127], v[234:237], v[226:229], v[112:127]
	v_mfma_f32_32x32x16_bf16 v[48:63], v[234:237], v[230:233], v[48:63]
	s_waitcnt lgkmcnt(0)
	v_mfma_f32_32x32x16_bf16 v[96:111], v[238:241], v[226:229], v[96:111]
	v_mfma_f32_32x32x16_bf16 v[32:47], v[238:241], v[230:233], v[32:47]
	ds_read_b128 v[234:237], v204 offset:9280
	ds_read_b128 v[238:241], v204 offset:13888
	s_waitcnt vmcnt(7)
	ds_write_b128 v217, v[176:179]
	s_waitcnt vmcnt(6)
	ds_write_b128 v216, v[180:183]
	ds_read_b128 v[176:179], v205 offset:36960
	ds_read_b128 v[180:183], v205 offset:41568
	s_waitcnt lgkmcnt(5)
	v_mfma_f32_32x32x16_bf16 v[80:95], v[234:237], v[226:229], v[80:95]
	v_mfma_f32_32x32x16_bf16 v[16:31], v[234:237], v[230:233], v[16:31]
	ds_read_b128 v[234:237], v204 offset:96
	s_waitcnt lgkmcnt(5)
	v_mfma_f32_32x32x16_bf16 v[64:79], v[238:241], v[226:229], v[64:79]
	v_mfma_f32_32x32x16_bf16 v[0:15], v[238:241], v[230:233], v[0:15]
	ds_read_b128 v[238:241], v204 offset:4704
	s_setprio 0
	global_load_dwordx4 v[226:229], v[198:199], off offset:512
	global_load_dwordx4 v[230:233], v[200:201], off offset:512
	s_setprio 1
	s_waitcnt lgkmcnt(1)
	v_mfma_f32_32x32x16_bf16 v[112:127], v[234:237], v[176:179], v[112:127]
	v_mfma_f32_32x32x16_bf16 v[48:63], v[234:237], v[180:183], v[48:63]
	s_waitcnt lgkmcnt(0)
	v_mfma_f32_32x32x16_bf16 v[96:111], v[238:241], v[176:179], v[96:111]
	v_mfma_f32_32x32x16_bf16 v[32:47], v[238:241], v[180:183], v[32:47]
	ds_read_b128 v[234:237], v204 offset:9312
	ds_read_b128 v[238:241], v204 offset:13920
	s_waitcnt lgkmcnt(1)
	v_mfma_f32_32x32x16_bf16 v[80:95], v[234:237], v[176:179], v[80:95]
	v_mfma_f32_32x32x16_bf16 v[16:31], v[234:237], v[180:183], v[16:31]
	s_waitcnt lgkmcnt(0)
	v_mfma_f32_32x32x16_bf16 v[64:79], v[238:241], v[176:179], v[64:79]
	v_mfma_f32_32x32x16_bf16 v[0:15], v[238:241], v[180:183], v[0:15]
	s_setprio 0
	s_barrier
	global_load_dwordx4 v[176:179], v[190:191], off offset:640
	global_load_dwordx4 v[180:183], v[188:189], off offset:640
	s_waitcnt vmcnt(9)
	ds_write_b128 v215, v[168:171]
	s_waitcnt vmcnt(8)
	ds_write_b128 v215, v[172:175] offset:36864
	ds_read_b128 v[168:171], v208
	ds_read_b128 v[172:175], v208 offset:4608
	ds_read_b128 v[234:237], v192
	ds_read_b128 v[238:241], v192 offset:4608
	s_setprio 1
	s_waitcnt lgkmcnt(1)
	v_mfma_f32_32x32x16_bf16 v[112:127], v[234:237], v[168:171], v[112:127]
	v_mfma_f32_32x32x16_bf16 v[48:63], v[234:237], v[172:175], v[48:63]
	s_waitcnt lgkmcnt(0)
	v_mfma_f32_32x32x16_bf16 v[96:111], v[238:241], v[168:171], v[96:111]
	v_mfma_f32_32x32x16_bf16 v[32:47], v[238:241], v[172:175], v[32:47]
	ds_read_b128 v[234:237], v192 offset:9216
	ds_read_b128 v[238:241], v192 offset:13824
	s_waitcnt vmcnt(7)
	ds_write_b128 v215, v[160:163] offset:9216
	s_waitcnt vmcnt(6)
	ds_write_b128 v215, v[164:167] offset:46080
	ds_read_b128 v[160:163], v208 offset:32
	ds_read_b128 v[164:167], v208 offset:4640
	s_waitcnt lgkmcnt(5)
	v_mfma_f32_32x32x16_bf16 v[80:95], v[234:237], v[168:171], v[80:95]
	v_mfma_f32_32x32x16_bf16 v[16:31], v[234:237], v[172:175], v[16:31]
	ds_read_b128 v[234:237], v192 offset:32
	s_waitcnt lgkmcnt(5)
	v_mfma_f32_32x32x16_bf16 v[64:79], v[238:241], v[168:171], v[64:79]
	v_mfma_f32_32x32x16_bf16 v[0:15], v[238:241], v[172:175], v[0:15]
	ds_read_b128 v[238:241], v192 offset:4640
	s_setprio 0
	global_load_dwordx4 v[168:171], v[194:195], off offset:640
	global_load_dwordx4 v[172:175], v[196:197], off offset:640
	s_setprio 1
	s_waitcnt lgkmcnt(1)
	v_mfma_f32_32x32x16_bf16 v[112:127], v[234:237], v[160:163], v[112:127]
	v_mfma_f32_32x32x16_bf16 v[48:63], v[234:237], v[164:167], v[48:63]
	s_waitcnt lgkmcnt(0)
	v_mfma_f32_32x32x16_bf16 v[96:111], v[238:241], v[160:163], v[96:111]
	v_mfma_f32_32x32x16_bf16 v[32:47], v[238:241], v[164:167], v[32:47]
	ds_read_b128 v[234:237], v192 offset:9248
	ds_read_b128 v[238:241], v192 offset:13856
	s_waitcnt vmcnt(7)
	ds_write_b128 v215, v[218:221] offset:18432
	s_waitcnt vmcnt(6)
	ds_write_b128 v215, v[222:225] offset:55296
	ds_read_b128 v[218:221], v208 offset:64
	ds_read_b128 v[222:225], v208 offset:4672
	s_waitcnt lgkmcnt(5)
	v_mfma_f32_32x32x16_bf16 v[80:95], v[234:237], v[160:163], v[80:95]
	v_mfma_f32_32x32x16_bf16 v[16:31], v[234:237], v[164:167], v[16:31]
	ds_read_b128 v[234:237], v192 offset:64
	s_waitcnt lgkmcnt(5)
	v_mfma_f32_32x32x16_bf16 v[64:79], v[238:241], v[160:163], v[64:79]
	v_mfma_f32_32x32x16_bf16 v[0:15], v[238:241], v[164:167], v[0:15]
	ds_read_b128 v[238:241], v192 offset:4672
	s_setprio 0
	global_load_dwordx4 v[160:163], v[184:185], off offset:640
	global_load_dwordx4 v[164:167], v[186:187], off offset:640
	s_setprio 1
	s_waitcnt lgkmcnt(1)
	v_mfma_f32_32x32x16_bf16 v[112:127], v[234:237], v[218:221], v[112:127]
	v_mfma_f32_32x32x16_bf16 v[48:63], v[234:237], v[222:225], v[48:63]
	s_waitcnt lgkmcnt(0)
	v_mfma_f32_32x32x16_bf16 v[96:111], v[238:241], v[218:221], v[96:111]
	v_mfma_f32_32x32x16_bf16 v[32:47], v[238:241], v[222:225], v[32:47]
	ds_read_b128 v[234:237], v192 offset:9280
	ds_read_b128 v[238:241], v192 offset:13888
	s_waitcnt vmcnt(7)
	ds_write_b128 v215, v[226:229] offset:27648
	s_waitcnt vmcnt(6)
	ds_write_b128 v215, v[230:233] offset:64512
	ds_read_b128 v[226:229], v208 offset:96
	ds_read_b128 v[230:233], v208 offset:4704
	s_waitcnt lgkmcnt(5)
	v_mfma_f32_32x32x16_bf16 v[80:95], v[234:237], v[218:221], v[80:95]
	v_mfma_f32_32x32x16_bf16 v[16:31], v[234:237], v[222:225], v[16:31]
	ds_read_b128 v[234:237], v192 offset:96
	s_waitcnt lgkmcnt(5)
	v_mfma_f32_32x32x16_bf16 v[64:79], v[238:241], v[218:221], v[64:79]
	v_mfma_f32_32x32x16_bf16 v[0:15], v[238:241], v[222:225], v[0:15]
	ds_read_b128 v[238:241], v192 offset:4704
	s_setprio 0
	global_load_dwordx4 v[218:221], v[198:199], off offset:640
	global_load_dwordx4 v[222:225], v[200:201], off offset:640
	s_setprio 1
	s_waitcnt lgkmcnt(1)
	v_mfma_f32_32x32x16_bf16 v[112:127], v[234:237], v[226:229], v[112:127]
	v_mfma_f32_32x32x16_bf16 v[48:63], v[234:237], v[230:233], v[48:63]
	s_waitcnt lgkmcnt(0)
	v_mfma_f32_32x32x16_bf16 v[96:111], v[238:241], v[226:229], v[96:111]
	v_mfma_f32_32x32x16_bf16 v[32:47], v[238:241], v[230:233], v[32:47]
	ds_read_b128 v[234:237], v192 offset:9312
	ds_read_b128 v[238:241], v192 offset:13920
	s_waitcnt lgkmcnt(1)
	v_mfma_f32_32x32x16_bf16 v[80:95], v[234:237], v[226:229], v[80:95]
	v_mfma_f32_32x32x16_bf16 v[16:31], v[234:237], v[230:233], v[16:31]
	s_waitcnt lgkmcnt(0)
	v_mfma_f32_32x32x16_bf16 v[64:79], v[238:241], v[226:229], v[64:79]
	v_mfma_f32_32x32x16_bf16 v[0:15], v[238:241], v[230:233], v[0:15]
	s_setprio 0
	s_barrier
	global_load_dwordx4 v[226:229], v[190:191], off offset:768
	global_load_dwordx4 v[230:233], v[188:189], off offset:768
	s_waitcnt vmcnt(9)
	ds_write_b128 v209, v[176:179]
	s_waitcnt vmcnt(8)
	ds_write_b128 v210, v[180:183]
	ds_read_b128 v[176:179], v205 offset:36864
	ds_read_b128 v[180:183], v205 offset:41472
	ds_read_b128 v[234:237], v204
	ds_read_b128 v[238:241], v204 offset:4608
	s_setprio 1
	s_waitcnt lgkmcnt(1)
	v_mfma_f32_32x32x16_bf16 v[112:127], v[234:237], v[176:179], v[112:127]
	v_mfma_f32_32x32x16_bf16 v[48:63], v[234:237], v[180:183], v[48:63]
	s_waitcnt lgkmcnt(0)
	v_mfma_f32_32x32x16_bf16 v[96:111], v[238:241], v[176:179], v[96:111]
	v_mfma_f32_32x32x16_bf16 v[32:47], v[238:241], v[180:183], v[32:47]
	ds_read_b128 v[234:237], v204 offset:9216
	ds_read_b128 v[238:241], v204 offset:13824
	s_waitcnt vmcnt(7)
	ds_write_b128 v212, v[168:171]
	s_waitcnt vmcnt(6)
	ds_write_b128 v211, v[172:175]
	ds_read_b128 v[168:171], v205 offset:36896
	ds_read_b128 v[172:175], v205 offset:41504
	s_waitcnt lgkmcnt(5)
	v_mfma_f32_32x32x16_bf16 v[80:95], v[234:237], v[176:179], v[80:95]
	v_mfma_f32_32x32x16_bf16 v[16:31], v[234:237], v[180:183], v[16:31]
	ds_read_b128 v[234:237], v204 offset:32
	s_waitcnt lgkmcnt(5)
	v_mfma_f32_32x32x16_bf16 v[64:79], v[238:241], v[176:179], v[64:79]
	v_mfma_f32_32x32x16_bf16 v[0:15], v[238:241], v[180:183], v[0:15]
	ds_read_b128 v[238:241], v204 offset:4640
	s_setprio 0
	global_load_dwordx4 v[176:179], v[194:195], off offset:768
	global_load_dwordx4 v[180:183], v[196:197], off offset:768
	s_setprio 1
	s_waitcnt lgkmcnt(1)
	v_mfma_f32_32x32x16_bf16 v[112:127], v[234:237], v[168:171], v[112:127]
	v_mfma_f32_32x32x16_bf16 v[48:63], v[234:237], v[172:175], v[48:63]
	s_waitcnt lgkmcnt(0)
	v_mfma_f32_32x32x16_bf16 v[96:111], v[238:241], v[168:171], v[96:111]
	v_mfma_f32_32x32x16_bf16 v[32:47], v[238:241], v[172:175], v[32:47]
	ds_read_b128 v[234:237], v204 offset:9248
	ds_read_b128 v[238:241], v204 offset:13856
	s_waitcnt vmcnt(7)
	ds_write_b128 v214, v[160:163]
	s_waitcnt vmcnt(6)
	ds_write_b128 v213, v[164:167]
	ds_read_b128 v[160:163], v205 offset:36928
	ds_read_b128 v[164:167], v205 offset:41536
	s_waitcnt lgkmcnt(5)
	v_mfma_f32_32x32x16_bf16 v[80:95], v[234:237], v[168:171], v[80:95]
	v_mfma_f32_32x32x16_bf16 v[16:31], v[234:237], v[172:175], v[16:31]
	ds_read_b128 v[234:237], v204 offset:64
	s_waitcnt lgkmcnt(5)
	v_mfma_f32_32x32x16_bf16 v[64:79], v[238:241], v[168:171], v[64:79]
	v_mfma_f32_32x32x16_bf16 v[0:15], v[238:241], v[172:175], v[0:15]
	ds_read_b128 v[238:241], v204 offset:4672
	s_setprio 0
	global_load_dwordx4 v[168:171], v[184:185], off offset:768
	global_load_dwordx4 v[172:175], v[186:187], off offset:768
	s_setprio 1
	s_waitcnt lgkmcnt(1)
	v_mfma_f32_32x32x16_bf16 v[112:127], v[234:237], v[160:163], v[112:127]
	v_mfma_f32_32x32x16_bf16 v[48:63], v[234:237], v[164:167], v[48:63]
	s_waitcnt lgkmcnt(0)
	v_mfma_f32_32x32x16_bf16 v[96:111], v[238:241], v[160:163], v[96:111]
	v_mfma_f32_32x32x16_bf16 v[32:47], v[238:241], v[164:167], v[32:47]
	ds_read_b128 v[234:237], v204 offset:9280
	ds_read_b128 v[238:241], v204 offset:13888
	s_waitcnt vmcnt(7)
	ds_write_b128 v217, v[218:221]
	s_waitcnt vmcnt(6)
	ds_write_b128 v216, v[222:225]
	ds_read_b128 v[218:221], v205 offset:36960
	ds_read_b128 v[222:225], v205 offset:41568
	s_waitcnt lgkmcnt(5)
	v_mfma_f32_32x32x16_bf16 v[80:95], v[234:237], v[160:163], v[80:95]
	v_mfma_f32_32x32x16_bf16 v[16:31], v[234:237], v[164:167], v[16:31]
	ds_read_b128 v[234:237], v204 offset:96
	s_waitcnt lgkmcnt(5)
	v_mfma_f32_32x32x16_bf16 v[64:79], v[238:241], v[160:163], v[64:79]
	v_mfma_f32_32x32x16_bf16 v[0:15], v[238:241], v[164:167], v[0:15]
	ds_read_b128 v[238:241], v204 offset:4704
	s_setprio 0
	global_load_dwordx4 v[160:163], v[198:199], off offset:768
	global_load_dwordx4 v[164:167], v[200:201], off offset:768
	s_setprio 1
	s_waitcnt lgkmcnt(1)
	v_mfma_f32_32x32x16_bf16 v[112:127], v[234:237], v[218:221], v[112:127]
	v_mfma_f32_32x32x16_bf16 v[48:63], v[234:237], v[222:225], v[48:63]
	s_waitcnt lgkmcnt(0)
	v_mfma_f32_32x32x16_bf16 v[96:111], v[238:241], v[218:221], v[96:111]
	v_mfma_f32_32x32x16_bf16 v[32:47], v[238:241], v[222:225], v[32:47]
	ds_read_b128 v[234:237], v204 offset:9312
	ds_read_b128 v[238:241], v204 offset:13920
	s_waitcnt lgkmcnt(1)
	v_mfma_f32_32x32x16_bf16 v[80:95], v[234:237], v[218:221], v[80:95]
	v_mfma_f32_32x32x16_bf16 v[16:31], v[234:237], v[222:225], v[16:31]
	s_waitcnt lgkmcnt(0)
	v_mfma_f32_32x32x16_bf16 v[64:79], v[238:241], v[218:221], v[64:79]
	v_mfma_f32_32x32x16_bf16 v[0:15], v[238:241], v[222:225], v[0:15]
	s_setprio 0
	s_barrier
	global_load_dwordx4 v[218:221], v[190:191], off offset:896
	global_load_dwordx4 v[222:225], v[188:189], off offset:896
	s_waitcnt vmcnt(9)
	ds_write_b128 v215, v[226:229]
	s_waitcnt vmcnt(8)
	ds_write_b128 v215, v[230:233] offset:36864
	ds_read_b128 v[226:229], v208
	ds_read_b128 v[230:233], v208 offset:4608
	ds_read_b128 v[234:237], v192
	ds_read_b128 v[238:241], v192 offset:4608
	s_setprio 1
	s_waitcnt lgkmcnt(1)
	v_mfma_f32_32x32x16_bf16 v[112:127], v[234:237], v[226:229], v[112:127]
	v_mfma_f32_32x32x16_bf16 v[48:63], v[234:237], v[230:233], v[48:63]
	s_waitcnt lgkmcnt(0)
	v_mfma_f32_32x32x16_bf16 v[96:111], v[238:241], v[226:229], v[96:111]
	v_mfma_f32_32x32x16_bf16 v[32:47], v[238:241], v[230:233], v[32:47]
	ds_read_b128 v[234:237], v192 offset:9216
	ds_read_b128 v[238:241], v192 offset:13824
	s_waitcnt vmcnt(7)
	ds_write_b128 v215, v[176:179] offset:9216
	s_waitcnt vmcnt(6)
	ds_write_b128 v215, v[180:183] offset:46080
	ds_read_b128 v[176:179], v208 offset:32
	ds_read_b128 v[180:183], v208 offset:4640
	s_waitcnt lgkmcnt(5)
	v_mfma_f32_32x32x16_bf16 v[80:95], v[234:237], v[226:229], v[80:95]
	v_mfma_f32_32x32x16_bf16 v[16:31], v[234:237], v[230:233], v[16:31]
	ds_read_b128 v[234:237], v192 offset:32
	s_waitcnt lgkmcnt(5)
	v_mfma_f32_32x32x16_bf16 v[64:79], v[238:241], v[226:229], v[64:79]
	v_mfma_f32_32x32x16_bf16 v[0:15], v[238:241], v[230:233], v[0:15]
	ds_read_b128 v[238:241], v192 offset:4640
	s_setprio 0
	global_load_dwordx4 v[226:229], v[194:195], off offset:896
	global_load_dwordx4 v[230:233], v[196:197], off offset:896
	s_setprio 1
	s_waitcnt lgkmcnt(1)
	v_mfma_f32_32x32x16_bf16 v[112:127], v[234:237], v[176:179], v[112:127]
	v_mfma_f32_32x32x16_bf16 v[48:63], v[234:237], v[180:183], v[48:63]
	s_waitcnt lgkmcnt(0)
	v_mfma_f32_32x32x16_bf16 v[96:111], v[238:241], v[176:179], v[96:111]
	v_mfma_f32_32x32x16_bf16 v[32:47], v[238:241], v[180:183], v[32:47]
	ds_read_b128 v[234:237], v192 offset:9248
	ds_read_b128 v[238:241], v192 offset:13856
	s_waitcnt vmcnt(7)
	ds_write_b128 v215, v[168:171] offset:18432
	s_waitcnt vmcnt(6)
	ds_write_b128 v215, v[172:175] offset:55296
	ds_read_b128 v[168:171], v208 offset:64
	ds_read_b128 v[172:175], v208 offset:4672
	s_waitcnt lgkmcnt(5)
	v_mfma_f32_32x32x16_bf16 v[80:95], v[234:237], v[176:179], v[80:95]
	v_mfma_f32_32x32x16_bf16 v[16:31], v[234:237], v[180:183], v[16:31]
	ds_read_b128 v[234:237], v192 offset:64
	s_waitcnt lgkmcnt(5)
	v_mfma_f32_32x32x16_bf16 v[64:79], v[238:241], v[176:179], v[64:79]
	v_mfma_f32_32x32x16_bf16 v[0:15], v[238:241], v[180:183], v[0:15]
	ds_read_b128 v[238:241], v192 offset:4672
	s_setprio 0
	global_load_dwordx4 v[176:179], v[184:185], off offset:896
	global_load_dwordx4 v[180:183], v[186:187], off offset:896
	s_setprio 1
	s_waitcnt lgkmcnt(1)
	v_mfma_f32_32x32x16_bf16 v[112:127], v[234:237], v[168:171], v[112:127]
	v_mfma_f32_32x32x16_bf16 v[48:63], v[234:237], v[172:175], v[48:63]
	s_waitcnt lgkmcnt(0)
	v_mfma_f32_32x32x16_bf16 v[96:111], v[238:241], v[168:171], v[96:111]
	v_mfma_f32_32x32x16_bf16 v[32:47], v[238:241], v[172:175], v[32:47]
	ds_read_b128 v[234:237], v192 offset:9280
	ds_read_b128 v[238:241], v192 offset:13888
	s_waitcnt vmcnt(7)
	ds_write_b128 v215, v[160:163] offset:27648
	s_waitcnt vmcnt(6)
	ds_write_b128 v215, v[164:167] offset:64512
	ds_read_b128 v[160:163], v208 offset:96
	ds_read_b128 v[164:167], v208 offset:4704
	s_waitcnt lgkmcnt(5)
	v_mfma_f32_32x32x16_bf16 v[80:95], v[234:237], v[168:171], v[80:95]
	v_mfma_f32_32x32x16_bf16 v[16:31], v[234:237], v[172:175], v[16:31]
	ds_read_b128 v[234:237], v192 offset:96
	s_waitcnt lgkmcnt(5)
	v_mfma_f32_32x32x16_bf16 v[64:79], v[238:241], v[168:171], v[64:79]
	v_mfma_f32_32x32x16_bf16 v[0:15], v[238:241], v[172:175], v[0:15]
	ds_read_b128 v[238:241], v192 offset:4704
	s_setprio 0
	global_load_dwordx4 v[168:171], v[198:199], off offset:896
	global_load_dwordx4 v[172:175], v[200:201], off offset:896
	s_setprio 1
	s_waitcnt lgkmcnt(1)
	v_mfma_f32_32x32x16_bf16 v[112:127], v[234:237], v[160:163], v[112:127]
	v_mfma_f32_32x32x16_bf16 v[48:63], v[234:237], v[164:167], v[48:63]
	s_waitcnt lgkmcnt(0)
	v_mfma_f32_32x32x16_bf16 v[96:111], v[238:241], v[160:163], v[96:111]
	v_mfma_f32_32x32x16_bf16 v[32:47], v[238:241], v[164:167], v[32:47]
	ds_read_b128 v[234:237], v192 offset:9312
	ds_read_b128 v[238:241], v192 offset:13920
	s_waitcnt lgkmcnt(1)
	v_mfma_f32_32x32x16_bf16 v[80:95], v[234:237], v[160:163], v[80:95]
	v_mfma_f32_32x32x16_bf16 v[16:31], v[234:237], v[164:167], v[16:31]
	s_waitcnt lgkmcnt(0)
	v_mfma_f32_32x32x16_bf16 v[64:79], v[238:241], v[160:163], v[64:79]
	v_mfma_f32_32x32x16_bf16 v[0:15], v[238:241], v[164:167], v[0:15]
	s_setprio 0
	s_barrier
	global_load_dwordx4 v[160:163], v[190:191], off offset:1024
	global_load_dwordx4 v[164:167], v[188:189], off offset:1024
	s_waitcnt vmcnt(9)
	ds_write_b128 v209, v[218:221]
	s_waitcnt vmcnt(8)
	ds_write_b128 v210, v[222:225]
	ds_read_b128 v[218:221], v205 offset:36864
	ds_read_b128 v[222:225], v205 offset:41472
	ds_read_b128 v[234:237], v204
	ds_read_b128 v[238:241], v204 offset:4608
	s_setprio 1
	s_waitcnt lgkmcnt(1)
	v_mfma_f32_32x32x16_bf16 v[112:127], v[234:237], v[218:221], v[112:127]
	v_mfma_f32_32x32x16_bf16 v[48:63], v[234:237], v[222:225], v[48:63]
	s_waitcnt lgkmcnt(0)
	v_mfma_f32_32x32x16_bf16 v[96:111], v[238:241], v[218:221], v[96:111]
	v_mfma_f32_32x32x16_bf16 v[32:47], v[238:241], v[222:225], v[32:47]
	ds_read_b128 v[234:237], v204 offset:9216
	ds_read_b128 v[238:241], v204 offset:13824
	s_waitcnt vmcnt(7)
	ds_write_b128 v212, v[226:229]
	s_waitcnt vmcnt(6)
	ds_write_b128 v211, v[230:233]
	ds_read_b128 v[226:229], v205 offset:36896
	ds_read_b128 v[230:233], v205 offset:41504
	s_waitcnt lgkmcnt(5)
	v_mfma_f32_32x32x16_bf16 v[80:95], v[234:237], v[218:221], v[80:95]
	v_mfma_f32_32x32x16_bf16 v[16:31], v[234:237], v[222:225], v[16:31]
	ds_read_b128 v[234:237], v204 offset:32
	s_waitcnt lgkmcnt(5)
	v_mfma_f32_32x32x16_bf16 v[64:79], v[238:241], v[218:221], v[64:79]
	v_mfma_f32_32x32x16_bf16 v[0:15], v[238:241], v[222:225], v[0:15]
	ds_read_b128 v[238:241], v204 offset:4640
	s_setprio 0
	global_load_dwordx4 v[218:221], v[194:195], off offset:1024
	global_load_dwordx4 v[222:225], v[196:197], off offset:1024
	s_setprio 1
	s_waitcnt lgkmcnt(1)
	v_mfma_f32_32x32x16_bf16 v[112:127], v[234:237], v[226:229], v[112:127]
	v_mfma_f32_32x32x16_bf16 v[48:63], v[234:237], v[230:233], v[48:63]
	s_waitcnt lgkmcnt(0)
	v_mfma_f32_32x32x16_bf16 v[96:111], v[238:241], v[226:229], v[96:111]
	v_mfma_f32_32x32x16_bf16 v[32:47], v[238:241], v[230:233], v[32:47]
	ds_read_b128 v[234:237], v204 offset:9248
	ds_read_b128 v[238:241], v204 offset:13856
	s_waitcnt vmcnt(7)
	ds_write_b128 v214, v[176:179]
	s_waitcnt vmcnt(6)
	ds_write_b128 v213, v[180:183]
	ds_read_b128 v[176:179], v205 offset:36928
	ds_read_b128 v[180:183], v205 offset:41536
	s_waitcnt lgkmcnt(5)
	v_mfma_f32_32x32x16_bf16 v[80:95], v[234:237], v[226:229], v[80:95]
	v_mfma_f32_32x32x16_bf16 v[16:31], v[234:237], v[230:233], v[16:31]
	ds_read_b128 v[234:237], v204 offset:64
	s_waitcnt lgkmcnt(5)
	v_mfma_f32_32x32x16_bf16 v[64:79], v[238:241], v[226:229], v[64:79]
	v_mfma_f32_32x32x16_bf16 v[0:15], v[238:241], v[230:233], v[0:15]
	ds_read_b128 v[238:241], v204 offset:4672
	s_setprio 0
	global_load_dwordx4 v[226:229], v[184:185], off offset:1024
	global_load_dwordx4 v[230:233], v[186:187], off offset:1024
	s_setprio 1
	s_waitcnt lgkmcnt(1)
	v_mfma_f32_32x32x16_bf16 v[112:127], v[234:237], v[176:179], v[112:127]
	v_mfma_f32_32x32x16_bf16 v[48:63], v[234:237], v[180:183], v[48:63]
	s_waitcnt lgkmcnt(0)
	v_mfma_f32_32x32x16_bf16 v[96:111], v[238:241], v[176:179], v[96:111]
	v_mfma_f32_32x32x16_bf16 v[32:47], v[238:241], v[180:183], v[32:47]
	ds_read_b128 v[234:237], v204 offset:9280
	ds_read_b128 v[238:241], v204 offset:13888
	s_waitcnt vmcnt(7)
	ds_write_b128 v217, v[168:171]
	s_waitcnt vmcnt(6)
	ds_write_b128 v216, v[172:175]
	ds_read_b128 v[168:171], v205 offset:36960
	ds_read_b128 v[172:175], v205 offset:41568
	s_waitcnt lgkmcnt(5)
	v_mfma_f32_32x32x16_bf16 v[80:95], v[234:237], v[176:179], v[80:95]
	v_mfma_f32_32x32x16_bf16 v[16:31], v[234:237], v[180:183], v[16:31]
	ds_read_b128 v[234:237], v204 offset:96
	s_waitcnt lgkmcnt(5)
	v_mfma_f32_32x32x16_bf16 v[64:79], v[238:241], v[176:179], v[64:79]
	v_mfma_f32_32x32x16_bf16 v[0:15], v[238:241], v[180:183], v[0:15]
	ds_read_b128 v[238:241], v204 offset:4704
	s_setprio 0
	global_load_dwordx4 v[176:179], v[198:199], off offset:1024
	global_load_dwordx4 v[180:183], v[200:201], off offset:1024
	s_setprio 1
	s_waitcnt lgkmcnt(1)
	v_mfma_f32_32x32x16_bf16 v[112:127], v[234:237], v[168:171], v[112:127]
	v_mfma_f32_32x32x16_bf16 v[48:63], v[234:237], v[172:175], v[48:63]
	s_waitcnt lgkmcnt(0)
	v_mfma_f32_32x32x16_bf16 v[96:111], v[238:241], v[168:171], v[96:111]
	v_mfma_f32_32x32x16_bf16 v[32:47], v[238:241], v[172:175], v[32:47]
	ds_read_b128 v[234:237], v204 offset:9312
	ds_read_b128 v[238:241], v204 offset:13920
	s_waitcnt lgkmcnt(1)
	v_mfma_f32_32x32x16_bf16 v[80:95], v[234:237], v[168:171], v[80:95]
	v_mfma_f32_32x32x16_bf16 v[16:31], v[234:237], v[172:175], v[16:31]
	s_waitcnt lgkmcnt(0)
	v_mfma_f32_32x32x16_bf16 v[64:79], v[238:241], v[168:171], v[64:79]
	v_mfma_f32_32x32x16_bf16 v[0:15], v[238:241], v[172:175], v[0:15]
	s_setprio 0
	s_barrier
	global_load_dwordx4 v[168:171], v[190:191], off offset:1152
	global_load_dwordx4 v[172:175], v[188:189], off offset:1152
	s_waitcnt vmcnt(9)
	ds_write_b128 v215, v[160:163]
	s_waitcnt vmcnt(8)
	ds_write_b128 v215, v[164:167] offset:36864
	ds_read_b128 v[160:163], v208
	ds_read_b128 v[164:167], v208 offset:4608
	ds_read_b128 v[234:237], v192
	ds_read_b128 v[238:241], v192 offset:4608
	s_setprio 1
	s_waitcnt lgkmcnt(1)
	v_mfma_f32_32x32x16_bf16 v[112:127], v[234:237], v[160:163], v[112:127]
	v_mfma_f32_32x32x16_bf16 v[48:63], v[234:237], v[164:167], v[48:63]
	s_waitcnt lgkmcnt(0)
	v_mfma_f32_32x32x16_bf16 v[96:111], v[238:241], v[160:163], v[96:111]
	v_mfma_f32_32x32x16_bf16 v[32:47], v[238:241], v[164:167], v[32:47]
	ds_read_b128 v[234:237], v192 offset:9216
	ds_read_b128 v[238:241], v192 offset:13824
	s_waitcnt vmcnt(7)
	ds_write_b128 v215, v[218:221] offset:9216
	s_waitcnt vmcnt(6)
	ds_write_b128 v215, v[222:225] offset:46080
	ds_read_b128 v[218:221], v208 offset:32
	ds_read_b128 v[222:225], v208 offset:4640
	s_waitcnt lgkmcnt(5)
	v_mfma_f32_32x32x16_bf16 v[80:95], v[234:237], v[160:163], v[80:95]
	v_mfma_f32_32x32x16_bf16 v[16:31], v[234:237], v[164:167], v[16:31]
	ds_read_b128 v[234:237], v192 offset:32
	s_waitcnt lgkmcnt(5)
	v_mfma_f32_32x32x16_bf16 v[64:79], v[238:241], v[160:163], v[64:79]
	v_mfma_f32_32x32x16_bf16 v[0:15], v[238:241], v[164:167], v[0:15]
	ds_read_b128 v[238:241], v192 offset:4640
	s_setprio 0
	global_load_dwordx4 v[160:163], v[194:195], off offset:1152
	global_load_dwordx4 v[164:167], v[196:197], off offset:1152
	s_setprio 1
	s_waitcnt lgkmcnt(1)
	v_mfma_f32_32x32x16_bf16 v[112:127], v[234:237], v[218:221], v[112:127]
	v_mfma_f32_32x32x16_bf16 v[48:63], v[234:237], v[222:225], v[48:63]
	s_waitcnt lgkmcnt(0)
	v_mfma_f32_32x32x16_bf16 v[96:111], v[238:241], v[218:221], v[96:111]
	v_mfma_f32_32x32x16_bf16 v[32:47], v[238:241], v[222:225], v[32:47]
	ds_read_b128 v[234:237], v192 offset:9248
	ds_read_b128 v[238:241], v192 offset:13856
	s_waitcnt vmcnt(7)
	ds_write_b128 v215, v[226:229] offset:18432
	s_waitcnt vmcnt(6)
	ds_write_b128 v215, v[230:233] offset:55296
	ds_read_b128 v[226:229], v208 offset:64
	ds_read_b128 v[230:233], v208 offset:4672
	s_waitcnt lgkmcnt(5)
	v_mfma_f32_32x32x16_bf16 v[80:95], v[234:237], v[218:221], v[80:95]
	v_mfma_f32_32x32x16_bf16 v[16:31], v[234:237], v[222:225], v[16:31]
	ds_read_b128 v[234:237], v192 offset:64
	s_waitcnt lgkmcnt(5)
	v_mfma_f32_32x32x16_bf16 v[64:79], v[238:241], v[218:221], v[64:79]
	v_mfma_f32_32x32x16_bf16 v[0:15], v[238:241], v[222:225], v[0:15]
	ds_read_b128 v[238:241], v192 offset:4672
	s_setprio 0
	global_load_dwordx4 v[218:221], v[184:185], off offset:1152
	global_load_dwordx4 v[222:225], v[186:187], off offset:1152
	s_setprio 1
	s_waitcnt lgkmcnt(1)
	v_mfma_f32_32x32x16_bf16 v[112:127], v[234:237], v[226:229], v[112:127]
	v_mfma_f32_32x32x16_bf16 v[48:63], v[234:237], v[230:233], v[48:63]
	s_waitcnt lgkmcnt(0)
	v_mfma_f32_32x32x16_bf16 v[96:111], v[238:241], v[226:229], v[96:111]
	v_mfma_f32_32x32x16_bf16 v[32:47], v[238:241], v[230:233], v[32:47]
	ds_read_b128 v[234:237], v192 offset:9280
	ds_read_b128 v[238:241], v192 offset:13888
	s_waitcnt vmcnt(7)
	ds_write_b128 v215, v[176:179] offset:27648
	s_waitcnt vmcnt(6)
	ds_write_b128 v215, v[180:183] offset:64512
	ds_read_b128 v[176:179], v208 offset:96
	ds_read_b128 v[180:183], v208 offset:4704
	s_waitcnt lgkmcnt(5)
	v_mfma_f32_32x32x16_bf16 v[80:95], v[234:237], v[226:229], v[80:95]
	v_mfma_f32_32x32x16_bf16 v[16:31], v[234:237], v[230:233], v[16:31]
	ds_read_b128 v[234:237], v192 offset:96
	s_waitcnt lgkmcnt(5)
	v_mfma_f32_32x32x16_bf16 v[64:79], v[238:241], v[226:229], v[64:79]
	v_mfma_f32_32x32x16_bf16 v[0:15], v[238:241], v[230:233], v[0:15]
	ds_read_b128 v[238:241], v192 offset:4704
	s_setprio 0
	global_load_dwordx4 v[226:229], v[198:199], off offset:1152
	global_load_dwordx4 v[230:233], v[200:201], off offset:1152
	s_setprio 1
	s_waitcnt lgkmcnt(1)
	v_mfma_f32_32x32x16_bf16 v[112:127], v[234:237], v[176:179], v[112:127]
	v_mfma_f32_32x32x16_bf16 v[48:63], v[234:237], v[180:183], v[48:63]
	s_waitcnt lgkmcnt(0)
	v_mfma_f32_32x32x16_bf16 v[96:111], v[238:241], v[176:179], v[96:111]
	v_mfma_f32_32x32x16_bf16 v[32:47], v[238:241], v[180:183], v[32:47]
	ds_read_b128 v[234:237], v192 offset:9312
	ds_read_b128 v[238:241], v192 offset:13920
	s_waitcnt lgkmcnt(1)
	v_mfma_f32_32x32x16_bf16 v[80:95], v[234:237], v[176:179], v[80:95]
	v_mfma_f32_32x32x16_bf16 v[16:31], v[234:237], v[180:183], v[16:31]
	s_waitcnt lgkmcnt(0)
	v_mfma_f32_32x32x16_bf16 v[64:79], v[238:241], v[176:179], v[64:79]
	v_mfma_f32_32x32x16_bf16 v[0:15], v[238:241], v[180:183], v[0:15]
	s_setprio 0
	s_barrier
	global_load_dwordx4 v[176:179], v[190:191], off offset:1280
	global_load_dwordx4 v[180:183], v[188:189], off offset:1280
	s_waitcnt vmcnt(9)
	ds_write_b128 v209, v[168:171]
	s_waitcnt vmcnt(8)
	ds_write_b128 v210, v[172:175]
	ds_read_b128 v[168:171], v205 offset:36864
	ds_read_b128 v[172:175], v205 offset:41472
	ds_read_b128 v[234:237], v204
	ds_read_b128 v[238:241], v204 offset:4608
	s_setprio 1
	s_waitcnt lgkmcnt(1)
	v_mfma_f32_32x32x16_bf16 v[112:127], v[234:237], v[168:171], v[112:127]
	v_mfma_f32_32x32x16_bf16 v[48:63], v[234:237], v[172:175], v[48:63]
	s_waitcnt lgkmcnt(0)
	v_mfma_f32_32x32x16_bf16 v[96:111], v[238:241], v[168:171], v[96:111]
	v_mfma_f32_32x32x16_bf16 v[32:47], v[238:241], v[172:175], v[32:47]
	ds_read_b128 v[234:237], v204 offset:9216
	ds_read_b128 v[238:241], v204 offset:13824
	s_waitcnt vmcnt(7)
	ds_write_b128 v212, v[160:163]
	s_waitcnt vmcnt(6)
	ds_write_b128 v211, v[164:167]
	ds_read_b128 v[160:163], v205 offset:36896
	ds_read_b128 v[164:167], v205 offset:41504
	s_waitcnt lgkmcnt(5)
	v_mfma_f32_32x32x16_bf16 v[80:95], v[234:237], v[168:171], v[80:95]
	v_mfma_f32_32x32x16_bf16 v[16:31], v[234:237], v[172:175], v[16:31]
	ds_read_b128 v[234:237], v204 offset:32
	s_waitcnt lgkmcnt(5)
	v_mfma_f32_32x32x16_bf16 v[64:79], v[238:241], v[168:171], v[64:79]
	v_mfma_f32_32x32x16_bf16 v[0:15], v[238:241], v[172:175], v[0:15]
	ds_read_b128 v[238:241], v204 offset:4640
	s_setprio 0
	global_load_dwordx4 v[168:171], v[194:195], off offset:1280
	global_load_dwordx4 v[172:175], v[196:197], off offset:1280
	s_setprio 1
	s_waitcnt lgkmcnt(1)
	v_mfma_f32_32x32x16_bf16 v[112:127], v[234:237], v[160:163], v[112:127]
	v_mfma_f32_32x32x16_bf16 v[48:63], v[234:237], v[164:167], v[48:63]
	s_waitcnt lgkmcnt(0)
	v_mfma_f32_32x32x16_bf16 v[96:111], v[238:241], v[160:163], v[96:111]
	v_mfma_f32_32x32x16_bf16 v[32:47], v[238:241], v[164:167], v[32:47]
	ds_read_b128 v[234:237], v204 offset:9248
	ds_read_b128 v[238:241], v204 offset:13856
	s_waitcnt vmcnt(7)
	ds_write_b128 v214, v[218:221]
	s_waitcnt vmcnt(6)
	ds_write_b128 v213, v[222:225]
	ds_read_b128 v[218:221], v205 offset:36928
	ds_read_b128 v[222:225], v205 offset:41536
	s_waitcnt lgkmcnt(5)
	v_mfma_f32_32x32x16_bf16 v[80:95], v[234:237], v[160:163], v[80:95]
	v_mfma_f32_32x32x16_bf16 v[16:31], v[234:237], v[164:167], v[16:31]
	ds_read_b128 v[234:237], v204 offset:64
	s_waitcnt lgkmcnt(5)
	v_mfma_f32_32x32x16_bf16 v[64:79], v[238:241], v[160:163], v[64:79]
	v_mfma_f32_32x32x16_bf16 v[0:15], v[238:241], v[164:167], v[0:15]
	ds_read_b128 v[238:241], v204 offset:4672
	s_setprio 0
	global_load_dwordx4 v[160:163], v[184:185], off offset:1280
	global_load_dwordx4 v[164:167], v[186:187], off offset:1280
	s_setprio 1
	s_waitcnt lgkmcnt(1)
	v_mfma_f32_32x32x16_bf16 v[112:127], v[234:237], v[218:221], v[112:127]
	v_mfma_f32_32x32x16_bf16 v[48:63], v[234:237], v[222:225], v[48:63]
	s_waitcnt lgkmcnt(0)
	v_mfma_f32_32x32x16_bf16 v[96:111], v[238:241], v[218:221], v[96:111]
	v_mfma_f32_32x32x16_bf16 v[32:47], v[238:241], v[222:225], v[32:47]
	ds_read_b128 v[234:237], v204 offset:9280
	ds_read_b128 v[238:241], v204 offset:13888
	s_waitcnt vmcnt(7)
	ds_write_b128 v217, v[226:229]
	s_waitcnt vmcnt(6)
	ds_write_b128 v216, v[230:233]
	ds_read_b128 v[226:229], v205 offset:36960
	ds_read_b128 v[230:233], v205 offset:41568
	s_waitcnt lgkmcnt(5)
	v_mfma_f32_32x32x16_bf16 v[80:95], v[234:237], v[218:221], v[80:95]
	v_mfma_f32_32x32x16_bf16 v[16:31], v[234:237], v[222:225], v[16:31]
	ds_read_b128 v[234:237], v204 offset:96
	s_waitcnt lgkmcnt(5)
	v_mfma_f32_32x32x16_bf16 v[64:79], v[238:241], v[218:221], v[64:79]
	v_mfma_f32_32x32x16_bf16 v[0:15], v[238:241], v[222:225], v[0:15]
	ds_read_b128 v[238:241], v204 offset:4704
	s_setprio 0
	global_load_dwordx4 v[218:221], v[198:199], off offset:1280
	global_load_dwordx4 v[222:225], v[200:201], off offset:1280
	s_setprio 1
	s_waitcnt lgkmcnt(1)
	v_mfma_f32_32x32x16_bf16 v[112:127], v[234:237], v[226:229], v[112:127]
	v_mfma_f32_32x32x16_bf16 v[48:63], v[234:237], v[230:233], v[48:63]
	s_waitcnt lgkmcnt(0)
	v_mfma_f32_32x32x16_bf16 v[96:111], v[238:241], v[226:229], v[96:111]
	v_mfma_f32_32x32x16_bf16 v[32:47], v[238:241], v[230:233], v[32:47]
	ds_read_b128 v[234:237], v204 offset:9312
	ds_read_b128 v[238:241], v204 offset:13920
	s_waitcnt lgkmcnt(1)
	v_mfma_f32_32x32x16_bf16 v[80:95], v[234:237], v[226:229], v[80:95]
	v_mfma_f32_32x32x16_bf16 v[16:31], v[234:237], v[230:233], v[16:31]
	s_waitcnt lgkmcnt(0)
	v_mfma_f32_32x32x16_bf16 v[64:79], v[238:241], v[226:229], v[64:79]
	v_mfma_f32_32x32x16_bf16 v[0:15], v[238:241], v[230:233], v[0:15]
	s_setprio 0
	s_barrier
	global_load_dwordx4 v[226:229], v[190:191], off offset:1408
	global_load_dwordx4 v[230:233], v[188:189], off offset:1408
	s_waitcnt vmcnt(9)
	ds_write_b128 v215, v[176:179]
	s_waitcnt vmcnt(8)
	ds_write_b128 v215, v[180:183] offset:36864
	ds_read_b128 v[176:179], v208
	ds_read_b128 v[180:183], v208 offset:4608
	ds_read_b128 v[234:237], v192
	ds_read_b128 v[238:241], v192 offset:4608
	s_setprio 1
	s_waitcnt lgkmcnt(1)
	v_mfma_f32_32x32x16_bf16 v[112:127], v[234:237], v[176:179], v[112:127]
	v_mfma_f32_32x32x16_bf16 v[48:63], v[234:237], v[180:183], v[48:63]
	s_waitcnt lgkmcnt(0)
	v_mfma_f32_32x32x16_bf16 v[96:111], v[238:241], v[176:179], v[96:111]
	v_mfma_f32_32x32x16_bf16 v[32:47], v[238:241], v[180:183], v[32:47]
	ds_read_b128 v[234:237], v192 offset:9216
	ds_read_b128 v[238:241], v192 offset:13824
	s_waitcnt vmcnt(7)
	ds_write_b128 v215, v[168:171] offset:9216
	s_waitcnt vmcnt(6)
	ds_write_b128 v215, v[172:175] offset:46080
	ds_read_b128 v[168:171], v208 offset:32
	ds_read_b128 v[172:175], v208 offset:4640
	s_waitcnt lgkmcnt(5)
	v_mfma_f32_32x32x16_bf16 v[80:95], v[234:237], v[176:179], v[80:95]
	v_mfma_f32_32x32x16_bf16 v[16:31], v[234:237], v[180:183], v[16:31]
	ds_read_b128 v[234:237], v192 offset:32
	s_waitcnt lgkmcnt(5)
	v_mfma_f32_32x32x16_bf16 v[64:79], v[238:241], v[176:179], v[64:79]
	v_mfma_f32_32x32x16_bf16 v[0:15], v[238:241], v[180:183], v[0:15]
	ds_read_b128 v[238:241], v192 offset:4640
	s_setprio 0
	global_load_dwordx4 v[176:179], v[194:195], off offset:1408
	global_load_dwordx4 v[180:183], v[196:197], off offset:1408
	s_setprio 1
	s_waitcnt lgkmcnt(1)
	v_mfma_f32_32x32x16_bf16 v[112:127], v[234:237], v[168:171], v[112:127]
	v_mfma_f32_32x32x16_bf16 v[48:63], v[234:237], v[172:175], v[48:63]
	s_waitcnt lgkmcnt(0)
	v_mfma_f32_32x32x16_bf16 v[96:111], v[238:241], v[168:171], v[96:111]
	v_mfma_f32_32x32x16_bf16 v[32:47], v[238:241], v[172:175], v[32:47]
	ds_read_b128 v[234:237], v192 offset:9248
	ds_read_b128 v[238:241], v192 offset:13856
	s_waitcnt vmcnt(7)
	ds_write_b128 v215, v[160:163] offset:18432
	s_waitcnt vmcnt(6)
	ds_write_b128 v215, v[164:167] offset:55296
	ds_read_b128 v[160:163], v208 offset:64
	ds_read_b128 v[164:167], v208 offset:4672
	s_waitcnt lgkmcnt(5)
	v_mfma_f32_32x32x16_bf16 v[80:95], v[234:237], v[168:171], v[80:95]
	v_mfma_f32_32x32x16_bf16 v[16:31], v[234:237], v[172:175], v[16:31]
	ds_read_b128 v[234:237], v192 offset:64
	s_waitcnt lgkmcnt(5)
	v_mfma_f32_32x32x16_bf16 v[64:79], v[238:241], v[168:171], v[64:79]
	v_mfma_f32_32x32x16_bf16 v[0:15], v[238:241], v[172:175], v[0:15]
	ds_read_b128 v[238:241], v192 offset:4672
	s_setprio 0
	global_load_dwordx4 v[168:171], v[184:185], off offset:1408
	global_load_dwordx4 v[172:175], v[186:187], off offset:1408
	s_setprio 1
	s_waitcnt lgkmcnt(1)
	v_mfma_f32_32x32x16_bf16 v[112:127], v[234:237], v[160:163], v[112:127]
	v_mfma_f32_32x32x16_bf16 v[48:63], v[234:237], v[164:167], v[48:63]
	s_waitcnt lgkmcnt(0)
	v_mfma_f32_32x32x16_bf16 v[96:111], v[238:241], v[160:163], v[96:111]
	v_mfma_f32_32x32x16_bf16 v[32:47], v[238:241], v[164:167], v[32:47]
	ds_read_b128 v[234:237], v192 offset:9280
	ds_read_b128 v[238:241], v192 offset:13888
	s_waitcnt vmcnt(7)
	ds_write_b128 v215, v[218:221] offset:27648
	s_waitcnt vmcnt(6)
	ds_write_b128 v215, v[222:225] offset:64512
	ds_read_b128 v[218:221], v208 offset:96
	ds_read_b128 v[222:225], v208 offset:4704
	s_waitcnt lgkmcnt(5)
	v_mfma_f32_32x32x16_bf16 v[80:95], v[234:237], v[160:163], v[80:95]
	v_mfma_f32_32x32x16_bf16 v[16:31], v[234:237], v[164:167], v[16:31]
	ds_read_b128 v[234:237], v192 offset:96
	s_waitcnt lgkmcnt(5)
	v_mfma_f32_32x32x16_bf16 v[64:79], v[238:241], v[160:163], v[64:79]
	v_mfma_f32_32x32x16_bf16 v[0:15], v[238:241], v[164:167], v[0:15]
	ds_read_b128 v[238:241], v192 offset:4704
	s_setprio 0
	global_load_dwordx4 v[160:163], v[198:199], off offset:1408
	global_load_dwordx4 v[164:167], v[200:201], off offset:1408
	s_setprio 1
	s_waitcnt lgkmcnt(1)
	v_mfma_f32_32x32x16_bf16 v[112:127], v[234:237], v[218:221], v[112:127]
	v_mfma_f32_32x32x16_bf16 v[48:63], v[234:237], v[222:225], v[48:63]
	s_waitcnt lgkmcnt(0)
	v_mfma_f32_32x32x16_bf16 v[96:111], v[238:241], v[218:221], v[96:111]
	v_mfma_f32_32x32x16_bf16 v[32:47], v[238:241], v[222:225], v[32:47]
	ds_read_b128 v[234:237], v192 offset:9312
	ds_read_b128 v[238:241], v192 offset:13920
	s_waitcnt lgkmcnt(1)
	v_mfma_f32_32x32x16_bf16 v[80:95], v[234:237], v[218:221], v[80:95]
	v_mfma_f32_32x32x16_bf16 v[16:31], v[234:237], v[222:225], v[16:31]
	s_waitcnt lgkmcnt(0)
	v_mfma_f32_32x32x16_bf16 v[64:79], v[238:241], v[218:221], v[64:79]
	v_mfma_f32_32x32x16_bf16 v[0:15], v[238:241], v[222:225], v[0:15]
	s_setprio 0
	s_barrier
	global_load_dwordx4 v[218:221], v[190:191], off offset:1536
	global_load_dwordx4 v[222:225], v[188:189], off offset:1536
	s_waitcnt vmcnt(9)
	ds_write_b128 v209, v[226:229]
	s_waitcnt vmcnt(8)
	ds_write_b128 v210, v[230:233]
	ds_read_b128 v[226:229], v205 offset:36864
	ds_read_b128 v[230:233], v205 offset:41472
	ds_read_b128 v[234:237], v204
	ds_read_b128 v[238:241], v204 offset:4608
	s_setprio 1
	s_waitcnt lgkmcnt(1)
	v_mfma_f32_32x32x16_bf16 v[112:127], v[234:237], v[226:229], v[112:127]
	v_mfma_f32_32x32x16_bf16 v[48:63], v[234:237], v[230:233], v[48:63]
	s_waitcnt lgkmcnt(0)
	v_mfma_f32_32x32x16_bf16 v[96:111], v[238:241], v[226:229], v[96:111]
	v_mfma_f32_32x32x16_bf16 v[32:47], v[238:241], v[230:233], v[32:47]
	ds_read_b128 v[234:237], v204 offset:9216
	ds_read_b128 v[238:241], v204 offset:13824
	s_waitcnt vmcnt(7)
	ds_write_b128 v212, v[176:179]
	s_waitcnt vmcnt(6)
	ds_write_b128 v211, v[180:183]
	ds_read_b128 v[176:179], v205 offset:36896
	ds_read_b128 v[180:183], v205 offset:41504
	s_waitcnt lgkmcnt(5)
	v_mfma_f32_32x32x16_bf16 v[80:95], v[234:237], v[226:229], v[80:95]
	v_mfma_f32_32x32x16_bf16 v[16:31], v[234:237], v[230:233], v[16:31]
	ds_read_b128 v[234:237], v204 offset:32
	s_waitcnt lgkmcnt(5)
	v_mfma_f32_32x32x16_bf16 v[64:79], v[238:241], v[226:229], v[64:79]
	v_mfma_f32_32x32x16_bf16 v[0:15], v[238:241], v[230:233], v[0:15]
	ds_read_b128 v[238:241], v204 offset:4640
	s_setprio 0
	global_load_dwordx4 v[226:229], v[194:195], off offset:1536
	global_load_dwordx4 v[230:233], v[196:197], off offset:1536
	s_setprio 1
	s_waitcnt lgkmcnt(1)
	v_mfma_f32_32x32x16_bf16 v[112:127], v[234:237], v[176:179], v[112:127]
	v_mfma_f32_32x32x16_bf16 v[48:63], v[234:237], v[180:183], v[48:63]
	s_waitcnt lgkmcnt(0)
	v_mfma_f32_32x32x16_bf16 v[96:111], v[238:241], v[176:179], v[96:111]
	v_mfma_f32_32x32x16_bf16 v[32:47], v[238:241], v[180:183], v[32:47]
	ds_read_b128 v[234:237], v204 offset:9248
	ds_read_b128 v[238:241], v204 offset:13856
	s_waitcnt vmcnt(7)
	ds_write_b128 v214, v[168:171]
	s_waitcnt vmcnt(6)
	ds_write_b128 v213, v[172:175]
	ds_read_b128 v[168:171], v205 offset:36928
	ds_read_b128 v[172:175], v205 offset:41536
	s_waitcnt lgkmcnt(5)
	v_mfma_f32_32x32x16_bf16 v[80:95], v[234:237], v[176:179], v[80:95]
	v_mfma_f32_32x32x16_bf16 v[16:31], v[234:237], v[180:183], v[16:31]
	ds_read_b128 v[234:237], v204 offset:64
	s_waitcnt lgkmcnt(5)
	v_mfma_f32_32x32x16_bf16 v[64:79], v[238:241], v[176:179], v[64:79]
	v_mfma_f32_32x32x16_bf16 v[0:15], v[238:241], v[180:183], v[0:15]
	ds_read_b128 v[238:241], v204 offset:4672
	s_setprio 0
	global_load_dwordx4 v[176:179], v[184:185], off offset:1536
	global_load_dwordx4 v[180:183], v[186:187], off offset:1536
	s_setprio 1
	s_waitcnt lgkmcnt(1)
	v_mfma_f32_32x32x16_bf16 v[112:127], v[234:237], v[168:171], v[112:127]
	v_mfma_f32_32x32x16_bf16 v[48:63], v[234:237], v[172:175], v[48:63]
	s_waitcnt lgkmcnt(0)
	v_mfma_f32_32x32x16_bf16 v[96:111], v[238:241], v[168:171], v[96:111]
	v_mfma_f32_32x32x16_bf16 v[32:47], v[238:241], v[172:175], v[32:47]
	ds_read_b128 v[234:237], v204 offset:9280
	ds_read_b128 v[238:241], v204 offset:13888
	s_waitcnt vmcnt(7)
	ds_write_b128 v217, v[160:163]
	s_waitcnt vmcnt(6)
	ds_write_b128 v216, v[164:167]
	ds_read_b128 v[160:163], v205 offset:36960
	ds_read_b128 v[164:167], v205 offset:41568
	s_waitcnt lgkmcnt(5)
	v_mfma_f32_32x32x16_bf16 v[80:95], v[234:237], v[168:171], v[80:95]
	v_mfma_f32_32x32x16_bf16 v[16:31], v[234:237], v[172:175], v[16:31]
	ds_read_b128 v[234:237], v204 offset:96
	s_waitcnt lgkmcnt(5)
	v_mfma_f32_32x32x16_bf16 v[64:79], v[238:241], v[168:171], v[64:79]
	v_mfma_f32_32x32x16_bf16 v[0:15], v[238:241], v[172:175], v[0:15]
	ds_read_b128 v[238:241], v204 offset:4704
	s_setprio 0
	global_load_dwordx4 v[168:171], v[198:199], off offset:1536
	global_load_dwordx4 v[172:175], v[200:201], off offset:1536
	s_setprio 1
	s_waitcnt lgkmcnt(1)
	v_mfma_f32_32x32x16_bf16 v[112:127], v[234:237], v[160:163], v[112:127]
	v_mfma_f32_32x32x16_bf16 v[48:63], v[234:237], v[164:167], v[48:63]
	s_waitcnt lgkmcnt(0)
	v_mfma_f32_32x32x16_bf16 v[96:111], v[238:241], v[160:163], v[96:111]
	v_mfma_f32_32x32x16_bf16 v[32:47], v[238:241], v[164:167], v[32:47]
	ds_read_b128 v[234:237], v204 offset:9312
	ds_read_b128 v[238:241], v204 offset:13920
	s_waitcnt lgkmcnt(1)
	v_mfma_f32_32x32x16_bf16 v[80:95], v[234:237], v[160:163], v[80:95]
	v_mfma_f32_32x32x16_bf16 v[16:31], v[234:237], v[164:167], v[16:31]
	s_waitcnt lgkmcnt(0)
	v_mfma_f32_32x32x16_bf16 v[64:79], v[238:241], v[160:163], v[64:79]
	v_mfma_f32_32x32x16_bf16 v[0:15], v[238:241], v[164:167], v[0:15]
	s_setprio 0
	s_barrier
	global_load_dwordx4 v[160:163], v[190:191], off offset:1664
	global_load_dwordx4 v[164:167], v[188:189], off offset:1664
	s_waitcnt vmcnt(9)
	ds_write_b128 v215, v[218:221]
	s_waitcnt vmcnt(8)
	ds_write_b128 v215, v[222:225] offset:36864
	ds_read_b128 v[218:221], v208
	ds_read_b128 v[222:225], v208 offset:4608
	ds_read_b128 v[234:237], v192
	ds_read_b128 v[238:241], v192 offset:4608
	s_setprio 1
	s_waitcnt lgkmcnt(1)
	v_mfma_f32_32x32x16_bf16 v[112:127], v[234:237], v[218:221], v[112:127]
	v_mfma_f32_32x32x16_bf16 v[48:63], v[234:237], v[222:225], v[48:63]
	s_waitcnt lgkmcnt(0)
	v_mfma_f32_32x32x16_bf16 v[96:111], v[238:241], v[218:221], v[96:111]
	v_mfma_f32_32x32x16_bf16 v[32:47], v[238:241], v[222:225], v[32:47]
	ds_read_b128 v[234:237], v192 offset:9216
	ds_read_b128 v[238:241], v192 offset:13824
	s_waitcnt vmcnt(7)
	ds_write_b128 v215, v[226:229] offset:9216
	s_waitcnt vmcnt(6)
	ds_write_b128 v215, v[230:233] offset:46080
	ds_read_b128 v[226:229], v208 offset:32
	ds_read_b128 v[230:233], v208 offset:4640
	s_waitcnt lgkmcnt(5)
	v_mfma_f32_32x32x16_bf16 v[80:95], v[234:237], v[218:221], v[80:95]
	v_mfma_f32_32x32x16_bf16 v[16:31], v[234:237], v[222:225], v[16:31]
	ds_read_b128 v[234:237], v192 offset:32
	s_waitcnt lgkmcnt(5)
	v_mfma_f32_32x32x16_bf16 v[64:79], v[238:241], v[218:221], v[64:79]
	v_mfma_f32_32x32x16_bf16 v[0:15], v[238:241], v[222:225], v[0:15]
	ds_read_b128 v[238:241], v192 offset:4640
	s_setprio 0
	global_load_dwordx4 v[218:221], v[194:195], off offset:1664
	global_load_dwordx4 v[222:225], v[196:197], off offset:1664
	s_setprio 1
	s_waitcnt lgkmcnt(1)
	v_mfma_f32_32x32x16_bf16 v[112:127], v[234:237], v[226:229], v[112:127]
	v_mfma_f32_32x32x16_bf16 v[48:63], v[234:237], v[230:233], v[48:63]
	s_waitcnt lgkmcnt(0)
	v_mfma_f32_32x32x16_bf16 v[96:111], v[238:241], v[226:229], v[96:111]
	v_mfma_f32_32x32x16_bf16 v[32:47], v[238:241], v[230:233], v[32:47]
	ds_read_b128 v[234:237], v192 offset:9248
	ds_read_b128 v[238:241], v192 offset:13856
	s_waitcnt vmcnt(7)
	ds_write_b128 v215, v[176:179] offset:18432
	s_waitcnt vmcnt(6)
	ds_write_b128 v215, v[180:183] offset:55296
	ds_read_b128 v[176:179], v208 offset:64
	ds_read_b128 v[180:183], v208 offset:4672
	s_waitcnt lgkmcnt(5)
	v_mfma_f32_32x32x16_bf16 v[80:95], v[234:237], v[226:229], v[80:95]
	v_mfma_f32_32x32x16_bf16 v[16:31], v[234:237], v[230:233], v[16:31]
	ds_read_b128 v[234:237], v192 offset:64
	s_waitcnt lgkmcnt(5)
	v_mfma_f32_32x32x16_bf16 v[64:79], v[238:241], v[226:229], v[64:79]
	v_mfma_f32_32x32x16_bf16 v[0:15], v[238:241], v[230:233], v[0:15]
	ds_read_b128 v[238:241], v192 offset:4672
	s_setprio 0
	global_load_dwordx4 v[226:229], v[184:185], off offset:1664
	global_load_dwordx4 v[230:233], v[186:187], off offset:1664
	s_setprio 1
	s_waitcnt lgkmcnt(1)
	v_mfma_f32_32x32x16_bf16 v[112:127], v[234:237], v[176:179], v[112:127]
	v_mfma_f32_32x32x16_bf16 v[48:63], v[234:237], v[180:183], v[48:63]
	s_waitcnt lgkmcnt(0)
	v_mfma_f32_32x32x16_bf16 v[96:111], v[238:241], v[176:179], v[96:111]
	v_mfma_f32_32x32x16_bf16 v[32:47], v[238:241], v[180:183], v[32:47]
	ds_read_b128 v[234:237], v192 offset:9280
	ds_read_b128 v[238:241], v192 offset:13888
	s_waitcnt vmcnt(7)
	ds_write_b128 v215, v[168:171] offset:27648
	s_waitcnt vmcnt(6)
	ds_write_b128 v215, v[172:175] offset:64512
	ds_read_b128 v[168:171], v208 offset:96
	ds_read_b128 v[172:175], v208 offset:4704
	s_waitcnt lgkmcnt(5)
	v_mfma_f32_32x32x16_bf16 v[80:95], v[234:237], v[176:179], v[80:95]
	v_mfma_f32_32x32x16_bf16 v[16:31], v[234:237], v[180:183], v[16:31]
	ds_read_b128 v[234:237], v192 offset:96
	s_waitcnt lgkmcnt(5)
	v_mfma_f32_32x32x16_bf16 v[64:79], v[238:241], v[176:179], v[64:79]
	v_mfma_f32_32x32x16_bf16 v[0:15], v[238:241], v[180:183], v[0:15]
	ds_read_b128 v[238:241], v192 offset:4704
	s_setprio 0
	global_load_dwordx4 v[176:179], v[198:199], off offset:1664
	global_load_dwordx4 v[180:183], v[200:201], off offset:1664
	s_setprio 1
	s_waitcnt lgkmcnt(1)
	v_mfma_f32_32x32x16_bf16 v[112:127], v[234:237], v[168:171], v[112:127]
	v_mfma_f32_32x32x16_bf16 v[48:63], v[234:237], v[172:175], v[48:63]
	s_waitcnt lgkmcnt(0)
	v_mfma_f32_32x32x16_bf16 v[96:111], v[238:241], v[168:171], v[96:111]
	v_mfma_f32_32x32x16_bf16 v[32:47], v[238:241], v[172:175], v[32:47]
	ds_read_b128 v[234:237], v192 offset:9312
	ds_read_b128 v[238:241], v192 offset:13920
	s_waitcnt lgkmcnt(1)
	v_mfma_f32_32x32x16_bf16 v[80:95], v[234:237], v[168:171], v[80:95]
	v_mfma_f32_32x32x16_bf16 v[16:31], v[234:237], v[172:175], v[16:31]
	s_waitcnt lgkmcnt(0)
	v_mfma_f32_32x32x16_bf16 v[64:79], v[238:241], v[168:171], v[64:79]
	v_mfma_f32_32x32x16_bf16 v[0:15], v[238:241], v[172:175], v[0:15]
	s_setprio 0
	s_barrier
	global_load_dwordx4 v[168:171], v[190:191], off offset:1792
	global_load_dwordx4 v[172:175], v[188:189], off offset:1792
	s_waitcnt vmcnt(9)
	ds_write_b128 v209, v[160:163]
	s_waitcnt vmcnt(8)
	ds_write_b128 v210, v[164:167]
	ds_read_b128 v[160:163], v205 offset:36864
	ds_read_b128 v[164:167], v205 offset:41472
	ds_read_b128 v[234:237], v204
	ds_read_b128 v[238:241], v204 offset:4608
	s_setprio 1
	s_waitcnt lgkmcnt(1)
	v_mfma_f32_32x32x16_bf16 v[112:127], v[234:237], v[160:163], v[112:127]
	v_mfma_f32_32x32x16_bf16 v[48:63], v[234:237], v[164:167], v[48:63]
	s_waitcnt lgkmcnt(0)
	v_mfma_f32_32x32x16_bf16 v[96:111], v[238:241], v[160:163], v[96:111]
	v_mfma_f32_32x32x16_bf16 v[32:47], v[238:241], v[164:167], v[32:47]
	ds_read_b128 v[234:237], v204 offset:9216
	ds_read_b128 v[238:241], v204 offset:13824
	s_waitcnt vmcnt(7)
	ds_write_b128 v212, v[218:221]
	s_waitcnt vmcnt(6)
	ds_write_b128 v211, v[222:225]
	ds_read_b128 v[218:221], v205 offset:36896
	ds_read_b128 v[222:225], v205 offset:41504
	s_waitcnt lgkmcnt(5)
	v_mfma_f32_32x32x16_bf16 v[80:95], v[234:237], v[160:163], v[80:95]
	v_mfma_f32_32x32x16_bf16 v[16:31], v[234:237], v[164:167], v[16:31]
	ds_read_b128 v[234:237], v204 offset:32
	s_waitcnt lgkmcnt(5)
	v_mfma_f32_32x32x16_bf16 v[64:79], v[238:241], v[160:163], v[64:79]
	v_mfma_f32_32x32x16_bf16 v[0:15], v[238:241], v[164:167], v[0:15]
	ds_read_b128 v[238:241], v204 offset:4640
	s_setprio 0
	global_load_dwordx4 v[160:163], v[194:195], off offset:1792
	global_load_dwordx4 v[164:167], v[196:197], off offset:1792
	s_setprio 1
	s_waitcnt lgkmcnt(1)
	v_mfma_f32_32x32x16_bf16 v[112:127], v[234:237], v[218:221], v[112:127]
	v_mfma_f32_32x32x16_bf16 v[48:63], v[234:237], v[222:225], v[48:63]
	s_waitcnt lgkmcnt(0)
	v_mfma_f32_32x32x16_bf16 v[96:111], v[238:241], v[218:221], v[96:111]
	v_mfma_f32_32x32x16_bf16 v[32:47], v[238:241], v[222:225], v[32:47]
	ds_read_b128 v[234:237], v204 offset:9248
	ds_read_b128 v[238:241], v204 offset:13856
	s_waitcnt vmcnt(7)
	ds_write_b128 v214, v[226:229]
	s_waitcnt vmcnt(6)
	ds_write_b128 v213, v[230:233]
	ds_read_b128 v[226:229], v205 offset:36928
	ds_read_b128 v[230:233], v205 offset:41536
	s_waitcnt lgkmcnt(5)
	v_mfma_f32_32x32x16_bf16 v[80:95], v[234:237], v[218:221], v[80:95]
	v_mfma_f32_32x32x16_bf16 v[16:31], v[234:237], v[222:225], v[16:31]
	ds_read_b128 v[234:237], v204 offset:64
	s_waitcnt lgkmcnt(5)
	v_mfma_f32_32x32x16_bf16 v[64:79], v[238:241], v[218:221], v[64:79]
	v_mfma_f32_32x32x16_bf16 v[0:15], v[238:241], v[222:225], v[0:15]
	ds_read_b128 v[238:241], v204 offset:4672
	s_setprio 0
	global_load_dwordx4 v[218:221], v[184:185], off offset:1792
	global_load_dwordx4 v[222:225], v[186:187], off offset:1792
	s_setprio 1
	s_waitcnt lgkmcnt(1)
	v_mfma_f32_32x32x16_bf16 v[112:127], v[234:237], v[226:229], v[112:127]
	v_mfma_f32_32x32x16_bf16 v[48:63], v[234:237], v[230:233], v[48:63]
	s_waitcnt lgkmcnt(0)
	v_mfma_f32_32x32x16_bf16 v[96:111], v[238:241], v[226:229], v[96:111]
	v_mfma_f32_32x32x16_bf16 v[32:47], v[238:241], v[230:233], v[32:47]
	ds_read_b128 v[234:237], v204 offset:9280
	ds_read_b128 v[238:241], v204 offset:13888
	s_waitcnt vmcnt(7)
	ds_write_b128 v217, v[176:179]
	s_waitcnt vmcnt(6)
	ds_write_b128 v216, v[180:183]
	ds_read_b128 v[176:179], v205 offset:36960
	ds_read_b128 v[180:183], v205 offset:41568
	s_waitcnt lgkmcnt(5)
	v_mfma_f32_32x32x16_bf16 v[80:95], v[234:237], v[226:229], v[80:95]
	v_mfma_f32_32x32x16_bf16 v[16:31], v[234:237], v[230:233], v[16:31]
	ds_read_b128 v[234:237], v204 offset:96
	s_waitcnt lgkmcnt(5)
	v_mfma_f32_32x32x16_bf16 v[64:79], v[238:241], v[226:229], v[64:79]
	v_mfma_f32_32x32x16_bf16 v[0:15], v[238:241], v[230:233], v[0:15]
	ds_read_b128 v[238:241], v204 offset:4704
	s_setprio 0
	global_load_dwordx4 v[226:229], v[198:199], off offset:1792
	global_load_dwordx4 v[230:233], v[200:201], off offset:1792
	s_setprio 1
	s_waitcnt lgkmcnt(1)
	v_mfma_f32_32x32x16_bf16 v[112:127], v[234:237], v[176:179], v[112:127]
	v_mfma_f32_32x32x16_bf16 v[48:63], v[234:237], v[180:183], v[48:63]
	s_waitcnt lgkmcnt(0)
	v_mfma_f32_32x32x16_bf16 v[96:111], v[238:241], v[176:179], v[96:111]
	v_mfma_f32_32x32x16_bf16 v[32:47], v[238:241], v[180:183], v[32:47]
	ds_read_b128 v[234:237], v204 offset:9312
	ds_read_b128 v[238:241], v204 offset:13920
	s_waitcnt lgkmcnt(1)
	v_mfma_f32_32x32x16_bf16 v[80:95], v[234:237], v[176:179], v[80:95]
	v_mfma_f32_32x32x16_bf16 v[16:31], v[234:237], v[180:183], v[16:31]
	s_waitcnt lgkmcnt(0)
	v_mfma_f32_32x32x16_bf16 v[64:79], v[238:241], v[176:179], v[64:79]
	v_mfma_f32_32x32x16_bf16 v[0:15], v[238:241], v[180:183], v[0:15]
	s_setprio 0
	s_barrier
	global_load_dwordx4 v[176:179], v[190:191], off offset:1920
	global_load_dwordx4 v[180:183], v[188:189], off offset:1920
	s_waitcnt vmcnt(9)
	ds_write_b128 v215, v[168:171]
	s_waitcnt vmcnt(8)
	ds_write_b128 v215, v[172:175] offset:36864
	ds_read_b128 v[168:171], v208
	ds_read_b128 v[172:175], v208 offset:4608
	ds_read_b128 v[234:237], v192
	ds_read_b128 v[238:241], v192 offset:4608
	s_setprio 1
	s_waitcnt lgkmcnt(1)
	v_mfma_f32_32x32x16_bf16 v[112:127], v[234:237], v[168:171], v[112:127]
	v_mfma_f32_32x32x16_bf16 v[48:63], v[234:237], v[172:175], v[48:63]
	s_waitcnt lgkmcnt(0)
	v_mfma_f32_32x32x16_bf16 v[96:111], v[238:241], v[168:171], v[96:111]
	v_mfma_f32_32x32x16_bf16 v[32:47], v[238:241], v[172:175], v[32:47]
	ds_read_b128 v[234:237], v192 offset:9216
	ds_read_b128 v[238:241], v192 offset:13824
	s_waitcnt vmcnt(7)
	ds_write_b128 v215, v[160:163] offset:9216
	s_waitcnt vmcnt(6)
	ds_write_b128 v215, v[164:167] offset:46080
	ds_read_b128 v[160:163], v208 offset:32
	ds_read_b128 v[164:167], v208 offset:4640
	s_waitcnt lgkmcnt(5)
	v_mfma_f32_32x32x16_bf16 v[80:95], v[234:237], v[168:171], v[80:95]
	v_mfma_f32_32x32x16_bf16 v[16:31], v[234:237], v[172:175], v[16:31]
	ds_read_b128 v[234:237], v192 offset:32
	s_waitcnt lgkmcnt(5)
	v_mfma_f32_32x32x16_bf16 v[64:79], v[238:241], v[168:171], v[64:79]
	v_mfma_f32_32x32x16_bf16 v[0:15], v[238:241], v[172:175], v[0:15]
	ds_read_b128 v[238:241], v192 offset:4640
	s_setprio 0
	global_load_dwordx4 v[168:171], v[194:195], off offset:1920
	global_load_dwordx4 v[172:175], v[196:197], off offset:1920
	s_setprio 1
	s_waitcnt lgkmcnt(1)
	v_mfma_f32_32x32x16_bf16 v[112:127], v[234:237], v[160:163], v[112:127]
	v_mfma_f32_32x32x16_bf16 v[48:63], v[234:237], v[164:167], v[48:63]
	s_waitcnt lgkmcnt(0)
	v_mfma_f32_32x32x16_bf16 v[96:111], v[238:241], v[160:163], v[96:111]
	v_mfma_f32_32x32x16_bf16 v[32:47], v[238:241], v[164:167], v[32:47]
	ds_read_b128 v[234:237], v192 offset:9248
	ds_read_b128 v[238:241], v192 offset:13856
	s_waitcnt vmcnt(7)
	ds_write_b128 v215, v[218:221] offset:18432
	s_waitcnt vmcnt(6)
	ds_write_b128 v215, v[222:225] offset:55296
	ds_read_b128 v[218:221], v208 offset:64
	ds_read_b128 v[222:225], v208 offset:4672
	s_waitcnt lgkmcnt(5)
	v_mfma_f32_32x32x16_bf16 v[80:95], v[234:237], v[160:163], v[80:95]
	v_mfma_f32_32x32x16_bf16 v[16:31], v[234:237], v[164:167], v[16:31]
	ds_read_b128 v[234:237], v192 offset:64
	s_waitcnt lgkmcnt(5)
	v_mfma_f32_32x32x16_bf16 v[64:79], v[238:241], v[160:163], v[64:79]
	v_mfma_f32_32x32x16_bf16 v[0:15], v[238:241], v[164:167], v[0:15]
	ds_read_b128 v[238:241], v192 offset:4672
	s_setprio 0
	global_load_dwordx4 v[160:163], v[184:185], off offset:1920
	global_load_dwordx4 v[164:167], v[186:187], off offset:1920
	s_setprio 1
	s_waitcnt lgkmcnt(1)
	v_mfma_f32_32x32x16_bf16 v[112:127], v[234:237], v[218:221], v[112:127]
	v_mfma_f32_32x32x16_bf16 v[48:63], v[234:237], v[222:225], v[48:63]
	s_waitcnt lgkmcnt(0)
	v_mfma_f32_32x32x16_bf16 v[96:111], v[238:241], v[218:221], v[96:111]
	v_mfma_f32_32x32x16_bf16 v[32:47], v[238:241], v[222:225], v[32:47]
	ds_read_b128 v[234:237], v192 offset:9280
	ds_read_b128 v[238:241], v192 offset:13888
	s_waitcnt vmcnt(7)
	ds_write_b128 v215, v[226:229] offset:27648
	s_waitcnt vmcnt(6)
	ds_write_b128 v215, v[230:233] offset:64512
	ds_read_b128 v[226:229], v208 offset:96
	ds_read_b128 v[230:233], v208 offset:4704
	s_waitcnt lgkmcnt(5)
	v_mfma_f32_32x32x16_bf16 v[80:95], v[234:237], v[218:221], v[80:95]
	v_mfma_f32_32x32x16_bf16 v[16:31], v[234:237], v[222:225], v[16:31]
	ds_read_b128 v[234:237], v192 offset:96
	s_waitcnt lgkmcnt(5)
	v_mfma_f32_32x32x16_bf16 v[64:79], v[238:241], v[218:221], v[64:79]
	v_mfma_f32_32x32x16_bf16 v[0:15], v[238:241], v[222:225], v[0:15]
	ds_read_b128 v[238:241], v192 offset:4704
	s_setprio 0
	global_load_dwordx4 v[218:221], v[198:199], off offset:1920
	global_load_dwordx4 v[222:225], v[200:201], off offset:1920
	s_setprio 1
	s_waitcnt lgkmcnt(1)
	v_mfma_f32_32x32x16_bf16 v[112:127], v[234:237], v[226:229], v[112:127]
	v_mfma_f32_32x32x16_bf16 v[48:63], v[234:237], v[230:233], v[48:63]
	s_waitcnt lgkmcnt(0)
	v_mfma_f32_32x32x16_bf16 v[96:111], v[238:241], v[226:229], v[96:111]
	v_mfma_f32_32x32x16_bf16 v[32:47], v[238:241], v[230:233], v[32:47]
	ds_read_b128 v[234:237], v192 offset:9312
	ds_read_b128 v[238:241], v192 offset:13920
	s_waitcnt lgkmcnt(1)
	v_mfma_f32_32x32x16_bf16 v[80:95], v[234:237], v[226:229], v[80:95]
	v_mfma_f32_32x32x16_bf16 v[16:31], v[234:237], v[230:233], v[16:31]
	s_waitcnt lgkmcnt(0)
	v_mfma_f32_32x32x16_bf16 v[64:79], v[238:241], v[226:229], v[64:79]
	v_mfma_f32_32x32x16_bf16 v[0:15], v[238:241], v[230:233], v[0:15]
	s_setprio 0
	s_barrier
	global_load_dwordx4 v[226:229], v[190:191], off offset:2048
	global_load_dwordx4 v[230:233], v[188:189], off offset:2048
	s_waitcnt vmcnt(9)
	ds_write_b128 v209, v[176:179]
	s_waitcnt vmcnt(8)
	ds_write_b128 v210, v[180:183]
	ds_read_b128 v[176:179], v205 offset:36864
	ds_read_b128 v[180:183], v205 offset:41472
	ds_read_b128 v[234:237], v204
	ds_read_b128 v[238:241], v204 offset:4608
	s_setprio 1
	s_waitcnt lgkmcnt(1)
	v_mfma_f32_32x32x16_bf16 v[112:127], v[234:237], v[176:179], v[112:127]
	v_mfma_f32_32x32x16_bf16 v[48:63], v[234:237], v[180:183], v[48:63]
	s_waitcnt lgkmcnt(0)
	v_mfma_f32_32x32x16_bf16 v[96:111], v[238:241], v[176:179], v[96:111]
	v_mfma_f32_32x32x16_bf16 v[32:47], v[238:241], v[180:183], v[32:47]
	ds_read_b128 v[234:237], v204 offset:9216
	ds_read_b128 v[238:241], v204 offset:13824
	s_waitcnt vmcnt(7)
	ds_write_b128 v212, v[168:171]
	s_waitcnt vmcnt(6)
	ds_write_b128 v211, v[172:175]
	ds_read_b128 v[168:171], v205 offset:36896
	ds_read_b128 v[172:175], v205 offset:41504
	s_waitcnt lgkmcnt(5)
	v_mfma_f32_32x32x16_bf16 v[80:95], v[234:237], v[176:179], v[80:95]
	v_mfma_f32_32x32x16_bf16 v[16:31], v[234:237], v[180:183], v[16:31]
	ds_read_b128 v[234:237], v204 offset:32
	s_waitcnt lgkmcnt(5)
	v_mfma_f32_32x32x16_bf16 v[64:79], v[238:241], v[176:179], v[64:79]
	v_mfma_f32_32x32x16_bf16 v[0:15], v[238:241], v[180:183], v[0:15]
	ds_read_b128 v[238:241], v204 offset:4640
	s_setprio 0
	global_load_dwordx4 v[176:179], v[194:195], off offset:2048
	global_load_dwordx4 v[180:183], v[196:197], off offset:2048
	s_setprio 1
	s_waitcnt lgkmcnt(1)
	v_mfma_f32_32x32x16_bf16 v[112:127], v[234:237], v[168:171], v[112:127]
	v_mfma_f32_32x32x16_bf16 v[48:63], v[234:237], v[172:175], v[48:63]
	s_waitcnt lgkmcnt(0)
	v_mfma_f32_32x32x16_bf16 v[96:111], v[238:241], v[168:171], v[96:111]
	v_mfma_f32_32x32x16_bf16 v[32:47], v[238:241], v[172:175], v[32:47]
	ds_read_b128 v[234:237], v204 offset:9248
	ds_read_b128 v[238:241], v204 offset:13856
	s_waitcnt vmcnt(7)
	ds_write_b128 v214, v[160:163]
	s_waitcnt vmcnt(6)
	ds_write_b128 v213, v[164:167]
	ds_read_b128 v[160:163], v205 offset:36928
	ds_read_b128 v[164:167], v205 offset:41536
	s_waitcnt lgkmcnt(5)
	v_mfma_f32_32x32x16_bf16 v[80:95], v[234:237], v[168:171], v[80:95]
	v_mfma_f32_32x32x16_bf16 v[16:31], v[234:237], v[172:175], v[16:31]
	ds_read_b128 v[234:237], v204 offset:64
	s_waitcnt lgkmcnt(5)
	v_mfma_f32_32x32x16_bf16 v[64:79], v[238:241], v[168:171], v[64:79]
	v_mfma_f32_32x32x16_bf16 v[0:15], v[238:241], v[172:175], v[0:15]
	ds_read_b128 v[238:241], v204 offset:4672
	s_setprio 0
	global_load_dwordx4 v[168:171], v[184:185], off offset:2048
	global_load_dwordx4 v[172:175], v[186:187], off offset:2048
	s_setprio 1
	s_waitcnt lgkmcnt(1)
	v_mfma_f32_32x32x16_bf16 v[112:127], v[234:237], v[160:163], v[112:127]
	v_mfma_f32_32x32x16_bf16 v[48:63], v[234:237], v[164:167], v[48:63]
	s_waitcnt lgkmcnt(0)
	v_mfma_f32_32x32x16_bf16 v[96:111], v[238:241], v[160:163], v[96:111]
	v_mfma_f32_32x32x16_bf16 v[32:47], v[238:241], v[164:167], v[32:47]
	ds_read_b128 v[234:237], v204 offset:9280
	ds_read_b128 v[238:241], v204 offset:13888
	s_waitcnt vmcnt(7)
	ds_write_b128 v217, v[218:221]
	s_waitcnt vmcnt(6)
	ds_write_b128 v216, v[222:225]
	ds_read_b128 v[218:221], v205 offset:36960
	ds_read_b128 v[222:225], v205 offset:41568
	s_waitcnt lgkmcnt(5)
	v_mfma_f32_32x32x16_bf16 v[80:95], v[234:237], v[160:163], v[80:95]
	v_mfma_f32_32x32x16_bf16 v[16:31], v[234:237], v[164:167], v[16:31]
	ds_read_b128 v[234:237], v204 offset:96
	s_waitcnt lgkmcnt(5)
	v_mfma_f32_32x32x16_bf16 v[64:79], v[238:241], v[160:163], v[64:79]
	v_mfma_f32_32x32x16_bf16 v[0:15], v[238:241], v[164:167], v[0:15]
	ds_read_b128 v[238:241], v204 offset:4704
	s_setprio 0
	global_load_dwordx4 v[160:163], v[198:199], off offset:2048
	global_load_dwordx4 v[164:167], v[200:201], off offset:2048
	s_setprio 1
	s_waitcnt lgkmcnt(1)
	v_mfma_f32_32x32x16_bf16 v[112:127], v[234:237], v[218:221], v[112:127]
	v_mfma_f32_32x32x16_bf16 v[48:63], v[234:237], v[222:225], v[48:63]
	s_waitcnt lgkmcnt(0)
	v_mfma_f32_32x32x16_bf16 v[96:111], v[238:241], v[218:221], v[96:111]
	v_mfma_f32_32x32x16_bf16 v[32:47], v[238:241], v[222:225], v[32:47]
	ds_read_b128 v[234:237], v204 offset:9312
	ds_read_b128 v[238:241], v204 offset:13920
	s_waitcnt lgkmcnt(1)
	v_mfma_f32_32x32x16_bf16 v[80:95], v[234:237], v[218:221], v[80:95]
	v_mfma_f32_32x32x16_bf16 v[16:31], v[234:237], v[222:225], v[16:31]
	s_waitcnt lgkmcnt(0)
	v_mfma_f32_32x32x16_bf16 v[64:79], v[238:241], v[218:221], v[64:79]
	v_mfma_f32_32x32x16_bf16 v[0:15], v[238:241], v[222:225], v[0:15]
	s_setprio 0
	s_barrier
	global_load_dwordx4 v[218:221], v[190:191], off offset:2176
	global_load_dwordx4 v[222:225], v[188:189], off offset:2176
	s_waitcnt vmcnt(9)
	ds_write_b128 v215, v[226:229]
	s_waitcnt vmcnt(8)
	ds_write_b128 v215, v[230:233] offset:36864
	ds_read_b128 v[226:229], v208
	ds_read_b128 v[230:233], v208 offset:4608
	ds_read_b128 v[234:237], v192
	ds_read_b128 v[238:241], v192 offset:4608
	s_setprio 1
	s_waitcnt lgkmcnt(1)
	v_mfma_f32_32x32x16_bf16 v[112:127], v[234:237], v[226:229], v[112:127]
	v_mfma_f32_32x32x16_bf16 v[48:63], v[234:237], v[230:233], v[48:63]
	s_waitcnt lgkmcnt(0)
	v_mfma_f32_32x32x16_bf16 v[96:111], v[238:241], v[226:229], v[96:111]
	v_mfma_f32_32x32x16_bf16 v[32:47], v[238:241], v[230:233], v[32:47]
	ds_read_b128 v[234:237], v192 offset:9216
	ds_read_b128 v[238:241], v192 offset:13824
	s_waitcnt vmcnt(7)
	ds_write_b128 v215, v[176:179] offset:9216
	s_waitcnt vmcnt(6)
	ds_write_b128 v215, v[180:183] offset:46080
	ds_read_b128 v[176:179], v208 offset:32
	ds_read_b128 v[180:183], v208 offset:4640
	s_waitcnt lgkmcnt(5)
	v_mfma_f32_32x32x16_bf16 v[80:95], v[234:237], v[226:229], v[80:95]
	v_mfma_f32_32x32x16_bf16 v[16:31], v[234:237], v[230:233], v[16:31]
	ds_read_b128 v[234:237], v192 offset:32
	s_waitcnt lgkmcnt(5)
	v_mfma_f32_32x32x16_bf16 v[64:79], v[238:241], v[226:229], v[64:79]
	v_mfma_f32_32x32x16_bf16 v[0:15], v[238:241], v[230:233], v[0:15]
	ds_read_b128 v[238:241], v192 offset:4640
	s_setprio 0
	global_load_dwordx4 v[226:229], v[194:195], off offset:2176
	global_load_dwordx4 v[230:233], v[196:197], off offset:2176
	s_setprio 1
	s_waitcnt lgkmcnt(1)
	v_mfma_f32_32x32x16_bf16 v[112:127], v[234:237], v[176:179], v[112:127]
	v_mfma_f32_32x32x16_bf16 v[48:63], v[234:237], v[180:183], v[48:63]
	s_waitcnt lgkmcnt(0)
	v_mfma_f32_32x32x16_bf16 v[96:111], v[238:241], v[176:179], v[96:111]
	v_mfma_f32_32x32x16_bf16 v[32:47], v[238:241], v[180:183], v[32:47]
	ds_read_b128 v[234:237], v192 offset:9248
	ds_read_b128 v[238:241], v192 offset:13856
	s_waitcnt vmcnt(7)
	ds_write_b128 v215, v[168:171] offset:18432
	s_waitcnt vmcnt(6)
	ds_write_b128 v215, v[172:175] offset:55296
	ds_read_b128 v[168:171], v208 offset:64
	ds_read_b128 v[172:175], v208 offset:4672
	s_waitcnt lgkmcnt(5)
	v_mfma_f32_32x32x16_bf16 v[80:95], v[234:237], v[176:179], v[80:95]
	v_mfma_f32_32x32x16_bf16 v[16:31], v[234:237], v[180:183], v[16:31]
	ds_read_b128 v[234:237], v192 offset:64
	s_waitcnt lgkmcnt(5)
	v_mfma_f32_32x32x16_bf16 v[64:79], v[238:241], v[176:179], v[64:79]
	v_mfma_f32_32x32x16_bf16 v[0:15], v[238:241], v[180:183], v[0:15]
	ds_read_b128 v[238:241], v192 offset:4672
	s_setprio 0
	global_load_dwordx4 v[176:179], v[184:185], off offset:2176
	global_load_dwordx4 v[180:183], v[186:187], off offset:2176
	s_setprio 1
	s_waitcnt lgkmcnt(1)
	v_mfma_f32_32x32x16_bf16 v[112:127], v[234:237], v[168:171], v[112:127]
	v_mfma_f32_32x32x16_bf16 v[48:63], v[234:237], v[172:175], v[48:63]
	s_waitcnt lgkmcnt(0)
	v_mfma_f32_32x32x16_bf16 v[96:111], v[238:241], v[168:171], v[96:111]
	v_mfma_f32_32x32x16_bf16 v[32:47], v[238:241], v[172:175], v[32:47]
	ds_read_b128 v[234:237], v192 offset:9280
	ds_read_b128 v[238:241], v192 offset:13888
	s_waitcnt vmcnt(7)
	ds_write_b128 v215, v[160:163] offset:27648
	s_waitcnt vmcnt(6)
	ds_write_b128 v215, v[164:167] offset:64512
	ds_read_b128 v[160:163], v208 offset:96
	ds_read_b128 v[164:167], v208 offset:4704
	s_waitcnt lgkmcnt(5)
	v_mfma_f32_32x32x16_bf16 v[80:95], v[234:237], v[168:171], v[80:95]
	v_mfma_f32_32x32x16_bf16 v[16:31], v[234:237], v[172:175], v[16:31]
	ds_read_b128 v[234:237], v192 offset:96
	s_waitcnt lgkmcnt(5)
	v_mfma_f32_32x32x16_bf16 v[64:79], v[238:241], v[168:171], v[64:79]
	v_mfma_f32_32x32x16_bf16 v[0:15], v[238:241], v[172:175], v[0:15]
	ds_read_b128 v[238:241], v192 offset:4704
	s_setprio 0
	global_load_dwordx4 v[168:171], v[198:199], off offset:2176
	global_load_dwordx4 v[172:175], v[200:201], off offset:2176
	s_setprio 1
	s_waitcnt lgkmcnt(1)
	v_mfma_f32_32x32x16_bf16 v[112:127], v[234:237], v[160:163], v[112:127]
	v_mfma_f32_32x32x16_bf16 v[48:63], v[234:237], v[164:167], v[48:63]
	s_waitcnt lgkmcnt(0)
	v_mfma_f32_32x32x16_bf16 v[96:111], v[238:241], v[160:163], v[96:111]
	v_mfma_f32_32x32x16_bf16 v[32:47], v[238:241], v[164:167], v[32:47]
	ds_read_b128 v[234:237], v192 offset:9312
	ds_read_b128 v[238:241], v192 offset:13920
	s_waitcnt lgkmcnt(1)
	v_mfma_f32_32x32x16_bf16 v[80:95], v[234:237], v[160:163], v[80:95]
	v_mfma_f32_32x32x16_bf16 v[16:31], v[234:237], v[164:167], v[16:31]
	s_waitcnt lgkmcnt(0)
	v_mfma_f32_32x32x16_bf16 v[64:79], v[238:241], v[160:163], v[64:79]
	v_mfma_f32_32x32x16_bf16 v[0:15], v[238:241], v[164:167], v[0:15]
	s_setprio 0
	s_barrier
	global_load_dwordx4 v[160:163], v[190:191], off offset:2304
	global_load_dwordx4 v[164:167], v[188:189], off offset:2304
	s_waitcnt vmcnt(9)
	ds_write_b128 v209, v[218:221]
	s_waitcnt vmcnt(8)
	ds_write_b128 v210, v[222:225]
	ds_read_b128 v[218:221], v205 offset:36864
	ds_read_b128 v[222:225], v205 offset:41472
	ds_read_b128 v[234:237], v204
	ds_read_b128 v[238:241], v204 offset:4608
	s_setprio 1
	s_waitcnt lgkmcnt(1)
	v_mfma_f32_32x32x16_bf16 v[112:127], v[234:237], v[218:221], v[112:127]
	v_mfma_f32_32x32x16_bf16 v[48:63], v[234:237], v[222:225], v[48:63]
	s_waitcnt lgkmcnt(0)
	v_mfma_f32_32x32x16_bf16 v[96:111], v[238:241], v[218:221], v[96:111]
	v_mfma_f32_32x32x16_bf16 v[32:47], v[238:241], v[222:225], v[32:47]
	ds_read_b128 v[234:237], v204 offset:9216
	ds_read_b128 v[238:241], v204 offset:13824
	s_waitcnt vmcnt(7)
	ds_write_b128 v212, v[226:229]
	s_waitcnt vmcnt(6)
	ds_write_b128 v211, v[230:233]
	ds_read_b128 v[226:229], v205 offset:36896
	ds_read_b128 v[230:233], v205 offset:41504
	s_waitcnt lgkmcnt(5)
	v_mfma_f32_32x32x16_bf16 v[80:95], v[234:237], v[218:221], v[80:95]
	v_mfma_f32_32x32x16_bf16 v[16:31], v[234:237], v[222:225], v[16:31]
	ds_read_b128 v[234:237], v204 offset:32
	s_waitcnt lgkmcnt(5)
	v_mfma_f32_32x32x16_bf16 v[64:79], v[238:241], v[218:221], v[64:79]
	v_mfma_f32_32x32x16_bf16 v[0:15], v[238:241], v[222:225], v[0:15]
	ds_read_b128 v[238:241], v204 offset:4640
	s_setprio 0
	global_load_dwordx4 v[218:221], v[194:195], off offset:2304
	global_load_dwordx4 v[222:225], v[196:197], off offset:2304
	s_setprio 1
	s_waitcnt lgkmcnt(1)
	v_mfma_f32_32x32x16_bf16 v[112:127], v[234:237], v[226:229], v[112:127]
	v_mfma_f32_32x32x16_bf16 v[48:63], v[234:237], v[230:233], v[48:63]
	s_waitcnt lgkmcnt(0)
	v_mfma_f32_32x32x16_bf16 v[96:111], v[238:241], v[226:229], v[96:111]
	v_mfma_f32_32x32x16_bf16 v[32:47], v[238:241], v[230:233], v[32:47]
	ds_read_b128 v[234:237], v204 offset:9248
	ds_read_b128 v[238:241], v204 offset:13856
	s_waitcnt vmcnt(7)
	ds_write_b128 v214, v[176:179]
	s_waitcnt vmcnt(6)
	ds_write_b128 v213, v[180:183]
	ds_read_b128 v[176:179], v205 offset:36928
	ds_read_b128 v[180:183], v205 offset:41536
	s_waitcnt lgkmcnt(5)
	v_mfma_f32_32x32x16_bf16 v[80:95], v[234:237], v[226:229], v[80:95]
	v_mfma_f32_32x32x16_bf16 v[16:31], v[234:237], v[230:233], v[16:31]
	ds_read_b128 v[234:237], v204 offset:64
	s_waitcnt lgkmcnt(5)
	v_mfma_f32_32x32x16_bf16 v[64:79], v[238:241], v[226:229], v[64:79]
	v_mfma_f32_32x32x16_bf16 v[0:15], v[238:241], v[230:233], v[0:15]
	ds_read_b128 v[238:241], v204 offset:4672
	s_setprio 0
	global_load_dwordx4 v[226:229], v[184:185], off offset:2304
	global_load_dwordx4 v[230:233], v[186:187], off offset:2304
	s_setprio 1
	s_waitcnt lgkmcnt(1)
	v_mfma_f32_32x32x16_bf16 v[112:127], v[234:237], v[176:179], v[112:127]
	v_mfma_f32_32x32x16_bf16 v[48:63], v[234:237], v[180:183], v[48:63]
	s_waitcnt lgkmcnt(0)
	v_mfma_f32_32x32x16_bf16 v[96:111], v[238:241], v[176:179], v[96:111]
	v_mfma_f32_32x32x16_bf16 v[32:47], v[238:241], v[180:183], v[32:47]
	ds_read_b128 v[234:237], v204 offset:9280
	ds_read_b128 v[238:241], v204 offset:13888
	s_waitcnt vmcnt(7)
	ds_write_b128 v217, v[168:171]
	s_waitcnt vmcnt(6)
	ds_write_b128 v216, v[172:175]
	ds_read_b128 v[168:171], v205 offset:36960
	ds_read_b128 v[172:175], v205 offset:41568
	s_waitcnt lgkmcnt(5)
	v_mfma_f32_32x32x16_bf16 v[80:95], v[234:237], v[176:179], v[80:95]
	v_mfma_f32_32x32x16_bf16 v[16:31], v[234:237], v[180:183], v[16:31]
	ds_read_b128 v[234:237], v204 offset:96
	s_waitcnt lgkmcnt(5)
	v_mfma_f32_32x32x16_bf16 v[64:79], v[238:241], v[176:179], v[64:79]
	v_mfma_f32_32x32x16_bf16 v[0:15], v[238:241], v[180:183], v[0:15]
	ds_read_b128 v[238:241], v204 offset:4704
	s_setprio 0
	global_load_dwordx4 v[176:179], v[198:199], off offset:2304
	global_load_dwordx4 v[180:183], v[200:201], off offset:2304
	s_setprio 1
	s_waitcnt lgkmcnt(1)
	v_mfma_f32_32x32x16_bf16 v[112:127], v[234:237], v[168:171], v[112:127]
	v_mfma_f32_32x32x16_bf16 v[48:63], v[234:237], v[172:175], v[48:63]
	s_waitcnt lgkmcnt(0)
	v_mfma_f32_32x32x16_bf16 v[96:111], v[238:241], v[168:171], v[96:111]
	v_mfma_f32_32x32x16_bf16 v[32:47], v[238:241], v[172:175], v[32:47]
	ds_read_b128 v[234:237], v204 offset:9312
	ds_read_b128 v[238:241], v204 offset:13920
	s_waitcnt lgkmcnt(1)
	v_mfma_f32_32x32x16_bf16 v[80:95], v[234:237], v[168:171], v[80:95]
	v_mfma_f32_32x32x16_bf16 v[16:31], v[234:237], v[172:175], v[16:31]
	s_waitcnt lgkmcnt(0)
	v_mfma_f32_32x32x16_bf16 v[64:79], v[238:241], v[168:171], v[64:79]
	v_mfma_f32_32x32x16_bf16 v[0:15], v[238:241], v[172:175], v[0:15]
	s_setprio 0
	s_barrier
	global_load_dwordx4 v[168:171], v[190:191], off offset:2432
	global_load_dwordx4 v[172:175], v[188:189], off offset:2432
	s_waitcnt vmcnt(9)
	ds_write_b128 v215, v[160:163]
	s_waitcnt vmcnt(8)
	ds_write_b128 v215, v[164:167] offset:36864
	ds_read_b128 v[160:163], v208
	ds_read_b128 v[164:167], v208 offset:4608
	ds_read_b128 v[234:237], v192
	ds_read_b128 v[238:241], v192 offset:4608
	s_setprio 1
	s_waitcnt lgkmcnt(1)
	v_mfma_f32_32x32x16_bf16 v[112:127], v[234:237], v[160:163], v[112:127]
	v_mfma_f32_32x32x16_bf16 v[48:63], v[234:237], v[164:167], v[48:63]
	s_waitcnt lgkmcnt(0)
	v_mfma_f32_32x32x16_bf16 v[96:111], v[238:241], v[160:163], v[96:111]
	v_mfma_f32_32x32x16_bf16 v[32:47], v[238:241], v[164:167], v[32:47]
	ds_read_b128 v[234:237], v192 offset:9216
	ds_read_b128 v[238:241], v192 offset:13824
	s_waitcnt vmcnt(7)
	ds_write_b128 v215, v[218:221] offset:9216
	s_waitcnt vmcnt(6)
	ds_write_b128 v215, v[222:225] offset:46080
	ds_read_b128 v[218:221], v208 offset:32
	ds_read_b128 v[222:225], v208 offset:4640
	s_waitcnt lgkmcnt(5)
	v_mfma_f32_32x32x16_bf16 v[80:95], v[234:237], v[160:163], v[80:95]
	v_mfma_f32_32x32x16_bf16 v[16:31], v[234:237], v[164:167], v[16:31]
	ds_read_b128 v[234:237], v192 offset:32
	s_waitcnt lgkmcnt(5)
	v_mfma_f32_32x32x16_bf16 v[64:79], v[238:241], v[160:163], v[64:79]
	v_mfma_f32_32x32x16_bf16 v[0:15], v[238:241], v[164:167], v[0:15]
	ds_read_b128 v[238:241], v192 offset:4640
	s_setprio 0
	global_load_dwordx4 v[160:163], v[194:195], off offset:2432
	global_load_dwordx4 v[164:167], v[196:197], off offset:2432
	s_setprio 1
	s_waitcnt lgkmcnt(1)
	v_mfma_f32_32x32x16_bf16 v[112:127], v[234:237], v[218:221], v[112:127]
	v_mfma_f32_32x32x16_bf16 v[48:63], v[234:237], v[222:225], v[48:63]
	s_waitcnt lgkmcnt(0)
	v_mfma_f32_32x32x16_bf16 v[96:111], v[238:241], v[218:221], v[96:111]
	v_mfma_f32_32x32x16_bf16 v[32:47], v[238:241], v[222:225], v[32:47]
	ds_read_b128 v[234:237], v192 offset:9248
	ds_read_b128 v[238:241], v192 offset:13856
	s_waitcnt vmcnt(7)
	ds_write_b128 v215, v[226:229] offset:18432
	s_waitcnt vmcnt(6)
	ds_write_b128 v215, v[230:233] offset:55296
	ds_read_b128 v[226:229], v208 offset:64
	ds_read_b128 v[230:233], v208 offset:4672
	s_waitcnt lgkmcnt(5)
	v_mfma_f32_32x32x16_bf16 v[80:95], v[234:237], v[218:221], v[80:95]
	v_mfma_f32_32x32x16_bf16 v[16:31], v[234:237], v[222:225], v[16:31]
	ds_read_b128 v[234:237], v192 offset:64
	s_waitcnt lgkmcnt(5)
	v_mfma_f32_32x32x16_bf16 v[64:79], v[238:241], v[218:221], v[64:79]
	v_mfma_f32_32x32x16_bf16 v[0:15], v[238:241], v[222:225], v[0:15]
	ds_read_b128 v[238:241], v192 offset:4672
	s_setprio 0
	global_load_dwordx4 v[218:221], v[184:185], off offset:2432
	global_load_dwordx4 v[222:225], v[186:187], off offset:2432
	s_setprio 1
	s_waitcnt lgkmcnt(1)
	v_mfma_f32_32x32x16_bf16 v[112:127], v[234:237], v[226:229], v[112:127]
	v_mfma_f32_32x32x16_bf16 v[48:63], v[234:237], v[230:233], v[48:63]
	s_waitcnt lgkmcnt(0)
	v_mfma_f32_32x32x16_bf16 v[96:111], v[238:241], v[226:229], v[96:111]
	v_mfma_f32_32x32x16_bf16 v[32:47], v[238:241], v[230:233], v[32:47]
	ds_read_b128 v[234:237], v192 offset:9280
	ds_read_b128 v[238:241], v192 offset:13888
	s_waitcnt vmcnt(7)
	ds_write_b128 v215, v[176:179] offset:27648
	s_waitcnt vmcnt(6)
	ds_write_b128 v215, v[180:183] offset:64512
	ds_read_b128 v[176:179], v208 offset:96
	ds_read_b128 v[180:183], v208 offset:4704
	s_waitcnt lgkmcnt(5)
	v_mfma_f32_32x32x16_bf16 v[80:95], v[234:237], v[226:229], v[80:95]
	v_mfma_f32_32x32x16_bf16 v[16:31], v[234:237], v[230:233], v[16:31]
	ds_read_b128 v[234:237], v192 offset:96
	s_waitcnt lgkmcnt(5)
	v_mfma_f32_32x32x16_bf16 v[64:79], v[238:241], v[226:229], v[64:79]
	v_mfma_f32_32x32x16_bf16 v[0:15], v[238:241], v[230:233], v[0:15]
	ds_read_b128 v[238:241], v192 offset:4704
	s_setprio 0
	global_load_dwordx4 v[226:229], v[198:199], off offset:2432
	global_load_dwordx4 v[230:233], v[200:201], off offset:2432
	s_setprio 1
	s_waitcnt lgkmcnt(1)
	v_mfma_f32_32x32x16_bf16 v[112:127], v[234:237], v[176:179], v[112:127]
	v_mfma_f32_32x32x16_bf16 v[48:63], v[234:237], v[180:183], v[48:63]
	s_waitcnt lgkmcnt(0)
	v_mfma_f32_32x32x16_bf16 v[96:111], v[238:241], v[176:179], v[96:111]
	v_mfma_f32_32x32x16_bf16 v[32:47], v[238:241], v[180:183], v[32:47]
	ds_read_b128 v[234:237], v192 offset:9312
	ds_read_b128 v[238:241], v192 offset:13920
	s_waitcnt lgkmcnt(1)
	v_mfma_f32_32x32x16_bf16 v[80:95], v[234:237], v[176:179], v[80:95]
	v_mfma_f32_32x32x16_bf16 v[16:31], v[234:237], v[180:183], v[16:31]
	s_waitcnt lgkmcnt(0)
	v_mfma_f32_32x32x16_bf16 v[64:79], v[238:241], v[176:179], v[64:79]
	v_mfma_f32_32x32x16_bf16 v[0:15], v[238:241], v[180:183], v[0:15]
	s_setprio 0
	s_barrier
	global_load_dwordx4 v[176:179], v[190:191], off offset:2560
	global_load_dwordx4 v[180:183], v[188:189], off offset:2560
	s_waitcnt vmcnt(9)
	ds_write_b128 v209, v[168:171]
	s_waitcnt vmcnt(8)
	ds_write_b128 v210, v[172:175]
	ds_read_b128 v[168:171], v205 offset:36864
	ds_read_b128 v[172:175], v205 offset:41472
	ds_read_b128 v[234:237], v204
	ds_read_b128 v[238:241], v204 offset:4608
	s_setprio 1
	s_waitcnt lgkmcnt(1)
	v_mfma_f32_32x32x16_bf16 v[112:127], v[234:237], v[168:171], v[112:127]
	v_mfma_f32_32x32x16_bf16 v[48:63], v[234:237], v[172:175], v[48:63]
	s_waitcnt lgkmcnt(0)
	v_mfma_f32_32x32x16_bf16 v[96:111], v[238:241], v[168:171], v[96:111]
	v_mfma_f32_32x32x16_bf16 v[32:47], v[238:241], v[172:175], v[32:47]
	ds_read_b128 v[234:237], v204 offset:9216
	ds_read_b128 v[238:241], v204 offset:13824
	s_waitcnt vmcnt(7)
	ds_write_b128 v212, v[160:163]
	s_waitcnt vmcnt(6)
	ds_write_b128 v211, v[164:167]
	ds_read_b128 v[160:163], v205 offset:36896
	ds_read_b128 v[164:167], v205 offset:41504
	s_waitcnt lgkmcnt(5)
	v_mfma_f32_32x32x16_bf16 v[80:95], v[234:237], v[168:171], v[80:95]
	v_mfma_f32_32x32x16_bf16 v[16:31], v[234:237], v[172:175], v[16:31]
	ds_read_b128 v[234:237], v204 offset:32
	s_waitcnt lgkmcnt(5)
	v_mfma_f32_32x32x16_bf16 v[64:79], v[238:241], v[168:171], v[64:79]
	v_mfma_f32_32x32x16_bf16 v[0:15], v[238:241], v[172:175], v[0:15]
	ds_read_b128 v[238:241], v204 offset:4640
	s_setprio 0
	global_load_dwordx4 v[168:171], v[194:195], off offset:2560
	global_load_dwordx4 v[172:175], v[196:197], off offset:2560
	s_setprio 1
	s_waitcnt lgkmcnt(1)
	v_mfma_f32_32x32x16_bf16 v[112:127], v[234:237], v[160:163], v[112:127]
	v_mfma_f32_32x32x16_bf16 v[48:63], v[234:237], v[164:167], v[48:63]
	s_waitcnt lgkmcnt(0)
	v_mfma_f32_32x32x16_bf16 v[96:111], v[238:241], v[160:163], v[96:111]
	v_mfma_f32_32x32x16_bf16 v[32:47], v[238:241], v[164:167], v[32:47]
	ds_read_b128 v[234:237], v204 offset:9248
	ds_read_b128 v[238:241], v204 offset:13856
	s_waitcnt vmcnt(7)
	ds_write_b128 v214, v[218:221]
	s_waitcnt vmcnt(6)
	ds_write_b128 v213, v[222:225]
	ds_read_b128 v[218:221], v205 offset:36928
	ds_read_b128 v[222:225], v205 offset:41536
	s_waitcnt lgkmcnt(5)
	v_mfma_f32_32x32x16_bf16 v[80:95], v[234:237], v[160:163], v[80:95]
	v_mfma_f32_32x32x16_bf16 v[16:31], v[234:237], v[164:167], v[16:31]
	ds_read_b128 v[234:237], v204 offset:64
	s_waitcnt lgkmcnt(5)
	v_mfma_f32_32x32x16_bf16 v[64:79], v[238:241], v[160:163], v[64:79]
	v_mfma_f32_32x32x16_bf16 v[0:15], v[238:241], v[164:167], v[0:15]
	ds_read_b128 v[238:241], v204 offset:4672
	s_setprio 0
	global_load_dwordx4 v[160:163], v[184:185], off offset:2560
	global_load_dwordx4 v[164:167], v[186:187], off offset:2560
	s_setprio 1
	s_waitcnt lgkmcnt(1)
	v_mfma_f32_32x32x16_bf16 v[112:127], v[234:237], v[218:221], v[112:127]
	v_mfma_f32_32x32x16_bf16 v[48:63], v[234:237], v[222:225], v[48:63]
	s_waitcnt lgkmcnt(0)
	v_mfma_f32_32x32x16_bf16 v[96:111], v[238:241], v[218:221], v[96:111]
	v_mfma_f32_32x32x16_bf16 v[32:47], v[238:241], v[222:225], v[32:47]
	ds_read_b128 v[234:237], v204 offset:9280
	ds_read_b128 v[238:241], v204 offset:13888
	s_waitcnt vmcnt(7)
	ds_write_b128 v217, v[226:229]
	s_waitcnt vmcnt(6)
	ds_write_b128 v216, v[230:233]
	ds_read_b128 v[226:229], v205 offset:36960
	ds_read_b128 v[230:233], v205 offset:41568
	s_waitcnt lgkmcnt(5)
	v_mfma_f32_32x32x16_bf16 v[80:95], v[234:237], v[218:221], v[80:95]
	v_mfma_f32_32x32x16_bf16 v[16:31], v[234:237], v[222:225], v[16:31]
	ds_read_b128 v[234:237], v204 offset:96
	s_waitcnt lgkmcnt(5)
	v_mfma_f32_32x32x16_bf16 v[64:79], v[238:241], v[218:221], v[64:79]
	v_mfma_f32_32x32x16_bf16 v[0:15], v[238:241], v[222:225], v[0:15]
	ds_read_b128 v[238:241], v204 offset:4704
	s_setprio 0
	global_load_dwordx4 v[218:221], v[198:199], off offset:2560
	global_load_dwordx4 v[222:225], v[200:201], off offset:2560
	s_setprio 1
	s_waitcnt lgkmcnt(1)
	v_mfma_f32_32x32x16_bf16 v[112:127], v[234:237], v[226:229], v[112:127]
	v_mfma_f32_32x32x16_bf16 v[48:63], v[234:237], v[230:233], v[48:63]
	s_waitcnt lgkmcnt(0)
	v_mfma_f32_32x32x16_bf16 v[96:111], v[238:241], v[226:229], v[96:111]
	v_mfma_f32_32x32x16_bf16 v[32:47], v[238:241], v[230:233], v[32:47]
	ds_read_b128 v[234:237], v204 offset:9312
	ds_read_b128 v[238:241], v204 offset:13920
	s_waitcnt lgkmcnt(1)
	v_mfma_f32_32x32x16_bf16 v[80:95], v[234:237], v[226:229], v[80:95]
	v_mfma_f32_32x32x16_bf16 v[16:31], v[234:237], v[230:233], v[16:31]
	s_waitcnt lgkmcnt(0)
	v_mfma_f32_32x32x16_bf16 v[64:79], v[238:241], v[226:229], v[64:79]
	v_mfma_f32_32x32x16_bf16 v[0:15], v[238:241], v[230:233], v[0:15]
	s_setprio 0
	s_barrier
	global_load_dwordx4 v[226:229], v[190:191], off offset:2688
	global_load_dwordx4 v[230:233], v[188:189], off offset:2688
	s_waitcnt vmcnt(9)
	ds_write_b128 v215, v[176:179]
	s_waitcnt vmcnt(8)
	ds_write_b128 v215, v[180:183] offset:36864
	ds_read_b128 v[176:179], v208
	ds_read_b128 v[180:183], v208 offset:4608
	ds_read_b128 v[234:237], v192
	ds_read_b128 v[238:241], v192 offset:4608
	s_setprio 1
	s_waitcnt lgkmcnt(1)
	v_mfma_f32_32x32x16_bf16 v[112:127], v[234:237], v[176:179], v[112:127]
	v_mfma_f32_32x32x16_bf16 v[48:63], v[234:237], v[180:183], v[48:63]
	s_waitcnt lgkmcnt(0)
	v_mfma_f32_32x32x16_bf16 v[96:111], v[238:241], v[176:179], v[96:111]
	v_mfma_f32_32x32x16_bf16 v[32:47], v[238:241], v[180:183], v[32:47]
	ds_read_b128 v[234:237], v192 offset:9216
	ds_read_b128 v[238:241], v192 offset:13824
	s_waitcnt vmcnt(7)
	ds_write_b128 v215, v[168:171] offset:9216
	s_waitcnt vmcnt(6)
	ds_write_b128 v215, v[172:175] offset:46080
	ds_read_b128 v[168:171], v208 offset:32
	ds_read_b128 v[172:175], v208 offset:4640
	s_waitcnt lgkmcnt(5)
	v_mfma_f32_32x32x16_bf16 v[80:95], v[234:237], v[176:179], v[80:95]
	v_mfma_f32_32x32x16_bf16 v[16:31], v[234:237], v[180:183], v[16:31]
	ds_read_b128 v[234:237], v192 offset:32
	s_waitcnt lgkmcnt(5)
	v_mfma_f32_32x32x16_bf16 v[64:79], v[238:241], v[176:179], v[64:79]
	v_mfma_f32_32x32x16_bf16 v[0:15], v[238:241], v[180:183], v[0:15]
	ds_read_b128 v[238:241], v192 offset:4640
	s_setprio 0
	global_load_dwordx4 v[176:179], v[194:195], off offset:2688
	global_load_dwordx4 v[180:183], v[196:197], off offset:2688
	s_setprio 1
	s_waitcnt lgkmcnt(1)
	v_mfma_f32_32x32x16_bf16 v[112:127], v[234:237], v[168:171], v[112:127]
	v_mfma_f32_32x32x16_bf16 v[48:63], v[234:237], v[172:175], v[48:63]
	s_waitcnt lgkmcnt(0)
	v_mfma_f32_32x32x16_bf16 v[96:111], v[238:241], v[168:171], v[96:111]
	v_mfma_f32_32x32x16_bf16 v[32:47], v[238:241], v[172:175], v[32:47]
	ds_read_b128 v[234:237], v192 offset:9248
	ds_read_b128 v[238:241], v192 offset:13856
	s_waitcnt vmcnt(7)
	ds_write_b128 v215, v[160:163] offset:18432
	s_waitcnt vmcnt(6)
	ds_write_b128 v215, v[164:167] offset:55296
	ds_read_b128 v[160:163], v208 offset:64
	ds_read_b128 v[164:167], v208 offset:4672
	s_waitcnt lgkmcnt(5)
	v_mfma_f32_32x32x16_bf16 v[80:95], v[234:237], v[168:171], v[80:95]
	v_mfma_f32_32x32x16_bf16 v[16:31], v[234:237], v[172:175], v[16:31]
	ds_read_b128 v[234:237], v192 offset:64
	s_waitcnt lgkmcnt(5)
	v_mfma_f32_32x32x16_bf16 v[64:79], v[238:241], v[168:171], v[64:79]
	v_mfma_f32_32x32x16_bf16 v[0:15], v[238:241], v[172:175], v[0:15]
	ds_read_b128 v[238:241], v192 offset:4672
	s_setprio 0
	global_load_dwordx4 v[168:171], v[184:185], off offset:2688
	global_load_dwordx4 v[172:175], v[186:187], off offset:2688
	s_setprio 1
	s_waitcnt lgkmcnt(1)
	v_mfma_f32_32x32x16_bf16 v[112:127], v[234:237], v[160:163], v[112:127]
	v_mfma_f32_32x32x16_bf16 v[48:63], v[234:237], v[164:167], v[48:63]
	s_waitcnt lgkmcnt(0)
	v_mfma_f32_32x32x16_bf16 v[96:111], v[238:241], v[160:163], v[96:111]
	v_mfma_f32_32x32x16_bf16 v[32:47], v[238:241], v[164:167], v[32:47]
	ds_read_b128 v[234:237], v192 offset:9280
	ds_read_b128 v[238:241], v192 offset:13888
	s_waitcnt vmcnt(7)
	ds_write_b128 v215, v[218:221] offset:27648
	s_waitcnt vmcnt(6)
	ds_write_b128 v215, v[222:225] offset:64512
	ds_read_b128 v[218:221], v208 offset:96
	ds_read_b128 v[222:225], v208 offset:4704
	s_waitcnt lgkmcnt(5)
	v_mfma_f32_32x32x16_bf16 v[80:95], v[234:237], v[160:163], v[80:95]
	v_mfma_f32_32x32x16_bf16 v[16:31], v[234:237], v[164:167], v[16:31]
	ds_read_b128 v[234:237], v192 offset:96
	s_waitcnt lgkmcnt(5)
	v_mfma_f32_32x32x16_bf16 v[64:79], v[238:241], v[160:163], v[64:79]
	v_mfma_f32_32x32x16_bf16 v[0:15], v[238:241], v[164:167], v[0:15]
	ds_read_b128 v[238:241], v192 offset:4704
	s_setprio 0
	global_load_dwordx4 v[160:163], v[198:199], off offset:2688
	global_load_dwordx4 v[164:167], v[200:201], off offset:2688
	s_setprio 1
	s_waitcnt lgkmcnt(1)
	v_mfma_f32_32x32x16_bf16 v[112:127], v[234:237], v[218:221], v[112:127]
	v_mfma_f32_32x32x16_bf16 v[48:63], v[234:237], v[222:225], v[48:63]
	s_waitcnt lgkmcnt(0)
	v_mfma_f32_32x32x16_bf16 v[96:111], v[238:241], v[218:221], v[96:111]
	v_mfma_f32_32x32x16_bf16 v[32:47], v[238:241], v[222:225], v[32:47]
	ds_read_b128 v[234:237], v192 offset:9312
	ds_read_b128 v[238:241], v192 offset:13920
	s_waitcnt lgkmcnt(1)
	v_mfma_f32_32x32x16_bf16 v[80:95], v[234:237], v[218:221], v[80:95]
	v_mfma_f32_32x32x16_bf16 v[16:31], v[234:237], v[222:225], v[16:31]
	s_waitcnt lgkmcnt(0)
	v_mfma_f32_32x32x16_bf16 v[64:79], v[238:241], v[218:221], v[64:79]
	v_mfma_f32_32x32x16_bf16 v[0:15], v[238:241], v[222:225], v[0:15]
	s_setprio 0
	s_barrier
; template <bool trans>
; DI void gemm_core(const GTile& tl, const GTile& nx, bool has_next  , bool chain  , bool pre, u32x4 (&ra)[4], u32x4 (&rb)[4], char* smem, f32x16 (&acc)[2][4]) {
;     ...
;   const int nk = K / 64;
;   if (!pre) { G_LOAD(0); G_STORE(0); G_LOAD(1); }
;   for (int kt = 0; kt < nk; ++kt) {
;     __syncthreads();
;     G_COMPUTE(kt & 1, kt);
;   }
	global_load_dwordx4 v[218:221], v[190:191], off offset:2816
	global_load_dwordx4 v[222:225], v[188:189], off offset:2816
	s_waitcnt vmcnt(9)
	ds_write_b128 v209, v[226:229]
	s_waitcnt vmcnt(8)
	ds_write_b128 v210, v[230:233]
	ds_read_b128 v[226:229], v205 offset:36864
	ds_read_b128 v[230:233], v205 offset:41472
	ds_read_b128 v[234:237], v204
	ds_read_b128 v[238:241], v204 offset:4608
	s_setprio 1
	s_waitcnt lgkmcnt(1)
	v_mfma_f32_32x32x16_bf16 v[112:127], v[234:237], v[226:229], v[112:127]
	v_mfma_f32_32x32x16_bf16 v[48:63], v[234:237], v[230:233], v[48:63]
	s_waitcnt lgkmcnt(0)
	v_mfma_f32_32x32x16_bf16 v[96:111], v[238:241], v[226:229], v[96:111]
	v_mfma_f32_32x32x16_bf16 v[32:47], v[238:241], v[230:233], v[32:47]
	ds_read_b128 v[234:237], v204 offset:9216
	ds_read_b128 v[238:241], v204 offset:13824
	s_waitcnt vmcnt(7)
	ds_write_b128 v212, v[176:179]
	s_waitcnt vmcnt(6)
	ds_write_b128 v211, v[180:183]
	ds_read_b128 v[176:179], v205 offset:36896
	ds_read_b128 v[180:183], v205 offset:41504
	s_waitcnt lgkmcnt(5)
	v_mfma_f32_32x32x16_bf16 v[80:95], v[234:237], v[226:229], v[80:95]
	v_mfma_f32_32x32x16_bf16 v[16:31], v[234:237], v[230:233], v[16:31]
	ds_read_b128 v[234:237], v204 offset:32
	s_waitcnt lgkmcnt(5)
	v_mfma_f32_32x32x16_bf16 v[64:79], v[238:241], v[226:229], v[64:79]
	v_mfma_f32_32x32x16_bf16 v[0:15], v[238:241], v[230:233], v[0:15]
	ds_read_b128 v[238:241], v204 offset:4640
	s_setprio 0
	global_load_dwordx4 v[226:229], v[194:195], off offset:2816
	global_load_dwordx4 v[230:233], v[196:197], off offset:2816
	s_setprio 1
	s_waitcnt lgkmcnt(1)
	v_mfma_f32_32x32x16_bf16 v[112:127], v[234:237], v[176:179], v[112:127]
	v_mfma_f32_32x32x16_bf16 v[48:63], v[234:237], v[180:183], v[48:63]
	s_waitcnt lgkmcnt(0)
	v_mfma_f32_32x32x16_bf16 v[96:111], v[238:241], v[176:179], v[96:111]
	v_mfma_f32_32x32x16_bf16 v[32:47], v[238:241], v[180:183], v[32:47]
	ds_read_b128 v[234:237], v204 offset:9248
	ds_read_b128 v[238:241], v204 offset:13856
	s_waitcnt vmcnt(7)
	ds_write_b128 v214, v[168:171]
	s_waitcnt vmcnt(6)
	ds_write_b128 v213, v[172:175]
	ds_read_b128 v[168:171], v205 offset:36928
	ds_read_b128 v[172:175], v205 offset:41536
	s_waitcnt lgkmcnt(5)
	v_mfma_f32_32x32x16_bf16 v[80:95], v[234:237], v[176:179], v[80:95]
	v_mfma_f32_32x32x16_bf16 v[16:31], v[234:237], v[180:183], v[16:31]
	ds_read_b128 v[234:237], v204 offset:64
	s_waitcnt lgkmcnt(5)
	v_mfma_f32_32x32x16_bf16 v[64:79], v[238:241], v[176:179], v[64:79]
	v_mfma_f32_32x32x16_bf16 v[0:15], v[238:241], v[180:183], v[0:15]
	ds_read_b128 v[238:241], v204 offset:4672
	s_setprio 0
	global_load_dwordx4 v[176:179], v[184:185], off offset:2816
	global_load_dwordx4 v[180:183], v[186:187], off offset:2816
	s_setprio 1
	s_waitcnt lgkmcnt(1)
	v_mfma_f32_32x32x16_bf16 v[112:127], v[234:237], v[168:171], v[112:127]
	v_mfma_f32_32x32x16_bf16 v[48:63], v[234:237], v[172:175], v[48:63]
	s_waitcnt lgkmcnt(0)
	v_mfma_f32_32x32x16_bf16 v[96:111], v[238:241], v[168:171], v[96:111]
	v_mfma_f32_32x32x16_bf16 v[32:47], v[238:241], v[172:175], v[32:47]
	ds_read_b128 v[234:237], v204 offset:9280
	ds_read_b128 v[238:241], v204 offset:13888
	s_waitcnt vmcnt(7)
	ds_write_b128 v217, v[160:163]
	s_waitcnt vmcnt(6)
	ds_write_b128 v216, v[164:167]
	ds_read_b128 v[160:163], v205 offset:36960
	ds_read_b128 v[164:167], v205 offset:41568
	s_waitcnt lgkmcnt(5)
	v_mfma_f32_32x32x16_bf16 v[80:95], v[234:237], v[168:171], v[80:95]
	v_mfma_f32_32x32x16_bf16 v[16:31], v[234:237], v[172:175], v[16:31]
	ds_read_b128 v[234:237], v204 offset:96
	s_waitcnt lgkmcnt(5)
	v_mfma_f32_32x32x16_bf16 v[64:79], v[238:241], v[168:171], v[64:79]
	v_mfma_f32_32x32x16_bf16 v[0:15], v[238:241], v[172:175], v[0:15]
	ds_read_b128 v[238:241], v204 offset:4704
	s_setprio 0
	global_load_dwordx4 v[168:171], v[198:199], off offset:2816
	global_load_dwordx4 v[172:175], v[200:201], off offset:2816
	s_setprio 1
	s_waitcnt lgkmcnt(1)
	v_mfma_f32_32x32x16_bf16 v[112:127], v[234:237], v[160:163], v[112:127]
	v_mfma_f32_32x32x16_bf16 v[48:63], v[234:237], v[164:167], v[48:63]
	s_waitcnt lgkmcnt(0)
	v_mfma_f32_32x32x16_bf16 v[96:111], v[238:241], v[160:163], v[96:111]
	v_mfma_f32_32x32x16_bf16 v[32:47], v[238:241], v[164:167], v[32:47]
	ds_read_b128 v[234:237], v204 offset:9312
	ds_read_b128 v[238:241], v204 offset:13920
	s_waitcnt lgkmcnt(1)
	v_mfma_f32_32x32x16_bf16 v[80:95], v[234:237], v[160:163], v[80:95]
	v_mfma_f32_32x32x16_bf16 v[16:31], v[234:237], v[164:167], v[16:31]
	s_waitcnt lgkmcnt(0)
	v_mfma_f32_32x32x16_bf16 v[64:79], v[238:241], v[160:163], v[64:79]
	v_mfma_f32_32x32x16_bf16 v[0:15], v[238:241], v[164:167], v[0:15]
	s_setprio 0
	s_barrier
; template <bool trans>
; DI void gemm_core(const GTile& tl, const GTile& nx, bool has_next  , bool chain  , bool pre, u32x4 (&ra)[4], u32x4 (&rb)[4], char* smem, f32x16 (&acc)[2][4]) {
;     ...
;   const int nk = K / 64;
;   if (!pre) { G_LOAD(0); G_STORE(0); G_LOAD(1); }
;   for (int kt = 0; kt < nk; ++kt) {
;     __syncthreads();
;     G_COMPUTE(kt & 1, kt);
;   }
	global_load_dwordx4 v[160:163], v[190:191], off offset:2944
	global_load_dwordx4 v[164:167], v[188:189], off offset:2944
	s_waitcnt vmcnt(9)
	ds_write_b128 v215, v[218:221]
	s_waitcnt vmcnt(8)
	ds_write_b128 v215, v[222:225] offset:36864
	ds_read_b128 v[218:221], v208
	ds_read_b128 v[222:225], v208 offset:4608
	ds_read_b128 v[234:237], v192
	ds_read_b128 v[238:241], v192 offset:4608
	s_setprio 1
	s_waitcnt lgkmcnt(1)
	v_mfma_f32_32x32x16_bf16 v[112:127], v[234:237], v[218:221], v[112:127]
	v_mfma_f32_32x32x16_bf16 v[48:63], v[234:237], v[222:225], v[48:63]
	s_waitcnt lgkmcnt(0)
	v_mfma_f32_32x32x16_bf16 v[96:111], v[238:241], v[218:221], v[96:111]
	v_mfma_f32_32x32x16_bf16 v[32:47], v[238:241], v[222:225], v[32:47]
	ds_read_b128 v[234:237], v192 offset:9216
	ds_read_b128 v[238:241], v192 offset:13824
	s_waitcnt vmcnt(7)
	ds_write_b128 v215, v[226:229] offset:9216
	s_waitcnt vmcnt(6)
	ds_write_b128 v215, v[230:233] offset:46080
	ds_read_b128 v[226:229], v208 offset:32
	ds_read_b128 v[230:233], v208 offset:4640
	s_waitcnt lgkmcnt(5)
	v_mfma_f32_32x32x16_bf16 v[80:95], v[234:237], v[218:221], v[80:95]
	v_mfma_f32_32x32x16_bf16 v[16:31], v[234:237], v[222:225], v[16:31]
	ds_read_b128 v[234:237], v192 offset:32
	s_waitcnt lgkmcnt(5)
	v_mfma_f32_32x32x16_bf16 v[64:79], v[238:241], v[218:221], v[64:79]
	v_mfma_f32_32x32x16_bf16 v[0:15], v[238:241], v[222:225], v[0:15]
	ds_read_b128 v[238:241], v192 offset:4640
	s_setprio 0
	global_load_dwordx4 v[218:221], v[194:195], off offset:2944
	global_load_dwordx4 v[222:225], v[196:197], off offset:2944
	s_setprio 1
	s_waitcnt lgkmcnt(1)
	v_mfma_f32_32x32x16_bf16 v[112:127], v[234:237], v[226:229], v[112:127]
	v_mfma_f32_32x32x16_bf16 v[48:63], v[234:237], v[230:233], v[48:63]
	s_waitcnt lgkmcnt(0)
	v_mfma_f32_32x32x16_bf16 v[96:111], v[238:241], v[226:229], v[96:111]
	v_mfma_f32_32x32x16_bf16 v[32:47], v[238:241], v[230:233], v[32:47]
	ds_read_b128 v[234:237], v192 offset:9248
	ds_read_b128 v[238:241], v192 offset:13856
	s_waitcnt vmcnt(7)
	ds_write_b128 v215, v[176:179] offset:18432
	s_waitcnt vmcnt(6)
	ds_write_b128 v215, v[180:183] offset:55296
	ds_read_b128 v[176:179], v208 offset:64
	ds_read_b128 v[180:183], v208 offset:4672
	s_waitcnt lgkmcnt(5)
	v_mfma_f32_32x32x16_bf16 v[80:95], v[234:237], v[226:229], v[80:95]
	v_mfma_f32_32x32x16_bf16 v[16:31], v[234:237], v[230:233], v[16:31]
	ds_read_b128 v[234:237], v192 offset:64
	s_waitcnt lgkmcnt(5)
	v_mfma_f32_32x32x16_bf16 v[64:79], v[238:241], v[226:229], v[64:79]
	v_mfma_f32_32x32x16_bf16 v[0:15], v[238:241], v[230:233], v[0:15]
	ds_read_b128 v[238:241], v192 offset:4672
	s_setprio 0
	global_load_dwordx4 v[226:229], v[184:185], off offset:2944
	global_load_dwordx4 v[230:233], v[186:187], off offset:2944
	s_setprio 1
	s_waitcnt lgkmcnt(1)
	v_mfma_f32_32x32x16_bf16 v[112:127], v[234:237], v[176:179], v[112:127]
	v_mfma_f32_32x32x16_bf16 v[48:63], v[234:237], v[180:183], v[48:63]
	s_waitcnt lgkmcnt(0)
	v_mfma_f32_32x32x16_bf16 v[96:111], v[238:241], v[176:179], v[96:111]
	v_mfma_f32_32x32x16_bf16 v[32:47], v[238:241], v[180:183], v[32:47]
	ds_read_b128 v[234:237], v192 offset:9280
	ds_read_b128 v[238:241], v192 offset:13888
	s_waitcnt vmcnt(7)
	ds_write_b128 v215, v[168:171] offset:27648
	s_waitcnt vmcnt(6)
	ds_write_b128 v215, v[172:175] offset:64512
	ds_read_b128 v[168:171], v208 offset:96
	ds_read_b128 v[172:175], v208 offset:4704
	s_waitcnt lgkmcnt(5)
	v_mfma_f32_32x32x16_bf16 v[80:95], v[234:237], v[176:179], v[80:95]
	v_mfma_f32_32x32x16_bf16 v[16:31], v[234:237], v[180:183], v[16:31]
	ds_read_b128 v[234:237], v192 offset:96
	s_waitcnt lgkmcnt(5)
	v_mfma_f32_32x32x16_bf16 v[64:79], v[238:241], v[176:179], v[64:79]
	v_mfma_f32_32x32x16_bf16 v[0:15], v[238:241], v[180:183], v[0:15]
	ds_read_b128 v[238:241], v192 offset:4704
	s_setprio 0
	global_load_dwordx4 v[176:179], v[198:199], off offset:2944
	global_load_dwordx4 v[180:183], v[200:201], off offset:2944
	s_setprio 1
	s_waitcnt lgkmcnt(1)
	v_mfma_f32_32x32x16_bf16 v[112:127], v[234:237], v[168:171], v[112:127]
	v_mfma_f32_32x32x16_bf16 v[48:63], v[234:237], v[172:175], v[48:63]
	s_waitcnt lgkmcnt(0)
	v_mfma_f32_32x32x16_bf16 v[96:111], v[238:241], v[168:171], v[96:111]
	v_mfma_f32_32x32x16_bf16 v[32:47], v[238:241], v[172:175], v[32:47]
	ds_read_b128 v[234:237], v192 offset:9312
	ds_read_b128 v[238:241], v192 offset:13920
	s_waitcnt lgkmcnt(1)
	v_mfma_f32_32x32x16_bf16 v[80:95], v[234:237], v[168:171], v[80:95]
	v_mfma_f32_32x32x16_bf16 v[16:31], v[234:237], v[172:175], v[16:31]
	s_waitcnt lgkmcnt(0)
	v_mfma_f32_32x32x16_bf16 v[64:79], v[238:241], v[168:171], v[64:79]
	v_mfma_f32_32x32x16_bf16 v[0:15], v[238:241], v[172:175], v[0:15]
	s_setprio 0
	s_barrier
; template <bool trans>
; DI void gemm_core(const GTile& tl, const GTile& nx, bool has_next  , bool chain  , bool pre, u32x4 (&ra)[4], u32x4 (&rb)[4], char* smem, f32x16 (&acc)[2][4]) {
;     ...
;   const int nk = K / 64;
;   if (!pre) { G_LOAD(0); G_STORE(0); G_LOAD(1); }
;   for (int kt = 0; kt < nk; ++kt) {
;     __syncthreads();
;     G_COMPUTE(kt & 1, kt);
;   }
	global_load_dwordx4 v[168:171], v[190:191], off offset:3072
	global_load_dwordx4 v[172:175], v[188:189], off offset:3072
	s_waitcnt vmcnt(9)
	ds_write_b128 v209, v[160:163]
	s_waitcnt vmcnt(8)
	ds_write_b128 v210, v[164:167]
	ds_read_b128 v[160:163], v205 offset:36864
	ds_read_b128 v[164:167], v205 offset:41472
	ds_read_b128 v[234:237], v204
	ds_read_b128 v[238:241], v204 offset:4608
	s_setprio 1
	s_waitcnt lgkmcnt(1)
	v_mfma_f32_32x32x16_bf16 v[112:127], v[234:237], v[160:163], v[112:127]
	v_mfma_f32_32x32x16_bf16 v[48:63], v[234:237], v[164:167], v[48:63]
	s_waitcnt lgkmcnt(0)
	v_mfma_f32_32x32x16_bf16 v[96:111], v[238:241], v[160:163], v[96:111]
	v_mfma_f32_32x32x16_bf16 v[32:47], v[238:241], v[164:167], v[32:47]
	ds_read_b128 v[234:237], v204 offset:9216
	ds_read_b128 v[238:241], v204 offset:13824
	s_waitcnt vmcnt(7)
	ds_write_b128 v212, v[218:221]
	s_waitcnt vmcnt(6)
	ds_write_b128 v211, v[222:225]
	ds_read_b128 v[218:221], v205 offset:36896
	ds_read_b128 v[222:225], v205 offset:41504
	s_waitcnt lgkmcnt(5)
	v_mfma_f32_32x32x16_bf16 v[80:95], v[234:237], v[160:163], v[80:95]
	v_mfma_f32_32x32x16_bf16 v[16:31], v[234:237], v[164:167], v[16:31]
	ds_read_b128 v[234:237], v204 offset:32
	s_waitcnt lgkmcnt(5)
	v_mfma_f32_32x32x16_bf16 v[64:79], v[238:241], v[160:163], v[64:79]
	v_mfma_f32_32x32x16_bf16 v[0:15], v[238:241], v[164:167], v[0:15]
	ds_read_b128 v[238:241], v204 offset:4640
	s_setprio 0
	global_load_dwordx4 v[160:163], v[194:195], off offset:3072
	global_load_dwordx4 v[164:167], v[196:197], off offset:3072
	s_setprio 1
	s_waitcnt lgkmcnt(1)
	v_mfma_f32_32x32x16_bf16 v[112:127], v[234:237], v[218:221], v[112:127]
	v_mfma_f32_32x32x16_bf16 v[48:63], v[234:237], v[222:225], v[48:63]
	s_waitcnt lgkmcnt(0)
	v_mfma_f32_32x32x16_bf16 v[96:111], v[238:241], v[218:221], v[96:111]
	v_mfma_f32_32x32x16_bf16 v[32:47], v[238:241], v[222:225], v[32:47]
	ds_read_b128 v[234:237], v204 offset:9248
	ds_read_b128 v[238:241], v204 offset:13856
	s_waitcnt vmcnt(7)
	ds_write_b128 v214, v[226:229]
	s_waitcnt vmcnt(6)
	ds_write_b128 v213, v[230:233]
	ds_read_b128 v[226:229], v205 offset:36928
	ds_read_b128 v[230:233], v205 offset:41536
	s_waitcnt lgkmcnt(5)
	v_mfma_f32_32x32x16_bf16 v[80:95], v[234:237], v[218:221], v[80:95]
	v_mfma_f32_32x32x16_bf16 v[16:31], v[234:237], v[222:225], v[16:31]
	ds_read_b128 v[234:237], v204 offset:64
	s_waitcnt lgkmcnt(5)
	v_mfma_f32_32x32x16_bf16 v[64:79], v[238:241], v[218:221], v[64:79]
	v_mfma_f32_32x32x16_bf16 v[0:15], v[238:241], v[222:225], v[0:15]
	ds_read_b128 v[238:241], v204 offset:4672
	s_setprio 0
	global_load_dwordx4 v[218:221], v[184:185], off offset:3072
	global_load_dwordx4 v[222:225], v[186:187], off offset:3072
	s_setprio 1
	s_waitcnt lgkmcnt(1)
	v_mfma_f32_32x32x16_bf16 v[112:127], v[234:237], v[226:229], v[112:127]
	v_mfma_f32_32x32x16_bf16 v[48:63], v[234:237], v[230:233], v[48:63]
	s_waitcnt lgkmcnt(0)
	v_mfma_f32_32x32x16_bf16 v[96:111], v[238:241], v[226:229], v[96:111]
	v_mfma_f32_32x32x16_bf16 v[32:47], v[238:241], v[230:233], v[32:47]
	ds_read_b128 v[234:237], v204 offset:9280
	ds_read_b128 v[238:241], v204 offset:13888
	s_waitcnt vmcnt(7)
	ds_write_b128 v217, v[176:179]
	s_waitcnt vmcnt(6)
	ds_write_b128 v216, v[180:183]
	ds_read_b128 v[176:179], v205 offset:36960
	ds_read_b128 v[180:183], v205 offset:41568
	s_waitcnt lgkmcnt(5)
	v_mfma_f32_32x32x16_bf16 v[80:95], v[234:237], v[226:229], v[80:95]
	v_mfma_f32_32x32x16_bf16 v[16:31], v[234:237], v[230:233], v[16:31]
	ds_read_b128 v[234:237], v204 offset:96
	s_waitcnt lgkmcnt(5)
	v_mfma_f32_32x32x16_bf16 v[64:79], v[238:241], v[226:229], v[64:79]
	v_mfma_f32_32x32x16_bf16 v[0:15], v[238:241], v[230:233], v[0:15]
	ds_read_b128 v[238:241], v204 offset:4704
	s_setprio 0
	global_load_dwordx4 v[226:229], v[198:199], off offset:3072
	global_load_dwordx4 v[230:233], v[200:201], off offset:3072
	s_setprio 1
	s_waitcnt lgkmcnt(1)
	v_mfma_f32_32x32x16_bf16 v[112:127], v[234:237], v[176:179], v[112:127]
	v_mfma_f32_32x32x16_bf16 v[48:63], v[234:237], v[180:183], v[48:63]
	s_waitcnt lgkmcnt(0)
	v_mfma_f32_32x32x16_bf16 v[96:111], v[238:241], v[176:179], v[96:111]
	v_mfma_f32_32x32x16_bf16 v[32:47], v[238:241], v[180:183], v[32:47]
	ds_read_b128 v[234:237], v204 offset:9312
	ds_read_b128 v[238:241], v204 offset:13920
	s_waitcnt lgkmcnt(1)
	v_mfma_f32_32x32x16_bf16 v[80:95], v[234:237], v[176:179], v[80:95]
	v_mfma_f32_32x32x16_bf16 v[16:31], v[234:237], v[180:183], v[16:31]
	s_waitcnt lgkmcnt(0)
	v_mfma_f32_32x32x16_bf16 v[64:79], v[238:241], v[176:179], v[64:79]
	v_mfma_f32_32x32x16_bf16 v[0:15], v[238:241], v[180:183], v[0:15]
	s_setprio 0
	s_barrier
; template <bool trans>
; DI void gemm_core(const GTile& tl, const GTile& nx, bool has_next  , bool chain  , bool pre, u32x4 (&ra)[4], u32x4 (&rb)[4], char* smem, f32x16 (&acc)[2][4]) {
;     ...
;   const int nk = K / 64;
;   if (!pre) { G_LOAD(0); G_STORE(0); G_LOAD(1); }
;   for (int kt = 0; kt < nk; ++kt) {
;     __syncthreads();
;     G_COMPUTE(kt & 1, kt);
;   }
	global_load_dwordx4 v[176:179], v[190:191], off offset:3200
	global_load_dwordx4 v[180:183], v[188:189], off offset:3200
	s_waitcnt vmcnt(9)
	ds_write_b128 v215, v[168:171]
	s_waitcnt vmcnt(8)
	ds_write_b128 v215, v[172:175] offset:36864
	ds_read_b128 v[168:171], v208
	ds_read_b128 v[172:175], v208 offset:4608
	ds_read_b128 v[234:237], v192
	ds_read_b128 v[238:241], v192 offset:4608
	s_setprio 1
	s_waitcnt lgkmcnt(1)
	v_mfma_f32_32x32x16_bf16 v[112:127], v[234:237], v[168:171], v[112:127]
	v_mfma_f32_32x32x16_bf16 v[48:63], v[234:237], v[172:175], v[48:63]
	s_waitcnt lgkmcnt(0)
	v_mfma_f32_32x32x16_bf16 v[96:111], v[238:241], v[168:171], v[96:111]
	v_mfma_f32_32x32x16_bf16 v[32:47], v[238:241], v[172:175], v[32:47]
	ds_read_b128 v[234:237], v192 offset:9216
	ds_read_b128 v[238:241], v192 offset:13824
	s_waitcnt vmcnt(7)
	ds_write_b128 v215, v[160:163] offset:9216
	s_waitcnt vmcnt(6)
	ds_write_b128 v215, v[164:167] offset:46080
	ds_read_b128 v[160:163], v208 offset:32
	ds_read_b128 v[164:167], v208 offset:4640
	s_waitcnt lgkmcnt(5)
	v_mfma_f32_32x32x16_bf16 v[80:95], v[234:237], v[168:171], v[80:95]
	v_mfma_f32_32x32x16_bf16 v[16:31], v[234:237], v[172:175], v[16:31]
	ds_read_b128 v[234:237], v192 offset:32
	s_waitcnt lgkmcnt(5)
	v_mfma_f32_32x32x16_bf16 v[64:79], v[238:241], v[168:171], v[64:79]
	v_mfma_f32_32x32x16_bf16 v[0:15], v[238:241], v[172:175], v[0:15]
	ds_read_b128 v[238:241], v192 offset:4640
	s_setprio 0
	global_load_dwordx4 v[168:171], v[194:195], off offset:3200
	global_load_dwordx4 v[172:175], v[196:197], off offset:3200
	s_setprio 1
	s_waitcnt lgkmcnt(1)
	v_mfma_f32_32x32x16_bf16 v[112:127], v[234:237], v[160:163], v[112:127]
	v_mfma_f32_32x32x16_bf16 v[48:63], v[234:237], v[164:167], v[48:63]
	s_waitcnt lgkmcnt(0)
	v_mfma_f32_32x32x16_bf16 v[96:111], v[238:241], v[160:163], v[96:111]
	v_mfma_f32_32x32x16_bf16 v[32:47], v[238:241], v[164:167], v[32:47]
	ds_read_b128 v[234:237], v192 offset:9248
	ds_read_b128 v[238:241], v192 offset:13856
	s_waitcnt vmcnt(7)
	ds_write_b128 v215, v[218:221] offset:18432
	s_waitcnt vmcnt(6)
	ds_write_b128 v215, v[222:225] offset:55296
	ds_read_b128 v[218:221], v208 offset:64
	ds_read_b128 v[222:225], v208 offset:4672
	s_waitcnt lgkmcnt(5)
	v_mfma_f32_32x32x16_bf16 v[80:95], v[234:237], v[160:163], v[80:95]
	v_mfma_f32_32x32x16_bf16 v[16:31], v[234:237], v[164:167], v[16:31]
	ds_read_b128 v[234:237], v192 offset:64
	s_waitcnt lgkmcnt(5)
	v_mfma_f32_32x32x16_bf16 v[64:79], v[238:241], v[160:163], v[64:79]
	v_mfma_f32_32x32x16_bf16 v[0:15], v[238:241], v[164:167], v[0:15]
	ds_read_b128 v[238:241], v192 offset:4672
	s_setprio 0
	global_load_dwordx4 v[160:163], v[184:185], off offset:3200
	global_load_dwordx4 v[164:167], v[186:187], off offset:3200
	s_setprio 1
	s_waitcnt lgkmcnt(1)
	v_mfma_f32_32x32x16_bf16 v[112:127], v[234:237], v[218:221], v[112:127]
	v_mfma_f32_32x32x16_bf16 v[48:63], v[234:237], v[222:225], v[48:63]
	s_waitcnt lgkmcnt(0)
	v_mfma_f32_32x32x16_bf16 v[96:111], v[238:241], v[218:221], v[96:111]
	v_mfma_f32_32x32x16_bf16 v[32:47], v[238:241], v[222:225], v[32:47]
	ds_read_b128 v[234:237], v192 offset:9280
	ds_read_b128 v[238:241], v192 offset:13888
	s_waitcnt vmcnt(7)
	ds_write_b128 v215, v[226:229] offset:27648
	s_waitcnt vmcnt(6)
	ds_write_b128 v215, v[230:233] offset:64512
	ds_read_b128 v[226:229], v208 offset:96
	ds_read_b128 v[230:233], v208 offset:4704
	s_waitcnt lgkmcnt(5)
	v_mfma_f32_32x32x16_bf16 v[80:95], v[234:237], v[218:221], v[80:95]
	v_mfma_f32_32x32x16_bf16 v[16:31], v[234:237], v[222:225], v[16:31]
	ds_read_b128 v[234:237], v192 offset:96
	s_waitcnt lgkmcnt(5)
	v_mfma_f32_32x32x16_bf16 v[64:79], v[238:241], v[218:221], v[64:79]
	v_mfma_f32_32x32x16_bf16 v[0:15], v[238:241], v[222:225], v[0:15]
	ds_read_b128 v[238:241], v192 offset:4704
	s_setprio 0
	global_load_dwordx4 v[218:221], v[198:199], off offset:3200
	global_load_dwordx4 v[222:225], v[200:201], off offset:3200
	s_setprio 1
	s_waitcnt lgkmcnt(1)
	v_mfma_f32_32x32x16_bf16 v[112:127], v[234:237], v[226:229], v[112:127]
	v_mfma_f32_32x32x16_bf16 v[48:63], v[234:237], v[230:233], v[48:63]
	s_waitcnt lgkmcnt(0)
	v_mfma_f32_32x32x16_bf16 v[96:111], v[238:241], v[226:229], v[96:111]
	v_mfma_f32_32x32x16_bf16 v[32:47], v[238:241], v[230:233], v[32:47]
	ds_read_b128 v[234:237], v192 offset:9312
	ds_read_b128 v[238:241], v192 offset:13920
	s_waitcnt lgkmcnt(1)
	v_mfma_f32_32x32x16_bf16 v[80:95], v[234:237], v[226:229], v[80:95]
	v_mfma_f32_32x32x16_bf16 v[16:31], v[234:237], v[230:233], v[16:31]
	s_waitcnt lgkmcnt(0)
	v_mfma_f32_32x32x16_bf16 v[64:79], v[238:241], v[226:229], v[64:79]
	v_mfma_f32_32x32x16_bf16 v[0:15], v[238:241], v[230:233], v[0:15]
	s_setprio 0
	s_barrier
; template <bool trans>
; DI void gemm_core(const GTile& tl, const GTile& nx, bool has_next  , bool chain  , bool pre, u32x4 (&ra)[4], u32x4 (&rb)[4], char* smem, f32x16 (&acc)[2][4]) {
;     ...
;   const int nk = K / 64;
;   if (!pre) { G_LOAD(0); G_STORE(0); G_LOAD(1); }
;   for (int kt = 0; kt < nk; ++kt) {
;     __syncthreads();
;     G_COMPUTE(kt & 1, kt);
;   }
	global_load_dwordx4 v[226:229], v[190:191], off offset:3328
	global_load_dwordx4 v[230:233], v[188:189], off offset:3328
	s_waitcnt vmcnt(9)
	ds_write_b128 v209, v[176:179]
	s_waitcnt vmcnt(8)
	ds_write_b128 v210, v[180:183]
	ds_read_b128 v[176:179], v205 offset:36864
	ds_read_b128 v[180:183], v205 offset:41472
	ds_read_b128 v[234:237], v204
	ds_read_b128 v[238:241], v204 offset:4608
	s_setprio 1
	s_waitcnt lgkmcnt(1)
	v_mfma_f32_32x32x16_bf16 v[112:127], v[234:237], v[176:179], v[112:127]
	v_mfma_f32_32x32x16_bf16 v[48:63], v[234:237], v[180:183], v[48:63]
	s_waitcnt lgkmcnt(0)
	v_mfma_f32_32x32x16_bf16 v[96:111], v[238:241], v[176:179], v[96:111]
	v_mfma_f32_32x32x16_bf16 v[32:47], v[238:241], v[180:183], v[32:47]
	ds_read_b128 v[234:237], v204 offset:9216
	ds_read_b128 v[238:241], v204 offset:13824
	s_waitcnt vmcnt(7)
	ds_write_b128 v212, v[168:171]
	s_waitcnt vmcnt(6)
	ds_write_b128 v211, v[172:175]
	ds_read_b128 v[168:171], v205 offset:36896
	ds_read_b128 v[172:175], v205 offset:41504
	s_waitcnt lgkmcnt(5)
	v_mfma_f32_32x32x16_bf16 v[80:95], v[234:237], v[176:179], v[80:95]
	v_mfma_f32_32x32x16_bf16 v[16:31], v[234:237], v[180:183], v[16:31]
	ds_read_b128 v[234:237], v204 offset:32
	s_waitcnt lgkmcnt(5)
	v_mfma_f32_32x32x16_bf16 v[64:79], v[238:241], v[176:179], v[64:79]
	v_mfma_f32_32x32x16_bf16 v[0:15], v[238:241], v[180:183], v[0:15]
	ds_read_b128 v[238:241], v204 offset:4640
	s_setprio 0
	global_load_dwordx4 v[176:179], v[194:195], off offset:3328
	global_load_dwordx4 v[180:183], v[196:197], off offset:3328
	s_setprio 1
	s_waitcnt lgkmcnt(1)
	v_mfma_f32_32x32x16_bf16 v[112:127], v[234:237], v[168:171], v[112:127]
	v_mfma_f32_32x32x16_bf16 v[48:63], v[234:237], v[172:175], v[48:63]
	s_waitcnt lgkmcnt(0)
	v_mfma_f32_32x32x16_bf16 v[96:111], v[238:241], v[168:171], v[96:111]
	v_mfma_f32_32x32x16_bf16 v[32:47], v[238:241], v[172:175], v[32:47]
	ds_read_b128 v[234:237], v204 offset:9248
	ds_read_b128 v[238:241], v204 offset:13856
	s_waitcnt vmcnt(7)
	ds_write_b128 v214, v[160:163]
	s_waitcnt vmcnt(6)
	ds_write_b128 v213, v[164:167]
	ds_read_b128 v[160:163], v205 offset:36928
	ds_read_b128 v[164:167], v205 offset:41536
	s_waitcnt lgkmcnt(5)
	v_mfma_f32_32x32x16_bf16 v[80:95], v[234:237], v[168:171], v[80:95]
	v_mfma_f32_32x32x16_bf16 v[16:31], v[234:237], v[172:175], v[16:31]
	ds_read_b128 v[234:237], v204 offset:64
	s_waitcnt lgkmcnt(5)
	v_mfma_f32_32x32x16_bf16 v[64:79], v[238:241], v[168:171], v[64:79]
	v_mfma_f32_32x32x16_bf16 v[0:15], v[238:241], v[172:175], v[0:15]
	ds_read_b128 v[238:241], v204 offset:4672
	s_setprio 0
	global_load_dwordx4 v[168:171], v[184:185], off offset:3328
	global_load_dwordx4 v[172:175], v[186:187], off offset:3328
	s_setprio 1
	s_waitcnt lgkmcnt(1)
	v_mfma_f32_32x32x16_bf16 v[112:127], v[234:237], v[160:163], v[112:127]
	v_mfma_f32_32x32x16_bf16 v[48:63], v[234:237], v[164:167], v[48:63]
	s_waitcnt lgkmcnt(0)
	v_mfma_f32_32x32x16_bf16 v[96:111], v[238:241], v[160:163], v[96:111]
	v_mfma_f32_32x32x16_bf16 v[32:47], v[238:241], v[164:167], v[32:47]
	ds_read_b128 v[234:237], v204 offset:9280
	ds_read_b128 v[238:241], v204 offset:13888
	s_waitcnt vmcnt(7)
	ds_write_b128 v217, v[218:221]
	s_waitcnt vmcnt(6)
	ds_write_b128 v216, v[222:225]
	ds_read_b128 v[218:221], v205 offset:36960
	ds_read_b128 v[222:225], v205 offset:41568
	s_waitcnt lgkmcnt(5)
	v_mfma_f32_32x32x16_bf16 v[80:95], v[234:237], v[160:163], v[80:95]
	v_mfma_f32_32x32x16_bf16 v[16:31], v[234:237], v[164:167], v[16:31]
	ds_read_b128 v[234:237], v204 offset:96
	s_waitcnt lgkmcnt(5)
	v_mfma_f32_32x32x16_bf16 v[64:79], v[238:241], v[160:163], v[64:79]
	v_mfma_f32_32x32x16_bf16 v[0:15], v[238:241], v[164:167], v[0:15]
	ds_read_b128 v[238:241], v204 offset:4704
	s_setprio 0
	global_load_dwordx4 v[160:163], v[198:199], off offset:3328
	global_load_dwordx4 v[164:167], v[200:201], off offset:3328
	s_setprio 1
	s_waitcnt lgkmcnt(1)
	v_mfma_f32_32x32x16_bf16 v[112:127], v[234:237], v[218:221], v[112:127]
	v_mfma_f32_32x32x16_bf16 v[48:63], v[234:237], v[222:225], v[48:63]
	s_waitcnt lgkmcnt(0)
	v_mfma_f32_32x32x16_bf16 v[96:111], v[238:241], v[218:221], v[96:111]
	v_mfma_f32_32x32x16_bf16 v[32:47], v[238:241], v[222:225], v[32:47]
	ds_read_b128 v[234:237], v204 offset:9312
	ds_read_b128 v[238:241], v204 offset:13920
	s_waitcnt lgkmcnt(1)
	v_mfma_f32_32x32x16_bf16 v[80:95], v[234:237], v[218:221], v[80:95]
	v_mfma_f32_32x32x16_bf16 v[16:31], v[234:237], v[222:225], v[16:31]
	s_waitcnt lgkmcnt(0)
	v_mfma_f32_32x32x16_bf16 v[64:79], v[238:241], v[218:221], v[64:79]
	v_mfma_f32_32x32x16_bf16 v[0:15], v[238:241], v[222:225], v[0:15]
	s_setprio 0
	s_barrier
; template <bool trans>
; DI void gemm_core(const GTile& tl, const GTile& nx, bool has_next  , bool chain  , bool pre, u32x4 (&ra)[4], u32x4 (&rb)[4], char* smem, f32x16 (&acc)[2][4]) {
;     ...
;   const int nk = K / 64;
;   if (!pre) { G_LOAD(0); G_STORE(0); G_LOAD(1); }
;   for (int kt = 0; kt < nk; ++kt) {
;     __syncthreads();
;     G_COMPUTE(kt & 1, kt);
;   }
	global_load_dwordx4 v[218:221], v[190:191], off offset:3456
	global_load_dwordx4 v[222:225], v[188:189], off offset:3456
	s_waitcnt vmcnt(9)
	ds_write_b128 v215, v[226:229]
	s_waitcnt vmcnt(8)
	ds_write_b128 v215, v[230:233] offset:36864
	ds_read_b128 v[226:229], v208
	ds_read_b128 v[230:233], v208 offset:4608
	ds_read_b128 v[234:237], v192
	ds_read_b128 v[238:241], v192 offset:4608
	s_setprio 1
	s_waitcnt lgkmcnt(1)
	v_mfma_f32_32x32x16_bf16 v[112:127], v[234:237], v[226:229], v[112:127]
	v_mfma_f32_32x32x16_bf16 v[48:63], v[234:237], v[230:233], v[48:63]
	s_waitcnt lgkmcnt(0)
	v_mfma_f32_32x32x16_bf16 v[96:111], v[238:241], v[226:229], v[96:111]
	v_mfma_f32_32x32x16_bf16 v[32:47], v[238:241], v[230:233], v[32:47]
	ds_read_b128 v[234:237], v192 offset:9216
	ds_read_b128 v[238:241], v192 offset:13824
	s_waitcnt vmcnt(7)
	ds_write_b128 v215, v[176:179] offset:9216
	s_waitcnt vmcnt(6)
	ds_write_b128 v215, v[180:183] offset:46080
	ds_read_b128 v[176:179], v208 offset:32
	ds_read_b128 v[180:183], v208 offset:4640
	s_waitcnt lgkmcnt(5)
	v_mfma_f32_32x32x16_bf16 v[80:95], v[234:237], v[226:229], v[80:95]
	v_mfma_f32_32x32x16_bf16 v[16:31], v[234:237], v[230:233], v[16:31]
	ds_read_b128 v[234:237], v192 offset:32
	s_waitcnt lgkmcnt(5)
	v_mfma_f32_32x32x16_bf16 v[64:79], v[238:241], v[226:229], v[64:79]
	v_mfma_f32_32x32x16_bf16 v[0:15], v[238:241], v[230:233], v[0:15]
	ds_read_b128 v[238:241], v192 offset:4640
	s_setprio 0
	global_load_dwordx4 v[226:229], v[194:195], off offset:3456
	global_load_dwordx4 v[230:233], v[196:197], off offset:3456
	s_setprio 1
	s_waitcnt lgkmcnt(1)
	v_mfma_f32_32x32x16_bf16 v[112:127], v[234:237], v[176:179], v[112:127]
	v_mfma_f32_32x32x16_bf16 v[48:63], v[234:237], v[180:183], v[48:63]
	s_waitcnt lgkmcnt(0)
	v_mfma_f32_32x32x16_bf16 v[96:111], v[238:241], v[176:179], v[96:111]
	v_mfma_f32_32x32x16_bf16 v[32:47], v[238:241], v[180:183], v[32:47]
	ds_read_b128 v[234:237], v192 offset:9248
	ds_read_b128 v[238:241], v192 offset:13856
	s_waitcnt vmcnt(7)
	ds_write_b128 v215, v[168:171] offset:18432
	s_waitcnt vmcnt(6)
	ds_write_b128 v215, v[172:175] offset:55296
	ds_read_b128 v[168:171], v208 offset:64
	ds_read_b128 v[172:175], v208 offset:4672
	s_waitcnt lgkmcnt(5)
	v_mfma_f32_32x32x16_bf16 v[80:95], v[234:237], v[176:179], v[80:95]
	v_mfma_f32_32x32x16_bf16 v[16:31], v[234:237], v[180:183], v[16:31]
	ds_read_b128 v[234:237], v192 offset:64
	s_waitcnt lgkmcnt(5)
	v_mfma_f32_32x32x16_bf16 v[64:79], v[238:241], v[176:179], v[64:79]
	v_mfma_f32_32x32x16_bf16 v[0:15], v[238:241], v[180:183], v[0:15]
	ds_read_b128 v[238:241], v192 offset:4672
	s_setprio 0
	global_load_dwordx4 v[176:179], v[184:185], off offset:3456
	global_load_dwordx4 v[180:183], v[186:187], off offset:3456
	s_setprio 1
	s_waitcnt lgkmcnt(1)
	v_mfma_f32_32x32x16_bf16 v[112:127], v[234:237], v[168:171], v[112:127]
	v_mfma_f32_32x32x16_bf16 v[48:63], v[234:237], v[172:175], v[48:63]
	s_waitcnt lgkmcnt(0)
	v_mfma_f32_32x32x16_bf16 v[96:111], v[238:241], v[168:171], v[96:111]
	v_mfma_f32_32x32x16_bf16 v[32:47], v[238:241], v[172:175], v[32:47]
	ds_read_b128 v[234:237], v192 offset:9280
	ds_read_b128 v[238:241], v192 offset:13888
	s_waitcnt vmcnt(7)
	ds_write_b128 v215, v[160:163] offset:27648
	s_waitcnt vmcnt(6)
	ds_write_b128 v215, v[164:167] offset:64512
	ds_read_b128 v[160:163], v208 offset:96
	ds_read_b128 v[164:167], v208 offset:4704
	s_waitcnt lgkmcnt(5)
	v_mfma_f32_32x32x16_bf16 v[80:95], v[234:237], v[168:171], v[80:95]
	v_mfma_f32_32x32x16_bf16 v[16:31], v[234:237], v[172:175], v[16:31]
	ds_read_b128 v[234:237], v192 offset:96
	s_waitcnt lgkmcnt(5)
	v_mfma_f32_32x32x16_bf16 v[64:79], v[238:241], v[168:171], v[64:79]
	v_mfma_f32_32x32x16_bf16 v[0:15], v[238:241], v[172:175], v[0:15]
	ds_read_b128 v[238:241], v192 offset:4704
	s_setprio 0
	global_load_dwordx4 v[168:171], v[198:199], off offset:3456
	global_load_dwordx4 v[172:175], v[200:201], off offset:3456
	s_setprio 1
	s_waitcnt lgkmcnt(1)
	v_mfma_f32_32x32x16_bf16 v[112:127], v[234:237], v[160:163], v[112:127]
	v_mfma_f32_32x32x16_bf16 v[48:63], v[234:237], v[164:167], v[48:63]
	s_waitcnt lgkmcnt(0)
	v_mfma_f32_32x32x16_bf16 v[96:111], v[238:241], v[160:163], v[96:111]
	v_mfma_f32_32x32x16_bf16 v[32:47], v[238:241], v[164:167], v[32:47]
	ds_read_b128 v[234:237], v192 offset:9312
	ds_read_b128 v[238:241], v192 offset:13920
	s_waitcnt lgkmcnt(1)
	v_mfma_f32_32x32x16_bf16 v[80:95], v[234:237], v[160:163], v[80:95]
	v_mfma_f32_32x32x16_bf16 v[16:31], v[234:237], v[164:167], v[16:31]
	s_waitcnt lgkmcnt(0)
	v_mfma_f32_32x32x16_bf16 v[64:79], v[238:241], v[160:163], v[64:79]
	v_mfma_f32_32x32x16_bf16 v[0:15], v[238:241], v[164:167], v[0:15]
	s_setprio 0
	s_barrier
; template <bool trans>
; DI void gemm_core(const GTile& tl, const GTile& nx, bool has_next  , bool chain  , bool pre, u32x4 (&ra)[4], u32x4 (&rb)[4], char* smem, f32x16 (&acc)[2][4]) {
;     ...
;   const int nk = K / 64;
;   if (!pre) { G_LOAD(0); G_STORE(0); G_LOAD(1); }
;   for (int kt = 0; kt < nk; ++kt) {
;     __syncthreads();
;     G_COMPUTE(kt & 1, kt);
;   }
	global_load_dwordx4 v[160:163], v[190:191], off offset:3584
	global_load_dwordx4 v[164:167], v[188:189], off offset:3584
	s_waitcnt vmcnt(9)
	ds_write_b128 v209, v[218:221]
	s_waitcnt vmcnt(8)
	ds_write_b128 v210, v[222:225]
	ds_read_b128 v[218:221], v205 offset:36864
	ds_read_b128 v[222:225], v205 offset:41472
	ds_read_b128 v[234:237], v204
	ds_read_b128 v[238:241], v204 offset:4608
	s_setprio 1
	s_waitcnt lgkmcnt(1)
	v_mfma_f32_32x32x16_bf16 v[112:127], v[234:237], v[218:221], v[112:127]
	v_mfma_f32_32x32x16_bf16 v[48:63], v[234:237], v[222:225], v[48:63]
	s_waitcnt lgkmcnt(0)
	v_mfma_f32_32x32x16_bf16 v[96:111], v[238:241], v[218:221], v[96:111]
	v_mfma_f32_32x32x16_bf16 v[32:47], v[238:241], v[222:225], v[32:47]
	ds_read_b128 v[234:237], v204 offset:9216
	ds_read_b128 v[238:241], v204 offset:13824
	s_waitcnt vmcnt(7)
	ds_write_b128 v212, v[226:229]
	s_waitcnt vmcnt(6)
	ds_write_b128 v211, v[230:233]
	ds_read_b128 v[226:229], v205 offset:36896
	ds_read_b128 v[230:233], v205 offset:41504
	s_waitcnt lgkmcnt(5)
	v_mfma_f32_32x32x16_bf16 v[80:95], v[234:237], v[218:221], v[80:95]
	v_mfma_f32_32x32x16_bf16 v[16:31], v[234:237], v[222:225], v[16:31]
	ds_read_b128 v[234:237], v204 offset:32
	s_waitcnt lgkmcnt(5)
	v_mfma_f32_32x32x16_bf16 v[64:79], v[238:241], v[218:221], v[64:79]
	v_mfma_f32_32x32x16_bf16 v[0:15], v[238:241], v[222:225], v[0:15]
	ds_read_b128 v[238:241], v204 offset:4640
	s_setprio 0
	global_load_dwordx4 v[218:221], v[194:195], off offset:3584
	global_load_dwordx4 v[222:225], v[196:197], off offset:3584
	s_setprio 1
	s_waitcnt lgkmcnt(1)
	v_mfma_f32_32x32x16_bf16 v[112:127], v[234:237], v[226:229], v[112:127]
	v_mfma_f32_32x32x16_bf16 v[48:63], v[234:237], v[230:233], v[48:63]
	s_waitcnt lgkmcnt(0)
	v_mfma_f32_32x32x16_bf16 v[96:111], v[238:241], v[226:229], v[96:111]
	v_mfma_f32_32x32x16_bf16 v[32:47], v[238:241], v[230:233], v[32:47]
	ds_read_b128 v[234:237], v204 offset:9248
	ds_read_b128 v[238:241], v204 offset:13856
	s_waitcnt vmcnt(7)
	ds_write_b128 v214, v[176:179]
	s_waitcnt vmcnt(6)
	ds_write_b128 v213, v[180:183]
	ds_read_b128 v[176:179], v205 offset:36928
	ds_read_b128 v[180:183], v205 offset:41536
	s_waitcnt lgkmcnt(5)
	v_mfma_f32_32x32x16_bf16 v[80:95], v[234:237], v[226:229], v[80:95]
	v_mfma_f32_32x32x16_bf16 v[16:31], v[234:237], v[230:233], v[16:31]
	ds_read_b128 v[234:237], v204 offset:64
	s_waitcnt lgkmcnt(5)
	v_mfma_f32_32x32x16_bf16 v[64:79], v[238:241], v[226:229], v[64:79]
	v_mfma_f32_32x32x16_bf16 v[0:15], v[238:241], v[230:233], v[0:15]
	ds_read_b128 v[238:241], v204 offset:4672
	s_setprio 0
	global_load_dwordx4 v[226:229], v[184:185], off offset:3584
	global_load_dwordx4 v[230:233], v[186:187], off offset:3584
	s_setprio 1
	s_waitcnt lgkmcnt(1)
	v_mfma_f32_32x32x16_bf16 v[112:127], v[234:237], v[176:179], v[112:127]
	v_mfma_f32_32x32x16_bf16 v[48:63], v[234:237], v[180:183], v[48:63]
	s_waitcnt lgkmcnt(0)
	v_mfma_f32_32x32x16_bf16 v[96:111], v[238:241], v[176:179], v[96:111]
	v_mfma_f32_32x32x16_bf16 v[32:47], v[238:241], v[180:183], v[32:47]
	ds_read_b128 v[234:237], v204 offset:9280
	ds_read_b128 v[238:241], v204 offset:13888
	s_waitcnt vmcnt(7)
	ds_write_b128 v217, v[168:171]
	s_waitcnt vmcnt(6)
	ds_write_b128 v216, v[172:175]
	ds_read_b128 v[168:171], v205 offset:36960
	ds_read_b128 v[172:175], v205 offset:41568
	s_waitcnt lgkmcnt(5)
	v_mfma_f32_32x32x16_bf16 v[80:95], v[234:237], v[176:179], v[80:95]
	v_mfma_f32_32x32x16_bf16 v[16:31], v[234:237], v[180:183], v[16:31]
	ds_read_b128 v[234:237], v204 offset:96
	s_waitcnt lgkmcnt(5)
	v_mfma_f32_32x32x16_bf16 v[64:79], v[238:241], v[176:179], v[64:79]
	v_mfma_f32_32x32x16_bf16 v[0:15], v[238:241], v[180:183], v[0:15]
	ds_read_b128 v[238:241], v204 offset:4704
	s_setprio 0
	global_load_dwordx4 v[176:179], v[198:199], off offset:3584
	global_load_dwordx4 v[180:183], v[200:201], off offset:3584
	s_setprio 1
	s_waitcnt lgkmcnt(1)
	v_mfma_f32_32x32x16_bf16 v[112:127], v[234:237], v[168:171], v[112:127]
	v_mfma_f32_32x32x16_bf16 v[48:63], v[234:237], v[172:175], v[48:63]
	s_waitcnt lgkmcnt(0)
	v_mfma_f32_32x32x16_bf16 v[96:111], v[238:241], v[168:171], v[96:111]
	v_mfma_f32_32x32x16_bf16 v[32:47], v[238:241], v[172:175], v[32:47]
	ds_read_b128 v[234:237], v204 offset:9312
	ds_read_b128 v[238:241], v204 offset:13920
	s_waitcnt lgkmcnt(1)
	v_mfma_f32_32x32x16_bf16 v[80:95], v[234:237], v[168:171], v[80:95]
	v_mfma_f32_32x32x16_bf16 v[16:31], v[234:237], v[172:175], v[16:31]
	s_waitcnt lgkmcnt(0)
	v_mfma_f32_32x32x16_bf16 v[64:79], v[238:241], v[168:171], v[64:79]
	v_mfma_f32_32x32x16_bf16 v[0:15], v[238:241], v[172:175], v[0:15]
	s_setprio 0
	s_barrier
; template <bool trans>
; DI void gemm_core(const GTile& tl, const GTile& nx, bool has_next  , bool chain  , bool pre, u32x4 (&ra)[4], u32x4 (&rb)[4], char* smem, f32x16 (&acc)[2][4]) {
;     ...
;   const int nk = K / 64;
;   if (!pre) { G_LOAD(0); G_STORE(0); G_LOAD(1); }
;   for (int kt = 0; kt < nk; ++kt) {
;     __syncthreads();
;     G_COMPUTE(kt & 1, kt);
;   }
	global_load_dwordx4 v[168:171], v[190:191], off offset:3712
	global_load_dwordx4 v[172:175], v[188:189], off offset:3712
	s_waitcnt vmcnt(9)
	ds_write_b128 v215, v[160:163]
	s_waitcnt vmcnt(8)
	ds_write_b128 v215, v[164:167] offset:36864
	ds_read_b128 v[160:163], v208
	ds_read_b128 v[164:167], v208 offset:4608
	ds_read_b128 v[234:237], v192
	ds_read_b128 v[238:241], v192 offset:4608
	s_setprio 1
	s_waitcnt lgkmcnt(1)
	v_mfma_f32_32x32x16_bf16 v[112:127], v[234:237], v[160:163], v[112:127]
	v_mfma_f32_32x32x16_bf16 v[48:63], v[234:237], v[164:167], v[48:63]
	s_waitcnt lgkmcnt(0)
	v_mfma_f32_32x32x16_bf16 v[96:111], v[238:241], v[160:163], v[96:111]
	v_mfma_f32_32x32x16_bf16 v[32:47], v[238:241], v[164:167], v[32:47]
	ds_read_b128 v[234:237], v192 offset:9216
	ds_read_b128 v[238:241], v192 offset:13824
	s_waitcnt vmcnt(7)
	ds_write_b128 v215, v[218:221] offset:9216
	s_waitcnt vmcnt(6)
	ds_write_b128 v215, v[222:225] offset:46080
	ds_read_b128 v[218:221], v208 offset:32
	ds_read_b128 v[222:225], v208 offset:4640
	s_waitcnt lgkmcnt(5)
	v_mfma_f32_32x32x16_bf16 v[80:95], v[234:237], v[160:163], v[80:95]
	v_mfma_f32_32x32x16_bf16 v[16:31], v[234:237], v[164:167], v[16:31]
	ds_read_b128 v[234:237], v192 offset:32
	s_waitcnt lgkmcnt(5)
	v_mfma_f32_32x32x16_bf16 v[64:79], v[238:241], v[160:163], v[64:79]
	v_mfma_f32_32x32x16_bf16 v[0:15], v[238:241], v[164:167], v[0:15]
	ds_read_b128 v[238:241], v192 offset:4640
	s_setprio 0
	global_load_dwordx4 v[160:163], v[194:195], off offset:3712
	global_load_dwordx4 v[164:167], v[196:197], off offset:3712
	s_setprio 1
	s_waitcnt lgkmcnt(1)
	v_mfma_f32_32x32x16_bf16 v[112:127], v[234:237], v[218:221], v[112:127]
	v_mfma_f32_32x32x16_bf16 v[48:63], v[234:237], v[222:225], v[48:63]
	s_waitcnt lgkmcnt(0)
	v_mfma_f32_32x32x16_bf16 v[96:111], v[238:241], v[218:221], v[96:111]
	v_mfma_f32_32x32x16_bf16 v[32:47], v[238:241], v[222:225], v[32:47]
	ds_read_b128 v[234:237], v192 offset:9248
	ds_read_b128 v[238:241], v192 offset:13856
	s_waitcnt vmcnt(7)
	ds_write_b128 v215, v[226:229] offset:18432
	s_waitcnt vmcnt(6)
	ds_write_b128 v215, v[230:233] offset:55296
	ds_read_b128 v[226:229], v208 offset:64
	ds_read_b128 v[230:233], v208 offset:4672
	s_waitcnt lgkmcnt(5)
	v_mfma_f32_32x32x16_bf16 v[80:95], v[234:237], v[218:221], v[80:95]
	v_mfma_f32_32x32x16_bf16 v[16:31], v[234:237], v[222:225], v[16:31]
	ds_read_b128 v[234:237], v192 offset:64
	s_waitcnt lgkmcnt(5)
	v_mfma_f32_32x32x16_bf16 v[64:79], v[238:241], v[218:221], v[64:79]
	v_mfma_f32_32x32x16_bf16 v[0:15], v[238:241], v[222:225], v[0:15]
	ds_read_b128 v[238:241], v192 offset:4672
	s_setprio 0
	global_load_dwordx4 v[218:221], v[184:185], off offset:3712
	global_load_dwordx4 v[222:225], v[186:187], off offset:3712
	s_setprio 1
	s_waitcnt lgkmcnt(1)
	v_mfma_f32_32x32x16_bf16 v[112:127], v[234:237], v[226:229], v[112:127]
	v_mfma_f32_32x32x16_bf16 v[48:63], v[234:237], v[230:233], v[48:63]
	s_waitcnt lgkmcnt(0)
	v_mfma_f32_32x32x16_bf16 v[96:111], v[238:241], v[226:229], v[96:111]
	v_mfma_f32_32x32x16_bf16 v[32:47], v[238:241], v[230:233], v[32:47]
	ds_read_b128 v[234:237], v192 offset:9280
	ds_read_b128 v[238:241], v192 offset:13888
	s_waitcnt vmcnt(7)
	ds_write_b128 v215, v[176:179] offset:27648
	s_waitcnt vmcnt(6)
	ds_write_b128 v215, v[180:183] offset:64512
	ds_read_b128 v[176:179], v208 offset:96
	ds_read_b128 v[180:183], v208 offset:4704
	s_waitcnt lgkmcnt(5)
	v_mfma_f32_32x32x16_bf16 v[80:95], v[234:237], v[226:229], v[80:95]
	v_mfma_f32_32x32x16_bf16 v[16:31], v[234:237], v[230:233], v[16:31]
	ds_read_b128 v[234:237], v192 offset:96
	s_waitcnt lgkmcnt(5)
	v_mfma_f32_32x32x16_bf16 v[64:79], v[238:241], v[226:229], v[64:79]
	v_mfma_f32_32x32x16_bf16 v[0:15], v[238:241], v[230:233], v[0:15]
	ds_read_b128 v[238:241], v192 offset:4704
	s_setprio 0
	global_load_dwordx4 v[226:229], v[198:199], off offset:3712
	global_load_dwordx4 v[230:233], v[200:201], off offset:3712
	s_setprio 1
	s_waitcnt lgkmcnt(1)
	v_mfma_f32_32x32x16_bf16 v[112:127], v[234:237], v[176:179], v[112:127]
	v_mfma_f32_32x32x16_bf16 v[48:63], v[234:237], v[180:183], v[48:63]
	s_waitcnt lgkmcnt(0)
	v_mfma_f32_32x32x16_bf16 v[96:111], v[238:241], v[176:179], v[96:111]
	v_mfma_f32_32x32x16_bf16 v[32:47], v[238:241], v[180:183], v[32:47]
	ds_read_b128 v[234:237], v192 offset:9312
	ds_read_b128 v[238:241], v192 offset:13920
	s_waitcnt lgkmcnt(1)
	v_mfma_f32_32x32x16_bf16 v[80:95], v[234:237], v[176:179], v[80:95]
	v_mfma_f32_32x32x16_bf16 v[16:31], v[234:237], v[180:183], v[16:31]
	s_waitcnt lgkmcnt(0)
	v_mfma_f32_32x32x16_bf16 v[64:79], v[238:241], v[176:179], v[64:79]
	v_mfma_f32_32x32x16_bf16 v[0:15], v[238:241], v[180:183], v[0:15]
	s_setprio 0
	s_barrier
; template <bool trans>
; DI void gemm_core(const GTile& tl, const GTile& nx, bool has_next  , bool chain  , bool pre, u32x4 (&ra)[4], u32x4 (&rb)[4], char* smem, f32x16 (&acc)[2][4]) {
;     ...
;   const int nk = K / 64;
;   if (!pre) { G_LOAD(0); G_STORE(0); G_LOAD(1); }
;   for (int kt = 0; kt < nk; ++kt) {
;     __syncthreads();
;     G_COMPUTE(kt & 1, kt);
;   }
	global_load_dwordx4 v[176:179], v[190:191], off offset:3840
	global_load_dwordx4 v[180:183], v[188:189], off offset:3840
	s_waitcnt vmcnt(9)
	ds_write_b128 v209, v[168:171]
	s_waitcnt vmcnt(8)
	ds_write_b128 v210, v[172:175]
	ds_read_b128 v[168:171], v205 offset:36864
	ds_read_b128 v[172:175], v205 offset:41472
	ds_read_b128 v[234:237], v204
	ds_read_b128 v[238:241], v204 offset:4608
	s_setprio 1
	s_waitcnt lgkmcnt(1)
	v_mfma_f32_32x32x16_bf16 v[112:127], v[234:237], v[168:171], v[112:127]
	v_mfma_f32_32x32x16_bf16 v[48:63], v[234:237], v[172:175], v[48:63]
	s_waitcnt lgkmcnt(0)
	v_mfma_f32_32x32x16_bf16 v[96:111], v[238:241], v[168:171], v[96:111]
	v_mfma_f32_32x32x16_bf16 v[32:47], v[238:241], v[172:175], v[32:47]
	ds_read_b128 v[234:237], v204 offset:9216
	ds_read_b128 v[238:241], v204 offset:13824
	s_waitcnt lgkmcnt(1)
	v_mfma_f32_32x32x16_bf16 v[80:95], v[234:237], v[168:171], v[80:95]
	v_mfma_f32_32x32x16_bf16 v[16:31], v[234:237], v[172:175], v[16:31]
	s_waitcnt lgkmcnt(0)
	v_mfma_f32_32x32x16_bf16 v[64:79], v[238:241], v[168:171], v[64:79]
	v_mfma_f32_32x32x16_bf16 v[0:15], v[238:241], v[172:175], v[0:15]
	s_setprio 0
	global_load_dwordx4 v[234:237], v[194:195], off offset:3840
	global_load_dwordx4 v[238:241], v[196:197], off offset:3840
	s_waitcnt vmcnt(9)
	ds_write_b128 v212, v[160:163]
	s_waitcnt vmcnt(8)
	ds_write_b128 v211, v[164:167]
	ds_read_b128 v[160:163], v205 offset:36896
	ds_read_b128 v[164:167], v205 offset:41504
	ds_read_b128 v[168:171], v204 offset:32
	ds_read_b128 v[172:175], v204 offset:4640
	s_setprio 1
	s_waitcnt lgkmcnt(1)
	v_mfma_f32_32x32x16_bf16 v[112:127], v[168:171], v[160:163], v[112:127]
	v_mfma_f32_32x32x16_bf16 v[48:63], v[168:171], v[164:167], v[48:63]
	s_waitcnt lgkmcnt(0)
	v_mfma_f32_32x32x16_bf16 v[96:111], v[172:175], v[160:163], v[96:111]
	v_mfma_f32_32x32x16_bf16 v[32:47], v[172:175], v[164:167], v[32:47]
	ds_read_b128 v[168:171], v204 offset:9248
	ds_read_b128 v[172:175], v204 offset:13856
	s_waitcnt lgkmcnt(1)
	v_mfma_f32_32x32x16_bf16 v[80:95], v[168:171], v[160:163], v[80:95]
	v_mfma_f32_32x32x16_bf16 v[16:31], v[168:171], v[164:167], v[16:31]
	s_waitcnt lgkmcnt(0)
	v_mfma_f32_32x32x16_bf16 v[64:79], v[172:175], v[160:163], v[64:79]
	v_mfma_f32_32x32x16_bf16 v[0:15], v[172:175], v[164:167], v[0:15]
	s_setprio 0
	global_load_dwordx4 v[242:245], v[184:185], off offset:3840
	global_load_dwordx4 v[246:249], v[186:187], off offset:3840
	s_waitcnt vmcnt(9)
	ds_write_b128 v214, v[218:221]
	s_waitcnt vmcnt(8)
	ds_write_b128 v213, v[222:225]
	ds_read_b128 v[160:163], v205 offset:36928
	ds_read_b128 v[164:167], v205 offset:41536
	ds_read_b128 v[168:171], v204 offset:64
	ds_read_b128 v[172:175], v204 offset:4672
	s_setprio 1
	s_waitcnt lgkmcnt(1)
	v_mfma_f32_32x32x16_bf16 v[112:127], v[168:171], v[160:163], v[112:127]
	v_mfma_f32_32x32x16_bf16 v[48:63], v[168:171], v[164:167], v[48:63]
	s_waitcnt lgkmcnt(0)
	v_mfma_f32_32x32x16_bf16 v[96:111], v[172:175], v[160:163], v[96:111]
	v_mfma_f32_32x32x16_bf16 v[32:47], v[172:175], v[164:167], v[32:47]
	ds_read_b128 v[168:171], v204 offset:9280
	ds_read_b128 v[172:175], v204 offset:13888
	s_waitcnt lgkmcnt(1)
	v_mfma_f32_32x32x16_bf16 v[80:95], v[168:171], v[160:163], v[80:95]
	v_mfma_f32_32x32x16_bf16 v[16:31], v[168:171], v[164:167], v[16:31]
	s_waitcnt lgkmcnt(0)
	v_mfma_f32_32x32x16_bf16 v[64:79], v[172:175], v[160:163], v[64:79]
	v_mfma_f32_32x32x16_bf16 v[0:15], v[172:175], v[164:167], v[0:15]
	s_setprio 0
	global_load_dwordx4 v[218:221], v[198:199], off offset:3840
	global_load_dwordx4 v[222:225], v[200:201], off offset:3840
	s_waitcnt vmcnt(9)
	ds_write_b128 v217, v[226:229]
	s_waitcnt vmcnt(8)
	ds_write_b128 v216, v[230:233]
	ds_read_b128 v[160:163], v205 offset:36960
	ds_read_b128 v[164:167], v205 offset:41568
	ds_read_b128 v[168:171], v204 offset:96
	ds_read_b128 v[172:175], v204 offset:4704
	s_setprio 1
	s_waitcnt lgkmcnt(1)
	v_mfma_f32_32x32x16_bf16 v[112:127], v[168:171], v[160:163], v[112:127]
	v_mfma_f32_32x32x16_bf16 v[48:63], v[168:171], v[164:167], v[48:63]
	s_waitcnt lgkmcnt(0)
	v_mfma_f32_32x32x16_bf16 v[96:111], v[172:175], v[160:163], v[96:111]
	v_mfma_f32_32x32x16_bf16 v[32:47], v[172:175], v[164:167], v[32:47]
	ds_read_b128 v[168:171], v204 offset:9312
	ds_read_b128 v[172:175], v204 offset:13920
	s_waitcnt lgkmcnt(1)
	v_mfma_f32_32x32x16_bf16 v[80:95], v[168:171], v[160:163], v[80:95]
	v_mfma_f32_32x32x16_bf16 v[16:31], v[168:171], v[164:167], v[16:31]
	s_waitcnt lgkmcnt(0)
	v_mfma_f32_32x32x16_bf16 v[64:79], v[172:175], v[160:163], v[64:79]
	v_mfma_f32_32x32x16_bf16 v[0:15], v[172:175], v[164:167], v[0:15]
	s_setprio 0
	s_barrier
; template <bool trans>
; DI void gemm_core(const GTile& tl, const GTile& nx, bool has_next  , bool chain  , bool pre, u32x4 (&ra)[4], u32x4 (&rb)[4], char* smem, f32x16 (&acc)[2][4]) {
;     ...
;   const int nk = K / 64;
;   if (!pre) { G_LOAD(0); G_STORE(0); G_LOAD(1); }
;   for (int kt = 0; kt < nk; ++kt) {
;     __syncthreads();
;     G_COMPUTE(kt & 1, kt);
;   }
	global_load_dwordx4 v[160:163], v[190:191], off offset:3968
	global_load_dwordx4 v[164:167], v[188:189], off offset:3968
	s_waitcnt vmcnt(9)
	ds_write_b128 v215, v[176:179]
	s_waitcnt vmcnt(8)
	ds_write_b128 v215, v[180:183] offset:36864
	ds_read_b128 v[168:171], v208
	ds_read_b128 v[172:175], v208 offset:4608
	ds_read_b128 v[176:179], v192
	ds_read_b128 v[180:183], v192 offset:4608
	s_setprio 1
	s_waitcnt lgkmcnt(1)
	v_mfma_f32_32x32x16_bf16 v[112:127], v[176:179], v[168:171], v[112:127]
	v_mfma_f32_32x32x16_bf16 v[48:63], v[176:179], v[172:175], v[48:63]
	s_waitcnt lgkmcnt(0)
	v_mfma_f32_32x32x16_bf16 v[96:111], v[180:183], v[168:171], v[96:111]
	v_mfma_f32_32x32x16_bf16 v[32:47], v[180:183], v[172:175], v[32:47]
	ds_read_b128 v[176:179], v192 offset:9216
	ds_read_b128 v[180:183], v192 offset:13824
	s_waitcnt lgkmcnt(1)
	v_mfma_f32_32x32x16_bf16 v[80:95], v[176:179], v[168:171], v[80:95]
	v_mfma_f32_32x32x16_bf16 v[16:31], v[176:179], v[172:175], v[16:31]
	s_waitcnt lgkmcnt(0)
	v_mfma_f32_32x32x16_bf16 v[64:79], v[180:183], v[168:171], v[64:79]
	v_mfma_f32_32x32x16_bf16 v[0:15], v[180:183], v[172:175], v[0:15]
	s_setprio 0
	global_load_dwordx4 v[168:171], v[194:195], off offset:3968
	global_load_dwordx4 v[172:175], v[196:197], off offset:3968
	s_waitcnt vmcnt(9)
	ds_write_b128 v215, v[234:237] offset:9216
	s_waitcnt vmcnt(8)
	ds_write_b128 v215, v[238:241] offset:46080
	ds_read_b128 v[176:179], v208 offset:32
	ds_read_b128 v[180:183], v208 offset:4640
	ds_read_b128 v[188:191], v192 offset:32
	ds_read_b128 v[194:197], v192 offset:4640
	s_setprio 1
	s_waitcnt lgkmcnt(1)
	v_mfma_f32_32x32x16_bf16 v[112:127], v[188:191], v[176:179], v[112:127]
	v_mfma_f32_32x32x16_bf16 v[48:63], v[188:191], v[180:183], v[48:63]
	s_waitcnt lgkmcnt(0)
	v_mfma_f32_32x32x16_bf16 v[96:111], v[194:197], v[176:179], v[96:111]
	v_mfma_f32_32x32x16_bf16 v[32:47], v[194:197], v[180:183], v[32:47]
	ds_read_b128 v[188:191], v192 offset:9248
	ds_read_b128 v[194:197], v192 offset:13856
	s_waitcnt lgkmcnt(1)
	v_mfma_f32_32x32x16_bf16 v[80:95], v[188:191], v[176:179], v[80:95]
	v_mfma_f32_32x32x16_bf16 v[16:31], v[188:191], v[180:183], v[16:31]
	s_waitcnt lgkmcnt(0)
	v_mfma_f32_32x32x16_bf16 v[64:79], v[194:197], v[176:179], v[64:79]
	v_mfma_f32_32x32x16_bf16 v[0:15], v[194:197], v[180:183], v[0:15]
	s_setprio 0
	global_load_dwordx4 v[176:179], v[184:185], off offset:3968
	global_load_dwordx4 v[180:183], v[186:187], off offset:3968
	s_waitcnt vmcnt(9)
	ds_write_b128 v215, v[242:245] offset:18432
	s_waitcnt vmcnt(8)
	ds_write_b128 v215, v[246:249] offset:55296
	ds_read_b128 v[184:187], v208 offset:64
	ds_read_b128 v[188:191], v208 offset:4672
	ds_read_b128 v[194:197], v192 offset:64
	ds_read_b128 v[226:229], v192 offset:4672
	s_setprio 1
	s_waitcnt lgkmcnt(1)
	v_mfma_f32_32x32x16_bf16 v[112:127], v[194:197], v[184:187], v[112:127]
	v_mfma_f32_32x32x16_bf16 v[48:63], v[194:197], v[188:191], v[48:63]
	s_waitcnt lgkmcnt(0)
	v_mfma_f32_32x32x16_bf16 v[96:111], v[226:229], v[184:187], v[96:111]
	v_mfma_f32_32x32x16_bf16 v[32:47], v[226:229], v[188:191], v[32:47]
	ds_read_b128 v[194:197], v192 offset:9280
	ds_read_b128 v[226:229], v192 offset:13888
	s_waitcnt lgkmcnt(1)
	v_mfma_f32_32x32x16_bf16 v[80:95], v[194:197], v[184:187], v[80:95]
	v_mfma_f32_32x32x16_bf16 v[16:31], v[194:197], v[188:191], v[16:31]
	s_waitcnt lgkmcnt(0)
	v_mfma_f32_32x32x16_bf16 v[64:79], v[226:229], v[184:187], v[64:79]
	v_mfma_f32_32x32x16_bf16 v[0:15], v[226:229], v[188:191], v[0:15]
	s_setprio 0
	global_load_dwordx4 v[184:187], v[198:199], off offset:3968
	global_load_dwordx4 v[188:191], v[200:201], off offset:3968
	s_waitcnt vmcnt(9)
	ds_write_b128 v215, v[218:221] offset:27648
	s_waitcnt vmcnt(8)
	ds_write_b128 v215, v[222:225] offset:64512
	ds_read_b128 v[194:197], v208 offset:96
	ds_read_b128 v[198:201], v208 offset:4704
	ds_read_b128 v[218:221], v192 offset:96
	ds_read_b128 v[222:225], v192 offset:4704
	s_setprio 1
	s_waitcnt lgkmcnt(1)
	v_mfma_f32_32x32x16_bf16 v[112:127], v[218:221], v[194:197], v[112:127]
	v_mfma_f32_32x32x16_bf16 v[48:63], v[218:221], v[198:201], v[48:63]
	s_waitcnt lgkmcnt(0)
	v_mfma_f32_32x32x16_bf16 v[96:111], v[222:225], v[194:197], v[96:111]
	v_mfma_f32_32x32x16_bf16 v[32:47], v[222:225], v[198:201], v[32:47]
	ds_read_b128 v[218:221], v192 offset:9312
	ds_read_b128 v[222:225], v192 offset:13920
	s_waitcnt lgkmcnt(1)
	v_mfma_f32_32x32x16_bf16 v[80:95], v[218:221], v[194:197], v[80:95]
	v_mfma_f32_32x32x16_bf16 v[16:31], v[218:221], v[198:201], v[16:31]
	s_waitcnt lgkmcnt(0)
	v_mfma_f32_32x32x16_bf16 v[64:79], v[222:225], v[194:197], v[64:79]
	v_mfma_f32_32x32x16_bf16 v[0:15], v[222:225], v[198:201], v[0:15]
	s_setprio 0
	s_barrier
; template <bool trans>
; DI void gemm_core(const GTile& tl, const GTile& nx, bool has_next  , bool chain  , bool pre, u32x4 (&ra)[4], u32x4 (&rb)[4], char* smem, f32x16 (&acc)[2][4]) {
;     ...
;   const int nk = K / 64;
;   if (!pre) { G_LOAD(0); G_STORE(0); G_LOAD(1); }
;   for (int kt = 0; kt < nk; ++kt) {
;     __syncthreads();
;     G_COMPUTE(kt & 1, kt);
;   }
	s_waitcnt vmcnt(7)
	ds_write_b128 v209, v[160:163]
	s_waitcnt vmcnt(6)
	ds_write_b128 v210, v[164:167]
	ds_read_b128 v[194:197], v205 offset:36864
	ds_read_b128 v[198:201], v205 offset:41472
	ds_read_b128 v[218:221], v204
	ds_read_b128 v[222:225], v204 offset:4608
	s_setprio 1
	s_waitcnt lgkmcnt(1)
	v_mfma_f32_32x32x16_bf16 v[112:127], v[218:221], v[194:197], v[112:127]
	v_mfma_f32_32x32x16_bf16 v[48:63], v[218:221], v[198:201], v[48:63]
	s_waitcnt lgkmcnt(0)
	v_mfma_f32_32x32x16_bf16 v[96:111], v[222:225], v[194:197], v[96:111]
	v_mfma_f32_32x32x16_bf16 v[32:47], v[222:225], v[198:201], v[32:47]
	ds_read_b128 v[218:221], v204 offset:9216
	ds_read_b128 v[222:225], v204 offset:13824
	s_waitcnt lgkmcnt(1)
	v_mfma_f32_32x32x16_bf16 v[80:95], v[218:221], v[194:197], v[80:95]
	v_mfma_f32_32x32x16_bf16 v[16:31], v[218:221], v[198:201], v[16:31]
	s_waitcnt lgkmcnt(0)
	v_mfma_f32_32x32x16_bf16 v[64:79], v[222:225], v[194:197], v[64:79]
	v_mfma_f32_32x32x16_bf16 v[0:15], v[222:225], v[198:201], v[0:15]
	s_setprio 0
	s_waitcnt vmcnt(5)
	ds_write_b128 v212, v[168:171]
	s_waitcnt vmcnt(4)
	ds_write_b128 v211, v[172:175]
	ds_read_b128 v[194:197], v205 offset:36896
	ds_read_b128 v[198:201], v205 offset:41504
	ds_read_b128 v[218:221], v204 offset:32
	ds_read_b128 v[222:225], v204 offset:4640
	s_setprio 1
	s_waitcnt lgkmcnt(1)
	v_mfma_f32_32x32x16_bf16 v[112:127], v[218:221], v[194:197], v[112:127]
	v_mfma_f32_32x32x16_bf16 v[48:63], v[218:221], v[198:201], v[48:63]
	s_waitcnt lgkmcnt(0)
	v_mfma_f32_32x32x16_bf16 v[96:111], v[222:225], v[194:197], v[96:111]
	v_mfma_f32_32x32x16_bf16 v[32:47], v[222:225], v[198:201], v[32:47]
	ds_read_b128 v[218:221], v204 offset:9248
	ds_read_b128 v[222:225], v204 offset:13856
	s_waitcnt lgkmcnt(1)
	v_mfma_f32_32x32x16_bf16 v[80:95], v[218:221], v[194:197], v[80:95]
	v_mfma_f32_32x32x16_bf16 v[16:31], v[218:221], v[198:201], v[16:31]
	s_waitcnt lgkmcnt(0)
	v_mfma_f32_32x32x16_bf16 v[64:79], v[222:225], v[194:197], v[64:79]
	v_mfma_f32_32x32x16_bf16 v[0:15], v[222:225], v[198:201], v[0:15]
	s_setprio 0
	s_waitcnt vmcnt(3)
	ds_write_b128 v214, v[176:179]
	s_waitcnt vmcnt(2)
	ds_write_b128 v213, v[180:183]
	ds_read_b128 v[194:197], v205 offset:36928
	ds_read_b128 v[198:201], v205 offset:41536
	ds_read_b128 v[210:213], v204 offset:64
	ds_read_b128 v[218:221], v204 offset:4672
	s_setprio 1
	s_waitcnt lgkmcnt(1)
	v_mfma_f32_32x32x16_bf16 v[112:127], v[210:213], v[194:197], v[112:127]
	v_mfma_f32_32x32x16_bf16 v[48:63], v[210:213], v[198:201], v[48:63]
	s_waitcnt lgkmcnt(0)
	v_mfma_f32_32x32x16_bf16 v[96:111], v[218:221], v[194:197], v[96:111]
	v_mfma_f32_32x32x16_bf16 v[32:47], v[218:221], v[198:201], v[32:47]
	ds_read_b128 v[210:213], v204 offset:9280
	ds_read_b128 v[218:221], v204 offset:13888
	s_waitcnt lgkmcnt(1)
	v_mfma_f32_32x32x16_bf16 v[80:95], v[210:213], v[194:197], v[80:95]
	v_mfma_f32_32x32x16_bf16 v[16:31], v[210:213], v[198:201], v[16:31]
	s_waitcnt lgkmcnt(0)
	v_mfma_f32_32x32x16_bf16 v[64:79], v[218:221], v[194:197], v[64:79]
	v_mfma_f32_32x32x16_bf16 v[0:15], v[218:221], v[198:201], v[0:15]
	s_setprio 0
	s_waitcnt vmcnt(1)
	ds_write_b128 v217, v[184:187]
	s_waitcnt vmcnt(0)
	ds_write_b128 v216, v[188:191]
	ds_read_b128 v[194:197], v205 offset:36960
	ds_read_b128 v[198:201], v205 offset:41568
	ds_read_b128 v[210:213], v204 offset:96
	ds_read_b128 v[214:217], v204 offset:4704
	s_setprio 1
	s_waitcnt lgkmcnt(1)
	v_mfma_f32_32x32x16_bf16 v[112:127], v[210:213], v[194:197], v[112:127]
	v_mfma_f32_32x32x16_bf16 v[48:63], v[210:213], v[198:201], v[48:63]
	s_waitcnt lgkmcnt(0)
	v_mfma_f32_32x32x16_bf16 v[96:111], v[214:217], v[194:197], v[96:111]
	v_mfma_f32_32x32x16_bf16 v[32:47], v[214:217], v[198:201], v[32:47]
	ds_read_b128 v[210:213], v204 offset:9312
	ds_read_b128 v[214:217], v204 offset:13920
	s_waitcnt lgkmcnt(1)
	v_mfma_f32_32x32x16_bf16 v[80:95], v[210:213], v[194:197], v[80:95]
	v_mfma_f32_32x32x16_bf16 v[16:31], v[210:213], v[198:201], v[16:31]
	s_waitcnt lgkmcnt(0)
	v_mfma_f32_32x32x16_bf16 v[64:79], v[214:217], v[194:197], v[64:79]
	v_mfma_f32_32x32x16_bf16 v[0:15], v[214:217], v[198:201], v[0:15]
	s_setprio 0
	s_barrier
; template <bool trans>
; DI void gemm_core(const GTile& tl, const GTile& nx, bool has_next  , bool chain  , bool pre, u32x4 (&ra)[4], u32x4 (&rb)[4], char* smem, f32x16 (&acc)[2][4]) {
;     ...
;   const int nk = K / 64;
;   if (!pre) { G_LOAD(0); G_STORE(0); G_LOAD(1); }
;   for (int kt = 0; kt < nk; ++kt) {
;     __syncthreads();
;     G_COMPUTE(kt & 1, kt);
;   }
;   if (!has_next) __syncthreads();
	ds_read_b128 v[194:197], v208
	ds_read_b128 v[198:201], v208 offset:4608
	ds_read_b128 v[210:213], v192
	ds_read_b128 v[214:217], v192 offset:4608
	s_setprio 1
	s_waitcnt lgkmcnt(1)
	v_mfma_f32_32x32x16_bf16 v[112:127], v[210:213], v[194:197], v[112:127]
	v_mfma_f32_32x32x16_bf16 v[48:63], v[210:213], v[198:201], v[48:63]
	s_waitcnt lgkmcnt(0)
	v_mfma_f32_32x32x16_bf16 v[96:111], v[214:217], v[194:197], v[96:111]
	v_mfma_f32_32x32x16_bf16 v[32:47], v[214:217], v[198:201], v[32:47]
	ds_read_b128 v[210:213], v192 offset:9216
	ds_read_b128 v[214:217], v192 offset:13824
	s_waitcnt lgkmcnt(1)
	v_mfma_f32_32x32x16_bf16 v[80:95], v[210:213], v[194:197], v[80:95]
	v_mfma_f32_32x32x16_bf16 v[16:31], v[210:213], v[198:201], v[16:31]
	s_waitcnt lgkmcnt(0)
	v_mfma_f32_32x32x16_bf16 v[64:79], v[214:217], v[194:197], v[64:79]
	v_mfma_f32_32x32x16_bf16 v[0:15], v[214:217], v[198:201], v[0:15]
	s_setprio 0
	ds_read_b128 v[194:197], v208 offset:32
	ds_read_b128 v[198:201], v208 offset:4640
	ds_read_b128 v[210:213], v192 offset:32
	ds_read_b128 v[214:217], v192 offset:4640
	s_setprio 1
	s_waitcnt lgkmcnt(1)
	v_mfma_f32_32x32x16_bf16 v[112:127], v[210:213], v[194:197], v[112:127]
	v_mfma_f32_32x32x16_bf16 v[48:63], v[210:213], v[198:201], v[48:63]
	s_waitcnt lgkmcnt(0)
	v_mfma_f32_32x32x16_bf16 v[96:111], v[214:217], v[194:197], v[96:111]
	v_mfma_f32_32x32x16_bf16 v[32:47], v[214:217], v[198:201], v[32:47]
	ds_read_b128 v[210:213], v192 offset:9248
	ds_read_b128 v[214:217], v192 offset:13856
	s_waitcnt lgkmcnt(1)
	v_mfma_f32_32x32x16_bf16 v[80:95], v[210:213], v[194:197], v[80:95]
	v_mfma_f32_32x32x16_bf16 v[16:31], v[210:213], v[198:201], v[16:31]
	s_waitcnt lgkmcnt(0)
	v_mfma_f32_32x32x16_bf16 v[64:79], v[214:217], v[194:197], v[64:79]
	v_mfma_f32_32x32x16_bf16 v[0:15], v[214:217], v[198:201], v[0:15]
	s_setprio 0
	ds_read_b128 v[194:197], v208 offset:64
	ds_read_b128 v[198:201], v208 offset:4672
	ds_read_b128 v[210:213], v192 offset:64
	ds_read_b128 v[214:217], v192 offset:4672
	s_setprio 1
	s_waitcnt lgkmcnt(1)
	v_mfma_f32_32x32x16_bf16 v[112:127], v[210:213], v[194:197], v[112:127]
	v_mfma_f32_32x32x16_bf16 v[48:63], v[210:213], v[198:201], v[48:63]
	s_waitcnt lgkmcnt(0)
	v_mfma_f32_32x32x16_bf16 v[96:111], v[214:217], v[194:197], v[96:111]
	v_mfma_f32_32x32x16_bf16 v[32:47], v[214:217], v[198:201], v[32:47]
	ds_read_b128 v[210:213], v192 offset:9280
	ds_read_b128 v[214:217], v192 offset:13888
	s_waitcnt lgkmcnt(1)
	v_mfma_f32_32x32x16_bf16 v[80:95], v[210:213], v[194:197], v[80:95]
	v_mfma_f32_32x32x16_bf16 v[16:31], v[210:213], v[198:201], v[16:31]
	s_waitcnt lgkmcnt(0)
	v_mfma_f32_32x32x16_bf16 v[64:79], v[214:217], v[194:197], v[64:79]
	v_mfma_f32_32x32x16_bf16 v[0:15], v[214:217], v[198:201], v[0:15]
	s_setprio 0
	ds_read_b128 v[194:197], v208 offset:96
	ds_read_b128 v[198:201], v208 offset:4704
	ds_read_b128 v[208:211], v192 offset:96
	ds_read_b128 v[212:215], v192 offset:4704
	s_setprio 1
	s_waitcnt lgkmcnt(1)
	v_mfma_f32_32x32x16_bf16 v[112:127], v[208:211], v[194:197], v[112:127]
	v_mfma_f32_32x32x16_bf16 v[48:63], v[208:211], v[198:201], v[48:63]
	s_waitcnt lgkmcnt(0)
	v_mfma_f32_32x32x16_bf16 v[96:111], v[212:215], v[194:197], v[96:111]
	v_mfma_f32_32x32x16_bf16 v[32:47], v[212:215], v[198:201], v[32:47]
	ds_read_b128 v[208:211], v192 offset:9312
	ds_read_b128 v[212:215], v192 offset:13920
	s_waitcnt lgkmcnt(1)
	v_mfma_f32_32x32x16_bf16 v[80:95], v[208:211], v[194:197], v[80:95]
	v_mfma_f32_32x32x16_bf16 v[16:31], v[208:211], v[198:201], v[16:31]
	s_waitcnt lgkmcnt(0)
	v_mfma_f32_32x32x16_bf16 v[64:79], v[212:215], v[194:197], v[64:79]
	v_mfma_f32_32x32x16_bf16 v[0:15], v[212:215], v[198:201], v[0:15]
	s_setprio 0
	s_andn2_b64 vcc, exec, s[48:49]
	s_cbranch_vccnz .LBB0_105
	s_barrier

; template <bool trans>
; DI void gemm_core(const GTile& tl, const GTile& nx, bool has_next  , bool chain  , bool pre, u32x4 (&ra)[4], u32x4 (&rb)[4], char* smem, f32x16 (&acc)[2][4]) {
;     ...
;   const int lrow = tid >> 3, kc = tid & 7;
;   const unsigned aoff = (unsigned)(lrow * lda + kc * 8) * 2u, boff = (unsigned)(lrow * ldb + kc * 8) * 2u;
;   const char* ag = (const char*)(A + (size_t)m0 * lda);
;   const char* bg = (const char*)(Bt + (size_t)n0 * ldb);
;   const unsigned aoffn = (unsigned)(lrow * nx.lda + kc * 8) * 2u, boffn = (unsigned)(lrow * nx.ldb + kc * 8) * 2u;
;   const char* agn = (const char*)(nx.A + (size_t)nx.m0 * nx.lda);
;   const char* bgn = (const char*)(nx.Bt + (size_t)nx.n0 * nx.ldb);
;     ...
;   const int nk = K / 64;
;   if (!pre) { G_LOAD(0); G_STORE(0); G_LOAD(1); }
;   for (int kt = 0; kt < nk; ++kt) {
;     __syncthreads();
;     G_COMPUTE(kt & 1, kt);
.LBB0_111:
	v_lshl_add_u64 v[136:137], s[0:1], 0, v[192:193]
	v_lshl_add_u64 v[138:139], s[2:3], 0, v[192:193]
	s_waitcnt lgkmcnt(0)
	s_barrier
	global_load_dwordx4 v[184:187], v[136:137], off offset:256
	global_load_dwordx4 v[188:191], v[138:139], off offset:256
	s_and_b32 s1, s36, 0x1f80000
	s_and_b32 s0, s38, 0xffffff00
	s_and_b32 s4, s33, 0xc0
	s_lshl_b32 s1, s1, 1
	s_add_u32 s2, s16, s1
	s_addc_u32 s3, s17, 0
	s_ashr_i32 s1, s0, 31
	s_lshl_b64 s[0:1], s[0:1], 12
	s_add_u32 s0, s22, s0
	s_addc_u32 s1, s23, s1
	s_lshr_b32 s5, s33, 1
	v_and_b32_e32 v11, 31, v8
	s_and_b32 s5, s5, 0xfffff80
	v_or_b32_e32 v12, s5, v11
	v_or_b32_e32 v11, s4, v11
	v_add3_u32 v148, 16, v10, v9
	v_lshrrev_b32_e32 v8, 1, v8
	v_mul_u32_u24_e32 v150, 0x90, v11
	v_lshl_add_u64 v[130:131], s[2:3], 0, v[192:193]
	v_lshl_add_u64 v[128:129], s[0:1], 0, v[192:193]
	v_and_b32_e32 v204, 16, v8
	v_add_u32_e32 v192, 0x12000, v148
	v_mul_lo_u32 v149, v12, s45
	v_add3_u32 v152, 16, v150, v204
	v_add_u32_e32 v159, 0x1b000, v148
	ds_write_b128 v192, v[0:3]
	s_waitcnt vmcnt(5)
	ds_write_b128 v159, v[4:7]
	v_add3_u32 v151, 16, v149, v204
	ds_read_b128 v[0:3], v152 offset:36864
	ds_read_b128 v[4:7], v152 offset:41472
	ds_read_b128 v[8:11], v151
	ds_read_b128 v[12:15], v151 offset:4608
	v_lshl_add_u64 v[140:141], v[136:137], 0, s[34:35]
	v_lshl_add_u64 v[142:143], v[138:139], 0, s[34:35]
	v_lshl_add_u64 v[132:133], v[136:137], 0, s[42:43]
	v_lshl_add_u64 v[134:135], v[138:139], 0, s[42:43]
	s_setprio 1
	s_waitcnt lgkmcnt(1)
	v_mfma_f32_32x32x16_bf16 v[112:127], v[0:3], v[8:11], 0
	v_mfma_f32_32x32x16_bf16 v[48:63], v[4:7], v[8:11], 0
	s_waitcnt lgkmcnt(0)
	v_mfma_f32_32x32x16_bf16 v[96:111], v[0:3], v[12:15], 0
	v_mfma_f32_32x32x16_bf16 v[32:47], v[4:7], v[12:15], 0
	ds_read_b128 v[8:11], v151 offset:9216
	ds_read_b128 v[12:15], v151 offset:13824
	s_waitcnt lgkmcnt(1)
	v_mfma_f32_32x32x16_bf16 v[80:95], v[0:3], v[8:11], 0
	v_mfma_f32_32x32x16_bf16 v[16:31], v[4:7], v[8:11], 0
	s_waitcnt lgkmcnt(0)
	v_mfma_f32_32x32x16_bf16 v[64:79], v[0:3], v[12:15], 0
	v_mfma_f32_32x32x16_bf16 v[0:15], v[4:7], v[12:15], 0
	s_setprio 0
	global_load_dwordx4 v[194:197], v[140:141], off offset:256
	global_load_dwordx4 v[198:201], v[142:143], off offset:256
	v_add_u32_e32 v158, 0x14400, v148
	v_add_u32_e32 v157, 0x1d400, v148
	ds_write_b128 v158, v[176:179]
	s_waitcnt vmcnt(6)
	ds_write_b128 v157, v[180:183]
	ds_read_b128 v[144:147], v152 offset:36896
	ds_read_b128 v[176:179], v152 offset:41504
	ds_read_b128 v[180:183], v151 offset:32
	ds_read_b128 v[208:211], v151 offset:4640
	s_setprio 1
	s_waitcnt lgkmcnt(1)
	v_mfma_f32_32x32x16_bf16 v[112:127], v[144:147], v[180:183], v[112:127]
	v_mfma_f32_32x32x16_bf16 v[48:63], v[176:179], v[180:183], v[48:63]
	s_waitcnt lgkmcnt(0)
	v_mfma_f32_32x32x16_bf16 v[96:111], v[144:147], v[208:211], v[96:111]
	v_mfma_f32_32x32x16_bf16 v[32:47], v[176:179], v[208:211], v[32:47]
	ds_read_b128 v[180:183], v151 offset:9248
	ds_read_b128 v[208:211], v151 offset:13856
	s_waitcnt lgkmcnt(1)
	v_mfma_f32_32x32x16_bf16 v[80:95], v[144:147], v[180:183], v[80:95]
	v_mfma_f32_32x32x16_bf16 v[16:31], v[176:179], v[180:183], v[16:31]
	s_waitcnt lgkmcnt(0)
	v_mfma_f32_32x32x16_bf16 v[64:79], v[144:147], v[208:211], v[64:79]
	v_mfma_f32_32x32x16_bf16 v[0:15], v[176:179], v[208:211], v[0:15]
	s_setprio 0
	global_load_dwordx4 v[176:179], v[132:133], off offset:256
	global_load_dwordx4 v[180:183], v[134:135], off offset:256
	v_add_u32_e32 v154, 0x16800, v148
	v_add_u32_e32 v153, 0x1f800, v148
	ds_write_b128 v154, v[168:171]
	s_waitcnt vmcnt(7)
	ds_write_b128 v153, v[172:175]
	ds_read_b128 v[144:147], v152 offset:36928
	ds_read_b128 v[168:171], v152 offset:41536
	ds_read_b128 v[172:175], v151 offset:64
	ds_read_b128 v[208:211], v151 offset:4672
	s_setprio 1
	s_waitcnt lgkmcnt(1)
	v_mfma_f32_32x32x16_bf16 v[112:127], v[144:147], v[172:175], v[112:127]
	v_mfma_f32_32x32x16_bf16 v[48:63], v[168:171], v[172:175], v[48:63]
	s_waitcnt lgkmcnt(0)
	v_mfma_f32_32x32x16_bf16 v[96:111], v[144:147], v[208:211], v[96:111]
	v_mfma_f32_32x32x16_bf16 v[32:47], v[168:171], v[208:211], v[32:47]
	ds_read_b128 v[172:175], v151 offset:9280
	ds_read_b128 v[208:211], v151 offset:13888
	s_waitcnt lgkmcnt(1)
	v_mfma_f32_32x32x16_bf16 v[80:95], v[144:147], v[172:175], v[80:95]
	v_mfma_f32_32x32x16_bf16 v[16:31], v[168:171], v[172:175], v[16:31]
	s_waitcnt lgkmcnt(0)
	v_mfma_f32_32x32x16_bf16 v[64:79], v[144:147], v[208:211], v[64:79]
	v_mfma_f32_32x32x16_bf16 v[0:15], v[168:171], v[208:211], v[0:15]
	s_setprio 0
	v_add_co_u32_e32 v144, vcc, s44, v136
	v_add_u32_e32 v156, 0x18c00, v148
	s_nop 0
	v_addc_co_u32_e32 v145, vcc, 0, v137, vcc
	v_add_co_u32_e32 v146, vcc, s44, v138
	v_add_u32_e32 v155, 0x21c00, v148
	s_nop 0
	v_addc_co_u32_e32 v147, vcc, 0, v139, vcc
	global_load_dwordx4 v[168:171], v[144:145], off offset:256
	global_load_dwordx4 v[172:175], v[146:147], off offset:256
	ds_write_b128 v156, v[160:163]
	s_waitcnt vmcnt(8)
	ds_write_b128 v155, v[164:167]
	ds_read_b128 v[160:163], v152 offset:36960
	ds_read_b128 v[164:167], v152 offset:41568
	ds_read_b128 v[208:211], v151 offset:96
	ds_read_b128 v[212:215], v151 offset:4704
	s_setprio 1
	s_waitcnt lgkmcnt(1)
	v_mfma_f32_32x32x16_bf16 v[112:127], v[160:163], v[208:211], v[112:127]
	v_mfma_f32_32x32x16_bf16 v[48:63], v[164:167], v[208:211], v[48:63]
	s_waitcnt lgkmcnt(0)
	v_mfma_f32_32x32x16_bf16 v[96:111], v[160:163], v[212:215], v[96:111]
	v_mfma_f32_32x32x16_bf16 v[32:47], v[164:167], v[212:215], v[32:47]
	ds_read_b128 v[208:211], v151 offset:9312
	ds_read_b128 v[212:215], v151 offset:13920
	s_waitcnt lgkmcnt(1)
	v_mfma_f32_32x32x16_bf16 v[80:95], v[160:163], v[208:211], v[80:95]
	v_mfma_f32_32x32x16_bf16 v[16:31], v[164:167], v[208:211], v[16:31]
	s_waitcnt lgkmcnt(0)
	v_mfma_f32_32x32x16_bf16 v[64:79], v[160:163], v[212:215], v[64:79]
	v_mfma_f32_32x32x16_bf16 v[0:15], v[164:167], v[212:215], v[0:15]
	s_setprio 0
	s_barrier
; template <bool trans>
; DI void gemm_core(const GTile& tl, const GTile& nx, bool has_next  , bool chain  , bool pre, u32x4 (&ra)[4], u32x4 (&rb)[4], char* smem, f32x16 (&acc)[2][4]) {
;     ...
;   const int nk = K / 64;
;   if (!pre) { G_LOAD(0); G_STORE(0); G_LOAD(1); }
;   for (int kt = 0; kt < nk; ++kt) {
;     __syncthreads();
;     G_COMPUTE(kt & 1, kt);
;   }
	global_load_dwordx4 v[160:163], v[136:137], off offset:384
	global_load_dwordx4 v[164:167], v[138:139], off offset:384
	s_add_i32 s0, 16, 0x12000
	v_add3_u32 v149, s0, v149, v204
	s_add_i32 s0, 16, 0x1b000
	v_add3_u32 v150, s0, v150, v204
	s_waitcnt vmcnt(9)
	ds_write_b128 v148, v[184:187]
	s_waitcnt vmcnt(8)
	ds_write_b128 v148, v[188:191] offset:36864
	ds_read_b128 v[184:187], v150
	ds_read_b128 v[188:191], v150 offset:4608
	ds_read_b128 v[208:211], v149
	ds_read_b128 v[212:215], v149 offset:4608
	s_setprio 1
	s_waitcnt lgkmcnt(1)
	v_mfma_f32_32x32x16_bf16 v[112:127], v[184:187], v[208:211], v[112:127]
	v_mfma_f32_32x32x16_bf16 v[48:63], v[188:191], v[208:211], v[48:63]
	s_waitcnt lgkmcnt(0)
	v_mfma_f32_32x32x16_bf16 v[96:111], v[184:187], v[212:215], v[96:111]
	v_mfma_f32_32x32x16_bf16 v[32:47], v[188:191], v[212:215], v[32:47]
	ds_read_b128 v[208:211], v149 offset:9216
	ds_read_b128 v[212:215], v149 offset:13824
	s_waitcnt lgkmcnt(1)
	v_mfma_f32_32x32x16_bf16 v[80:95], v[184:187], v[208:211], v[80:95]
	v_mfma_f32_32x32x16_bf16 v[16:31], v[188:191], v[208:211], v[16:31]
	s_waitcnt lgkmcnt(0)
	v_mfma_f32_32x32x16_bf16 v[64:79], v[184:187], v[212:215], v[64:79]
	v_mfma_f32_32x32x16_bf16 v[0:15], v[188:191], v[212:215], v[0:15]
	s_setprio 0
	global_load_dwordx4 v[184:187], v[140:141], off offset:384
	global_load_dwordx4 v[188:191], v[142:143], off offset:384
	s_waitcnt vmcnt(9)
	ds_write_b128 v148, v[194:197] offset:9216
	s_waitcnt vmcnt(8)
	ds_write_b128 v148, v[198:201] offset:46080
	ds_read_b128 v[194:197], v150 offset:32
	ds_read_b128 v[198:201], v150 offset:4640
	ds_read_b128 v[208:211], v149 offset:32
	ds_read_b128 v[212:215], v149 offset:4640
	s_setprio 1
	s_waitcnt lgkmcnt(1)
	v_mfma_f32_32x32x16_bf16 v[112:127], v[194:197], v[208:211], v[112:127]
	v_mfma_f32_32x32x16_bf16 v[48:63], v[198:201], v[208:211], v[48:63]
	s_waitcnt lgkmcnt(0)
	v_mfma_f32_32x32x16_bf16 v[96:111], v[194:197], v[212:215], v[96:111]
	v_mfma_f32_32x32x16_bf16 v[32:47], v[198:201], v[212:215], v[32:47]
	ds_read_b128 v[208:211], v149 offset:9248
	ds_read_b128 v[212:215], v149 offset:13856
	s_waitcnt lgkmcnt(1)
	v_mfma_f32_32x32x16_bf16 v[80:95], v[194:197], v[208:211], v[80:95]
	v_mfma_f32_32x32x16_bf16 v[16:31], v[198:201], v[208:211], v[16:31]
	s_waitcnt lgkmcnt(0)
	v_mfma_f32_32x32x16_bf16 v[64:79], v[194:197], v[212:215], v[64:79]
	v_mfma_f32_32x32x16_bf16 v[0:15], v[198:201], v[212:215], v[0:15]
	s_setprio 0
	global_load_dwordx4 v[194:197], v[132:133], off offset:384
	global_load_dwordx4 v[198:201], v[134:135], off offset:384
	s_waitcnt vmcnt(9)
	ds_write_b128 v148, v[176:179] offset:18432
	s_waitcnt vmcnt(8)
	ds_write_b128 v148, v[180:183] offset:55296
	ds_read_b128 v[176:179], v150 offset:64
	ds_read_b128 v[180:183], v150 offset:4672
	ds_read_b128 v[208:211], v149 offset:64
	ds_read_b128 v[212:215], v149 offset:4672
	s_setprio 1
	s_waitcnt lgkmcnt(1)
	v_mfma_f32_32x32x16_bf16 v[112:127], v[176:179], v[208:211], v[112:127]
	v_mfma_f32_32x32x16_bf16 v[48:63], v[180:183], v[208:211], v[48:63]
	s_waitcnt lgkmcnt(0)
	v_mfma_f32_32x32x16_bf16 v[96:111], v[176:179], v[212:215], v[96:111]
	v_mfma_f32_32x32x16_bf16 v[32:47], v[180:183], v[212:215], v[32:47]
	ds_read_b128 v[208:211], v149 offset:9280
	ds_read_b128 v[212:215], v149 offset:13888
	s_waitcnt lgkmcnt(1)
	v_mfma_f32_32x32x16_bf16 v[80:95], v[176:179], v[208:211], v[80:95]
	v_mfma_f32_32x32x16_bf16 v[16:31], v[180:183], v[208:211], v[16:31]
	s_waitcnt lgkmcnt(0)
	v_mfma_f32_32x32x16_bf16 v[64:79], v[176:179], v[212:215], v[64:79]
	v_mfma_f32_32x32x16_bf16 v[0:15], v[180:183], v[212:215], v[0:15]
	s_setprio 0
	global_load_dwordx4 v[176:179], v[144:145], off offset:384
	global_load_dwordx4 v[180:183], v[146:147], off offset:384
	s_waitcnt vmcnt(9)
	ds_write_b128 v148, v[168:171] offset:27648
	s_waitcnt vmcnt(8)
	ds_write_b128 v148, v[172:175] offset:64512
	ds_read_b128 v[168:171], v150 offset:96
	ds_read_b128 v[172:175], v150 offset:4704
	ds_read_b128 v[208:211], v149 offset:96
	ds_read_b128 v[212:215], v149 offset:4704
	s_setprio 1
	s_waitcnt lgkmcnt(1)
	v_mfma_f32_32x32x16_bf16 v[112:127], v[168:171], v[208:211], v[112:127]
	v_mfma_f32_32x32x16_bf16 v[48:63], v[172:175], v[208:211], v[48:63]
	s_waitcnt lgkmcnt(0)
	v_mfma_f32_32x32x16_bf16 v[96:111], v[168:171], v[212:215], v[96:111]
	v_mfma_f32_32x32x16_bf16 v[32:47], v[172:175], v[212:215], v[32:47]
	ds_read_b128 v[208:211], v149 offset:9312
	ds_read_b128 v[212:215], v149 offset:13920
	s_waitcnt lgkmcnt(1)
	v_mfma_f32_32x32x16_bf16 v[80:95], v[168:171], v[208:211], v[80:95]
	v_mfma_f32_32x32x16_bf16 v[16:31], v[172:175], v[208:211], v[16:31]
	s_waitcnt lgkmcnt(0)
	v_mfma_f32_32x32x16_bf16 v[64:79], v[168:171], v[212:215], v[64:79]
	v_mfma_f32_32x32x16_bf16 v[0:15], v[172:175], v[212:215], v[0:15]
	s_setprio 0
	s_barrier
; template <bool trans>
; DI void gemm_core(const GTile& tl, const GTile& nx, bool has_next  , bool chain  , bool pre, u32x4 (&ra)[4], u32x4 (&rb)[4], char* smem, f32x16 (&acc)[2][4]) {
;     ...
;   const int nk = K / 64;
;   if (!pre) { G_LOAD(0); G_STORE(0); G_LOAD(1); }
;   for (int kt = 0; kt < nk; ++kt) {
;     __syncthreads();
;     G_COMPUTE(kt & 1, kt);
;   }
	global_load_dwordx4 v[168:171], v[136:137], off offset:512
	global_load_dwordx4 v[172:175], v[138:139], off offset:512
	s_waitcnt vmcnt(9)
	ds_write_b128 v192, v[160:163]
	s_waitcnt vmcnt(8)
	ds_write_b128 v159, v[164:167]
	ds_read_b128 v[160:163], v152 offset:36864
	ds_read_b128 v[164:167], v152 offset:41472
	ds_read_b128 v[208:211], v151
	ds_read_b128 v[212:215], v151 offset:4608
	s_setprio 1
	s_waitcnt lgkmcnt(1)
	v_mfma_f32_32x32x16_bf16 v[112:127], v[160:163], v[208:211], v[112:127]
	v_mfma_f32_32x32x16_bf16 v[48:63], v[164:167], v[208:211], v[48:63]
	s_waitcnt lgkmcnt(0)
	v_mfma_f32_32x32x16_bf16 v[96:111], v[160:163], v[212:215], v[96:111]
	v_mfma_f32_32x32x16_bf16 v[32:47], v[164:167], v[212:215], v[32:47]
	ds_read_b128 v[208:211], v151 offset:9216
	ds_read_b128 v[212:215], v151 offset:13824
	s_waitcnt vmcnt(7)
	ds_write_b128 v158, v[184:187]
	s_waitcnt vmcnt(6)
	ds_write_b128 v157, v[188:191]
	ds_read_b128 v[184:187], v152 offset:36896
	ds_read_b128 v[188:191], v152 offset:41504
	s_waitcnt lgkmcnt(5)
	v_mfma_f32_32x32x16_bf16 v[80:95], v[160:163], v[208:211], v[80:95]
	v_mfma_f32_32x32x16_bf16 v[16:31], v[164:167], v[208:211], v[16:31]
	ds_read_b128 v[208:211], v151 offset:32
	s_waitcnt lgkmcnt(5)
	v_mfma_f32_32x32x16_bf16 v[64:79], v[160:163], v[212:215], v[64:79]
	v_mfma_f32_32x32x16_bf16 v[0:15], v[164:167], v[212:215], v[0:15]
	ds_read_b128 v[212:215], v151 offset:4640
	s_setprio 0
	global_load_dwordx4 v[160:163], v[140:141], off offset:512
	global_load_dwordx4 v[164:167], v[142:143], off offset:512
	s_setprio 1
	s_waitcnt lgkmcnt(1)
	v_mfma_f32_32x32x16_bf16 v[112:127], v[184:187], v[208:211], v[112:127]
	v_mfma_f32_32x32x16_bf16 v[48:63], v[188:191], v[208:211], v[48:63]
	s_waitcnt lgkmcnt(0)
	v_mfma_f32_32x32x16_bf16 v[96:111], v[184:187], v[212:215], v[96:111]
	v_mfma_f32_32x32x16_bf16 v[32:47], v[188:191], v[212:215], v[32:47]
	ds_read_b128 v[208:211], v151 offset:9248
	ds_read_b128 v[212:215], v151 offset:13856
	s_waitcnt vmcnt(7)
	ds_write_b128 v154, v[194:197]
	s_waitcnt vmcnt(6)
	ds_write_b128 v153, v[198:201]
	ds_read_b128 v[194:197], v152 offset:36928
	ds_read_b128 v[198:201], v152 offset:41536
	s_waitcnt lgkmcnt(5)
	v_mfma_f32_32x32x16_bf16 v[80:95], v[184:187], v[208:211], v[80:95]
	v_mfma_f32_32x32x16_bf16 v[16:31], v[188:191], v[208:211], v[16:31]
	ds_read_b128 v[208:211], v151 offset:64
	s_waitcnt lgkmcnt(5)
	v_mfma_f32_32x32x16_bf16 v[64:79], v[184:187], v[212:215], v[64:79]
	v_mfma_f32_32x32x16_bf16 v[0:15], v[188:191], v[212:215], v[0:15]
	ds_read_b128 v[212:215], v151 offset:4672
	s_setprio 0
	global_load_dwordx4 v[184:187], v[132:133], off offset:512
	global_load_dwordx4 v[188:191], v[134:135], off offset:512
	s_setprio 1
	s_waitcnt lgkmcnt(1)
	v_mfma_f32_32x32x16_bf16 v[112:127], v[194:197], v[208:211], v[112:127]
	v_mfma_f32_32x32x16_bf16 v[48:63], v[198:201], v[208:211], v[48:63]
	s_waitcnt lgkmcnt(0)
	v_mfma_f32_32x32x16_bf16 v[96:111], v[194:197], v[212:215], v[96:111]
	v_mfma_f32_32x32x16_bf16 v[32:47], v[198:201], v[212:215], v[32:47]
	ds_read_b128 v[208:211], v151 offset:9280
	ds_read_b128 v[212:215], v151 offset:13888
	s_waitcnt vmcnt(7)
	ds_write_b128 v156, v[176:179]
	s_waitcnt vmcnt(6)
	ds_write_b128 v155, v[180:183]
	ds_read_b128 v[176:179], v152 offset:36960
	ds_read_b128 v[180:183], v152 offset:41568
	s_waitcnt lgkmcnt(5)
	v_mfma_f32_32x32x16_bf16 v[80:95], v[194:197], v[208:211], v[80:95]
	v_mfma_f32_32x32x16_bf16 v[16:31], v[198:201], v[208:211], v[16:31]
	ds_read_b128 v[208:211], v151 offset:96
	s_waitcnt lgkmcnt(5)
	v_mfma_f32_32x32x16_bf16 v[64:79], v[194:197], v[212:215], v[64:79]
	v_mfma_f32_32x32x16_bf16 v[0:15], v[198:201], v[212:215], v[0:15]
	ds_read_b128 v[212:215], v151 offset:4704
	s_setprio 0
	global_load_dwordx4 v[194:197], v[144:145], off offset:512
	global_load_dwordx4 v[198:201], v[146:147], off offset:512
	s_setprio 1
	s_waitcnt lgkmcnt(1)
	v_mfma_f32_32x32x16_bf16 v[112:127], v[176:179], v[208:211], v[112:127]
	v_mfma_f32_32x32x16_bf16 v[48:63], v[180:183], v[208:211], v[48:63]
	s_waitcnt lgkmcnt(0)
	v_mfma_f32_32x32x16_bf16 v[96:111], v[176:179], v[212:215], v[96:111]
	v_mfma_f32_32x32x16_bf16 v[32:47], v[180:183], v[212:215], v[32:47]
	ds_read_b128 v[208:211], v151 offset:9312
	ds_read_b128 v[212:215], v151 offset:13920
	s_waitcnt lgkmcnt(1)
	v_mfma_f32_32x32x16_bf16 v[80:95], v[176:179], v[208:211], v[80:95]
	v_mfma_f32_32x32x16_bf16 v[16:31], v[180:183], v[208:211], v[16:31]
	s_waitcnt lgkmcnt(0)
	v_mfma_f32_32x32x16_bf16 v[64:79], v[176:179], v[212:215], v[64:79]
	v_mfma_f32_32x32x16_bf16 v[0:15], v[180:183], v[212:215], v[0:15]
	s_setprio 0
	s_barrier
; template <bool trans>
; DI void gemm_core(const GTile& tl, const GTile& nx, bool has_next  , bool chain  , bool pre, u32x4 (&ra)[4], u32x4 (&rb)[4], char* smem, f32x16 (&acc)[2][4]) {
;     ...
;   const int nk = K / 64;
;   if (!pre) { G_LOAD(0); G_STORE(0); G_LOAD(1); }
;   for (int kt = 0; kt < nk; ++kt) {
;     __syncthreads();
;     G_COMPUTE(kt & 1, kt);
;   }
	global_load_dwordx4 v[176:179], v[136:137], off offset:640
	global_load_dwordx4 v[180:183], v[138:139], off offset:640
	s_waitcnt vmcnt(9)
	ds_write_b128 v148, v[168:171]
	s_waitcnt vmcnt(8)
	ds_write_b128 v148, v[172:175] offset:36864
	ds_read_b128 v[168:171], v150
	ds_read_b128 v[172:175], v150 offset:4608
	ds_read_b128 v[208:211], v149
	ds_read_b128 v[212:215], v149 offset:4608
	s_setprio 1
	s_waitcnt lgkmcnt(1)
	v_mfma_f32_32x32x16_bf16 v[112:127], v[168:171], v[208:211], v[112:127]
	v_mfma_f32_32x32x16_bf16 v[48:63], v[172:175], v[208:211], v[48:63]
	s_waitcnt lgkmcnt(0)
	v_mfma_f32_32x32x16_bf16 v[96:111], v[168:171], v[212:215], v[96:111]
	v_mfma_f32_32x32x16_bf16 v[32:47], v[172:175], v[212:215], v[32:47]
	ds_read_b128 v[208:211], v149 offset:9216
	ds_read_b128 v[212:215], v149 offset:13824
	s_waitcnt vmcnt(7)
	ds_write_b128 v148, v[160:163] offset:9216
	s_waitcnt vmcnt(6)
	ds_write_b128 v148, v[164:167] offset:46080
	ds_read_b128 v[160:163], v150 offset:32
	ds_read_b128 v[164:167], v150 offset:4640
	s_waitcnt lgkmcnt(5)
	v_mfma_f32_32x32x16_bf16 v[80:95], v[168:171], v[208:211], v[80:95]
	v_mfma_f32_32x32x16_bf16 v[16:31], v[172:175], v[208:211], v[16:31]
	ds_read_b128 v[208:211], v149 offset:32
	s_waitcnt lgkmcnt(5)
	v_mfma_f32_32x32x16_bf16 v[64:79], v[168:171], v[212:215], v[64:79]
	v_mfma_f32_32x32x16_bf16 v[0:15], v[172:175], v[212:215], v[0:15]
	ds_read_b128 v[212:215], v149 offset:4640
	s_setprio 0
	global_load_dwordx4 v[168:171], v[140:141], off offset:640
	global_load_dwordx4 v[172:175], v[142:143], off offset:640
	s_setprio 1
	s_waitcnt lgkmcnt(1)
	v_mfma_f32_32x32x16_bf16 v[112:127], v[160:163], v[208:211], v[112:127]
	v_mfma_f32_32x32x16_bf16 v[48:63], v[164:167], v[208:211], v[48:63]
	s_waitcnt lgkmcnt(0)
	v_mfma_f32_32x32x16_bf16 v[96:111], v[160:163], v[212:215], v[96:111]
	v_mfma_f32_32x32x16_bf16 v[32:47], v[164:167], v[212:215], v[32:47]
	ds_read_b128 v[208:211], v149 offset:9248
	ds_read_b128 v[212:215], v149 offset:13856
	s_waitcnt vmcnt(7)
	ds_write_b128 v148, v[184:187] offset:18432
	s_waitcnt vmcnt(6)
	ds_write_b128 v148, v[188:191] offset:55296
	ds_read_b128 v[184:187], v150 offset:64
	ds_read_b128 v[188:191], v150 offset:4672
	s_waitcnt lgkmcnt(5)
	v_mfma_f32_32x32x16_bf16 v[80:95], v[160:163], v[208:211], v[80:95]
	v_mfma_f32_32x32x16_bf16 v[16:31], v[164:167], v[208:211], v[16:31]
	ds_read_b128 v[208:211], v149 offset:64
	s_waitcnt lgkmcnt(5)
	v_mfma_f32_32x32x16_bf16 v[64:79], v[160:163], v[212:215], v[64:79]
	v_mfma_f32_32x32x16_bf16 v[0:15], v[164:167], v[212:215], v[0:15]
	ds_read_b128 v[212:215], v149 offset:4672
	s_setprio 0
	global_load_dwordx4 v[160:163], v[132:133], off offset:640
	global_load_dwordx4 v[164:167], v[134:135], off offset:640
	s_setprio 1
	s_waitcnt lgkmcnt(1)
	v_mfma_f32_32x32x16_bf16 v[112:127], v[184:187], v[208:211], v[112:127]
	v_mfma_f32_32x32x16_bf16 v[48:63], v[188:191], v[208:211], v[48:63]
	s_waitcnt lgkmcnt(0)
	v_mfma_f32_32x32x16_bf16 v[96:111], v[184:187], v[212:215], v[96:111]
	v_mfma_f32_32x32x16_bf16 v[32:47], v[188:191], v[212:215], v[32:47]
	ds_read_b128 v[208:211], v149 offset:9280
	ds_read_b128 v[212:215], v149 offset:13888
	s_waitcnt vmcnt(7)
	ds_write_b128 v148, v[194:197] offset:27648
	s_waitcnt vmcnt(6)
	ds_write_b128 v148, v[198:201] offset:64512
	ds_read_b128 v[194:197], v150 offset:96
	ds_read_b128 v[198:201], v150 offset:4704
	s_waitcnt lgkmcnt(5)
	v_mfma_f32_32x32x16_bf16 v[80:95], v[184:187], v[208:211], v[80:95]
	v_mfma_f32_32x32x16_bf16 v[16:31], v[188:191], v[208:211], v[16:31]
	ds_read_b128 v[208:211], v149 offset:96
	s_waitcnt lgkmcnt(5)
	v_mfma_f32_32x32x16_bf16 v[64:79], v[184:187], v[212:215], v[64:79]
	v_mfma_f32_32x32x16_bf16 v[0:15], v[188:191], v[212:215], v[0:15]
	ds_read_b128 v[212:215], v149 offset:4704
	s_setprio 0
	global_load_dwordx4 v[184:187], v[144:145], off offset:640
	global_load_dwordx4 v[188:191], v[146:147], off offset:640
	s_setprio 1
	s_waitcnt lgkmcnt(1)
	v_mfma_f32_32x32x16_bf16 v[112:127], v[194:197], v[208:211], v[112:127]
	v_mfma_f32_32x32x16_bf16 v[48:63], v[198:201], v[208:211], v[48:63]
	s_waitcnt lgkmcnt(0)
	v_mfma_f32_32x32x16_bf16 v[96:111], v[194:197], v[212:215], v[96:111]
	v_mfma_f32_32x32x16_bf16 v[32:47], v[198:201], v[212:215], v[32:47]
	ds_read_b128 v[208:211], v149 offset:9312
	ds_read_b128 v[212:215], v149 offset:13920
	s_waitcnt lgkmcnt(1)
	v_mfma_f32_32x32x16_bf16 v[80:95], v[194:197], v[208:211], v[80:95]
	v_mfma_f32_32x32x16_bf16 v[16:31], v[198:201], v[208:211], v[16:31]
	s_waitcnt lgkmcnt(0)
	v_mfma_f32_32x32x16_bf16 v[64:79], v[194:197], v[212:215], v[64:79]
	v_mfma_f32_32x32x16_bf16 v[0:15], v[198:201], v[212:215], v[0:15]
	s_setprio 0
	s_barrier
; template <bool trans>
; DI void gemm_core(const GTile& tl, const GTile& nx, bool has_next  , bool chain  , bool pre, u32x4 (&ra)[4], u32x4 (&rb)[4], char* smem, f32x16 (&acc)[2][4]) {
;     ...
;   const int nk = K / 64;
;   if (!pre) { G_LOAD(0); G_STORE(0); G_LOAD(1); }
;   for (int kt = 0; kt < nk; ++kt) {
;     __syncthreads();
;     G_COMPUTE(kt & 1, kt);
;   }
	global_load_dwordx4 v[194:197], v[136:137], off offset:768
	global_load_dwordx4 v[198:201], v[138:139], off offset:768
	s_waitcnt vmcnt(9)
	ds_write_b128 v192, v[176:179]
	s_waitcnt vmcnt(8)
	ds_write_b128 v159, v[180:183]
	ds_read_b128 v[176:179], v152 offset:36864
	ds_read_b128 v[180:183], v152 offset:41472
	ds_read_b128 v[208:211], v151
	ds_read_b128 v[212:215], v151 offset:4608
	s_setprio 1
	s_waitcnt lgkmcnt(1)
	v_mfma_f32_32x32x16_bf16 v[112:127], v[176:179], v[208:211], v[112:127]
	v_mfma_f32_32x32x16_bf16 v[48:63], v[180:183], v[208:211], v[48:63]
	s_waitcnt lgkmcnt(0)
	v_mfma_f32_32x32x16_bf16 v[96:111], v[176:179], v[212:215], v[96:111]
	v_mfma_f32_32x32x16_bf16 v[32:47], v[180:183], v[212:215], v[32:47]
	ds_read_b128 v[208:211], v151 offset:9216
	ds_read_b128 v[212:215], v151 offset:13824
	s_waitcnt vmcnt(7)
	ds_write_b128 v158, v[168:171]
	s_waitcnt vmcnt(6)
	ds_write_b128 v157, v[172:175]
	ds_read_b128 v[168:171], v152 offset:36896
	ds_read_b128 v[172:175], v152 offset:41504
	s_waitcnt lgkmcnt(5)
	v_mfma_f32_32x32x16_bf16 v[80:95], v[176:179], v[208:211], v[80:95]
	v_mfma_f32_32x32x16_bf16 v[16:31], v[180:183], v[208:211], v[16:31]
	ds_read_b128 v[208:211], v151 offset:32
	s_waitcnt lgkmcnt(5)
	v_mfma_f32_32x32x16_bf16 v[64:79], v[176:179], v[212:215], v[64:79]
	v_mfma_f32_32x32x16_bf16 v[0:15], v[180:183], v[212:215], v[0:15]
	ds_read_b128 v[212:215], v151 offset:4640
	s_setprio 0
	global_load_dwordx4 v[176:179], v[140:141], off offset:768
	global_load_dwordx4 v[180:183], v[142:143], off offset:768
	s_setprio 1
	s_waitcnt lgkmcnt(1)
	v_mfma_f32_32x32x16_bf16 v[112:127], v[168:171], v[208:211], v[112:127]
	v_mfma_f32_32x32x16_bf16 v[48:63], v[172:175], v[208:211], v[48:63]
	s_waitcnt lgkmcnt(0)
	v_mfma_f32_32x32x16_bf16 v[96:111], v[168:171], v[212:215], v[96:111]
	v_mfma_f32_32x32x16_bf16 v[32:47], v[172:175], v[212:215], v[32:47]
	ds_read_b128 v[208:211], v151 offset:9248
	ds_read_b128 v[212:215], v151 offset:13856
	s_waitcnt vmcnt(7)
	ds_write_b128 v154, v[160:163]
	s_waitcnt vmcnt(6)
	ds_write_b128 v153, v[164:167]
	ds_read_b128 v[160:163], v152 offset:36928
	ds_read_b128 v[164:167], v152 offset:41536
	s_waitcnt lgkmcnt(5)
	v_mfma_f32_32x32x16_bf16 v[80:95], v[168:171], v[208:211], v[80:95]
	v_mfma_f32_32x32x16_bf16 v[16:31], v[172:175], v[208:211], v[16:31]
	ds_read_b128 v[208:211], v151 offset:64
	s_waitcnt lgkmcnt(5)
	v_mfma_f32_32x32x16_bf16 v[64:79], v[168:171], v[212:215], v[64:79]
	v_mfma_f32_32x32x16_bf16 v[0:15], v[172:175], v[212:215], v[0:15]
	ds_read_b128 v[212:215], v151 offset:4672
	s_setprio 0
	global_load_dwordx4 v[168:171], v[132:133], off offset:768
	global_load_dwordx4 v[172:175], v[134:135], off offset:768
	s_setprio 1
	s_waitcnt lgkmcnt(1)
	v_mfma_f32_32x32x16_bf16 v[112:127], v[160:163], v[208:211], v[112:127]
	v_mfma_f32_32x32x16_bf16 v[48:63], v[164:167], v[208:211], v[48:63]
	s_waitcnt lgkmcnt(0)
	v_mfma_f32_32x32x16_bf16 v[96:111], v[160:163], v[212:215], v[96:111]
	v_mfma_f32_32x32x16_bf16 v[32:47], v[164:167], v[212:215], v[32:47]
	ds_read_b128 v[208:211], v151 offset:9280
	ds_read_b128 v[212:215], v151 offset:13888
	s_waitcnt vmcnt(7)
	ds_write_b128 v156, v[184:187]
	s_waitcnt vmcnt(6)
	ds_write_b128 v155, v[188:191]
	ds_read_b128 v[184:187], v152 offset:36960
	ds_read_b128 v[188:191], v152 offset:41568
	s_waitcnt lgkmcnt(5)
	v_mfma_f32_32x32x16_bf16 v[80:95], v[160:163], v[208:211], v[80:95]
	v_mfma_f32_32x32x16_bf16 v[16:31], v[164:167], v[208:211], v[16:31]
	ds_read_b128 v[208:211], v151 offset:96
	s_waitcnt lgkmcnt(5)
	v_mfma_f32_32x32x16_bf16 v[64:79], v[160:163], v[212:215], v[64:79]
	v_mfma_f32_32x32x16_bf16 v[0:15], v[164:167], v[212:215], v[0:15]
	ds_read_b128 v[212:215], v151 offset:4704
	s_setprio 0
	global_load_dwordx4 v[160:163], v[144:145], off offset:768
	global_load_dwordx4 v[164:167], v[146:147], off offset:768
	s_setprio 1
	s_waitcnt lgkmcnt(1)
	v_mfma_f32_32x32x16_bf16 v[112:127], v[184:187], v[208:211], v[112:127]
	v_mfma_f32_32x32x16_bf16 v[48:63], v[188:191], v[208:211], v[48:63]
	s_waitcnt lgkmcnt(0)
	v_mfma_f32_32x32x16_bf16 v[96:111], v[184:187], v[212:215], v[96:111]
	v_mfma_f32_32x32x16_bf16 v[32:47], v[188:191], v[212:215], v[32:47]
	ds_read_b128 v[208:211], v151 offset:9312
	ds_read_b128 v[212:215], v151 offset:13920
	s_waitcnt lgkmcnt(1)
	v_mfma_f32_32x32x16_bf16 v[80:95], v[184:187], v[208:211], v[80:95]
	v_mfma_f32_32x32x16_bf16 v[16:31], v[188:191], v[208:211], v[16:31]
	s_waitcnt lgkmcnt(0)
	v_mfma_f32_32x32x16_bf16 v[64:79], v[184:187], v[212:215], v[64:79]
	v_mfma_f32_32x32x16_bf16 v[0:15], v[188:191], v[212:215], v[0:15]
	s_setprio 0
	s_barrier
; template <bool trans>
; DI void gemm_core(const GTile& tl, const GTile& nx, bool has_next  , bool chain  , bool pre, u32x4 (&ra)[4], u32x4 (&rb)[4], char* smem, f32x16 (&acc)[2][4]) {
;     ...
;   const int nk = K / 64;
;   if (!pre) { G_LOAD(0); G_STORE(0); G_LOAD(1); }
;   for (int kt = 0; kt < nk; ++kt) {
;     __syncthreads();
;     G_COMPUTE(kt & 1, kt);
;   }
	global_load_dwordx4 v[184:187], v[136:137], off offset:896
	global_load_dwordx4 v[188:191], v[138:139], off offset:896
	s_waitcnt vmcnt(9)
	ds_write_b128 v148, v[194:197]
	s_waitcnt vmcnt(8)
	ds_write_b128 v148, v[198:201] offset:36864
	ds_read_b128 v[194:197], v150
	ds_read_b128 v[198:201], v150 offset:4608
	ds_read_b128 v[208:211], v149
	ds_read_b128 v[212:215], v149 offset:4608
	s_setprio 1
	s_waitcnt lgkmcnt(1)
	v_mfma_f32_32x32x16_bf16 v[112:127], v[194:197], v[208:211], v[112:127]
	v_mfma_f32_32x32x16_bf16 v[48:63], v[198:201], v[208:211], v[48:63]
	s_waitcnt lgkmcnt(0)
	v_mfma_f32_32x32x16_bf16 v[96:111], v[194:197], v[212:215], v[96:111]
	v_mfma_f32_32x32x16_bf16 v[32:47], v[198:201], v[212:215], v[32:47]
	ds_read_b128 v[208:211], v149 offset:9216
	ds_read_b128 v[212:215], v149 offset:13824
	s_waitcnt vmcnt(7)
	ds_write_b128 v148, v[176:179] offset:9216
	s_waitcnt vmcnt(6)
	ds_write_b128 v148, v[180:183] offset:46080
	ds_read_b128 v[176:179], v150 offset:32
	ds_read_b128 v[180:183], v150 offset:4640
	s_waitcnt lgkmcnt(5)
	v_mfma_f32_32x32x16_bf16 v[80:95], v[194:197], v[208:211], v[80:95]
	v_mfma_f32_32x32x16_bf16 v[16:31], v[198:201], v[208:211], v[16:31]
	ds_read_b128 v[208:211], v149 offset:32
	s_waitcnt lgkmcnt(5)
	v_mfma_f32_32x32x16_bf16 v[64:79], v[194:197], v[212:215], v[64:79]
	v_mfma_f32_32x32x16_bf16 v[0:15], v[198:201], v[212:215], v[0:15]
	ds_read_b128 v[212:215], v149 offset:4640
	s_setprio 0
	global_load_dwordx4 v[194:197], v[140:141], off offset:896
	global_load_dwordx4 v[198:201], v[142:143], off offset:896
	s_setprio 1
	s_waitcnt lgkmcnt(1)
	v_mfma_f32_32x32x16_bf16 v[112:127], v[176:179], v[208:211], v[112:127]
	v_mfma_f32_32x32x16_bf16 v[48:63], v[180:183], v[208:211], v[48:63]
	s_waitcnt lgkmcnt(0)
	v_mfma_f32_32x32x16_bf16 v[96:111], v[176:179], v[212:215], v[96:111]
	v_mfma_f32_32x32x16_bf16 v[32:47], v[180:183], v[212:215], v[32:47]
	ds_read_b128 v[208:211], v149 offset:9248
	ds_read_b128 v[212:215], v149 offset:13856
	s_waitcnt vmcnt(7)
	ds_write_b128 v148, v[168:171] offset:18432
	s_waitcnt vmcnt(6)
	ds_write_b128 v148, v[172:175] offset:55296
	ds_read_b128 v[168:171], v150 offset:64
	ds_read_b128 v[172:175], v150 offset:4672
	s_waitcnt lgkmcnt(5)
	v_mfma_f32_32x32x16_bf16 v[80:95], v[176:179], v[208:211], v[80:95]
	v_mfma_f32_32x32x16_bf16 v[16:31], v[180:183], v[208:211], v[16:31]
	ds_read_b128 v[208:211], v149 offset:64
	s_waitcnt lgkmcnt(5)
	v_mfma_f32_32x32x16_bf16 v[64:79], v[176:179], v[212:215], v[64:79]
	v_mfma_f32_32x32x16_bf16 v[0:15], v[180:183], v[212:215], v[0:15]
	ds_read_b128 v[212:215], v149 offset:4672
	s_setprio 0
	global_load_dwordx4 v[176:179], v[132:133], off offset:896
	global_load_dwordx4 v[180:183], v[134:135], off offset:896
	s_setprio 1
	s_waitcnt lgkmcnt(1)
	v_mfma_f32_32x32x16_bf16 v[112:127], v[168:171], v[208:211], v[112:127]
	v_mfma_f32_32x32x16_bf16 v[48:63], v[172:175], v[208:211], v[48:63]
	s_waitcnt lgkmcnt(0)
	v_mfma_f32_32x32x16_bf16 v[96:111], v[168:171], v[212:215], v[96:111]
	v_mfma_f32_32x32x16_bf16 v[32:47], v[172:175], v[212:215], v[32:47]
	ds_read_b128 v[208:211], v149 offset:9280
	ds_read_b128 v[212:215], v149 offset:13888
	s_waitcnt vmcnt(7)
	ds_write_b128 v148, v[160:163] offset:27648
	s_waitcnt vmcnt(6)
	ds_write_b128 v148, v[164:167] offset:64512
	ds_read_b128 v[160:163], v150 offset:96
	ds_read_b128 v[164:167], v150 offset:4704
	s_waitcnt lgkmcnt(5)
	v_mfma_f32_32x32x16_bf16 v[80:95], v[168:171], v[208:211], v[80:95]
	v_mfma_f32_32x32x16_bf16 v[16:31], v[172:175], v[208:211], v[16:31]
	ds_read_b128 v[208:211], v149 offset:96
	s_waitcnt lgkmcnt(5)
	v_mfma_f32_32x32x16_bf16 v[64:79], v[168:171], v[212:215], v[64:79]
	v_mfma_f32_32x32x16_bf16 v[0:15], v[172:175], v[212:215], v[0:15]
	ds_read_b128 v[212:215], v149 offset:4704
	s_setprio 0
	global_load_dwordx4 v[168:171], v[144:145], off offset:896
	global_load_dwordx4 v[172:175], v[146:147], off offset:896
	s_setprio 1
	s_waitcnt lgkmcnt(1)
	v_mfma_f32_32x32x16_bf16 v[112:127], v[160:163], v[208:211], v[112:127]
	v_mfma_f32_32x32x16_bf16 v[48:63], v[164:167], v[208:211], v[48:63]
	s_waitcnt lgkmcnt(0)
	v_mfma_f32_32x32x16_bf16 v[96:111], v[160:163], v[212:215], v[96:111]
	v_mfma_f32_32x32x16_bf16 v[32:47], v[164:167], v[212:215], v[32:47]
	ds_read_b128 v[208:211], v149 offset:9312
	ds_read_b128 v[212:215], v149 offset:13920
	s_waitcnt lgkmcnt(1)
	v_mfma_f32_32x32x16_bf16 v[80:95], v[160:163], v[208:211], v[80:95]
	v_mfma_f32_32x32x16_bf16 v[16:31], v[164:167], v[208:211], v[16:31]
	s_waitcnt lgkmcnt(0)
	v_mfma_f32_32x32x16_bf16 v[64:79], v[160:163], v[212:215], v[64:79]
	v_mfma_f32_32x32x16_bf16 v[0:15], v[164:167], v[212:215], v[0:15]
	s_setprio 0
	s_barrier
; template <bool trans>
; DI void gemm_core(const GTile& tl, const GTile& nx, bool has_next  , bool chain  , bool pre, u32x4 (&ra)[4], u32x4 (&rb)[4], char* smem, f32x16 (&acc)[2][4]) {
;     ...
;   const int nk = K / 64;
;   if (!pre) { G_LOAD(0); G_STORE(0); G_LOAD(1); }
;   for (int kt = 0; kt < nk; ++kt) {
;     __syncthreads();
;     G_COMPUTE(kt & 1, kt);
;   }
	global_load_dwordx4 v[160:163], v[136:137], off offset:1024
	global_load_dwordx4 v[164:167], v[138:139], off offset:1024
	s_waitcnt vmcnt(9)
	ds_write_b128 v192, v[184:187]
	s_waitcnt vmcnt(8)
	ds_write_b128 v159, v[188:191]
	ds_read_b128 v[184:187], v152 offset:36864
	ds_read_b128 v[188:191], v152 offset:41472
	ds_read_b128 v[208:211], v151
	ds_read_b128 v[212:215], v151 offset:4608
	s_setprio 1
	s_waitcnt lgkmcnt(1)
	v_mfma_f32_32x32x16_bf16 v[112:127], v[184:187], v[208:211], v[112:127]
	v_mfma_f32_32x32x16_bf16 v[48:63], v[188:191], v[208:211], v[48:63]
	s_waitcnt lgkmcnt(0)
	v_mfma_f32_32x32x16_bf16 v[96:111], v[184:187], v[212:215], v[96:111]
	v_mfma_f32_32x32x16_bf16 v[32:47], v[188:191], v[212:215], v[32:47]
	ds_read_b128 v[208:211], v151 offset:9216
	ds_read_b128 v[212:215], v151 offset:13824
	s_waitcnt vmcnt(7)
	ds_write_b128 v158, v[194:197]
	s_waitcnt vmcnt(6)
	ds_write_b128 v157, v[198:201]
	ds_read_b128 v[194:197], v152 offset:36896
	ds_read_b128 v[198:201], v152 offset:41504
	s_waitcnt lgkmcnt(5)
	v_mfma_f32_32x32x16_bf16 v[80:95], v[184:187], v[208:211], v[80:95]
	v_mfma_f32_32x32x16_bf16 v[16:31], v[188:191], v[208:211], v[16:31]
	ds_read_b128 v[208:211], v151 offset:32
	s_waitcnt lgkmcnt(5)
	v_mfma_f32_32x32x16_bf16 v[64:79], v[184:187], v[212:215], v[64:79]
	v_mfma_f32_32x32x16_bf16 v[0:15], v[188:191], v[212:215], v[0:15]
	ds_read_b128 v[212:215], v151 offset:4640
	s_setprio 0
	global_load_dwordx4 v[184:187], v[140:141], off offset:1024
	global_load_dwordx4 v[188:191], v[142:143], off offset:1024
	s_setprio 1
	s_waitcnt lgkmcnt(1)
	v_mfma_f32_32x32x16_bf16 v[112:127], v[194:197], v[208:211], v[112:127]
	v_mfma_f32_32x32x16_bf16 v[48:63], v[198:201], v[208:211], v[48:63]
	s_waitcnt lgkmcnt(0)
	v_mfma_f32_32x32x16_bf16 v[96:111], v[194:197], v[212:215], v[96:111]
	v_mfma_f32_32x32x16_bf16 v[32:47], v[198:201], v[212:215], v[32:47]
	ds_read_b128 v[208:211], v151 offset:9248
	ds_read_b128 v[212:215], v151 offset:13856
	s_waitcnt vmcnt(7)
	ds_write_b128 v154, v[176:179]
	s_waitcnt vmcnt(6)
	ds_write_b128 v153, v[180:183]
	ds_read_b128 v[176:179], v152 offset:36928
	ds_read_b128 v[180:183], v152 offset:41536
	s_waitcnt lgkmcnt(5)
	v_mfma_f32_32x32x16_bf16 v[80:95], v[194:197], v[208:211], v[80:95]
	v_mfma_f32_32x32x16_bf16 v[16:31], v[198:201], v[208:211], v[16:31]
	ds_read_b128 v[208:211], v151 offset:64
	s_waitcnt lgkmcnt(5)
	v_mfma_f32_32x32x16_bf16 v[64:79], v[194:197], v[212:215], v[64:79]
	v_mfma_f32_32x32x16_bf16 v[0:15], v[198:201], v[212:215], v[0:15]
	ds_read_b128 v[212:215], v151 offset:4672
	s_setprio 0
	global_load_dwordx4 v[194:197], v[132:133], off offset:1024
	global_load_dwordx4 v[198:201], v[134:135], off offset:1024
	s_setprio 1
	s_waitcnt lgkmcnt(1)
	v_mfma_f32_32x32x16_bf16 v[112:127], v[176:179], v[208:211], v[112:127]
	v_mfma_f32_32x32x16_bf16 v[48:63], v[180:183], v[208:211], v[48:63]
	s_waitcnt lgkmcnt(0)
	v_mfma_f32_32x32x16_bf16 v[96:111], v[176:179], v[212:215], v[96:111]
	v_mfma_f32_32x32x16_bf16 v[32:47], v[180:183], v[212:215], v[32:47]
	ds_read_b128 v[208:211], v151 offset:9280
	ds_read_b128 v[212:215], v151 offset:13888
	s_waitcnt vmcnt(7)
	ds_write_b128 v156, v[168:171]
	s_waitcnt vmcnt(6)
	ds_write_b128 v155, v[172:175]
	ds_read_b128 v[168:171], v152 offset:36960
	ds_read_b128 v[172:175], v152 offset:41568
	s_waitcnt lgkmcnt(5)
	v_mfma_f32_32x32x16_bf16 v[80:95], v[176:179], v[208:211], v[80:95]
	v_mfma_f32_32x32x16_bf16 v[16:31], v[180:183], v[208:211], v[16:31]
	ds_read_b128 v[208:211], v151 offset:96
	s_waitcnt lgkmcnt(5)
	v_mfma_f32_32x32x16_bf16 v[64:79], v[176:179], v[212:215], v[64:79]
	v_mfma_f32_32x32x16_bf16 v[0:15], v[180:183], v[212:215], v[0:15]
	ds_read_b128 v[212:215], v151 offset:4704
	s_setprio 0
	global_load_dwordx4 v[176:179], v[144:145], off offset:1024
	global_load_dwordx4 v[180:183], v[146:147], off offset:1024
	s_setprio 1
	s_waitcnt lgkmcnt(1)
	v_mfma_f32_32x32x16_bf16 v[112:127], v[168:171], v[208:211], v[112:127]
	v_mfma_f32_32x32x16_bf16 v[48:63], v[172:175], v[208:211], v[48:63]
	s_waitcnt lgkmcnt(0)
	v_mfma_f32_32x32x16_bf16 v[96:111], v[168:171], v[212:215], v[96:111]
	v_mfma_f32_32x32x16_bf16 v[32:47], v[172:175], v[212:215], v[32:47]
	ds_read_b128 v[208:211], v151 offset:9312
	ds_read_b128 v[212:215], v151 offset:13920
	s_waitcnt lgkmcnt(1)
	v_mfma_f32_32x32x16_bf16 v[80:95], v[168:171], v[208:211], v[80:95]
	v_mfma_f32_32x32x16_bf16 v[16:31], v[172:175], v[208:211], v[16:31]
	s_waitcnt lgkmcnt(0)
	v_mfma_f32_32x32x16_bf16 v[64:79], v[168:171], v[212:215], v[64:79]
	v_mfma_f32_32x32x16_bf16 v[0:15], v[172:175], v[212:215], v[0:15]
	s_setprio 0
	s_barrier
; template <bool trans>
; DI void gemm_core(const GTile& tl, const GTile& nx, bool has_next  , bool chain  , bool pre, u32x4 (&ra)[4], u32x4 (&rb)[4], char* smem, f32x16 (&acc)[2][4]) {
;     ...
;   const int nk = K / 64;
;   if (!pre) { G_LOAD(0); G_STORE(0); G_LOAD(1); }
;   for (int kt = 0; kt < nk; ++kt) {
;     __syncthreads();
;     G_COMPUTE(kt & 1, kt);
;   }
	global_load_dwordx4 v[168:171], v[136:137], off offset:1152
	global_load_dwordx4 v[172:175], v[138:139], off offset:1152
	s_waitcnt vmcnt(9)
	ds_write_b128 v148, v[160:163]
	s_waitcnt vmcnt(8)
	ds_write_b128 v148, v[164:167] offset:36864
	ds_read_b128 v[160:163], v150
	ds_read_b128 v[164:167], v150 offset:4608
	ds_read_b128 v[208:211], v149
	ds_read_b128 v[212:215], v149 offset:4608
	s_setprio 1
	s_waitcnt lgkmcnt(1)
	v_mfma_f32_32x32x16_bf16 v[112:127], v[160:163], v[208:211], v[112:127]
	v_mfma_f32_32x32x16_bf16 v[48:63], v[164:167], v[208:211], v[48:63]
	s_waitcnt lgkmcnt(0)
	v_mfma_f32_32x32x16_bf16 v[96:111], v[160:163], v[212:215], v[96:111]
	v_mfma_f32_32x32x16_bf16 v[32:47], v[164:167], v[212:215], v[32:47]
	ds_read_b128 v[208:211], v149 offset:9216
	ds_read_b128 v[212:215], v149 offset:13824
	s_waitcnt vmcnt(7)
	ds_write_b128 v148, v[184:187] offset:9216
	s_waitcnt vmcnt(6)
	ds_write_b128 v148, v[188:191] offset:46080
	ds_read_b128 v[184:187], v150 offset:32
	ds_read_b128 v[188:191], v150 offset:4640
	s_waitcnt lgkmcnt(5)
	v_mfma_f32_32x32x16_bf16 v[80:95], v[160:163], v[208:211], v[80:95]
	v_mfma_f32_32x32x16_bf16 v[16:31], v[164:167], v[208:211], v[16:31]
	ds_read_b128 v[208:211], v149 offset:32
	s_waitcnt lgkmcnt(5)
	v_mfma_f32_32x32x16_bf16 v[64:79], v[160:163], v[212:215], v[64:79]
	v_mfma_f32_32x32x16_bf16 v[0:15], v[164:167], v[212:215], v[0:15]
	ds_read_b128 v[212:215], v149 offset:4640
	s_setprio 0
	global_load_dwordx4 v[160:163], v[140:141], off offset:1152
	global_load_dwordx4 v[164:167], v[142:143], off offset:1152
	s_setprio 1
	s_waitcnt lgkmcnt(1)
	v_mfma_f32_32x32x16_bf16 v[112:127], v[184:187], v[208:211], v[112:127]
	v_mfma_f32_32x32x16_bf16 v[48:63], v[188:191], v[208:211], v[48:63]
	s_waitcnt lgkmcnt(0)
	v_mfma_f32_32x32x16_bf16 v[96:111], v[184:187], v[212:215], v[96:111]
	v_mfma_f32_32x32x16_bf16 v[32:47], v[188:191], v[212:215], v[32:47]
	ds_read_b128 v[208:211], v149 offset:9248
	ds_read_b128 v[212:215], v149 offset:13856
	s_waitcnt vmcnt(7)
	ds_write_b128 v148, v[194:197] offset:18432
	s_waitcnt vmcnt(6)
	ds_write_b128 v148, v[198:201] offset:55296
	ds_read_b128 v[194:197], v150 offset:64
	ds_read_b128 v[198:201], v150 offset:4672
	s_waitcnt lgkmcnt(5)
	v_mfma_f32_32x32x16_bf16 v[80:95], v[184:187], v[208:211], v[80:95]
	v_mfma_f32_32x32x16_bf16 v[16:31], v[188:191], v[208:211], v[16:31]
	ds_read_b128 v[208:211], v149 offset:64
	s_waitcnt lgkmcnt(5)
	v_mfma_f32_32x32x16_bf16 v[64:79], v[184:187], v[212:215], v[64:79]
	v_mfma_f32_32x32x16_bf16 v[0:15], v[188:191], v[212:215], v[0:15]
	ds_read_b128 v[212:215], v149 offset:4672
	s_setprio 0
	global_load_dwordx4 v[184:187], v[132:133], off offset:1152
	global_load_dwordx4 v[188:191], v[134:135], off offset:1152
	s_setprio 1
	s_waitcnt lgkmcnt(1)
	v_mfma_f32_32x32x16_bf16 v[112:127], v[194:197], v[208:211], v[112:127]
	v_mfma_f32_32x32x16_bf16 v[48:63], v[198:201], v[208:211], v[48:63]
	s_waitcnt lgkmcnt(0)
	v_mfma_f32_32x32x16_bf16 v[96:111], v[194:197], v[212:215], v[96:111]
	v_mfma_f32_32x32x16_bf16 v[32:47], v[198:201], v[212:215], v[32:47]
	ds_read_b128 v[208:211], v149 offset:9280
	ds_read_b128 v[212:215], v149 offset:13888
	s_waitcnt vmcnt(7)
	ds_write_b128 v148, v[176:179] offset:27648
	s_waitcnt vmcnt(6)
	ds_write_b128 v148, v[180:183] offset:64512
	ds_read_b128 v[176:179], v150 offset:96
	ds_read_b128 v[180:183], v150 offset:4704
	s_waitcnt lgkmcnt(5)
	v_mfma_f32_32x32x16_bf16 v[80:95], v[194:197], v[208:211], v[80:95]
	v_mfma_f32_32x32x16_bf16 v[16:31], v[198:201], v[208:211], v[16:31]
	ds_read_b128 v[208:211], v149 offset:96
	s_waitcnt lgkmcnt(5)
	v_mfma_f32_32x32x16_bf16 v[64:79], v[194:197], v[212:215], v[64:79]
	v_mfma_f32_32x32x16_bf16 v[0:15], v[198:201], v[212:215], v[0:15]
	ds_read_b128 v[212:215], v149 offset:4704
	s_setprio 0
	global_load_dwordx4 v[194:197], v[144:145], off offset:1152
	global_load_dwordx4 v[198:201], v[146:147], off offset:1152
	s_setprio 1
	s_waitcnt lgkmcnt(1)
	v_mfma_f32_32x32x16_bf16 v[112:127], v[176:179], v[208:211], v[112:127]
	v_mfma_f32_32x32x16_bf16 v[48:63], v[180:183], v[208:211], v[48:63]
	s_waitcnt lgkmcnt(0)
	v_mfma_f32_32x32x16_bf16 v[96:111], v[176:179], v[212:215], v[96:111]
	v_mfma_f32_32x32x16_bf16 v[32:47], v[180:183], v[212:215], v[32:47]
	ds_read_b128 v[208:211], v149 offset:9312
	ds_read_b128 v[212:215], v149 offset:13920
	s_waitcnt lgkmcnt(1)
	v_mfma_f32_32x32x16_bf16 v[80:95], v[176:179], v[208:211], v[80:95]
	v_mfma_f32_32x32x16_bf16 v[16:31], v[180:183], v[208:211], v[16:31]
	s_waitcnt lgkmcnt(0)
	v_mfma_f32_32x32x16_bf16 v[64:79], v[176:179], v[212:215], v[64:79]
	v_mfma_f32_32x32x16_bf16 v[0:15], v[180:183], v[212:215], v[0:15]
	s_setprio 0
	s_barrier
; template <bool trans>
; DI void gemm_core(const GTile& tl, const GTile& nx, bool has_next  , bool chain  , bool pre, u32x4 (&ra)[4], u32x4 (&rb)[4], char* smem, f32x16 (&acc)[2][4]) {
;     ...
;   const int nk = K / 64;
;   if (!pre) { G_LOAD(0); G_STORE(0); G_LOAD(1); }
;   for (int kt = 0; kt < nk; ++kt) {
;     __syncthreads();
;     G_COMPUTE(kt & 1, kt);
;   }
	global_load_dwordx4 v[176:179], v[136:137], off offset:1280
	global_load_dwordx4 v[180:183], v[138:139], off offset:1280
	s_waitcnt vmcnt(9)
	ds_write_b128 v192, v[168:171]
	s_waitcnt vmcnt(8)
	ds_write_b128 v159, v[172:175]
	ds_read_b128 v[168:171], v152 offset:36864
	ds_read_b128 v[172:175], v152 offset:41472
	ds_read_b128 v[208:211], v151
	ds_read_b128 v[212:215], v151 offset:4608
	s_setprio 1
	s_waitcnt lgkmcnt(1)
	v_mfma_f32_32x32x16_bf16 v[112:127], v[168:171], v[208:211], v[112:127]
	v_mfma_f32_32x32x16_bf16 v[48:63], v[172:175], v[208:211], v[48:63]
	s_waitcnt lgkmcnt(0)
	v_mfma_f32_32x32x16_bf16 v[96:111], v[168:171], v[212:215], v[96:111]
	v_mfma_f32_32x32x16_bf16 v[32:47], v[172:175], v[212:215], v[32:47]
	ds_read_b128 v[208:211], v151 offset:9216
	ds_read_b128 v[212:215], v151 offset:13824
	s_waitcnt vmcnt(7)
	ds_write_b128 v158, v[160:163]
	s_waitcnt vmcnt(6)
	ds_write_b128 v157, v[164:167]
	ds_read_b128 v[160:163], v152 offset:36896
	ds_read_b128 v[164:167], v152 offset:41504
	s_waitcnt lgkmcnt(5)
	v_mfma_f32_32x32x16_bf16 v[80:95], v[168:171], v[208:211], v[80:95]
	v_mfma_f32_32x32x16_bf16 v[16:31], v[172:175], v[208:211], v[16:31]
	ds_read_b128 v[208:211], v151 offset:32
	s_waitcnt lgkmcnt(5)
	v_mfma_f32_32x32x16_bf16 v[64:79], v[168:171], v[212:215], v[64:79]
	v_mfma_f32_32x32x16_bf16 v[0:15], v[172:175], v[212:215], v[0:15]
	ds_read_b128 v[212:215], v151 offset:4640
	s_setprio 0
	global_load_dwordx4 v[168:171], v[140:141], off offset:1280
	global_load_dwordx4 v[172:175], v[142:143], off offset:1280
	s_setprio 1
	s_waitcnt lgkmcnt(1)
	v_mfma_f32_32x32x16_bf16 v[112:127], v[160:163], v[208:211], v[112:127]
	v_mfma_f32_32x32x16_bf16 v[48:63], v[164:167], v[208:211], v[48:63]
	s_waitcnt lgkmcnt(0)
	v_mfma_f32_32x32x16_bf16 v[96:111], v[160:163], v[212:215], v[96:111]
	v_mfma_f32_32x32x16_bf16 v[32:47], v[164:167], v[212:215], v[32:47]
	ds_read_b128 v[208:211], v151 offset:9248
	ds_read_b128 v[212:215], v151 offset:13856
	s_waitcnt vmcnt(7)
	ds_write_b128 v154, v[184:187]
	s_waitcnt vmcnt(6)
	ds_write_b128 v153, v[188:191]
	ds_read_b128 v[184:187], v152 offset:36928
	ds_read_b128 v[188:191], v152 offset:41536
	s_waitcnt lgkmcnt(5)
	v_mfma_f32_32x32x16_bf16 v[80:95], v[160:163], v[208:211], v[80:95]
	v_mfma_f32_32x32x16_bf16 v[16:31], v[164:167], v[208:211], v[16:31]
	ds_read_b128 v[208:211], v151 offset:64
	s_waitcnt lgkmcnt(5)
	v_mfma_f32_32x32x16_bf16 v[64:79], v[160:163], v[212:215], v[64:79]
	v_mfma_f32_32x32x16_bf16 v[0:15], v[164:167], v[212:215], v[0:15]
	ds_read_b128 v[212:215], v151 offset:4672
	s_setprio 0
	global_load_dwordx4 v[160:163], v[132:133], off offset:1280
	global_load_dwordx4 v[164:167], v[134:135], off offset:1280
	s_setprio 1
	s_waitcnt lgkmcnt(1)
	v_mfma_f32_32x32x16_bf16 v[112:127], v[184:187], v[208:211], v[112:127]
	v_mfma_f32_32x32x16_bf16 v[48:63], v[188:191], v[208:211], v[48:63]
	s_waitcnt lgkmcnt(0)
	v_mfma_f32_32x32x16_bf16 v[96:111], v[184:187], v[212:215], v[96:111]
	v_mfma_f32_32x32x16_bf16 v[32:47], v[188:191], v[212:215], v[32:47]
	ds_read_b128 v[208:211], v151 offset:9280
	ds_read_b128 v[212:215], v151 offset:13888
	s_waitcnt vmcnt(7)
	ds_write_b128 v156, v[194:197]
	s_waitcnt vmcnt(6)
	ds_write_b128 v155, v[198:201]
	ds_read_b128 v[194:197], v152 offset:36960
	ds_read_b128 v[198:201], v152 offset:41568
	s_waitcnt lgkmcnt(5)
	v_mfma_f32_32x32x16_bf16 v[80:95], v[184:187], v[208:211], v[80:95]
	v_mfma_f32_32x32x16_bf16 v[16:31], v[188:191], v[208:211], v[16:31]
	ds_read_b128 v[208:211], v151 offset:96
	s_waitcnt lgkmcnt(5)
	v_mfma_f32_32x32x16_bf16 v[64:79], v[184:187], v[212:215], v[64:79]
	v_mfma_f32_32x32x16_bf16 v[0:15], v[188:191], v[212:215], v[0:15]
	ds_read_b128 v[212:215], v151 offset:4704
	s_setprio 0
	global_load_dwordx4 v[184:187], v[144:145], off offset:1280
	global_load_dwordx4 v[188:191], v[146:147], off offset:1280
	s_setprio 1
	s_waitcnt lgkmcnt(1)
	v_mfma_f32_32x32x16_bf16 v[112:127], v[194:197], v[208:211], v[112:127]
	v_mfma_f32_32x32x16_bf16 v[48:63], v[198:201], v[208:211], v[48:63]
	s_waitcnt lgkmcnt(0)
	v_mfma_f32_32x32x16_bf16 v[96:111], v[194:197], v[212:215], v[96:111]
	v_mfma_f32_32x32x16_bf16 v[32:47], v[198:201], v[212:215], v[32:47]
	ds_read_b128 v[208:211], v151 offset:9312
	ds_read_b128 v[212:215], v151 offset:13920
	s_waitcnt lgkmcnt(1)
	v_mfma_f32_32x32x16_bf16 v[80:95], v[194:197], v[208:211], v[80:95]
	v_mfma_f32_32x32x16_bf16 v[16:31], v[198:201], v[208:211], v[16:31]
	s_waitcnt lgkmcnt(0)
	v_mfma_f32_32x32x16_bf16 v[64:79], v[194:197], v[212:215], v[64:79]
	v_mfma_f32_32x32x16_bf16 v[0:15], v[198:201], v[212:215], v[0:15]
	s_setprio 0
	s_barrier
; template <bool trans>
; DI void gemm_core(const GTile& tl, const GTile& nx, bool has_next  , bool chain  , bool pre, u32x4 (&ra)[4], u32x4 (&rb)[4], char* smem, f32x16 (&acc)[2][4]) {
;     ...
;   const int nk = K / 64;
;   if (!pre) { G_LOAD(0); G_STORE(0); G_LOAD(1); }
;   for (int kt = 0; kt < nk; ++kt) {
;     __syncthreads();
;     G_COMPUTE(kt & 1, kt);
;   }
	global_load_dwordx4 v[194:197], v[136:137], off offset:1408
	global_load_dwordx4 v[198:201], v[138:139], off offset:1408
	s_waitcnt vmcnt(9)
	ds_write_b128 v148, v[176:179]
	s_waitcnt vmcnt(8)
	ds_write_b128 v148, v[180:183] offset:36864
	ds_read_b128 v[176:179], v150
	ds_read_b128 v[180:183], v150 offset:4608
	ds_read_b128 v[208:211], v149
	ds_read_b128 v[212:215], v149 offset:4608
	s_setprio 1
	s_waitcnt lgkmcnt(1)
	v_mfma_f32_32x32x16_bf16 v[112:127], v[176:179], v[208:211], v[112:127]
	v_mfma_f32_32x32x16_bf16 v[48:63], v[180:183], v[208:211], v[48:63]
	s_waitcnt lgkmcnt(0)
	v_mfma_f32_32x32x16_bf16 v[96:111], v[176:179], v[212:215], v[96:111]
	v_mfma_f32_32x32x16_bf16 v[32:47], v[180:183], v[212:215], v[32:47]
	ds_read_b128 v[208:211], v149 offset:9216
	ds_read_b128 v[212:215], v149 offset:13824
	s_waitcnt vmcnt(7)
	ds_write_b128 v148, v[168:171] offset:9216
	s_waitcnt vmcnt(6)
	ds_write_b128 v148, v[172:175] offset:46080
	ds_read_b128 v[168:171], v150 offset:32
	ds_read_b128 v[172:175], v150 offset:4640
	s_waitcnt lgkmcnt(5)
	v_mfma_f32_32x32x16_bf16 v[80:95], v[176:179], v[208:211], v[80:95]
	v_mfma_f32_32x32x16_bf16 v[16:31], v[180:183], v[208:211], v[16:31]
	ds_read_b128 v[208:211], v149 offset:32
	s_waitcnt lgkmcnt(5)
	v_mfma_f32_32x32x16_bf16 v[64:79], v[176:179], v[212:215], v[64:79]
	v_mfma_f32_32x32x16_bf16 v[0:15], v[180:183], v[212:215], v[0:15]
	ds_read_b128 v[212:215], v149 offset:4640
	s_setprio 0
	global_load_dwordx4 v[176:179], v[140:141], off offset:1408
	global_load_dwordx4 v[180:183], v[142:143], off offset:1408
	s_setprio 1
	s_waitcnt lgkmcnt(1)
	v_mfma_f32_32x32x16_bf16 v[112:127], v[168:171], v[208:211], v[112:127]
	v_mfma_f32_32x32x16_bf16 v[48:63], v[172:175], v[208:211], v[48:63]
	s_waitcnt lgkmcnt(0)
	v_mfma_f32_32x32x16_bf16 v[96:111], v[168:171], v[212:215], v[96:111]
	v_mfma_f32_32x32x16_bf16 v[32:47], v[172:175], v[212:215], v[32:47]
	ds_read_b128 v[208:211], v149 offset:9248
	ds_read_b128 v[212:215], v149 offset:13856
	s_waitcnt vmcnt(7)
	ds_write_b128 v148, v[160:163] offset:18432
	s_waitcnt vmcnt(6)
	ds_write_b128 v148, v[164:167] offset:55296
	ds_read_b128 v[160:163], v150 offset:64
	ds_read_b128 v[164:167], v150 offset:4672
	s_waitcnt lgkmcnt(5)
	v_mfma_f32_32x32x16_bf16 v[80:95], v[168:171], v[208:211], v[80:95]
	v_mfma_f32_32x32x16_bf16 v[16:31], v[172:175], v[208:211], v[16:31]
	ds_read_b128 v[208:211], v149 offset:64
	s_waitcnt lgkmcnt(5)
	v_mfma_f32_32x32x16_bf16 v[64:79], v[168:171], v[212:215], v[64:79]
	v_mfma_f32_32x32x16_bf16 v[0:15], v[172:175], v[212:215], v[0:15]
	ds_read_b128 v[212:215], v149 offset:4672
	s_setprio 0
	global_load_dwordx4 v[168:171], v[132:133], off offset:1408
	global_load_dwordx4 v[172:175], v[134:135], off offset:1408
	s_setprio 1
	s_waitcnt lgkmcnt(1)
	v_mfma_f32_32x32x16_bf16 v[112:127], v[160:163], v[208:211], v[112:127]
	v_mfma_f32_32x32x16_bf16 v[48:63], v[164:167], v[208:211], v[48:63]
	s_waitcnt lgkmcnt(0)
	v_mfma_f32_32x32x16_bf16 v[96:111], v[160:163], v[212:215], v[96:111]
	v_mfma_f32_32x32x16_bf16 v[32:47], v[164:167], v[212:215], v[32:47]
	ds_read_b128 v[208:211], v149 offset:9280
	ds_read_b128 v[212:215], v149 offset:13888
	s_waitcnt vmcnt(7)
	ds_write_b128 v148, v[184:187] offset:27648
	s_waitcnt vmcnt(6)
	ds_write_b128 v148, v[188:191] offset:64512
	ds_read_b128 v[184:187], v150 offset:96
	ds_read_b128 v[188:191], v150 offset:4704
	s_waitcnt lgkmcnt(5)
	v_mfma_f32_32x32x16_bf16 v[80:95], v[160:163], v[208:211], v[80:95]
	v_mfma_f32_32x32x16_bf16 v[16:31], v[164:167], v[208:211], v[16:31]
	ds_read_b128 v[208:211], v149 offset:96
	s_waitcnt lgkmcnt(5)
	v_mfma_f32_32x32x16_bf16 v[64:79], v[160:163], v[212:215], v[64:79]
	v_mfma_f32_32x32x16_bf16 v[0:15], v[164:167], v[212:215], v[0:15]
	ds_read_b128 v[212:215], v149 offset:4704
	s_setprio 0
	global_load_dwordx4 v[160:163], v[144:145], off offset:1408
	global_load_dwordx4 v[164:167], v[146:147], off offset:1408
	s_setprio 1
	s_waitcnt lgkmcnt(1)
	v_mfma_f32_32x32x16_bf16 v[112:127], v[184:187], v[208:211], v[112:127]
	v_mfma_f32_32x32x16_bf16 v[48:63], v[188:191], v[208:211], v[48:63]
	s_waitcnt lgkmcnt(0)
	v_mfma_f32_32x32x16_bf16 v[96:111], v[184:187], v[212:215], v[96:111]
	v_mfma_f32_32x32x16_bf16 v[32:47], v[188:191], v[212:215], v[32:47]
	ds_read_b128 v[208:211], v149 offset:9312
	ds_read_b128 v[212:215], v149 offset:13920
	s_waitcnt lgkmcnt(1)
	v_mfma_f32_32x32x16_bf16 v[80:95], v[184:187], v[208:211], v[80:95]
	v_mfma_f32_32x32x16_bf16 v[16:31], v[188:191], v[208:211], v[16:31]
	s_waitcnt lgkmcnt(0)
	v_mfma_f32_32x32x16_bf16 v[64:79], v[184:187], v[212:215], v[64:79]
	v_mfma_f32_32x32x16_bf16 v[0:15], v[188:191], v[212:215], v[0:15]
	s_setprio 0
	s_barrier
; template <bool trans>
; DI void gemm_core(const GTile& tl, const GTile& nx, bool has_next  , bool chain  , bool pre, u32x4 (&ra)[4], u32x4 (&rb)[4], char* smem, f32x16 (&acc)[2][4]) {
;     ...
;   const int nk = K / 64;
;   if (!pre) { G_LOAD(0); G_STORE(0); G_LOAD(1); }
;   for (int kt = 0; kt < nk; ++kt) {
;     __syncthreads();
;     G_COMPUTE(kt & 1, kt);
;   }
	global_load_dwordx4 v[184:187], v[136:137], off offset:1536
	global_load_dwordx4 v[188:191], v[138:139], off offset:1536
	s_waitcnt vmcnt(9)
	ds_write_b128 v192, v[194:197]
	s_waitcnt vmcnt(8)
	ds_write_b128 v159, v[198:201]
	ds_read_b128 v[194:197], v152 offset:36864
	ds_read_b128 v[198:201], v152 offset:41472
	ds_read_b128 v[208:211], v151
	ds_read_b128 v[212:215], v151 offset:4608
	s_setprio 1
	s_waitcnt lgkmcnt(1)
	v_mfma_f32_32x32x16_bf16 v[112:127], v[194:197], v[208:211], v[112:127]
	v_mfma_f32_32x32x16_bf16 v[48:63], v[198:201], v[208:211], v[48:63]
	s_waitcnt lgkmcnt(0)
	v_mfma_f32_32x32x16_bf16 v[96:111], v[194:197], v[212:215], v[96:111]
	v_mfma_f32_32x32x16_bf16 v[32:47], v[198:201], v[212:215], v[32:47]
	ds_read_b128 v[208:211], v151 offset:9216
	ds_read_b128 v[212:215], v151 offset:13824
	s_waitcnt vmcnt(7)
	ds_write_b128 v158, v[176:179]
	s_waitcnt vmcnt(6)
	ds_write_b128 v157, v[180:183]
	ds_read_b128 v[176:179], v152 offset:36896
	ds_read_b128 v[180:183], v152 offset:41504
	s_waitcnt lgkmcnt(5)
	v_mfma_f32_32x32x16_bf16 v[80:95], v[194:197], v[208:211], v[80:95]
	v_mfma_f32_32x32x16_bf16 v[16:31], v[198:201], v[208:211], v[16:31]
	ds_read_b128 v[208:211], v151 offset:32
	s_waitcnt lgkmcnt(5)
	v_mfma_f32_32x32x16_bf16 v[64:79], v[194:197], v[212:215], v[64:79]
	v_mfma_f32_32x32x16_bf16 v[0:15], v[198:201], v[212:215], v[0:15]
	ds_read_b128 v[212:215], v151 offset:4640
	s_setprio 0
	global_load_dwordx4 v[194:197], v[140:141], off offset:1536
	global_load_dwordx4 v[198:201], v[142:143], off offset:1536
	s_setprio 1
	s_waitcnt lgkmcnt(1)
	v_mfma_f32_32x32x16_bf16 v[112:127], v[176:179], v[208:211], v[112:127]
	v_mfma_f32_32x32x16_bf16 v[48:63], v[180:183], v[208:211], v[48:63]
	s_waitcnt lgkmcnt(0)
	v_mfma_f32_32x32x16_bf16 v[96:111], v[176:179], v[212:215], v[96:111]
	v_mfma_f32_32x32x16_bf16 v[32:47], v[180:183], v[212:215], v[32:47]
	ds_read_b128 v[208:211], v151 offset:9248
	ds_read_b128 v[212:215], v151 offset:13856
	s_waitcnt vmcnt(7)
	ds_write_b128 v154, v[168:171]
	s_waitcnt vmcnt(6)
	ds_write_b128 v153, v[172:175]
	ds_read_b128 v[168:171], v152 offset:36928
	ds_read_b128 v[172:175], v152 offset:41536
	s_waitcnt lgkmcnt(5)
	v_mfma_f32_32x32x16_bf16 v[80:95], v[176:179], v[208:211], v[80:95]
	v_mfma_f32_32x32x16_bf16 v[16:31], v[180:183], v[208:211], v[16:31]
	ds_read_b128 v[208:211], v151 offset:64
	s_waitcnt lgkmcnt(5)
	v_mfma_f32_32x32x16_bf16 v[64:79], v[176:179], v[212:215], v[64:79]
	v_mfma_f32_32x32x16_bf16 v[0:15], v[180:183], v[212:215], v[0:15]
	ds_read_b128 v[212:215], v151 offset:4672
	s_setprio 0
	global_load_dwordx4 v[176:179], v[132:133], off offset:1536
	global_load_dwordx4 v[180:183], v[134:135], off offset:1536
	s_setprio 1
	s_waitcnt lgkmcnt(1)
	v_mfma_f32_32x32x16_bf16 v[112:127], v[168:171], v[208:211], v[112:127]
	v_mfma_f32_32x32x16_bf16 v[48:63], v[172:175], v[208:211], v[48:63]
	s_waitcnt lgkmcnt(0)
	v_mfma_f32_32x32x16_bf16 v[96:111], v[168:171], v[212:215], v[96:111]
	v_mfma_f32_32x32x16_bf16 v[32:47], v[172:175], v[212:215], v[32:47]
	ds_read_b128 v[208:211], v151 offset:9280
	ds_read_b128 v[212:215], v151 offset:13888
	s_waitcnt vmcnt(7)
	ds_write_b128 v156, v[160:163]
	s_waitcnt vmcnt(6)
	ds_write_b128 v155, v[164:167]
	ds_read_b128 v[160:163], v152 offset:36960
	ds_read_b128 v[164:167], v152 offset:41568
	s_waitcnt lgkmcnt(5)
	v_mfma_f32_32x32x16_bf16 v[80:95], v[168:171], v[208:211], v[80:95]
	v_mfma_f32_32x32x16_bf16 v[16:31], v[172:175], v[208:211], v[16:31]
	ds_read_b128 v[208:211], v151 offset:96
	s_waitcnt lgkmcnt(5)
	v_mfma_f32_32x32x16_bf16 v[64:79], v[168:171], v[212:215], v[64:79]
	v_mfma_f32_32x32x16_bf16 v[0:15], v[172:175], v[212:215], v[0:15]
	ds_read_b128 v[212:215], v151 offset:4704
	s_setprio 0
	global_load_dwordx4 v[168:171], v[144:145], off offset:1536
	global_load_dwordx4 v[172:175], v[146:147], off offset:1536
	s_setprio 1
	s_waitcnt lgkmcnt(1)
	v_mfma_f32_32x32x16_bf16 v[112:127], v[160:163], v[208:211], v[112:127]
	v_mfma_f32_32x32x16_bf16 v[48:63], v[164:167], v[208:211], v[48:63]
	s_waitcnt lgkmcnt(0)
	v_mfma_f32_32x32x16_bf16 v[96:111], v[160:163], v[212:215], v[96:111]
	v_mfma_f32_32x32x16_bf16 v[32:47], v[164:167], v[212:215], v[32:47]
	ds_read_b128 v[208:211], v151 offset:9312
	ds_read_b128 v[212:215], v151 offset:13920
	s_waitcnt lgkmcnt(1)
	v_mfma_f32_32x32x16_bf16 v[80:95], v[160:163], v[208:211], v[80:95]
	v_mfma_f32_32x32x16_bf16 v[16:31], v[164:167], v[208:211], v[16:31]
	s_waitcnt lgkmcnt(0)
	v_mfma_f32_32x32x16_bf16 v[64:79], v[160:163], v[212:215], v[64:79]
	v_mfma_f32_32x32x16_bf16 v[0:15], v[164:167], v[212:215], v[0:15]
	s_setprio 0
	s_barrier
; template <bool trans>
; DI void gemm_core(const GTile& tl, const GTile& nx, bool has_next  , bool chain  , bool pre, u32x4 (&ra)[4], u32x4 (&rb)[4], char* smem, f32x16 (&acc)[2][4]) {
;     ...
;   const int nk = K / 64;
;   if (!pre) { G_LOAD(0); G_STORE(0); G_LOAD(1); }
;   for (int kt = 0; kt < nk; ++kt) {
;     __syncthreads();
;     G_COMPUTE(kt & 1, kt);
	global_load_dwordx4 v[160:163], v[136:137], off offset:1664
	global_load_dwordx4 v[164:167], v[138:139], off offset:1664
	s_waitcnt vmcnt(9)
	ds_write_b128 v148, v[184:187]
	s_waitcnt vmcnt(8)
	ds_write_b128 v148, v[188:191] offset:36864
	ds_read_b128 v[184:187], v150
	ds_read_b128 v[188:191], v150 offset:4608
	ds_read_b128 v[208:211], v149
	ds_read_b128 v[212:215], v149 offset:4608
	s_setprio 1
	s_waitcnt lgkmcnt(1)
	v_mfma_f32_32x32x16_bf16 v[112:127], v[184:187], v[208:211], v[112:127]
	v_mfma_f32_32x32x16_bf16 v[48:63], v[188:191], v[208:211], v[48:63]
	s_waitcnt lgkmcnt(0)
	v_mfma_f32_32x32x16_bf16 v[96:111], v[184:187], v[212:215], v[96:111]
	v_mfma_f32_32x32x16_bf16 v[32:47], v[188:191], v[212:215], v[32:47]
	ds_read_b128 v[208:211], v149 offset:9216
	ds_read_b128 v[212:215], v149 offset:13824
	s_waitcnt vmcnt(7)
	ds_write_b128 v148, v[194:197] offset:9216
	s_waitcnt vmcnt(6)
	ds_write_b128 v148, v[198:201] offset:46080
	ds_read_b128 v[194:197], v150 offset:32
	ds_read_b128 v[198:201], v150 offset:4640
	s_waitcnt lgkmcnt(5)
	v_mfma_f32_32x32x16_bf16 v[80:95], v[184:187], v[208:211], v[80:95]
	v_mfma_f32_32x32x16_bf16 v[16:31], v[188:191], v[208:211], v[16:31]
	ds_read_b128 v[208:211], v149 offset:32
	s_waitcnt lgkmcnt(5)
	v_mfma_f32_32x32x16_bf16 v[64:79], v[184:187], v[212:215], v[64:79]
	v_mfma_f32_32x32x16_bf16 v[0:15], v[188:191], v[212:215], v[0:15]
	ds_read_b128 v[212:215], v149 offset:4640
	s_setprio 0
	global_load_dwordx4 v[184:187], v[140:141], off offset:1664
	global_load_dwordx4 v[188:191], v[142:143], off offset:1664
	s_setprio 1
	s_waitcnt lgkmcnt(1)
	v_mfma_f32_32x32x16_bf16 v[112:127], v[194:197], v[208:211], v[112:127]
	v_mfma_f32_32x32x16_bf16 v[48:63], v[198:201], v[208:211], v[48:63]
	s_waitcnt lgkmcnt(0)
	v_mfma_f32_32x32x16_bf16 v[96:111], v[194:197], v[212:215], v[96:111]
	v_mfma_f32_32x32x16_bf16 v[32:47], v[198:201], v[212:215], v[32:47]
	ds_read_b128 v[208:211], v149 offset:9248
	ds_read_b128 v[212:215], v149 offset:13856
	s_waitcnt vmcnt(7)
	ds_write_b128 v148, v[176:179] offset:18432
	s_waitcnt vmcnt(6)
	ds_write_b128 v148, v[180:183] offset:55296
	ds_read_b128 v[176:179], v150 offset:64
	ds_read_b128 v[180:183], v150 offset:4672
	s_waitcnt lgkmcnt(5)
	v_mfma_f32_32x32x16_bf16 v[80:95], v[194:197], v[208:211], v[80:95]
	v_mfma_f32_32x32x16_bf16 v[16:31], v[198:201], v[208:211], v[16:31]
	ds_read_b128 v[208:211], v149 offset:64
	s_waitcnt lgkmcnt(5)
	v_mfma_f32_32x32x16_bf16 v[64:79], v[194:197], v[212:215], v[64:79]
	v_mfma_f32_32x32x16_bf16 v[0:15], v[198:201], v[212:215], v[0:15]
	ds_read_b128 v[212:215], v149 offset:4672
	s_setprio 0
	global_load_dwordx4 v[194:197], v[132:133], off offset:1664
	global_load_dwordx4 v[198:201], v[134:135], off offset:1664
	s_setprio 1
	s_waitcnt lgkmcnt(1)
	v_mfma_f32_32x32x16_bf16 v[112:127], v[176:179], v[208:211], v[112:127]
	v_mfma_f32_32x32x16_bf16 v[48:63], v[180:183], v[208:211], v[48:63]
	s_waitcnt lgkmcnt(0)
	v_mfma_f32_32x32x16_bf16 v[96:111], v[176:179], v[212:215], v[96:111]
	v_mfma_f32_32x32x16_bf16 v[32:47], v[180:183], v[212:215], v[32:47]
	ds_read_b128 v[208:211], v149 offset:9280
	ds_read_b128 v[212:215], v149 offset:13888
	s_waitcnt vmcnt(7)
	ds_write_b128 v148, v[168:171] offset:27648
	s_waitcnt vmcnt(6)
	ds_write_b128 v148, v[172:175] offset:64512
	ds_read_b128 v[168:171], v150 offset:96
	ds_read_b128 v[172:175], v150 offset:4704
	s_waitcnt lgkmcnt(5)
	v_mfma_f32_32x32x16_bf16 v[80:95], v[176:179], v[208:211], v[80:95]
	v_mfma_f32_32x32x16_bf16 v[16:31], v[180:183], v[208:211], v[16:31]
	ds_read_b128 v[208:211], v149 offset:96
	s_waitcnt lgkmcnt(5)
	v_mfma_f32_32x32x16_bf16 v[64:79], v[176:179], v[212:215], v[64:79]
	v_mfma_f32_32x32x16_bf16 v[0:15], v[180:183], v[212:215], v[0:15]
	ds_read_b128 v[212:215], v149 offset:4704
	s_setprio 0
	global_load_dwordx4 v[176:179], v[144:145], off offset:1664
	global_load_dwordx4 v[180:183], v[146:147], off offset:1664
	s_setprio 1
	s_waitcnt lgkmcnt(1)
	v_mfma_f32_32x32x16_bf16 v[112:127], v[168:171], v[208:211], v[112:127]
	v_mfma_f32_32x32x16_bf16 v[48:63], v[172:175], v[208:211], v[48:63]
	s_waitcnt lgkmcnt(0)
	v_mfma_f32_32x32x16_bf16 v[96:111], v[168:171], v[212:215], v[96:111]
	v_mfma_f32_32x32x16_bf16 v[32:47], v[172:175], v[212:215], v[32:47]
	ds_read_b128 v[208:211], v149 offset:9312
	ds_read_b128 v[212:215], v149 offset:13920
	s_waitcnt lgkmcnt(1)
	v_mfma_f32_32x32x16_bf16 v[80:95], v[168:171], v[208:211], v[80:95]
	v_mfma_f32_32x32x16_bf16 v[16:31], v[172:175], v[208:211], v[16:31]
	s_waitcnt lgkmcnt(0)
	v_mfma_f32_32x32x16_bf16 v[64:79], v[168:171], v[212:215], v[64:79]
	v_mfma_f32_32x32x16_bf16 v[0:15], v[172:175], v[212:215], v[0:15]
	s_setprio 0
	s_barrier
; template <bool trans>
; DI void gemm_core(const GTile& tl, const GTile& nx, bool has_next  , bool chain  , bool pre, u32x4 (&ra)[4], u32x4 (&rb)[4], char* smem, f32x16 (&acc)[2][4]) {
;     ...
;   const int nk = K / 64;
;   if (!pre) { G_LOAD(0); G_STORE(0); G_LOAD(1); }
;   for (int kt = 0; kt < nk; ++kt) {
;     __syncthreads();
;     G_COMPUTE(kt & 1, kt);
	global_load_dwordx4 v[168:171], v[136:137], off offset:1792
	global_load_dwordx4 v[172:175], v[138:139], off offset:1792
	s_waitcnt vmcnt(9)
	ds_write_b128 v192, v[160:163]
	s_waitcnt vmcnt(8)
	ds_write_b128 v159, v[164:167]
	ds_read_b128 v[160:163], v152 offset:36864
	ds_read_b128 v[164:167], v152 offset:41472
	ds_read_b128 v[208:211], v151
	ds_read_b128 v[212:215], v151 offset:4608
	s_setprio 1
	s_waitcnt lgkmcnt(1)
	v_mfma_f32_32x32x16_bf16 v[112:127], v[160:163], v[208:211], v[112:127]
	v_mfma_f32_32x32x16_bf16 v[48:63], v[164:167], v[208:211], v[48:63]
	s_waitcnt lgkmcnt(0)
	v_mfma_f32_32x32x16_bf16 v[96:111], v[160:163], v[212:215], v[96:111]
	v_mfma_f32_32x32x16_bf16 v[32:47], v[164:167], v[212:215], v[32:47]
	ds_read_b128 v[208:211], v151 offset:9216
	ds_read_b128 v[212:215], v151 offset:13824
	s_waitcnt vmcnt(7)
	ds_write_b128 v158, v[184:187]
	s_waitcnt vmcnt(6)
	ds_write_b128 v157, v[188:191]
	ds_read_b128 v[184:187], v152 offset:36896
	ds_read_b128 v[188:191], v152 offset:41504
	s_waitcnt lgkmcnt(5)
	v_mfma_f32_32x32x16_bf16 v[80:95], v[160:163], v[208:211], v[80:95]
	v_mfma_f32_32x32x16_bf16 v[16:31], v[164:167], v[208:211], v[16:31]
	ds_read_b128 v[208:211], v151 offset:32
	s_waitcnt lgkmcnt(5)
	v_mfma_f32_32x32x16_bf16 v[64:79], v[160:163], v[212:215], v[64:79]
	v_mfma_f32_32x32x16_bf16 v[0:15], v[164:167], v[212:215], v[0:15]
	ds_read_b128 v[212:215], v151 offset:4640
	s_setprio 0
	global_load_dwordx4 v[160:163], v[140:141], off offset:1792
	global_load_dwordx4 v[164:167], v[142:143], off offset:1792
	s_setprio 1
	s_waitcnt lgkmcnt(1)
	v_mfma_f32_32x32x16_bf16 v[112:127], v[184:187], v[208:211], v[112:127]
	v_mfma_f32_32x32x16_bf16 v[48:63], v[188:191], v[208:211], v[48:63]
	s_waitcnt lgkmcnt(0)
	v_mfma_f32_32x32x16_bf16 v[96:111], v[184:187], v[212:215], v[96:111]
	v_mfma_f32_32x32x16_bf16 v[32:47], v[188:191], v[212:215], v[32:47]
	ds_read_b128 v[208:211], v151 offset:9248
	ds_read_b128 v[212:215], v151 offset:13856
	s_waitcnt vmcnt(7)
	ds_write_b128 v154, v[194:197]
	s_waitcnt vmcnt(6)
	ds_write_b128 v153, v[198:201]
	ds_read_b128 v[194:197], v152 offset:36928
	ds_read_b128 v[198:201], v152 offset:41536
	s_waitcnt lgkmcnt(5)
	v_mfma_f32_32x32x16_bf16 v[80:95], v[184:187], v[208:211], v[80:95]
	v_mfma_f32_32x32x16_bf16 v[16:31], v[188:191], v[208:211], v[16:31]
	ds_read_b128 v[208:211], v151 offset:64
	s_waitcnt lgkmcnt(5)
	v_mfma_f32_32x32x16_bf16 v[64:79], v[184:187], v[212:215], v[64:79]
	v_mfma_f32_32x32x16_bf16 v[0:15], v[188:191], v[212:215], v[0:15]
	ds_read_b128 v[212:215], v151 offset:4672
	s_setprio 0
	global_load_dwordx4 v[184:187], v[132:133], off offset:1792
	global_load_dwordx4 v[188:191], v[134:135], off offset:1792
	s_setprio 1
	s_waitcnt lgkmcnt(1)
	v_mfma_f32_32x32x16_bf16 v[112:127], v[194:197], v[208:211], v[112:127]
	v_mfma_f32_32x32x16_bf16 v[48:63], v[198:201], v[208:211], v[48:63]
	s_waitcnt lgkmcnt(0)
	v_mfma_f32_32x32x16_bf16 v[96:111], v[194:197], v[212:215], v[96:111]
	v_mfma_f32_32x32x16_bf16 v[32:47], v[198:201], v[212:215], v[32:47]
	ds_read_b128 v[208:211], v151 offset:9280
	ds_read_b128 v[212:215], v151 offset:13888
	s_waitcnt vmcnt(7)
	ds_write_b128 v156, v[176:179]
	s_waitcnt vmcnt(6)
	ds_write_b128 v155, v[180:183]
	ds_read_b128 v[176:179], v152 offset:36960
	ds_read_b128 v[180:183], v152 offset:41568
	s_waitcnt lgkmcnt(5)
	v_mfma_f32_32x32x16_bf16 v[80:95], v[194:197], v[208:211], v[80:95]
	v_mfma_f32_32x32x16_bf16 v[16:31], v[198:201], v[208:211], v[16:31]
	ds_read_b128 v[208:211], v151 offset:96
	s_waitcnt lgkmcnt(5)
	v_mfma_f32_32x32x16_bf16 v[64:79], v[194:197], v[212:215], v[64:79]
	v_mfma_f32_32x32x16_bf16 v[0:15], v[198:201], v[212:215], v[0:15]
	ds_read_b128 v[212:215], v151 offset:4704
	s_setprio 0
	global_load_dwordx4 v[194:197], v[144:145], off offset:1792
	global_load_dwordx4 v[198:201], v[146:147], off offset:1792
	s_setprio 1
	s_waitcnt lgkmcnt(1)
	v_mfma_f32_32x32x16_bf16 v[112:127], v[176:179], v[208:211], v[112:127]
	v_mfma_f32_32x32x16_bf16 v[48:63], v[180:183], v[208:211], v[48:63]
	s_waitcnt lgkmcnt(0)
	v_mfma_f32_32x32x16_bf16 v[96:111], v[176:179], v[212:215], v[96:111]
	v_mfma_f32_32x32x16_bf16 v[32:47], v[180:183], v[212:215], v[32:47]
	ds_read_b128 v[208:211], v151 offset:9312
	ds_read_b128 v[212:215], v151 offset:13920
	s_waitcnt lgkmcnt(1)
	v_mfma_f32_32x32x16_bf16 v[80:95], v[176:179], v[208:211], v[80:95]
	v_mfma_f32_32x32x16_bf16 v[16:31], v[180:183], v[208:211], v[16:31]
	s_waitcnt lgkmcnt(0)
	v_mfma_f32_32x32x16_bf16 v[64:79], v[176:179], v[212:215], v[64:79]
	v_mfma_f32_32x32x16_bf16 v[0:15], v[180:183], v[212:215], v[0:15]
	s_setprio 0
	s_barrier
; template <bool trans>
; DI void gemm_core(const GTile& tl, const GTile& nx, bool has_next  , bool chain  , bool pre, u32x4 (&ra)[4], u32x4 (&rb)[4], char* smem, f32x16 (&acc)[2][4]) {
;     ...
;   const int nk = K / 64;
;   if (!pre) { G_LOAD(0); G_STORE(0); G_LOAD(1); }
;   for (int kt = 0; kt < nk; ++kt) {
;     __syncthreads();
;     G_COMPUTE(kt & 1, kt);
	global_load_dwordx4 v[176:179], v[136:137], off offset:1920
	global_load_dwordx4 v[180:183], v[138:139], off offset:1920
	s_waitcnt vmcnt(9)
	ds_write_b128 v148, v[168:171]
	s_waitcnt vmcnt(8)
	ds_write_b128 v148, v[172:175] offset:36864
	ds_read_b128 v[168:171], v150
	ds_read_b128 v[172:175], v150 offset:4608
	ds_read_b128 v[208:211], v149
	ds_read_b128 v[212:215], v149 offset:4608
	s_setprio 1
	s_waitcnt lgkmcnt(1)
	v_mfma_f32_32x32x16_bf16 v[112:127], v[168:171], v[208:211], v[112:127]
	v_mfma_f32_32x32x16_bf16 v[48:63], v[172:175], v[208:211], v[48:63]
	s_waitcnt lgkmcnt(0)
	v_mfma_f32_32x32x16_bf16 v[96:111], v[168:171], v[212:215], v[96:111]
	v_mfma_f32_32x32x16_bf16 v[32:47], v[172:175], v[212:215], v[32:47]
	ds_read_b128 v[208:211], v149 offset:9216
	ds_read_b128 v[212:215], v149 offset:13824
	s_waitcnt vmcnt(7)
	ds_write_b128 v148, v[160:163] offset:9216
	s_waitcnt vmcnt(6)
	ds_write_b128 v148, v[164:167] offset:46080
	ds_read_b128 v[160:163], v150 offset:32
	ds_read_b128 v[164:167], v150 offset:4640
	s_waitcnt lgkmcnt(5)
	v_mfma_f32_32x32x16_bf16 v[80:95], v[168:171], v[208:211], v[80:95]
	v_mfma_f32_32x32x16_bf16 v[16:31], v[172:175], v[208:211], v[16:31]
	ds_read_b128 v[208:211], v149 offset:32
	s_waitcnt lgkmcnt(5)
	v_mfma_f32_32x32x16_bf16 v[64:79], v[168:171], v[212:215], v[64:79]
	v_mfma_f32_32x32x16_bf16 v[0:15], v[172:175], v[212:215], v[0:15]
	ds_read_b128 v[212:215], v149 offset:4640
	s_setprio 0
	global_load_dwordx4 v[168:171], v[140:141], off offset:1920
	global_load_dwordx4 v[172:175], v[142:143], off offset:1920
	s_setprio 1
	s_waitcnt lgkmcnt(1)
	v_mfma_f32_32x32x16_bf16 v[112:127], v[160:163], v[208:211], v[112:127]
	v_mfma_f32_32x32x16_bf16 v[48:63], v[164:167], v[208:211], v[48:63]
	s_waitcnt lgkmcnt(0)
	v_mfma_f32_32x32x16_bf16 v[96:111], v[160:163], v[212:215], v[96:111]
	v_mfma_f32_32x32x16_bf16 v[32:47], v[164:167], v[212:215], v[32:47]
	ds_read_b128 v[208:211], v149 offset:9248
	ds_read_b128 v[212:215], v149 offset:13856
	s_waitcnt vmcnt(7)
	ds_write_b128 v148, v[184:187] offset:18432
	s_waitcnt vmcnt(6)
	ds_write_b128 v148, v[188:191] offset:55296
	ds_read_b128 v[184:187], v150 offset:64
	ds_read_b128 v[188:191], v150 offset:4672
	s_waitcnt lgkmcnt(5)
	v_mfma_f32_32x32x16_bf16 v[80:95], v[160:163], v[208:211], v[80:95]
	v_mfma_f32_32x32x16_bf16 v[16:31], v[164:167], v[208:211], v[16:31]
	ds_read_b128 v[208:211], v149 offset:64
	s_waitcnt lgkmcnt(5)
	v_mfma_f32_32x32x16_bf16 v[64:79], v[160:163], v[212:215], v[64:79]
	v_mfma_f32_32x32x16_bf16 v[0:15], v[164:167], v[212:215], v[0:15]
	ds_read_b128 v[212:215], v149 offset:4672
	s_setprio 0
	global_load_dwordx4 v[160:163], v[132:133], off offset:1920
	global_load_dwordx4 v[164:167], v[134:135], off offset:1920
	s_setprio 1
	s_waitcnt lgkmcnt(1)
	v_mfma_f32_32x32x16_bf16 v[112:127], v[184:187], v[208:211], v[112:127]
	v_mfma_f32_32x32x16_bf16 v[48:63], v[188:191], v[208:211], v[48:63]
	s_waitcnt lgkmcnt(0)
	v_mfma_f32_32x32x16_bf16 v[96:111], v[184:187], v[212:215], v[96:111]
	v_mfma_f32_32x32x16_bf16 v[32:47], v[188:191], v[212:215], v[32:47]
	ds_read_b128 v[208:211], v149 offset:9280
	ds_read_b128 v[212:215], v149 offset:13888
	s_waitcnt vmcnt(7)
	ds_write_b128 v148, v[194:197] offset:27648
	s_waitcnt vmcnt(6)
	ds_write_b128 v148, v[198:201] offset:64512
	ds_read_b128 v[194:197], v150 offset:96
	ds_read_b128 v[198:201], v150 offset:4704
	s_waitcnt lgkmcnt(5)
	v_mfma_f32_32x32x16_bf16 v[80:95], v[184:187], v[208:211], v[80:95]
	v_mfma_f32_32x32x16_bf16 v[16:31], v[188:191], v[208:211], v[16:31]
	ds_read_b128 v[208:211], v149 offset:96
	s_waitcnt lgkmcnt(5)
	v_mfma_f32_32x32x16_bf16 v[64:79], v[184:187], v[212:215], v[64:79]
	v_mfma_f32_32x32x16_bf16 v[0:15], v[188:191], v[212:215], v[0:15]
	ds_read_b128 v[212:215], v149 offset:4704
	s_setprio 0
	global_load_dwordx4 v[184:187], v[144:145], off offset:1920
	global_load_dwordx4 v[188:191], v[146:147], off offset:1920
	s_setprio 1
	s_waitcnt lgkmcnt(1)
	v_mfma_f32_32x32x16_bf16 v[112:127], v[194:197], v[208:211], v[112:127]
	v_mfma_f32_32x32x16_bf16 v[48:63], v[198:201], v[208:211], v[48:63]
	s_waitcnt lgkmcnt(0)
	v_mfma_f32_32x32x16_bf16 v[96:111], v[194:197], v[212:215], v[96:111]
	v_mfma_f32_32x32x16_bf16 v[32:47], v[198:201], v[212:215], v[32:47]
	ds_read_b128 v[208:211], v149 offset:9312
	ds_read_b128 v[212:215], v149 offset:13920
	s_waitcnt lgkmcnt(1)
	v_mfma_f32_32x32x16_bf16 v[80:95], v[194:197], v[208:211], v[80:95]
	v_mfma_f32_32x32x16_bf16 v[16:31], v[198:201], v[208:211], v[16:31]
	s_waitcnt lgkmcnt(0)
	v_mfma_f32_32x32x16_bf16 v[64:79], v[194:197], v[212:215], v[64:79]
	v_mfma_f32_32x32x16_bf16 v[0:15], v[198:201], v[212:215], v[0:15]
	s_setprio 0
	s_barrier
; template <bool trans>
; DI void gemm_core(const GTile& tl, const GTile& nx, bool has_next  , bool chain  , bool pre, u32x4 (&ra)[4], u32x4 (&rb)[4], char* smem, f32x16 (&acc)[2][4]) {
;     ...
;   const int nk = K / 64;
;   if (!pre) { G_LOAD(0); G_STORE(0); G_LOAD(1); }
;   for (int kt = 0; kt < nk; ++kt) {
;     __syncthreads();
;     G_COMPUTE(kt & 1, kt);
	global_load_dwordx4 v[194:197], v[136:137], off offset:2048
	global_load_dwordx4 v[198:201], v[138:139], off offset:2048
	s_waitcnt vmcnt(9)
	ds_write_b128 v192, v[176:179]
	s_waitcnt vmcnt(8)
	ds_write_b128 v159, v[180:183]
	ds_read_b128 v[176:179], v152 offset:36864
	ds_read_b128 v[180:183], v152 offset:41472
	ds_read_b128 v[208:211], v151
	ds_read_b128 v[212:215], v151 offset:4608
	s_setprio 1
	s_waitcnt lgkmcnt(1)
	v_mfma_f32_32x32x16_bf16 v[112:127], v[176:179], v[208:211], v[112:127]
	v_mfma_f32_32x32x16_bf16 v[48:63], v[180:183], v[208:211], v[48:63]
	s_waitcnt lgkmcnt(0)
	v_mfma_f32_32x32x16_bf16 v[96:111], v[176:179], v[212:215], v[96:111]
	v_mfma_f32_32x32x16_bf16 v[32:47], v[180:183], v[212:215], v[32:47]
	ds_read_b128 v[208:211], v151 offset:9216
	ds_read_b128 v[212:215], v151 offset:13824
	s_waitcnt vmcnt(7)
	ds_write_b128 v158, v[168:171]
	s_waitcnt vmcnt(6)
	ds_write_b128 v157, v[172:175]
	ds_read_b128 v[168:171], v152 offset:36896
	ds_read_b128 v[172:175], v152 offset:41504
	s_waitcnt lgkmcnt(5)
	v_mfma_f32_32x32x16_bf16 v[80:95], v[176:179], v[208:211], v[80:95]
	v_mfma_f32_32x32x16_bf16 v[16:31], v[180:183], v[208:211], v[16:31]
	ds_read_b128 v[208:211], v151 offset:32
	s_waitcnt lgkmcnt(5)
	v_mfma_f32_32x32x16_bf16 v[64:79], v[176:179], v[212:215], v[64:79]
	v_mfma_f32_32x32x16_bf16 v[0:15], v[180:183], v[212:215], v[0:15]
	ds_read_b128 v[212:215], v151 offset:4640
	s_setprio 0
	global_load_dwordx4 v[176:179], v[140:141], off offset:2048
	global_load_dwordx4 v[180:183], v[142:143], off offset:2048
	s_setprio 1
	s_waitcnt lgkmcnt(1)
	v_mfma_f32_32x32x16_bf16 v[112:127], v[168:171], v[208:211], v[112:127]
	v_mfma_f32_32x32x16_bf16 v[48:63], v[172:175], v[208:211], v[48:63]
	s_waitcnt lgkmcnt(0)
	v_mfma_f32_32x32x16_bf16 v[96:111], v[168:171], v[212:215], v[96:111]
	v_mfma_f32_32x32x16_bf16 v[32:47], v[172:175], v[212:215], v[32:47]
	ds_read_b128 v[208:211], v151 offset:9248
	ds_read_b128 v[212:215], v151 offset:13856
	s_waitcnt vmcnt(7)
	ds_write_b128 v154, v[160:163]
	s_waitcnt vmcnt(6)
	ds_write_b128 v153, v[164:167]
	ds_read_b128 v[160:163], v152 offset:36928
	ds_read_b128 v[164:167], v152 offset:41536
	s_waitcnt lgkmcnt(5)
	v_mfma_f32_32x32x16_bf16 v[80:95], v[168:171], v[208:211], v[80:95]
	v_mfma_f32_32x32x16_bf16 v[16:31], v[172:175], v[208:211], v[16:31]
	ds_read_b128 v[208:211], v151 offset:64
	s_waitcnt lgkmcnt(5)
	v_mfma_f32_32x32x16_bf16 v[64:79], v[168:171], v[212:215], v[64:79]
	v_mfma_f32_32x32x16_bf16 v[0:15], v[172:175], v[212:215], v[0:15]
	ds_read_b128 v[212:215], v151 offset:4672
	s_setprio 0
	global_load_dwordx4 v[168:171], v[132:133], off offset:2048
	global_load_dwordx4 v[172:175], v[134:135], off offset:2048
	s_setprio 1
	s_waitcnt lgkmcnt(1)
	v_mfma_f32_32x32x16_bf16 v[112:127], v[160:163], v[208:211], v[112:127]
	v_mfma_f32_32x32x16_bf16 v[48:63], v[164:167], v[208:211], v[48:63]
	s_waitcnt lgkmcnt(0)
	v_mfma_f32_32x32x16_bf16 v[96:111], v[160:163], v[212:215], v[96:111]
	v_mfma_f32_32x32x16_bf16 v[32:47], v[164:167], v[212:215], v[32:47]
	ds_read_b128 v[208:211], v151 offset:9280
	ds_read_b128 v[212:215], v151 offset:13888
	s_waitcnt vmcnt(7)
	ds_write_b128 v156, v[184:187]
	s_waitcnt vmcnt(6)
	ds_write_b128 v155, v[188:191]
	ds_read_b128 v[184:187], v152 offset:36960
	ds_read_b128 v[188:191], v152 offset:41568
	s_waitcnt lgkmcnt(5)
	v_mfma_f32_32x32x16_bf16 v[80:95], v[160:163], v[208:211], v[80:95]
	v_mfma_f32_32x32x16_bf16 v[16:31], v[164:167], v[208:211], v[16:31]
	ds_read_b128 v[208:211], v151 offset:96
	s_waitcnt lgkmcnt(5)
	v_mfma_f32_32x32x16_bf16 v[64:79], v[160:163], v[212:215], v[64:79]
	v_mfma_f32_32x32x16_bf16 v[0:15], v[164:167], v[212:215], v[0:15]
	ds_read_b128 v[212:215], v151 offset:4704
	s_setprio 0
	global_load_dwordx4 v[160:163], v[144:145], off offset:2048
	global_load_dwordx4 v[164:167], v[146:147], off offset:2048
	s_setprio 1
	s_waitcnt lgkmcnt(1)
	v_mfma_f32_32x32x16_bf16 v[112:127], v[184:187], v[208:211], v[112:127]
	v_mfma_f32_32x32x16_bf16 v[48:63], v[188:191], v[208:211], v[48:63]
	s_waitcnt lgkmcnt(0)
	v_mfma_f32_32x32x16_bf16 v[96:111], v[184:187], v[212:215], v[96:111]
	v_mfma_f32_32x32x16_bf16 v[32:47], v[188:191], v[212:215], v[32:47]
	ds_read_b128 v[208:211], v151 offset:9312
	ds_read_b128 v[212:215], v151 offset:13920
	s_waitcnt lgkmcnt(1)
	v_mfma_f32_32x32x16_bf16 v[80:95], v[184:187], v[208:211], v[80:95]
	v_mfma_f32_32x32x16_bf16 v[16:31], v[188:191], v[208:211], v[16:31]
	s_waitcnt lgkmcnt(0)
	v_mfma_f32_32x32x16_bf16 v[64:79], v[184:187], v[212:215], v[64:79]
	v_mfma_f32_32x32x16_bf16 v[0:15], v[188:191], v[212:215], v[0:15]
	s_setprio 0
	s_barrier
; template <bool trans>
; DI void gemm_core(const GTile& tl, const GTile& nx, bool has_next  , bool chain  , bool pre, u32x4 (&ra)[4], u32x4 (&rb)[4], char* smem, f32x16 (&acc)[2][4]) {
;     ...
;   const int nk = K / 64;
;   if (!pre) { G_LOAD(0); G_STORE(0); G_LOAD(1); }
;   for (int kt = 0; kt < nk; ++kt) {
;     __syncthreads();
;     G_COMPUTE(kt & 1, kt);
	global_load_dwordx4 v[184:187], v[136:137], off offset:2176
	global_load_dwordx4 v[188:191], v[138:139], off offset:2176
	s_waitcnt vmcnt(9)
	ds_write_b128 v148, v[194:197]
	s_waitcnt vmcnt(8)
	ds_write_b128 v148, v[198:201] offset:36864
	ds_read_b128 v[194:197], v150
	ds_read_b128 v[198:201], v150 offset:4608
	ds_read_b128 v[208:211], v149
	ds_read_b128 v[212:215], v149 offset:4608
	s_setprio 1
	s_waitcnt lgkmcnt(1)
	v_mfma_f32_32x32x16_bf16 v[112:127], v[194:197], v[208:211], v[112:127]
	v_mfma_f32_32x32x16_bf16 v[48:63], v[198:201], v[208:211], v[48:63]
	s_waitcnt lgkmcnt(0)
	v_mfma_f32_32x32x16_bf16 v[96:111], v[194:197], v[212:215], v[96:111]
	v_mfma_f32_32x32x16_bf16 v[32:47], v[198:201], v[212:215], v[32:47]
	ds_read_b128 v[208:211], v149 offset:9216
	ds_read_b128 v[212:215], v149 offset:13824
	s_waitcnt vmcnt(7)
	ds_write_b128 v148, v[176:179] offset:9216
	s_waitcnt vmcnt(6)
	ds_write_b128 v148, v[180:183] offset:46080
	ds_read_b128 v[176:179], v150 offset:32
	ds_read_b128 v[180:183], v150 offset:4640
	s_waitcnt lgkmcnt(5)
	v_mfma_f32_32x32x16_bf16 v[80:95], v[194:197], v[208:211], v[80:95]
	v_mfma_f32_32x32x16_bf16 v[16:31], v[198:201], v[208:211], v[16:31]
	ds_read_b128 v[208:211], v149 offset:32
	s_waitcnt lgkmcnt(5)
	v_mfma_f32_32x32x16_bf16 v[64:79], v[194:197], v[212:215], v[64:79]
	v_mfma_f32_32x32x16_bf16 v[0:15], v[198:201], v[212:215], v[0:15]
	ds_read_b128 v[212:215], v149 offset:4640
	s_setprio 0
	global_load_dwordx4 v[194:197], v[140:141], off offset:2176
	global_load_dwordx4 v[198:201], v[142:143], off offset:2176
	s_setprio 1
	s_waitcnt lgkmcnt(1)
	v_mfma_f32_32x32x16_bf16 v[112:127], v[176:179], v[208:211], v[112:127]
	v_mfma_f32_32x32x16_bf16 v[48:63], v[180:183], v[208:211], v[48:63]
	s_waitcnt lgkmcnt(0)
	v_mfma_f32_32x32x16_bf16 v[96:111], v[176:179], v[212:215], v[96:111]
	v_mfma_f32_32x32x16_bf16 v[32:47], v[180:183], v[212:215], v[32:47]
	ds_read_b128 v[208:211], v149 offset:9248
	ds_read_b128 v[212:215], v149 offset:13856
	s_waitcnt vmcnt(7)
	ds_write_b128 v148, v[168:171] offset:18432
	s_waitcnt vmcnt(6)
	ds_write_b128 v148, v[172:175] offset:55296
	ds_read_b128 v[168:171], v150 offset:64
	ds_read_b128 v[172:175], v150 offset:4672
	s_waitcnt lgkmcnt(5)
	v_mfma_f32_32x32x16_bf16 v[80:95], v[176:179], v[208:211], v[80:95]
	v_mfma_f32_32x32x16_bf16 v[16:31], v[180:183], v[208:211], v[16:31]
	ds_read_b128 v[208:211], v149 offset:64
	s_waitcnt lgkmcnt(5)
	v_mfma_f32_32x32x16_bf16 v[64:79], v[176:179], v[212:215], v[64:79]
	v_mfma_f32_32x32x16_bf16 v[0:15], v[180:183], v[212:215], v[0:15]
	ds_read_b128 v[212:215], v149 offset:4672
	s_setprio 0
	global_load_dwordx4 v[176:179], v[132:133], off offset:2176
	global_load_dwordx4 v[180:183], v[134:135], off offset:2176
	s_setprio 1
	s_waitcnt lgkmcnt(1)
	v_mfma_f32_32x32x16_bf16 v[112:127], v[168:171], v[208:211], v[112:127]
	v_mfma_f32_32x32x16_bf16 v[48:63], v[172:175], v[208:211], v[48:63]
	s_waitcnt lgkmcnt(0)
	v_mfma_f32_32x32x16_bf16 v[96:111], v[168:171], v[212:215], v[96:111]
	v_mfma_f32_32x32x16_bf16 v[32:47], v[172:175], v[212:215], v[32:47]
	ds_read_b128 v[208:211], v149 offset:9280
	ds_read_b128 v[212:215], v149 offset:13888
	s_waitcnt vmcnt(7)
	ds_write_b128 v148, v[160:163] offset:27648
	s_waitcnt vmcnt(6)
	ds_write_b128 v148, v[164:167] offset:64512
	ds_read_b128 v[160:163], v150 offset:96
	ds_read_b128 v[164:167], v150 offset:4704
	s_waitcnt lgkmcnt(5)
	v_mfma_f32_32x32x16_bf16 v[80:95], v[168:171], v[208:211], v[80:95]
	v_mfma_f32_32x32x16_bf16 v[16:31], v[172:175], v[208:211], v[16:31]
	ds_read_b128 v[208:211], v149 offset:96
	s_waitcnt lgkmcnt(5)
	v_mfma_f32_32x32x16_bf16 v[64:79], v[168:171], v[212:215], v[64:79]
	v_mfma_f32_32x32x16_bf16 v[0:15], v[172:175], v[212:215], v[0:15]
	ds_read_b128 v[212:215], v149 offset:4704
	s_setprio 0
	global_load_dwordx4 v[168:171], v[144:145], off offset:2176
	global_load_dwordx4 v[172:175], v[146:147], off offset:2176
	s_setprio 1
	s_waitcnt lgkmcnt(1)
	v_mfma_f32_32x32x16_bf16 v[112:127], v[160:163], v[208:211], v[112:127]
	v_mfma_f32_32x32x16_bf16 v[48:63], v[164:167], v[208:211], v[48:63]
	s_waitcnt lgkmcnt(0)
	v_mfma_f32_32x32x16_bf16 v[96:111], v[160:163], v[212:215], v[96:111]
	v_mfma_f32_32x32x16_bf16 v[32:47], v[164:167], v[212:215], v[32:47]
	ds_read_b128 v[208:211], v149 offset:9312
	ds_read_b128 v[212:215], v149 offset:13920
	s_waitcnt lgkmcnt(1)
	v_mfma_f32_32x32x16_bf16 v[80:95], v[160:163], v[208:211], v[80:95]
	v_mfma_f32_32x32x16_bf16 v[16:31], v[164:167], v[208:211], v[16:31]
	s_waitcnt lgkmcnt(0)
	v_mfma_f32_32x32x16_bf16 v[64:79], v[160:163], v[212:215], v[64:79]
	v_mfma_f32_32x32x16_bf16 v[0:15], v[164:167], v[212:215], v[0:15]
	s_setprio 0
	s_barrier
; template <bool trans>
; DI void gemm_core(const GTile& tl, const GTile& nx, bool has_next  , bool chain  , bool pre, u32x4 (&ra)[4], u32x4 (&rb)[4], char* smem, f32x16 (&acc)[2][4]) {
;     ...
;   const int nk = K / 64;
;   if (!pre) { G_LOAD(0); G_STORE(0); G_LOAD(1); }
;   for (int kt = 0; kt < nk; ++kt) {
;     __syncthreads();
;     G_COMPUTE(kt & 1, kt);
	global_load_dwordx4 v[160:163], v[136:137], off offset:2304
	global_load_dwordx4 v[164:167], v[138:139], off offset:2304
	s_waitcnt vmcnt(9)
	ds_write_b128 v192, v[184:187]
	s_waitcnt vmcnt(8)
	ds_write_b128 v159, v[188:191]
	ds_read_b128 v[184:187], v152 offset:36864
	ds_read_b128 v[188:191], v152 offset:41472
	ds_read_b128 v[208:211], v151
	ds_read_b128 v[212:215], v151 offset:4608
	s_setprio 1
	s_waitcnt lgkmcnt(1)
	v_mfma_f32_32x32x16_bf16 v[112:127], v[184:187], v[208:211], v[112:127]
	v_mfma_f32_32x32x16_bf16 v[48:63], v[188:191], v[208:211], v[48:63]
	s_waitcnt lgkmcnt(0)
	v_mfma_f32_32x32x16_bf16 v[96:111], v[184:187], v[212:215], v[96:111]
	v_mfma_f32_32x32x16_bf16 v[32:47], v[188:191], v[212:215], v[32:47]
	ds_read_b128 v[208:211], v151 offset:9216
	ds_read_b128 v[212:215], v151 offset:13824
	s_waitcnt vmcnt(7)
	ds_write_b128 v158, v[194:197]
	s_waitcnt vmcnt(6)
	ds_write_b128 v157, v[198:201]
	ds_read_b128 v[194:197], v152 offset:36896
	ds_read_b128 v[198:201], v152 offset:41504
	s_waitcnt lgkmcnt(5)
	v_mfma_f32_32x32x16_bf16 v[80:95], v[184:187], v[208:211], v[80:95]
	v_mfma_f32_32x32x16_bf16 v[16:31], v[188:191], v[208:211], v[16:31]
	ds_read_b128 v[208:211], v151 offset:32
	s_waitcnt lgkmcnt(5)
	v_mfma_f32_32x32x16_bf16 v[64:79], v[184:187], v[212:215], v[64:79]
	v_mfma_f32_32x32x16_bf16 v[0:15], v[188:191], v[212:215], v[0:15]
	ds_read_b128 v[212:215], v151 offset:4640
	s_setprio 0
	global_load_dwordx4 v[184:187], v[140:141], off offset:2304
	global_load_dwordx4 v[188:191], v[142:143], off offset:2304
	s_setprio 1
	s_waitcnt lgkmcnt(1)
	v_mfma_f32_32x32x16_bf16 v[112:127], v[194:197], v[208:211], v[112:127]
	v_mfma_f32_32x32x16_bf16 v[48:63], v[198:201], v[208:211], v[48:63]
	s_waitcnt lgkmcnt(0)
	v_mfma_f32_32x32x16_bf16 v[96:111], v[194:197], v[212:215], v[96:111]
	v_mfma_f32_32x32x16_bf16 v[32:47], v[198:201], v[212:215], v[32:47]
	ds_read_b128 v[208:211], v151 offset:9248
	ds_read_b128 v[212:215], v151 offset:13856
	s_waitcnt vmcnt(7)
	ds_write_b128 v154, v[176:179]
	s_waitcnt vmcnt(6)
	ds_write_b128 v153, v[180:183]
	ds_read_b128 v[176:179], v152 offset:36928
	ds_read_b128 v[180:183], v152 offset:41536
	s_waitcnt lgkmcnt(5)
	v_mfma_f32_32x32x16_bf16 v[80:95], v[194:197], v[208:211], v[80:95]
	v_mfma_f32_32x32x16_bf16 v[16:31], v[198:201], v[208:211], v[16:31]
	ds_read_b128 v[208:211], v151 offset:64
	s_waitcnt lgkmcnt(5)
	v_mfma_f32_32x32x16_bf16 v[64:79], v[194:197], v[212:215], v[64:79]
	v_mfma_f32_32x32x16_bf16 v[0:15], v[198:201], v[212:215], v[0:15]
	ds_read_b128 v[212:215], v151 offset:4672
	s_setprio 0
	global_load_dwordx4 v[194:197], v[132:133], off offset:2304
	global_load_dwordx4 v[198:201], v[134:135], off offset:2304
	s_setprio 1
	s_waitcnt lgkmcnt(1)
	v_mfma_f32_32x32x16_bf16 v[112:127], v[176:179], v[208:211], v[112:127]
	v_mfma_f32_32x32x16_bf16 v[48:63], v[180:183], v[208:211], v[48:63]
	s_waitcnt lgkmcnt(0)
	v_mfma_f32_32x32x16_bf16 v[96:111], v[176:179], v[212:215], v[96:111]
	v_mfma_f32_32x32x16_bf16 v[32:47], v[180:183], v[212:215], v[32:47]
	ds_read_b128 v[208:211], v151 offset:9280
	ds_read_b128 v[212:215], v151 offset:13888
	s_waitcnt vmcnt(7)
	ds_write_b128 v156, v[168:171]
	s_waitcnt vmcnt(6)
	ds_write_b128 v155, v[172:175]
	ds_read_b128 v[168:171], v152 offset:36960
	ds_read_b128 v[172:175], v152 offset:41568
	s_waitcnt lgkmcnt(5)
	v_mfma_f32_32x32x16_bf16 v[80:95], v[176:179], v[208:211], v[80:95]
	v_mfma_f32_32x32x16_bf16 v[16:31], v[180:183], v[208:211], v[16:31]
	ds_read_b128 v[208:211], v151 offset:96
	s_waitcnt lgkmcnt(5)
	v_mfma_f32_32x32x16_bf16 v[64:79], v[176:179], v[212:215], v[64:79]
	v_mfma_f32_32x32x16_bf16 v[0:15], v[180:183], v[212:215], v[0:15]
	ds_read_b128 v[212:215], v151 offset:4704
	s_setprio 0
	global_load_dwordx4 v[176:179], v[144:145], off offset:2304
	global_load_dwordx4 v[180:183], v[146:147], off offset:2304
	s_setprio 1
	s_waitcnt lgkmcnt(1)
	v_mfma_f32_32x32x16_bf16 v[112:127], v[168:171], v[208:211], v[112:127]
	v_mfma_f32_32x32x16_bf16 v[48:63], v[172:175], v[208:211], v[48:63]
	s_waitcnt lgkmcnt(0)
	v_mfma_f32_32x32x16_bf16 v[96:111], v[168:171], v[212:215], v[96:111]
	v_mfma_f32_32x32x16_bf16 v[32:47], v[172:175], v[212:215], v[32:47]
	ds_read_b128 v[208:211], v151 offset:9312
	ds_read_b128 v[212:215], v151 offset:13920
	s_waitcnt lgkmcnt(1)
	v_mfma_f32_32x32x16_bf16 v[80:95], v[168:171], v[208:211], v[80:95]
	v_mfma_f32_32x32x16_bf16 v[16:31], v[172:175], v[208:211], v[16:31]
	s_waitcnt lgkmcnt(0)
	v_mfma_f32_32x32x16_bf16 v[64:79], v[168:171], v[212:215], v[64:79]
	v_mfma_f32_32x32x16_bf16 v[0:15], v[172:175], v[212:215], v[0:15]
	s_setprio 0
	s_barrier
; template <bool trans>
; DI void gemm_core(const GTile& tl, const GTile& nx, bool has_next  , bool chain  , bool pre, u32x4 (&ra)[4], u32x4 (&rb)[4], char* smem, f32x16 (&acc)[2][4]) {
;     ...
;   const int nk = K / 64;
;   if (!pre) { G_LOAD(0); G_STORE(0); G_LOAD(1); }
;   for (int kt = 0; kt < nk; ++kt) {
;     __syncthreads();
;     G_COMPUTE(kt & 1, kt);
	global_load_dwordx4 v[168:171], v[136:137], off offset:2432
	global_load_dwordx4 v[172:175], v[138:139], off offset:2432
	s_waitcnt vmcnt(9)
	ds_write_b128 v148, v[160:163]
	s_waitcnt vmcnt(8)
	ds_write_b128 v148, v[164:167] offset:36864
	ds_read_b128 v[160:163], v150
	ds_read_b128 v[164:167], v150 offset:4608
	ds_read_b128 v[208:211], v149
	ds_read_b128 v[212:215], v149 offset:4608
	s_setprio 1
	s_waitcnt lgkmcnt(1)
	v_mfma_f32_32x32x16_bf16 v[112:127], v[160:163], v[208:211], v[112:127]
	v_mfma_f32_32x32x16_bf16 v[48:63], v[164:167], v[208:211], v[48:63]
	s_waitcnt lgkmcnt(0)
	v_mfma_f32_32x32x16_bf16 v[96:111], v[160:163], v[212:215], v[96:111]
	v_mfma_f32_32x32x16_bf16 v[32:47], v[164:167], v[212:215], v[32:47]
	ds_read_b128 v[208:211], v149 offset:9216
	ds_read_b128 v[212:215], v149 offset:13824
	s_waitcnt vmcnt(7)
	ds_write_b128 v148, v[184:187] offset:9216
	s_waitcnt vmcnt(6)
	ds_write_b128 v148, v[188:191] offset:46080
	ds_read_b128 v[184:187], v150 offset:32
	ds_read_b128 v[188:191], v150 offset:4640
	s_waitcnt lgkmcnt(5)
	v_mfma_f32_32x32x16_bf16 v[80:95], v[160:163], v[208:211], v[80:95]
	v_mfma_f32_32x32x16_bf16 v[16:31], v[164:167], v[208:211], v[16:31]
	ds_read_b128 v[208:211], v149 offset:32
	s_waitcnt lgkmcnt(5)
	v_mfma_f32_32x32x16_bf16 v[64:79], v[160:163], v[212:215], v[64:79]
	v_mfma_f32_32x32x16_bf16 v[0:15], v[164:167], v[212:215], v[0:15]
	ds_read_b128 v[212:215], v149 offset:4640
	s_setprio 0
	global_load_dwordx4 v[160:163], v[140:141], off offset:2432
	global_load_dwordx4 v[164:167], v[142:143], off offset:2432
	s_setprio 1
	s_waitcnt lgkmcnt(1)
	v_mfma_f32_32x32x16_bf16 v[112:127], v[184:187], v[208:211], v[112:127]
	v_mfma_f32_32x32x16_bf16 v[48:63], v[188:191], v[208:211], v[48:63]
	s_waitcnt lgkmcnt(0)
	v_mfma_f32_32x32x16_bf16 v[96:111], v[184:187], v[212:215], v[96:111]
	v_mfma_f32_32x32x16_bf16 v[32:47], v[188:191], v[212:215], v[32:47]
	ds_read_b128 v[208:211], v149 offset:9248
	ds_read_b128 v[212:215], v149 offset:13856
	s_waitcnt vmcnt(7)
	ds_write_b128 v148, v[194:197] offset:18432
	s_waitcnt vmcnt(6)
	ds_write_b128 v148, v[198:201] offset:55296
	ds_read_b128 v[194:197], v150 offset:64
	ds_read_b128 v[198:201], v150 offset:4672
	s_waitcnt lgkmcnt(5)
	v_mfma_f32_32x32x16_bf16 v[80:95], v[184:187], v[208:211], v[80:95]
	v_mfma_f32_32x32x16_bf16 v[16:31], v[188:191], v[208:211], v[16:31]
	ds_read_b128 v[208:211], v149 offset:64
	s_waitcnt lgkmcnt(5)
	v_mfma_f32_32x32x16_bf16 v[64:79], v[184:187], v[212:215], v[64:79]
	v_mfma_f32_32x32x16_bf16 v[0:15], v[188:191], v[212:215], v[0:15]
	ds_read_b128 v[212:215], v149 offset:4672
	s_setprio 0
	global_load_dwordx4 v[184:187], v[132:133], off offset:2432
	global_load_dwordx4 v[188:191], v[134:135], off offset:2432
	s_setprio 1
	s_waitcnt lgkmcnt(1)
	v_mfma_f32_32x32x16_bf16 v[112:127], v[194:197], v[208:211], v[112:127]
	v_mfma_f32_32x32x16_bf16 v[48:63], v[198:201], v[208:211], v[48:63]
	s_waitcnt lgkmcnt(0)
	v_mfma_f32_32x32x16_bf16 v[96:111], v[194:197], v[212:215], v[96:111]
	v_mfma_f32_32x32x16_bf16 v[32:47], v[198:201], v[212:215], v[32:47]
	ds_read_b128 v[208:211], v149 offset:9280
	ds_read_b128 v[212:215], v149 offset:13888
	s_waitcnt vmcnt(7)
	ds_write_b128 v148, v[176:179] offset:27648
	s_waitcnt vmcnt(6)
	ds_write_b128 v148, v[180:183] offset:64512
	ds_read_b128 v[176:179], v150 offset:96
	ds_read_b128 v[180:183], v150 offset:4704
	s_waitcnt lgkmcnt(5)
	v_mfma_f32_32x32x16_bf16 v[80:95], v[194:197], v[208:211], v[80:95]
	v_mfma_f32_32x32x16_bf16 v[16:31], v[198:201], v[208:211], v[16:31]
	ds_read_b128 v[208:211], v149 offset:96
	s_waitcnt lgkmcnt(5)
	v_mfma_f32_32x32x16_bf16 v[64:79], v[194:197], v[212:215], v[64:79]
	v_mfma_f32_32x32x16_bf16 v[0:15], v[198:201], v[212:215], v[0:15]
	ds_read_b128 v[212:215], v149 offset:4704
	s_setprio 0
	global_load_dwordx4 v[194:197], v[144:145], off offset:2432
	global_load_dwordx4 v[198:201], v[146:147], off offset:2432
	s_setprio 1
	s_waitcnt lgkmcnt(1)
	v_mfma_f32_32x32x16_bf16 v[112:127], v[176:179], v[208:211], v[112:127]
	v_mfma_f32_32x32x16_bf16 v[48:63], v[180:183], v[208:211], v[48:63]
	s_waitcnt lgkmcnt(0)
	v_mfma_f32_32x32x16_bf16 v[96:111], v[176:179], v[212:215], v[96:111]
	v_mfma_f32_32x32x16_bf16 v[32:47], v[180:183], v[212:215], v[32:47]
	ds_read_b128 v[208:211], v149 offset:9312
	ds_read_b128 v[212:215], v149 offset:13920
	s_waitcnt lgkmcnt(1)
	v_mfma_f32_32x32x16_bf16 v[80:95], v[176:179], v[208:211], v[80:95]
	v_mfma_f32_32x32x16_bf16 v[16:31], v[180:183], v[208:211], v[16:31]
	s_waitcnt lgkmcnt(0)
	v_mfma_f32_32x32x16_bf16 v[64:79], v[176:179], v[212:215], v[64:79]
	v_mfma_f32_32x32x16_bf16 v[0:15], v[180:183], v[212:215], v[0:15]
	s_setprio 0
	s_barrier
; template <bool trans>
; DI void gemm_core(const GTile& tl, const GTile& nx, bool has_next  , bool chain  , bool pre, u32x4 (&ra)[4], u32x4 (&rb)[4], char* smem, f32x16 (&acc)[2][4]) {
;     ...
;   const int nk = K / 64;
;   if (!pre) { G_LOAD(0); G_STORE(0); G_LOAD(1); }
;   for (int kt = 0; kt < nk; ++kt) {
;     __syncthreads();
;     G_COMPUTE(kt & 1, kt);
	global_load_dwordx4 v[176:179], v[136:137], off offset:2560
	global_load_dwordx4 v[180:183], v[138:139], off offset:2560
	s_waitcnt vmcnt(9)
	ds_write_b128 v192, v[168:171]
	s_waitcnt vmcnt(8)
	ds_write_b128 v159, v[172:175]
	ds_read_b128 v[168:171], v152 offset:36864
	ds_read_b128 v[172:175], v152 offset:41472
	ds_read_b128 v[208:211], v151
	ds_read_b128 v[212:215], v151 offset:4608
	s_setprio 1
	s_waitcnt lgkmcnt(1)
	v_mfma_f32_32x32x16_bf16 v[112:127], v[168:171], v[208:211], v[112:127]
	v_mfma_f32_32x32x16_bf16 v[48:63], v[172:175], v[208:211], v[48:63]
	s_waitcnt lgkmcnt(0)
	v_mfma_f32_32x32x16_bf16 v[96:111], v[168:171], v[212:215], v[96:111]
	v_mfma_f32_32x32x16_bf16 v[32:47], v[172:175], v[212:215], v[32:47]
	ds_read_b128 v[208:211], v151 offset:9216
	ds_read_b128 v[212:215], v151 offset:13824
	s_waitcnt vmcnt(7)
	ds_write_b128 v158, v[160:163]
	s_waitcnt vmcnt(6)
	ds_write_b128 v157, v[164:167]
	ds_read_b128 v[160:163], v152 offset:36896
	ds_read_b128 v[164:167], v152 offset:41504
	s_waitcnt lgkmcnt(5)
	v_mfma_f32_32x32x16_bf16 v[80:95], v[168:171], v[208:211], v[80:95]
	v_mfma_f32_32x32x16_bf16 v[16:31], v[172:175], v[208:211], v[16:31]
	ds_read_b128 v[208:211], v151 offset:32
	s_waitcnt lgkmcnt(5)
	v_mfma_f32_32x32x16_bf16 v[64:79], v[168:171], v[212:215], v[64:79]
	v_mfma_f32_32x32x16_bf16 v[0:15], v[172:175], v[212:215], v[0:15]
	ds_read_b128 v[212:215], v151 offset:4640
	s_setprio 0
	global_load_dwordx4 v[168:171], v[140:141], off offset:2560
	global_load_dwordx4 v[172:175], v[142:143], off offset:2560
	s_setprio 1
	s_waitcnt lgkmcnt(1)
	v_mfma_f32_32x32x16_bf16 v[112:127], v[160:163], v[208:211], v[112:127]
	v_mfma_f32_32x32x16_bf16 v[48:63], v[164:167], v[208:211], v[48:63]
	s_waitcnt lgkmcnt(0)
	v_mfma_f32_32x32x16_bf16 v[96:111], v[160:163], v[212:215], v[96:111]
	v_mfma_f32_32x32x16_bf16 v[32:47], v[164:167], v[212:215], v[32:47]
	ds_read_b128 v[208:211], v151 offset:9248
	ds_read_b128 v[212:215], v151 offset:13856
	s_waitcnt vmcnt(7)
	ds_write_b128 v154, v[184:187]
	s_waitcnt vmcnt(6)
	ds_write_b128 v153, v[188:191]
	ds_read_b128 v[184:187], v152 offset:36928
	ds_read_b128 v[188:191], v152 offset:41536
	s_waitcnt lgkmcnt(5)
	v_mfma_f32_32x32x16_bf16 v[80:95], v[160:163], v[208:211], v[80:95]
	v_mfma_f32_32x32x16_bf16 v[16:31], v[164:167], v[208:211], v[16:31]
	ds_read_b128 v[208:211], v151 offset:64
	s_waitcnt lgkmcnt(5)
	v_mfma_f32_32x32x16_bf16 v[64:79], v[160:163], v[212:215], v[64:79]
	v_mfma_f32_32x32x16_bf16 v[0:15], v[164:167], v[212:215], v[0:15]
	ds_read_b128 v[212:215], v151 offset:4672
	s_setprio 0
	global_load_dwordx4 v[160:163], v[132:133], off offset:2560
	global_load_dwordx4 v[164:167], v[134:135], off offset:2560
	s_setprio 1
	s_waitcnt lgkmcnt(1)
	v_mfma_f32_32x32x16_bf16 v[112:127], v[184:187], v[208:211], v[112:127]
	v_mfma_f32_32x32x16_bf16 v[48:63], v[188:191], v[208:211], v[48:63]
	s_waitcnt lgkmcnt(0)
	v_mfma_f32_32x32x16_bf16 v[96:111], v[184:187], v[212:215], v[96:111]
	v_mfma_f32_32x32x16_bf16 v[32:47], v[188:191], v[212:215], v[32:47]
	ds_read_b128 v[208:211], v151 offset:9280
	ds_read_b128 v[212:215], v151 offset:13888
	s_waitcnt vmcnt(7)
	ds_write_b128 v156, v[194:197]
	s_waitcnt vmcnt(6)
	ds_write_b128 v155, v[198:201]
	ds_read_b128 v[194:197], v152 offset:36960
	ds_read_b128 v[198:201], v152 offset:41568
	s_waitcnt lgkmcnt(5)
	v_mfma_f32_32x32x16_bf16 v[80:95], v[184:187], v[208:211], v[80:95]
	v_mfma_f32_32x32x16_bf16 v[16:31], v[188:191], v[208:211], v[16:31]
	ds_read_b128 v[208:211], v151 offset:96
	s_waitcnt lgkmcnt(5)
	v_mfma_f32_32x32x16_bf16 v[64:79], v[184:187], v[212:215], v[64:79]
	v_mfma_f32_32x32x16_bf16 v[0:15], v[188:191], v[212:215], v[0:15]
	ds_read_b128 v[212:215], v151 offset:4704
	s_setprio 0
	global_load_dwordx4 v[184:187], v[144:145], off offset:2560
	global_load_dwordx4 v[188:191], v[146:147], off offset:2560
	s_setprio 1
	s_waitcnt lgkmcnt(1)
	v_mfma_f32_32x32x16_bf16 v[112:127], v[194:197], v[208:211], v[112:127]
	v_mfma_f32_32x32x16_bf16 v[48:63], v[198:201], v[208:211], v[48:63]
	s_waitcnt lgkmcnt(0)
	v_mfma_f32_32x32x16_bf16 v[96:111], v[194:197], v[212:215], v[96:111]
	v_mfma_f32_32x32x16_bf16 v[32:47], v[198:201], v[212:215], v[32:47]
	ds_read_b128 v[208:211], v151 offset:9312
	ds_read_b128 v[212:215], v151 offset:13920
	s_waitcnt lgkmcnt(1)
	v_mfma_f32_32x32x16_bf16 v[80:95], v[194:197], v[208:211], v[80:95]
	v_mfma_f32_32x32x16_bf16 v[16:31], v[198:201], v[208:211], v[16:31]
	s_waitcnt lgkmcnt(0)
	v_mfma_f32_32x32x16_bf16 v[64:79], v[194:197], v[212:215], v[64:79]
	v_mfma_f32_32x32x16_bf16 v[0:15], v[198:201], v[212:215], v[0:15]
	s_setprio 0
	s_barrier
; template <bool trans>
; DI void gemm_core(const GTile& tl, const GTile& nx, bool has_next  , bool chain  , bool pre, u32x4 (&ra)[4], u32x4 (&rb)[4], char* smem, f32x16 (&acc)[2][4]) {
;     ...
;   const int nk = K / 64;
;   if (!pre) { G_LOAD(0); G_STORE(0); G_LOAD(1); }
;   for (int kt = 0; kt < nk; ++kt) {
;     __syncthreads();
;     G_COMPUTE(kt & 1, kt);
	global_load_dwordx4 v[194:197], v[136:137], off offset:2688
	global_load_dwordx4 v[198:201], v[138:139], off offset:2688
	s_waitcnt vmcnt(9)
	ds_write_b128 v148, v[176:179]
	s_waitcnt vmcnt(8)
	ds_write_b128 v148, v[180:183] offset:36864
	ds_read_b128 v[176:179], v150
	ds_read_b128 v[180:183], v150 offset:4608
	ds_read_b128 v[208:211], v149
	ds_read_b128 v[212:215], v149 offset:4608
	s_setprio 1
	s_waitcnt lgkmcnt(1)
	v_mfma_f32_32x32x16_bf16 v[112:127], v[176:179], v[208:211], v[112:127]
	v_mfma_f32_32x32x16_bf16 v[48:63], v[180:183], v[208:211], v[48:63]
	s_waitcnt lgkmcnt(0)
	v_mfma_f32_32x32x16_bf16 v[96:111], v[176:179], v[212:215], v[96:111]
	v_mfma_f32_32x32x16_bf16 v[32:47], v[180:183], v[212:215], v[32:47]
	ds_read_b128 v[208:211], v149 offset:9216
	ds_read_b128 v[212:215], v149 offset:13824
	s_waitcnt vmcnt(7)
	ds_write_b128 v148, v[168:171] offset:9216
	s_waitcnt vmcnt(6)
	ds_write_b128 v148, v[172:175] offset:46080
	ds_read_b128 v[168:171], v150 offset:32
	ds_read_b128 v[172:175], v150 offset:4640
	s_waitcnt lgkmcnt(5)
	v_mfma_f32_32x32x16_bf16 v[80:95], v[176:179], v[208:211], v[80:95]
	v_mfma_f32_32x32x16_bf16 v[16:31], v[180:183], v[208:211], v[16:31]
	ds_read_b128 v[208:211], v149 offset:32
	s_waitcnt lgkmcnt(5)
	v_mfma_f32_32x32x16_bf16 v[64:79], v[176:179], v[212:215], v[64:79]
	v_mfma_f32_32x32x16_bf16 v[0:15], v[180:183], v[212:215], v[0:15]
	ds_read_b128 v[212:215], v149 offset:4640
	s_setprio 0
	global_load_dwordx4 v[176:179], v[140:141], off offset:2688
	global_load_dwordx4 v[180:183], v[142:143], off offset:2688
	s_setprio 1
	s_waitcnt lgkmcnt(1)
	v_mfma_f32_32x32x16_bf16 v[112:127], v[168:171], v[208:211], v[112:127]
	v_mfma_f32_32x32x16_bf16 v[48:63], v[172:175], v[208:211], v[48:63]
	s_waitcnt lgkmcnt(0)
	v_mfma_f32_32x32x16_bf16 v[96:111], v[168:171], v[212:215], v[96:111]
	v_mfma_f32_32x32x16_bf16 v[32:47], v[172:175], v[212:215], v[32:47]
	ds_read_b128 v[208:211], v149 offset:9248
	ds_read_b128 v[212:215], v149 offset:13856
	s_waitcnt vmcnt(7)
	ds_write_b128 v148, v[160:163] offset:18432
	s_waitcnt vmcnt(6)
	ds_write_b128 v148, v[164:167] offset:55296
	ds_read_b128 v[160:163], v150 offset:64
	ds_read_b128 v[164:167], v150 offset:4672
	s_waitcnt lgkmcnt(5)
	v_mfma_f32_32x32x16_bf16 v[80:95], v[168:171], v[208:211], v[80:95]
	v_mfma_f32_32x32x16_bf16 v[16:31], v[172:175], v[208:211], v[16:31]
	ds_read_b128 v[208:211], v149 offset:64
	s_waitcnt lgkmcnt(5)
	v_mfma_f32_32x32x16_bf16 v[64:79], v[168:171], v[212:215], v[64:79]
	v_mfma_f32_32x32x16_bf16 v[0:15], v[172:175], v[212:215], v[0:15]
	ds_read_b128 v[212:215], v149 offset:4672
	s_setprio 0
	global_load_dwordx4 v[168:171], v[132:133], off offset:2688
	global_load_dwordx4 v[172:175], v[134:135], off offset:2688
	s_setprio 1
	s_waitcnt lgkmcnt(1)
	v_mfma_f32_32x32x16_bf16 v[112:127], v[160:163], v[208:211], v[112:127]
	v_mfma_f32_32x32x16_bf16 v[48:63], v[164:167], v[208:211], v[48:63]
	s_waitcnt lgkmcnt(0)
	v_mfma_f32_32x32x16_bf16 v[96:111], v[160:163], v[212:215], v[96:111]
	v_mfma_f32_32x32x16_bf16 v[32:47], v[164:167], v[212:215], v[32:47]
	ds_read_b128 v[208:211], v149 offset:9280
	ds_read_b128 v[212:215], v149 offset:13888
	s_waitcnt vmcnt(7)
	ds_write_b128 v148, v[184:187] offset:27648
	s_waitcnt vmcnt(6)
	ds_write_b128 v148, v[188:191] offset:64512
	ds_read_b128 v[184:187], v150 offset:96
	ds_read_b128 v[188:191], v150 offset:4704
	s_waitcnt lgkmcnt(5)
	v_mfma_f32_32x32x16_bf16 v[80:95], v[160:163], v[208:211], v[80:95]
	v_mfma_f32_32x32x16_bf16 v[16:31], v[164:167], v[208:211], v[16:31]
	ds_read_b128 v[208:211], v149 offset:96
	s_waitcnt lgkmcnt(5)
	v_mfma_f32_32x32x16_bf16 v[64:79], v[160:163], v[212:215], v[64:79]
	v_mfma_f32_32x32x16_bf16 v[0:15], v[164:167], v[212:215], v[0:15]
	ds_read_b128 v[212:215], v149 offset:4704
	s_setprio 0
	global_load_dwordx4 v[160:163], v[144:145], off offset:2688
	global_load_dwordx4 v[164:167], v[146:147], off offset:2688
	s_setprio 1
	s_waitcnt lgkmcnt(1)
	v_mfma_f32_32x32x16_bf16 v[112:127], v[184:187], v[208:211], v[112:127]
	v_mfma_f32_32x32x16_bf16 v[48:63], v[188:191], v[208:211], v[48:63]
	s_waitcnt lgkmcnt(0)
	v_mfma_f32_32x32x16_bf16 v[96:111], v[184:187], v[212:215], v[96:111]
	v_mfma_f32_32x32x16_bf16 v[32:47], v[188:191], v[212:215], v[32:47]
	ds_read_b128 v[208:211], v149 offset:9312
	ds_read_b128 v[212:215], v149 offset:13920
	s_waitcnt lgkmcnt(1)
	v_mfma_f32_32x32x16_bf16 v[80:95], v[184:187], v[208:211], v[80:95]
	v_mfma_f32_32x32x16_bf16 v[16:31], v[188:191], v[208:211], v[16:31]
	s_waitcnt lgkmcnt(0)
	v_mfma_f32_32x32x16_bf16 v[64:79], v[184:187], v[212:215], v[64:79]
	v_mfma_f32_32x32x16_bf16 v[0:15], v[188:191], v[212:215], v[0:15]
	s_setprio 0
	s_barrier
; template <bool trans>
; DI void gemm_core(const GTile& tl, const GTile& nx, bool has_next  , bool chain  , bool pre, u32x4 (&ra)[4], u32x4 (&rb)[4], char* smem, f32x16 (&acc)[2][4]) {
;     ...
;   const int nk = K / 64;
;   if (!pre) { G_LOAD(0); G_STORE(0); G_LOAD(1); }
;   for (int kt = 0; kt < nk; ++kt) {
;     __syncthreads();
;     G_COMPUTE(kt & 1, kt);
	global_load_dwordx4 v[184:187], v[136:137], off offset:2816
	global_load_dwordx4 v[188:191], v[138:139], off offset:2816
	s_waitcnt vmcnt(9)
	ds_write_b128 v192, v[194:197]
	s_waitcnt vmcnt(8)
	ds_write_b128 v159, v[198:201]
	ds_read_b128 v[194:197], v152 offset:36864
	ds_read_b128 v[198:201], v152 offset:41472
	ds_read_b128 v[208:211], v151
	ds_read_b128 v[212:215], v151 offset:4608
	s_setprio 1
	s_waitcnt lgkmcnt(1)
	v_mfma_f32_32x32x16_bf16 v[112:127], v[194:197], v[208:211], v[112:127]
	v_mfma_f32_32x32x16_bf16 v[48:63], v[198:201], v[208:211], v[48:63]
	s_waitcnt lgkmcnt(0)
	v_mfma_f32_32x32x16_bf16 v[96:111], v[194:197], v[212:215], v[96:111]
	v_mfma_f32_32x32x16_bf16 v[32:47], v[198:201], v[212:215], v[32:47]
	ds_read_b128 v[208:211], v151 offset:9216
	ds_read_b128 v[212:215], v151 offset:13824
	s_waitcnt vmcnt(7)
	ds_write_b128 v158, v[176:179]
	s_waitcnt vmcnt(6)
	ds_write_b128 v157, v[180:183]
	ds_read_b128 v[176:179], v152 offset:36896
	ds_read_b128 v[180:183], v152 offset:41504
	s_waitcnt lgkmcnt(5)
	v_mfma_f32_32x32x16_bf16 v[80:95], v[194:197], v[208:211], v[80:95]
	v_mfma_f32_32x32x16_bf16 v[16:31], v[198:201], v[208:211], v[16:31]
	ds_read_b128 v[208:211], v151 offset:32
	s_waitcnt lgkmcnt(5)
	v_mfma_f32_32x32x16_bf16 v[64:79], v[194:197], v[212:215], v[64:79]
	v_mfma_f32_32x32x16_bf16 v[0:15], v[198:201], v[212:215], v[0:15]
	ds_read_b128 v[212:215], v151 offset:4640
	s_setprio 0
	global_load_dwordx4 v[194:197], v[140:141], off offset:2816
	global_load_dwordx4 v[198:201], v[142:143], off offset:2816
	s_setprio 1
	s_waitcnt lgkmcnt(1)
	v_mfma_f32_32x32x16_bf16 v[112:127], v[176:179], v[208:211], v[112:127]
	v_mfma_f32_32x32x16_bf16 v[48:63], v[180:183], v[208:211], v[48:63]
	s_waitcnt lgkmcnt(0)
	v_mfma_f32_32x32x16_bf16 v[96:111], v[176:179], v[212:215], v[96:111]
	v_mfma_f32_32x32x16_bf16 v[32:47], v[180:183], v[212:215], v[32:47]
	ds_read_b128 v[208:211], v151 offset:9248
	ds_read_b128 v[212:215], v151 offset:13856
	s_waitcnt vmcnt(7)
	ds_write_b128 v154, v[168:171]
	s_waitcnt vmcnt(6)
	ds_write_b128 v153, v[172:175]
	ds_read_b128 v[168:171], v152 offset:36928
	ds_read_b128 v[172:175], v152 offset:41536
	s_waitcnt lgkmcnt(5)
	v_mfma_f32_32x32x16_bf16 v[80:95], v[176:179], v[208:211], v[80:95]
	v_mfma_f32_32x32x16_bf16 v[16:31], v[180:183], v[208:211], v[16:31]
	ds_read_b128 v[208:211], v151 offset:64
	s_waitcnt lgkmcnt(5)
	v_mfma_f32_32x32x16_bf16 v[64:79], v[176:179], v[212:215], v[64:79]
	v_mfma_f32_32x32x16_bf16 v[0:15], v[180:183], v[212:215], v[0:15]
	ds_read_b128 v[212:215], v151 offset:4672
	s_setprio 0
	global_load_dwordx4 v[176:179], v[132:133], off offset:2816
	global_load_dwordx4 v[180:183], v[134:135], off offset:2816
	s_setprio 1
	s_waitcnt lgkmcnt(1)
	v_mfma_f32_32x32x16_bf16 v[112:127], v[168:171], v[208:211], v[112:127]
	v_mfma_f32_32x32x16_bf16 v[48:63], v[172:175], v[208:211], v[48:63]
	s_waitcnt lgkmcnt(0)
	v_mfma_f32_32x32x16_bf16 v[96:111], v[168:171], v[212:215], v[96:111]
	v_mfma_f32_32x32x16_bf16 v[32:47], v[172:175], v[212:215], v[32:47]
	ds_read_b128 v[208:211], v151 offset:9280
	ds_read_b128 v[212:215], v151 offset:13888
	s_waitcnt vmcnt(7)
	ds_write_b128 v156, v[160:163]
	s_waitcnt vmcnt(6)
	ds_write_b128 v155, v[164:167]
	ds_read_b128 v[160:163], v152 offset:36960
	ds_read_b128 v[164:167], v152 offset:41568
	s_waitcnt lgkmcnt(5)
	v_mfma_f32_32x32x16_bf16 v[80:95], v[168:171], v[208:211], v[80:95]
	v_mfma_f32_32x32x16_bf16 v[16:31], v[172:175], v[208:211], v[16:31]
	ds_read_b128 v[208:211], v151 offset:96
	s_waitcnt lgkmcnt(5)
	v_mfma_f32_32x32x16_bf16 v[64:79], v[168:171], v[212:215], v[64:79]
	v_mfma_f32_32x32x16_bf16 v[0:15], v[172:175], v[212:215], v[0:15]
	ds_read_b128 v[212:215], v151 offset:4704
	s_setprio 0
	global_load_dwordx4 v[168:171], v[144:145], off offset:2816
	global_load_dwordx4 v[172:175], v[146:147], off offset:2816
	s_setprio 1
	s_waitcnt lgkmcnt(1)
	v_mfma_f32_32x32x16_bf16 v[112:127], v[160:163], v[208:211], v[112:127]
	v_mfma_f32_32x32x16_bf16 v[48:63], v[164:167], v[208:211], v[48:63]
	s_waitcnt lgkmcnt(0)
	v_mfma_f32_32x32x16_bf16 v[96:111], v[160:163], v[212:215], v[96:111]
	v_mfma_f32_32x32x16_bf16 v[32:47], v[164:167], v[212:215], v[32:47]
	ds_read_b128 v[208:211], v151 offset:9312
	ds_read_b128 v[212:215], v151 offset:13920
	s_waitcnt lgkmcnt(1)
	v_mfma_f32_32x32x16_bf16 v[80:95], v[160:163], v[208:211], v[80:95]
	v_mfma_f32_32x32x16_bf16 v[16:31], v[164:167], v[208:211], v[16:31]
	s_waitcnt lgkmcnt(0)
	v_mfma_f32_32x32x16_bf16 v[64:79], v[160:163], v[212:215], v[64:79]
	v_mfma_f32_32x32x16_bf16 v[0:15], v[164:167], v[212:215], v[0:15]
	s_setprio 0
	s_barrier
; template <bool trans>
; DI void gemm_core(const GTile& tl, const GTile& nx, bool has_next  , bool chain  , bool pre, u32x4 (&ra)[4], u32x4 (&rb)[4], char* smem, f32x16 (&acc)[2][4]) {
;     ...
;   const int nk = K / 64;
;   if (!pre) { G_LOAD(0); G_STORE(0); G_LOAD(1); }
;   for (int kt = 0; kt < nk; ++kt) {
;     __syncthreads();
;     G_COMPUTE(kt & 1, kt);
	global_load_dwordx4 v[160:163], v[136:137], off offset:2944
	global_load_dwordx4 v[164:167], v[138:139], off offset:2944
	s_waitcnt vmcnt(9)
	ds_write_b128 v148, v[184:187]
	s_waitcnt vmcnt(8)
	ds_write_b128 v148, v[188:191] offset:36864
	ds_read_b128 v[184:187], v150
	ds_read_b128 v[188:191], v150 offset:4608
	ds_read_b128 v[208:211], v149
	ds_read_b128 v[212:215], v149 offset:4608
	s_setprio 1
	s_waitcnt lgkmcnt(1)
	v_mfma_f32_32x32x16_bf16 v[112:127], v[184:187], v[208:211], v[112:127]
	v_mfma_f32_32x32x16_bf16 v[48:63], v[188:191], v[208:211], v[48:63]
	s_waitcnt lgkmcnt(0)
	v_mfma_f32_32x32x16_bf16 v[96:111], v[184:187], v[212:215], v[96:111]
	v_mfma_f32_32x32x16_bf16 v[32:47], v[188:191], v[212:215], v[32:47]
	ds_read_b128 v[208:211], v149 offset:9216
	ds_read_b128 v[212:215], v149 offset:13824
	s_waitcnt vmcnt(7)
	ds_write_b128 v148, v[194:197] offset:9216
	s_waitcnt vmcnt(6)
	ds_write_b128 v148, v[198:201] offset:46080
	ds_read_b128 v[194:197], v150 offset:32
	ds_read_b128 v[198:201], v150 offset:4640
	s_waitcnt lgkmcnt(5)
	v_mfma_f32_32x32x16_bf16 v[80:95], v[184:187], v[208:211], v[80:95]
	v_mfma_f32_32x32x16_bf16 v[16:31], v[188:191], v[208:211], v[16:31]
	ds_read_b128 v[208:211], v149 offset:32
	s_waitcnt lgkmcnt(5)
	v_mfma_f32_32x32x16_bf16 v[64:79], v[184:187], v[212:215], v[64:79]
	v_mfma_f32_32x32x16_bf16 v[0:15], v[188:191], v[212:215], v[0:15]
	ds_read_b128 v[212:215], v149 offset:4640
	s_setprio 0
	global_load_dwordx4 v[184:187], v[140:141], off offset:2944
	global_load_dwordx4 v[188:191], v[142:143], off offset:2944
	s_setprio 1
	s_waitcnt lgkmcnt(1)
	v_mfma_f32_32x32x16_bf16 v[112:127], v[194:197], v[208:211], v[112:127]
	v_mfma_f32_32x32x16_bf16 v[48:63], v[198:201], v[208:211], v[48:63]
	s_waitcnt lgkmcnt(0)
	v_mfma_f32_32x32x16_bf16 v[96:111], v[194:197], v[212:215], v[96:111]
	v_mfma_f32_32x32x16_bf16 v[32:47], v[198:201], v[212:215], v[32:47]
	ds_read_b128 v[208:211], v149 offset:9248
	ds_read_b128 v[212:215], v149 offset:13856
	s_waitcnt vmcnt(7)
	ds_write_b128 v148, v[176:179] offset:18432
	s_waitcnt vmcnt(6)
	ds_write_b128 v148, v[180:183] offset:55296
	ds_read_b128 v[176:179], v150 offset:64
	ds_read_b128 v[180:183], v150 offset:4672
	s_waitcnt lgkmcnt(5)
	v_mfma_f32_32x32x16_bf16 v[80:95], v[194:197], v[208:211], v[80:95]
	v_mfma_f32_32x32x16_bf16 v[16:31], v[198:201], v[208:211], v[16:31]
	ds_read_b128 v[208:211], v149 offset:64
	s_waitcnt lgkmcnt(5)
	v_mfma_f32_32x32x16_bf16 v[64:79], v[194:197], v[212:215], v[64:79]
	v_mfma_f32_32x32x16_bf16 v[0:15], v[198:201], v[212:215], v[0:15]
	ds_read_b128 v[212:215], v149 offset:4672
	s_setprio 0
	global_load_dwordx4 v[194:197], v[132:133], off offset:2944
	global_load_dwordx4 v[198:201], v[134:135], off offset:2944
	s_setprio 1
	s_waitcnt lgkmcnt(1)
	v_mfma_f32_32x32x16_bf16 v[112:127], v[176:179], v[208:211], v[112:127]
	v_mfma_f32_32x32x16_bf16 v[48:63], v[180:183], v[208:211], v[48:63]
	s_waitcnt lgkmcnt(0)
	v_mfma_f32_32x32x16_bf16 v[96:111], v[176:179], v[212:215], v[96:111]
	v_mfma_f32_32x32x16_bf16 v[32:47], v[180:183], v[212:215], v[32:47]
	ds_read_b128 v[208:211], v149 offset:9280
	ds_read_b128 v[212:215], v149 offset:13888
	s_waitcnt vmcnt(7)
	ds_write_b128 v148, v[168:171] offset:27648
	s_waitcnt vmcnt(6)
	ds_write_b128 v148, v[172:175] offset:64512
	ds_read_b128 v[168:171], v150 offset:96
	ds_read_b128 v[172:175], v150 offset:4704
	s_waitcnt lgkmcnt(5)
	v_mfma_f32_32x32x16_bf16 v[80:95], v[176:179], v[208:211], v[80:95]
	v_mfma_f32_32x32x16_bf16 v[16:31], v[180:183], v[208:211], v[16:31]
	ds_read_b128 v[208:211], v149 offset:96
	s_waitcnt lgkmcnt(5)
	v_mfma_f32_32x32x16_bf16 v[64:79], v[176:179], v[212:215], v[64:79]
	v_mfma_f32_32x32x16_bf16 v[0:15], v[180:183], v[212:215], v[0:15]
	ds_read_b128 v[212:215], v149 offset:4704
	s_setprio 0
	global_load_dwordx4 v[176:179], v[144:145], off offset:2944
	global_load_dwordx4 v[180:183], v[146:147], off offset:2944
	s_setprio 1
	s_waitcnt lgkmcnt(1)
	v_mfma_f32_32x32x16_bf16 v[112:127], v[168:171], v[208:211], v[112:127]
	v_mfma_f32_32x32x16_bf16 v[48:63], v[172:175], v[208:211], v[48:63]
	s_waitcnt lgkmcnt(0)
	v_mfma_f32_32x32x16_bf16 v[96:111], v[168:171], v[212:215], v[96:111]
	v_mfma_f32_32x32x16_bf16 v[32:47], v[172:175], v[212:215], v[32:47]
	ds_read_b128 v[208:211], v149 offset:9312
	ds_read_b128 v[212:215], v149 offset:13920
	s_waitcnt lgkmcnt(1)
	v_mfma_f32_32x32x16_bf16 v[80:95], v[168:171], v[208:211], v[80:95]
	v_mfma_f32_32x32x16_bf16 v[16:31], v[172:175], v[208:211], v[16:31]
	s_waitcnt lgkmcnt(0)
	v_mfma_f32_32x32x16_bf16 v[64:79], v[168:171], v[212:215], v[64:79]
	v_mfma_f32_32x32x16_bf16 v[0:15], v[172:175], v[212:215], v[0:15]
	s_setprio 0
	s_barrier
; template <bool trans>
; DI void gemm_core(const GTile& tl, const GTile& nx, bool has_next  , bool chain  , bool pre, u32x4 (&ra)[4], u32x4 (&rb)[4], char* smem, f32x16 (&acc)[2][4]) {
;     ...
;   const int nk = K / 64;
;   if (!pre) { G_LOAD(0); G_STORE(0); G_LOAD(1); }
;   for (int kt = 0; kt < nk; ++kt) {
;     __syncthreads();
;     G_COMPUTE(kt & 1, kt);
	global_load_dwordx4 v[168:171], v[136:137], off offset:3072
	global_load_dwordx4 v[172:175], v[138:139], off offset:3072
	s_waitcnt vmcnt(9)
	ds_write_b128 v192, v[160:163]
	s_waitcnt vmcnt(8)
	ds_write_b128 v159, v[164:167]
	ds_read_b128 v[160:163], v152 offset:36864
	ds_read_b128 v[164:167], v152 offset:41472
	ds_read_b128 v[208:211], v151
	ds_read_b128 v[212:215], v151 offset:4608
	s_setprio 1
	s_waitcnt lgkmcnt(1)
	v_mfma_f32_32x32x16_bf16 v[112:127], v[160:163], v[208:211], v[112:127]
	v_mfma_f32_32x32x16_bf16 v[48:63], v[164:167], v[208:211], v[48:63]
	s_waitcnt lgkmcnt(0)
	v_mfma_f32_32x32x16_bf16 v[96:111], v[160:163], v[212:215], v[96:111]
	v_mfma_f32_32x32x16_bf16 v[32:47], v[164:167], v[212:215], v[32:47]
	ds_read_b128 v[208:211], v151 offset:9216
	ds_read_b128 v[212:215], v151 offset:13824
	s_waitcnt vmcnt(7)
	ds_write_b128 v158, v[184:187]
	s_waitcnt vmcnt(6)
	ds_write_b128 v157, v[188:191]
	ds_read_b128 v[184:187], v152 offset:36896
	ds_read_b128 v[188:191], v152 offset:41504
	s_waitcnt lgkmcnt(5)
	v_mfma_f32_32x32x16_bf16 v[80:95], v[160:163], v[208:211], v[80:95]
	v_mfma_f32_32x32x16_bf16 v[16:31], v[164:167], v[208:211], v[16:31]
	ds_read_b128 v[208:211], v151 offset:32
	s_waitcnt lgkmcnt(5)
	v_mfma_f32_32x32x16_bf16 v[64:79], v[160:163], v[212:215], v[64:79]
	v_mfma_f32_32x32x16_bf16 v[0:15], v[164:167], v[212:215], v[0:15]
	ds_read_b128 v[212:215], v151 offset:4640
	s_setprio 0
	global_load_dwordx4 v[160:163], v[140:141], off offset:3072
	global_load_dwordx4 v[164:167], v[142:143], off offset:3072
	s_setprio 1
	s_waitcnt lgkmcnt(1)
	v_mfma_f32_32x32x16_bf16 v[112:127], v[184:187], v[208:211], v[112:127]
	v_mfma_f32_32x32x16_bf16 v[48:63], v[188:191], v[208:211], v[48:63]
	s_waitcnt lgkmcnt(0)
	v_mfma_f32_32x32x16_bf16 v[96:111], v[184:187], v[212:215], v[96:111]
	v_mfma_f32_32x32x16_bf16 v[32:47], v[188:191], v[212:215], v[32:47]
	ds_read_b128 v[208:211], v151 offset:9248
	ds_read_b128 v[212:215], v151 offset:13856
	s_waitcnt vmcnt(7)
	ds_write_b128 v154, v[194:197]
	s_waitcnt vmcnt(6)
	ds_write_b128 v153, v[198:201]
	ds_read_b128 v[194:197], v152 offset:36928
	ds_read_b128 v[198:201], v152 offset:41536
	s_waitcnt lgkmcnt(5)
	v_mfma_f32_32x32x16_bf16 v[80:95], v[184:187], v[208:211], v[80:95]
	v_mfma_f32_32x32x16_bf16 v[16:31], v[188:191], v[208:211], v[16:31]
	ds_read_b128 v[208:211], v151 offset:64
	s_waitcnt lgkmcnt(5)
	v_mfma_f32_32x32x16_bf16 v[64:79], v[184:187], v[212:215], v[64:79]
	v_mfma_f32_32x32x16_bf16 v[0:15], v[188:191], v[212:215], v[0:15]
	ds_read_b128 v[212:215], v151 offset:4672
	s_setprio 0
	global_load_dwordx4 v[184:187], v[132:133], off offset:3072
	global_load_dwordx4 v[188:191], v[134:135], off offset:3072
	s_setprio 1
	s_waitcnt lgkmcnt(1)
	v_mfma_f32_32x32x16_bf16 v[112:127], v[194:197], v[208:211], v[112:127]
	v_mfma_f32_32x32x16_bf16 v[48:63], v[198:201], v[208:211], v[48:63]
	s_waitcnt lgkmcnt(0)
	v_mfma_f32_32x32x16_bf16 v[96:111], v[194:197], v[212:215], v[96:111]
	v_mfma_f32_32x32x16_bf16 v[32:47], v[198:201], v[212:215], v[32:47]
	ds_read_b128 v[208:211], v151 offset:9280
	ds_read_b128 v[212:215], v151 offset:13888
	s_waitcnt vmcnt(7)
	ds_write_b128 v156, v[176:179]
	s_waitcnt vmcnt(6)
	ds_write_b128 v155, v[180:183]
	ds_read_b128 v[176:179], v152 offset:36960
	ds_read_b128 v[180:183], v152 offset:41568
	s_waitcnt lgkmcnt(5)
	v_mfma_f32_32x32x16_bf16 v[80:95], v[194:197], v[208:211], v[80:95]
	v_mfma_f32_32x32x16_bf16 v[16:31], v[198:201], v[208:211], v[16:31]
	ds_read_b128 v[208:211], v151 offset:96
	s_waitcnt lgkmcnt(5)
	v_mfma_f32_32x32x16_bf16 v[64:79], v[194:197], v[212:215], v[64:79]
	v_mfma_f32_32x32x16_bf16 v[0:15], v[198:201], v[212:215], v[0:15]
	ds_read_b128 v[212:215], v151 offset:4704
	s_setprio 0
	global_load_dwordx4 v[194:197], v[144:145], off offset:3072
	global_load_dwordx4 v[198:201], v[146:147], off offset:3072
	s_setprio 1
	s_waitcnt lgkmcnt(1)
	v_mfma_f32_32x32x16_bf16 v[112:127], v[176:179], v[208:211], v[112:127]
	v_mfma_f32_32x32x16_bf16 v[48:63], v[180:183], v[208:211], v[48:63]
	s_waitcnt lgkmcnt(0)
	v_mfma_f32_32x32x16_bf16 v[96:111], v[176:179], v[212:215], v[96:111]
	v_mfma_f32_32x32x16_bf16 v[32:47], v[180:183], v[212:215], v[32:47]
	ds_read_b128 v[208:211], v151 offset:9312
	ds_read_b128 v[212:215], v151 offset:13920
	s_waitcnt lgkmcnt(1)
	v_mfma_f32_32x32x16_bf16 v[80:95], v[176:179], v[208:211], v[80:95]
	v_mfma_f32_32x32x16_bf16 v[16:31], v[180:183], v[208:211], v[16:31]
	s_waitcnt lgkmcnt(0)
	v_mfma_f32_32x32x16_bf16 v[64:79], v[176:179], v[212:215], v[64:79]
	v_mfma_f32_32x32x16_bf16 v[0:15], v[180:183], v[212:215], v[0:15]
	s_setprio 0
	s_barrier
; template <bool trans>
; DI void gemm_core(const GTile& tl, const GTile& nx, bool has_next  , bool chain  , bool pre, u32x4 (&ra)[4], u32x4 (&rb)[4], char* smem, f32x16 (&acc)[2][4]) {
;     ...
;   const int nk = K / 64;
;   if (!pre) { G_LOAD(0); G_STORE(0); G_LOAD(1); }
;   for (int kt = 0; kt < nk; ++kt) {
;     __syncthreads();
;     G_COMPUTE(kt & 1, kt);
	global_load_dwordx4 v[176:179], v[136:137], off offset:3200
	global_load_dwordx4 v[180:183], v[138:139], off offset:3200
	s_waitcnt vmcnt(9)
	ds_write_b128 v148, v[168:171]
	s_waitcnt vmcnt(8)
	ds_write_b128 v148, v[172:175] offset:36864
	ds_read_b128 v[168:171], v150
	ds_read_b128 v[172:175], v150 offset:4608
	ds_read_b128 v[208:211], v149
	ds_read_b128 v[212:215], v149 offset:4608
	s_setprio 1
	s_waitcnt lgkmcnt(1)
	v_mfma_f32_32x32x16_bf16 v[112:127], v[168:171], v[208:211], v[112:127]
	v_mfma_f32_32x32x16_bf16 v[48:63], v[172:175], v[208:211], v[48:63]
	s_waitcnt lgkmcnt(0)
	v_mfma_f32_32x32x16_bf16 v[96:111], v[168:171], v[212:215], v[96:111]
	v_mfma_f32_32x32x16_bf16 v[32:47], v[172:175], v[212:215], v[32:47]
	ds_read_b128 v[208:211], v149 offset:9216
	ds_read_b128 v[212:215], v149 offset:13824
	s_waitcnt vmcnt(7)
	ds_write_b128 v148, v[160:163] offset:9216
	s_waitcnt vmcnt(6)
	ds_write_b128 v148, v[164:167] offset:46080
	ds_read_b128 v[160:163], v150 offset:32
	ds_read_b128 v[164:167], v150 offset:4640
	s_waitcnt lgkmcnt(5)
	v_mfma_f32_32x32x16_bf16 v[80:95], v[168:171], v[208:211], v[80:95]
	v_mfma_f32_32x32x16_bf16 v[16:31], v[172:175], v[208:211], v[16:31]
	ds_read_b128 v[208:211], v149 offset:32
	s_waitcnt lgkmcnt(5)
	v_mfma_f32_32x32x16_bf16 v[64:79], v[168:171], v[212:215], v[64:79]
	v_mfma_f32_32x32x16_bf16 v[0:15], v[172:175], v[212:215], v[0:15]
	ds_read_b128 v[212:215], v149 offset:4640
	s_setprio 0
	global_load_dwordx4 v[168:171], v[140:141], off offset:3200
	global_load_dwordx4 v[172:175], v[142:143], off offset:3200
	s_setprio 1
	s_waitcnt lgkmcnt(1)
	v_mfma_f32_32x32x16_bf16 v[112:127], v[160:163], v[208:211], v[112:127]
	v_mfma_f32_32x32x16_bf16 v[48:63], v[164:167], v[208:211], v[48:63]
	s_waitcnt lgkmcnt(0)
	v_mfma_f32_32x32x16_bf16 v[96:111], v[160:163], v[212:215], v[96:111]
	v_mfma_f32_32x32x16_bf16 v[32:47], v[164:167], v[212:215], v[32:47]
	ds_read_b128 v[208:211], v149 offset:9248
	ds_read_b128 v[212:215], v149 offset:13856
	s_waitcnt vmcnt(7)
	ds_write_b128 v148, v[184:187] offset:18432
	s_waitcnt vmcnt(6)
	ds_write_b128 v148, v[188:191] offset:55296
	ds_read_b128 v[184:187], v150 offset:64
	ds_read_b128 v[188:191], v150 offset:4672
	s_waitcnt lgkmcnt(5)
	v_mfma_f32_32x32x16_bf16 v[80:95], v[160:163], v[208:211], v[80:95]
	v_mfma_f32_32x32x16_bf16 v[16:31], v[164:167], v[208:211], v[16:31]
	ds_read_b128 v[208:211], v149 offset:64
	s_waitcnt lgkmcnt(5)
	v_mfma_f32_32x32x16_bf16 v[64:79], v[160:163], v[212:215], v[64:79]
	v_mfma_f32_32x32x16_bf16 v[0:15], v[164:167], v[212:215], v[0:15]
	ds_read_b128 v[212:215], v149 offset:4672
	s_setprio 0
	global_load_dwordx4 v[160:163], v[132:133], off offset:3200
	global_load_dwordx4 v[164:167], v[134:135], off offset:3200
	s_setprio 1
	s_waitcnt lgkmcnt(1)
	v_mfma_f32_32x32x16_bf16 v[112:127], v[184:187], v[208:211], v[112:127]
	v_mfma_f32_32x32x16_bf16 v[48:63], v[188:191], v[208:211], v[48:63]
	s_waitcnt lgkmcnt(0)
	v_mfma_f32_32x32x16_bf16 v[96:111], v[184:187], v[212:215], v[96:111]
	v_mfma_f32_32x32x16_bf16 v[32:47], v[188:191], v[212:215], v[32:47]
	ds_read_b128 v[208:211], v149 offset:9280
	ds_read_b128 v[212:215], v149 offset:13888
	s_waitcnt vmcnt(7)
	ds_write_b128 v148, v[194:197] offset:27648
	s_waitcnt vmcnt(6)
	ds_write_b128 v148, v[198:201] offset:64512
	ds_read_b128 v[194:197], v150 offset:96
	ds_read_b128 v[198:201], v150 offset:4704
	s_waitcnt lgkmcnt(5)
	v_mfma_f32_32x32x16_bf16 v[80:95], v[184:187], v[208:211], v[80:95]
	v_mfma_f32_32x32x16_bf16 v[16:31], v[188:191], v[208:211], v[16:31]
	ds_read_b128 v[208:211], v149 offset:96
	s_waitcnt lgkmcnt(5)
	v_mfma_f32_32x32x16_bf16 v[64:79], v[184:187], v[212:215], v[64:79]
	v_mfma_f32_32x32x16_bf16 v[0:15], v[188:191], v[212:215], v[0:15]
	ds_read_b128 v[212:215], v149 offset:4704
	s_setprio 0
	global_load_dwordx4 v[184:187], v[144:145], off offset:3200
	global_load_dwordx4 v[188:191], v[146:147], off offset:3200
	s_setprio 1
	s_waitcnt lgkmcnt(1)
	v_mfma_f32_32x32x16_bf16 v[112:127], v[194:197], v[208:211], v[112:127]
	v_mfma_f32_32x32x16_bf16 v[48:63], v[198:201], v[208:211], v[48:63]
	s_waitcnt lgkmcnt(0)
	v_mfma_f32_32x32x16_bf16 v[96:111], v[194:197], v[212:215], v[96:111]
	v_mfma_f32_32x32x16_bf16 v[32:47], v[198:201], v[212:215], v[32:47]
	ds_read_b128 v[208:211], v149 offset:9312
	ds_read_b128 v[212:215], v149 offset:13920
	s_waitcnt lgkmcnt(1)
	v_mfma_f32_32x32x16_bf16 v[80:95], v[194:197], v[208:211], v[80:95]
	v_mfma_f32_32x32x16_bf16 v[16:31], v[198:201], v[208:211], v[16:31]
	s_waitcnt lgkmcnt(0)
	v_mfma_f32_32x32x16_bf16 v[64:79], v[194:197], v[212:215], v[64:79]
	v_mfma_f32_32x32x16_bf16 v[0:15], v[198:201], v[212:215], v[0:15]
	s_setprio 0
	s_barrier
; template <bool trans>
; DI void gemm_core(const GTile& tl, const GTile& nx, bool has_next  , bool chain  , bool pre, u32x4 (&ra)[4], u32x4 (&rb)[4], char* smem, f32x16 (&acc)[2][4]) {
;     ...
;   const int nk = K / 64;
;   if (!pre) { G_LOAD(0); G_STORE(0); G_LOAD(1); }
;   for (int kt = 0; kt < nk; ++kt) {
;     __syncthreads();
;     G_COMPUTE(kt & 1, kt);
	global_load_dwordx4 v[194:197], v[136:137], off offset:3328
	global_load_dwordx4 v[198:201], v[138:139], off offset:3328
	s_waitcnt vmcnt(9)
	ds_write_b128 v192, v[176:179]
	s_waitcnt vmcnt(8)
	ds_write_b128 v159, v[180:183]
	ds_read_b128 v[176:179], v152 offset:36864
	ds_read_b128 v[180:183], v152 offset:41472
	ds_read_b128 v[208:211], v151
	ds_read_b128 v[212:215], v151 offset:4608
	s_setprio 1
	s_waitcnt lgkmcnt(1)
	v_mfma_f32_32x32x16_bf16 v[112:127], v[176:179], v[208:211], v[112:127]
	v_mfma_f32_32x32x16_bf16 v[48:63], v[180:183], v[208:211], v[48:63]
	s_waitcnt lgkmcnt(0)
	v_mfma_f32_32x32x16_bf16 v[96:111], v[176:179], v[212:215], v[96:111]
	v_mfma_f32_32x32x16_bf16 v[32:47], v[180:183], v[212:215], v[32:47]
	ds_read_b128 v[208:211], v151 offset:9216
	ds_read_b128 v[212:215], v151 offset:13824
	s_waitcnt vmcnt(7)
	ds_write_b128 v158, v[168:171]
	s_waitcnt vmcnt(6)
	ds_write_b128 v157, v[172:175]
	ds_read_b128 v[168:171], v152 offset:36896
	ds_read_b128 v[172:175], v152 offset:41504
	s_waitcnt lgkmcnt(5)
	v_mfma_f32_32x32x16_bf16 v[80:95], v[176:179], v[208:211], v[80:95]
	v_mfma_f32_32x32x16_bf16 v[16:31], v[180:183], v[208:211], v[16:31]
	ds_read_b128 v[208:211], v151 offset:32
	s_waitcnt lgkmcnt(5)
	v_mfma_f32_32x32x16_bf16 v[64:79], v[176:179], v[212:215], v[64:79]
	v_mfma_f32_32x32x16_bf16 v[0:15], v[180:183], v[212:215], v[0:15]
	ds_read_b128 v[212:215], v151 offset:4640
	s_setprio 0
	global_load_dwordx4 v[176:179], v[140:141], off offset:3328
	global_load_dwordx4 v[180:183], v[142:143], off offset:3328
	s_setprio 1
	s_waitcnt lgkmcnt(1)
	v_mfma_f32_32x32x16_bf16 v[112:127], v[168:171], v[208:211], v[112:127]
	v_mfma_f32_32x32x16_bf16 v[48:63], v[172:175], v[208:211], v[48:63]
	s_waitcnt lgkmcnt(0)
	v_mfma_f32_32x32x16_bf16 v[96:111], v[168:171], v[212:215], v[96:111]
	v_mfma_f32_32x32x16_bf16 v[32:47], v[172:175], v[212:215], v[32:47]
	ds_read_b128 v[208:211], v151 offset:9248
	ds_read_b128 v[212:215], v151 offset:13856
	s_waitcnt vmcnt(7)
	ds_write_b128 v154, v[160:163]
	s_waitcnt vmcnt(6)
	ds_write_b128 v153, v[164:167]
	ds_read_b128 v[160:163], v152 offset:36928
	ds_read_b128 v[164:167], v152 offset:41536
	s_waitcnt lgkmcnt(5)
	v_mfma_f32_32x32x16_bf16 v[80:95], v[168:171], v[208:211], v[80:95]
	v_mfma_f32_32x32x16_bf16 v[16:31], v[172:175], v[208:211], v[16:31]
	ds_read_b128 v[208:211], v151 offset:64
	s_waitcnt lgkmcnt(5)
	v_mfma_f32_32x32x16_bf16 v[64:79], v[168:171], v[212:215], v[64:79]
	v_mfma_f32_32x32x16_bf16 v[0:15], v[172:175], v[212:215], v[0:15]
	ds_read_b128 v[212:215], v151 offset:4672
	s_setprio 0
	global_load_dwordx4 v[168:171], v[132:133], off offset:3328
	global_load_dwordx4 v[172:175], v[134:135], off offset:3328
	s_setprio 1
	s_waitcnt lgkmcnt(1)
	v_mfma_f32_32x32x16_bf16 v[112:127], v[160:163], v[208:211], v[112:127]
	v_mfma_f32_32x32x16_bf16 v[48:63], v[164:167], v[208:211], v[48:63]
	s_waitcnt lgkmcnt(0)
	v_mfma_f32_32x32x16_bf16 v[96:111], v[160:163], v[212:215], v[96:111]
	v_mfma_f32_32x32x16_bf16 v[32:47], v[164:167], v[212:215], v[32:47]
	ds_read_b128 v[208:211], v151 offset:9280
	ds_read_b128 v[212:215], v151 offset:13888
	s_waitcnt vmcnt(7)
	ds_write_b128 v156, v[184:187]
	s_waitcnt vmcnt(6)
	ds_write_b128 v155, v[188:191]
	ds_read_b128 v[184:187], v152 offset:36960
	ds_read_b128 v[188:191], v152 offset:41568
	s_waitcnt lgkmcnt(5)
	v_mfma_f32_32x32x16_bf16 v[80:95], v[160:163], v[208:211], v[80:95]
	v_mfma_f32_32x32x16_bf16 v[16:31], v[164:167], v[208:211], v[16:31]
	ds_read_b128 v[208:211], v151 offset:96
	s_waitcnt lgkmcnt(5)
	v_mfma_f32_32x32x16_bf16 v[64:79], v[160:163], v[212:215], v[64:79]
	v_mfma_f32_32x32x16_bf16 v[0:15], v[164:167], v[212:215], v[0:15]
	ds_read_b128 v[212:215], v151 offset:4704
	s_setprio 0
	global_load_dwordx4 v[160:163], v[144:145], off offset:3328
	global_load_dwordx4 v[164:167], v[146:147], off offset:3328
	s_setprio 1
	s_waitcnt lgkmcnt(1)
	v_mfma_f32_32x32x16_bf16 v[112:127], v[184:187], v[208:211], v[112:127]
	v_mfma_f32_32x32x16_bf16 v[48:63], v[188:191], v[208:211], v[48:63]
	s_waitcnt lgkmcnt(0)
	v_mfma_f32_32x32x16_bf16 v[96:111], v[184:187], v[212:215], v[96:111]
	v_mfma_f32_32x32x16_bf16 v[32:47], v[188:191], v[212:215], v[32:47]
	ds_read_b128 v[208:211], v151 offset:9312
	ds_read_b128 v[212:215], v151 offset:13920
	s_waitcnt lgkmcnt(1)
	v_mfma_f32_32x32x16_bf16 v[80:95], v[184:187], v[208:211], v[80:95]
	v_mfma_f32_32x32x16_bf16 v[16:31], v[188:191], v[208:211], v[16:31]
	s_waitcnt lgkmcnt(0)
	v_mfma_f32_32x32x16_bf16 v[64:79], v[184:187], v[212:215], v[64:79]
	v_mfma_f32_32x32x16_bf16 v[0:15], v[188:191], v[212:215], v[0:15]
	s_setprio 0
	s_barrier
; template <bool trans>
; DI void gemm_core(const GTile& tl, const GTile& nx, bool has_next  , bool chain  , bool pre, u32x4 (&ra)[4], u32x4 (&rb)[4], char* smem, f32x16 (&acc)[2][4]) {
;     ...
;   const int nk = K / 64;
;   if (!pre) { G_LOAD(0); G_STORE(0); G_LOAD(1); }
;   for (int kt = 0; kt < nk; ++kt) {
;     __syncthreads();
;     G_COMPUTE(kt & 1, kt);
	global_load_dwordx4 v[184:187], v[136:137], off offset:3456
	global_load_dwordx4 v[188:191], v[138:139], off offset:3456
	s_waitcnt vmcnt(9)
	ds_write_b128 v148, v[194:197]
	s_waitcnt vmcnt(8)
	ds_write_b128 v148, v[198:201] offset:36864
	ds_read_b128 v[194:197], v150
	ds_read_b128 v[198:201], v150 offset:4608
	ds_read_b128 v[208:211], v149
	ds_read_b128 v[212:215], v149 offset:4608
	s_setprio 1
	s_waitcnt lgkmcnt(1)
	v_mfma_f32_32x32x16_bf16 v[112:127], v[194:197], v[208:211], v[112:127]
	v_mfma_f32_32x32x16_bf16 v[48:63], v[198:201], v[208:211], v[48:63]
	s_waitcnt lgkmcnt(0)
	v_mfma_f32_32x32x16_bf16 v[96:111], v[194:197], v[212:215], v[96:111]
	v_mfma_f32_32x32x16_bf16 v[32:47], v[198:201], v[212:215], v[32:47]
	ds_read_b128 v[208:211], v149 offset:9216
	ds_read_b128 v[212:215], v149 offset:13824
	s_waitcnt vmcnt(7)
	ds_write_b128 v148, v[176:179] offset:9216
	s_waitcnt vmcnt(6)
	ds_write_b128 v148, v[180:183] offset:46080
	ds_read_b128 v[176:179], v150 offset:32
	ds_read_b128 v[180:183], v150 offset:4640
	s_waitcnt lgkmcnt(5)
	v_mfma_f32_32x32x16_bf16 v[80:95], v[194:197], v[208:211], v[80:95]
	v_mfma_f32_32x32x16_bf16 v[16:31], v[198:201], v[208:211], v[16:31]
	ds_read_b128 v[208:211], v149 offset:32
	s_waitcnt lgkmcnt(5)
	v_mfma_f32_32x32x16_bf16 v[64:79], v[194:197], v[212:215], v[64:79]
	v_mfma_f32_32x32x16_bf16 v[0:15], v[198:201], v[212:215], v[0:15]
	ds_read_b128 v[212:215], v149 offset:4640
	s_setprio 0
	global_load_dwordx4 v[194:197], v[140:141], off offset:3456
	global_load_dwordx4 v[198:201], v[142:143], off offset:3456
	s_setprio 1
	s_waitcnt lgkmcnt(1)
	v_mfma_f32_32x32x16_bf16 v[112:127], v[176:179], v[208:211], v[112:127]
	v_mfma_f32_32x32x16_bf16 v[48:63], v[180:183], v[208:211], v[48:63]
	s_waitcnt lgkmcnt(0)
	v_mfma_f32_32x32x16_bf16 v[96:111], v[176:179], v[212:215], v[96:111]
	v_mfma_f32_32x32x16_bf16 v[32:47], v[180:183], v[212:215], v[32:47]
	ds_read_b128 v[208:211], v149 offset:9248
	ds_read_b128 v[212:215], v149 offset:13856
	s_waitcnt vmcnt(7)
	ds_write_b128 v148, v[168:171] offset:18432
	s_waitcnt vmcnt(6)
	ds_write_b128 v148, v[172:175] offset:55296
	ds_read_b128 v[168:171], v150 offset:64
	ds_read_b128 v[172:175], v150 offset:4672
	s_waitcnt lgkmcnt(5)
	v_mfma_f32_32x32x16_bf16 v[80:95], v[176:179], v[208:211], v[80:95]
	v_mfma_f32_32x32x16_bf16 v[16:31], v[180:183], v[208:211], v[16:31]
	ds_read_b128 v[208:211], v149 offset:64
	s_waitcnt lgkmcnt(5)
	v_mfma_f32_32x32x16_bf16 v[64:79], v[176:179], v[212:215], v[64:79]
	v_mfma_f32_32x32x16_bf16 v[0:15], v[180:183], v[212:215], v[0:15]
	ds_read_b128 v[212:215], v149 offset:4672
	s_setprio 0
	global_load_dwordx4 v[176:179], v[132:133], off offset:3456
	global_load_dwordx4 v[180:183], v[134:135], off offset:3456
	s_setprio 1
	s_waitcnt lgkmcnt(1)
	v_mfma_f32_32x32x16_bf16 v[112:127], v[168:171], v[208:211], v[112:127]
	v_mfma_f32_32x32x16_bf16 v[48:63], v[172:175], v[208:211], v[48:63]
	s_waitcnt lgkmcnt(0)
	v_mfma_f32_32x32x16_bf16 v[96:111], v[168:171], v[212:215], v[96:111]
	v_mfma_f32_32x32x16_bf16 v[32:47], v[172:175], v[212:215], v[32:47]
	ds_read_b128 v[208:211], v149 offset:9280
	ds_read_b128 v[212:215], v149 offset:13888
	s_waitcnt vmcnt(7)
	ds_write_b128 v148, v[160:163] offset:27648
	s_waitcnt vmcnt(6)
	ds_write_b128 v148, v[164:167] offset:64512
	ds_read_b128 v[160:163], v150 offset:96
	ds_read_b128 v[164:167], v150 offset:4704
	s_waitcnt lgkmcnt(5)
	v_mfma_f32_32x32x16_bf16 v[80:95], v[168:171], v[208:211], v[80:95]
	v_mfma_f32_32x32x16_bf16 v[16:31], v[172:175], v[208:211], v[16:31]
	ds_read_b128 v[208:211], v149 offset:96
	s_waitcnt lgkmcnt(5)
	v_mfma_f32_32x32x16_bf16 v[64:79], v[168:171], v[212:215], v[64:79]
	v_mfma_f32_32x32x16_bf16 v[0:15], v[172:175], v[212:215], v[0:15]
	ds_read_b128 v[212:215], v149 offset:4704
	s_setprio 0
	global_load_dwordx4 v[168:171], v[144:145], off offset:3456
	global_load_dwordx4 v[172:175], v[146:147], off offset:3456
	s_setprio 1
	s_waitcnt lgkmcnt(1)
	v_mfma_f32_32x32x16_bf16 v[112:127], v[160:163], v[208:211], v[112:127]
	v_mfma_f32_32x32x16_bf16 v[48:63], v[164:167], v[208:211], v[48:63]
	s_waitcnt lgkmcnt(0)
	v_mfma_f32_32x32x16_bf16 v[96:111], v[160:163], v[212:215], v[96:111]
	v_mfma_f32_32x32x16_bf16 v[32:47], v[164:167], v[212:215], v[32:47]
	ds_read_b128 v[208:211], v149 offset:9312
	ds_read_b128 v[212:215], v149 offset:13920
	s_waitcnt lgkmcnt(1)
	v_mfma_f32_32x32x16_bf16 v[80:95], v[160:163], v[208:211], v[80:95]
	v_mfma_f32_32x32x16_bf16 v[16:31], v[164:167], v[208:211], v[16:31]
	s_waitcnt lgkmcnt(0)
	v_mfma_f32_32x32x16_bf16 v[64:79], v[160:163], v[212:215], v[64:79]
	v_mfma_f32_32x32x16_bf16 v[0:15], v[164:167], v[212:215], v[0:15]
	s_setprio 0
	s_barrier
; template <bool trans>
; DI void gemm_core(const GTile& tl, const GTile& nx, bool has_next  , bool chain  , bool pre, u32x4 (&ra)[4], u32x4 (&rb)[4], char* smem, f32x16 (&acc)[2][4]) {
;     ...
;   const int nk = K / 64;
;   if (!pre) { G_LOAD(0); G_STORE(0); G_LOAD(1); }
;   for (int kt = 0; kt < nk; ++kt) {
;     __syncthreads();
;     G_COMPUTE(kt & 1, kt);
	global_load_dwordx4 v[160:163], v[136:137], off offset:3584
	global_load_dwordx4 v[164:167], v[138:139], off offset:3584
	s_waitcnt vmcnt(9)
	ds_write_b128 v192, v[184:187]
	s_waitcnt vmcnt(8)
	ds_write_b128 v159, v[188:191]
	ds_read_b128 v[184:187], v152 offset:36864
	ds_read_b128 v[188:191], v152 offset:41472
	ds_read_b128 v[208:211], v151
	ds_read_b128 v[212:215], v151 offset:4608
	s_setprio 1
	s_waitcnt lgkmcnt(1)
	v_mfma_f32_32x32x16_bf16 v[112:127], v[184:187], v[208:211], v[112:127]
	v_mfma_f32_32x32x16_bf16 v[48:63], v[188:191], v[208:211], v[48:63]
	s_waitcnt lgkmcnt(0)
	v_mfma_f32_32x32x16_bf16 v[96:111], v[184:187], v[212:215], v[96:111]
	v_mfma_f32_32x32x16_bf16 v[32:47], v[188:191], v[212:215], v[32:47]
	ds_read_b128 v[208:211], v151 offset:9216
	ds_read_b128 v[212:215], v151 offset:13824
	s_waitcnt vmcnt(7)
	ds_write_b128 v158, v[194:197]
	s_waitcnt vmcnt(6)
	ds_write_b128 v157, v[198:201]
	ds_read_b128 v[194:197], v152 offset:36896
	ds_read_b128 v[198:201], v152 offset:41504
	s_waitcnt lgkmcnt(5)
	v_mfma_f32_32x32x16_bf16 v[80:95], v[184:187], v[208:211], v[80:95]
	v_mfma_f32_32x32x16_bf16 v[16:31], v[188:191], v[208:211], v[16:31]
	ds_read_b128 v[208:211], v151 offset:32
	s_waitcnt lgkmcnt(5)
	v_mfma_f32_32x32x16_bf16 v[64:79], v[184:187], v[212:215], v[64:79]
	v_mfma_f32_32x32x16_bf16 v[0:15], v[188:191], v[212:215], v[0:15]
	ds_read_b128 v[212:215], v151 offset:4640
	s_setprio 0
	global_load_dwordx4 v[184:187], v[140:141], off offset:3584
	global_load_dwordx4 v[188:191], v[142:143], off offset:3584
	s_setprio 1
	s_waitcnt lgkmcnt(1)
	v_mfma_f32_32x32x16_bf16 v[112:127], v[194:197], v[208:211], v[112:127]
	v_mfma_f32_32x32x16_bf16 v[48:63], v[198:201], v[208:211], v[48:63]
	s_waitcnt lgkmcnt(0)
	v_mfma_f32_32x32x16_bf16 v[96:111], v[194:197], v[212:215], v[96:111]
	v_mfma_f32_32x32x16_bf16 v[32:47], v[198:201], v[212:215], v[32:47]
	ds_read_b128 v[208:211], v151 offset:9248
	ds_read_b128 v[212:215], v151 offset:13856
	s_waitcnt vmcnt(7)
	ds_write_b128 v154, v[176:179]
	s_waitcnt vmcnt(6)
	ds_write_b128 v153, v[180:183]
	ds_read_b128 v[176:179], v152 offset:36928
	ds_read_b128 v[180:183], v152 offset:41536
	s_waitcnt lgkmcnt(5)
	v_mfma_f32_32x32x16_bf16 v[80:95], v[194:197], v[208:211], v[80:95]
	v_mfma_f32_32x32x16_bf16 v[16:31], v[198:201], v[208:211], v[16:31]
	ds_read_b128 v[208:211], v151 offset:64
	s_waitcnt lgkmcnt(5)
	v_mfma_f32_32x32x16_bf16 v[64:79], v[194:197], v[212:215], v[64:79]
	v_mfma_f32_32x32x16_bf16 v[0:15], v[198:201], v[212:215], v[0:15]
	ds_read_b128 v[212:215], v151 offset:4672
	s_setprio 0
	global_load_dwordx4 v[194:197], v[132:133], off offset:3584
	global_load_dwordx4 v[198:201], v[134:135], off offset:3584
	s_setprio 1
	s_waitcnt lgkmcnt(1)
	v_mfma_f32_32x32x16_bf16 v[112:127], v[176:179], v[208:211], v[112:127]
	v_mfma_f32_32x32x16_bf16 v[48:63], v[180:183], v[208:211], v[48:63]
	s_waitcnt lgkmcnt(0)
	v_mfma_f32_32x32x16_bf16 v[96:111], v[176:179], v[212:215], v[96:111]
	v_mfma_f32_32x32x16_bf16 v[32:47], v[180:183], v[212:215], v[32:47]
	ds_read_b128 v[208:211], v151 offset:9280
	ds_read_b128 v[212:215], v151 offset:13888
	s_waitcnt vmcnt(7)
	ds_write_b128 v156, v[168:171]
	s_waitcnt vmcnt(6)
	ds_write_b128 v155, v[172:175]
	ds_read_b128 v[168:171], v152 offset:36960
	ds_read_b128 v[172:175], v152 offset:41568
	s_waitcnt lgkmcnt(5)
	v_mfma_f32_32x32x16_bf16 v[80:95], v[176:179], v[208:211], v[80:95]
	v_mfma_f32_32x32x16_bf16 v[16:31], v[180:183], v[208:211], v[16:31]
	ds_read_b128 v[208:211], v151 offset:96
	s_waitcnt lgkmcnt(5)
	v_mfma_f32_32x32x16_bf16 v[64:79], v[176:179], v[212:215], v[64:79]
	v_mfma_f32_32x32x16_bf16 v[0:15], v[180:183], v[212:215], v[0:15]
	ds_read_b128 v[212:215], v151 offset:4704
	s_setprio 0
	global_load_dwordx4 v[176:179], v[144:145], off offset:3584
	global_load_dwordx4 v[180:183], v[146:147], off offset:3584
	s_setprio 1
	s_waitcnt lgkmcnt(1)
	v_mfma_f32_32x32x16_bf16 v[112:127], v[168:171], v[208:211], v[112:127]
	v_mfma_f32_32x32x16_bf16 v[48:63], v[172:175], v[208:211], v[48:63]
	s_waitcnt lgkmcnt(0)
	v_mfma_f32_32x32x16_bf16 v[96:111], v[168:171], v[212:215], v[96:111]
	v_mfma_f32_32x32x16_bf16 v[32:47], v[172:175], v[212:215], v[32:47]
	ds_read_b128 v[208:211], v151 offset:9312
	ds_read_b128 v[212:215], v151 offset:13920
	s_waitcnt lgkmcnt(1)
	v_mfma_f32_32x32x16_bf16 v[80:95], v[168:171], v[208:211], v[80:95]
	v_mfma_f32_32x32x16_bf16 v[16:31], v[172:175], v[208:211], v[16:31]
	s_waitcnt lgkmcnt(0)
	v_mfma_f32_32x32x16_bf16 v[64:79], v[168:171], v[212:215], v[64:79]
	v_mfma_f32_32x32x16_bf16 v[0:15], v[172:175], v[212:215], v[0:15]
	s_setprio 0
	s_barrier
; template <bool trans>
; DI void gemm_core(const GTile& tl, const GTile& nx, bool has_next  , bool chain  , bool pre, u32x4 (&ra)[4], u32x4 (&rb)[4], char* smem, f32x16 (&acc)[2][4]) {
;     ...
;   const int nk = K / 64;
;   if (!pre) { G_LOAD(0); G_STORE(0); G_LOAD(1); }
;   for (int kt = 0; kt < nk; ++kt) {
;     __syncthreads();
;     G_COMPUTE(kt & 1, kt);
	global_load_dwordx4 v[168:171], v[136:137], off offset:3712
	global_load_dwordx4 v[172:175], v[138:139], off offset:3712
	s_waitcnt vmcnt(9)
	ds_write_b128 v148, v[160:163]
	s_waitcnt vmcnt(8)
	ds_write_b128 v148, v[164:167] offset:36864
	ds_read_b128 v[160:163], v150
	ds_read_b128 v[164:167], v150 offset:4608
	ds_read_b128 v[208:211], v149
	ds_read_b128 v[212:215], v149 offset:4608
	s_setprio 1
	s_waitcnt lgkmcnt(1)
	v_mfma_f32_32x32x16_bf16 v[112:127], v[160:163], v[208:211], v[112:127]
	v_mfma_f32_32x32x16_bf16 v[48:63], v[164:167], v[208:211], v[48:63]
	s_waitcnt lgkmcnt(0)
	v_mfma_f32_32x32x16_bf16 v[96:111], v[160:163], v[212:215], v[96:111]
	v_mfma_f32_32x32x16_bf16 v[32:47], v[164:167], v[212:215], v[32:47]
	ds_read_b128 v[208:211], v149 offset:9216
	ds_read_b128 v[212:215], v149 offset:13824
	s_waitcnt vmcnt(7)
	ds_write_b128 v148, v[184:187] offset:9216
	s_waitcnt vmcnt(6)
	ds_write_b128 v148, v[188:191] offset:46080
	ds_read_b128 v[184:187], v150 offset:32
	ds_read_b128 v[188:191], v150 offset:4640
	s_waitcnt lgkmcnt(5)
	v_mfma_f32_32x32x16_bf16 v[80:95], v[160:163], v[208:211], v[80:95]
	v_mfma_f32_32x32x16_bf16 v[16:31], v[164:167], v[208:211], v[16:31]
	ds_read_b128 v[208:211], v149 offset:32
	s_waitcnt lgkmcnt(5)
	v_mfma_f32_32x32x16_bf16 v[64:79], v[160:163], v[212:215], v[64:79]
	v_mfma_f32_32x32x16_bf16 v[0:15], v[164:167], v[212:215], v[0:15]
	ds_read_b128 v[212:215], v149 offset:4640
	s_setprio 0
	global_load_dwordx4 v[160:163], v[140:141], off offset:3712
	global_load_dwordx4 v[164:167], v[142:143], off offset:3712
	s_setprio 1
	s_waitcnt lgkmcnt(1)
	v_mfma_f32_32x32x16_bf16 v[112:127], v[184:187], v[208:211], v[112:127]
	v_mfma_f32_32x32x16_bf16 v[48:63], v[188:191], v[208:211], v[48:63]
	s_waitcnt lgkmcnt(0)
	v_mfma_f32_32x32x16_bf16 v[96:111], v[184:187], v[212:215], v[96:111]
	v_mfma_f32_32x32x16_bf16 v[32:47], v[188:191], v[212:215], v[32:47]
	ds_read_b128 v[208:211], v149 offset:9248
	ds_read_b128 v[212:215], v149 offset:13856
	s_waitcnt vmcnt(7)
	ds_write_b128 v148, v[194:197] offset:18432
	s_waitcnt vmcnt(6)
	ds_write_b128 v148, v[198:201] offset:55296
	ds_read_b128 v[194:197], v150 offset:64
	ds_read_b128 v[198:201], v150 offset:4672
	s_waitcnt lgkmcnt(5)
	v_mfma_f32_32x32x16_bf16 v[80:95], v[184:187], v[208:211], v[80:95]
	v_mfma_f32_32x32x16_bf16 v[16:31], v[188:191], v[208:211], v[16:31]
	ds_read_b128 v[208:211], v149 offset:64
	s_waitcnt lgkmcnt(5)
	v_mfma_f32_32x32x16_bf16 v[64:79], v[184:187], v[212:215], v[64:79]
	v_mfma_f32_32x32x16_bf16 v[0:15], v[188:191], v[212:215], v[0:15]
	ds_read_b128 v[212:215], v149 offset:4672
	s_setprio 0
	global_load_dwordx4 v[184:187], v[132:133], off offset:3712
	global_load_dwordx4 v[188:191], v[134:135], off offset:3712
	s_setprio 1
	s_waitcnt lgkmcnt(1)
	v_mfma_f32_32x32x16_bf16 v[112:127], v[194:197], v[208:211], v[112:127]
	v_mfma_f32_32x32x16_bf16 v[48:63], v[198:201], v[208:211], v[48:63]
	s_waitcnt lgkmcnt(0)
	v_mfma_f32_32x32x16_bf16 v[96:111], v[194:197], v[212:215], v[96:111]
	v_mfma_f32_32x32x16_bf16 v[32:47], v[198:201], v[212:215], v[32:47]
	ds_read_b128 v[208:211], v149 offset:9280
	ds_read_b128 v[212:215], v149 offset:13888
	s_waitcnt vmcnt(7)
	ds_write_b128 v148, v[176:179] offset:27648
	s_waitcnt vmcnt(6)
	ds_write_b128 v148, v[180:183] offset:64512
	ds_read_b128 v[176:179], v150 offset:96
	ds_read_b128 v[180:183], v150 offset:4704
	s_waitcnt lgkmcnt(5)
	v_mfma_f32_32x32x16_bf16 v[80:95], v[194:197], v[208:211], v[80:95]
	v_mfma_f32_32x32x16_bf16 v[16:31], v[198:201], v[208:211], v[16:31]
	ds_read_b128 v[208:211], v149 offset:96
	s_waitcnt lgkmcnt(5)
	v_mfma_f32_32x32x16_bf16 v[64:79], v[194:197], v[212:215], v[64:79]
	v_mfma_f32_32x32x16_bf16 v[0:15], v[198:201], v[212:215], v[0:15]
	ds_read_b128 v[212:215], v149 offset:4704
	s_setprio 0
	global_load_dwordx4 v[194:197], v[144:145], off offset:3712
	global_load_dwordx4 v[198:201], v[146:147], off offset:3712
	s_setprio 1
	s_waitcnt lgkmcnt(1)
	v_mfma_f32_32x32x16_bf16 v[112:127], v[176:179], v[208:211], v[112:127]
	v_mfma_f32_32x32x16_bf16 v[48:63], v[180:183], v[208:211], v[48:63]
	s_waitcnt lgkmcnt(0)
	v_mfma_f32_32x32x16_bf16 v[96:111], v[176:179], v[212:215], v[96:111]
	v_mfma_f32_32x32x16_bf16 v[32:47], v[180:183], v[212:215], v[32:47]
	ds_read_b128 v[208:211], v149 offset:9312
	ds_read_b128 v[212:215], v149 offset:13920
	s_waitcnt lgkmcnt(1)
	v_mfma_f32_32x32x16_bf16 v[80:95], v[176:179], v[208:211], v[80:95]
	v_mfma_f32_32x32x16_bf16 v[16:31], v[180:183], v[208:211], v[16:31]
	s_waitcnt lgkmcnt(0)
	v_mfma_f32_32x32x16_bf16 v[64:79], v[176:179], v[212:215], v[64:79]
	v_mfma_f32_32x32x16_bf16 v[0:15], v[180:183], v[212:215], v[0:15]
	s_setprio 0
	s_barrier
; template <bool trans>
; DI void gemm_core(const GTile& tl, const GTile& nx, bool has_next  , bool chain  , bool pre, u32x4 (&ra)[4], u32x4 (&rb)[4], char* smem, f32x16 (&acc)[2][4]) {
;     ...
;   const int nk = K / 64;
;   if (!pre) { G_LOAD(0); G_STORE(0); G_LOAD(1); }
;   for (int kt = 0; kt < nk; ++kt) {
;     __syncthreads();
;     G_COMPUTE(kt & 1, kt);
	global_load_dwordx4 v[176:179], v[136:137], off offset:3840
	global_load_dwordx4 v[180:183], v[138:139], off offset:3840
	s_waitcnt vmcnt(9)
	ds_write_b128 v192, v[168:171]
	s_waitcnt vmcnt(8)
	ds_write_b128 v159, v[172:175]
	ds_read_b128 v[168:171], v152 offset:36864
	ds_read_b128 v[172:175], v152 offset:41472
	ds_read_b128 v[208:211], v151
	ds_read_b128 v[212:215], v151 offset:4608
	s_setprio 1
	s_waitcnt lgkmcnt(1)
	v_mfma_f32_32x32x16_bf16 v[112:127], v[168:171], v[208:211], v[112:127]
	v_mfma_f32_32x32x16_bf16 v[48:63], v[172:175], v[208:211], v[48:63]
	s_waitcnt lgkmcnt(0)
	v_mfma_f32_32x32x16_bf16 v[96:111], v[168:171], v[212:215], v[96:111]
	v_mfma_f32_32x32x16_bf16 v[32:47], v[172:175], v[212:215], v[32:47]
	ds_read_b128 v[208:211], v151 offset:9216
	ds_read_b128 v[212:215], v151 offset:13824
	s_waitcnt lgkmcnt(1)
	v_mfma_f32_32x32x16_bf16 v[80:95], v[168:171], v[208:211], v[80:95]
	v_mfma_f32_32x32x16_bf16 v[16:31], v[172:175], v[208:211], v[16:31]
	s_waitcnt lgkmcnt(0)
	v_mfma_f32_32x32x16_bf16 v[64:79], v[168:171], v[212:215], v[64:79]
	v_mfma_f32_32x32x16_bf16 v[0:15], v[172:175], v[212:215], v[0:15]
	s_setprio 0
	global_load_dwordx4 v[208:211], v[140:141], off offset:3840
	global_load_dwordx4 v[212:215], v[142:143], off offset:3840
	s_waitcnt vmcnt(9)
	ds_write_b128 v158, v[160:163]
	s_waitcnt vmcnt(8)
	ds_write_b128 v157, v[164:167]
	ds_read_b128 v[160:163], v152 offset:36896
	ds_read_b128 v[164:167], v152 offset:41504
	ds_read_b128 v[168:171], v151 offset:32
	ds_read_b128 v[172:175], v151 offset:4640
	s_setprio 1
	s_waitcnt lgkmcnt(1)
	v_mfma_f32_32x32x16_bf16 v[112:127], v[160:163], v[168:171], v[112:127]
	v_mfma_f32_32x32x16_bf16 v[48:63], v[164:167], v[168:171], v[48:63]
	s_waitcnt lgkmcnt(0)
	v_mfma_f32_32x32x16_bf16 v[96:111], v[160:163], v[172:175], v[96:111]
	v_mfma_f32_32x32x16_bf16 v[32:47], v[164:167], v[172:175], v[32:47]
	ds_read_b128 v[168:171], v151 offset:9248
	ds_read_b128 v[172:175], v151 offset:13856
	s_waitcnt lgkmcnt(1)
	v_mfma_f32_32x32x16_bf16 v[80:95], v[160:163], v[168:171], v[80:95]
	v_mfma_f32_32x32x16_bf16 v[16:31], v[164:167], v[168:171], v[16:31]
	s_waitcnt lgkmcnt(0)
	v_mfma_f32_32x32x16_bf16 v[64:79], v[160:163], v[172:175], v[64:79]
	v_mfma_f32_32x32x16_bf16 v[0:15], v[164:167], v[172:175], v[0:15]
	s_setprio 0
	global_load_dwordx4 v[216:219], v[132:133], off offset:3840
	global_load_dwordx4 v[220:223], v[134:135], off offset:3840
	s_waitcnt vmcnt(9)
	ds_write_b128 v154, v[184:187]
	s_waitcnt vmcnt(8)
	ds_write_b128 v153, v[188:191]
	ds_read_b128 v[160:163], v152 offset:36928
	ds_read_b128 v[164:167], v152 offset:41536
	ds_read_b128 v[168:171], v151 offset:64
	ds_read_b128 v[172:175], v151 offset:4672
	s_setprio 1
	s_waitcnt lgkmcnt(1)
	v_mfma_f32_32x32x16_bf16 v[112:127], v[160:163], v[168:171], v[112:127]
	v_mfma_f32_32x32x16_bf16 v[48:63], v[164:167], v[168:171], v[48:63]
	s_waitcnt lgkmcnt(0)
	v_mfma_f32_32x32x16_bf16 v[96:111], v[160:163], v[172:175], v[96:111]
	v_mfma_f32_32x32x16_bf16 v[32:47], v[164:167], v[172:175], v[32:47]
	ds_read_b128 v[168:171], v151 offset:9280
	ds_read_b128 v[172:175], v151 offset:13888
	s_waitcnt lgkmcnt(1)
	v_mfma_f32_32x32x16_bf16 v[80:95], v[160:163], v[168:171], v[80:95]
	v_mfma_f32_32x32x16_bf16 v[16:31], v[164:167], v[168:171], v[16:31]
	s_waitcnt lgkmcnt(0)
	v_mfma_f32_32x32x16_bf16 v[64:79], v[160:163], v[172:175], v[64:79]
	v_mfma_f32_32x32x16_bf16 v[0:15], v[164:167], v[172:175], v[0:15]
	s_setprio 0
	global_load_dwordx4 v[224:227], v[144:145], off offset:3840
	global_load_dwordx4 v[228:231], v[146:147], off offset:3840
	s_waitcnt vmcnt(9)
	ds_write_b128 v156, v[194:197]
	s_waitcnt vmcnt(8)
	ds_write_b128 v155, v[198:201]
	ds_read_b128 v[160:163], v152 offset:36960
	ds_read_b128 v[164:167], v152 offset:41568
	ds_read_b128 v[168:171], v151 offset:96
	ds_read_b128 v[172:175], v151 offset:4704
	s_setprio 1
	s_waitcnt lgkmcnt(1)
	v_mfma_f32_32x32x16_bf16 v[112:127], v[160:163], v[168:171], v[112:127]
	v_mfma_f32_32x32x16_bf16 v[48:63], v[164:167], v[168:171], v[48:63]
	s_waitcnt lgkmcnt(0)
	v_mfma_f32_32x32x16_bf16 v[96:111], v[160:163], v[172:175], v[96:111]
	v_mfma_f32_32x32x16_bf16 v[32:47], v[164:167], v[172:175], v[32:47]
	ds_read_b128 v[168:171], v151 offset:9312
	ds_read_b128 v[172:175], v151 offset:13920
	s_waitcnt lgkmcnt(1)
	v_mfma_f32_32x32x16_bf16 v[80:95], v[160:163], v[168:171], v[80:95]
	v_mfma_f32_32x32x16_bf16 v[16:31], v[164:167], v[168:171], v[16:31]
	s_waitcnt lgkmcnt(0)
	v_mfma_f32_32x32x16_bf16 v[64:79], v[160:163], v[172:175], v[64:79]
	v_mfma_f32_32x32x16_bf16 v[0:15], v[164:167], v[172:175], v[0:15]
	s_setprio 0
	s_barrier
; template <bool trans>
; DI void gemm_core(const GTile& tl, const GTile& nx, bool has_next  , bool chain  , bool pre, u32x4 (&ra)[4], u32x4 (&rb)[4], char* smem, f32x16 (&acc)[2][4]) {
;     ...
;   const int nk = K / 64;
;   if (!pre) { G_LOAD(0); G_STORE(0); G_LOAD(1); }
;   for (int kt = 0; kt < nk; ++kt) {
;     __syncthreads();
;     G_COMPUTE(kt & 1, kt);
	global_load_dwordx4 v[160:163], v[136:137], off offset:3968
	global_load_dwordx4 v[164:167], v[138:139], off offset:3968
	s_waitcnt vmcnt(9)
	ds_write_b128 v148, v[176:179]
	s_waitcnt vmcnt(8)
	ds_write_b128 v148, v[180:183] offset:36864
	ds_read_b128 v[136:139], v150
	ds_read_b128 v[168:171], v150 offset:4608
	ds_read_b128 v[172:175], v149
	ds_read_b128 v[176:179], v149 offset:4608
	s_setprio 1
	s_waitcnt lgkmcnt(1)
	v_mfma_f32_32x32x16_bf16 v[112:127], v[136:139], v[172:175], v[112:127]
	v_mfma_f32_32x32x16_bf16 v[48:63], v[168:171], v[172:175], v[48:63]
	s_waitcnt lgkmcnt(0)
	v_mfma_f32_32x32x16_bf16 v[96:111], v[136:139], v[176:179], v[96:111]
	v_mfma_f32_32x32x16_bf16 v[32:47], v[168:171], v[176:179], v[32:47]
	ds_read_b128 v[172:175], v149 offset:9216
	ds_read_b128 v[176:179], v149 offset:13824
	s_waitcnt lgkmcnt(1)
	v_mfma_f32_32x32x16_bf16 v[80:95], v[136:139], v[172:175], v[80:95]
	v_mfma_f32_32x32x16_bf16 v[16:31], v[168:171], v[172:175], v[16:31]
	s_waitcnt lgkmcnt(0)
	v_mfma_f32_32x32x16_bf16 v[64:79], v[136:139], v[176:179], v[64:79]
	v_mfma_f32_32x32x16_bf16 v[0:15], v[168:171], v[176:179], v[0:15]
	s_setprio 0
	global_load_dwordx4 v[168:171], v[140:141], off offset:3968
	global_load_dwordx4 v[172:175], v[142:143], off offset:3968
	s_waitcnt vmcnt(9)
	ds_write_b128 v148, v[208:211] offset:9216
	s_waitcnt vmcnt(8)
	ds_write_b128 v148, v[212:215] offset:46080
	ds_read_b128 v[136:139], v150 offset:32
	ds_read_b128 v[140:143], v150 offset:4640
	ds_read_b128 v[176:179], v149 offset:32
	ds_read_b128 v[180:183], v149 offset:4640
	s_setprio 1
	s_waitcnt lgkmcnt(1)
	v_mfma_f32_32x32x16_bf16 v[112:127], v[136:139], v[176:179], v[112:127]
	v_mfma_f32_32x32x16_bf16 v[48:63], v[140:143], v[176:179], v[48:63]
	s_waitcnt lgkmcnt(0)
	v_mfma_f32_32x32x16_bf16 v[96:111], v[136:139], v[180:183], v[96:111]
	v_mfma_f32_32x32x16_bf16 v[32:47], v[140:143], v[180:183], v[32:47]
	ds_read_b128 v[176:179], v149 offset:9248
	ds_read_b128 v[180:183], v149 offset:13856
	s_waitcnt lgkmcnt(1)
	v_mfma_f32_32x32x16_bf16 v[80:95], v[136:139], v[176:179], v[80:95]
	v_mfma_f32_32x32x16_bf16 v[16:31], v[140:143], v[176:179], v[16:31]
	s_waitcnt lgkmcnt(0)
	v_mfma_f32_32x32x16_bf16 v[64:79], v[136:139], v[180:183], v[64:79]
	v_mfma_f32_32x32x16_bf16 v[0:15], v[140:143], v[180:183], v[0:15]
	s_setprio 0
	global_load_dwordx4 v[176:179], v[132:133], off offset:3968
	global_load_dwordx4 v[180:183], v[134:135], off offset:3968
	s_waitcnt vmcnt(9)
	ds_write_b128 v148, v[216:219] offset:18432
	s_waitcnt vmcnt(8)
	ds_write_b128 v148, v[220:223] offset:55296
	ds_read_b128 v[132:135], v150 offset:64
	ds_read_b128 v[136:139], v150 offset:4672
	ds_read_b128 v[140:143], v149 offset:64
	ds_read_b128 v[184:187], v149 offset:4672
	s_setprio 1
	s_waitcnt lgkmcnt(1)
	v_mfma_f32_32x32x16_bf16 v[112:127], v[132:135], v[140:143], v[112:127]
	v_mfma_f32_32x32x16_bf16 v[48:63], v[136:139], v[140:143], v[48:63]
	s_waitcnt lgkmcnt(0)
	v_mfma_f32_32x32x16_bf16 v[96:111], v[132:135], v[184:187], v[96:111]
	v_mfma_f32_32x32x16_bf16 v[32:47], v[136:139], v[184:187], v[32:47]
	ds_read_b128 v[140:143], v149 offset:9280
	ds_read_b128 v[184:187], v149 offset:13888
	s_waitcnt lgkmcnt(1)
	v_mfma_f32_32x32x16_bf16 v[80:95], v[132:135], v[140:143], v[80:95]
	v_mfma_f32_32x32x16_bf16 v[16:31], v[136:139], v[140:143], v[16:31]
	s_waitcnt lgkmcnt(0)
	v_mfma_f32_32x32x16_bf16 v[64:79], v[132:135], v[184:187], v[64:79]
	v_mfma_f32_32x32x16_bf16 v[0:15], v[136:139], v[184:187], v[0:15]
	s_setprio 0
	global_load_dwordx4 v[184:187], v[144:145], off offset:3968
	global_load_dwordx4 v[188:191], v[146:147], off offset:3968
	s_waitcnt vmcnt(9)
	ds_write_b128 v148, v[224:227] offset:27648
	s_waitcnt vmcnt(8)
	ds_write_b128 v148, v[228:231] offset:64512
	ds_read_b128 v[132:135], v150 offset:96
	ds_read_b128 v[136:139], v150 offset:4704
	ds_read_b128 v[140:143], v149 offset:96
	ds_read_b128 v[144:147], v149 offset:4704
	s_setprio 1
	s_waitcnt lgkmcnt(1)
	v_mfma_f32_32x32x16_bf16 v[112:127], v[132:135], v[140:143], v[112:127]
	v_mfma_f32_32x32x16_bf16 v[48:63], v[136:139], v[140:143], v[48:63]
	s_waitcnt lgkmcnt(0)
	v_mfma_f32_32x32x16_bf16 v[96:111], v[132:135], v[144:147], v[96:111]
	v_mfma_f32_32x32x16_bf16 v[32:47], v[136:139], v[144:147], v[32:47]
	ds_read_b128 v[140:143], v149 offset:9312
	ds_read_b128 v[144:147], v149 offset:13920
	s_waitcnt lgkmcnt(1)
	v_mfma_f32_32x32x16_bf16 v[80:95], v[132:135], v[140:143], v[80:95]
	v_mfma_f32_32x32x16_bf16 v[16:31], v[136:139], v[140:143], v[16:31]
	s_waitcnt lgkmcnt(0)
	v_mfma_f32_32x32x16_bf16 v[64:79], v[132:135], v[144:147], v[64:79]
	v_mfma_f32_32x32x16_bf16 v[0:15], v[136:139], v[144:147], v[0:15]
	s_setprio 0
	v_cndmask_b32_e64 v132, 0, 1, s[52:53]
	v_cmp_ne_u32_e64 s[4:5], 1, v132
	s_andn2_b64 vcc, exec, s[52:53]
	s_barrier
	s_waitcnt vmcnt(7)
	ds_write_b128 v192, v[160:163]
	s_waitcnt vmcnt(6)
	ds_write_b128 v159, v[164:167]
	s_cbranch_vccnz .LBB0_113
	global_load_dwordx4 v[160:163], v[130:131], off
	global_load_dwordx4 v[164:167], v[128:129], off

;   DI bf16_t* h() const { return (bf16_t*)(ws + OFF_H); }
; template <bool trans>
; DI void gemm_core(const GTile& tl, const GTile& nx, bool has_next  , bool chain  , bool pre, u32x4 (&ra)[4], u32x4 (&rb)[4], char* smem, f32x16 (&acc)[2][4]) {
;     ...
;   const int nk = K / 64;
;   if (!pre) { G_LOAD(0); G_STORE(0); G_LOAD(1); }
;   for (int kt = 0; kt < nk; ++kt) {
;     __syncthreads();
;     G_COMPUTE(kt & 1, kt);
; DI void phase_gemm_out(const Params& p, char* smem, const bf16_t* Wt, const float* R, float* O) {
;     ...
;   for (int t = blockIdx.x; t < 64 * 8; t += gridDim.x) {
;     const int mt = t & 63, nt = t >> 6, tn = t + gridDim.x;
;     const bool has_next = tn < 64 * 8;
;     const GTile tl{p.h(), D, Wt, D, D, mt * 256, nt * 256}, nx{p.h(), D, Wt, D, D, (tn & 63) * 256, (tn >> 6) * 256};
;     WAVE_GEOM;
;     f32x16 acc[2][4];
;     gemm_core<false>(tl, nx, has_next, has_next, pre, ra, rb, smem, acc);
.LBB0_749:
	v_lshl_add_u64 v[128:129], s[2:3], 0, v[184:185]
	v_lshl_add_u64 v[132:133], s[6:7], 0, v[184:185]
	s_waitcnt lgkmcnt(0)
	s_barrier
	global_load_dwordx4 v[198:201], v[128:129], off offset:256
	global_load_dwordx4 v[202:205], v[132:133], off offset:256
	s_add_i32 s38, s38, s96
	s_cmpk_lt_i32 s38, 0x200
	s_cselect_b64 s[14:15], -1, 0
	s_cmpk_gt_i32 s38, 0x1ff
	s_cselect_b64 s[12:13], -1, 0
	s_and_b32 s3, s28, 0x1f80000
	s_add_i32 s24, s25, s24
	s_and_b32 s2, s24, 0xffffff00
	s_and_b32 s40, s33, 0xc0
	s_lshl_b32 s3, s3, 1
	s_add_u32 s6, s18, s3
	s_addc_u32 s7, s19, 0
	s_ashr_i32 s3, s2, 31
	s_lshl_b64 s[2:3], s[2:3], 12
	s_add_u32 s2, s16, s2
	s_addc_u32 s3, s17, s3
	s_lshr_b32 s33, s33, 1
	v_and_b32_e32 v11, 31, v8
	s_and_b32 s33, s33, 0xfffff80
	v_or_b32_e32 v12, s33, v11
	v_or_b32_e32 v11, s40, v11
	v_add3_u32 v191, 16, v10, v9
	v_lshrrev_b32_e32 v8, 1, v8
	v_mul_u32_u24_e32 v131, 0x90, v11
	v_and_b32_e32 v134, 16, v8
	v_add_u32_e32 v195, 0x12000, v191
	v_mul_lo_u32 v130, v12, s35
	v_add3_u32 v192, 16, v131, v134
	v_add_u32_e32 v196, 0x1b000, v191
	ds_write_b128 v195, v[0:3]
	s_waitcnt vmcnt(5)
	ds_write_b128 v196, v[4:7]
	v_lshl_add_u64 v[188:189], s[6:7], 0, v[184:185]
	v_lshl_add_u64 v[186:187], s[2:3], 0, v[184:185]
	v_add3_u32 v184, 16, v130, v134
	ds_read_b128 v[0:3], v192 offset:36864
	ds_read_b128 v[4:7], v192 offset:41472
	ds_read_b128 v[8:11], v184
	ds_read_b128 v[12:15], v184 offset:4608
	v_lshl_add_u64 v[136:137], v[128:129], 0, s[0:1]
	v_lshl_add_u64 v[140:141], v[132:133], 0, s[0:1]
	v_lshl_add_u64 v[144:145], v[128:129], 0, s[8:9]
	v_lshl_add_u64 v[148:149], v[132:133], 0, s[8:9]
	s_setprio 1
	s_waitcnt lgkmcnt(1)
	v_mfma_f32_32x32x16_bf16 v[112:127], v[0:3], v[8:11], 0
	v_mfma_f32_32x32x16_bf16 v[48:63], v[4:7], v[8:11], 0
	s_waitcnt lgkmcnt(0)
	v_mfma_f32_32x32x16_bf16 v[96:111], v[0:3], v[12:15], 0
	v_mfma_f32_32x32x16_bf16 v[32:47], v[4:7], v[12:15], 0
	ds_read_b128 v[8:11], v184 offset:9216
	ds_read_b128 v[12:15], v184 offset:13824
	s_waitcnt lgkmcnt(1)
	v_mfma_f32_32x32x16_bf16 v[80:95], v[0:3], v[8:11], 0
	v_mfma_f32_32x32x16_bf16 v[16:31], v[4:7], v[8:11], 0
	s_waitcnt lgkmcnt(0)
	v_mfma_f32_32x32x16_bf16 v[64:79], v[0:3], v[12:15], 0
	v_mfma_f32_32x32x16_bf16 v[0:15], v[4:7], v[12:15], 0
	s_setprio 0
	global_load_dwordx4 v[208:211], v[136:137], off offset:256
	global_load_dwordx4 v[212:215], v[140:141], off offset:256
	v_add_u32_e32 v194, 0x14400, v191
	v_add_u32_e32 v193, 0x1d400, v191
	ds_write_b128 v194, v[176:179]
	s_waitcnt vmcnt(6)
	ds_write_b128 v193, v[180:183]
	ds_read_b128 v[150:153], v192 offset:36896
	ds_read_b128 v[154:157], v192 offset:41504
	ds_read_b128 v[176:179], v184 offset:32
	ds_read_b128 v[180:183], v184 offset:4640
	s_setprio 1
	s_waitcnt lgkmcnt(1)
	v_mfma_f32_32x32x16_bf16 v[112:127], v[150:153], v[176:179], v[112:127]
	v_mfma_f32_32x32x16_bf16 v[48:63], v[154:157], v[176:179], v[48:63]
	s_waitcnt lgkmcnt(0)
	v_mfma_f32_32x32x16_bf16 v[96:111], v[150:153], v[180:183], v[96:111]
	v_mfma_f32_32x32x16_bf16 v[32:47], v[154:157], v[180:183], v[32:47]
	ds_read_b128 v[176:179], v184 offset:9248
	ds_read_b128 v[180:183], v184 offset:13856
	s_waitcnt lgkmcnt(1)
	v_mfma_f32_32x32x16_bf16 v[80:95], v[150:153], v[176:179], v[80:95]
	v_mfma_f32_32x32x16_bf16 v[16:31], v[154:157], v[176:179], v[16:31]
	s_waitcnt lgkmcnt(0)
	v_mfma_f32_32x32x16_bf16 v[64:79], v[150:153], v[180:183], v[64:79]
	v_mfma_f32_32x32x16_bf16 v[0:15], v[154:157], v[180:183], v[0:15]
	s_setprio 0
	global_load_dwordx4 v[178:181], v[144:145], off offset:256
	global_load_dwordx4 v[216:219], v[148:149], off offset:256
	v_add_u32_e32 v177, 0x16800, v191
	v_add_u32_e32 v176, 0x1f800, v191
	ds_write_b128 v177, v[168:171]
	s_waitcnt vmcnt(7)
	ds_write_b128 v176, v[172:175]
	ds_read_b128 v[150:153], v192 offset:36928
	ds_read_b128 v[154:157], v192 offset:41536
	ds_read_b128 v[168:171], v184 offset:64
	ds_read_b128 v[172:175], v184 offset:4672
	s_setprio 1
	s_waitcnt lgkmcnt(1)
	v_mfma_f32_32x32x16_bf16 v[112:127], v[150:153], v[168:171], v[112:127]
	v_mfma_f32_32x32x16_bf16 v[48:63], v[154:157], v[168:171], v[48:63]
	s_waitcnt lgkmcnt(0)
	v_mfma_f32_32x32x16_bf16 v[96:111], v[150:153], v[172:175], v[96:111]
	v_mfma_f32_32x32x16_bf16 v[32:47], v[154:157], v[172:175], v[32:47]
	ds_read_b128 v[168:171], v184 offset:9280
	ds_read_b128 v[172:175], v184 offset:13888
	s_waitcnt lgkmcnt(1)
	v_mfma_f32_32x32x16_bf16 v[80:95], v[150:153], v[168:171], v[80:95]
	v_mfma_f32_32x32x16_bf16 v[16:31], v[154:157], v[168:171], v[16:31]
	s_waitcnt lgkmcnt(0)
	v_mfma_f32_32x32x16_bf16 v[64:79], v[150:153], v[172:175], v[64:79]
	v_mfma_f32_32x32x16_bf16 v[0:15], v[154:157], v[172:175], v[0:15]
	s_setprio 0
	v_add_co_u32_e32 v152, vcc, s34, v128
	v_add_u32_e32 v171, 0x18c00, v191
	s_nop 0
	v_addc_co_u32_e32 v153, vcc, 0, v129, vcc
	v_add_co_u32_e32 v156, vcc, s34, v132
	v_add_u32_e32 v170, 0x21c00, v191
	s_nop 0
	v_addc_co_u32_e32 v157, vcc, 0, v133, vcc
	global_load_dwordx4 v[172:175], v[152:153], off offset:256
	global_load_dwordx4 v[220:223], v[156:157], off offset:256
	ds_write_b128 v171, v[160:163]
	s_waitcnt vmcnt(8)
	ds_write_b128 v170, v[164:167]
	ds_read_b128 v[158:161], v192 offset:36960
	ds_read_b128 v[162:165], v192 offset:41568
	ds_read_b128 v[166:169], v184 offset:96
	ds_read_b128 v[224:227], v184 offset:4704
	s_setprio 1
	s_waitcnt lgkmcnt(1)
	v_mfma_f32_32x32x16_bf16 v[112:127], v[158:161], v[166:169], v[112:127]
	v_mfma_f32_32x32x16_bf16 v[48:63], v[162:165], v[166:169], v[48:63]
	s_waitcnt lgkmcnt(0)
	v_mfma_f32_32x32x16_bf16 v[96:111], v[158:161], v[224:227], v[96:111]
	v_mfma_f32_32x32x16_bf16 v[32:47], v[162:165], v[224:227], v[32:47]
	ds_read_b128 v[166:169], v184 offset:9312
	ds_read_b128 v[224:227], v184 offset:13920
	s_waitcnt lgkmcnt(1)
	v_mfma_f32_32x32x16_bf16 v[80:95], v[158:161], v[166:169], v[80:95]
	v_mfma_f32_32x32x16_bf16 v[16:31], v[162:165], v[166:169], v[16:31]
	s_waitcnt lgkmcnt(0)
	v_mfma_f32_32x32x16_bf16 v[64:79], v[158:161], v[224:227], v[64:79]
	v_mfma_f32_32x32x16_bf16 v[0:15], v[162:165], v[224:227], v[0:15]
	s_setprio 0
	s_barrier
; template <bool trans>
; DI void gemm_core(const GTile& tl, const GTile& nx, bool has_next  , bool chain  , bool pre, u32x4 (&ra)[4], u32x4 (&rb)[4], char* smem, f32x16 (&acc)[2][4]) {
;     ...
;   const int nk = K / 64;
;   if (!pre) { G_LOAD(0); G_STORE(0); G_LOAD(1); }
;   for (int kt = 0; kt < nk; ++kt) {
;     __syncthreads();
;     G_COMPUTE(kt & 1, kt);
	global_load_dwordx4 v[158:161], v[128:129], off offset:384
	global_load_dwordx4 v[162:165], v[132:133], off offset:384
	v_add3_u32 v169, s37, v131, v134
	s_waitcnt vmcnt(9)
	ds_write_b128 v191, v[198:201]
	s_waitcnt vmcnt(8)
	ds_write_b128 v191, v[202:205] offset:36864
	v_add3_u32 v168, s36, v130, v134
	ds_read_b128 v[198:201], v169
	ds_read_b128 v[202:205], v169 offset:4608
	ds_read_b128 v[224:227], v168
	ds_read_b128 v[228:231], v168 offset:4608
	s_setprio 1
	s_waitcnt lgkmcnt(1)
	v_mfma_f32_32x32x16_bf16 v[112:127], v[198:201], v[224:227], v[112:127]
	v_mfma_f32_32x32x16_bf16 v[48:63], v[202:205], v[224:227], v[48:63]
	s_waitcnt lgkmcnt(0)
	v_mfma_f32_32x32x16_bf16 v[96:111], v[198:201], v[228:231], v[96:111]
	v_mfma_f32_32x32x16_bf16 v[32:47], v[202:205], v[228:231], v[32:47]
	ds_read_b128 v[224:227], v168 offset:9216
	ds_read_b128 v[228:231], v168 offset:13824
	s_waitcnt lgkmcnt(1)
	v_mfma_f32_32x32x16_bf16 v[80:95], v[198:201], v[224:227], v[80:95]
	v_mfma_f32_32x32x16_bf16 v[16:31], v[202:205], v[224:227], v[16:31]
	s_waitcnt lgkmcnt(0)
	v_mfma_f32_32x32x16_bf16 v[64:79], v[198:201], v[228:231], v[64:79]
	v_mfma_f32_32x32x16_bf16 v[0:15], v[202:205], v[228:231], v[0:15]
	s_setprio 0
	global_load_dwordx4 v[198:201], v[136:137], off offset:384
	global_load_dwordx4 v[202:205], v[140:141], off offset:384
	s_waitcnt vmcnt(9)
	ds_write_b128 v191, v[208:211] offset:9216
	s_waitcnt vmcnt(8)
	ds_write_b128 v191, v[212:215] offset:46080
	ds_read_b128 v[208:211], v169 offset:32
	ds_read_b128 v[212:215], v169 offset:4640
	ds_read_b128 v[224:227], v168 offset:32
	ds_read_b128 v[228:231], v168 offset:4640
	s_setprio 1
	s_waitcnt lgkmcnt(1)
	v_mfma_f32_32x32x16_bf16 v[112:127], v[208:211], v[224:227], v[112:127]
	v_mfma_f32_32x32x16_bf16 v[48:63], v[212:215], v[224:227], v[48:63]
	s_waitcnt lgkmcnt(0)
	v_mfma_f32_32x32x16_bf16 v[96:111], v[208:211], v[228:231], v[96:111]
	v_mfma_f32_32x32x16_bf16 v[32:47], v[212:215], v[228:231], v[32:47]
	ds_read_b128 v[224:227], v168 offset:9248
	ds_read_b128 v[228:231], v168 offset:13856
	s_waitcnt lgkmcnt(1)
	v_mfma_f32_32x32x16_bf16 v[80:95], v[208:211], v[224:227], v[80:95]
	v_mfma_f32_32x32x16_bf16 v[16:31], v[212:215], v[224:227], v[16:31]
	s_waitcnt lgkmcnt(0)
	v_mfma_f32_32x32x16_bf16 v[64:79], v[208:211], v[228:231], v[64:79]
	v_mfma_f32_32x32x16_bf16 v[0:15], v[212:215], v[228:231], v[0:15]
	s_setprio 0
	global_load_dwordx4 v[208:211], v[144:145], off offset:384
	global_load_dwordx4 v[212:215], v[148:149], off offset:384
	s_waitcnt vmcnt(9)
	ds_write_b128 v191, v[178:181] offset:18432
	s_waitcnt vmcnt(8)
	ds_write_b128 v191, v[216:219] offset:55296
	ds_read_b128 v[178:181], v169 offset:64
	ds_read_b128 v[216:219], v169 offset:4672
	ds_read_b128 v[224:227], v168 offset:64
	ds_read_b128 v[228:231], v168 offset:4672
	s_setprio 1
	s_waitcnt lgkmcnt(1)
	v_mfma_f32_32x32x16_bf16 v[112:127], v[178:181], v[224:227], v[112:127]
	v_mfma_f32_32x32x16_bf16 v[48:63], v[216:219], v[224:227], v[48:63]
	s_waitcnt lgkmcnt(0)
	v_mfma_f32_32x32x16_bf16 v[96:111], v[178:181], v[228:231], v[96:111]
	v_mfma_f32_32x32x16_bf16 v[32:47], v[216:219], v[228:231], v[32:47]
	ds_read_b128 v[224:227], v168 offset:9280
	ds_read_b128 v[228:231], v168 offset:13888
	s_waitcnt lgkmcnt(1)
	v_mfma_f32_32x32x16_bf16 v[80:95], v[178:181], v[224:227], v[80:95]
	v_mfma_f32_32x32x16_bf16 v[16:31], v[216:219], v[224:227], v[16:31]
	s_waitcnt lgkmcnt(0)
	v_mfma_f32_32x32x16_bf16 v[64:79], v[178:181], v[228:231], v[64:79]
	v_mfma_f32_32x32x16_bf16 v[0:15], v[216:219], v[228:231], v[0:15]
	s_setprio 0
	global_load_dwordx4 v[178:181], v[152:153], off offset:384
	global_load_dwordx4 v[216:219], v[156:157], off offset:384
	s_waitcnt vmcnt(9)
	ds_write_b128 v191, v[172:175] offset:27648
	s_waitcnt vmcnt(8)
	ds_write_b128 v191, v[220:223] offset:64512
	ds_read_b128 v[172:175], v169 offset:96
	ds_read_b128 v[220:223], v169 offset:4704
	ds_read_b128 v[224:227], v168 offset:96
	ds_read_b128 v[228:231], v168 offset:4704
	s_setprio 1
	s_waitcnt lgkmcnt(1)
	v_mfma_f32_32x32x16_bf16 v[112:127], v[172:175], v[224:227], v[112:127]
	v_mfma_f32_32x32x16_bf16 v[48:63], v[220:223], v[224:227], v[48:63]
	s_waitcnt lgkmcnt(0)
	v_mfma_f32_32x32x16_bf16 v[96:111], v[172:175], v[228:231], v[96:111]
	v_mfma_f32_32x32x16_bf16 v[32:47], v[220:223], v[228:231], v[32:47]
	ds_read_b128 v[224:227], v168 offset:9312
	ds_read_b128 v[228:231], v168 offset:13920
	s_waitcnt lgkmcnt(1)
	v_mfma_f32_32x32x16_bf16 v[80:95], v[172:175], v[224:227], v[80:95]
	v_mfma_f32_32x32x16_bf16 v[16:31], v[220:223], v[224:227], v[16:31]
	s_waitcnt lgkmcnt(0)
	v_mfma_f32_32x32x16_bf16 v[64:79], v[172:175], v[228:231], v[64:79]
	v_mfma_f32_32x32x16_bf16 v[0:15], v[220:223], v[228:231], v[0:15]
	s_setprio 0
	s_barrier
; template <bool trans>
; DI void gemm_core(const GTile& tl, const GTile& nx, bool has_next  , bool chain  , bool pre, u32x4 (&ra)[4], u32x4 (&rb)[4], char* smem, f32x16 (&acc)[2][4]) {
;     ...
;   const int nk = K / 64;
;   if (!pre) { G_LOAD(0); G_STORE(0); G_LOAD(1); }
;   for (int kt = 0; kt < nk; ++kt) {
;     __syncthreads();
;     G_COMPUTE(kt & 1, kt);
	global_load_dwordx4 v[172:175], v[128:129], off offset:512
	global_load_dwordx4 v[220:223], v[132:133], off offset:512
	s_waitcnt vmcnt(9)
	ds_write_b128 v195, v[158:161]
	s_waitcnt vmcnt(8)
	ds_write_b128 v196, v[162:165]
	ds_read_b128 v[158:161], v192 offset:36864
	ds_read_b128 v[162:165], v192 offset:41472
	ds_read_b128 v[224:227], v184
	ds_read_b128 v[228:231], v184 offset:4608
	s_setprio 1
	s_waitcnt lgkmcnt(1)
	v_mfma_f32_32x32x16_bf16 v[112:127], v[158:161], v[224:227], v[112:127]
	v_mfma_f32_32x32x16_bf16 v[48:63], v[162:165], v[224:227], v[48:63]
	s_waitcnt lgkmcnt(0)
	v_mfma_f32_32x32x16_bf16 v[96:111], v[158:161], v[228:231], v[96:111]
	v_mfma_f32_32x32x16_bf16 v[32:47], v[162:165], v[228:231], v[32:47]
	ds_read_b128 v[224:227], v184 offset:9216
	ds_read_b128 v[228:231], v184 offset:13824
	s_waitcnt vmcnt(7)
	ds_write_b128 v194, v[198:201]
	s_waitcnt vmcnt(6)
	ds_write_b128 v193, v[202:205]
	ds_read_b128 v[198:201], v192 offset:36896
	ds_read_b128 v[202:205], v192 offset:41504
	s_waitcnt lgkmcnt(5)
	v_mfma_f32_32x32x16_bf16 v[80:95], v[158:161], v[224:227], v[80:95]
	v_mfma_f32_32x32x16_bf16 v[16:31], v[162:165], v[224:227], v[16:31]
	ds_read_b128 v[224:227], v184 offset:32
	s_waitcnt lgkmcnt(5)
	v_mfma_f32_32x32x16_bf16 v[64:79], v[158:161], v[228:231], v[64:79]
	v_mfma_f32_32x32x16_bf16 v[0:15], v[162:165], v[228:231], v[0:15]
	ds_read_b128 v[228:231], v184 offset:4640
	s_setprio 0
	global_load_dwordx4 v[158:161], v[136:137], off offset:512
	global_load_dwordx4 v[162:165], v[140:141], off offset:512
	s_setprio 1
	s_waitcnt lgkmcnt(1)
	v_mfma_f32_32x32x16_bf16 v[112:127], v[198:201], v[224:227], v[112:127]
	v_mfma_f32_32x32x16_bf16 v[48:63], v[202:205], v[224:227], v[48:63]
	s_waitcnt lgkmcnt(0)
	v_mfma_f32_32x32x16_bf16 v[96:111], v[198:201], v[228:231], v[96:111]
	v_mfma_f32_32x32x16_bf16 v[32:47], v[202:205], v[228:231], v[32:47]
	ds_read_b128 v[224:227], v184 offset:9248
	ds_read_b128 v[228:231], v184 offset:13856
	s_waitcnt vmcnt(7)
	ds_write_b128 v177, v[208:211]
	s_waitcnt vmcnt(6)
	ds_write_b128 v176, v[212:215]
	ds_read_b128 v[208:211], v192 offset:36928
	ds_read_b128 v[212:215], v192 offset:41536
	s_waitcnt lgkmcnt(5)
	v_mfma_f32_32x32x16_bf16 v[80:95], v[198:201], v[224:227], v[80:95]
	v_mfma_f32_32x32x16_bf16 v[16:31], v[202:205], v[224:227], v[16:31]
	ds_read_b128 v[224:227], v184 offset:64
	s_waitcnt lgkmcnt(5)
	v_mfma_f32_32x32x16_bf16 v[64:79], v[198:201], v[228:231], v[64:79]
	v_mfma_f32_32x32x16_bf16 v[0:15], v[202:205], v[228:231], v[0:15]
	ds_read_b128 v[228:231], v184 offset:4672
	s_setprio 0
	global_load_dwordx4 v[198:201], v[144:145], off offset:512
	global_load_dwordx4 v[202:205], v[148:149], off offset:512
	s_setprio 1
	s_waitcnt lgkmcnt(1)
	v_mfma_f32_32x32x16_bf16 v[112:127], v[208:211], v[224:227], v[112:127]
	v_mfma_f32_32x32x16_bf16 v[48:63], v[212:215], v[224:227], v[48:63]
	s_waitcnt lgkmcnt(0)
	v_mfma_f32_32x32x16_bf16 v[96:111], v[208:211], v[228:231], v[96:111]
	v_mfma_f32_32x32x16_bf16 v[32:47], v[212:215], v[228:231], v[32:47]
	ds_read_b128 v[224:227], v184 offset:9280
	ds_read_b128 v[228:231], v184 offset:13888
	s_waitcnt vmcnt(7)
	ds_write_b128 v171, v[178:181]
	s_waitcnt vmcnt(6)
	ds_write_b128 v170, v[216:219]
	ds_read_b128 v[178:181], v192 offset:36960
	ds_read_b128 v[216:219], v192 offset:41568
	s_waitcnt lgkmcnt(5)
	v_mfma_f32_32x32x16_bf16 v[80:95], v[208:211], v[224:227], v[80:95]
	v_mfma_f32_32x32x16_bf16 v[16:31], v[212:215], v[224:227], v[16:31]
	ds_read_b128 v[224:227], v184 offset:96
	s_waitcnt lgkmcnt(5)
	v_mfma_f32_32x32x16_bf16 v[64:79], v[208:211], v[228:231], v[64:79]
	v_mfma_f32_32x32x16_bf16 v[0:15], v[212:215], v[228:231], v[0:15]
	ds_read_b128 v[228:231], v184 offset:4704
	s_setprio 0
	global_load_dwordx4 v[208:211], v[152:153], off offset:512
	global_load_dwordx4 v[212:215], v[156:157], off offset:512
	s_setprio 1
	s_waitcnt lgkmcnt(1)
	v_mfma_f32_32x32x16_bf16 v[112:127], v[178:181], v[224:227], v[112:127]
	v_mfma_f32_32x32x16_bf16 v[48:63], v[216:219], v[224:227], v[48:63]
	s_waitcnt lgkmcnt(0)
	v_mfma_f32_32x32x16_bf16 v[96:111], v[178:181], v[228:231], v[96:111]
	v_mfma_f32_32x32x16_bf16 v[32:47], v[216:219], v[228:231], v[32:47]
	ds_read_b128 v[224:227], v184 offset:9312
	ds_read_b128 v[228:231], v184 offset:13920
	s_waitcnt lgkmcnt(1)
	v_mfma_f32_32x32x16_bf16 v[80:95], v[178:181], v[224:227], v[80:95]
	v_mfma_f32_32x32x16_bf16 v[16:31], v[216:219], v[224:227], v[16:31]
	s_waitcnt lgkmcnt(0)
	v_mfma_f32_32x32x16_bf16 v[64:79], v[178:181], v[228:231], v[64:79]
	v_mfma_f32_32x32x16_bf16 v[0:15], v[216:219], v[228:231], v[0:15]
	s_setprio 0
	s_barrier
	global_load_dwordx4 v[178:181], v[128:129], off offset:640
	global_load_dwordx4 v[216:219], v[132:133], off offset:640
	s_waitcnt vmcnt(9)
	ds_write_b128 v191, v[172:175]
	s_waitcnt vmcnt(8)
	ds_write_b128 v191, v[220:223] offset:36864
	ds_read_b128 v[172:175], v169
	ds_read_b128 v[220:223], v169 offset:4608
	ds_read_b128 v[224:227], v168
	ds_read_b128 v[228:231], v168 offset:4608
	s_setprio 1
	s_waitcnt lgkmcnt(1)
	v_mfma_f32_32x32x16_bf16 v[112:127], v[172:175], v[224:227], v[112:127]
	v_mfma_f32_32x32x16_bf16 v[48:63], v[220:223], v[224:227], v[48:63]
	s_waitcnt lgkmcnt(0)
	v_mfma_f32_32x32x16_bf16 v[96:111], v[172:175], v[228:231], v[96:111]
	v_mfma_f32_32x32x16_bf16 v[32:47], v[220:223], v[228:231], v[32:47]
	ds_read_b128 v[224:227], v168 offset:9216
	ds_read_b128 v[228:231], v168 offset:13824
	s_waitcnt vmcnt(7)
	ds_write_b128 v191, v[158:161] offset:9216
	s_waitcnt vmcnt(6)
	ds_write_b128 v191, v[162:165] offset:46080
	ds_read_b128 v[158:161], v169 offset:32
	ds_read_b128 v[162:165], v169 offset:4640
	s_waitcnt lgkmcnt(5)
	v_mfma_f32_32x32x16_bf16 v[80:95], v[172:175], v[224:227], v[80:95]
	v_mfma_f32_32x32x16_bf16 v[16:31], v[220:223], v[224:227], v[16:31]
	ds_read_b128 v[224:227], v168 offset:32
	s_waitcnt lgkmcnt(5)
	v_mfma_f32_32x32x16_bf16 v[64:79], v[172:175], v[228:231], v[64:79]
	v_mfma_f32_32x32x16_bf16 v[0:15], v[220:223], v[228:231], v[0:15]
	ds_read_b128 v[228:231], v168 offset:4640
	s_setprio 0
	global_load_dwordx4 v[172:175], v[136:137], off offset:640
	global_load_dwordx4 v[220:223], v[140:141], off offset:640
	s_setprio 1
	s_waitcnt lgkmcnt(1)
	v_mfma_f32_32x32x16_bf16 v[112:127], v[158:161], v[224:227], v[112:127]
	v_mfma_f32_32x32x16_bf16 v[48:63], v[162:165], v[224:227], v[48:63]
	s_waitcnt lgkmcnt(0)
	v_mfma_f32_32x32x16_bf16 v[96:111], v[158:161], v[228:231], v[96:111]
	v_mfma_f32_32x32x16_bf16 v[32:47], v[162:165], v[228:231], v[32:47]
	ds_read_b128 v[224:227], v168 offset:9248
	ds_read_b128 v[228:231], v168 offset:13856
	s_waitcnt vmcnt(7)
	ds_write_b128 v191, v[198:201] offset:18432
	s_waitcnt vmcnt(6)
	ds_write_b128 v191, v[202:205] offset:55296
	ds_read_b128 v[198:201], v169 offset:64
	ds_read_b128 v[202:205], v169 offset:4672
	s_waitcnt lgkmcnt(5)
	v_mfma_f32_32x32x16_bf16 v[80:95], v[158:161], v[224:227], v[80:95]
	v_mfma_f32_32x32x16_bf16 v[16:31], v[162:165], v[224:227], v[16:31]
	ds_read_b128 v[224:227], v168 offset:64
	s_waitcnt lgkmcnt(5)
	v_mfma_f32_32x32x16_bf16 v[64:79], v[158:161], v[228:231], v[64:79]
	v_mfma_f32_32x32x16_bf16 v[0:15], v[162:165], v[228:231], v[0:15]
	ds_read_b128 v[228:231], v168 offset:4672
	s_setprio 0
	global_load_dwordx4 v[158:161], v[144:145], off offset:640
	global_load_dwordx4 v[162:165], v[148:149], off offset:640
	s_setprio 1
	s_waitcnt lgkmcnt(1)
	v_mfma_f32_32x32x16_bf16 v[112:127], v[198:201], v[224:227], v[112:127]
	v_mfma_f32_32x32x16_bf16 v[48:63], v[202:205], v[224:227], v[48:63]
	s_waitcnt lgkmcnt(0)
	v_mfma_f32_32x32x16_bf16 v[96:111], v[198:201], v[228:231], v[96:111]
	v_mfma_f32_32x32x16_bf16 v[32:47], v[202:205], v[228:231], v[32:47]
	ds_read_b128 v[224:227], v168 offset:9280
	ds_read_b128 v[228:231], v168 offset:13888
	s_waitcnt vmcnt(7)
	ds_write_b128 v191, v[208:211] offset:27648
	s_waitcnt vmcnt(6)
	ds_write_b128 v191, v[212:215] offset:64512
	ds_read_b128 v[208:211], v169 offset:96
	ds_read_b128 v[212:215], v169 offset:4704
	s_waitcnt lgkmcnt(5)
	v_mfma_f32_32x32x16_bf16 v[80:95], v[198:201], v[224:227], v[80:95]
	v_mfma_f32_32x32x16_bf16 v[16:31], v[202:205], v[224:227], v[16:31]
	ds_read_b128 v[224:227], v168 offset:96
	s_waitcnt lgkmcnt(5)
	v_mfma_f32_32x32x16_bf16 v[64:79], v[198:201], v[228:231], v[64:79]
	v_mfma_f32_32x32x16_bf16 v[0:15], v[202:205], v[228:231], v[0:15]
	ds_read_b128 v[228:231], v168 offset:4704
	s_setprio 0
	global_load_dwordx4 v[198:201], v[152:153], off offset:640
	global_load_dwordx4 v[202:205], v[156:157], off offset:640
	s_setprio 1
	s_waitcnt lgkmcnt(1)
	v_mfma_f32_32x32x16_bf16 v[112:127], v[208:211], v[224:227], v[112:127]
	v_mfma_f32_32x32x16_bf16 v[48:63], v[212:215], v[224:227], v[48:63]
	s_waitcnt lgkmcnt(0)
	v_mfma_f32_32x32x16_bf16 v[96:111], v[208:211], v[228:231], v[96:111]
	v_mfma_f32_32x32x16_bf16 v[32:47], v[212:215], v[228:231], v[32:47]
	ds_read_b128 v[224:227], v168 offset:9312
	ds_read_b128 v[228:231], v168 offset:13920
	s_waitcnt lgkmcnt(1)
	v_mfma_f32_32x32x16_bf16 v[80:95], v[208:211], v[224:227], v[80:95]
	v_mfma_f32_32x32x16_bf16 v[16:31], v[212:215], v[224:227], v[16:31]
	s_waitcnt lgkmcnt(0)
	v_mfma_f32_32x32x16_bf16 v[64:79], v[208:211], v[228:231], v[64:79]
	v_mfma_f32_32x32x16_bf16 v[0:15], v[212:215], v[228:231], v[0:15]
	s_setprio 0
	s_barrier
	global_load_dwordx4 v[208:211], v[128:129], off offset:768
	global_load_dwordx4 v[212:215], v[132:133], off offset:768
	s_waitcnt vmcnt(9)
	ds_write_b128 v195, v[178:181]
	s_waitcnt vmcnt(8)
	ds_write_b128 v196, v[216:219]
	ds_read_b128 v[178:181], v192 offset:36864
	ds_read_b128 v[216:219], v192 offset:41472
	ds_read_b128 v[224:227], v184
	ds_read_b128 v[228:231], v184 offset:4608
	s_setprio 1
	s_waitcnt lgkmcnt(1)
	v_mfma_f32_32x32x16_bf16 v[112:127], v[178:181], v[224:227], v[112:127]
	v_mfma_f32_32x32x16_bf16 v[48:63], v[216:219], v[224:227], v[48:63]
	s_waitcnt lgkmcnt(0)
	v_mfma_f32_32x32x16_bf16 v[96:111], v[178:181], v[228:231], v[96:111]
	v_mfma_f32_32x32x16_bf16 v[32:47], v[216:219], v[228:231], v[32:47]
	ds_read_b128 v[224:227], v184 offset:9216
	ds_read_b128 v[228:231], v184 offset:13824
	s_waitcnt vmcnt(7)
	ds_write_b128 v194, v[172:175]
	s_waitcnt vmcnt(6)
	ds_write_b128 v193, v[220:223]
	ds_read_b128 v[172:175], v192 offset:36896
	ds_read_b128 v[220:223], v192 offset:41504
	s_waitcnt lgkmcnt(5)
	v_mfma_f32_32x32x16_bf16 v[80:95], v[178:181], v[224:227], v[80:95]
	v_mfma_f32_32x32x16_bf16 v[16:31], v[216:219], v[224:227], v[16:31]
	ds_read_b128 v[224:227], v184 offset:32
	s_waitcnt lgkmcnt(5)
	v_mfma_f32_32x32x16_bf16 v[64:79], v[178:181], v[228:231], v[64:79]
	v_mfma_f32_32x32x16_bf16 v[0:15], v[216:219], v[228:231], v[0:15]
	ds_read_b128 v[228:231], v184 offset:4640
	s_setprio 0
	global_load_dwordx4 v[178:181], v[136:137], off offset:768
	global_load_dwordx4 v[216:219], v[140:141], off offset:768
	s_setprio 1
	s_waitcnt lgkmcnt(1)
	v_mfma_f32_32x32x16_bf16 v[112:127], v[172:175], v[224:227], v[112:127]
	v_mfma_f32_32x32x16_bf16 v[48:63], v[220:223], v[224:227], v[48:63]
	s_waitcnt lgkmcnt(0)
	v_mfma_f32_32x32x16_bf16 v[96:111], v[172:175], v[228:231], v[96:111]
	v_mfma_f32_32x32x16_bf16 v[32:47], v[220:223], v[228:231], v[32:47]
	ds_read_b128 v[224:227], v184 offset:9248
	ds_read_b128 v[228:231], v184 offset:13856
	s_waitcnt vmcnt(7)
	ds_write_b128 v177, v[158:161]
	s_waitcnt vmcnt(6)
	ds_write_b128 v176, v[162:165]
	ds_read_b128 v[158:161], v192 offset:36928
	ds_read_b128 v[162:165], v192 offset:41536
	s_waitcnt lgkmcnt(5)
	v_mfma_f32_32x32x16_bf16 v[80:95], v[172:175], v[224:227], v[80:95]
	v_mfma_f32_32x32x16_bf16 v[16:31], v[220:223], v[224:227], v[16:31]
	ds_read_b128 v[224:227], v184 offset:64
	s_waitcnt lgkmcnt(5)
	v_mfma_f32_32x32x16_bf16 v[64:79], v[172:175], v[228:231], v[64:79]
	v_mfma_f32_32x32x16_bf16 v[0:15], v[220:223], v[228:231], v[0:15]
	ds_read_b128 v[228:231], v184 offset:4672
	s_setprio 0
	global_load_dwordx4 v[172:175], v[144:145], off offset:768
	global_load_dwordx4 v[220:223], v[148:149], off offset:768
	s_setprio 1
	s_waitcnt lgkmcnt(1)
	v_mfma_f32_32x32x16_bf16 v[112:127], v[158:161], v[224:227], v[112:127]
	v_mfma_f32_32x32x16_bf16 v[48:63], v[162:165], v[224:227], v[48:63]
	s_waitcnt lgkmcnt(0)
	v_mfma_f32_32x32x16_bf16 v[96:111], v[158:161], v[228:231], v[96:111]
	v_mfma_f32_32x32x16_bf16 v[32:47], v[162:165], v[228:231], v[32:47]
	ds_read_b128 v[224:227], v184 offset:9280
	ds_read_b128 v[228:231], v184 offset:13888
	s_waitcnt vmcnt(7)
	ds_write_b128 v171, v[198:201]
	s_waitcnt vmcnt(6)
	ds_write_b128 v170, v[202:205]
	ds_read_b128 v[198:201], v192 offset:36960
	ds_read_b128 v[202:205], v192 offset:41568
	s_waitcnt lgkmcnt(5)
	v_mfma_f32_32x32x16_bf16 v[80:95], v[158:161], v[224:227], v[80:95]
	v_mfma_f32_32x32x16_bf16 v[16:31], v[162:165], v[224:227], v[16:31]
	ds_read_b128 v[224:227], v184 offset:96
	s_waitcnt lgkmcnt(5)
	v_mfma_f32_32x32x16_bf16 v[64:79], v[158:161], v[228:231], v[64:79]
	v_mfma_f32_32x32x16_bf16 v[0:15], v[162:165], v[228:231], v[0:15]
	ds_read_b128 v[228:231], v184 offset:4704
	s_setprio 0
	global_load_dwordx4 v[158:161], v[152:153], off offset:768
	global_load_dwordx4 v[162:165], v[156:157], off offset:768
	s_setprio 1
	s_waitcnt lgkmcnt(1)
	v_mfma_f32_32x32x16_bf16 v[112:127], v[198:201], v[224:227], v[112:127]
	v_mfma_f32_32x32x16_bf16 v[48:63], v[202:205], v[224:227], v[48:63]
	s_waitcnt lgkmcnt(0)
	v_mfma_f32_32x32x16_bf16 v[96:111], v[198:201], v[228:231], v[96:111]
	v_mfma_f32_32x32x16_bf16 v[32:47], v[202:205], v[228:231], v[32:47]
	ds_read_b128 v[224:227], v184 offset:9312
	ds_read_b128 v[228:231], v184 offset:13920
	s_waitcnt lgkmcnt(1)
	v_mfma_f32_32x32x16_bf16 v[80:95], v[198:201], v[224:227], v[80:95]
	v_mfma_f32_32x32x16_bf16 v[16:31], v[202:205], v[224:227], v[16:31]
	s_waitcnt lgkmcnt(0)
	v_mfma_f32_32x32x16_bf16 v[64:79], v[198:201], v[228:231], v[64:79]
	v_mfma_f32_32x32x16_bf16 v[0:15], v[202:205], v[228:231], v[0:15]
	s_setprio 0
	s_barrier
	global_load_dwordx4 v[198:201], v[128:129], off offset:896
	global_load_dwordx4 v[202:205], v[132:133], off offset:896
	s_waitcnt vmcnt(9)
	ds_write_b128 v191, v[208:211]
	s_waitcnt vmcnt(8)
	ds_write_b128 v191, v[212:215] offset:36864
	ds_read_b128 v[208:211], v169
	ds_read_b128 v[212:215], v169 offset:4608
	ds_read_b128 v[224:227], v168
	ds_read_b128 v[228:231], v168 offset:4608
	s_setprio 1
	s_waitcnt lgkmcnt(1)
	v_mfma_f32_32x32x16_bf16 v[112:127], v[208:211], v[224:227], v[112:127]
	v_mfma_f32_32x32x16_bf16 v[48:63], v[212:215], v[224:227], v[48:63]
	s_waitcnt lgkmcnt(0)
	v_mfma_f32_32x32x16_bf16 v[96:111], v[208:211], v[228:231], v[96:111]
	v_mfma_f32_32x32x16_bf16 v[32:47], v[212:215], v[228:231], v[32:47]
	ds_read_b128 v[224:227], v168 offset:9216
	ds_read_b128 v[228:231], v168 offset:13824
	s_waitcnt vmcnt(7)
	ds_write_b128 v191, v[178:181] offset:9216
	s_waitcnt vmcnt(6)
	ds_write_b128 v191, v[216:219] offset:46080
	ds_read_b128 v[178:181], v169 offset:32
	ds_read_b128 v[216:219], v169 offset:4640
	s_waitcnt lgkmcnt(5)
	v_mfma_f32_32x32x16_bf16 v[80:95], v[208:211], v[224:227], v[80:95]
	v_mfma_f32_32x32x16_bf16 v[16:31], v[212:215], v[224:227], v[16:31]
	ds_read_b128 v[224:227], v168 offset:32
	s_waitcnt lgkmcnt(5)
	v_mfma_f32_32x32x16_bf16 v[64:79], v[208:211], v[228:231], v[64:79]
	v_mfma_f32_32x32x16_bf16 v[0:15], v[212:215], v[228:231], v[0:15]
	ds_read_b128 v[228:231], v168 offset:4640
	s_setprio 0
	global_load_dwordx4 v[208:211], v[136:137], off offset:896
	global_load_dwordx4 v[212:215], v[140:141], off offset:896
	s_setprio 1
	s_waitcnt lgkmcnt(1)
	v_mfma_f32_32x32x16_bf16 v[112:127], v[178:181], v[224:227], v[112:127]
	v_mfma_f32_32x32x16_bf16 v[48:63], v[216:219], v[224:227], v[48:63]
	s_waitcnt lgkmcnt(0)
	v_mfma_f32_32x32x16_bf16 v[96:111], v[178:181], v[228:231], v[96:111]
	v_mfma_f32_32x32x16_bf16 v[32:47], v[216:219], v[228:231], v[32:47]
	ds_read_b128 v[224:227], v168 offset:9248
	ds_read_b128 v[228:231], v168 offset:13856
	s_waitcnt vmcnt(7)
	ds_write_b128 v191, v[172:175] offset:18432
	s_waitcnt vmcnt(6)
	ds_write_b128 v191, v[220:223] offset:55296
	ds_read_b128 v[172:175], v169 offset:64
	ds_read_b128 v[220:223], v169 offset:4672
	s_waitcnt lgkmcnt(5)
	v_mfma_f32_32x32x16_bf16 v[80:95], v[178:181], v[224:227], v[80:95]
	v_mfma_f32_32x32x16_bf16 v[16:31], v[216:219], v[224:227], v[16:31]
	ds_read_b128 v[224:227], v168 offset:64
	s_waitcnt lgkmcnt(5)
	v_mfma_f32_32x32x16_bf16 v[64:79], v[178:181], v[228:231], v[64:79]
	v_mfma_f32_32x32x16_bf16 v[0:15], v[216:219], v[228:231], v[0:15]
	ds_read_b128 v[228:231], v168 offset:4672
	s_setprio 0
	global_load_dwordx4 v[178:181], v[144:145], off offset:896
	global_load_dwordx4 v[216:219], v[148:149], off offset:896
	s_setprio 1
	s_waitcnt lgkmcnt(1)
	v_mfma_f32_32x32x16_bf16 v[112:127], v[172:175], v[224:227], v[112:127]
	v_mfma_f32_32x32x16_bf16 v[48:63], v[220:223], v[224:227], v[48:63]
	s_waitcnt lgkmcnt(0)
	v_mfma_f32_32x32x16_bf16 v[96:111], v[172:175], v[228:231], v[96:111]
	v_mfma_f32_32x32x16_bf16 v[32:47], v[220:223], v[228:231], v[32:47]
	ds_read_b128 v[224:227], v168 offset:9280
	ds_read_b128 v[228:231], v168 offset:13888
	s_waitcnt vmcnt(7)
	ds_write_b128 v191, v[158:161] offset:27648
	s_waitcnt vmcnt(6)
	ds_write_b128 v191, v[162:165] offset:64512
	ds_read_b128 v[158:161], v169 offset:96
	ds_read_b128 v[162:165], v169 offset:4704
	s_waitcnt lgkmcnt(5)
	v_mfma_f32_32x32x16_bf16 v[80:95], v[172:175], v[224:227], v[80:95]
	v_mfma_f32_32x32x16_bf16 v[16:31], v[220:223], v[224:227], v[16:31]
	ds_read_b128 v[224:227], v168 offset:96
	s_waitcnt lgkmcnt(5)
	v_mfma_f32_32x32x16_bf16 v[64:79], v[172:175], v[228:231], v[64:79]
	v_mfma_f32_32x32x16_bf16 v[0:15], v[220:223], v[228:231], v[0:15]
	ds_read_b128 v[228:231], v168 offset:4704
	s_setprio 0
	global_load_dwordx4 v[172:175], v[152:153], off offset:896
	global_load_dwordx4 v[220:223], v[156:157], off offset:896
	s_setprio 1
	s_waitcnt lgkmcnt(1)
	v_mfma_f32_32x32x16_bf16 v[112:127], v[158:161], v[224:227], v[112:127]
	v_mfma_f32_32x32x16_bf16 v[48:63], v[162:165], v[224:227], v[48:63]
	s_waitcnt lgkmcnt(0)
	v_mfma_f32_32x32x16_bf16 v[96:111], v[158:161], v[228:231], v[96:111]
	v_mfma_f32_32x32x16_bf16 v[32:47], v[162:165], v[228:231], v[32:47]
	ds_read_b128 v[224:227], v168 offset:9312
	ds_read_b128 v[228:231], v168 offset:13920
	s_waitcnt lgkmcnt(1)
	v_mfma_f32_32x32x16_bf16 v[80:95], v[158:161], v[224:227], v[80:95]
	v_mfma_f32_32x32x16_bf16 v[16:31], v[162:165], v[224:227], v[16:31]
	s_waitcnt lgkmcnt(0)
	v_mfma_f32_32x32x16_bf16 v[64:79], v[158:161], v[228:231], v[64:79]
	v_mfma_f32_32x32x16_bf16 v[0:15], v[162:165], v[228:231], v[0:15]
	s_setprio 0
	s_barrier
	global_load_dwordx4 v[158:161], v[128:129], off offset:1024
	global_load_dwordx4 v[162:165], v[132:133], off offset:1024
	s_waitcnt vmcnt(9)
	ds_write_b128 v195, v[198:201]
	s_waitcnt vmcnt(8)
	ds_write_b128 v196, v[202:205]
	ds_read_b128 v[198:201], v192 offset:36864
	ds_read_b128 v[202:205], v192 offset:41472
	ds_read_b128 v[224:227], v184
	ds_read_b128 v[228:231], v184 offset:4608
	s_setprio 1
	s_waitcnt lgkmcnt(1)
	v_mfma_f32_32x32x16_bf16 v[112:127], v[198:201], v[224:227], v[112:127]
	v_mfma_f32_32x32x16_bf16 v[48:63], v[202:205], v[224:227], v[48:63]
	s_waitcnt lgkmcnt(0)
	v_mfma_f32_32x32x16_bf16 v[96:111], v[198:201], v[228:231], v[96:111]
	v_mfma_f32_32x32x16_bf16 v[32:47], v[202:205], v[228:231], v[32:47]
	ds_read_b128 v[224:227], v184 offset:9216
	ds_read_b128 v[228:231], v184 offset:13824
	s_waitcnt vmcnt(7)
	ds_write_b128 v194, v[208:211]
	s_waitcnt vmcnt(6)
	ds_write_b128 v193, v[212:215]
	ds_read_b128 v[208:211], v192 offset:36896
	ds_read_b128 v[212:215], v192 offset:41504
	s_waitcnt lgkmcnt(5)
	v_mfma_f32_32x32x16_bf16 v[80:95], v[198:201], v[224:227], v[80:95]
	v_mfma_f32_32x32x16_bf16 v[16:31], v[202:205], v[224:227], v[16:31]
	ds_read_b128 v[224:227], v184 offset:32
	s_waitcnt lgkmcnt(5)
	v_mfma_f32_32x32x16_bf16 v[64:79], v[198:201], v[228:231], v[64:79]
	v_mfma_f32_32x32x16_bf16 v[0:15], v[202:205], v[228:231], v[0:15]
	ds_read_b128 v[228:231], v184 offset:4640
	s_setprio 0
	global_load_dwordx4 v[198:201], v[136:137], off offset:1024
	global_load_dwordx4 v[202:205], v[140:141], off offset:1024
	s_setprio 1
	s_waitcnt lgkmcnt(1)
	v_mfma_f32_32x32x16_bf16 v[112:127], v[208:211], v[224:227], v[112:127]
	v_mfma_f32_32x32x16_bf16 v[48:63], v[212:215], v[224:227], v[48:63]
	s_waitcnt lgkmcnt(0)
	v_mfma_f32_32x32x16_bf16 v[96:111], v[208:211], v[228:231], v[96:111]
	v_mfma_f32_32x32x16_bf16 v[32:47], v[212:215], v[228:231], v[32:47]
	ds_read_b128 v[224:227], v184 offset:9248
	ds_read_b128 v[228:231], v184 offset:13856
	s_waitcnt vmcnt(7)
	ds_write_b128 v177, v[178:181]
	s_waitcnt vmcnt(6)
	ds_write_b128 v176, v[216:219]
	ds_read_b128 v[178:181], v192 offset:36928
	ds_read_b128 v[216:219], v192 offset:41536
	s_waitcnt lgkmcnt(5)
	v_mfma_f32_32x32x16_bf16 v[80:95], v[208:211], v[224:227], v[80:95]
	v_mfma_f32_32x32x16_bf16 v[16:31], v[212:215], v[224:227], v[16:31]
	ds_read_b128 v[224:227], v184 offset:64
	s_waitcnt lgkmcnt(5)
	v_mfma_f32_32x32x16_bf16 v[64:79], v[208:211], v[228:231], v[64:79]
	v_mfma_f32_32x32x16_bf16 v[0:15], v[212:215], v[228:231], v[0:15]
	ds_read_b128 v[228:231], v184 offset:4672
	s_setprio 0
	global_load_dwordx4 v[208:211], v[144:145], off offset:1024
	global_load_dwordx4 v[212:215], v[148:149], off offset:1024
	s_setprio 1
	s_waitcnt lgkmcnt(1)
	v_mfma_f32_32x32x16_bf16 v[112:127], v[178:181], v[224:227], v[112:127]
	v_mfma_f32_32x32x16_bf16 v[48:63], v[216:219], v[224:227], v[48:63]
	s_waitcnt lgkmcnt(0)
	v_mfma_f32_32x32x16_bf16 v[96:111], v[178:181], v[228:231], v[96:111]
	v_mfma_f32_32x32x16_bf16 v[32:47], v[216:219], v[228:231], v[32:47]
	ds_read_b128 v[224:227], v184 offset:9280
	ds_read_b128 v[228:231], v184 offset:13888
	s_waitcnt vmcnt(7)
	ds_write_b128 v171, v[172:175]
	s_waitcnt vmcnt(6)
	ds_write_b128 v170, v[220:223]
	ds_read_b128 v[172:175], v192 offset:36960
	ds_read_b128 v[220:223], v192 offset:41568
	s_waitcnt lgkmcnt(5)
	v_mfma_f32_32x32x16_bf16 v[80:95], v[178:181], v[224:227], v[80:95]
	v_mfma_f32_32x32x16_bf16 v[16:31], v[216:219], v[224:227], v[16:31]
	ds_read_b128 v[224:227], v184 offset:96
	s_waitcnt lgkmcnt(5)
	v_mfma_f32_32x32x16_bf16 v[64:79], v[178:181], v[228:231], v[64:79]
	v_mfma_f32_32x32x16_bf16 v[0:15], v[216:219], v[228:231], v[0:15]
	ds_read_b128 v[228:231], v184 offset:4704
	s_setprio 0
	global_load_dwordx4 v[178:181], v[152:153], off offset:1024
	global_load_dwordx4 v[216:219], v[156:157], off offset:1024
	s_setprio 1
	s_waitcnt lgkmcnt(1)
	v_mfma_f32_32x32x16_bf16 v[112:127], v[172:175], v[224:227], v[112:127]
	v_mfma_f32_32x32x16_bf16 v[48:63], v[220:223], v[224:227], v[48:63]
	s_waitcnt lgkmcnt(0)
	v_mfma_f32_32x32x16_bf16 v[96:111], v[172:175], v[228:231], v[96:111]
	v_mfma_f32_32x32x16_bf16 v[32:47], v[220:223], v[228:231], v[32:47]
	ds_read_b128 v[224:227], v184 offset:9312
	ds_read_b128 v[228:231], v184 offset:13920
	s_waitcnt lgkmcnt(1)
	v_mfma_f32_32x32x16_bf16 v[80:95], v[172:175], v[224:227], v[80:95]
	v_mfma_f32_32x32x16_bf16 v[16:31], v[220:223], v[224:227], v[16:31]
	s_waitcnt lgkmcnt(0)
	v_mfma_f32_32x32x16_bf16 v[64:79], v[172:175], v[228:231], v[64:79]
	v_mfma_f32_32x32x16_bf16 v[0:15], v[220:223], v[228:231], v[0:15]
	s_setprio 0
	s_barrier
	global_load_dwordx4 v[172:175], v[128:129], off offset:1152
	global_load_dwordx4 v[220:223], v[132:133], off offset:1152
	s_waitcnt vmcnt(9)
	ds_write_b128 v191, v[158:161]
	s_waitcnt vmcnt(8)
	ds_write_b128 v191, v[162:165] offset:36864
	ds_read_b128 v[158:161], v169
	ds_read_b128 v[162:165], v169 offset:4608
	ds_read_b128 v[224:227], v168
	ds_read_b128 v[228:231], v168 offset:4608
	s_setprio 1
	s_waitcnt lgkmcnt(1)
	v_mfma_f32_32x32x16_bf16 v[112:127], v[158:161], v[224:227], v[112:127]
	v_mfma_f32_32x32x16_bf16 v[48:63], v[162:165], v[224:227], v[48:63]
	s_waitcnt lgkmcnt(0)
	v_mfma_f32_32x32x16_bf16 v[96:111], v[158:161], v[228:231], v[96:111]
	v_mfma_f32_32x32x16_bf16 v[32:47], v[162:165], v[228:231], v[32:47]
	ds_read_b128 v[224:227], v168 offset:9216
	ds_read_b128 v[228:231], v168 offset:13824
	s_waitcnt vmcnt(7)
	ds_write_b128 v191, v[198:201] offset:9216
	s_waitcnt vmcnt(6)
	ds_write_b128 v191, v[202:205] offset:46080
	ds_read_b128 v[198:201], v169 offset:32
	ds_read_b128 v[202:205], v169 offset:4640
	s_waitcnt lgkmcnt(5)
	v_mfma_f32_32x32x16_bf16 v[80:95], v[158:161], v[224:227], v[80:95]
	v_mfma_f32_32x32x16_bf16 v[16:31], v[162:165], v[224:227], v[16:31]
	ds_read_b128 v[224:227], v168 offset:32
	s_waitcnt lgkmcnt(5)
	v_mfma_f32_32x32x16_bf16 v[64:79], v[158:161], v[228:231], v[64:79]
	v_mfma_f32_32x32x16_bf16 v[0:15], v[162:165], v[228:231], v[0:15]
	ds_read_b128 v[228:231], v168 offset:4640
	s_setprio 0
	global_load_dwordx4 v[158:161], v[136:137], off offset:1152
	global_load_dwordx4 v[162:165], v[140:141], off offset:1152
	s_setprio 1
	s_waitcnt lgkmcnt(1)
	v_mfma_f32_32x32x16_bf16 v[112:127], v[198:201], v[224:227], v[112:127]
	v_mfma_f32_32x32x16_bf16 v[48:63], v[202:205], v[224:227], v[48:63]
	s_waitcnt lgkmcnt(0)
	v_mfma_f32_32x32x16_bf16 v[96:111], v[198:201], v[228:231], v[96:111]
	v_mfma_f32_32x32x16_bf16 v[32:47], v[202:205], v[228:231], v[32:47]
	ds_read_b128 v[224:227], v168 offset:9248
	ds_read_b128 v[228:231], v168 offset:13856
	s_waitcnt vmcnt(7)
	ds_write_b128 v191, v[208:211] offset:18432
	s_waitcnt vmcnt(6)
	ds_write_b128 v191, v[212:215] offset:55296
	ds_read_b128 v[208:211], v169 offset:64
	ds_read_b128 v[212:215], v169 offset:4672
	s_waitcnt lgkmcnt(5)
	v_mfma_f32_32x32x16_bf16 v[80:95], v[198:201], v[224:227], v[80:95]
	v_mfma_f32_32x32x16_bf16 v[16:31], v[202:205], v[224:227], v[16:31]
	ds_read_b128 v[224:227], v168 offset:64
	s_waitcnt lgkmcnt(5)
	v_mfma_f32_32x32x16_bf16 v[64:79], v[198:201], v[228:231], v[64:79]
	v_mfma_f32_32x32x16_bf16 v[0:15], v[202:205], v[228:231], v[0:15]
	ds_read_b128 v[228:231], v168 offset:4672
	s_setprio 0
	global_load_dwordx4 v[198:201], v[144:145], off offset:1152
	global_load_dwordx4 v[202:205], v[148:149], off offset:1152
	s_setprio 1
	s_waitcnt lgkmcnt(1)
	v_mfma_f32_32x32x16_bf16 v[112:127], v[208:211], v[224:227], v[112:127]
	v_mfma_f32_32x32x16_bf16 v[48:63], v[212:215], v[224:227], v[48:63]
	s_waitcnt lgkmcnt(0)
	v_mfma_f32_32x32x16_bf16 v[96:111], v[208:211], v[228:231], v[96:111]
	v_mfma_f32_32x32x16_bf16 v[32:47], v[212:215], v[228:231], v[32:47]
	ds_read_b128 v[224:227], v168 offset:9280
	ds_read_b128 v[228:231], v168 offset:13888
	s_waitcnt vmcnt(7)
	ds_write_b128 v191, v[178:181] offset:27648
	s_waitcnt vmcnt(6)
	ds_write_b128 v191, v[216:219] offset:64512
	ds_read_b128 v[178:181], v169 offset:96
	ds_read_b128 v[216:219], v169 offset:4704
	s_waitcnt lgkmcnt(5)
	v_mfma_f32_32x32x16_bf16 v[80:95], v[208:211], v[224:227], v[80:95]
	v_mfma_f32_32x32x16_bf16 v[16:31], v[212:215], v[224:227], v[16:31]
	ds_read_b128 v[224:227], v168 offset:96
	s_waitcnt lgkmcnt(5)
	v_mfma_f32_32x32x16_bf16 v[64:79], v[208:211], v[228:231], v[64:79]
	v_mfma_f32_32x32x16_bf16 v[0:15], v[212:215], v[228:231], v[0:15]
	ds_read_b128 v[228:231], v168 offset:4704
	s_setprio 0
	global_load_dwordx4 v[208:211], v[152:153], off offset:1152
	global_load_dwordx4 v[212:215], v[156:157], off offset:1152
	s_setprio 1
	s_waitcnt lgkmcnt(1)
	v_mfma_f32_32x32x16_bf16 v[112:127], v[178:181], v[224:227], v[112:127]
	v_mfma_f32_32x32x16_bf16 v[48:63], v[216:219], v[224:227], v[48:63]
	s_waitcnt lgkmcnt(0)
	v_mfma_f32_32x32x16_bf16 v[96:111], v[178:181], v[228:231], v[96:111]
	v_mfma_f32_32x32x16_bf16 v[32:47], v[216:219], v[228:231], v[32:47]
	ds_read_b128 v[224:227], v168 offset:9312
	ds_read_b128 v[228:231], v168 offset:13920
	s_waitcnt lgkmcnt(1)
	v_mfma_f32_32x32x16_bf16 v[80:95], v[178:181], v[224:227], v[80:95]
	v_mfma_f32_32x32x16_bf16 v[16:31], v[216:219], v[224:227], v[16:31]
	s_waitcnt lgkmcnt(0)
	v_mfma_f32_32x32x16_bf16 v[64:79], v[178:181], v[228:231], v[64:79]
	v_mfma_f32_32x32x16_bf16 v[0:15], v[216:219], v[228:231], v[0:15]
	s_setprio 0
	s_barrier
	global_load_dwordx4 v[178:181], v[128:129], off offset:1280
	global_load_dwordx4 v[216:219], v[132:133], off offset:1280
	s_waitcnt vmcnt(9)
	ds_write_b128 v195, v[172:175]
	s_waitcnt vmcnt(8)
	ds_write_b128 v196, v[220:223]
	ds_read_b128 v[172:175], v192 offset:36864
	ds_read_b128 v[220:223], v192 offset:41472
	ds_read_b128 v[224:227], v184
	ds_read_b128 v[228:231], v184 offset:4608
	s_setprio 1
	s_waitcnt lgkmcnt(1)
	v_mfma_f32_32x32x16_bf16 v[112:127], v[172:175], v[224:227], v[112:127]
	v_mfma_f32_32x32x16_bf16 v[48:63], v[220:223], v[224:227], v[48:63]
	s_waitcnt lgkmcnt(0)
	v_mfma_f32_32x32x16_bf16 v[96:111], v[172:175], v[228:231], v[96:111]
	v_mfma_f32_32x32x16_bf16 v[32:47], v[220:223], v[228:231], v[32:47]
	ds_read_b128 v[224:227], v184 offset:9216
	ds_read_b128 v[228:231], v184 offset:13824
	s_waitcnt vmcnt(7)
	ds_write_b128 v194, v[158:161]
	s_waitcnt vmcnt(6)
	ds_write_b128 v193, v[162:165]
	ds_read_b128 v[158:161], v192 offset:36896
	ds_read_b128 v[162:165], v192 offset:41504
	s_waitcnt lgkmcnt(5)
	v_mfma_f32_32x32x16_bf16 v[80:95], v[172:175], v[224:227], v[80:95]
	v_mfma_f32_32x32x16_bf16 v[16:31], v[220:223], v[224:227], v[16:31]
	ds_read_b128 v[224:227], v184 offset:32
	s_waitcnt lgkmcnt(5)
	v_mfma_f32_32x32x16_bf16 v[64:79], v[172:175], v[228:231], v[64:79]
	v_mfma_f32_32x32x16_bf16 v[0:15], v[220:223], v[228:231], v[0:15]
	ds_read_b128 v[228:231], v184 offset:4640
	s_setprio 0
	global_load_dwordx4 v[172:175], v[136:137], off offset:1280
	global_load_dwordx4 v[220:223], v[140:141], off offset:1280
	s_setprio 1
	s_waitcnt lgkmcnt(1)
	v_mfma_f32_32x32x16_bf16 v[112:127], v[158:161], v[224:227], v[112:127]
	v_mfma_f32_32x32x16_bf16 v[48:63], v[162:165], v[224:227], v[48:63]
	s_waitcnt lgkmcnt(0)
	v_mfma_f32_32x32x16_bf16 v[96:111], v[158:161], v[228:231], v[96:111]
	v_mfma_f32_32x32x16_bf16 v[32:47], v[162:165], v[228:231], v[32:47]
	ds_read_b128 v[224:227], v184 offset:9248
	ds_read_b128 v[228:231], v184 offset:13856
	s_waitcnt vmcnt(7)
	ds_write_b128 v177, v[198:201]
	s_waitcnt vmcnt(6)
	ds_write_b128 v176, v[202:205]
	ds_read_b128 v[198:201], v192 offset:36928
	ds_read_b128 v[202:205], v192 offset:41536
	s_waitcnt lgkmcnt(5)
	v_mfma_f32_32x32x16_bf16 v[80:95], v[158:161], v[224:227], v[80:95]
	v_mfma_f32_32x32x16_bf16 v[16:31], v[162:165], v[224:227], v[16:31]
	ds_read_b128 v[224:227], v184 offset:64
	s_waitcnt lgkmcnt(5)
	v_mfma_f32_32x32x16_bf16 v[64:79], v[158:161], v[228:231], v[64:79]
	v_mfma_f32_32x32x16_bf16 v[0:15], v[162:165], v[228:231], v[0:15]
	ds_read_b128 v[228:231], v184 offset:4672
	s_setprio 0
	global_load_dwordx4 v[158:161], v[144:145], off offset:1280
	global_load_dwordx4 v[162:165], v[148:149], off offset:1280
	s_setprio 1
	s_waitcnt lgkmcnt(1)
	v_mfma_f32_32x32x16_bf16 v[112:127], v[198:201], v[224:227], v[112:127]
	v_mfma_f32_32x32x16_bf16 v[48:63], v[202:205], v[224:227], v[48:63]
	s_waitcnt lgkmcnt(0)
	v_mfma_f32_32x32x16_bf16 v[96:111], v[198:201], v[228:231], v[96:111]
	v_mfma_f32_32x32x16_bf16 v[32:47], v[202:205], v[228:231], v[32:47]
	ds_read_b128 v[224:227], v184 offset:9280
	ds_read_b128 v[228:231], v184 offset:13888
	s_waitcnt vmcnt(7)
	ds_write_b128 v171, v[208:211]
	s_waitcnt vmcnt(6)
	ds_write_b128 v170, v[212:215]
	ds_read_b128 v[208:211], v192 offset:36960
	ds_read_b128 v[212:215], v192 offset:41568
	s_waitcnt lgkmcnt(5)
	v_mfma_f32_32x32x16_bf16 v[80:95], v[198:201], v[224:227], v[80:95]
	v_mfma_f32_32x32x16_bf16 v[16:31], v[202:205], v[224:227], v[16:31]
	ds_read_b128 v[224:227], v184 offset:96
	s_waitcnt lgkmcnt(5)
	v_mfma_f32_32x32x16_bf16 v[64:79], v[198:201], v[228:231], v[64:79]
	v_mfma_f32_32x32x16_bf16 v[0:15], v[202:205], v[228:231], v[0:15]
	ds_read_b128 v[228:231], v184 offset:4704
	s_setprio 0
	global_load_dwordx4 v[198:201], v[152:153], off offset:1280
	global_load_dwordx4 v[202:205], v[156:157], off offset:1280
	s_setprio 1
	s_waitcnt lgkmcnt(1)
	v_mfma_f32_32x32x16_bf16 v[112:127], v[208:211], v[224:227], v[112:127]
	v_mfma_f32_32x32x16_bf16 v[48:63], v[212:215], v[224:227], v[48:63]
	s_waitcnt lgkmcnt(0)
	v_mfma_f32_32x32x16_bf16 v[96:111], v[208:211], v[228:231], v[96:111]
	v_mfma_f32_32x32x16_bf16 v[32:47], v[212:215], v[228:231], v[32:47]
	ds_read_b128 v[224:227], v184 offset:9312
	ds_read_b128 v[228:231], v184 offset:13920
	s_waitcnt lgkmcnt(1)
	v_mfma_f32_32x32x16_bf16 v[80:95], v[208:211], v[224:227], v[80:95]
	v_mfma_f32_32x32x16_bf16 v[16:31], v[212:215], v[224:227], v[16:31]
	s_waitcnt lgkmcnt(0)
	v_mfma_f32_32x32x16_bf16 v[64:79], v[208:211], v[228:231], v[64:79]
	v_mfma_f32_32x32x16_bf16 v[0:15], v[212:215], v[228:231], v[0:15]
	s_setprio 0
	s_barrier
	global_load_dwordx4 v[208:211], v[128:129], off offset:1408
	global_load_dwordx4 v[212:215], v[132:133], off offset:1408
	s_waitcnt vmcnt(9)
	ds_write_b128 v191, v[178:181]
	s_waitcnt vmcnt(8)
	ds_write_b128 v191, v[216:219] offset:36864
	ds_read_b128 v[178:181], v169
	ds_read_b128 v[216:219], v169 offset:4608
	ds_read_b128 v[224:227], v168
	ds_read_b128 v[228:231], v168 offset:4608
	s_setprio 1
	s_waitcnt lgkmcnt(1)
	v_mfma_f32_32x32x16_bf16 v[112:127], v[178:181], v[224:227], v[112:127]
	v_mfma_f32_32x32x16_bf16 v[48:63], v[216:219], v[224:227], v[48:63]
	s_waitcnt lgkmcnt(0)
	v_mfma_f32_32x32x16_bf16 v[96:111], v[178:181], v[228:231], v[96:111]
	v_mfma_f32_32x32x16_bf16 v[32:47], v[216:219], v[228:231], v[32:47]
	ds_read_b128 v[224:227], v168 offset:9216
	ds_read_b128 v[228:231], v168 offset:13824
	s_waitcnt vmcnt(7)
	ds_write_b128 v191, v[172:175] offset:9216
	s_waitcnt vmcnt(6)
	ds_write_b128 v191, v[220:223] offset:46080
	ds_read_b128 v[172:175], v169 offset:32
	ds_read_b128 v[220:223], v169 offset:4640
	s_waitcnt lgkmcnt(5)
	v_mfma_f32_32x32x16_bf16 v[80:95], v[178:181], v[224:227], v[80:95]
	v_mfma_f32_32x32x16_bf16 v[16:31], v[216:219], v[224:227], v[16:31]
	ds_read_b128 v[224:227], v168 offset:32
	s_waitcnt lgkmcnt(5)
	v_mfma_f32_32x32x16_bf16 v[64:79], v[178:181], v[228:231], v[64:79]
	v_mfma_f32_32x32x16_bf16 v[0:15], v[216:219], v[228:231], v[0:15]
	ds_read_b128 v[228:231], v168 offset:4640
	s_setprio 0
	global_load_dwordx4 v[178:181], v[136:137], off offset:1408
	global_load_dwordx4 v[216:219], v[140:141], off offset:1408
	s_setprio 1
	s_waitcnt lgkmcnt(1)
	v_mfma_f32_32x32x16_bf16 v[112:127], v[172:175], v[224:227], v[112:127]
	v_mfma_f32_32x32x16_bf16 v[48:63], v[220:223], v[224:227], v[48:63]
	s_waitcnt lgkmcnt(0)
	v_mfma_f32_32x32x16_bf16 v[96:111], v[172:175], v[228:231], v[96:111]
	v_mfma_f32_32x32x16_bf16 v[32:47], v[220:223], v[228:231], v[32:47]
	ds_read_b128 v[224:227], v168 offset:9248
	ds_read_b128 v[228:231], v168 offset:13856
	s_waitcnt vmcnt(7)
	ds_write_b128 v191, v[158:161] offset:18432
	s_waitcnt vmcnt(6)
	ds_write_b128 v191, v[162:165] offset:55296
	ds_read_b128 v[158:161], v169 offset:64
	ds_read_b128 v[162:165], v169 offset:4672
	s_waitcnt lgkmcnt(5)
	v_mfma_f32_32x32x16_bf16 v[80:95], v[172:175], v[224:227], v[80:95]
	v_mfma_f32_32x32x16_bf16 v[16:31], v[220:223], v[224:227], v[16:31]
	ds_read_b128 v[224:227], v168 offset:64
	s_waitcnt lgkmcnt(5)
	v_mfma_f32_32x32x16_bf16 v[64:79], v[172:175], v[228:231], v[64:79]
	v_mfma_f32_32x32x16_bf16 v[0:15], v[220:223], v[228:231], v[0:15]
	ds_read_b128 v[228:231], v168 offset:4672
	s_setprio 0
	global_load_dwordx4 v[172:175], v[144:145], off offset:1408
	global_load_dwordx4 v[220:223], v[148:149], off offset:1408
	s_setprio 1
	s_waitcnt lgkmcnt(1)
	v_mfma_f32_32x32x16_bf16 v[112:127], v[158:161], v[224:227], v[112:127]
	v_mfma_f32_32x32x16_bf16 v[48:63], v[162:165], v[224:227], v[48:63]
	s_waitcnt lgkmcnt(0)
	v_mfma_f32_32x32x16_bf16 v[96:111], v[158:161], v[228:231], v[96:111]
	v_mfma_f32_32x32x16_bf16 v[32:47], v[162:165], v[228:231], v[32:47]
	ds_read_b128 v[224:227], v168 offset:9280
	ds_read_b128 v[228:231], v168 offset:13888
	s_waitcnt vmcnt(7)
	ds_write_b128 v191, v[198:201] offset:27648
	s_waitcnt vmcnt(6)
	ds_write_b128 v191, v[202:205] offset:64512
	ds_read_b128 v[198:201], v169 offset:96
	ds_read_b128 v[202:205], v169 offset:4704
	s_waitcnt lgkmcnt(5)
	v_mfma_f32_32x32x16_bf16 v[80:95], v[158:161], v[224:227], v[80:95]
	v_mfma_f32_32x32x16_bf16 v[16:31], v[162:165], v[224:227], v[16:31]
	ds_read_b128 v[224:227], v168 offset:96
	s_waitcnt lgkmcnt(5)
	v_mfma_f32_32x32x16_bf16 v[64:79], v[158:161], v[228:231], v[64:79]
	v_mfma_f32_32x32x16_bf16 v[0:15], v[162:165], v[228:231], v[0:15]
	ds_read_b128 v[228:231], v168 offset:4704
	s_setprio 0
	global_load_dwordx4 v[158:161], v[152:153], off offset:1408
	global_load_dwordx4 v[162:165], v[156:157], off offset:1408
	s_setprio 1
	s_waitcnt lgkmcnt(1)
	v_mfma_f32_32x32x16_bf16 v[112:127], v[198:201], v[224:227], v[112:127]
	v_mfma_f32_32x32x16_bf16 v[48:63], v[202:205], v[224:227], v[48:63]
	s_waitcnt lgkmcnt(0)
	v_mfma_f32_32x32x16_bf16 v[96:111], v[198:201], v[228:231], v[96:111]
	v_mfma_f32_32x32x16_bf16 v[32:47], v[202:205], v[228:231], v[32:47]
	ds_read_b128 v[224:227], v168 offset:9312
	ds_read_b128 v[228:231], v168 offset:13920
	s_waitcnt lgkmcnt(1)
	v_mfma_f32_32x32x16_bf16 v[80:95], v[198:201], v[224:227], v[80:95]
	v_mfma_f32_32x32x16_bf16 v[16:31], v[202:205], v[224:227], v[16:31]
	s_waitcnt lgkmcnt(0)
	v_mfma_f32_32x32x16_bf16 v[64:79], v[198:201], v[228:231], v[64:79]
	v_mfma_f32_32x32x16_bf16 v[0:15], v[202:205], v[228:231], v[0:15]
	s_setprio 0
	s_barrier
	global_load_dwordx4 v[198:201], v[128:129], off offset:1536
	global_load_dwordx4 v[202:205], v[132:133], off offset:1536
	s_waitcnt vmcnt(9)
	ds_write_b128 v195, v[208:211]
	s_waitcnt vmcnt(8)
	ds_write_b128 v196, v[212:215]
	ds_read_b128 v[208:211], v192 offset:36864
	ds_read_b128 v[212:215], v192 offset:41472
	ds_read_b128 v[224:227], v184
	ds_read_b128 v[228:231], v184 offset:4608
	s_setprio 1
	s_waitcnt lgkmcnt(1)
	v_mfma_f32_32x32x16_bf16 v[112:127], v[208:211], v[224:227], v[112:127]
	v_mfma_f32_32x32x16_bf16 v[48:63], v[212:215], v[224:227], v[48:63]
	s_waitcnt lgkmcnt(0)
	v_mfma_f32_32x32x16_bf16 v[96:111], v[208:211], v[228:231], v[96:111]
	v_mfma_f32_32x32x16_bf16 v[32:47], v[212:215], v[228:231], v[32:47]
	ds_read_b128 v[224:227], v184 offset:9216
	ds_read_b128 v[228:231], v184 offset:13824
	s_waitcnt vmcnt(7)
	ds_write_b128 v194, v[178:181]
	s_waitcnt vmcnt(6)
	ds_write_b128 v193, v[216:219]
	ds_read_b128 v[178:181], v192 offset:36896
	ds_read_b128 v[216:219], v192 offset:41504
	s_waitcnt lgkmcnt(5)
	v_mfma_f32_32x32x16_bf16 v[80:95], v[208:211], v[224:227], v[80:95]
	v_mfma_f32_32x32x16_bf16 v[16:31], v[212:215], v[224:227], v[16:31]
	ds_read_b128 v[224:227], v184 offset:32
	s_waitcnt lgkmcnt(5)
	v_mfma_f32_32x32x16_bf16 v[64:79], v[208:211], v[228:231], v[64:79]
	v_mfma_f32_32x32x16_bf16 v[0:15], v[212:215], v[228:231], v[0:15]
	ds_read_b128 v[228:231], v184 offset:4640
	s_setprio 0
	global_load_dwordx4 v[208:211], v[136:137], off offset:1536
	global_load_dwordx4 v[212:215], v[140:141], off offset:1536
	s_setprio 1
	s_waitcnt lgkmcnt(1)
	v_mfma_f32_32x32x16_bf16 v[112:127], v[178:181], v[224:227], v[112:127]
	v_mfma_f32_32x32x16_bf16 v[48:63], v[216:219], v[224:227], v[48:63]
	s_waitcnt lgkmcnt(0)
	v_mfma_f32_32x32x16_bf16 v[96:111], v[178:181], v[228:231], v[96:111]
	v_mfma_f32_32x32x16_bf16 v[32:47], v[216:219], v[228:231], v[32:47]
	ds_read_b128 v[224:227], v184 offset:9248
	ds_read_b128 v[228:231], v184 offset:13856
	s_waitcnt vmcnt(7)
	ds_write_b128 v177, v[172:175]
	s_waitcnt vmcnt(6)
	ds_write_b128 v176, v[220:223]
	ds_read_b128 v[172:175], v192 offset:36928
	ds_read_b128 v[220:223], v192 offset:41536
	s_waitcnt lgkmcnt(5)
	v_mfma_f32_32x32x16_bf16 v[80:95], v[178:181], v[224:227], v[80:95]
	v_mfma_f32_32x32x16_bf16 v[16:31], v[216:219], v[224:227], v[16:31]
	ds_read_b128 v[224:227], v184 offset:64
	s_waitcnt lgkmcnt(5)
	v_mfma_f32_32x32x16_bf16 v[64:79], v[178:181], v[228:231], v[64:79]
	v_mfma_f32_32x32x16_bf16 v[0:15], v[216:219], v[228:231], v[0:15]
	ds_read_b128 v[228:231], v184 offset:4672
	s_setprio 0
	global_load_dwordx4 v[178:181], v[144:145], off offset:1536
	global_load_dwordx4 v[216:219], v[148:149], off offset:1536
	s_setprio 1
	s_waitcnt lgkmcnt(1)
	v_mfma_f32_32x32x16_bf16 v[112:127], v[172:175], v[224:227], v[112:127]
	v_mfma_f32_32x32x16_bf16 v[48:63], v[220:223], v[224:227], v[48:63]
	s_waitcnt lgkmcnt(0)
	v_mfma_f32_32x32x16_bf16 v[96:111], v[172:175], v[228:231], v[96:111]
	v_mfma_f32_32x32x16_bf16 v[32:47], v[220:223], v[228:231], v[32:47]
	ds_read_b128 v[224:227], v184 offset:9280
	ds_read_b128 v[228:231], v184 offset:13888
	s_waitcnt vmcnt(7)
	ds_write_b128 v171, v[158:161]
	s_waitcnt vmcnt(6)
	ds_write_b128 v170, v[162:165]
	ds_read_b128 v[158:161], v192 offset:36960
	ds_read_b128 v[162:165], v192 offset:41568
	s_waitcnt lgkmcnt(5)
	v_mfma_f32_32x32x16_bf16 v[80:95], v[172:175], v[224:227], v[80:95]
	v_mfma_f32_32x32x16_bf16 v[16:31], v[220:223], v[224:227], v[16:31]
	ds_read_b128 v[224:227], v184 offset:96
	s_waitcnt lgkmcnt(5)
	v_mfma_f32_32x32x16_bf16 v[64:79], v[172:175], v[228:231], v[64:79]
	v_mfma_f32_32x32x16_bf16 v[0:15], v[220:223], v[228:231], v[0:15]
	ds_read_b128 v[228:231], v184 offset:4704
	s_setprio 0
	global_load_dwordx4 v[172:175], v[152:153], off offset:1536
	global_load_dwordx4 v[220:223], v[156:157], off offset:1536
	s_setprio 1
	s_waitcnt lgkmcnt(1)
	v_mfma_f32_32x32x16_bf16 v[112:127], v[158:161], v[224:227], v[112:127]
	v_mfma_f32_32x32x16_bf16 v[48:63], v[162:165], v[224:227], v[48:63]
	s_waitcnt lgkmcnt(0)
	v_mfma_f32_32x32x16_bf16 v[96:111], v[158:161], v[228:231], v[96:111]
	v_mfma_f32_32x32x16_bf16 v[32:47], v[162:165], v[228:231], v[32:47]
	ds_read_b128 v[224:227], v184 offset:9312
	ds_read_b128 v[228:231], v184 offset:13920
	s_waitcnt lgkmcnt(1)
	v_mfma_f32_32x32x16_bf16 v[80:95], v[158:161], v[224:227], v[80:95]
	v_mfma_f32_32x32x16_bf16 v[16:31], v[162:165], v[224:227], v[16:31]
	s_waitcnt lgkmcnt(0)
	v_mfma_f32_32x32x16_bf16 v[64:79], v[158:161], v[228:231], v[64:79]
	v_mfma_f32_32x32x16_bf16 v[0:15], v[162:165], v[228:231], v[0:15]
	s_setprio 0
	s_barrier
	global_load_dwordx4 v[158:161], v[128:129], off offset:1664
	global_load_dwordx4 v[162:165], v[132:133], off offset:1664
	s_waitcnt vmcnt(9)
	ds_write_b128 v191, v[198:201]
	s_waitcnt vmcnt(8)
	ds_write_b128 v191, v[202:205] offset:36864
	ds_read_b128 v[198:201], v169
	ds_read_b128 v[202:205], v169 offset:4608
	ds_read_b128 v[224:227], v168
	ds_read_b128 v[228:231], v168 offset:4608
	s_setprio 1
	s_waitcnt lgkmcnt(1)
	v_mfma_f32_32x32x16_bf16 v[112:127], v[198:201], v[224:227], v[112:127]
	v_mfma_f32_32x32x16_bf16 v[48:63], v[202:205], v[224:227], v[48:63]
	s_waitcnt lgkmcnt(0)
	v_mfma_f32_32x32x16_bf16 v[96:111], v[198:201], v[228:231], v[96:111]
	v_mfma_f32_32x32x16_bf16 v[32:47], v[202:205], v[228:231], v[32:47]
	ds_read_b128 v[224:227], v168 offset:9216
	ds_read_b128 v[228:231], v168 offset:13824
	s_waitcnt vmcnt(7)
	ds_write_b128 v191, v[208:211] offset:9216
	s_waitcnt vmcnt(6)
	ds_write_b128 v191, v[212:215] offset:46080
	ds_read_b128 v[208:211], v169 offset:32
	ds_read_b128 v[212:215], v169 offset:4640
	s_waitcnt lgkmcnt(5)
	v_mfma_f32_32x32x16_bf16 v[80:95], v[198:201], v[224:227], v[80:95]
	v_mfma_f32_32x32x16_bf16 v[16:31], v[202:205], v[224:227], v[16:31]
	ds_read_b128 v[224:227], v168 offset:32
	s_waitcnt lgkmcnt(5)
	v_mfma_f32_32x32x16_bf16 v[64:79], v[198:201], v[228:231], v[64:79]
	v_mfma_f32_32x32x16_bf16 v[0:15], v[202:205], v[228:231], v[0:15]
	ds_read_b128 v[228:231], v168 offset:4640
	s_setprio 0
	global_load_dwordx4 v[198:201], v[136:137], off offset:1664
	global_load_dwordx4 v[202:205], v[140:141], off offset:1664
	s_setprio 1
	s_waitcnt lgkmcnt(1)
	v_mfma_f32_32x32x16_bf16 v[112:127], v[208:211], v[224:227], v[112:127]
	v_mfma_f32_32x32x16_bf16 v[48:63], v[212:215], v[224:227], v[48:63]
	s_waitcnt lgkmcnt(0)
	v_mfma_f32_32x32x16_bf16 v[96:111], v[208:211], v[228:231], v[96:111]
	v_mfma_f32_32x32x16_bf16 v[32:47], v[212:215], v[228:231], v[32:47]
	ds_read_b128 v[224:227], v168 offset:9248
	ds_read_b128 v[228:231], v168 offset:13856
	s_waitcnt vmcnt(7)
	ds_write_b128 v191, v[178:181] offset:18432
	s_waitcnt vmcnt(6)
	ds_write_b128 v191, v[216:219] offset:55296
	ds_read_b128 v[178:181], v169 offset:64
	ds_read_b128 v[216:219], v169 offset:4672
	s_waitcnt lgkmcnt(5)
	v_mfma_f32_32x32x16_bf16 v[80:95], v[208:211], v[224:227], v[80:95]
	v_mfma_f32_32x32x16_bf16 v[16:31], v[212:215], v[224:227], v[16:31]
	ds_read_b128 v[224:227], v168 offset:64
	s_waitcnt lgkmcnt(5)
	v_mfma_f32_32x32x16_bf16 v[64:79], v[208:211], v[228:231], v[64:79]
	v_mfma_f32_32x32x16_bf16 v[0:15], v[212:215], v[228:231], v[0:15]
	ds_read_b128 v[228:231], v168 offset:4672
	s_setprio 0
	global_load_dwordx4 v[208:211], v[144:145], off offset:1664
	global_load_dwordx4 v[212:215], v[148:149], off offset:1664
	s_setprio 1
	s_waitcnt lgkmcnt(1)
	v_mfma_f32_32x32x16_bf16 v[112:127], v[178:181], v[224:227], v[112:127]
	v_mfma_f32_32x32x16_bf16 v[48:63], v[216:219], v[224:227], v[48:63]
	s_waitcnt lgkmcnt(0)
	v_mfma_f32_32x32x16_bf16 v[96:111], v[178:181], v[228:231], v[96:111]
	v_mfma_f32_32x32x16_bf16 v[32:47], v[216:219], v[228:231], v[32:47]
	ds_read_b128 v[224:227], v168 offset:9280
	ds_read_b128 v[228:231], v168 offset:13888
	s_waitcnt vmcnt(7)
	ds_write_b128 v191, v[172:175] offset:27648
	s_waitcnt vmcnt(6)
	ds_write_b128 v191, v[220:223] offset:64512
	ds_read_b128 v[172:175], v169 offset:96
	ds_read_b128 v[220:223], v169 offset:4704
	s_waitcnt lgkmcnt(5)
	v_mfma_f32_32x32x16_bf16 v[80:95], v[178:181], v[224:227], v[80:95]
	v_mfma_f32_32x32x16_bf16 v[16:31], v[216:219], v[224:227], v[16:31]
	ds_read_b128 v[224:227], v168 offset:96
	s_waitcnt lgkmcnt(5)
	v_mfma_f32_32x32x16_bf16 v[64:79], v[178:181], v[228:231], v[64:79]
	v_mfma_f32_32x32x16_bf16 v[0:15], v[216:219], v[228:231], v[0:15]
	ds_read_b128 v[228:231], v168 offset:4704
	s_setprio 0
	global_load_dwordx4 v[178:181], v[152:153], off offset:1664
	global_load_dwordx4 v[216:219], v[156:157], off offset:1664
	s_setprio 1
	s_waitcnt lgkmcnt(1)
	v_mfma_f32_32x32x16_bf16 v[112:127], v[172:175], v[224:227], v[112:127]
	v_mfma_f32_32x32x16_bf16 v[48:63], v[220:223], v[224:227], v[48:63]
	s_waitcnt lgkmcnt(0)
	v_mfma_f32_32x32x16_bf16 v[96:111], v[172:175], v[228:231], v[96:111]
	v_mfma_f32_32x32x16_bf16 v[32:47], v[220:223], v[228:231], v[32:47]
	ds_read_b128 v[224:227], v168 offset:9312
	ds_read_b128 v[228:231], v168 offset:13920
	s_waitcnt lgkmcnt(1)
	v_mfma_f32_32x32x16_bf16 v[80:95], v[172:175], v[224:227], v[80:95]
	v_mfma_f32_32x32x16_bf16 v[16:31], v[220:223], v[224:227], v[16:31]
	s_waitcnt lgkmcnt(0)
	v_mfma_f32_32x32x16_bf16 v[64:79], v[172:175], v[228:231], v[64:79]
	v_mfma_f32_32x32x16_bf16 v[0:15], v[220:223], v[228:231], v[0:15]
	s_setprio 0
	s_barrier
	global_load_dwordx4 v[172:175], v[128:129], off offset:1792
	global_load_dwordx4 v[220:223], v[132:133], off offset:1792
	s_waitcnt vmcnt(9)
	ds_write_b128 v195, v[158:161]
	s_waitcnt vmcnt(8)
	ds_write_b128 v196, v[162:165]
	ds_read_b128 v[158:161], v192 offset:36864
	ds_read_b128 v[162:165], v192 offset:41472
	ds_read_b128 v[224:227], v184
	ds_read_b128 v[228:231], v184 offset:4608
	s_setprio 1
	s_waitcnt lgkmcnt(1)
	v_mfma_f32_32x32x16_bf16 v[112:127], v[158:161], v[224:227], v[112:127]
	v_mfma_f32_32x32x16_bf16 v[48:63], v[162:165], v[224:227], v[48:63]
	s_waitcnt lgkmcnt(0)
	v_mfma_f32_32x32x16_bf16 v[96:111], v[158:161], v[228:231], v[96:111]
	v_mfma_f32_32x32x16_bf16 v[32:47], v[162:165], v[228:231], v[32:47]
	ds_read_b128 v[224:227], v184 offset:9216
	ds_read_b128 v[228:231], v184 offset:13824
	s_waitcnt vmcnt(7)
	ds_write_b128 v194, v[198:201]
	s_waitcnt vmcnt(6)
	ds_write_b128 v193, v[202:205]
	ds_read_b128 v[198:201], v192 offset:36896
	ds_read_b128 v[202:205], v192 offset:41504
	s_waitcnt lgkmcnt(5)
	v_mfma_f32_32x32x16_bf16 v[80:95], v[158:161], v[224:227], v[80:95]
	v_mfma_f32_32x32x16_bf16 v[16:31], v[162:165], v[224:227], v[16:31]
	ds_read_b128 v[224:227], v184 offset:32
	s_waitcnt lgkmcnt(5)
	v_mfma_f32_32x32x16_bf16 v[64:79], v[158:161], v[228:231], v[64:79]
	v_mfma_f32_32x32x16_bf16 v[0:15], v[162:165], v[228:231], v[0:15]
	ds_read_b128 v[228:231], v184 offset:4640
	s_setprio 0
	global_load_dwordx4 v[158:161], v[136:137], off offset:1792
	global_load_dwordx4 v[162:165], v[140:141], off offset:1792
	s_setprio 1
	s_waitcnt lgkmcnt(1)
	v_mfma_f32_32x32x16_bf16 v[112:127], v[198:201], v[224:227], v[112:127]
	v_mfma_f32_32x32x16_bf16 v[48:63], v[202:205], v[224:227], v[48:63]
	s_waitcnt lgkmcnt(0)
	v_mfma_f32_32x32x16_bf16 v[96:111], v[198:201], v[228:231], v[96:111]
	v_mfma_f32_32x32x16_bf16 v[32:47], v[202:205], v[228:231], v[32:47]
	ds_read_b128 v[224:227], v184 offset:9248
	ds_read_b128 v[228:231], v184 offset:13856
	s_waitcnt vmcnt(7)
	ds_write_b128 v177, v[208:211]
	s_waitcnt vmcnt(6)
	ds_write_b128 v176, v[212:215]
	ds_read_b128 v[208:211], v192 offset:36928
	ds_read_b128 v[212:215], v192 offset:41536
	s_waitcnt lgkmcnt(5)
	v_mfma_f32_32x32x16_bf16 v[80:95], v[198:201], v[224:227], v[80:95]
	v_mfma_f32_32x32x16_bf16 v[16:31], v[202:205], v[224:227], v[16:31]
	ds_read_b128 v[224:227], v184 offset:64
	s_waitcnt lgkmcnt(5)
	v_mfma_f32_32x32x16_bf16 v[64:79], v[198:201], v[228:231], v[64:79]
	v_mfma_f32_32x32x16_bf16 v[0:15], v[202:205], v[228:231], v[0:15]
	ds_read_b128 v[228:231], v184 offset:4672
	s_setprio 0
	global_load_dwordx4 v[198:201], v[144:145], off offset:1792
	global_load_dwordx4 v[202:205], v[148:149], off offset:1792
	s_setprio 1
	s_waitcnt lgkmcnt(1)
	v_mfma_f32_32x32x16_bf16 v[112:127], v[208:211], v[224:227], v[112:127]
	v_mfma_f32_32x32x16_bf16 v[48:63], v[212:215], v[224:227], v[48:63]
	s_waitcnt lgkmcnt(0)
	v_mfma_f32_32x32x16_bf16 v[96:111], v[208:211], v[228:231], v[96:111]
	v_mfma_f32_32x32x16_bf16 v[32:47], v[212:215], v[228:231], v[32:47]
	ds_read_b128 v[224:227], v184 offset:9280
	ds_read_b128 v[228:231], v184 offset:13888
	s_waitcnt vmcnt(7)
	ds_write_b128 v171, v[178:181]
	s_waitcnt vmcnt(6)
	ds_write_b128 v170, v[216:219]
	ds_read_b128 v[178:181], v192 offset:36960
	ds_read_b128 v[216:219], v192 offset:41568
	s_waitcnt lgkmcnt(5)
	v_mfma_f32_32x32x16_bf16 v[80:95], v[208:211], v[224:227], v[80:95]
	v_mfma_f32_32x32x16_bf16 v[16:31], v[212:215], v[224:227], v[16:31]
	ds_read_b128 v[224:227], v184 offset:96
	s_waitcnt lgkmcnt(5)
	v_mfma_f32_32x32x16_bf16 v[64:79], v[208:211], v[228:231], v[64:79]
	v_mfma_f32_32x32x16_bf16 v[0:15], v[212:215], v[228:231], v[0:15]
	ds_read_b128 v[228:231], v184 offset:4704
	s_setprio 0
	global_load_dwordx4 v[208:211], v[152:153], off offset:1792
	global_load_dwordx4 v[212:215], v[156:157], off offset:1792
	s_setprio 1
	s_waitcnt lgkmcnt(1)
	v_mfma_f32_32x32x16_bf16 v[112:127], v[178:181], v[224:227], v[112:127]
	v_mfma_f32_32x32x16_bf16 v[48:63], v[216:219], v[224:227], v[48:63]
	s_waitcnt lgkmcnt(0)
	v_mfma_f32_32x32x16_bf16 v[96:111], v[178:181], v[228:231], v[96:111]
	v_mfma_f32_32x32x16_bf16 v[32:47], v[216:219], v[228:231], v[32:47]
	ds_read_b128 v[224:227], v184 offset:9312
	ds_read_b128 v[228:231], v184 offset:13920
	s_waitcnt lgkmcnt(1)
	v_mfma_f32_32x32x16_bf16 v[80:95], v[178:181], v[224:227], v[80:95]
	v_mfma_f32_32x32x16_bf16 v[16:31], v[216:219], v[224:227], v[16:31]
	s_waitcnt lgkmcnt(0)
	v_mfma_f32_32x32x16_bf16 v[64:79], v[178:181], v[228:231], v[64:79]
	v_mfma_f32_32x32x16_bf16 v[0:15], v[216:219], v[228:231], v[0:15]
	s_setprio 0
	s_barrier
	global_load_dwordx4 v[178:181], v[128:129], off offset:1920
	global_load_dwordx4 v[216:219], v[132:133], off offset:1920
	s_waitcnt vmcnt(9)
	ds_write_b128 v191, v[172:175]
	s_waitcnt vmcnt(8)
	ds_write_b128 v191, v[220:223] offset:36864
	ds_read_b128 v[172:175], v169
	ds_read_b128 v[220:223], v169 offset:4608
	ds_read_b128 v[224:227], v168
	ds_read_b128 v[228:231], v168 offset:4608
	s_setprio 1
	s_waitcnt lgkmcnt(1)
	v_mfma_f32_32x32x16_bf16 v[112:127], v[172:175], v[224:227], v[112:127]
	v_mfma_f32_32x32x16_bf16 v[48:63], v[220:223], v[224:227], v[48:63]
	s_waitcnt lgkmcnt(0)
	v_mfma_f32_32x32x16_bf16 v[96:111], v[172:175], v[228:231], v[96:111]
	v_mfma_f32_32x32x16_bf16 v[32:47], v[220:223], v[228:231], v[32:47]
	ds_read_b128 v[224:227], v168 offset:9216
	ds_read_b128 v[228:231], v168 offset:13824
	s_waitcnt vmcnt(7)
	ds_write_b128 v191, v[158:161] offset:9216
	s_waitcnt vmcnt(6)
	ds_write_b128 v191, v[162:165] offset:46080
	ds_read_b128 v[158:161], v169 offset:32
	ds_read_b128 v[162:165], v169 offset:4640
	s_waitcnt lgkmcnt(5)
	v_mfma_f32_32x32x16_bf16 v[80:95], v[172:175], v[224:227], v[80:95]
	v_mfma_f32_32x32x16_bf16 v[16:31], v[220:223], v[224:227], v[16:31]
	ds_read_b128 v[224:227], v168 offset:32
	s_waitcnt lgkmcnt(5)
	v_mfma_f32_32x32x16_bf16 v[64:79], v[172:175], v[228:231], v[64:79]
	v_mfma_f32_32x32x16_bf16 v[0:15], v[220:223], v[228:231], v[0:15]
	ds_read_b128 v[228:231], v168 offset:4640
	s_setprio 0
	global_load_dwordx4 v[172:175], v[136:137], off offset:1920
	global_load_dwordx4 v[220:223], v[140:141], off offset:1920
	s_setprio 1
	s_waitcnt lgkmcnt(1)
	v_mfma_f32_32x32x16_bf16 v[112:127], v[158:161], v[224:227], v[112:127]
	v_mfma_f32_32x32x16_bf16 v[48:63], v[162:165], v[224:227], v[48:63]
	s_waitcnt lgkmcnt(0)
	v_mfma_f32_32x32x16_bf16 v[96:111], v[158:161], v[228:231], v[96:111]
	v_mfma_f32_32x32x16_bf16 v[32:47], v[162:165], v[228:231], v[32:47]
	ds_read_b128 v[224:227], v168 offset:9248
	ds_read_b128 v[228:231], v168 offset:13856
	s_waitcnt vmcnt(7)
	ds_write_b128 v191, v[198:201] offset:18432
	s_waitcnt vmcnt(6)
	ds_write_b128 v191, v[202:205] offset:55296
	ds_read_b128 v[198:201], v169 offset:64
	ds_read_b128 v[202:205], v169 offset:4672
	s_waitcnt lgkmcnt(5)
	v_mfma_f32_32x32x16_bf16 v[80:95], v[158:161], v[224:227], v[80:95]
	v_mfma_f32_32x32x16_bf16 v[16:31], v[162:165], v[224:227], v[16:31]
	ds_read_b128 v[224:227], v168 offset:64
	s_waitcnt lgkmcnt(5)
	v_mfma_f32_32x32x16_bf16 v[64:79], v[158:161], v[228:231], v[64:79]
	v_mfma_f32_32x32x16_bf16 v[0:15], v[162:165], v[228:231], v[0:15]
	ds_read_b128 v[228:231], v168 offset:4672
	s_setprio 0
	global_load_dwordx4 v[158:161], v[144:145], off offset:1920
	global_load_dwordx4 v[162:165], v[148:149], off offset:1920
	s_setprio 1
	s_waitcnt lgkmcnt(1)
	v_mfma_f32_32x32x16_bf16 v[112:127], v[198:201], v[224:227], v[112:127]
	v_mfma_f32_32x32x16_bf16 v[48:63], v[202:205], v[224:227], v[48:63]
	s_waitcnt lgkmcnt(0)
	v_mfma_f32_32x32x16_bf16 v[96:111], v[198:201], v[228:231], v[96:111]
	v_mfma_f32_32x32x16_bf16 v[32:47], v[202:205], v[228:231], v[32:47]
	ds_read_b128 v[224:227], v168 offset:9280
	ds_read_b128 v[228:231], v168 offset:13888
	s_waitcnt vmcnt(7)
	ds_write_b128 v191, v[208:211] offset:27648
	s_waitcnt vmcnt(6)
	ds_write_b128 v191, v[212:215] offset:64512
	ds_read_b128 v[208:211], v169 offset:96
	ds_read_b128 v[212:215], v169 offset:4704
	s_waitcnt lgkmcnt(5)
	v_mfma_f32_32x32x16_bf16 v[80:95], v[198:201], v[224:227], v[80:95]
	v_mfma_f32_32x32x16_bf16 v[16:31], v[202:205], v[224:227], v[16:31]
	ds_read_b128 v[224:227], v168 offset:96
	s_waitcnt lgkmcnt(5)
	v_mfma_f32_32x32x16_bf16 v[64:79], v[198:201], v[228:231], v[64:79]
	v_mfma_f32_32x32x16_bf16 v[0:15], v[202:205], v[228:231], v[0:15]
	ds_read_b128 v[228:231], v168 offset:4704
	s_setprio 0
	global_load_dwordx4 v[198:201], v[152:153], off offset:1920
	global_load_dwordx4 v[202:205], v[156:157], off offset:1920
	s_setprio 1
	s_waitcnt lgkmcnt(1)
	v_mfma_f32_32x32x16_bf16 v[112:127], v[208:211], v[224:227], v[112:127]
	v_mfma_f32_32x32x16_bf16 v[48:63], v[212:215], v[224:227], v[48:63]
	s_waitcnt lgkmcnt(0)
	v_mfma_f32_32x32x16_bf16 v[96:111], v[208:211], v[228:231], v[96:111]
	v_mfma_f32_32x32x16_bf16 v[32:47], v[212:215], v[228:231], v[32:47]
	ds_read_b128 v[224:227], v168 offset:9312
	ds_read_b128 v[228:231], v168 offset:13920
	s_waitcnt lgkmcnt(1)
	v_mfma_f32_32x32x16_bf16 v[80:95], v[208:211], v[224:227], v[80:95]
	v_mfma_f32_32x32x16_bf16 v[16:31], v[212:215], v[224:227], v[16:31]
	s_waitcnt lgkmcnt(0)
	v_mfma_f32_32x32x16_bf16 v[64:79], v[208:211], v[228:231], v[64:79]
	v_mfma_f32_32x32x16_bf16 v[0:15], v[212:215], v[228:231], v[0:15]
	s_setprio 0
	s_barrier
	global_load_dwordx4 v[208:211], v[128:129], off offset:2048
	global_load_dwordx4 v[212:215], v[132:133], off offset:2048
	s_waitcnt vmcnt(9)
	ds_write_b128 v195, v[178:181]
	s_waitcnt vmcnt(8)
	ds_write_b128 v196, v[216:219]
	ds_read_b128 v[178:181], v192 offset:36864
	ds_read_b128 v[216:219], v192 offset:41472
	ds_read_b128 v[224:227], v184
	ds_read_b128 v[228:231], v184 offset:4608
	s_setprio 1
	s_waitcnt lgkmcnt(1)
	v_mfma_f32_32x32x16_bf16 v[112:127], v[178:181], v[224:227], v[112:127]
	v_mfma_f32_32x32x16_bf16 v[48:63], v[216:219], v[224:227], v[48:63]
	s_waitcnt lgkmcnt(0)
	v_mfma_f32_32x32x16_bf16 v[96:111], v[178:181], v[228:231], v[96:111]
	v_mfma_f32_32x32x16_bf16 v[32:47], v[216:219], v[228:231], v[32:47]
	ds_read_b128 v[224:227], v184 offset:9216
	ds_read_b128 v[228:231], v184 offset:13824
	s_waitcnt vmcnt(7)
	ds_write_b128 v194, v[172:175]
	s_waitcnt vmcnt(6)
	ds_write_b128 v193, v[220:223]
	ds_read_b128 v[172:175], v192 offset:36896
	ds_read_b128 v[220:223], v192 offset:41504
	s_waitcnt lgkmcnt(5)
	v_mfma_f32_32x32x16_bf16 v[80:95], v[178:181], v[224:227], v[80:95]
	v_mfma_f32_32x32x16_bf16 v[16:31], v[216:219], v[224:227], v[16:31]
	ds_read_b128 v[224:227], v184 offset:32
	s_waitcnt lgkmcnt(5)
	v_mfma_f32_32x32x16_bf16 v[64:79], v[178:181], v[228:231], v[64:79]
	v_mfma_f32_32x32x16_bf16 v[0:15], v[216:219], v[228:231], v[0:15]
	ds_read_b128 v[228:231], v184 offset:4640
	s_setprio 0
	global_load_dwordx4 v[178:181], v[136:137], off offset:2048
	global_load_dwordx4 v[216:219], v[140:141], off offset:2048
	s_setprio 1
	s_waitcnt lgkmcnt(1)
	v_mfma_f32_32x32x16_bf16 v[112:127], v[172:175], v[224:227], v[112:127]
	v_mfma_f32_32x32x16_bf16 v[48:63], v[220:223], v[224:227], v[48:63]
	s_waitcnt lgkmcnt(0)
	v_mfma_f32_32x32x16_bf16 v[96:111], v[172:175], v[228:231], v[96:111]
	v_mfma_f32_32x32x16_bf16 v[32:47], v[220:223], v[228:231], v[32:47]
	ds_read_b128 v[224:227], v184 offset:9248
	ds_read_b128 v[228:231], v184 offset:13856
	s_waitcnt vmcnt(7)
	ds_write_b128 v177, v[158:161]
	s_waitcnt vmcnt(6)
	ds_write_b128 v176, v[162:165]
	ds_read_b128 v[158:161], v192 offset:36928
	ds_read_b128 v[162:165], v192 offset:41536
	s_waitcnt lgkmcnt(5)
	v_mfma_f32_32x32x16_bf16 v[80:95], v[172:175], v[224:227], v[80:95]
	v_mfma_f32_32x32x16_bf16 v[16:31], v[220:223], v[224:227], v[16:31]
	ds_read_b128 v[224:227], v184 offset:64
	s_waitcnt lgkmcnt(5)
	v_mfma_f32_32x32x16_bf16 v[64:79], v[172:175], v[228:231], v[64:79]
	v_mfma_f32_32x32x16_bf16 v[0:15], v[220:223], v[228:231], v[0:15]
	ds_read_b128 v[228:231], v184 offset:4672
	s_setprio 0
	global_load_dwordx4 v[172:175], v[144:145], off offset:2048
	global_load_dwordx4 v[220:223], v[148:149], off offset:2048
	s_setprio 1
	s_waitcnt lgkmcnt(1)
	v_mfma_f32_32x32x16_bf16 v[112:127], v[158:161], v[224:227], v[112:127]
	v_mfma_f32_32x32x16_bf16 v[48:63], v[162:165], v[224:227], v[48:63]
	s_waitcnt lgkmcnt(0)
	v_mfma_f32_32x32x16_bf16 v[96:111], v[158:161], v[228:231], v[96:111]
	v_mfma_f32_32x32x16_bf16 v[32:47], v[162:165], v[228:231], v[32:47]
	ds_read_b128 v[224:227], v184 offset:9280
	ds_read_b128 v[228:231], v184 offset:13888
	s_waitcnt vmcnt(7)
	ds_write_b128 v171, v[198:201]
	s_waitcnt vmcnt(6)
	ds_write_b128 v170, v[202:205]
	ds_read_b128 v[198:201], v192 offset:36960
	ds_read_b128 v[202:205], v192 offset:41568
	s_waitcnt lgkmcnt(5)
	v_mfma_f32_32x32x16_bf16 v[80:95], v[158:161], v[224:227], v[80:95]
	v_mfma_f32_32x32x16_bf16 v[16:31], v[162:165], v[224:227], v[16:31]
	ds_read_b128 v[224:227], v184 offset:96
	s_waitcnt lgkmcnt(5)
	v_mfma_f32_32x32x16_bf16 v[64:79], v[158:161], v[228:231], v[64:79]
	v_mfma_f32_32x32x16_bf16 v[0:15], v[162:165], v[228:231], v[0:15]
	ds_read_b128 v[228:231], v184 offset:4704
	s_setprio 0
	global_load_dwordx4 v[158:161], v[152:153], off offset:2048
	global_load_dwordx4 v[162:165], v[156:157], off offset:2048
	s_setprio 1
	s_waitcnt lgkmcnt(1)
	v_mfma_f32_32x32x16_bf16 v[112:127], v[198:201], v[224:227], v[112:127]
	v_mfma_f32_32x32x16_bf16 v[48:63], v[202:205], v[224:227], v[48:63]
	s_waitcnt lgkmcnt(0)
	v_mfma_f32_32x32x16_bf16 v[96:111], v[198:201], v[228:231], v[96:111]
	v_mfma_f32_32x32x16_bf16 v[32:47], v[202:205], v[228:231], v[32:47]
	ds_read_b128 v[224:227], v184 offset:9312
	ds_read_b128 v[228:231], v184 offset:13920
	s_waitcnt lgkmcnt(1)
	v_mfma_f32_32x32x16_bf16 v[80:95], v[198:201], v[224:227], v[80:95]
	v_mfma_f32_32x32x16_bf16 v[16:31], v[202:205], v[224:227], v[16:31]
	s_waitcnt lgkmcnt(0)
	v_mfma_f32_32x32x16_bf16 v[64:79], v[198:201], v[228:231], v[64:79]
	v_mfma_f32_32x32x16_bf16 v[0:15], v[202:205], v[228:231], v[0:15]
	s_setprio 0
	s_barrier
	global_load_dwordx4 v[198:201], v[128:129], off offset:2176
	global_load_dwordx4 v[202:205], v[132:133], off offset:2176
	s_waitcnt vmcnt(9)
	ds_write_b128 v191, v[208:211]
	s_waitcnt vmcnt(8)
	ds_write_b128 v191, v[212:215] offset:36864
	ds_read_b128 v[208:211], v169
	ds_read_b128 v[212:215], v169 offset:4608
	ds_read_b128 v[224:227], v168
	ds_read_b128 v[228:231], v168 offset:4608
	s_setprio 1
	s_waitcnt lgkmcnt(1)
	v_mfma_f32_32x32x16_bf16 v[112:127], v[208:211], v[224:227], v[112:127]
	v_mfma_f32_32x32x16_bf16 v[48:63], v[212:215], v[224:227], v[48:63]
	s_waitcnt lgkmcnt(0)
	v_mfma_f32_32x32x16_bf16 v[96:111], v[208:211], v[228:231], v[96:111]
	v_mfma_f32_32x32x16_bf16 v[32:47], v[212:215], v[228:231], v[32:47]
	ds_read_b128 v[224:227], v168 offset:9216
	ds_read_b128 v[228:231], v168 offset:13824
	s_waitcnt vmcnt(7)
	ds_write_b128 v191, v[178:181] offset:9216
	s_waitcnt vmcnt(6)
	ds_write_b128 v191, v[216:219] offset:46080
	ds_read_b128 v[178:181], v169 offset:32
	ds_read_b128 v[216:219], v169 offset:4640
	s_waitcnt lgkmcnt(5)
	v_mfma_f32_32x32x16_bf16 v[80:95], v[208:211], v[224:227], v[80:95]
	v_mfma_f32_32x32x16_bf16 v[16:31], v[212:215], v[224:227], v[16:31]
	ds_read_b128 v[224:227], v168 offset:32
	s_waitcnt lgkmcnt(5)
	v_mfma_f32_32x32x16_bf16 v[64:79], v[208:211], v[228:231], v[64:79]
	v_mfma_f32_32x32x16_bf16 v[0:15], v[212:215], v[228:231], v[0:15]
	ds_read_b128 v[228:231], v168 offset:4640
	s_setprio 0
	global_load_dwordx4 v[208:211], v[136:137], off offset:2176
	global_load_dwordx4 v[212:215], v[140:141], off offset:2176
	s_setprio 1
	s_waitcnt lgkmcnt(1)
	v_mfma_f32_32x32x16_bf16 v[112:127], v[178:181], v[224:227], v[112:127]
	v_mfma_f32_32x32x16_bf16 v[48:63], v[216:219], v[224:227], v[48:63]
	s_waitcnt lgkmcnt(0)
	v_mfma_f32_32x32x16_bf16 v[96:111], v[178:181], v[228:231], v[96:111]
	v_mfma_f32_32x32x16_bf16 v[32:47], v[216:219], v[228:231], v[32:47]
	ds_read_b128 v[224:227], v168 offset:9248
	ds_read_b128 v[228:231], v168 offset:13856
	s_waitcnt vmcnt(7)
	ds_write_b128 v191, v[172:175] offset:18432
	s_waitcnt vmcnt(6)
	ds_write_b128 v191, v[220:223] offset:55296
	ds_read_b128 v[172:175], v169 offset:64
	ds_read_b128 v[220:223], v169 offset:4672
	s_waitcnt lgkmcnt(5)
	v_mfma_f32_32x32x16_bf16 v[80:95], v[178:181], v[224:227], v[80:95]
	v_mfma_f32_32x32x16_bf16 v[16:31], v[216:219], v[224:227], v[16:31]
	ds_read_b128 v[224:227], v168 offset:64
	s_waitcnt lgkmcnt(5)
	v_mfma_f32_32x32x16_bf16 v[64:79], v[178:181], v[228:231], v[64:79]
	v_mfma_f32_32x32x16_bf16 v[0:15], v[216:219], v[228:231], v[0:15]
	ds_read_b128 v[228:231], v168 offset:4672
	s_setprio 0
	global_load_dwordx4 v[178:181], v[144:145], off offset:2176
	global_load_dwordx4 v[216:219], v[148:149], off offset:2176
	s_setprio 1
	s_waitcnt lgkmcnt(1)
	v_mfma_f32_32x32x16_bf16 v[112:127], v[172:175], v[224:227], v[112:127]
	v_mfma_f32_32x32x16_bf16 v[48:63], v[220:223], v[224:227], v[48:63]
	s_waitcnt lgkmcnt(0)
	v_mfma_f32_32x32x16_bf16 v[96:111], v[172:175], v[228:231], v[96:111]
	v_mfma_f32_32x32x16_bf16 v[32:47], v[220:223], v[228:231], v[32:47]
	ds_read_b128 v[224:227], v168 offset:9280
	ds_read_b128 v[228:231], v168 offset:13888
	s_waitcnt vmcnt(7)
	ds_write_b128 v191, v[158:161] offset:27648
	s_waitcnt vmcnt(6)
	ds_write_b128 v191, v[162:165] offset:64512
	ds_read_b128 v[158:161], v169 offset:96
	ds_read_b128 v[162:165], v169 offset:4704
	s_waitcnt lgkmcnt(5)
	v_mfma_f32_32x32x16_bf16 v[80:95], v[172:175], v[224:227], v[80:95]
	v_mfma_f32_32x32x16_bf16 v[16:31], v[220:223], v[224:227], v[16:31]
	ds_read_b128 v[224:227], v168 offset:96
	s_waitcnt lgkmcnt(5)
	v_mfma_f32_32x32x16_bf16 v[64:79], v[172:175], v[228:231], v[64:79]
	v_mfma_f32_32x32x16_bf16 v[0:15], v[220:223], v[228:231], v[0:15]
	ds_read_b128 v[228:231], v168 offset:4704
	s_setprio 0
	global_load_dwordx4 v[172:175], v[152:153], off offset:2176
	global_load_dwordx4 v[220:223], v[156:157], off offset:2176
	s_setprio 1
	s_waitcnt lgkmcnt(1)
	v_mfma_f32_32x32x16_bf16 v[112:127], v[158:161], v[224:227], v[112:127]
	v_mfma_f32_32x32x16_bf16 v[48:63], v[162:165], v[224:227], v[48:63]
	s_waitcnt lgkmcnt(0)
	v_mfma_f32_32x32x16_bf16 v[96:111], v[158:161], v[228:231], v[96:111]
	v_mfma_f32_32x32x16_bf16 v[32:47], v[162:165], v[228:231], v[32:47]
	ds_read_b128 v[224:227], v168 offset:9312
	ds_read_b128 v[228:231], v168 offset:13920
	s_waitcnt lgkmcnt(1)
	v_mfma_f32_32x32x16_bf16 v[80:95], v[158:161], v[224:227], v[80:95]
	v_mfma_f32_32x32x16_bf16 v[16:31], v[162:165], v[224:227], v[16:31]
	s_waitcnt lgkmcnt(0)
	v_mfma_f32_32x32x16_bf16 v[64:79], v[158:161], v[228:231], v[64:79]
	v_mfma_f32_32x32x16_bf16 v[0:15], v[162:165], v[228:231], v[0:15]
	s_setprio 0
	s_barrier
	global_load_dwordx4 v[158:161], v[128:129], off offset:2304
	global_load_dwordx4 v[162:165], v[132:133], off offset:2304
	s_waitcnt vmcnt(9)
	ds_write_b128 v195, v[198:201]
	s_waitcnt vmcnt(8)
	ds_write_b128 v196, v[202:205]
	ds_read_b128 v[198:201], v192 offset:36864
	ds_read_b128 v[202:205], v192 offset:41472
	ds_read_b128 v[224:227], v184
	ds_read_b128 v[228:231], v184 offset:4608
	s_setprio 1
	s_waitcnt lgkmcnt(1)
	v_mfma_f32_32x32x16_bf16 v[112:127], v[198:201], v[224:227], v[112:127]
	v_mfma_f32_32x32x16_bf16 v[48:63], v[202:205], v[224:227], v[48:63]
	s_waitcnt lgkmcnt(0)
	v_mfma_f32_32x32x16_bf16 v[96:111], v[198:201], v[228:231], v[96:111]
	v_mfma_f32_32x32x16_bf16 v[32:47], v[202:205], v[228:231], v[32:47]
	ds_read_b128 v[224:227], v184 offset:9216
	ds_read_b128 v[228:231], v184 offset:13824
	s_waitcnt vmcnt(7)
	ds_write_b128 v194, v[208:211]
	s_waitcnt vmcnt(6)
	ds_write_b128 v193, v[212:215]
	ds_read_b128 v[208:211], v192 offset:36896
	ds_read_b128 v[212:215], v192 offset:41504
	s_waitcnt lgkmcnt(5)
	v_mfma_f32_32x32x16_bf16 v[80:95], v[198:201], v[224:227], v[80:95]
	v_mfma_f32_32x32x16_bf16 v[16:31], v[202:205], v[224:227], v[16:31]
	ds_read_b128 v[224:227], v184 offset:32
	s_waitcnt lgkmcnt(5)
	v_mfma_f32_32x32x16_bf16 v[64:79], v[198:201], v[228:231], v[64:79]
	v_mfma_f32_32x32x16_bf16 v[0:15], v[202:205], v[228:231], v[0:15]
	ds_read_b128 v[228:231], v184 offset:4640
	s_setprio 0
	global_load_dwordx4 v[198:201], v[136:137], off offset:2304
	global_load_dwordx4 v[202:205], v[140:141], off offset:2304
	s_setprio 1
	s_waitcnt lgkmcnt(1)
	v_mfma_f32_32x32x16_bf16 v[112:127], v[208:211], v[224:227], v[112:127]
	v_mfma_f32_32x32x16_bf16 v[48:63], v[212:215], v[224:227], v[48:63]
	s_waitcnt lgkmcnt(0)
	v_mfma_f32_32x32x16_bf16 v[96:111], v[208:211], v[228:231], v[96:111]
	v_mfma_f32_32x32x16_bf16 v[32:47], v[212:215], v[228:231], v[32:47]
	ds_read_b128 v[224:227], v184 offset:9248
	ds_read_b128 v[228:231], v184 offset:13856
	s_waitcnt vmcnt(7)
	ds_write_b128 v177, v[178:181]
	s_waitcnt vmcnt(6)
	ds_write_b128 v176, v[216:219]
	ds_read_b128 v[178:181], v192 offset:36928
	ds_read_b128 v[216:219], v192 offset:41536
	s_waitcnt lgkmcnt(5)
	v_mfma_f32_32x32x16_bf16 v[80:95], v[208:211], v[224:227], v[80:95]
	v_mfma_f32_32x32x16_bf16 v[16:31], v[212:215], v[224:227], v[16:31]
	ds_read_b128 v[224:227], v184 offset:64
	s_waitcnt lgkmcnt(5)
	v_mfma_f32_32x32x16_bf16 v[64:79], v[208:211], v[228:231], v[64:79]
	v_mfma_f32_32x32x16_bf16 v[0:15], v[212:215], v[228:231], v[0:15]
	ds_read_b128 v[228:231], v184 offset:4672
	s_setprio 0
	global_load_dwordx4 v[208:211], v[144:145], off offset:2304
	global_load_dwordx4 v[212:215], v[148:149], off offset:2304
	s_setprio 1
	s_waitcnt lgkmcnt(1)
	v_mfma_f32_32x32x16_bf16 v[112:127], v[178:181], v[224:227], v[112:127]
	v_mfma_f32_32x32x16_bf16 v[48:63], v[216:219], v[224:227], v[48:63]
	s_waitcnt lgkmcnt(0)
	v_mfma_f32_32x32x16_bf16 v[96:111], v[178:181], v[228:231], v[96:111]
	v_mfma_f32_32x32x16_bf16 v[32:47], v[216:219], v[228:231], v[32:47]
	ds_read_b128 v[224:227], v184 offset:9280
	ds_read_b128 v[228:231], v184 offset:13888
	s_waitcnt vmcnt(7)
	ds_write_b128 v171, v[172:175]
	s_waitcnt vmcnt(6)
	ds_write_b128 v170, v[220:223]
	ds_read_b128 v[172:175], v192 offset:36960
	ds_read_b128 v[220:223], v192 offset:41568
	s_waitcnt lgkmcnt(5)
	v_mfma_f32_32x32x16_bf16 v[80:95], v[178:181], v[224:227], v[80:95]
	v_mfma_f32_32x32x16_bf16 v[16:31], v[216:219], v[224:227], v[16:31]
	ds_read_b128 v[224:227], v184 offset:96
	s_waitcnt lgkmcnt(5)
	v_mfma_f32_32x32x16_bf16 v[64:79], v[178:181], v[228:231], v[64:79]
	v_mfma_f32_32x32x16_bf16 v[0:15], v[216:219], v[228:231], v[0:15]
	ds_read_b128 v[228:231], v184 offset:4704
	s_setprio 0
	global_load_dwordx4 v[178:181], v[152:153], off offset:2304
	global_load_dwordx4 v[216:219], v[156:157], off offset:2304
	s_setprio 1
	s_waitcnt lgkmcnt(1)
	v_mfma_f32_32x32x16_bf16 v[112:127], v[172:175], v[224:227], v[112:127]
	v_mfma_f32_32x32x16_bf16 v[48:63], v[220:223], v[224:227], v[48:63]
	s_waitcnt lgkmcnt(0)
	v_mfma_f32_32x32x16_bf16 v[96:111], v[172:175], v[228:231], v[96:111]
	v_mfma_f32_32x32x16_bf16 v[32:47], v[220:223], v[228:231], v[32:47]
	ds_read_b128 v[224:227], v184 offset:9312
	ds_read_b128 v[228:231], v184 offset:13920
	s_waitcnt lgkmcnt(1)
	v_mfma_f32_32x32x16_bf16 v[80:95], v[172:175], v[224:227], v[80:95]
	v_mfma_f32_32x32x16_bf16 v[16:31], v[220:223], v[224:227], v[16:31]
	s_waitcnt lgkmcnt(0)
	v_mfma_f32_32x32x16_bf16 v[64:79], v[172:175], v[228:231], v[64:79]
	v_mfma_f32_32x32x16_bf16 v[0:15], v[220:223], v[228:231], v[0:15]
	s_setprio 0
	s_barrier
	global_load_dwordx4 v[172:175], v[128:129], off offset:2432
	global_load_dwordx4 v[220:223], v[132:133], off offset:2432
	s_waitcnt vmcnt(9)
	ds_write_b128 v191, v[158:161]
	s_waitcnt vmcnt(8)
	ds_write_b128 v191, v[162:165] offset:36864
	ds_read_b128 v[158:161], v169
	ds_read_b128 v[162:165], v169 offset:4608
	ds_read_b128 v[224:227], v168
	ds_read_b128 v[228:231], v168 offset:4608
	s_setprio 1
	s_waitcnt lgkmcnt(1)
	v_mfma_f32_32x32x16_bf16 v[112:127], v[158:161], v[224:227], v[112:127]
	v_mfma_f32_32x32x16_bf16 v[48:63], v[162:165], v[224:227], v[48:63]
	s_waitcnt lgkmcnt(0)
	v_mfma_f32_32x32x16_bf16 v[96:111], v[158:161], v[228:231], v[96:111]
	v_mfma_f32_32x32x16_bf16 v[32:47], v[162:165], v[228:231], v[32:47]
	ds_read_b128 v[224:227], v168 offset:9216
	ds_read_b128 v[228:231], v168 offset:13824
	s_waitcnt vmcnt(7)
	ds_write_b128 v191, v[198:201] offset:9216
	s_waitcnt vmcnt(6)
	ds_write_b128 v191, v[202:205] offset:46080
	ds_read_b128 v[198:201], v169 offset:32
	ds_read_b128 v[202:205], v169 offset:4640
	s_waitcnt lgkmcnt(5)
	v_mfma_f32_32x32x16_bf16 v[80:95], v[158:161], v[224:227], v[80:95]
	v_mfma_f32_32x32x16_bf16 v[16:31], v[162:165], v[224:227], v[16:31]
	ds_read_b128 v[224:227], v168 offset:32
	s_waitcnt lgkmcnt(5)
	v_mfma_f32_32x32x16_bf16 v[64:79], v[158:161], v[228:231], v[64:79]
	v_mfma_f32_32x32x16_bf16 v[0:15], v[162:165], v[228:231], v[0:15]
	ds_read_b128 v[228:231], v168 offset:4640
	s_setprio 0
	global_load_dwordx4 v[158:161], v[136:137], off offset:2432
	global_load_dwordx4 v[162:165], v[140:141], off offset:2432
	s_setprio 1
	s_waitcnt lgkmcnt(1)
	v_mfma_f32_32x32x16_bf16 v[112:127], v[198:201], v[224:227], v[112:127]
	v_mfma_f32_32x32x16_bf16 v[48:63], v[202:205], v[224:227], v[48:63]
	s_waitcnt lgkmcnt(0)
	v_mfma_f32_32x32x16_bf16 v[96:111], v[198:201], v[228:231], v[96:111]
	v_mfma_f32_32x32x16_bf16 v[32:47], v[202:205], v[228:231], v[32:47]
	ds_read_b128 v[224:227], v168 offset:9248
	ds_read_b128 v[228:231], v168 offset:13856
	s_waitcnt vmcnt(7)
	ds_write_b128 v191, v[208:211] offset:18432
	s_waitcnt vmcnt(6)
	ds_write_b128 v191, v[212:215] offset:55296
	ds_read_b128 v[208:211], v169 offset:64
	ds_read_b128 v[212:215], v169 offset:4672
	s_waitcnt lgkmcnt(5)
	v_mfma_f32_32x32x16_bf16 v[80:95], v[198:201], v[224:227], v[80:95]
	v_mfma_f32_32x32x16_bf16 v[16:31], v[202:205], v[224:227], v[16:31]
	ds_read_b128 v[224:227], v168 offset:64
	s_waitcnt lgkmcnt(5)
	v_mfma_f32_32x32x16_bf16 v[64:79], v[198:201], v[228:231], v[64:79]
	v_mfma_f32_32x32x16_bf16 v[0:15], v[202:205], v[228:231], v[0:15]
	ds_read_b128 v[228:231], v168 offset:4672
	s_setprio 0
	global_load_dwordx4 v[198:201], v[144:145], off offset:2432
	global_load_dwordx4 v[202:205], v[148:149], off offset:2432
	s_setprio 1
	s_waitcnt lgkmcnt(1)
	v_mfma_f32_32x32x16_bf16 v[112:127], v[208:211], v[224:227], v[112:127]
	v_mfma_f32_32x32x16_bf16 v[48:63], v[212:215], v[224:227], v[48:63]
	s_waitcnt lgkmcnt(0)
	v_mfma_f32_32x32x16_bf16 v[96:111], v[208:211], v[228:231], v[96:111]
	v_mfma_f32_32x32x16_bf16 v[32:47], v[212:215], v[228:231], v[32:47]
	ds_read_b128 v[224:227], v168 offset:9280
	ds_read_b128 v[228:231], v168 offset:13888
	s_waitcnt vmcnt(7)
	ds_write_b128 v191, v[178:181] offset:27648
	s_waitcnt vmcnt(6)
	ds_write_b128 v191, v[216:219] offset:64512
	ds_read_b128 v[178:181], v169 offset:96
	ds_read_b128 v[216:219], v169 offset:4704
	s_waitcnt lgkmcnt(5)
	v_mfma_f32_32x32x16_bf16 v[80:95], v[208:211], v[224:227], v[80:95]
	v_mfma_f32_32x32x16_bf16 v[16:31], v[212:215], v[224:227], v[16:31]
	ds_read_b128 v[224:227], v168 offset:96
	s_waitcnt lgkmcnt(5)
	v_mfma_f32_32x32x16_bf16 v[64:79], v[208:211], v[228:231], v[64:79]
	v_mfma_f32_32x32x16_bf16 v[0:15], v[212:215], v[228:231], v[0:15]
	ds_read_b128 v[228:231], v168 offset:4704
	s_setprio 0
	global_load_dwordx4 v[208:211], v[152:153], off offset:2432
	global_load_dwordx4 v[212:215], v[156:157], off offset:2432
	s_setprio 1
	s_waitcnt lgkmcnt(1)
	v_mfma_f32_32x32x16_bf16 v[112:127], v[178:181], v[224:227], v[112:127]
	v_mfma_f32_32x32x16_bf16 v[48:63], v[216:219], v[224:227], v[48:63]
	s_waitcnt lgkmcnt(0)
	v_mfma_f32_32x32x16_bf16 v[96:111], v[178:181], v[228:231], v[96:111]
	v_mfma_f32_32x32x16_bf16 v[32:47], v[216:219], v[228:231], v[32:47]
	ds_read_b128 v[224:227], v168 offset:9312
	ds_read_b128 v[228:231], v168 offset:13920
	s_waitcnt lgkmcnt(1)
	v_mfma_f32_32x32x16_bf16 v[80:95], v[178:181], v[224:227], v[80:95]
	v_mfma_f32_32x32x16_bf16 v[16:31], v[216:219], v[224:227], v[16:31]
	s_waitcnt lgkmcnt(0)
	v_mfma_f32_32x32x16_bf16 v[64:79], v[178:181], v[228:231], v[64:79]
	v_mfma_f32_32x32x16_bf16 v[0:15], v[216:219], v[228:231], v[0:15]
	s_setprio 0
	s_barrier
	global_load_dwordx4 v[178:181], v[128:129], off offset:2560
	global_load_dwordx4 v[216:219], v[132:133], off offset:2560
	s_waitcnt vmcnt(9)
	ds_write_b128 v195, v[172:175]
	s_waitcnt vmcnt(8)
	ds_write_b128 v196, v[220:223]
	ds_read_b128 v[172:175], v192 offset:36864
	ds_read_b128 v[220:223], v192 offset:41472
	ds_read_b128 v[224:227], v184
	ds_read_b128 v[228:231], v184 offset:4608
	s_setprio 1
	s_waitcnt lgkmcnt(1)
	v_mfma_f32_32x32x16_bf16 v[112:127], v[172:175], v[224:227], v[112:127]
	v_mfma_f32_32x32x16_bf16 v[48:63], v[220:223], v[224:227], v[48:63]
	s_waitcnt lgkmcnt(0)
	v_mfma_f32_32x32x16_bf16 v[96:111], v[172:175], v[228:231], v[96:111]
	v_mfma_f32_32x32x16_bf16 v[32:47], v[220:223], v[228:231], v[32:47]
	ds_read_b128 v[224:227], v184 offset:9216
	ds_read_b128 v[228:231], v184 offset:13824
	s_waitcnt vmcnt(7)
	ds_write_b128 v194, v[158:161]
	s_waitcnt vmcnt(6)
	ds_write_b128 v193, v[162:165]
	ds_read_b128 v[158:161], v192 offset:36896
	ds_read_b128 v[162:165], v192 offset:41504
	s_waitcnt lgkmcnt(5)
	v_mfma_f32_32x32x16_bf16 v[80:95], v[172:175], v[224:227], v[80:95]
	v_mfma_f32_32x32x16_bf16 v[16:31], v[220:223], v[224:227], v[16:31]
	ds_read_b128 v[224:227], v184 offset:32
	s_waitcnt lgkmcnt(5)
	v_mfma_f32_32x32x16_bf16 v[64:79], v[172:175], v[228:231], v[64:79]
	v_mfma_f32_32x32x16_bf16 v[0:15], v[220:223], v[228:231], v[0:15]
	ds_read_b128 v[228:231], v184 offset:4640
	s_setprio 0
	global_load_dwordx4 v[172:175], v[136:137], off offset:2560
	global_load_dwordx4 v[220:223], v[140:141], off offset:2560
	s_setprio 1
	s_waitcnt lgkmcnt(1)
	v_mfma_f32_32x32x16_bf16 v[112:127], v[158:161], v[224:227], v[112:127]
	v_mfma_f32_32x32x16_bf16 v[48:63], v[162:165], v[224:227], v[48:63]
	s_waitcnt lgkmcnt(0)
	v_mfma_f32_32x32x16_bf16 v[96:111], v[158:161], v[228:231], v[96:111]
	v_mfma_f32_32x32x16_bf16 v[32:47], v[162:165], v[228:231], v[32:47]
	ds_read_b128 v[224:227], v184 offset:9248
	ds_read_b128 v[228:231], v184 offset:13856
	s_waitcnt vmcnt(7)
	ds_write_b128 v177, v[198:201]
	s_waitcnt vmcnt(6)
	ds_write_b128 v176, v[202:205]
	ds_read_b128 v[198:201], v192 offset:36928
	ds_read_b128 v[202:205], v192 offset:41536
	s_waitcnt lgkmcnt(5)
	v_mfma_f32_32x32x16_bf16 v[80:95], v[158:161], v[224:227], v[80:95]
	v_mfma_f32_32x32x16_bf16 v[16:31], v[162:165], v[224:227], v[16:31]
	ds_read_b128 v[224:227], v184 offset:64
	s_waitcnt lgkmcnt(5)
	v_mfma_f32_32x32x16_bf16 v[64:79], v[158:161], v[228:231], v[64:79]
	v_mfma_f32_32x32x16_bf16 v[0:15], v[162:165], v[228:231], v[0:15]
	ds_read_b128 v[228:231], v184 offset:4672
	s_setprio 0
	global_load_dwordx4 v[158:161], v[144:145], off offset:2560
	global_load_dwordx4 v[162:165], v[148:149], off offset:2560
	s_setprio 1
	s_waitcnt lgkmcnt(1)
	v_mfma_f32_32x32x16_bf16 v[112:127], v[198:201], v[224:227], v[112:127]
	v_mfma_f32_32x32x16_bf16 v[48:63], v[202:205], v[224:227], v[48:63]
	s_waitcnt lgkmcnt(0)
	v_mfma_f32_32x32x16_bf16 v[96:111], v[198:201], v[228:231], v[96:111]
	v_mfma_f32_32x32x16_bf16 v[32:47], v[202:205], v[228:231], v[32:47]
	ds_read_b128 v[224:227], v184 offset:9280
	ds_read_b128 v[228:231], v184 offset:13888
	s_waitcnt vmcnt(7)
	ds_write_b128 v171, v[208:211]
	s_waitcnt vmcnt(6)
	ds_write_b128 v170, v[212:215]
	ds_read_b128 v[208:211], v192 offset:36960
	ds_read_b128 v[212:215], v192 offset:41568
	s_waitcnt lgkmcnt(5)
	v_mfma_f32_32x32x16_bf16 v[80:95], v[198:201], v[224:227], v[80:95]
	v_mfma_f32_32x32x16_bf16 v[16:31], v[202:205], v[224:227], v[16:31]
	ds_read_b128 v[224:227], v184 offset:96
	s_waitcnt lgkmcnt(5)
	v_mfma_f32_32x32x16_bf16 v[64:79], v[198:201], v[228:231], v[64:79]
	v_mfma_f32_32x32x16_bf16 v[0:15], v[202:205], v[228:231], v[0:15]
	ds_read_b128 v[228:231], v184 offset:4704
	s_setprio 0
	global_load_dwordx4 v[198:201], v[152:153], off offset:2560
	global_load_dwordx4 v[202:205], v[156:157], off offset:2560
	s_setprio 1
	s_waitcnt lgkmcnt(1)
	v_mfma_f32_32x32x16_bf16 v[112:127], v[208:211], v[224:227], v[112:127]
	v_mfma_f32_32x32x16_bf16 v[48:63], v[212:215], v[224:227], v[48:63]
	s_waitcnt lgkmcnt(0)
	v_mfma_f32_32x32x16_bf16 v[96:111], v[208:211], v[228:231], v[96:111]
	v_mfma_f32_32x32x16_bf16 v[32:47], v[212:215], v[228:231], v[32:47]
	ds_read_b128 v[224:227], v184 offset:9312
	ds_read_b128 v[228:231], v184 offset:13920
	s_waitcnt lgkmcnt(1)
	v_mfma_f32_32x32x16_bf16 v[80:95], v[208:211], v[224:227], v[80:95]
	v_mfma_f32_32x32x16_bf16 v[16:31], v[212:215], v[224:227], v[16:31]
	s_waitcnt lgkmcnt(0)
	v_mfma_f32_32x32x16_bf16 v[64:79], v[208:211], v[228:231], v[64:79]
	v_mfma_f32_32x32x16_bf16 v[0:15], v[212:215], v[228:231], v[0:15]
	s_setprio 0
	s_barrier
	global_load_dwordx4 v[208:211], v[128:129], off offset:2688
	global_load_dwordx4 v[212:215], v[132:133], off offset:2688
	s_waitcnt vmcnt(9)
	ds_write_b128 v191, v[178:181]
	s_waitcnt vmcnt(8)
	ds_write_b128 v191, v[216:219] offset:36864
	ds_read_b128 v[178:181], v169
	ds_read_b128 v[216:219], v169 offset:4608
	ds_read_b128 v[224:227], v168
	ds_read_b128 v[228:231], v168 offset:4608
	s_setprio 1
	s_waitcnt lgkmcnt(1)
	v_mfma_f32_32x32x16_bf16 v[112:127], v[178:181], v[224:227], v[112:127]
	v_mfma_f32_32x32x16_bf16 v[48:63], v[216:219], v[224:227], v[48:63]
	s_waitcnt lgkmcnt(0)
	v_mfma_f32_32x32x16_bf16 v[96:111], v[178:181], v[228:231], v[96:111]
	v_mfma_f32_32x32x16_bf16 v[32:47], v[216:219], v[228:231], v[32:47]
	ds_read_b128 v[224:227], v168 offset:9216
	ds_read_b128 v[228:231], v168 offset:13824
	s_waitcnt vmcnt(7)
	ds_write_b128 v191, v[172:175] offset:9216
	s_waitcnt vmcnt(6)
	ds_write_b128 v191, v[220:223] offset:46080
	ds_read_b128 v[172:175], v169 offset:32
	ds_read_b128 v[220:223], v169 offset:4640
	s_waitcnt lgkmcnt(5)
	v_mfma_f32_32x32x16_bf16 v[80:95], v[178:181], v[224:227], v[80:95]
	v_mfma_f32_32x32x16_bf16 v[16:31], v[216:219], v[224:227], v[16:31]
	ds_read_b128 v[224:227], v168 offset:32
	s_waitcnt lgkmcnt(5)
	v_mfma_f32_32x32x16_bf16 v[64:79], v[178:181], v[228:231], v[64:79]
	v_mfma_f32_32x32x16_bf16 v[0:15], v[216:219], v[228:231], v[0:15]
	ds_read_b128 v[228:231], v168 offset:4640
	s_setprio 0
	global_load_dwordx4 v[178:181], v[136:137], off offset:2688
	global_load_dwordx4 v[216:219], v[140:141], off offset:2688
	s_setprio 1
	s_waitcnt lgkmcnt(1)
	v_mfma_f32_32x32x16_bf16 v[112:127], v[172:175], v[224:227], v[112:127]
	v_mfma_f32_32x32x16_bf16 v[48:63], v[220:223], v[224:227], v[48:63]
	s_waitcnt lgkmcnt(0)
	v_mfma_f32_32x32x16_bf16 v[96:111], v[172:175], v[228:231], v[96:111]
	v_mfma_f32_32x32x16_bf16 v[32:47], v[220:223], v[228:231], v[32:47]
	ds_read_b128 v[224:227], v168 offset:9248
	ds_read_b128 v[228:231], v168 offset:13856
	s_waitcnt vmcnt(7)
	ds_write_b128 v191, v[158:161] offset:18432
	s_waitcnt vmcnt(6)
	ds_write_b128 v191, v[162:165] offset:55296
	ds_read_b128 v[158:161], v169 offset:64
	ds_read_b128 v[162:165], v169 offset:4672
	s_waitcnt lgkmcnt(5)
	v_mfma_f32_32x32x16_bf16 v[80:95], v[172:175], v[224:227], v[80:95]
	v_mfma_f32_32x32x16_bf16 v[16:31], v[220:223], v[224:227], v[16:31]
	ds_read_b128 v[224:227], v168 offset:64
	s_waitcnt lgkmcnt(5)
	v_mfma_f32_32x32x16_bf16 v[64:79], v[172:175], v[228:231], v[64:79]
	v_mfma_f32_32x32x16_bf16 v[0:15], v[220:223], v[228:231], v[0:15]
	ds_read_b128 v[228:231], v168 offset:4672
	s_setprio 0
	global_load_dwordx4 v[172:175], v[144:145], off offset:2688
	global_load_dwordx4 v[220:223], v[148:149], off offset:2688
	s_setprio 1
	s_waitcnt lgkmcnt(1)
	v_mfma_f32_32x32x16_bf16 v[112:127], v[158:161], v[224:227], v[112:127]
	v_mfma_f32_32x32x16_bf16 v[48:63], v[162:165], v[224:227], v[48:63]
	s_waitcnt lgkmcnt(0)
	v_mfma_f32_32x32x16_bf16 v[96:111], v[158:161], v[228:231], v[96:111]
	v_mfma_f32_32x32x16_bf16 v[32:47], v[162:165], v[228:231], v[32:47]
	ds_read_b128 v[224:227], v168 offset:9280
	ds_read_b128 v[228:231], v168 offset:13888
	s_waitcnt vmcnt(7)
	ds_write_b128 v191, v[198:201] offset:27648
	s_waitcnt vmcnt(6)
	ds_write_b128 v191, v[202:205] offset:64512
	ds_read_b128 v[198:201], v169 offset:96
	ds_read_b128 v[202:205], v169 offset:4704
	s_waitcnt lgkmcnt(5)
	v_mfma_f32_32x32x16_bf16 v[80:95], v[158:161], v[224:227], v[80:95]
	v_mfma_f32_32x32x16_bf16 v[16:31], v[162:165], v[224:227], v[16:31]
	ds_read_b128 v[224:227], v168 offset:96
	s_waitcnt lgkmcnt(5)
	v_mfma_f32_32x32x16_bf16 v[64:79], v[158:161], v[228:231], v[64:79]
	v_mfma_f32_32x32x16_bf16 v[0:15], v[162:165], v[228:231], v[0:15]
	ds_read_b128 v[228:231], v168 offset:4704
	s_setprio 0
	global_load_dwordx4 v[158:161], v[152:153], off offset:2688
	global_load_dwordx4 v[162:165], v[156:157], off offset:2688
	s_setprio 1
	s_waitcnt lgkmcnt(1)
	v_mfma_f32_32x32x16_bf16 v[112:127], v[198:201], v[224:227], v[112:127]
	v_mfma_f32_32x32x16_bf16 v[48:63], v[202:205], v[224:227], v[48:63]
	s_waitcnt lgkmcnt(0)
	v_mfma_f32_32x32x16_bf16 v[96:111], v[198:201], v[228:231], v[96:111]
	v_mfma_f32_32x32x16_bf16 v[32:47], v[202:205], v[228:231], v[32:47]
	ds_read_b128 v[224:227], v168 offset:9312
	ds_read_b128 v[228:231], v168 offset:13920
	s_waitcnt lgkmcnt(1)
	v_mfma_f32_32x32x16_bf16 v[80:95], v[198:201], v[224:227], v[80:95]
	v_mfma_f32_32x32x16_bf16 v[16:31], v[202:205], v[224:227], v[16:31]
	s_waitcnt lgkmcnt(0)
	v_mfma_f32_32x32x16_bf16 v[64:79], v[198:201], v[228:231], v[64:79]
	v_mfma_f32_32x32x16_bf16 v[0:15], v[202:205], v[228:231], v[0:15]
	s_setprio 0
	s_barrier
	global_load_dwordx4 v[198:201], v[128:129], off offset:2816
	global_load_dwordx4 v[202:205], v[132:133], off offset:2816
	s_waitcnt vmcnt(9)
	ds_write_b128 v195, v[208:211]
	s_waitcnt vmcnt(8)
	ds_write_b128 v196, v[212:215]
	ds_read_b128 v[208:211], v192 offset:36864
	ds_read_b128 v[212:215], v192 offset:41472
	ds_read_b128 v[224:227], v184
	ds_read_b128 v[228:231], v184 offset:4608
	s_setprio 1
	s_waitcnt lgkmcnt(1)
	v_mfma_f32_32x32x16_bf16 v[112:127], v[208:211], v[224:227], v[112:127]
	v_mfma_f32_32x32x16_bf16 v[48:63], v[212:215], v[224:227], v[48:63]
	s_waitcnt lgkmcnt(0)
	v_mfma_f32_32x32x16_bf16 v[96:111], v[208:211], v[228:231], v[96:111]
	v_mfma_f32_32x32x16_bf16 v[32:47], v[212:215], v[228:231], v[32:47]
	ds_read_b128 v[224:227], v184 offset:9216
	ds_read_b128 v[228:231], v184 offset:13824
	s_waitcnt vmcnt(7)
	ds_write_b128 v194, v[178:181]
	s_waitcnt vmcnt(6)
	ds_write_b128 v193, v[216:219]
	ds_read_b128 v[178:181], v192 offset:36896
	ds_read_b128 v[216:219], v192 offset:41504
	s_waitcnt lgkmcnt(5)
	v_mfma_f32_32x32x16_bf16 v[80:95], v[208:211], v[224:227], v[80:95]
	v_mfma_f32_32x32x16_bf16 v[16:31], v[212:215], v[224:227], v[16:31]
	ds_read_b128 v[224:227], v184 offset:32
	s_waitcnt lgkmcnt(5)
	v_mfma_f32_32x32x16_bf16 v[64:79], v[208:211], v[228:231], v[64:79]
	v_mfma_f32_32x32x16_bf16 v[0:15], v[212:215], v[228:231], v[0:15]
	ds_read_b128 v[228:231], v184 offset:4640
	s_setprio 0
	global_load_dwordx4 v[208:211], v[136:137], off offset:2816
	global_load_dwordx4 v[212:215], v[140:141], off offset:2816
	s_setprio 1
	s_waitcnt lgkmcnt(1)
	v_mfma_f32_32x32x16_bf16 v[112:127], v[178:181], v[224:227], v[112:127]
	v_mfma_f32_32x32x16_bf16 v[48:63], v[216:219], v[224:227], v[48:63]
	s_waitcnt lgkmcnt(0)
	v_mfma_f32_32x32x16_bf16 v[96:111], v[178:181], v[228:231], v[96:111]
	v_mfma_f32_32x32x16_bf16 v[32:47], v[216:219], v[228:231], v[32:47]
	ds_read_b128 v[224:227], v184 offset:9248
	ds_read_b128 v[228:231], v184 offset:13856
	s_waitcnt vmcnt(7)
	ds_write_b128 v177, v[172:175]
	s_waitcnt vmcnt(6)
	ds_write_b128 v176, v[220:223]
	ds_read_b128 v[172:175], v192 offset:36928
	ds_read_b128 v[220:223], v192 offset:41536
	s_waitcnt lgkmcnt(5)
	v_mfma_f32_32x32x16_bf16 v[80:95], v[178:181], v[224:227], v[80:95]
	v_mfma_f32_32x32x16_bf16 v[16:31], v[216:219], v[224:227], v[16:31]
	ds_read_b128 v[224:227], v184 offset:64
	s_waitcnt lgkmcnt(5)
	v_mfma_f32_32x32x16_bf16 v[64:79], v[178:181], v[228:231], v[64:79]
	v_mfma_f32_32x32x16_bf16 v[0:15], v[216:219], v[228:231], v[0:15]
	ds_read_b128 v[228:231], v184 offset:4672
	s_setprio 0
	global_load_dwordx4 v[178:181], v[144:145], off offset:2816
	global_load_dwordx4 v[216:219], v[148:149], off offset:2816
	s_setprio 1
	s_waitcnt lgkmcnt(1)
	v_mfma_f32_32x32x16_bf16 v[112:127], v[172:175], v[224:227], v[112:127]
	v_mfma_f32_32x32x16_bf16 v[48:63], v[220:223], v[224:227], v[48:63]
	s_waitcnt lgkmcnt(0)
	v_mfma_f32_32x32x16_bf16 v[96:111], v[172:175], v[228:231], v[96:111]
	v_mfma_f32_32x32x16_bf16 v[32:47], v[220:223], v[228:231], v[32:47]
	ds_read_b128 v[224:227], v184 offset:9280
	ds_read_b128 v[228:231], v184 offset:13888
	s_waitcnt vmcnt(7)
	ds_write_b128 v171, v[158:161]
	s_waitcnt vmcnt(6)
	ds_write_b128 v170, v[162:165]
	ds_read_b128 v[158:161], v192 offset:36960
	ds_read_b128 v[162:165], v192 offset:41568
	s_waitcnt lgkmcnt(5)
	v_mfma_f32_32x32x16_bf16 v[80:95], v[172:175], v[224:227], v[80:95]
	v_mfma_f32_32x32x16_bf16 v[16:31], v[220:223], v[224:227], v[16:31]
	ds_read_b128 v[224:227], v184 offset:96
	s_waitcnt lgkmcnt(5)
	v_mfma_f32_32x32x16_bf16 v[64:79], v[172:175], v[228:231], v[64:79]
	v_mfma_f32_32x32x16_bf16 v[0:15], v[220:223], v[228:231], v[0:15]
	ds_read_b128 v[228:231], v184 offset:4704
	s_setprio 0
	global_load_dwordx4 v[172:175], v[152:153], off offset:2816
	global_load_dwordx4 v[220:223], v[156:157], off offset:2816
	s_setprio 1
	s_waitcnt lgkmcnt(1)
	v_mfma_f32_32x32x16_bf16 v[112:127], v[158:161], v[224:227], v[112:127]
	v_mfma_f32_32x32x16_bf16 v[48:63], v[162:165], v[224:227], v[48:63]
	s_waitcnt lgkmcnt(0)
	v_mfma_f32_32x32x16_bf16 v[96:111], v[158:161], v[228:231], v[96:111]
	v_mfma_f32_32x32x16_bf16 v[32:47], v[162:165], v[228:231], v[32:47]
	ds_read_b128 v[224:227], v184 offset:9312
	ds_read_b128 v[228:231], v184 offset:13920
	s_waitcnt lgkmcnt(1)
	v_mfma_f32_32x32x16_bf16 v[80:95], v[158:161], v[224:227], v[80:95]
	v_mfma_f32_32x32x16_bf16 v[16:31], v[162:165], v[224:227], v[16:31]
	s_waitcnt lgkmcnt(0)
	v_mfma_f32_32x32x16_bf16 v[64:79], v[158:161], v[228:231], v[64:79]
	v_mfma_f32_32x32x16_bf16 v[0:15], v[162:165], v[228:231], v[0:15]
	s_setprio 0
	s_barrier
	global_load_dwordx4 v[158:161], v[128:129], off offset:2944
	global_load_dwordx4 v[162:165], v[132:133], off offset:2944
	s_waitcnt vmcnt(9)
	ds_write_b128 v191, v[198:201]
	s_waitcnt vmcnt(8)
	ds_write_b128 v191, v[202:205] offset:36864
	ds_read_b128 v[198:201], v169
	ds_read_b128 v[202:205], v169 offset:4608
	ds_read_b128 v[224:227], v168
	ds_read_b128 v[228:231], v168 offset:4608
	s_setprio 1
	s_waitcnt lgkmcnt(1)
	v_mfma_f32_32x32x16_bf16 v[112:127], v[198:201], v[224:227], v[112:127]
	v_mfma_f32_32x32x16_bf16 v[48:63], v[202:205], v[224:227], v[48:63]
	s_waitcnt lgkmcnt(0)
	v_mfma_f32_32x32x16_bf16 v[96:111], v[198:201], v[228:231], v[96:111]
	v_mfma_f32_32x32x16_bf16 v[32:47], v[202:205], v[228:231], v[32:47]
	ds_read_b128 v[224:227], v168 offset:9216
	ds_read_b128 v[228:231], v168 offset:13824
	s_waitcnt vmcnt(7)
	ds_write_b128 v191, v[208:211] offset:9216
	s_waitcnt vmcnt(6)
	ds_write_b128 v191, v[212:215] offset:46080
	ds_read_b128 v[208:211], v169 offset:32
	ds_read_b128 v[212:215], v169 offset:4640
	s_waitcnt lgkmcnt(5)
	v_mfma_f32_32x32x16_bf16 v[80:95], v[198:201], v[224:227], v[80:95]
	v_mfma_f32_32x32x16_bf16 v[16:31], v[202:205], v[224:227], v[16:31]
	ds_read_b128 v[224:227], v168 offset:32
	s_waitcnt lgkmcnt(5)
	v_mfma_f32_32x32x16_bf16 v[64:79], v[198:201], v[228:231], v[64:79]
	v_mfma_f32_32x32x16_bf16 v[0:15], v[202:205], v[228:231], v[0:15]
	ds_read_b128 v[228:231], v168 offset:4640
	s_setprio 0
	global_load_dwordx4 v[198:201], v[136:137], off offset:2944
	global_load_dwordx4 v[202:205], v[140:141], off offset:2944
	s_setprio 1
	s_waitcnt lgkmcnt(1)
	v_mfma_f32_32x32x16_bf16 v[112:127], v[208:211], v[224:227], v[112:127]
	v_mfma_f32_32x32x16_bf16 v[48:63], v[212:215], v[224:227], v[48:63]
	s_waitcnt lgkmcnt(0)
	v_mfma_f32_32x32x16_bf16 v[96:111], v[208:211], v[228:231], v[96:111]
	v_mfma_f32_32x32x16_bf16 v[32:47], v[212:215], v[228:231], v[32:47]
	ds_read_b128 v[224:227], v168 offset:9248
	ds_read_b128 v[228:231], v168 offset:13856
	s_waitcnt vmcnt(7)
	ds_write_b128 v191, v[178:181] offset:18432
	s_waitcnt vmcnt(6)
	ds_write_b128 v191, v[216:219] offset:55296
	ds_read_b128 v[178:181], v169 offset:64
	ds_read_b128 v[216:219], v169 offset:4672
	s_waitcnt lgkmcnt(5)
	v_mfma_f32_32x32x16_bf16 v[80:95], v[208:211], v[224:227], v[80:95]
	v_mfma_f32_32x32x16_bf16 v[16:31], v[212:215], v[224:227], v[16:31]
	ds_read_b128 v[224:227], v168 offset:64
	s_waitcnt lgkmcnt(5)
	v_mfma_f32_32x32x16_bf16 v[64:79], v[208:211], v[228:231], v[64:79]
	v_mfma_f32_32x32x16_bf16 v[0:15], v[212:215], v[228:231], v[0:15]
	ds_read_b128 v[228:231], v168 offset:4672
	s_setprio 0
	global_load_dwordx4 v[208:211], v[144:145], off offset:2944
	global_load_dwordx4 v[212:215], v[148:149], off offset:2944
	s_setprio 1
	s_waitcnt lgkmcnt(1)
	v_mfma_f32_32x32x16_bf16 v[112:127], v[178:181], v[224:227], v[112:127]
	v_mfma_f32_32x32x16_bf16 v[48:63], v[216:219], v[224:227], v[48:63]
	s_waitcnt lgkmcnt(0)
	v_mfma_f32_32x32x16_bf16 v[96:111], v[178:181], v[228:231], v[96:111]
	v_mfma_f32_32x32x16_bf16 v[32:47], v[216:219], v[228:231], v[32:47]
	ds_read_b128 v[224:227], v168 offset:9280
	ds_read_b128 v[228:231], v168 offset:13888
	s_waitcnt vmcnt(7)
	ds_write_b128 v191, v[172:175] offset:27648
	s_waitcnt vmcnt(6)
	ds_write_b128 v191, v[220:223] offset:64512
	ds_read_b128 v[172:175], v169 offset:96
	ds_read_b128 v[220:223], v169 offset:4704
	s_waitcnt lgkmcnt(5)
	v_mfma_f32_32x32x16_bf16 v[80:95], v[178:181], v[224:227], v[80:95]
	v_mfma_f32_32x32x16_bf16 v[16:31], v[216:219], v[224:227], v[16:31]
	ds_read_b128 v[224:227], v168 offset:96
	s_waitcnt lgkmcnt(5)
	v_mfma_f32_32x32x16_bf16 v[64:79], v[178:181], v[228:231], v[64:79]
	v_mfma_f32_32x32x16_bf16 v[0:15], v[216:219], v[228:231], v[0:15]
	ds_read_b128 v[228:231], v168 offset:4704
	s_setprio 0
	global_load_dwordx4 v[178:181], v[152:153], off offset:2944
	global_load_dwordx4 v[216:219], v[156:157], off offset:2944
	s_setprio 1
	s_waitcnt lgkmcnt(1)
	v_mfma_f32_32x32x16_bf16 v[112:127], v[172:175], v[224:227], v[112:127]
	v_mfma_f32_32x32x16_bf16 v[48:63], v[220:223], v[224:227], v[48:63]
	s_waitcnt lgkmcnt(0)
	v_mfma_f32_32x32x16_bf16 v[96:111], v[172:175], v[228:231], v[96:111]
	v_mfma_f32_32x32x16_bf16 v[32:47], v[220:223], v[228:231], v[32:47]
	ds_read_b128 v[224:227], v168 offset:9312
	ds_read_b128 v[228:231], v168 offset:13920
	s_waitcnt lgkmcnt(1)
	v_mfma_f32_32x32x16_bf16 v[80:95], v[172:175], v[224:227], v[80:95]
	v_mfma_f32_32x32x16_bf16 v[16:31], v[220:223], v[224:227], v[16:31]
	s_waitcnt lgkmcnt(0)
	v_mfma_f32_32x32x16_bf16 v[64:79], v[172:175], v[228:231], v[64:79]
	v_mfma_f32_32x32x16_bf16 v[0:15], v[220:223], v[228:231], v[0:15]
	s_setprio 0
	s_barrier
	global_load_dwordx4 v[172:175], v[128:129], off offset:3072
	global_load_dwordx4 v[220:223], v[132:133], off offset:3072
	s_waitcnt vmcnt(9)
	ds_write_b128 v195, v[158:161]
	s_waitcnt vmcnt(8)
	ds_write_b128 v196, v[162:165]
	ds_read_b128 v[158:161], v192 offset:36864
	ds_read_b128 v[162:165], v192 offset:41472
	ds_read_b128 v[224:227], v184
	ds_read_b128 v[228:231], v184 offset:4608
	s_setprio 1
	s_waitcnt lgkmcnt(1)
	v_mfma_f32_32x32x16_bf16 v[112:127], v[158:161], v[224:227], v[112:127]
	v_mfma_f32_32x32x16_bf16 v[48:63], v[162:165], v[224:227], v[48:63]
	s_waitcnt lgkmcnt(0)
	v_mfma_f32_32x32x16_bf16 v[96:111], v[158:161], v[228:231], v[96:111]
	v_mfma_f32_32x32x16_bf16 v[32:47], v[162:165], v[228:231], v[32:47]
	ds_read_b128 v[224:227], v184 offset:9216
	ds_read_b128 v[228:231], v184 offset:13824
	s_waitcnt vmcnt(7)
	ds_write_b128 v194, v[198:201]
	s_waitcnt vmcnt(6)
	ds_write_b128 v193, v[202:205]
	ds_read_b128 v[198:201], v192 offset:36896
	ds_read_b128 v[202:205], v192 offset:41504
	s_waitcnt lgkmcnt(5)
	v_mfma_f32_32x32x16_bf16 v[80:95], v[158:161], v[224:227], v[80:95]
	v_mfma_f32_32x32x16_bf16 v[16:31], v[162:165], v[224:227], v[16:31]
	ds_read_b128 v[224:227], v184 offset:32
	s_waitcnt lgkmcnt(5)
	v_mfma_f32_32x32x16_bf16 v[64:79], v[158:161], v[228:231], v[64:79]
	v_mfma_f32_32x32x16_bf16 v[0:15], v[162:165], v[228:231], v[0:15]
	ds_read_b128 v[228:231], v184 offset:4640
	s_setprio 0
	global_load_dwordx4 v[158:161], v[136:137], off offset:3072
	global_load_dwordx4 v[162:165], v[140:141], off offset:3072
	s_setprio 1
	s_waitcnt lgkmcnt(1)
	v_mfma_f32_32x32x16_bf16 v[112:127], v[198:201], v[224:227], v[112:127]
	v_mfma_f32_32x32x16_bf16 v[48:63], v[202:205], v[224:227], v[48:63]
	s_waitcnt lgkmcnt(0)
	v_mfma_f32_32x32x16_bf16 v[96:111], v[198:201], v[228:231], v[96:111]
	v_mfma_f32_32x32x16_bf16 v[32:47], v[202:205], v[228:231], v[32:47]
	ds_read_b128 v[224:227], v184 offset:9248
	ds_read_b128 v[228:231], v184 offset:13856
	s_waitcnt vmcnt(7)
	ds_write_b128 v177, v[208:211]
	s_waitcnt vmcnt(6)
	ds_write_b128 v176, v[212:215]
	ds_read_b128 v[208:211], v192 offset:36928
	ds_read_b128 v[212:215], v192 offset:41536
	s_waitcnt lgkmcnt(5)
	v_mfma_f32_32x32x16_bf16 v[80:95], v[198:201], v[224:227], v[80:95]
	v_mfma_f32_32x32x16_bf16 v[16:31], v[202:205], v[224:227], v[16:31]
	ds_read_b128 v[224:227], v184 offset:64
	s_waitcnt lgkmcnt(5)
	v_mfma_f32_32x32x16_bf16 v[64:79], v[198:201], v[228:231], v[64:79]
	v_mfma_f32_32x32x16_bf16 v[0:15], v[202:205], v[228:231], v[0:15]
	ds_read_b128 v[228:231], v184 offset:4672
	s_setprio 0
	global_load_dwordx4 v[198:201], v[144:145], off offset:3072
	global_load_dwordx4 v[202:205], v[148:149], off offset:3072
	s_setprio 1
	s_waitcnt lgkmcnt(1)
	v_mfma_f32_32x32x16_bf16 v[112:127], v[208:211], v[224:227], v[112:127]
	v_mfma_f32_32x32x16_bf16 v[48:63], v[212:215], v[224:227], v[48:63]
	s_waitcnt lgkmcnt(0)
	v_mfma_f32_32x32x16_bf16 v[96:111], v[208:211], v[228:231], v[96:111]
	v_mfma_f32_32x32x16_bf16 v[32:47], v[212:215], v[228:231], v[32:47]
	ds_read_b128 v[224:227], v184 offset:9280
	ds_read_b128 v[228:231], v184 offset:13888
	s_waitcnt vmcnt(7)
	ds_write_b128 v171, v[178:181]
	s_waitcnt vmcnt(6)
	ds_write_b128 v170, v[216:219]
	ds_read_b128 v[178:181], v192 offset:36960
	ds_read_b128 v[216:219], v192 offset:41568
	s_waitcnt lgkmcnt(5)
	v_mfma_f32_32x32x16_bf16 v[80:95], v[208:211], v[224:227], v[80:95]
	v_mfma_f32_32x32x16_bf16 v[16:31], v[212:215], v[224:227], v[16:31]
	ds_read_b128 v[224:227], v184 offset:96
	s_waitcnt lgkmcnt(5)
	v_mfma_f32_32x32x16_bf16 v[64:79], v[208:211], v[228:231], v[64:79]
	v_mfma_f32_32x32x16_bf16 v[0:15], v[212:215], v[228:231], v[0:15]
	ds_read_b128 v[228:231], v184 offset:4704
	s_setprio 0
	global_load_dwordx4 v[208:211], v[152:153], off offset:3072
	global_load_dwordx4 v[212:215], v[156:157], off offset:3072
	s_setprio 1
	s_waitcnt lgkmcnt(1)
	v_mfma_f32_32x32x16_bf16 v[112:127], v[178:181], v[224:227], v[112:127]
	v_mfma_f32_32x32x16_bf16 v[48:63], v[216:219], v[224:227], v[48:63]
	s_waitcnt lgkmcnt(0)
	v_mfma_f32_32x32x16_bf16 v[96:111], v[178:181], v[228:231], v[96:111]
	v_mfma_f32_32x32x16_bf16 v[32:47], v[216:219], v[228:231], v[32:47]
	ds_read_b128 v[224:227], v184 offset:9312
	ds_read_b128 v[228:231], v184 offset:13920
	s_waitcnt lgkmcnt(1)
	v_mfma_f32_32x32x16_bf16 v[80:95], v[178:181], v[224:227], v[80:95]
	v_mfma_f32_32x32x16_bf16 v[16:31], v[216:219], v[224:227], v[16:31]
	s_waitcnt lgkmcnt(0)
	v_mfma_f32_32x32x16_bf16 v[64:79], v[178:181], v[228:231], v[64:79]
	v_mfma_f32_32x32x16_bf16 v[0:15], v[216:219], v[228:231], v[0:15]
	s_setprio 0
	s_barrier
	global_load_dwordx4 v[178:181], v[128:129], off offset:3200
	global_load_dwordx4 v[216:219], v[132:133], off offset:3200
	s_waitcnt vmcnt(9)
	ds_write_b128 v191, v[172:175]
	s_waitcnt vmcnt(8)
	ds_write_b128 v191, v[220:223] offset:36864
	ds_read_b128 v[172:175], v169
	ds_read_b128 v[220:223], v169 offset:4608
	ds_read_b128 v[224:227], v168
	ds_read_b128 v[228:231], v168 offset:4608
	s_setprio 1
	s_waitcnt lgkmcnt(1)
	v_mfma_f32_32x32x16_bf16 v[112:127], v[172:175], v[224:227], v[112:127]
	v_mfma_f32_32x32x16_bf16 v[48:63], v[220:223], v[224:227], v[48:63]
	s_waitcnt lgkmcnt(0)
	v_mfma_f32_32x32x16_bf16 v[96:111], v[172:175], v[228:231], v[96:111]
	v_mfma_f32_32x32x16_bf16 v[32:47], v[220:223], v[228:231], v[32:47]
	ds_read_b128 v[224:227], v168 offset:9216
	ds_read_b128 v[228:231], v168 offset:13824
	s_waitcnt vmcnt(7)
	ds_write_b128 v191, v[158:161] offset:9216
	s_waitcnt vmcnt(6)
	ds_write_b128 v191, v[162:165] offset:46080
	ds_read_b128 v[158:161], v169 offset:32
	ds_read_b128 v[162:165], v169 offset:4640
	s_waitcnt lgkmcnt(5)
	v_mfma_f32_32x32x16_bf16 v[80:95], v[172:175], v[224:227], v[80:95]
	v_mfma_f32_32x32x16_bf16 v[16:31], v[220:223], v[224:227], v[16:31]
	ds_read_b128 v[224:227], v168 offset:32
	s_waitcnt lgkmcnt(5)
	v_mfma_f32_32x32x16_bf16 v[64:79], v[172:175], v[228:231], v[64:79]
	v_mfma_f32_32x32x16_bf16 v[0:15], v[220:223], v[228:231], v[0:15]
	ds_read_b128 v[228:231], v168 offset:4640
	s_setprio 0
	global_load_dwordx4 v[172:175], v[136:137], off offset:3200
	global_load_dwordx4 v[220:223], v[140:141], off offset:3200
	s_setprio 1
	s_waitcnt lgkmcnt(1)
	v_mfma_f32_32x32x16_bf16 v[112:127], v[158:161], v[224:227], v[112:127]
	v_mfma_f32_32x32x16_bf16 v[48:63], v[162:165], v[224:227], v[48:63]
	s_waitcnt lgkmcnt(0)
	v_mfma_f32_32x32x16_bf16 v[96:111], v[158:161], v[228:231], v[96:111]
	v_mfma_f32_32x32x16_bf16 v[32:47], v[162:165], v[228:231], v[32:47]
	ds_read_b128 v[224:227], v168 offset:9248
	ds_read_b128 v[228:231], v168 offset:13856
	s_waitcnt vmcnt(7)
	ds_write_b128 v191, v[198:201] offset:18432
	s_waitcnt vmcnt(6)
	ds_write_b128 v191, v[202:205] offset:55296
	ds_read_b128 v[198:201], v169 offset:64
	ds_read_b128 v[202:205], v169 offset:4672
	s_waitcnt lgkmcnt(5)
	v_mfma_f32_32x32x16_bf16 v[80:95], v[158:161], v[224:227], v[80:95]
	v_mfma_f32_32x32x16_bf16 v[16:31], v[162:165], v[224:227], v[16:31]
	ds_read_b128 v[224:227], v168 offset:64
	s_waitcnt lgkmcnt(5)
	v_mfma_f32_32x32x16_bf16 v[64:79], v[158:161], v[228:231], v[64:79]
	v_mfma_f32_32x32x16_bf16 v[0:15], v[162:165], v[228:231], v[0:15]
	ds_read_b128 v[228:231], v168 offset:4672
	s_setprio 0
	global_load_dwordx4 v[158:161], v[144:145], off offset:3200
	global_load_dwordx4 v[162:165], v[148:149], off offset:3200
	s_setprio 1
	s_waitcnt lgkmcnt(1)
	v_mfma_f32_32x32x16_bf16 v[112:127], v[198:201], v[224:227], v[112:127]
	v_mfma_f32_32x32x16_bf16 v[48:63], v[202:205], v[224:227], v[48:63]
	s_waitcnt lgkmcnt(0)
	v_mfma_f32_32x32x16_bf16 v[96:111], v[198:201], v[228:231], v[96:111]
	v_mfma_f32_32x32x16_bf16 v[32:47], v[202:205], v[228:231], v[32:47]
	ds_read_b128 v[224:227], v168 offset:9280
	ds_read_b128 v[228:231], v168 offset:13888
	s_waitcnt vmcnt(7)
	ds_write_b128 v191, v[208:211] offset:27648
	s_waitcnt vmcnt(6)
	ds_write_b128 v191, v[212:215] offset:64512
	ds_read_b128 v[208:211], v169 offset:96
	ds_read_b128 v[212:215], v169 offset:4704
	s_waitcnt lgkmcnt(5)
	v_mfma_f32_32x32x16_bf16 v[80:95], v[198:201], v[224:227], v[80:95]
	v_mfma_f32_32x32x16_bf16 v[16:31], v[202:205], v[224:227], v[16:31]
	ds_read_b128 v[224:227], v168 offset:96
	s_waitcnt lgkmcnt(5)
	v_mfma_f32_32x32x16_bf16 v[64:79], v[198:201], v[228:231], v[64:79]
	v_mfma_f32_32x32x16_bf16 v[0:15], v[202:205], v[228:231], v[0:15]
	ds_read_b128 v[228:231], v168 offset:4704
	s_setprio 0
	global_load_dwordx4 v[198:201], v[152:153], off offset:3200
	global_load_dwordx4 v[202:205], v[156:157], off offset:3200
	s_setprio 1
	s_waitcnt lgkmcnt(1)
	v_mfma_f32_32x32x16_bf16 v[112:127], v[208:211], v[224:227], v[112:127]
	v_mfma_f32_32x32x16_bf16 v[48:63], v[212:215], v[224:227], v[48:63]
	s_waitcnt lgkmcnt(0)
	v_mfma_f32_32x32x16_bf16 v[96:111], v[208:211], v[228:231], v[96:111]
	v_mfma_f32_32x32x16_bf16 v[32:47], v[212:215], v[228:231], v[32:47]
	ds_read_b128 v[224:227], v168 offset:9312
	ds_read_b128 v[228:231], v168 offset:13920
	s_waitcnt lgkmcnt(1)
	v_mfma_f32_32x32x16_bf16 v[80:95], v[208:211], v[224:227], v[80:95]
	v_mfma_f32_32x32x16_bf16 v[16:31], v[212:215], v[224:227], v[16:31]
	s_waitcnt lgkmcnt(0)
	v_mfma_f32_32x32x16_bf16 v[64:79], v[208:211], v[228:231], v[64:79]
	v_mfma_f32_32x32x16_bf16 v[0:15], v[212:215], v[228:231], v[0:15]
	s_setprio 0
	s_barrier
	global_load_dwordx4 v[208:211], v[128:129], off offset:3328
	global_load_dwordx4 v[212:215], v[132:133], off offset:3328
	s_waitcnt vmcnt(9)
	ds_write_b128 v195, v[178:181]
	s_waitcnt vmcnt(8)
	ds_write_b128 v196, v[216:219]
	ds_read_b128 v[178:181], v192 offset:36864
	ds_read_b128 v[216:219], v192 offset:41472
	ds_read_b128 v[224:227], v184
	ds_read_b128 v[228:231], v184 offset:4608
	s_setprio 1
	s_waitcnt lgkmcnt(1)
	v_mfma_f32_32x32x16_bf16 v[112:127], v[178:181], v[224:227], v[112:127]
	v_mfma_f32_32x32x16_bf16 v[48:63], v[216:219], v[224:227], v[48:63]
	s_waitcnt lgkmcnt(0)
	v_mfma_f32_32x32x16_bf16 v[96:111], v[178:181], v[228:231], v[96:111]
	v_mfma_f32_32x32x16_bf16 v[32:47], v[216:219], v[228:231], v[32:47]
	ds_read_b128 v[224:227], v184 offset:9216
	ds_read_b128 v[228:231], v184 offset:13824
	s_waitcnt vmcnt(7)
	ds_write_b128 v194, v[172:175]
	s_waitcnt vmcnt(6)
	ds_write_b128 v193, v[220:223]
	ds_read_b128 v[172:175], v192 offset:36896
	ds_read_b128 v[220:223], v192 offset:41504
	s_waitcnt lgkmcnt(5)
	v_mfma_f32_32x32x16_bf16 v[80:95], v[178:181], v[224:227], v[80:95]
	v_mfma_f32_32x32x16_bf16 v[16:31], v[216:219], v[224:227], v[16:31]
	ds_read_b128 v[224:227], v184 offset:32
	s_waitcnt lgkmcnt(5)
	v_mfma_f32_32x32x16_bf16 v[64:79], v[178:181], v[228:231], v[64:79]
	v_mfma_f32_32x32x16_bf16 v[0:15], v[216:219], v[228:231], v[0:15]
	ds_read_b128 v[228:231], v184 offset:4640
	s_setprio 0
	global_load_dwordx4 v[178:181], v[136:137], off offset:3328
	global_load_dwordx4 v[216:219], v[140:141], off offset:3328
	s_setprio 1
	s_waitcnt lgkmcnt(1)
	v_mfma_f32_32x32x16_bf16 v[112:127], v[172:175], v[224:227], v[112:127]
	v_mfma_f32_32x32x16_bf16 v[48:63], v[220:223], v[224:227], v[48:63]
	s_waitcnt lgkmcnt(0)
	v_mfma_f32_32x32x16_bf16 v[96:111], v[172:175], v[228:231], v[96:111]
	v_mfma_f32_32x32x16_bf16 v[32:47], v[220:223], v[228:231], v[32:47]
	ds_read_b128 v[224:227], v184 offset:9248
	ds_read_b128 v[228:231], v184 offset:13856
	s_waitcnt vmcnt(7)
	ds_write_b128 v177, v[158:161]
	s_waitcnt vmcnt(6)
	ds_write_b128 v176, v[162:165]
	ds_read_b128 v[158:161], v192 offset:36928
	ds_read_b128 v[162:165], v192 offset:41536
	s_waitcnt lgkmcnt(5)
	v_mfma_f32_32x32x16_bf16 v[80:95], v[172:175], v[224:227], v[80:95]
	v_mfma_f32_32x32x16_bf16 v[16:31], v[220:223], v[224:227], v[16:31]
	ds_read_b128 v[224:227], v184 offset:64
	s_waitcnt lgkmcnt(5)
	v_mfma_f32_32x32x16_bf16 v[64:79], v[172:175], v[228:231], v[64:79]
	v_mfma_f32_32x32x16_bf16 v[0:15], v[220:223], v[228:231], v[0:15]
	ds_read_b128 v[228:231], v184 offset:4672
	s_setprio 0
	global_load_dwordx4 v[172:175], v[144:145], off offset:3328
	global_load_dwordx4 v[220:223], v[148:149], off offset:3328
	s_setprio 1
	s_waitcnt lgkmcnt(1)
	v_mfma_f32_32x32x16_bf16 v[112:127], v[158:161], v[224:227], v[112:127]
	v_mfma_f32_32x32x16_bf16 v[48:63], v[162:165], v[224:227], v[48:63]
	s_waitcnt lgkmcnt(0)
	v_mfma_f32_32x32x16_bf16 v[96:111], v[158:161], v[228:231], v[96:111]
	v_mfma_f32_32x32x16_bf16 v[32:47], v[162:165], v[228:231], v[32:47]
	ds_read_b128 v[224:227], v184 offset:9280
	ds_read_b128 v[228:231], v184 offset:13888
	s_waitcnt vmcnt(7)
	ds_write_b128 v171, v[198:201]
	s_waitcnt vmcnt(6)
	ds_write_b128 v170, v[202:205]
	ds_read_b128 v[198:201], v192 offset:36960
	ds_read_b128 v[202:205], v192 offset:41568
	s_waitcnt lgkmcnt(5)
	v_mfma_f32_32x32x16_bf16 v[80:95], v[158:161], v[224:227], v[80:95]
	v_mfma_f32_32x32x16_bf16 v[16:31], v[162:165], v[224:227], v[16:31]
	ds_read_b128 v[224:227], v184 offset:96
	s_waitcnt lgkmcnt(5)
	v_mfma_f32_32x32x16_bf16 v[64:79], v[158:161], v[228:231], v[64:79]
	v_mfma_f32_32x32x16_bf16 v[0:15], v[162:165], v[228:231], v[0:15]
	ds_read_b128 v[228:231], v184 offset:4704
	s_setprio 0
	global_load_dwordx4 v[158:161], v[152:153], off offset:3328
	global_load_dwordx4 v[162:165], v[156:157], off offset:3328
	s_setprio 1
	s_waitcnt lgkmcnt(1)
	v_mfma_f32_32x32x16_bf16 v[112:127], v[198:201], v[224:227], v[112:127]
	v_mfma_f32_32x32x16_bf16 v[48:63], v[202:205], v[224:227], v[48:63]
	s_waitcnt lgkmcnt(0)
	v_mfma_f32_32x32x16_bf16 v[96:111], v[198:201], v[228:231], v[96:111]
	v_mfma_f32_32x32x16_bf16 v[32:47], v[202:205], v[228:231], v[32:47]
	ds_read_b128 v[224:227], v184 offset:9312
	ds_read_b128 v[228:231], v184 offset:13920
	s_waitcnt lgkmcnt(1)
	v_mfma_f32_32x32x16_bf16 v[80:95], v[198:201], v[224:227], v[80:95]
	v_mfma_f32_32x32x16_bf16 v[16:31], v[202:205], v[224:227], v[16:31]
	s_waitcnt lgkmcnt(0)
	v_mfma_f32_32x32x16_bf16 v[64:79], v[198:201], v[228:231], v[64:79]
	v_mfma_f32_32x32x16_bf16 v[0:15], v[202:205], v[228:231], v[0:15]
	s_setprio 0
	s_barrier
	global_load_dwordx4 v[198:201], v[128:129], off offset:3456
	global_load_dwordx4 v[202:205], v[132:133], off offset:3456
	s_waitcnt vmcnt(9)
	ds_write_b128 v191, v[208:211]
	s_waitcnt vmcnt(8)
	ds_write_b128 v191, v[212:215] offset:36864
	ds_read_b128 v[208:211], v169
	ds_read_b128 v[212:215], v169 offset:4608
	ds_read_b128 v[224:227], v168
	ds_read_b128 v[228:231], v168 offset:4608
	s_setprio 1
	s_waitcnt lgkmcnt(1)
	v_mfma_f32_32x32x16_bf16 v[112:127], v[208:211], v[224:227], v[112:127]
	v_mfma_f32_32x32x16_bf16 v[48:63], v[212:215], v[224:227], v[48:63]
	s_waitcnt lgkmcnt(0)
	v_mfma_f32_32x32x16_bf16 v[96:111], v[208:211], v[228:231], v[96:111]
	v_mfma_f32_32x32x16_bf16 v[32:47], v[212:215], v[228:231], v[32:47]
	ds_read_b128 v[224:227], v168 offset:9216
	ds_read_b128 v[228:231], v168 offset:13824
	s_waitcnt vmcnt(7)
	ds_write_b128 v191, v[178:181] offset:9216
	s_waitcnt vmcnt(6)
	ds_write_b128 v191, v[216:219] offset:46080
	ds_read_b128 v[178:181], v169 offset:32
	ds_read_b128 v[216:219], v169 offset:4640
	s_waitcnt lgkmcnt(5)
	v_mfma_f32_32x32x16_bf16 v[80:95], v[208:211], v[224:227], v[80:95]
	v_mfma_f32_32x32x16_bf16 v[16:31], v[212:215], v[224:227], v[16:31]
	ds_read_b128 v[224:227], v168 offset:32
	s_waitcnt lgkmcnt(5)
	v_mfma_f32_32x32x16_bf16 v[64:79], v[208:211], v[228:231], v[64:79]
	v_mfma_f32_32x32x16_bf16 v[0:15], v[212:215], v[228:231], v[0:15]
	ds_read_b128 v[228:231], v168 offset:4640
	s_setprio 0
	global_load_dwordx4 v[208:211], v[136:137], off offset:3456
	global_load_dwordx4 v[212:215], v[140:141], off offset:3456
	s_setprio 1
	s_waitcnt lgkmcnt(1)
	v_mfma_f32_32x32x16_bf16 v[112:127], v[178:181], v[224:227], v[112:127]
	v_mfma_f32_32x32x16_bf16 v[48:63], v[216:219], v[224:227], v[48:63]
	s_waitcnt lgkmcnt(0)
	v_mfma_f32_32x32x16_bf16 v[96:111], v[178:181], v[228:231], v[96:111]
	v_mfma_f32_32x32x16_bf16 v[32:47], v[216:219], v[228:231], v[32:47]
	ds_read_b128 v[224:227], v168 offset:9248
	ds_read_b128 v[228:231], v168 offset:13856
	s_waitcnt vmcnt(7)
	ds_write_b128 v191, v[172:175] offset:18432
	s_waitcnt vmcnt(6)
	ds_write_b128 v191, v[220:223] offset:55296
	ds_read_b128 v[172:175], v169 offset:64
	ds_read_b128 v[220:223], v169 offset:4672
	s_waitcnt lgkmcnt(5)
	v_mfma_f32_32x32x16_bf16 v[80:95], v[178:181], v[224:227], v[80:95]
	v_mfma_f32_32x32x16_bf16 v[16:31], v[216:219], v[224:227], v[16:31]
	ds_read_b128 v[224:227], v168 offset:64
	s_waitcnt lgkmcnt(5)
	v_mfma_f32_32x32x16_bf16 v[64:79], v[178:181], v[228:231], v[64:79]
	v_mfma_f32_32x32x16_bf16 v[0:15], v[216:219], v[228:231], v[0:15]
	ds_read_b128 v[228:231], v168 offset:4672
	s_setprio 0
	global_load_dwordx4 v[178:181], v[144:145], off offset:3456
	global_load_dwordx4 v[216:219], v[148:149], off offset:3456
	s_setprio 1
	s_waitcnt lgkmcnt(1)
	v_mfma_f32_32x32x16_bf16 v[112:127], v[172:175], v[224:227], v[112:127]
	v_mfma_f32_32x32x16_bf16 v[48:63], v[220:223], v[224:227], v[48:63]
	s_waitcnt lgkmcnt(0)
	v_mfma_f32_32x32x16_bf16 v[96:111], v[172:175], v[228:231], v[96:111]
	v_mfma_f32_32x32x16_bf16 v[32:47], v[220:223], v[228:231], v[32:47]
	ds_read_b128 v[224:227], v168 offset:9280
	ds_read_b128 v[228:231], v168 offset:13888
	s_waitcnt vmcnt(7)
	ds_write_b128 v191, v[158:161] offset:27648
	s_waitcnt vmcnt(6)
	ds_write_b128 v191, v[162:165] offset:64512
	ds_read_b128 v[158:161], v169 offset:96
	ds_read_b128 v[162:165], v169 offset:4704
	s_waitcnt lgkmcnt(5)
	v_mfma_f32_32x32x16_bf16 v[80:95], v[172:175], v[224:227], v[80:95]
	v_mfma_f32_32x32x16_bf16 v[16:31], v[220:223], v[224:227], v[16:31]
	ds_read_b128 v[224:227], v168 offset:96
	s_waitcnt lgkmcnt(5)
	v_mfma_f32_32x32x16_bf16 v[64:79], v[172:175], v[228:231], v[64:79]
	v_mfma_f32_32x32x16_bf16 v[0:15], v[220:223], v[228:231], v[0:15]
	ds_read_b128 v[228:231], v168 offset:4704
	s_setprio 0
	global_load_dwordx4 v[172:175], v[152:153], off offset:3456
	global_load_dwordx4 v[220:223], v[156:157], off offset:3456
	s_setprio 1
	s_waitcnt lgkmcnt(1)
	v_mfma_f32_32x32x16_bf16 v[112:127], v[158:161], v[224:227], v[112:127]
	v_mfma_f32_32x32x16_bf16 v[48:63], v[162:165], v[224:227], v[48:63]
	s_waitcnt lgkmcnt(0)
	v_mfma_f32_32x32x16_bf16 v[96:111], v[158:161], v[228:231], v[96:111]
	v_mfma_f32_32x32x16_bf16 v[32:47], v[162:165], v[228:231], v[32:47]
	ds_read_b128 v[224:227], v168 offset:9312
	ds_read_b128 v[228:231], v168 offset:13920
	s_waitcnt lgkmcnt(1)
	v_mfma_f32_32x32x16_bf16 v[80:95], v[158:161], v[224:227], v[80:95]
	v_mfma_f32_32x32x16_bf16 v[16:31], v[162:165], v[224:227], v[16:31]
	s_waitcnt lgkmcnt(0)
	v_mfma_f32_32x32x16_bf16 v[64:79], v[158:161], v[228:231], v[64:79]
	v_mfma_f32_32x32x16_bf16 v[0:15], v[162:165], v[228:231], v[0:15]
	s_setprio 0
	s_barrier
	global_load_dwordx4 v[158:161], v[128:129], off offset:3584
	global_load_dwordx4 v[162:165], v[132:133], off offset:3584
	s_waitcnt vmcnt(9)
	ds_write_b128 v195, v[198:201]
	s_waitcnt vmcnt(8)
	ds_write_b128 v196, v[202:205]
	ds_read_b128 v[198:201], v192 offset:36864
	ds_read_b128 v[202:205], v192 offset:41472
	ds_read_b128 v[224:227], v184
	ds_read_b128 v[228:231], v184 offset:4608
	s_setprio 1
	s_waitcnt lgkmcnt(1)
	v_mfma_f32_32x32x16_bf16 v[112:127], v[198:201], v[224:227], v[112:127]
	v_mfma_f32_32x32x16_bf16 v[48:63], v[202:205], v[224:227], v[48:63]
	s_waitcnt lgkmcnt(0)
	v_mfma_f32_32x32x16_bf16 v[96:111], v[198:201], v[228:231], v[96:111]
	v_mfma_f32_32x32x16_bf16 v[32:47], v[202:205], v[228:231], v[32:47]
	ds_read_b128 v[224:227], v184 offset:9216
	ds_read_b128 v[228:231], v184 offset:13824
	s_waitcnt vmcnt(7)
	ds_write_b128 v194, v[208:211]
	s_waitcnt vmcnt(6)
	ds_write_b128 v193, v[212:215]
	ds_read_b128 v[208:211], v192 offset:36896
	ds_read_b128 v[212:215], v192 offset:41504
	s_waitcnt lgkmcnt(5)
	v_mfma_f32_32x32x16_bf16 v[80:95], v[198:201], v[224:227], v[80:95]
	v_mfma_f32_32x32x16_bf16 v[16:31], v[202:205], v[224:227], v[16:31]
	ds_read_b128 v[224:227], v184 offset:32
	s_waitcnt lgkmcnt(5)
	v_mfma_f32_32x32x16_bf16 v[64:79], v[198:201], v[228:231], v[64:79]
	v_mfma_f32_32x32x16_bf16 v[0:15], v[202:205], v[228:231], v[0:15]
	ds_read_b128 v[228:231], v184 offset:4640
	s_setprio 0
	global_load_dwordx4 v[198:201], v[136:137], off offset:3584
	global_load_dwordx4 v[202:205], v[140:141], off offset:3584
	s_setprio 1
	s_waitcnt lgkmcnt(1)
	v_mfma_f32_32x32x16_bf16 v[112:127], v[208:211], v[224:227], v[112:127]
	v_mfma_f32_32x32x16_bf16 v[48:63], v[212:215], v[224:227], v[48:63]
	s_waitcnt lgkmcnt(0)
	v_mfma_f32_32x32x16_bf16 v[96:111], v[208:211], v[228:231], v[96:111]
	v_mfma_f32_32x32x16_bf16 v[32:47], v[212:215], v[228:231], v[32:47]
	ds_read_b128 v[224:227], v184 offset:9248
	ds_read_b128 v[228:231], v184 offset:13856
	s_waitcnt vmcnt(7)
	ds_write_b128 v177, v[178:181]
	s_waitcnt vmcnt(6)
	ds_write_b128 v176, v[216:219]
	ds_read_b128 v[178:181], v192 offset:36928
	ds_read_b128 v[216:219], v192 offset:41536
	s_waitcnt lgkmcnt(5)
	v_mfma_f32_32x32x16_bf16 v[80:95], v[208:211], v[224:227], v[80:95]
	v_mfma_f32_32x32x16_bf16 v[16:31], v[212:215], v[224:227], v[16:31]
	ds_read_b128 v[224:227], v184 offset:64
	s_waitcnt lgkmcnt(5)
	v_mfma_f32_32x32x16_bf16 v[64:79], v[208:211], v[228:231], v[64:79]
	v_mfma_f32_32x32x16_bf16 v[0:15], v[212:215], v[228:231], v[0:15]
	ds_read_b128 v[228:231], v184 offset:4672
	s_setprio 0
	global_load_dwordx4 v[208:211], v[144:145], off offset:3584
	global_load_dwordx4 v[212:215], v[148:149], off offset:3584
	s_setprio 1
	s_waitcnt lgkmcnt(1)
	v_mfma_f32_32x32x16_bf16 v[112:127], v[178:181], v[224:227], v[112:127]
	v_mfma_f32_32x32x16_bf16 v[48:63], v[216:219], v[224:227], v[48:63]
	s_waitcnt lgkmcnt(0)
	v_mfma_f32_32x32x16_bf16 v[96:111], v[178:181], v[228:231], v[96:111]
	v_mfma_f32_32x32x16_bf16 v[32:47], v[216:219], v[228:231], v[32:47]
	ds_read_b128 v[224:227], v184 offset:9280
	ds_read_b128 v[228:231], v184 offset:13888
	s_waitcnt vmcnt(7)
	ds_write_b128 v171, v[172:175]
	s_waitcnt vmcnt(6)
	ds_write_b128 v170, v[220:223]
	ds_read_b128 v[172:175], v192 offset:36960
	ds_read_b128 v[220:223], v192 offset:41568
	s_waitcnt lgkmcnt(5)
	v_mfma_f32_32x32x16_bf16 v[80:95], v[178:181], v[224:227], v[80:95]
	v_mfma_f32_32x32x16_bf16 v[16:31], v[216:219], v[224:227], v[16:31]
	ds_read_b128 v[224:227], v184 offset:96
	s_waitcnt lgkmcnt(5)
	v_mfma_f32_32x32x16_bf16 v[64:79], v[178:181], v[228:231], v[64:79]
	v_mfma_f32_32x32x16_bf16 v[0:15], v[216:219], v[228:231], v[0:15]
	ds_read_b128 v[228:231], v184 offset:4704
	s_setprio 0
	global_load_dwordx4 v[178:181], v[152:153], off offset:3584
	global_load_dwordx4 v[216:219], v[156:157], off offset:3584
	s_setprio 1
	s_waitcnt lgkmcnt(1)
	v_mfma_f32_32x32x16_bf16 v[112:127], v[172:175], v[224:227], v[112:127]
	v_mfma_f32_32x32x16_bf16 v[48:63], v[220:223], v[224:227], v[48:63]
	s_waitcnt lgkmcnt(0)
	v_mfma_f32_32x32x16_bf16 v[96:111], v[172:175], v[228:231], v[96:111]
	v_mfma_f32_32x32x16_bf16 v[32:47], v[220:223], v[228:231], v[32:47]
	ds_read_b128 v[224:227], v184 offset:9312
	ds_read_b128 v[228:231], v184 offset:13920
	s_waitcnt lgkmcnt(1)
	v_mfma_f32_32x32x16_bf16 v[80:95], v[172:175], v[224:227], v[80:95]
	v_mfma_f32_32x32x16_bf16 v[16:31], v[220:223], v[224:227], v[16:31]
	s_waitcnt lgkmcnt(0)
	v_mfma_f32_32x32x16_bf16 v[64:79], v[172:175], v[228:231], v[64:79]
	v_mfma_f32_32x32x16_bf16 v[0:15], v[220:223], v[228:231], v[0:15]
	s_setprio 0
	s_barrier
	global_load_dwordx4 v[172:175], v[128:129], off offset:3712
	global_load_dwordx4 v[220:223], v[132:133], off offset:3712
	s_waitcnt vmcnt(9)
	ds_write_b128 v191, v[158:161]
	s_waitcnt vmcnt(8)
	ds_write_b128 v191, v[162:165] offset:36864
	ds_read_b128 v[158:161], v169
	ds_read_b128 v[162:165], v169 offset:4608
	ds_read_b128 v[224:227], v168
	ds_read_b128 v[228:231], v168 offset:4608
	s_setprio 1
	s_waitcnt lgkmcnt(1)
	v_mfma_f32_32x32x16_bf16 v[112:127], v[158:161], v[224:227], v[112:127]
	v_mfma_f32_32x32x16_bf16 v[48:63], v[162:165], v[224:227], v[48:63]
	s_waitcnt lgkmcnt(0)
	v_mfma_f32_32x32x16_bf16 v[96:111], v[158:161], v[228:231], v[96:111]
	v_mfma_f32_32x32x16_bf16 v[32:47], v[162:165], v[228:231], v[32:47]
	ds_read_b128 v[224:227], v168 offset:9216
	ds_read_b128 v[228:231], v168 offset:13824
	s_waitcnt vmcnt(7)
	ds_write_b128 v191, v[198:201] offset:9216
	s_waitcnt vmcnt(6)
	ds_write_b128 v191, v[202:205] offset:46080
	ds_read_b128 v[198:201], v169 offset:32
	ds_read_b128 v[202:205], v169 offset:4640
	s_waitcnt lgkmcnt(5)
	v_mfma_f32_32x32x16_bf16 v[80:95], v[158:161], v[224:227], v[80:95]
	v_mfma_f32_32x32x16_bf16 v[16:31], v[162:165], v[224:227], v[16:31]
	ds_read_b128 v[224:227], v168 offset:32
	s_waitcnt lgkmcnt(5)
	v_mfma_f32_32x32x16_bf16 v[64:79], v[158:161], v[228:231], v[64:79]
	v_mfma_f32_32x32x16_bf16 v[0:15], v[162:165], v[228:231], v[0:15]
	ds_read_b128 v[228:231], v168 offset:4640
	s_setprio 0
	global_load_dwordx4 v[158:161], v[136:137], off offset:3712
	global_load_dwordx4 v[162:165], v[140:141], off offset:3712
	s_setprio 1
	s_waitcnt lgkmcnt(1)
	v_mfma_f32_32x32x16_bf16 v[112:127], v[198:201], v[224:227], v[112:127]
	v_mfma_f32_32x32x16_bf16 v[48:63], v[202:205], v[224:227], v[48:63]
	s_waitcnt lgkmcnt(0)
	v_mfma_f32_32x32x16_bf16 v[96:111], v[198:201], v[228:231], v[96:111]
	v_mfma_f32_32x32x16_bf16 v[32:47], v[202:205], v[228:231], v[32:47]
	ds_read_b128 v[224:227], v168 offset:9248
	ds_read_b128 v[228:231], v168 offset:13856
	s_waitcnt vmcnt(7)
	ds_write_b128 v191, v[208:211] offset:18432
	s_waitcnt vmcnt(6)
	ds_write_b128 v191, v[212:215] offset:55296
	ds_read_b128 v[208:211], v169 offset:64
	ds_read_b128 v[212:215], v169 offset:4672
	s_waitcnt lgkmcnt(5)
	v_mfma_f32_32x32x16_bf16 v[80:95], v[198:201], v[224:227], v[80:95]
	v_mfma_f32_32x32x16_bf16 v[16:31], v[202:205], v[224:227], v[16:31]
	ds_read_b128 v[224:227], v168 offset:64
	s_waitcnt lgkmcnt(5)
	v_mfma_f32_32x32x16_bf16 v[64:79], v[198:201], v[228:231], v[64:79]
	v_mfma_f32_32x32x16_bf16 v[0:15], v[202:205], v[228:231], v[0:15]
	ds_read_b128 v[228:231], v168 offset:4672
	s_setprio 0
	global_load_dwordx4 v[198:201], v[144:145], off offset:3712
	global_load_dwordx4 v[202:205], v[148:149], off offset:3712
	s_setprio 1
	s_waitcnt lgkmcnt(1)
	v_mfma_f32_32x32x16_bf16 v[112:127], v[208:211], v[224:227], v[112:127]
	v_mfma_f32_32x32x16_bf16 v[48:63], v[212:215], v[224:227], v[48:63]
	s_waitcnt lgkmcnt(0)
	v_mfma_f32_32x32x16_bf16 v[96:111], v[208:211], v[228:231], v[96:111]
	v_mfma_f32_32x32x16_bf16 v[32:47], v[212:215], v[228:231], v[32:47]
	ds_read_b128 v[224:227], v168 offset:9280
	ds_read_b128 v[228:231], v168 offset:13888
	s_waitcnt vmcnt(7)
	ds_write_b128 v191, v[178:181] offset:27648
	s_waitcnt vmcnt(6)
	ds_write_b128 v191, v[216:219] offset:64512
	ds_read_b128 v[178:181], v169 offset:96
	ds_read_b128 v[216:219], v169 offset:4704
	s_waitcnt lgkmcnt(5)
	v_mfma_f32_32x32x16_bf16 v[80:95], v[208:211], v[224:227], v[80:95]
	v_mfma_f32_32x32x16_bf16 v[16:31], v[212:215], v[224:227], v[16:31]
	ds_read_b128 v[224:227], v168 offset:96
	s_waitcnt lgkmcnt(5)
	v_mfma_f32_32x32x16_bf16 v[64:79], v[208:211], v[228:231], v[64:79]
	v_mfma_f32_32x32x16_bf16 v[0:15], v[212:215], v[228:231], v[0:15]
	ds_read_b128 v[228:231], v168 offset:4704
	s_setprio 0
	global_load_dwordx4 v[208:211], v[152:153], off offset:3712
	global_load_dwordx4 v[212:215], v[156:157], off offset:3712
	s_setprio 1
	s_waitcnt lgkmcnt(1)
	v_mfma_f32_32x32x16_bf16 v[112:127], v[178:181], v[224:227], v[112:127]
	v_mfma_f32_32x32x16_bf16 v[48:63], v[216:219], v[224:227], v[48:63]
	s_waitcnt lgkmcnt(0)
	v_mfma_f32_32x32x16_bf16 v[96:111], v[178:181], v[228:231], v[96:111]
	v_mfma_f32_32x32x16_bf16 v[32:47], v[216:219], v[228:231], v[32:47]
	ds_read_b128 v[224:227], v168 offset:9312
	ds_read_b128 v[228:231], v168 offset:13920
	s_waitcnt lgkmcnt(1)
	v_mfma_f32_32x32x16_bf16 v[80:95], v[178:181], v[224:227], v[80:95]
	v_mfma_f32_32x32x16_bf16 v[16:31], v[216:219], v[224:227], v[16:31]
	s_waitcnt lgkmcnt(0)
	v_mfma_f32_32x32x16_bf16 v[64:79], v[178:181], v[228:231], v[64:79]
	v_mfma_f32_32x32x16_bf16 v[0:15], v[216:219], v[228:231], v[0:15]
	s_setprio 0
	s_barrier
	global_load_dwordx4 v[178:181], v[128:129], off offset:3840
	global_load_dwordx4 v[216:219], v[132:133], off offset:3840
	s_waitcnt vmcnt(9)
	ds_write_b128 v195, v[172:175]
	s_waitcnt vmcnt(8)
	ds_write_b128 v196, v[220:223]
	ds_read_b128 v[172:175], v192 offset:36864
	ds_read_b128 v[220:223], v192 offset:41472
	ds_read_b128 v[224:227], v184
	ds_read_b128 v[228:231], v184 offset:4608
	s_setprio 1
	s_waitcnt lgkmcnt(1)
	v_mfma_f32_32x32x16_bf16 v[112:127], v[172:175], v[224:227], v[112:127]
	v_mfma_f32_32x32x16_bf16 v[48:63], v[220:223], v[224:227], v[48:63]
	s_waitcnt lgkmcnt(0)
	v_mfma_f32_32x32x16_bf16 v[96:111], v[172:175], v[228:231], v[96:111]
	v_mfma_f32_32x32x16_bf16 v[32:47], v[220:223], v[228:231], v[32:47]
	ds_read_b128 v[224:227], v184 offset:9216
	ds_read_b128 v[228:231], v184 offset:13824
	s_waitcnt vmcnt(7)
	ds_write_b128 v194, v[158:161]
	s_waitcnt vmcnt(6)
	ds_write_b128 v193, v[162:165]
	ds_read_b128 v[158:161], v192 offset:36896
	ds_read_b128 v[162:165], v192 offset:41504
	s_waitcnt lgkmcnt(5)
	v_mfma_f32_32x32x16_bf16 v[80:95], v[172:175], v[224:227], v[80:95]
	v_mfma_f32_32x32x16_bf16 v[16:31], v[220:223], v[224:227], v[16:31]
	ds_read_b128 v[224:227], v184 offset:32
	s_waitcnt lgkmcnt(5)
	v_mfma_f32_32x32x16_bf16 v[64:79], v[172:175], v[228:231], v[64:79]
	v_mfma_f32_32x32x16_bf16 v[0:15], v[220:223], v[228:231], v[0:15]
	ds_read_b128 v[228:231], v184 offset:4640
	s_setprio 0
	global_load_dwordx4 v[172:175], v[136:137], off offset:3840
	global_load_dwordx4 v[220:223], v[140:141], off offset:3840
	s_setprio 1
	s_waitcnt lgkmcnt(1)
	v_mfma_f32_32x32x16_bf16 v[112:127], v[158:161], v[224:227], v[112:127]
	v_mfma_f32_32x32x16_bf16 v[48:63], v[162:165], v[224:227], v[48:63]
	s_waitcnt lgkmcnt(0)
	v_mfma_f32_32x32x16_bf16 v[96:111], v[158:161], v[228:231], v[96:111]
	v_mfma_f32_32x32x16_bf16 v[32:47], v[162:165], v[228:231], v[32:47]
	ds_read_b128 v[224:227], v184 offset:9248
	ds_read_b128 v[228:231], v184 offset:13856
	s_waitcnt vmcnt(7)
	ds_write_b128 v177, v[198:201]
	s_waitcnt vmcnt(6)
	ds_write_b128 v176, v[202:205]
	ds_read_b128 v[198:201], v192 offset:36928
	ds_read_b128 v[202:205], v192 offset:41536
	s_waitcnt lgkmcnt(5)
	v_mfma_f32_32x32x16_bf16 v[80:95], v[158:161], v[224:227], v[80:95]
	v_mfma_f32_32x32x16_bf16 v[16:31], v[162:165], v[224:227], v[16:31]
	ds_read_b128 v[224:227], v184 offset:64
	s_waitcnt lgkmcnt(5)
	v_mfma_f32_32x32x16_bf16 v[64:79], v[158:161], v[228:231], v[64:79]
	v_mfma_f32_32x32x16_bf16 v[0:15], v[162:165], v[228:231], v[0:15]
	ds_read_b128 v[228:231], v184 offset:4672
	s_setprio 0
	global_load_dwordx4 v[158:161], v[144:145], off offset:3840
	global_load_dwordx4 v[162:165], v[148:149], off offset:3840
	s_setprio 1
	s_waitcnt lgkmcnt(1)
	v_mfma_f32_32x32x16_bf16 v[112:127], v[198:201], v[224:227], v[112:127]
	v_mfma_f32_32x32x16_bf16 v[48:63], v[202:205], v[224:227], v[48:63]
	s_waitcnt lgkmcnt(0)
	v_mfma_f32_32x32x16_bf16 v[96:111], v[198:201], v[228:231], v[96:111]
	v_mfma_f32_32x32x16_bf16 v[32:47], v[202:205], v[228:231], v[32:47]
	ds_read_b128 v[224:227], v184 offset:9280
	ds_read_b128 v[228:231], v184 offset:13888
	s_waitcnt vmcnt(7)
	ds_write_b128 v171, v[208:211]
	s_waitcnt vmcnt(6)
	ds_write_b128 v170, v[212:215]
	ds_read_b128 v[208:211], v192 offset:36960
	ds_read_b128 v[212:215], v192 offset:41568
	s_waitcnt lgkmcnt(5)
	v_mfma_f32_32x32x16_bf16 v[80:95], v[198:201], v[224:227], v[80:95]
	v_mfma_f32_32x32x16_bf16 v[16:31], v[202:205], v[224:227], v[16:31]
	ds_read_b128 v[224:227], v184 offset:96
	s_waitcnt lgkmcnt(5)
	v_mfma_f32_32x32x16_bf16 v[64:79], v[198:201], v[228:231], v[64:79]
	v_mfma_f32_32x32x16_bf16 v[0:15], v[202:205], v[228:231], v[0:15]
	ds_read_b128 v[228:231], v184 offset:4704
	s_setprio 0
	global_load_dwordx4 v[198:201], v[152:153], off offset:3840
	global_load_dwordx4 v[202:205], v[156:157], off offset:3840
	s_setprio 1
	s_waitcnt lgkmcnt(1)
	v_mfma_f32_32x32x16_bf16 v[112:127], v[208:211], v[224:227], v[112:127]
	v_mfma_f32_32x32x16_bf16 v[48:63], v[212:215], v[224:227], v[48:63]
	s_waitcnt lgkmcnt(0)
	v_mfma_f32_32x32x16_bf16 v[96:111], v[208:211], v[228:231], v[96:111]
	v_mfma_f32_32x32x16_bf16 v[32:47], v[212:215], v[228:231], v[32:47]
	ds_read_b128 v[224:227], v184 offset:9312
	ds_read_b128 v[228:231], v184 offset:13920
	s_waitcnt lgkmcnt(1)
	v_mfma_f32_32x32x16_bf16 v[80:95], v[208:211], v[224:227], v[80:95]
	v_mfma_f32_32x32x16_bf16 v[16:31], v[212:215], v[224:227], v[16:31]
	s_waitcnt lgkmcnt(0)
	v_mfma_f32_32x32x16_bf16 v[64:79], v[208:211], v[228:231], v[64:79]
	v_mfma_f32_32x32x16_bf16 v[0:15], v[212:215], v[228:231], v[0:15]
	s_setprio 0
	s_barrier
; template <bool trans>
; DI void gemm_core(const GTile& tl, const GTile& nx, bool has_next  , bool chain  , bool pre, u32x4 (&ra)[4], u32x4 (&rb)[4], char* smem, f32x16 (&acc)[2][4]) {
;     ...
;   const int nk = K / 64;
;   if (!pre) { G_LOAD(0); G_STORE(0); G_LOAD(1); }
;   for (int kt = 0; kt < nk; ++kt) {
;     __syncthreads();
;     G_COMPUTE(kt & 1, kt);
;   }
;   if (!has_next) __syncthreads();
	global_load_dwordx4 v[128:131], v[128:129], off offset:3968
	s_nop 0
	global_load_dwordx4 v[132:135], v[132:133], off offset:3968
	s_waitcnt vmcnt(9)
	ds_write_b128 v191, v[178:181]
	s_waitcnt vmcnt(8)
	ds_write_b128 v191, v[216:219] offset:36864
	ds_read_b128 v[178:181], v169
	ds_read_b128 v[208:211], v169 offset:4608
	ds_read_b128 v[212:215], v168
	ds_read_b128 v[216:219], v168 offset:4608
	s_setprio 1
	s_waitcnt lgkmcnt(1)
	v_mfma_f32_32x32x16_bf16 v[112:127], v[178:181], v[212:215], v[112:127]
	v_mfma_f32_32x32x16_bf16 v[48:63], v[208:211], v[212:215], v[48:63]
	s_waitcnt lgkmcnt(0)
	v_mfma_f32_32x32x16_bf16 v[96:111], v[178:181], v[216:219], v[96:111]
	v_mfma_f32_32x32x16_bf16 v[32:47], v[208:211], v[216:219], v[32:47]
	ds_read_b128 v[212:215], v168 offset:9216
	ds_read_b128 v[216:219], v168 offset:13824
	s_waitcnt lgkmcnt(1)
	v_mfma_f32_32x32x16_bf16 v[80:95], v[178:181], v[212:215], v[80:95]
	v_mfma_f32_32x32x16_bf16 v[16:31], v[208:211], v[212:215], v[16:31]
	s_waitcnt lgkmcnt(0)
	v_mfma_f32_32x32x16_bf16 v[64:79], v[178:181], v[216:219], v[64:79]
	v_mfma_f32_32x32x16_bf16 v[0:15], v[208:211], v[216:219], v[0:15]
	s_setprio 0
	global_load_dwordx4 v[136:139], v[136:137], off offset:3968
	s_nop 0
	global_load_dwordx4 v[140:143], v[140:141], off offset:3968
	s_waitcnt vmcnt(9)
	ds_write_b128 v191, v[172:175] offset:9216
	s_waitcnt vmcnt(8)
	ds_write_b128 v191, v[220:223] offset:46080
	ds_read_b128 v[172:175], v169 offset:32
	ds_read_b128 v[178:181], v169 offset:4640
	ds_read_b128 v[208:211], v168 offset:32
	ds_read_b128 v[212:215], v168 offset:4640
	s_setprio 1
	s_waitcnt lgkmcnt(1)
	v_mfma_f32_32x32x16_bf16 v[112:127], v[172:175], v[208:211], v[112:127]
	v_mfma_f32_32x32x16_bf16 v[48:63], v[178:181], v[208:211], v[48:63]
	s_waitcnt lgkmcnt(0)
	v_mfma_f32_32x32x16_bf16 v[96:111], v[172:175], v[212:215], v[96:111]
	v_mfma_f32_32x32x16_bf16 v[32:47], v[178:181], v[212:215], v[32:47]
	ds_read_b128 v[208:211], v168 offset:9248
	ds_read_b128 v[212:215], v168 offset:13856
	s_waitcnt lgkmcnt(1)
	v_mfma_f32_32x32x16_bf16 v[80:95], v[172:175], v[208:211], v[80:95]
	v_mfma_f32_32x32x16_bf16 v[16:31], v[178:181], v[208:211], v[16:31]
	s_waitcnt lgkmcnt(0)
	v_mfma_f32_32x32x16_bf16 v[64:79], v[172:175], v[212:215], v[64:79]
	v_mfma_f32_32x32x16_bf16 v[0:15], v[178:181], v[212:215], v[0:15]
	s_setprio 0
	global_load_dwordx4 v[144:147], v[144:145], off offset:3968
	s_nop 0
	global_load_dwordx4 v[148:151], v[148:149], off offset:3968
	s_waitcnt vmcnt(9)
	ds_write_b128 v191, v[158:161] offset:18432
	s_waitcnt vmcnt(8)
	ds_write_b128 v191, v[162:165] offset:55296
	ds_read_b128 v[158:161], v169 offset:64
	ds_read_b128 v[162:165], v169 offset:4672
	ds_read_b128 v[172:175], v168 offset:64
	ds_read_b128 v[178:181], v168 offset:4672
	s_setprio 1
	s_waitcnt lgkmcnt(1)
	v_mfma_f32_32x32x16_bf16 v[112:127], v[158:161], v[172:175], v[112:127]
	v_mfma_f32_32x32x16_bf16 v[48:63], v[162:165], v[172:175], v[48:63]
	s_waitcnt lgkmcnt(0)
	v_mfma_f32_32x32x16_bf16 v[96:111], v[158:161], v[178:181], v[96:111]
	v_mfma_f32_32x32x16_bf16 v[32:47], v[162:165], v[178:181], v[32:47]
	ds_read_b128 v[172:175], v168 offset:9280
	ds_read_b128 v[178:181], v168 offset:13888
	s_waitcnt lgkmcnt(1)
	v_mfma_f32_32x32x16_bf16 v[80:95], v[158:161], v[172:175], v[80:95]
	v_mfma_f32_32x32x16_bf16 v[16:31], v[162:165], v[172:175], v[16:31]
	s_waitcnt lgkmcnt(0)
	v_mfma_f32_32x32x16_bf16 v[64:79], v[158:161], v[178:181], v[64:79]
	v_mfma_f32_32x32x16_bf16 v[0:15], v[162:165], v[178:181], v[0:15]
	s_setprio 0
	global_load_dwordx4 v[152:155], v[152:153], off offset:3968
	s_nop 0
	global_load_dwordx4 v[156:159], v[156:157], off offset:3968
	s_waitcnt vmcnt(9)
	ds_write_b128 v191, v[198:201] offset:27648
	s_waitcnt vmcnt(8)
	ds_write_b128 v191, v[202:205] offset:64512
	ds_read_b128 v[160:163], v169 offset:96
	ds_read_b128 v[164:167], v169 offset:4704
	ds_read_b128 v[172:175], v168 offset:96
	ds_read_b128 v[178:181], v168 offset:4704
	s_setprio 1
	s_waitcnt lgkmcnt(1)
	v_mfma_f32_32x32x16_bf16 v[112:127], v[160:163], v[172:175], v[112:127]
	v_mfma_f32_32x32x16_bf16 v[48:63], v[164:167], v[172:175], v[48:63]
	s_waitcnt lgkmcnt(0)
	v_mfma_f32_32x32x16_bf16 v[96:111], v[160:163], v[178:181], v[96:111]
	v_mfma_f32_32x32x16_bf16 v[32:47], v[164:167], v[178:181], v[32:47]
	ds_read_b128 v[172:175], v168 offset:9312
	ds_read_b128 v[178:181], v168 offset:13920
	s_waitcnt lgkmcnt(1)
	v_mfma_f32_32x32x16_bf16 v[80:95], v[160:163], v[172:175], v[80:95]
	v_mfma_f32_32x32x16_bf16 v[16:31], v[164:167], v[172:175], v[16:31]
	s_waitcnt lgkmcnt(0)
	v_mfma_f32_32x32x16_bf16 v[64:79], v[160:163], v[178:181], v[64:79]
	v_mfma_f32_32x32x16_bf16 v[0:15], v[164:167], v[178:181], v[0:15]
	s_setprio 0
	s_and_b64 vcc, exec, s[12:13]
	s_barrier
	s_waitcnt vmcnt(7)
	ds_write_b128 v195, v[128:131]
	s_waitcnt vmcnt(6)
	ds_write_b128 v196, v[132:135]
	s_cbranch_vccnz .LBB0_751
	global_load_dwordx4 v[128:131], v[188:189], off
	global_load_dwordx4 v[132:135], v[186:187], off

; DI int otid() { int t = threadIdx.x; asm volatile("" : "+v"(t)); return t; }
; template <bool trans>
; DI void gemm_core(const GTile& tl, const GTile& nx, bool has_next  , bool chain  , bool pre, u32x4 (&ra)[4], u32x4 (&rb)[4], char* smem, f32x16 (&acc)[2][4]) {
;     ...
;   const int tid = otid(), lane = tid & 63, w = __builtin_amdgcn_readfirstlane(tid >> 6), wm = w >> 2, wn = w & 3, l32 = lane & 31, g = lane >> 5;
; #pragma unroll
;   for (int a = 0; a < 2; ++a)
; #pragma unroll
;     for (int b = 0; b < 4; ++b)
; #pragma unroll
;       for (int r = 0; r < 16; ++r) acc[a][b][r] = 0.f;
;   const int lrow = tid >> 3, kc = tid & 7;
;   const unsigned aoff = (unsigned)(lrow * lda + kc * 8) * 2u, boff = (unsigned)(lrow * ldb + kc * 8) * 2u;
;   const char* ag = (const char*)(A + (size_t)m0 * lda);
;   const char* bg = (const char*)(Bt + (size_t)n0 * ldb);
;   const unsigned aoffn = (unsigned)(lrow * nx.lda + kc * 8) * 2u, boffn = (unsigned)(lrow * nx.ldb + kc * 8) * 2u;
;   const char* agn = (const char*)(nx.A + (size_t)nx.m0 * nx.lda);
;   const char* bgn = (const char*)(nx.Bt + (size_t)nx.n0 * nx.ldb);
;     ...
;   const int nk = K / 64;
;   if (!pre) { G_LOAD(0); G_STORE(0); G_LOAD(1); }
;   for (int kt = 0; kt < nk; ++kt) {
;     __syncthreads();
;     G_COMPUTE(kt & 1, kt);
;   }
.LBB0_882:
	v_lshl_add_u64 v[190:191], s[2:3], 0, v[192:193]
	v_lshl_add_u64 v[188:189], s[16:17], 0, v[192:193]
	s_waitcnt lgkmcnt(0)
	s_barrier
	global_load_dwordx4 v[218:221], v[190:191], off offset:256
	global_load_dwordx4 v[222:225], v[188:189], off offset:256
	s_lshr_b32 s3, s33, 1
	s_and_b32 s2, s33, 0xc0
	v_and_b32_e32 v10, 31, v8
	s_and_b32 s3, s3, 0xfffff80
	v_or_b32_e32 v12, s3, v10
	v_or_b32_e32 v10, s2, v10
	v_add3_u32 v215, 16, v11, v9
	v_lshrrev_b32_e32 v8, 1, v8
	v_mul_u32_u24_e32 v208, 0x90, v10
	v_and_b32_e32 v242, 16, v8
	v_add_u32_e32 v209, 0x12000, v215
	v_mul_lo_u32 v205, v12, s54
	v_add3_u32 v204, 16, v208, v242
	v_add_u32_e32 v210, 0x1b000, v215
	ds_write_b128 v209, v[0:3]
	s_waitcnt vmcnt(5)
	ds_write_b128 v210, v[4:7]
	v_add3_u32 v192, 16, v205, v242
	ds_read_b128 v[0:3], v204 offset:36864
	ds_read_b128 v[4:7], v204 offset:41472
	ds_read_b128 v[8:11], v192
	ds_read_b128 v[12:15], v192 offset:4608
	v_lshl_add_u64 v[184:185], v[190:191], 0, s[14:15]
	v_lshl_add_u64 v[186:187], v[188:189], 0, s[14:15]
	v_lshl_add_u64 v[194:195], v[190:191], 0, s[12:13]
	v_lshl_add_u64 v[196:197], v[188:189], 0, s[12:13]
	s_setprio 1
	s_waitcnt lgkmcnt(1)
	v_mfma_f32_32x32x16_bf16 v[112:127], v[8:11], v[0:3], 0
	v_mfma_f32_32x32x16_bf16 v[48:63], v[8:11], v[4:7], 0
	s_waitcnt lgkmcnt(0)
	v_mfma_f32_32x32x16_bf16 v[96:111], v[12:15], v[0:3], 0
	v_mfma_f32_32x32x16_bf16 v[32:47], v[12:15], v[4:7], 0
	ds_read_b128 v[8:11], v192 offset:9216
	ds_read_b128 v[12:15], v192 offset:13824
	s_waitcnt lgkmcnt(1)
	v_mfma_f32_32x32x16_bf16 v[80:95], v[8:11], v[0:3], 0
	v_mfma_f32_32x32x16_bf16 v[16:31], v[8:11], v[4:7], 0
	s_waitcnt lgkmcnt(0)
	v_mfma_f32_32x32x16_bf16 v[64:79], v[12:15], v[0:3], 0
	v_mfma_f32_32x32x16_bf16 v[0:15], v[12:15], v[4:7], 0
	s_setprio 0
	global_load_dwordx4 v[226:229], v[194:195], off offset:256
	global_load_dwordx4 v[230:233], v[196:197], off offset:256
	v_add_u32_e32 v212, 0x14400, v215
	v_add_u32_e32 v211, 0x1d400, v215
	ds_write_b128 v212, v[176:179]
	s_waitcnt vmcnt(6)
	ds_write_b128 v211, v[180:183]
	ds_read_b128 v[176:179], v204 offset:36896
	ds_read_b128 v[180:183], v204 offset:41504
	ds_read_b128 v[198:201], v192 offset:32
	ds_read_b128 v[234:237], v192 offset:4640
	s_setprio 1
	s_waitcnt lgkmcnt(1)
	v_mfma_f32_32x32x16_bf16 v[112:127], v[198:201], v[176:179], v[112:127]
	v_mfma_f32_32x32x16_bf16 v[48:63], v[198:201], v[180:183], v[48:63]
	s_waitcnt lgkmcnt(0)
	v_mfma_f32_32x32x16_bf16 v[96:111], v[234:237], v[176:179], v[96:111]
	v_mfma_f32_32x32x16_bf16 v[32:47], v[234:237], v[180:183], v[32:47]
	ds_read_b128 v[198:201], v192 offset:9248
	ds_read_b128 v[234:237], v192 offset:13856
	s_waitcnt lgkmcnt(1)
	v_mfma_f32_32x32x16_bf16 v[80:95], v[198:201], v[176:179], v[80:95]
	v_mfma_f32_32x32x16_bf16 v[16:31], v[198:201], v[180:183], v[16:31]
	s_waitcnt lgkmcnt(0)
	v_mfma_f32_32x32x16_bf16 v[64:79], v[234:237], v[176:179], v[64:79]
	v_mfma_f32_32x32x16_bf16 v[0:15], v[234:237], v[180:183], v[0:15]
	s_setprio 0
	global_load_dwordx4 v[176:179], v[184:185], off offset:256
	global_load_dwordx4 v[180:183], v[186:187], off offset:256
	v_add_u32_e32 v214, 0x16800, v215
	v_add_u32_e32 v213, 0x1f800, v215
	ds_write_b128 v214, v[168:171]
	s_waitcnt vmcnt(7)
	ds_write_b128 v213, v[172:175]
	ds_read_b128 v[168:171], v204 offset:36928
	ds_read_b128 v[172:175], v204 offset:41536
	ds_read_b128 v[198:201], v192 offset:64
	ds_read_b128 v[234:237], v192 offset:4672
	s_setprio 1
	s_waitcnt lgkmcnt(1)
	v_mfma_f32_32x32x16_bf16 v[112:127], v[198:201], v[168:171], v[112:127]
	v_mfma_f32_32x32x16_bf16 v[48:63], v[198:201], v[172:175], v[48:63]
	s_waitcnt lgkmcnt(0)
	v_mfma_f32_32x32x16_bf16 v[96:111], v[234:237], v[168:171], v[96:111]
	v_mfma_f32_32x32x16_bf16 v[32:47], v[234:237], v[172:175], v[32:47]
	ds_read_b128 v[198:201], v192 offset:9280
	ds_read_b128 v[234:237], v192 offset:13888
	s_waitcnt lgkmcnt(1)
	v_mfma_f32_32x32x16_bf16 v[80:95], v[198:201], v[168:171], v[80:95]
	v_mfma_f32_32x32x16_bf16 v[16:31], v[198:201], v[172:175], v[16:31]
	s_waitcnt lgkmcnt(0)
	v_mfma_f32_32x32x16_bf16 v[64:79], v[234:237], v[168:171], v[64:79]
	v_mfma_f32_32x32x16_bf16 v[0:15], v[234:237], v[172:175], v[0:15]
	s_setprio 0
	v_add_co_u32_e32 v198, vcc, s53, v190
	v_add_u32_e32 v217, 0x18c00, v215
	s_nop 0
	v_addc_co_u32_e32 v199, vcc, 0, v191, vcc
	v_add_co_u32_e32 v200, vcc, s53, v188
	v_add_u32_e32 v216, 0x21c00, v215
	s_nop 0
	v_addc_co_u32_e32 v201, vcc, 0, v189, vcc
	global_load_dwordx4 v[168:171], v[198:199], off offset:256
	global_load_dwordx4 v[172:175], v[200:201], off offset:256
	ds_write_b128 v217, v[160:163]
	s_waitcnt vmcnt(8)
	ds_write_b128 v216, v[164:167]
	ds_read_b128 v[160:163], v204 offset:36960
	ds_read_b128 v[164:167], v204 offset:41568
	ds_read_b128 v[234:237], v192 offset:96
	ds_read_b128 v[238:241], v192 offset:4704
	s_setprio 1
	s_waitcnt lgkmcnt(1)
	v_mfma_f32_32x32x16_bf16 v[112:127], v[234:237], v[160:163], v[112:127]
	v_mfma_f32_32x32x16_bf16 v[48:63], v[234:237], v[164:167], v[48:63]
	s_waitcnt lgkmcnt(0)
	v_mfma_f32_32x32x16_bf16 v[96:111], v[238:241], v[160:163], v[96:111]
	v_mfma_f32_32x32x16_bf16 v[32:47], v[238:241], v[164:167], v[32:47]
	ds_read_b128 v[234:237], v192 offset:9312
	ds_read_b128 v[238:241], v192 offset:13920
	s_waitcnt lgkmcnt(1)
	v_mfma_f32_32x32x16_bf16 v[80:95], v[234:237], v[160:163], v[80:95]
	v_mfma_f32_32x32x16_bf16 v[16:31], v[234:237], v[164:167], v[16:31]
	s_waitcnt lgkmcnt(0)
	v_mfma_f32_32x32x16_bf16 v[64:79], v[238:241], v[160:163], v[64:79]
	v_mfma_f32_32x32x16_bf16 v[0:15], v[238:241], v[164:167], v[0:15]
	s_setprio 0
	s_barrier
; template <bool trans>
; DI void gemm_core(const GTile& tl, const GTile& nx, bool has_next  , bool chain  , bool pre, u32x4 (&ra)[4], u32x4 (&rb)[4], char* smem, f32x16 (&acc)[2][4]) {
;     ...
;   const int nk = K / 64;
;   if (!pre) { G_LOAD(0); G_STORE(0); G_LOAD(1); }
;   for (int kt = 0; kt < nk; ++kt) {
;     __syncthreads();
;     G_COMPUTE(kt & 1, kt);
;   }
	global_load_dwordx4 v[160:163], v[190:191], off offset:384
	global_load_dwordx4 v[164:167], v[188:189], off offset:384
	s_add_i32 s2, 16, 0x12000
	v_add3_u32 v205, s2, v205, v242
	s_add_i32 s2, 16, 0x1b000
	v_add3_u32 v208, s2, v208, v242
	s_waitcnt vmcnt(9)
	ds_write_b128 v215, v[218:221]
	s_waitcnt vmcnt(8)
	ds_write_b128 v215, v[222:225] offset:36864
	ds_read_b128 v[218:221], v208
	ds_read_b128 v[222:225], v208 offset:4608
	ds_read_b128 v[234:237], v205
	ds_read_b128 v[238:241], v205 offset:4608
	s_setprio 1
	s_waitcnt lgkmcnt(1)
	v_mfma_f32_32x32x16_bf16 v[112:127], v[234:237], v[218:221], v[112:127]
	v_mfma_f32_32x32x16_bf16 v[48:63], v[234:237], v[222:225], v[48:63]
	s_waitcnt lgkmcnt(0)
	v_mfma_f32_32x32x16_bf16 v[96:111], v[238:241], v[218:221], v[96:111]
	v_mfma_f32_32x32x16_bf16 v[32:47], v[238:241], v[222:225], v[32:47]
	ds_read_b128 v[234:237], v205 offset:9216
	ds_read_b128 v[238:241], v205 offset:13824
	s_waitcnt lgkmcnt(1)
	v_mfma_f32_32x32x16_bf16 v[80:95], v[234:237], v[218:221], v[80:95]
	v_mfma_f32_32x32x16_bf16 v[16:31], v[234:237], v[222:225], v[16:31]
	s_waitcnt lgkmcnt(0)
	v_mfma_f32_32x32x16_bf16 v[64:79], v[238:241], v[218:221], v[64:79]
	v_mfma_f32_32x32x16_bf16 v[0:15], v[238:241], v[222:225], v[0:15]
	s_setprio 0
	global_load_dwordx4 v[218:221], v[194:195], off offset:384
	global_load_dwordx4 v[222:225], v[196:197], off offset:384
	s_waitcnt vmcnt(9)
	ds_write_b128 v215, v[226:229] offset:9216
	s_waitcnt vmcnt(8)
	ds_write_b128 v215, v[230:233] offset:46080
	ds_read_b128 v[226:229], v208 offset:32
	ds_read_b128 v[230:233], v208 offset:4640
	ds_read_b128 v[234:237], v205 offset:32
	ds_read_b128 v[238:241], v205 offset:4640
	s_setprio 1
	s_waitcnt lgkmcnt(1)
	v_mfma_f32_32x32x16_bf16 v[112:127], v[234:237], v[226:229], v[112:127]
	v_mfma_f32_32x32x16_bf16 v[48:63], v[234:237], v[230:233], v[48:63]
	s_waitcnt lgkmcnt(0)
	v_mfma_f32_32x32x16_bf16 v[96:111], v[238:241], v[226:229], v[96:111]
	v_mfma_f32_32x32x16_bf16 v[32:47], v[238:241], v[230:233], v[32:47]
	ds_read_b128 v[234:237], v205 offset:9248
	ds_read_b128 v[238:241], v205 offset:13856
	s_waitcnt lgkmcnt(1)
	v_mfma_f32_32x32x16_bf16 v[80:95], v[234:237], v[226:229], v[80:95]
	v_mfma_f32_32x32x16_bf16 v[16:31], v[234:237], v[230:233], v[16:31]
	s_waitcnt lgkmcnt(0)
	v_mfma_f32_32x32x16_bf16 v[64:79], v[238:241], v[226:229], v[64:79]
	v_mfma_f32_32x32x16_bf16 v[0:15], v[238:241], v[230:233], v[0:15]
	s_setprio 0
	global_load_dwordx4 v[226:229], v[184:185], off offset:384
	global_load_dwordx4 v[230:233], v[186:187], off offset:384
	s_waitcnt vmcnt(9)
	ds_write_b128 v215, v[176:179] offset:18432
	s_waitcnt vmcnt(8)
	ds_write_b128 v215, v[180:183] offset:55296
	ds_read_b128 v[176:179], v208 offset:64
	ds_read_b128 v[180:183], v208 offset:4672
	ds_read_b128 v[234:237], v205 offset:64
	ds_read_b128 v[238:241], v205 offset:4672
	s_setprio 1
	s_waitcnt lgkmcnt(1)
	v_mfma_f32_32x32x16_bf16 v[112:127], v[234:237], v[176:179], v[112:127]
	v_mfma_f32_32x32x16_bf16 v[48:63], v[234:237], v[180:183], v[48:63]
	s_waitcnt lgkmcnt(0)
	v_mfma_f32_32x32x16_bf16 v[96:111], v[238:241], v[176:179], v[96:111]
	v_mfma_f32_32x32x16_bf16 v[32:47], v[238:241], v[180:183], v[32:47]
	ds_read_b128 v[234:237], v205 offset:9280
	ds_read_b128 v[238:241], v205 offset:13888
	s_waitcnt lgkmcnt(1)
	v_mfma_f32_32x32x16_bf16 v[80:95], v[234:237], v[176:179], v[80:95]
	v_mfma_f32_32x32x16_bf16 v[16:31], v[234:237], v[180:183], v[16:31]
	s_waitcnt lgkmcnt(0)
	v_mfma_f32_32x32x16_bf16 v[64:79], v[238:241], v[176:179], v[64:79]
	v_mfma_f32_32x32x16_bf16 v[0:15], v[238:241], v[180:183], v[0:15]
	s_setprio 0
	global_load_dwordx4 v[176:179], v[198:199], off offset:384
	global_load_dwordx4 v[180:183], v[200:201], off offset:384
	s_waitcnt vmcnt(9)
	ds_write_b128 v215, v[168:171] offset:27648
	s_waitcnt vmcnt(8)
	ds_write_b128 v215, v[172:175] offset:64512
	ds_read_b128 v[168:171], v208 offset:96
	ds_read_b128 v[172:175], v208 offset:4704
	ds_read_b128 v[234:237], v205 offset:96
	ds_read_b128 v[238:241], v205 offset:4704
	s_setprio 1
	s_waitcnt lgkmcnt(1)
	v_mfma_f32_32x32x16_bf16 v[112:127], v[234:237], v[168:171], v[112:127]
	v_mfma_f32_32x32x16_bf16 v[48:63], v[234:237], v[172:175], v[48:63]
	s_waitcnt lgkmcnt(0)
	v_mfma_f32_32x32x16_bf16 v[96:111], v[238:241], v[168:171], v[96:111]
	v_mfma_f32_32x32x16_bf16 v[32:47], v[238:241], v[172:175], v[32:47]
	ds_read_b128 v[234:237], v205 offset:9312
	ds_read_b128 v[238:241], v205 offset:13920
	s_waitcnt lgkmcnt(1)
	v_mfma_f32_32x32x16_bf16 v[80:95], v[234:237], v[168:171], v[80:95]
	v_mfma_f32_32x32x16_bf16 v[16:31], v[234:237], v[172:175], v[16:31]
	s_waitcnt lgkmcnt(0)
	v_mfma_f32_32x32x16_bf16 v[64:79], v[238:241], v[168:171], v[64:79]
	v_mfma_f32_32x32x16_bf16 v[0:15], v[238:241], v[172:175], v[0:15]
	s_setprio 0
	s_barrier
	global_load_dwordx4 v[168:171], v[190:191], off offset:512
	global_load_dwordx4 v[172:175], v[188:189], off offset:512
	s_waitcnt vmcnt(9)
	ds_write_b128 v209, v[160:163]
	s_waitcnt vmcnt(8)
	ds_write_b128 v210, v[164:167]
	ds_read_b128 v[160:163], v204 offset:36864
	ds_read_b128 v[164:167], v204 offset:41472
	ds_read_b128 v[234:237], v192
	ds_read_b128 v[238:241], v192 offset:4608
	s_setprio 1
	s_waitcnt lgkmcnt(1)
	v_mfma_f32_32x32x16_bf16 v[112:127], v[234:237], v[160:163], v[112:127]
	v_mfma_f32_32x32x16_bf16 v[48:63], v[234:237], v[164:167], v[48:63]
	s_waitcnt lgkmcnt(0)
	v_mfma_f32_32x32x16_bf16 v[96:111], v[238:241], v[160:163], v[96:111]
	v_mfma_f32_32x32x16_bf16 v[32:47], v[238:241], v[164:167], v[32:47]
	ds_read_b128 v[234:237], v192 offset:9216
	ds_read_b128 v[238:241], v192 offset:13824
	s_waitcnt vmcnt(7)
	ds_write_b128 v212, v[218:221]
	s_waitcnt vmcnt(6)
	ds_write_b128 v211, v[222:225]
	ds_read_b128 v[218:221], v204 offset:36896
	ds_read_b128 v[222:225], v204 offset:41504
	s_waitcnt lgkmcnt(5)
	v_mfma_f32_32x32x16_bf16 v[80:95], v[234:237], v[160:163], v[80:95]
	v_mfma_f32_32x32x16_bf16 v[16:31], v[234:237], v[164:167], v[16:31]
	ds_read_b128 v[234:237], v192 offset:32
	s_waitcnt lgkmcnt(5)
	v_mfma_f32_32x32x16_bf16 v[64:79], v[238:241], v[160:163], v[64:79]
	v_mfma_f32_32x32x16_bf16 v[0:15], v[238:241], v[164:167], v[0:15]
	ds_read_b128 v[238:241], v192 offset:4640
	s_setprio 0
	global_load_dwordx4 v[160:163], v[194:195], off offset:512
	global_load_dwordx4 v[164:167], v[196:197], off offset:512
	s_setprio 1
	s_waitcnt lgkmcnt(1)
	v_mfma_f32_32x32x16_bf16 v[112:127], v[234:237], v[218:221], v[112:127]
	v_mfma_f32_32x32x16_bf16 v[48:63], v[234:237], v[222:225], v[48:63]
	s_waitcnt lgkmcnt(0)
	v_mfma_f32_32x32x16_bf16 v[96:111], v[238:241], v[218:221], v[96:111]
	v_mfma_f32_32x32x16_bf16 v[32:47], v[238:241], v[222:225], v[32:47]
	ds_read_b128 v[234:237], v192 offset:9248
	ds_read_b128 v[238:241], v192 offset:13856
	s_waitcnt vmcnt(7)
	ds_write_b128 v214, v[226:229]
	s_waitcnt vmcnt(6)
	ds_write_b128 v213, v[230:233]
	ds_read_b128 v[226:229], v204 offset:36928
	ds_read_b128 v[230:233], v204 offset:41536
	s_waitcnt lgkmcnt(5)
	v_mfma_f32_32x32x16_bf16 v[80:95], v[234:237], v[218:221], v[80:95]
	v_mfma_f32_32x32x16_bf16 v[16:31], v[234:237], v[222:225], v[16:31]
	ds_read_b128 v[234:237], v192 offset:64
	s_waitcnt lgkmcnt(5)
	v_mfma_f32_32x32x16_bf16 v[64:79], v[238:241], v[218:221], v[64:79]
	v_mfma_f32_32x32x16_bf16 v[0:15], v[238:241], v[222:225], v[0:15]
	ds_read_b128 v[238:241], v192 offset:4672
	s_setprio 0
	global_load_dwordx4 v[218:221], v[184:185], off offset:512
	global_load_dwordx4 v[222:225], v[186:187], off offset:512
	s_setprio 1
	s_waitcnt lgkmcnt(1)
	v_mfma_f32_32x32x16_bf16 v[112:127], v[234:237], v[226:229], v[112:127]
	v_mfma_f32_32x32x16_bf16 v[48:63], v[234:237], v[230:233], v[48:63]
	s_waitcnt lgkmcnt(0)
	v_mfma_f32_32x32x16_bf16 v[96:111], v[238:241], v[226:229], v[96:111]
	v_mfma_f32_32x32x16_bf16 v[32:47], v[238:241], v[230:233], v[32:47]
	ds_read_b128 v[234:237], v192 offset:9280
	ds_read_b128 v[238:241], v192 offset:13888
	s_waitcnt vmcnt(7)
	ds_write_b128 v217, v[176:179]
	s_waitcnt vmcnt(6)
	ds_write_b128 v216, v[180:183]
	ds_read_b128 v[176:179], v204 offset:36960
	ds_read_b128 v[180:183], v204 offset:41568
	s_waitcnt lgkmcnt(5)
	v_mfma_f32_32x32x16_bf16 v[80:95], v[234:237], v[226:229], v[80:95]
	v_mfma_f32_32x32x16_bf16 v[16:31], v[234:237], v[230:233], v[16:31]
	ds_read_b128 v[234:237], v192 offset:96
	s_waitcnt lgkmcnt(5)
	v_mfma_f32_32x32x16_bf16 v[64:79], v[238:241], v[226:229], v[64:79]
	v_mfma_f32_32x32x16_bf16 v[0:15], v[238:241], v[230:233], v[0:15]
	ds_read_b128 v[238:241], v192 offset:4704
	s_setprio 0
	global_load_dwordx4 v[226:229], v[198:199], off offset:512
	global_load_dwordx4 v[230:233], v[200:201], off offset:512
	s_setprio 1
	s_waitcnt lgkmcnt(1)
	v_mfma_f32_32x32x16_bf16 v[112:127], v[234:237], v[176:179], v[112:127]
	v_mfma_f32_32x32x16_bf16 v[48:63], v[234:237], v[180:183], v[48:63]
	s_waitcnt lgkmcnt(0)
	v_mfma_f32_32x32x16_bf16 v[96:111], v[238:241], v[176:179], v[96:111]
	v_mfma_f32_32x32x16_bf16 v[32:47], v[238:241], v[180:183], v[32:47]
	ds_read_b128 v[234:237], v192 offset:9312
	ds_read_b128 v[238:241], v192 offset:13920
	s_waitcnt lgkmcnt(1)
	v_mfma_f32_32x32x16_bf16 v[80:95], v[234:237], v[176:179], v[80:95]
	v_mfma_f32_32x32x16_bf16 v[16:31], v[234:237], v[180:183], v[16:31]
	s_waitcnt lgkmcnt(0)
	v_mfma_f32_32x32x16_bf16 v[64:79], v[238:241], v[176:179], v[64:79]
	v_mfma_f32_32x32x16_bf16 v[0:15], v[238:241], v[180:183], v[0:15]
	s_setprio 0
	s_barrier
	global_load_dwordx4 v[176:179], v[190:191], off offset:640
	global_load_dwordx4 v[180:183], v[188:189], off offset:640
	s_waitcnt vmcnt(9)
	ds_write_b128 v215, v[168:171]
	s_waitcnt vmcnt(8)
	ds_write_b128 v215, v[172:175] offset:36864
	ds_read_b128 v[168:171], v208
	ds_read_b128 v[172:175], v208 offset:4608
	ds_read_b128 v[234:237], v205
	ds_read_b128 v[238:241], v205 offset:4608
	s_setprio 1
	s_waitcnt lgkmcnt(1)
	v_mfma_f32_32x32x16_bf16 v[112:127], v[234:237], v[168:171], v[112:127]
	v_mfma_f32_32x32x16_bf16 v[48:63], v[234:237], v[172:175], v[48:63]
	s_waitcnt lgkmcnt(0)
	v_mfma_f32_32x32x16_bf16 v[96:111], v[238:241], v[168:171], v[96:111]
	v_mfma_f32_32x32x16_bf16 v[32:47], v[238:241], v[172:175], v[32:47]
	ds_read_b128 v[234:237], v205 offset:9216
	ds_read_b128 v[238:241], v205 offset:13824
	s_waitcnt vmcnt(7)
	ds_write_b128 v215, v[160:163] offset:9216
	s_waitcnt vmcnt(6)
	ds_write_b128 v215, v[164:167] offset:46080
	ds_read_b128 v[160:163], v208 offset:32
	ds_read_b128 v[164:167], v208 offset:4640
	s_waitcnt lgkmcnt(5)
	v_mfma_f32_32x32x16_bf16 v[80:95], v[234:237], v[168:171], v[80:95]
	v_mfma_f32_32x32x16_bf16 v[16:31], v[234:237], v[172:175], v[16:31]
	ds_read_b128 v[234:237], v205 offset:32
	s_waitcnt lgkmcnt(5)
	v_mfma_f32_32x32x16_bf16 v[64:79], v[238:241], v[168:171], v[64:79]
	v_mfma_f32_32x32x16_bf16 v[0:15], v[238:241], v[172:175], v[0:15]
	ds_read_b128 v[238:241], v205 offset:4640
	s_setprio 0
	global_load_dwordx4 v[168:171], v[194:195], off offset:640
	global_load_dwordx4 v[172:175], v[196:197], off offset:640
	s_setprio 1
	s_waitcnt lgkmcnt(1)
	v_mfma_f32_32x32x16_bf16 v[112:127], v[234:237], v[160:163], v[112:127]
	v_mfma_f32_32x32x16_bf16 v[48:63], v[234:237], v[164:167], v[48:63]
	s_waitcnt lgkmcnt(0)
	v_mfma_f32_32x32x16_bf16 v[96:111], v[238:241], v[160:163], v[96:111]
	v_mfma_f32_32x32x16_bf16 v[32:47], v[238:241], v[164:167], v[32:47]
	ds_read_b128 v[234:237], v205 offset:9248
	ds_read_b128 v[238:241], v205 offset:13856
	s_waitcnt vmcnt(7)
	ds_write_b128 v215, v[218:221] offset:18432
	s_waitcnt vmcnt(6)
	ds_write_b128 v215, v[222:225] offset:55296
	ds_read_b128 v[218:221], v208 offset:64
	ds_read_b128 v[222:225], v208 offset:4672
	s_waitcnt lgkmcnt(5)
	v_mfma_f32_32x32x16_bf16 v[80:95], v[234:237], v[160:163], v[80:95]
	v_mfma_f32_32x32x16_bf16 v[16:31], v[234:237], v[164:167], v[16:31]
	ds_read_b128 v[234:237], v205 offset:64
	s_waitcnt lgkmcnt(5)
	v_mfma_f32_32x32x16_bf16 v[64:79], v[238:241], v[160:163], v[64:79]
	v_mfma_f32_32x32x16_bf16 v[0:15], v[238:241], v[164:167], v[0:15]
	ds_read_b128 v[238:241], v205 offset:4672
	s_setprio 0
	global_load_dwordx4 v[160:163], v[184:185], off offset:640
	global_load_dwordx4 v[164:167], v[186:187], off offset:640
	s_setprio 1
	s_waitcnt lgkmcnt(1)
	v_mfma_f32_32x32x16_bf16 v[112:127], v[234:237], v[218:221], v[112:127]
	v_mfma_f32_32x32x16_bf16 v[48:63], v[234:237], v[222:225], v[48:63]
	s_waitcnt lgkmcnt(0)
	v_mfma_f32_32x32x16_bf16 v[96:111], v[238:241], v[218:221], v[96:111]
	v_mfma_f32_32x32x16_bf16 v[32:47], v[238:241], v[222:225], v[32:47]
	ds_read_b128 v[234:237], v205 offset:9280
	ds_read_b128 v[238:241], v205 offset:13888
	s_waitcnt vmcnt(7)
	ds_write_b128 v215, v[226:229] offset:27648
	s_waitcnt vmcnt(6)
	ds_write_b128 v215, v[230:233] offset:64512
	ds_read_b128 v[226:229], v208 offset:96
	ds_read_b128 v[230:233], v208 offset:4704
	s_waitcnt lgkmcnt(5)
	v_mfma_f32_32x32x16_bf16 v[80:95], v[234:237], v[218:221], v[80:95]
	v_mfma_f32_32x32x16_bf16 v[16:31], v[234:237], v[222:225], v[16:31]
	ds_read_b128 v[234:237], v205 offset:96
	s_waitcnt lgkmcnt(5)
	v_mfma_f32_32x32x16_bf16 v[64:79], v[238:241], v[218:221], v[64:79]
	v_mfma_f32_32x32x16_bf16 v[0:15], v[238:241], v[222:225], v[0:15]
	ds_read_b128 v[238:241], v205 offset:4704
	s_setprio 0
	global_load_dwordx4 v[218:221], v[198:199], off offset:640
	global_load_dwordx4 v[222:225], v[200:201], off offset:640
	s_setprio 1
	s_waitcnt lgkmcnt(1)
	v_mfma_f32_32x32x16_bf16 v[112:127], v[234:237], v[226:229], v[112:127]
	v_mfma_f32_32x32x16_bf16 v[48:63], v[234:237], v[230:233], v[48:63]
	s_waitcnt lgkmcnt(0)
	v_mfma_f32_32x32x16_bf16 v[96:111], v[238:241], v[226:229], v[96:111]
	v_mfma_f32_32x32x16_bf16 v[32:47], v[238:241], v[230:233], v[32:47]
	ds_read_b128 v[234:237], v205 offset:9312
	ds_read_b128 v[238:241], v205 offset:13920
	s_waitcnt lgkmcnt(1)
	v_mfma_f32_32x32x16_bf16 v[80:95], v[234:237], v[226:229], v[80:95]
	v_mfma_f32_32x32x16_bf16 v[16:31], v[234:237], v[230:233], v[16:31]
	s_waitcnt lgkmcnt(0)
	v_mfma_f32_32x32x16_bf16 v[64:79], v[238:241], v[226:229], v[64:79]
	v_mfma_f32_32x32x16_bf16 v[0:15], v[238:241], v[230:233], v[0:15]
	s_setprio 0
	s_barrier
	global_load_dwordx4 v[226:229], v[190:191], off offset:768
	global_load_dwordx4 v[230:233], v[188:189], off offset:768
	s_waitcnt vmcnt(9)
	ds_write_b128 v209, v[176:179]
	s_waitcnt vmcnt(8)
	ds_write_b128 v210, v[180:183]
	ds_read_b128 v[176:179], v204 offset:36864
	ds_read_b128 v[180:183], v204 offset:41472
	ds_read_b128 v[234:237], v192
	ds_read_b128 v[238:241], v192 offset:4608
	s_setprio 1
	s_waitcnt lgkmcnt(1)
	v_mfma_f32_32x32x16_bf16 v[112:127], v[234:237], v[176:179], v[112:127]
	v_mfma_f32_32x32x16_bf16 v[48:63], v[234:237], v[180:183], v[48:63]
	s_waitcnt lgkmcnt(0)
	v_mfma_f32_32x32x16_bf16 v[96:111], v[238:241], v[176:179], v[96:111]
	v_mfma_f32_32x32x16_bf16 v[32:47], v[238:241], v[180:183], v[32:47]
	ds_read_b128 v[234:237], v192 offset:9216
	ds_read_b128 v[238:241], v192 offset:13824
	s_waitcnt vmcnt(7)
	ds_write_b128 v212, v[168:171]
	s_waitcnt vmcnt(6)
	ds_write_b128 v211, v[172:175]
	ds_read_b128 v[168:171], v204 offset:36896
	ds_read_b128 v[172:175], v204 offset:41504
	s_waitcnt lgkmcnt(5)
	v_mfma_f32_32x32x16_bf16 v[80:95], v[234:237], v[176:179], v[80:95]
	v_mfma_f32_32x32x16_bf16 v[16:31], v[234:237], v[180:183], v[16:31]
	ds_read_b128 v[234:237], v192 offset:32
	s_waitcnt lgkmcnt(5)
	v_mfma_f32_32x32x16_bf16 v[64:79], v[238:241], v[176:179], v[64:79]
	v_mfma_f32_32x32x16_bf16 v[0:15], v[238:241], v[180:183], v[0:15]
	ds_read_b128 v[238:241], v192 offset:4640
	s_setprio 0
	global_load_dwordx4 v[176:179], v[194:195], off offset:768
	global_load_dwordx4 v[180:183], v[196:197], off offset:768
	s_setprio 1
	s_waitcnt lgkmcnt(1)
	v_mfma_f32_32x32x16_bf16 v[112:127], v[234:237], v[168:171], v[112:127]
	v_mfma_f32_32x32x16_bf16 v[48:63], v[234:237], v[172:175], v[48:63]
	s_waitcnt lgkmcnt(0)
	v_mfma_f32_32x32x16_bf16 v[96:111], v[238:241], v[168:171], v[96:111]
	v_mfma_f32_32x32x16_bf16 v[32:47], v[238:241], v[172:175], v[32:47]
	ds_read_b128 v[234:237], v192 offset:9248
	ds_read_b128 v[238:241], v192 offset:13856
	s_waitcnt vmcnt(7)
	ds_write_b128 v214, v[160:163]
	s_waitcnt vmcnt(6)
	ds_write_b128 v213, v[164:167]
	ds_read_b128 v[160:163], v204 offset:36928
	ds_read_b128 v[164:167], v204 offset:41536
	s_waitcnt lgkmcnt(5)
	v_mfma_f32_32x32x16_bf16 v[80:95], v[234:237], v[168:171], v[80:95]
	v_mfma_f32_32x32x16_bf16 v[16:31], v[234:237], v[172:175], v[16:31]
	ds_read_b128 v[234:237], v192 offset:64
	s_waitcnt lgkmcnt(5)
	v_mfma_f32_32x32x16_bf16 v[64:79], v[238:241], v[168:171], v[64:79]
	v_mfma_f32_32x32x16_bf16 v[0:15], v[238:241], v[172:175], v[0:15]
	ds_read_b128 v[238:241], v192 offset:4672
	s_setprio 0
	global_load_dwordx4 v[168:171], v[184:185], off offset:768
	global_load_dwordx4 v[172:175], v[186:187], off offset:768
	s_setprio 1
	s_waitcnt lgkmcnt(1)
	v_mfma_f32_32x32x16_bf16 v[112:127], v[234:237], v[160:163], v[112:127]
	v_mfma_f32_32x32x16_bf16 v[48:63], v[234:237], v[164:167], v[48:63]
	s_waitcnt lgkmcnt(0)
	v_mfma_f32_32x32x16_bf16 v[96:111], v[238:241], v[160:163], v[96:111]
	v_mfma_f32_32x32x16_bf16 v[32:47], v[238:241], v[164:167], v[32:47]
	ds_read_b128 v[234:237], v192 offset:9280
	ds_read_b128 v[238:241], v192 offset:13888
	s_waitcnt vmcnt(7)
	ds_write_b128 v217, v[218:221]
	s_waitcnt vmcnt(6)
	ds_write_b128 v216, v[222:225]
	ds_read_b128 v[218:221], v204 offset:36960
	ds_read_b128 v[222:225], v204 offset:41568
	s_waitcnt lgkmcnt(5)
	v_mfma_f32_32x32x16_bf16 v[80:95], v[234:237], v[160:163], v[80:95]
	v_mfma_f32_32x32x16_bf16 v[16:31], v[234:237], v[164:167], v[16:31]
	ds_read_b128 v[234:237], v192 offset:96
	s_waitcnt lgkmcnt(5)
	v_mfma_f32_32x32x16_bf16 v[64:79], v[238:241], v[160:163], v[64:79]
	v_mfma_f32_32x32x16_bf16 v[0:15], v[238:241], v[164:167], v[0:15]
	ds_read_b128 v[238:241], v192 offset:4704
	s_setprio 0
	global_load_dwordx4 v[160:163], v[198:199], off offset:768
	global_load_dwordx4 v[164:167], v[200:201], off offset:768
	s_setprio 1
	s_waitcnt lgkmcnt(1)
	v_mfma_f32_32x32x16_bf16 v[112:127], v[234:237], v[218:221], v[112:127]
	v_mfma_f32_32x32x16_bf16 v[48:63], v[234:237], v[222:225], v[48:63]
	s_waitcnt lgkmcnt(0)
	v_mfma_f32_32x32x16_bf16 v[96:111], v[238:241], v[218:221], v[96:111]
	v_mfma_f32_32x32x16_bf16 v[32:47], v[238:241], v[222:225], v[32:47]
	ds_read_b128 v[234:237], v192 offset:9312
	ds_read_b128 v[238:241], v192 offset:13920
	s_waitcnt lgkmcnt(1)
	v_mfma_f32_32x32x16_bf16 v[80:95], v[234:237], v[218:221], v[80:95]
	v_mfma_f32_32x32x16_bf16 v[16:31], v[234:237], v[222:225], v[16:31]
	s_waitcnt lgkmcnt(0)
	v_mfma_f32_32x32x16_bf16 v[64:79], v[238:241], v[218:221], v[64:79]
	v_mfma_f32_32x32x16_bf16 v[0:15], v[238:241], v[222:225], v[0:15]
	s_setprio 0
	s_barrier
	global_load_dwordx4 v[218:221], v[190:191], off offset:896
	global_load_dwordx4 v[222:225], v[188:189], off offset:896
	s_waitcnt vmcnt(9)
	ds_write_b128 v215, v[226:229]
	s_waitcnt vmcnt(8)
	ds_write_b128 v215, v[230:233] offset:36864
	ds_read_b128 v[226:229], v208
	ds_read_b128 v[230:233], v208 offset:4608
	ds_read_b128 v[234:237], v205
	ds_read_b128 v[238:241], v205 offset:4608
	s_setprio 1
	s_waitcnt lgkmcnt(1)
	v_mfma_f32_32x32x16_bf16 v[112:127], v[234:237], v[226:229], v[112:127]
	v_mfma_f32_32x32x16_bf16 v[48:63], v[234:237], v[230:233], v[48:63]
	s_waitcnt lgkmcnt(0)
	v_mfma_f32_32x32x16_bf16 v[96:111], v[238:241], v[226:229], v[96:111]
	v_mfma_f32_32x32x16_bf16 v[32:47], v[238:241], v[230:233], v[32:47]
	ds_read_b128 v[234:237], v205 offset:9216
	ds_read_b128 v[238:241], v205 offset:13824
	s_waitcnt vmcnt(7)
	ds_write_b128 v215, v[176:179] offset:9216
	s_waitcnt vmcnt(6)
	ds_write_b128 v215, v[180:183] offset:46080
	ds_read_b128 v[176:179], v208 offset:32
	ds_read_b128 v[180:183], v208 offset:4640
	s_waitcnt lgkmcnt(5)
	v_mfma_f32_32x32x16_bf16 v[80:95], v[234:237], v[226:229], v[80:95]
	v_mfma_f32_32x32x16_bf16 v[16:31], v[234:237], v[230:233], v[16:31]
	ds_read_b128 v[234:237], v205 offset:32
	s_waitcnt lgkmcnt(5)
	v_mfma_f32_32x32x16_bf16 v[64:79], v[238:241], v[226:229], v[64:79]
	v_mfma_f32_32x32x16_bf16 v[0:15], v[238:241], v[230:233], v[0:15]
	ds_read_b128 v[238:241], v205 offset:4640
	s_setprio 0
	global_load_dwordx4 v[226:229], v[194:195], off offset:896
	global_load_dwordx4 v[230:233], v[196:197], off offset:896
	s_setprio 1
	s_waitcnt lgkmcnt(1)
	v_mfma_f32_32x32x16_bf16 v[112:127], v[234:237], v[176:179], v[112:127]
	v_mfma_f32_32x32x16_bf16 v[48:63], v[234:237], v[180:183], v[48:63]
	s_waitcnt lgkmcnt(0)
	v_mfma_f32_32x32x16_bf16 v[96:111], v[238:241], v[176:179], v[96:111]
	v_mfma_f32_32x32x16_bf16 v[32:47], v[238:241], v[180:183], v[32:47]
	ds_read_b128 v[234:237], v205 offset:9248
	ds_read_b128 v[238:241], v205 offset:13856
	s_waitcnt vmcnt(7)
	ds_write_b128 v215, v[168:171] offset:18432
	s_waitcnt vmcnt(6)
	ds_write_b128 v215, v[172:175] offset:55296
	ds_read_b128 v[168:171], v208 offset:64
	ds_read_b128 v[172:175], v208 offset:4672
	s_waitcnt lgkmcnt(5)
	v_mfma_f32_32x32x16_bf16 v[80:95], v[234:237], v[176:179], v[80:95]
	v_mfma_f32_32x32x16_bf16 v[16:31], v[234:237], v[180:183], v[16:31]
	ds_read_b128 v[234:237], v205 offset:64
	s_waitcnt lgkmcnt(5)
	v_mfma_f32_32x32x16_bf16 v[64:79], v[238:241], v[176:179], v[64:79]
	v_mfma_f32_32x32x16_bf16 v[0:15], v[238:241], v[180:183], v[0:15]
	ds_read_b128 v[238:241], v205 offset:4672
	s_setprio 0
	global_load_dwordx4 v[176:179], v[184:185], off offset:896
	global_load_dwordx4 v[180:183], v[186:187], off offset:896
	s_setprio 1
	s_waitcnt lgkmcnt(1)
	v_mfma_f32_32x32x16_bf16 v[112:127], v[234:237], v[168:171], v[112:127]
	v_mfma_f32_32x32x16_bf16 v[48:63], v[234:237], v[172:175], v[48:63]
	s_waitcnt lgkmcnt(0)
	v_mfma_f32_32x32x16_bf16 v[96:111], v[238:241], v[168:171], v[96:111]
	v_mfma_f32_32x32x16_bf16 v[32:47], v[238:241], v[172:175], v[32:47]
	ds_read_b128 v[234:237], v205 offset:9280
	ds_read_b128 v[238:241], v205 offset:13888
	s_waitcnt vmcnt(7)
	ds_write_b128 v215, v[160:163] offset:27648
	s_waitcnt vmcnt(6)
	ds_write_b128 v215, v[164:167] offset:64512
	ds_read_b128 v[160:163], v208 offset:96
	ds_read_b128 v[164:167], v208 offset:4704
	s_waitcnt lgkmcnt(5)
	v_mfma_f32_32x32x16_bf16 v[80:95], v[234:237], v[168:171], v[80:95]
	v_mfma_f32_32x32x16_bf16 v[16:31], v[234:237], v[172:175], v[16:31]
	ds_read_b128 v[234:237], v205 offset:96
	s_waitcnt lgkmcnt(5)
	v_mfma_f32_32x32x16_bf16 v[64:79], v[238:241], v[168:171], v[64:79]
	v_mfma_f32_32x32x16_bf16 v[0:15], v[238:241], v[172:175], v[0:15]
	ds_read_b128 v[238:241], v205 offset:4704
	s_setprio 0
	global_load_dwordx4 v[168:171], v[198:199], off offset:896
	global_load_dwordx4 v[172:175], v[200:201], off offset:896
	s_setprio 1
	s_waitcnt lgkmcnt(1)
	v_mfma_f32_32x32x16_bf16 v[112:127], v[234:237], v[160:163], v[112:127]
	v_mfma_f32_32x32x16_bf16 v[48:63], v[234:237], v[164:167], v[48:63]
	s_waitcnt lgkmcnt(0)
	v_mfma_f32_32x32x16_bf16 v[96:111], v[238:241], v[160:163], v[96:111]
	v_mfma_f32_32x32x16_bf16 v[32:47], v[238:241], v[164:167], v[32:47]
	ds_read_b128 v[234:237], v205 offset:9312
	ds_read_b128 v[238:241], v205 offset:13920
	s_waitcnt lgkmcnt(1)
	v_mfma_f32_32x32x16_bf16 v[80:95], v[234:237], v[160:163], v[80:95]
	v_mfma_f32_32x32x16_bf16 v[16:31], v[234:237], v[164:167], v[16:31]
	s_waitcnt lgkmcnt(0)
	v_mfma_f32_32x32x16_bf16 v[64:79], v[238:241], v[160:163], v[64:79]
	v_mfma_f32_32x32x16_bf16 v[0:15], v[238:241], v[164:167], v[0:15]
	s_setprio 0
	s_barrier
	global_load_dwordx4 v[160:163], v[190:191], off offset:1024
	global_load_dwordx4 v[164:167], v[188:189], off offset:1024
	s_waitcnt vmcnt(9)
	ds_write_b128 v209, v[218:221]
	s_waitcnt vmcnt(8)
	ds_write_b128 v210, v[222:225]
	ds_read_b128 v[218:221], v204 offset:36864
	ds_read_b128 v[222:225], v204 offset:41472
	ds_read_b128 v[234:237], v192
	ds_read_b128 v[238:241], v192 offset:4608
	s_setprio 1
	s_waitcnt lgkmcnt(1)
	v_mfma_f32_32x32x16_bf16 v[112:127], v[234:237], v[218:221], v[112:127]
	v_mfma_f32_32x32x16_bf16 v[48:63], v[234:237], v[222:225], v[48:63]
	s_waitcnt lgkmcnt(0)
	v_mfma_f32_32x32x16_bf16 v[96:111], v[238:241], v[218:221], v[96:111]
	v_mfma_f32_32x32x16_bf16 v[32:47], v[238:241], v[222:225], v[32:47]
	ds_read_b128 v[234:237], v192 offset:9216
	ds_read_b128 v[238:241], v192 offset:13824
	s_waitcnt vmcnt(7)
	ds_write_b128 v212, v[226:229]
	s_waitcnt vmcnt(6)
	ds_write_b128 v211, v[230:233]
	ds_read_b128 v[226:229], v204 offset:36896
	ds_read_b128 v[230:233], v204 offset:41504
	s_waitcnt lgkmcnt(5)
	v_mfma_f32_32x32x16_bf16 v[80:95], v[234:237], v[218:221], v[80:95]
	v_mfma_f32_32x32x16_bf16 v[16:31], v[234:237], v[222:225], v[16:31]
	ds_read_b128 v[234:237], v192 offset:32
	s_waitcnt lgkmcnt(5)
	v_mfma_f32_32x32x16_bf16 v[64:79], v[238:241], v[218:221], v[64:79]
	v_mfma_f32_32x32x16_bf16 v[0:15], v[238:241], v[222:225], v[0:15]
	ds_read_b128 v[238:241], v192 offset:4640
	s_setprio 0
	global_load_dwordx4 v[218:221], v[194:195], off offset:1024
	global_load_dwordx4 v[222:225], v[196:197], off offset:1024
	s_setprio 1
	s_waitcnt lgkmcnt(1)
	v_mfma_f32_32x32x16_bf16 v[112:127], v[234:237], v[226:229], v[112:127]
	v_mfma_f32_32x32x16_bf16 v[48:63], v[234:237], v[230:233], v[48:63]
	s_waitcnt lgkmcnt(0)
	v_mfma_f32_32x32x16_bf16 v[96:111], v[238:241], v[226:229], v[96:111]
	v_mfma_f32_32x32x16_bf16 v[32:47], v[238:241], v[230:233], v[32:47]
	ds_read_b128 v[234:237], v192 offset:9248
	ds_read_b128 v[238:241], v192 offset:13856
	s_waitcnt vmcnt(7)
	ds_write_b128 v214, v[176:179]
	s_waitcnt vmcnt(6)
	ds_write_b128 v213, v[180:183]
	ds_read_b128 v[176:179], v204 offset:36928
	ds_read_b128 v[180:183], v204 offset:41536
	s_waitcnt lgkmcnt(5)
	v_mfma_f32_32x32x16_bf16 v[80:95], v[234:237], v[226:229], v[80:95]
	v_mfma_f32_32x32x16_bf16 v[16:31], v[234:237], v[230:233], v[16:31]
	ds_read_b128 v[234:237], v192 offset:64
	s_waitcnt lgkmcnt(5)
	v_mfma_f32_32x32x16_bf16 v[64:79], v[238:241], v[226:229], v[64:79]
	v_mfma_f32_32x32x16_bf16 v[0:15], v[238:241], v[230:233], v[0:15]
	ds_read_b128 v[238:241], v192 offset:4672
	s_setprio 0
	global_load_dwordx4 v[226:229], v[184:185], off offset:1024
	global_load_dwordx4 v[230:233], v[186:187], off offset:1024
	s_setprio 1
	s_waitcnt lgkmcnt(1)
	v_mfma_f32_32x32x16_bf16 v[112:127], v[234:237], v[176:179], v[112:127]
	v_mfma_f32_32x32x16_bf16 v[48:63], v[234:237], v[180:183], v[48:63]
	s_waitcnt lgkmcnt(0)
	v_mfma_f32_32x32x16_bf16 v[96:111], v[238:241], v[176:179], v[96:111]
	v_mfma_f32_32x32x16_bf16 v[32:47], v[238:241], v[180:183], v[32:47]
	ds_read_b128 v[234:237], v192 offset:9280
	ds_read_b128 v[238:241], v192 offset:13888
	s_waitcnt vmcnt(7)
	ds_write_b128 v217, v[168:171]
	s_waitcnt vmcnt(6)
	ds_write_b128 v216, v[172:175]
	ds_read_b128 v[168:171], v204 offset:36960
	ds_read_b128 v[172:175], v204 offset:41568
	s_waitcnt lgkmcnt(5)
	v_mfma_f32_32x32x16_bf16 v[80:95], v[234:237], v[176:179], v[80:95]
	v_mfma_f32_32x32x16_bf16 v[16:31], v[234:237], v[180:183], v[16:31]
	ds_read_b128 v[234:237], v192 offset:96
	s_waitcnt lgkmcnt(5)
	v_mfma_f32_32x32x16_bf16 v[64:79], v[238:241], v[176:179], v[64:79]
	v_mfma_f32_32x32x16_bf16 v[0:15], v[238:241], v[180:183], v[0:15]
	ds_read_b128 v[238:241], v192 offset:4704
	s_setprio 0
	global_load_dwordx4 v[176:179], v[198:199], off offset:1024
	global_load_dwordx4 v[180:183], v[200:201], off offset:1024
	s_setprio 1
	s_waitcnt lgkmcnt(1)
	v_mfma_f32_32x32x16_bf16 v[112:127], v[234:237], v[168:171], v[112:127]
	v_mfma_f32_32x32x16_bf16 v[48:63], v[234:237], v[172:175], v[48:63]
	s_waitcnt lgkmcnt(0)
	v_mfma_f32_32x32x16_bf16 v[96:111], v[238:241], v[168:171], v[96:111]
	v_mfma_f32_32x32x16_bf16 v[32:47], v[238:241], v[172:175], v[32:47]
	ds_read_b128 v[234:237], v192 offset:9312
	ds_read_b128 v[238:241], v192 offset:13920
	s_waitcnt lgkmcnt(1)
	v_mfma_f32_32x32x16_bf16 v[80:95], v[234:237], v[168:171], v[80:95]
	v_mfma_f32_32x32x16_bf16 v[16:31], v[234:237], v[172:175], v[16:31]
	s_waitcnt lgkmcnt(0)
	v_mfma_f32_32x32x16_bf16 v[64:79], v[238:241], v[168:171], v[64:79]
	v_mfma_f32_32x32x16_bf16 v[0:15], v[238:241], v[172:175], v[0:15]
	s_setprio 0
	s_barrier
	global_load_dwordx4 v[168:171], v[190:191], off offset:1152
	global_load_dwordx4 v[172:175], v[188:189], off offset:1152
	s_waitcnt vmcnt(9)
	ds_write_b128 v215, v[160:163]
	s_waitcnt vmcnt(8)
	ds_write_b128 v215, v[164:167] offset:36864
	ds_read_b128 v[160:163], v208
	ds_read_b128 v[164:167], v208 offset:4608
	ds_read_b128 v[234:237], v205
	ds_read_b128 v[238:241], v205 offset:4608
	s_setprio 1
	s_waitcnt lgkmcnt(1)
	v_mfma_f32_32x32x16_bf16 v[112:127], v[234:237], v[160:163], v[112:127]
	v_mfma_f32_32x32x16_bf16 v[48:63], v[234:237], v[164:167], v[48:63]
	s_waitcnt lgkmcnt(0)
	v_mfma_f32_32x32x16_bf16 v[96:111], v[238:241], v[160:163], v[96:111]
	v_mfma_f32_32x32x16_bf16 v[32:47], v[238:241], v[164:167], v[32:47]
	ds_read_b128 v[234:237], v205 offset:9216
	ds_read_b128 v[238:241], v205 offset:13824
	s_waitcnt vmcnt(7)
	ds_write_b128 v215, v[218:221] offset:9216
	s_waitcnt vmcnt(6)
	ds_write_b128 v215, v[222:225] offset:46080
	ds_read_b128 v[218:221], v208 offset:32
	ds_read_b128 v[222:225], v208 offset:4640
	s_waitcnt lgkmcnt(5)
	v_mfma_f32_32x32x16_bf16 v[80:95], v[234:237], v[160:163], v[80:95]
	v_mfma_f32_32x32x16_bf16 v[16:31], v[234:237], v[164:167], v[16:31]
	ds_read_b128 v[234:237], v205 offset:32
	s_waitcnt lgkmcnt(5)
	v_mfma_f32_32x32x16_bf16 v[64:79], v[238:241], v[160:163], v[64:79]
	v_mfma_f32_32x32x16_bf16 v[0:15], v[238:241], v[164:167], v[0:15]
	ds_read_b128 v[238:241], v205 offset:4640
	s_setprio 0
	global_load_dwordx4 v[160:163], v[194:195], off offset:1152
	global_load_dwordx4 v[164:167], v[196:197], off offset:1152
	s_setprio 1
	s_waitcnt lgkmcnt(1)
	v_mfma_f32_32x32x16_bf16 v[112:127], v[234:237], v[218:221], v[112:127]
	v_mfma_f32_32x32x16_bf16 v[48:63], v[234:237], v[222:225], v[48:63]
	s_waitcnt lgkmcnt(0)
	v_mfma_f32_32x32x16_bf16 v[96:111], v[238:241], v[218:221], v[96:111]
	v_mfma_f32_32x32x16_bf16 v[32:47], v[238:241], v[222:225], v[32:47]
	ds_read_b128 v[234:237], v205 offset:9248
	ds_read_b128 v[238:241], v205 offset:13856
	s_waitcnt vmcnt(7)
	ds_write_b128 v215, v[226:229] offset:18432
	s_waitcnt vmcnt(6)
	ds_write_b128 v215, v[230:233] offset:55296
	ds_read_b128 v[226:229], v208 offset:64
	ds_read_b128 v[230:233], v208 offset:4672
	s_waitcnt lgkmcnt(5)
	v_mfma_f32_32x32x16_bf16 v[80:95], v[234:237], v[218:221], v[80:95]
	v_mfma_f32_32x32x16_bf16 v[16:31], v[234:237], v[222:225], v[16:31]
	ds_read_b128 v[234:237], v205 offset:64
	s_waitcnt lgkmcnt(5)
	v_mfma_f32_32x32x16_bf16 v[64:79], v[238:241], v[218:221], v[64:79]
	v_mfma_f32_32x32x16_bf16 v[0:15], v[238:241], v[222:225], v[0:15]
	ds_read_b128 v[238:241], v205 offset:4672
	s_setprio 0
	global_load_dwordx4 v[218:221], v[184:185], off offset:1152
	global_load_dwordx4 v[222:225], v[186:187], off offset:1152
	s_setprio 1
	s_waitcnt lgkmcnt(1)
	v_mfma_f32_32x32x16_bf16 v[112:127], v[234:237], v[226:229], v[112:127]
	v_mfma_f32_32x32x16_bf16 v[48:63], v[234:237], v[230:233], v[48:63]
	s_waitcnt lgkmcnt(0)
	v_mfma_f32_32x32x16_bf16 v[96:111], v[238:241], v[226:229], v[96:111]
	v_mfma_f32_32x32x16_bf16 v[32:47], v[238:241], v[230:233], v[32:47]
	ds_read_b128 v[234:237], v205 offset:9280
	ds_read_b128 v[238:241], v205 offset:13888
	s_waitcnt vmcnt(7)
	ds_write_b128 v215, v[176:179] offset:27648
	s_waitcnt vmcnt(6)
	ds_write_b128 v215, v[180:183] offset:64512
	ds_read_b128 v[176:179], v208 offset:96
	ds_read_b128 v[180:183], v208 offset:4704
	s_waitcnt lgkmcnt(5)
	v_mfma_f32_32x32x16_bf16 v[80:95], v[234:237], v[226:229], v[80:95]
	v_mfma_f32_32x32x16_bf16 v[16:31], v[234:237], v[230:233], v[16:31]
	ds_read_b128 v[234:237], v205 offset:96
	s_waitcnt lgkmcnt(5)
	v_mfma_f32_32x32x16_bf16 v[64:79], v[238:241], v[226:229], v[64:79]
	v_mfma_f32_32x32x16_bf16 v[0:15], v[238:241], v[230:233], v[0:15]
	ds_read_b128 v[238:241], v205 offset:4704
	s_setprio 0
	global_load_dwordx4 v[226:229], v[198:199], off offset:1152
	global_load_dwordx4 v[230:233], v[200:201], off offset:1152
	s_setprio 1
	s_waitcnt lgkmcnt(1)
	v_mfma_f32_32x32x16_bf16 v[112:127], v[234:237], v[176:179], v[112:127]
	v_mfma_f32_32x32x16_bf16 v[48:63], v[234:237], v[180:183], v[48:63]
	s_waitcnt lgkmcnt(0)
	v_mfma_f32_32x32x16_bf16 v[96:111], v[238:241], v[176:179], v[96:111]
	v_mfma_f32_32x32x16_bf16 v[32:47], v[238:241], v[180:183], v[32:47]
	ds_read_b128 v[234:237], v205 offset:9312
	ds_read_b128 v[238:241], v205 offset:13920
	s_waitcnt lgkmcnt(1)
	v_mfma_f32_32x32x16_bf16 v[80:95], v[234:237], v[176:179], v[80:95]
	v_mfma_f32_32x32x16_bf16 v[16:31], v[234:237], v[180:183], v[16:31]
	s_waitcnt lgkmcnt(0)
	v_mfma_f32_32x32x16_bf16 v[64:79], v[238:241], v[176:179], v[64:79]
	v_mfma_f32_32x32x16_bf16 v[0:15], v[238:241], v[180:183], v[0:15]
	s_setprio 0
	s_barrier
	global_load_dwordx4 v[176:179], v[190:191], off offset:1280
	global_load_dwordx4 v[180:183], v[188:189], off offset:1280
	s_waitcnt vmcnt(9)
	ds_write_b128 v209, v[168:171]
	s_waitcnt vmcnt(8)
	ds_write_b128 v210, v[172:175]
	ds_read_b128 v[168:171], v204 offset:36864
	ds_read_b128 v[172:175], v204 offset:41472
	ds_read_b128 v[234:237], v192
	ds_read_b128 v[238:241], v192 offset:4608
	s_setprio 1
	s_waitcnt lgkmcnt(1)
	v_mfma_f32_32x32x16_bf16 v[112:127], v[234:237], v[168:171], v[112:127]
	v_mfma_f32_32x32x16_bf16 v[48:63], v[234:237], v[172:175], v[48:63]
	s_waitcnt lgkmcnt(0)
	v_mfma_f32_32x32x16_bf16 v[96:111], v[238:241], v[168:171], v[96:111]
	v_mfma_f32_32x32x16_bf16 v[32:47], v[238:241], v[172:175], v[32:47]
	ds_read_b128 v[234:237], v192 offset:9216
	ds_read_b128 v[238:241], v192 offset:13824
	s_waitcnt vmcnt(7)
	ds_write_b128 v212, v[160:163]
	s_waitcnt vmcnt(6)
	ds_write_b128 v211, v[164:167]
	ds_read_b128 v[160:163], v204 offset:36896
	ds_read_b128 v[164:167], v204 offset:41504
	s_waitcnt lgkmcnt(5)
	v_mfma_f32_32x32x16_bf16 v[80:95], v[234:237], v[168:171], v[80:95]
	v_mfma_f32_32x32x16_bf16 v[16:31], v[234:237], v[172:175], v[16:31]
	ds_read_b128 v[234:237], v192 offset:32
	s_waitcnt lgkmcnt(5)
	v_mfma_f32_32x32x16_bf16 v[64:79], v[238:241], v[168:171], v[64:79]
	v_mfma_f32_32x32x16_bf16 v[0:15], v[238:241], v[172:175], v[0:15]
	ds_read_b128 v[238:241], v192 offset:4640
	s_setprio 0
	global_load_dwordx4 v[168:171], v[194:195], off offset:1280
	global_load_dwordx4 v[172:175], v[196:197], off offset:1280
	s_setprio 1
	s_waitcnt lgkmcnt(1)
	v_mfma_f32_32x32x16_bf16 v[112:127], v[234:237], v[160:163], v[112:127]
	v_mfma_f32_32x32x16_bf16 v[48:63], v[234:237], v[164:167], v[48:63]
	s_waitcnt lgkmcnt(0)
	v_mfma_f32_32x32x16_bf16 v[96:111], v[238:241], v[160:163], v[96:111]
	v_mfma_f32_32x32x16_bf16 v[32:47], v[238:241], v[164:167], v[32:47]
	ds_read_b128 v[234:237], v192 offset:9248
	ds_read_b128 v[238:241], v192 offset:13856
	s_waitcnt vmcnt(7)
	ds_write_b128 v214, v[218:221]
	s_waitcnt vmcnt(6)
	ds_write_b128 v213, v[222:225]
	ds_read_b128 v[218:221], v204 offset:36928
	ds_read_b128 v[222:225], v204 offset:41536
	s_waitcnt lgkmcnt(5)
	v_mfma_f32_32x32x16_bf16 v[80:95], v[234:237], v[160:163], v[80:95]
	v_mfma_f32_32x32x16_bf16 v[16:31], v[234:237], v[164:167], v[16:31]
	ds_read_b128 v[234:237], v192 offset:64
	s_waitcnt lgkmcnt(5)
	v_mfma_f32_32x32x16_bf16 v[64:79], v[238:241], v[160:163], v[64:79]
	v_mfma_f32_32x32x16_bf16 v[0:15], v[238:241], v[164:167], v[0:15]
	ds_read_b128 v[238:241], v192 offset:4672
	s_setprio 0
	global_load_dwordx4 v[160:163], v[184:185], off offset:1280
	global_load_dwordx4 v[164:167], v[186:187], off offset:1280
	s_setprio 1
	s_waitcnt lgkmcnt(1)
	v_mfma_f32_32x32x16_bf16 v[112:127], v[234:237], v[218:221], v[112:127]
	v_mfma_f32_32x32x16_bf16 v[48:63], v[234:237], v[222:225], v[48:63]
	s_waitcnt lgkmcnt(0)
	v_mfma_f32_32x32x16_bf16 v[96:111], v[238:241], v[218:221], v[96:111]
	v_mfma_f32_32x32x16_bf16 v[32:47], v[238:241], v[222:225], v[32:47]
	ds_read_b128 v[234:237], v192 offset:9280
	ds_read_b128 v[238:241], v192 offset:13888
	s_waitcnt vmcnt(7)
	ds_write_b128 v217, v[226:229]
	s_waitcnt vmcnt(6)
	ds_write_b128 v216, v[230:233]
	ds_read_b128 v[226:229], v204 offset:36960
	ds_read_b128 v[230:233], v204 offset:41568
	s_waitcnt lgkmcnt(5)
	v_mfma_f32_32x32x16_bf16 v[80:95], v[234:237], v[218:221], v[80:95]
	v_mfma_f32_32x32x16_bf16 v[16:31], v[234:237], v[222:225], v[16:31]
	ds_read_b128 v[234:237], v192 offset:96
	s_waitcnt lgkmcnt(5)
	v_mfma_f32_32x32x16_bf16 v[64:79], v[238:241], v[218:221], v[64:79]
	v_mfma_f32_32x32x16_bf16 v[0:15], v[238:241], v[222:225], v[0:15]
	ds_read_b128 v[238:241], v192 offset:4704
	s_setprio 0
	global_load_dwordx4 v[218:221], v[198:199], off offset:1280
	global_load_dwordx4 v[222:225], v[200:201], off offset:1280
	s_setprio 1
	s_waitcnt lgkmcnt(1)
	v_mfma_f32_32x32x16_bf16 v[112:127], v[234:237], v[226:229], v[112:127]
	v_mfma_f32_32x32x16_bf16 v[48:63], v[234:237], v[230:233], v[48:63]
	s_waitcnt lgkmcnt(0)
	v_mfma_f32_32x32x16_bf16 v[96:111], v[238:241], v[226:229], v[96:111]
	v_mfma_f32_32x32x16_bf16 v[32:47], v[238:241], v[230:233], v[32:47]
	ds_read_b128 v[234:237], v192 offset:9312
	ds_read_b128 v[238:241], v192 offset:13920
	s_waitcnt lgkmcnt(1)
	v_mfma_f32_32x32x16_bf16 v[80:95], v[234:237], v[226:229], v[80:95]
	v_mfma_f32_32x32x16_bf16 v[16:31], v[234:237], v[230:233], v[16:31]
	s_waitcnt lgkmcnt(0)
	v_mfma_f32_32x32x16_bf16 v[64:79], v[238:241], v[226:229], v[64:79]
	v_mfma_f32_32x32x16_bf16 v[0:15], v[238:241], v[230:233], v[0:15]
	s_setprio 0
	s_barrier
	global_load_dwordx4 v[226:229], v[190:191], off offset:1408
	global_load_dwordx4 v[230:233], v[188:189], off offset:1408
	s_waitcnt vmcnt(9)
	ds_write_b128 v215, v[176:179]
	s_waitcnt vmcnt(8)
	ds_write_b128 v215, v[180:183] offset:36864
	ds_read_b128 v[176:179], v208
	ds_read_b128 v[180:183], v208 offset:4608
	ds_read_b128 v[234:237], v205
	ds_read_b128 v[238:241], v205 offset:4608
	s_setprio 1
	s_waitcnt lgkmcnt(1)
	v_mfma_f32_32x32x16_bf16 v[112:127], v[234:237], v[176:179], v[112:127]
	v_mfma_f32_32x32x16_bf16 v[48:63], v[234:237], v[180:183], v[48:63]
	s_waitcnt lgkmcnt(0)
	v_mfma_f32_32x32x16_bf16 v[96:111], v[238:241], v[176:179], v[96:111]
	v_mfma_f32_32x32x16_bf16 v[32:47], v[238:241], v[180:183], v[32:47]
	ds_read_b128 v[234:237], v205 offset:9216
	ds_read_b128 v[238:241], v205 offset:13824
	s_waitcnt vmcnt(7)
	ds_write_b128 v215, v[168:171] offset:9216
	s_waitcnt vmcnt(6)
	ds_write_b128 v215, v[172:175] offset:46080
	ds_read_b128 v[168:171], v208 offset:32
	ds_read_b128 v[172:175], v208 offset:4640
	s_waitcnt lgkmcnt(5)
	v_mfma_f32_32x32x16_bf16 v[80:95], v[234:237], v[176:179], v[80:95]
	v_mfma_f32_32x32x16_bf16 v[16:31], v[234:237], v[180:183], v[16:31]
	ds_read_b128 v[234:237], v205 offset:32
	s_waitcnt lgkmcnt(5)
	v_mfma_f32_32x32x16_bf16 v[64:79], v[238:241], v[176:179], v[64:79]
	v_mfma_f32_32x32x16_bf16 v[0:15], v[238:241], v[180:183], v[0:15]
	ds_read_b128 v[238:241], v205 offset:4640
	s_setprio 0
	global_load_dwordx4 v[176:179], v[194:195], off offset:1408
	global_load_dwordx4 v[180:183], v[196:197], off offset:1408
	s_setprio 1
	s_waitcnt lgkmcnt(1)
	v_mfma_f32_32x32x16_bf16 v[112:127], v[234:237], v[168:171], v[112:127]
	v_mfma_f32_32x32x16_bf16 v[48:63], v[234:237], v[172:175], v[48:63]
	s_waitcnt lgkmcnt(0)
	v_mfma_f32_32x32x16_bf16 v[96:111], v[238:241], v[168:171], v[96:111]
	v_mfma_f32_32x32x16_bf16 v[32:47], v[238:241], v[172:175], v[32:47]
	ds_read_b128 v[234:237], v205 offset:9248
	ds_read_b128 v[238:241], v205 offset:13856
	s_waitcnt vmcnt(7)
	ds_write_b128 v215, v[160:163] offset:18432
	s_waitcnt vmcnt(6)
	ds_write_b128 v215, v[164:167] offset:55296
	ds_read_b128 v[160:163], v208 offset:64
	ds_read_b128 v[164:167], v208 offset:4672
	s_waitcnt lgkmcnt(5)
	v_mfma_f32_32x32x16_bf16 v[80:95], v[234:237], v[168:171], v[80:95]
	v_mfma_f32_32x32x16_bf16 v[16:31], v[234:237], v[172:175], v[16:31]
	ds_read_b128 v[234:237], v205 offset:64
	s_waitcnt lgkmcnt(5)
	v_mfma_f32_32x32x16_bf16 v[64:79], v[238:241], v[168:171], v[64:79]
	v_mfma_f32_32x32x16_bf16 v[0:15], v[238:241], v[172:175], v[0:15]
	ds_read_b128 v[238:241], v205 offset:4672
	s_setprio 0
	global_load_dwordx4 v[168:171], v[184:185], off offset:1408
	global_load_dwordx4 v[172:175], v[186:187], off offset:1408
	s_setprio 1
	s_waitcnt lgkmcnt(1)
	v_mfma_f32_32x32x16_bf16 v[112:127], v[234:237], v[160:163], v[112:127]
	v_mfma_f32_32x32x16_bf16 v[48:63], v[234:237], v[164:167], v[48:63]
	s_waitcnt lgkmcnt(0)
	v_mfma_f32_32x32x16_bf16 v[96:111], v[238:241], v[160:163], v[96:111]
	v_mfma_f32_32x32x16_bf16 v[32:47], v[238:241], v[164:167], v[32:47]
	ds_read_b128 v[234:237], v205 offset:9280
	ds_read_b128 v[238:241], v205 offset:13888
	s_waitcnt vmcnt(7)
	ds_write_b128 v215, v[218:221] offset:27648
	s_waitcnt vmcnt(6)
	ds_write_b128 v215, v[222:225] offset:64512
	ds_read_b128 v[218:221], v208 offset:96
	ds_read_b128 v[222:225], v208 offset:4704
	s_waitcnt lgkmcnt(5)
	v_mfma_f32_32x32x16_bf16 v[80:95], v[234:237], v[160:163], v[80:95]
	v_mfma_f32_32x32x16_bf16 v[16:31], v[234:237], v[164:167], v[16:31]
	ds_read_b128 v[234:237], v205 offset:96
	s_waitcnt lgkmcnt(5)
	v_mfma_f32_32x32x16_bf16 v[64:79], v[238:241], v[160:163], v[64:79]
	v_mfma_f32_32x32x16_bf16 v[0:15], v[238:241], v[164:167], v[0:15]
	ds_read_b128 v[238:241], v205 offset:4704
	s_setprio 0
	global_load_dwordx4 v[160:163], v[198:199], off offset:1408
	global_load_dwordx4 v[164:167], v[200:201], off offset:1408
	s_setprio 1
	s_waitcnt lgkmcnt(1)
	v_mfma_f32_32x32x16_bf16 v[112:127], v[234:237], v[218:221], v[112:127]
	v_mfma_f32_32x32x16_bf16 v[48:63], v[234:237], v[222:225], v[48:63]
	s_waitcnt lgkmcnt(0)
	v_mfma_f32_32x32x16_bf16 v[96:111], v[238:241], v[218:221], v[96:111]
	v_mfma_f32_32x32x16_bf16 v[32:47], v[238:241], v[222:225], v[32:47]
	ds_read_b128 v[234:237], v205 offset:9312
	ds_read_b128 v[238:241], v205 offset:13920
	s_waitcnt lgkmcnt(1)
	v_mfma_f32_32x32x16_bf16 v[80:95], v[234:237], v[218:221], v[80:95]
	v_mfma_f32_32x32x16_bf16 v[16:31], v[234:237], v[222:225], v[16:31]
	s_waitcnt lgkmcnt(0)
	v_mfma_f32_32x32x16_bf16 v[64:79], v[238:241], v[218:221], v[64:79]
	v_mfma_f32_32x32x16_bf16 v[0:15], v[238:241], v[222:225], v[0:15]
	s_setprio 0
	s_barrier
	global_load_dwordx4 v[218:221], v[190:191], off offset:1536
	global_load_dwordx4 v[222:225], v[188:189], off offset:1536
	s_waitcnt vmcnt(9)
	ds_write_b128 v209, v[226:229]
	s_waitcnt vmcnt(8)
	ds_write_b128 v210, v[230:233]
	ds_read_b128 v[226:229], v204 offset:36864
	ds_read_b128 v[230:233], v204 offset:41472
	ds_read_b128 v[234:237], v192
	ds_read_b128 v[238:241], v192 offset:4608
	s_setprio 1
	s_waitcnt lgkmcnt(1)
	v_mfma_f32_32x32x16_bf16 v[112:127], v[234:237], v[226:229], v[112:127]
	v_mfma_f32_32x32x16_bf16 v[48:63], v[234:237], v[230:233], v[48:63]
	s_waitcnt lgkmcnt(0)
	v_mfma_f32_32x32x16_bf16 v[96:111], v[238:241], v[226:229], v[96:111]
	v_mfma_f32_32x32x16_bf16 v[32:47], v[238:241], v[230:233], v[32:47]
	ds_read_b128 v[234:237], v192 offset:9216
	ds_read_b128 v[238:241], v192 offset:13824
	s_waitcnt vmcnt(7)
	ds_write_b128 v212, v[176:179]
	s_waitcnt vmcnt(6)
	ds_write_b128 v211, v[180:183]
	ds_read_b128 v[176:179], v204 offset:36896
	ds_read_b128 v[180:183], v204 offset:41504
	s_waitcnt lgkmcnt(5)
	v_mfma_f32_32x32x16_bf16 v[80:95], v[234:237], v[226:229], v[80:95]
	v_mfma_f32_32x32x16_bf16 v[16:31], v[234:237], v[230:233], v[16:31]
	ds_read_b128 v[234:237], v192 offset:32
	s_waitcnt lgkmcnt(5)
	v_mfma_f32_32x32x16_bf16 v[64:79], v[238:241], v[226:229], v[64:79]
	v_mfma_f32_32x32x16_bf16 v[0:15], v[238:241], v[230:233], v[0:15]
	ds_read_b128 v[238:241], v192 offset:4640
	s_setprio 0
	global_load_dwordx4 v[226:229], v[194:195], off offset:1536
	global_load_dwordx4 v[230:233], v[196:197], off offset:1536
	s_setprio 1
	s_waitcnt lgkmcnt(1)
	v_mfma_f32_32x32x16_bf16 v[112:127], v[234:237], v[176:179], v[112:127]
	v_mfma_f32_32x32x16_bf16 v[48:63], v[234:237], v[180:183], v[48:63]
	s_waitcnt lgkmcnt(0)
	v_mfma_f32_32x32x16_bf16 v[96:111], v[238:241], v[176:179], v[96:111]
	v_mfma_f32_32x32x16_bf16 v[32:47], v[238:241], v[180:183], v[32:47]
	ds_read_b128 v[234:237], v192 offset:9248
	ds_read_b128 v[238:241], v192 offset:13856
	s_waitcnt vmcnt(7)
	ds_write_b128 v214, v[168:171]
	s_waitcnt vmcnt(6)
	ds_write_b128 v213, v[172:175]
	ds_read_b128 v[168:171], v204 offset:36928
	ds_read_b128 v[172:175], v204 offset:41536
	s_waitcnt lgkmcnt(5)
	v_mfma_f32_32x32x16_bf16 v[80:95], v[234:237], v[176:179], v[80:95]
	v_mfma_f32_32x32x16_bf16 v[16:31], v[234:237], v[180:183], v[16:31]
	ds_read_b128 v[234:237], v192 offset:64
	s_waitcnt lgkmcnt(5)
	v_mfma_f32_32x32x16_bf16 v[64:79], v[238:241], v[176:179], v[64:79]
	v_mfma_f32_32x32x16_bf16 v[0:15], v[238:241], v[180:183], v[0:15]
	ds_read_b128 v[238:241], v192 offset:4672
	s_setprio 0
	global_load_dwordx4 v[176:179], v[184:185], off offset:1536
	global_load_dwordx4 v[180:183], v[186:187], off offset:1536
	s_setprio 1
	s_waitcnt lgkmcnt(1)
	v_mfma_f32_32x32x16_bf16 v[112:127], v[234:237], v[168:171], v[112:127]
	v_mfma_f32_32x32x16_bf16 v[48:63], v[234:237], v[172:175], v[48:63]
	s_waitcnt lgkmcnt(0)
	v_mfma_f32_32x32x16_bf16 v[96:111], v[238:241], v[168:171], v[96:111]
	v_mfma_f32_32x32x16_bf16 v[32:47], v[238:241], v[172:175], v[32:47]
	ds_read_b128 v[234:237], v192 offset:9280
	ds_read_b128 v[238:241], v192 offset:13888
	s_waitcnt vmcnt(7)
	ds_write_b128 v217, v[160:163]
	s_waitcnt vmcnt(6)
	ds_write_b128 v216, v[164:167]
	ds_read_b128 v[160:163], v204 offset:36960
	ds_read_b128 v[164:167], v204 offset:41568
	s_waitcnt lgkmcnt(5)
	v_mfma_f32_32x32x16_bf16 v[80:95], v[234:237], v[168:171], v[80:95]
	v_mfma_f32_32x32x16_bf16 v[16:31], v[234:237], v[172:175], v[16:31]
	ds_read_b128 v[234:237], v192 offset:96
	s_waitcnt lgkmcnt(5)
	v_mfma_f32_32x32x16_bf16 v[64:79], v[238:241], v[168:171], v[64:79]
	v_mfma_f32_32x32x16_bf16 v[0:15], v[238:241], v[172:175], v[0:15]
	ds_read_b128 v[238:241], v192 offset:4704
	s_setprio 0
	global_load_dwordx4 v[168:171], v[198:199], off offset:1536
	global_load_dwordx4 v[172:175], v[200:201], off offset:1536
	s_setprio 1
	s_waitcnt lgkmcnt(1)
	v_mfma_f32_32x32x16_bf16 v[112:127], v[234:237], v[160:163], v[112:127]
	v_mfma_f32_32x32x16_bf16 v[48:63], v[234:237], v[164:167], v[48:63]
	s_waitcnt lgkmcnt(0)
	v_mfma_f32_32x32x16_bf16 v[96:111], v[238:241], v[160:163], v[96:111]
	v_mfma_f32_32x32x16_bf16 v[32:47], v[238:241], v[164:167], v[32:47]
	ds_read_b128 v[234:237], v192 offset:9312
	ds_read_b128 v[238:241], v192 offset:13920
	s_waitcnt lgkmcnt(1)
	v_mfma_f32_32x32x16_bf16 v[80:95], v[234:237], v[160:163], v[80:95]
	v_mfma_f32_32x32x16_bf16 v[16:31], v[234:237], v[164:167], v[16:31]
	s_waitcnt lgkmcnt(0)
	v_mfma_f32_32x32x16_bf16 v[64:79], v[238:241], v[160:163], v[64:79]
	v_mfma_f32_32x32x16_bf16 v[0:15], v[238:241], v[164:167], v[0:15]
	s_setprio 0
	s_barrier
	global_load_dwordx4 v[160:163], v[190:191], off offset:1664
	global_load_dwordx4 v[164:167], v[188:189], off offset:1664
	s_waitcnt vmcnt(9)
	ds_write_b128 v215, v[218:221]
	s_waitcnt vmcnt(8)
	ds_write_b128 v215, v[222:225] offset:36864
	ds_read_b128 v[218:221], v208
	ds_read_b128 v[222:225], v208 offset:4608
	ds_read_b128 v[234:237], v205
	ds_read_b128 v[238:241], v205 offset:4608
	s_setprio 1
	s_waitcnt lgkmcnt(1)
	v_mfma_f32_32x32x16_bf16 v[112:127], v[234:237], v[218:221], v[112:127]
	v_mfma_f32_32x32x16_bf16 v[48:63], v[234:237], v[222:225], v[48:63]
	s_waitcnt lgkmcnt(0)
	v_mfma_f32_32x32x16_bf16 v[96:111], v[238:241], v[218:221], v[96:111]
	v_mfma_f32_32x32x16_bf16 v[32:47], v[238:241], v[222:225], v[32:47]
	ds_read_b128 v[234:237], v205 offset:9216
	ds_read_b128 v[238:241], v205 offset:13824
	s_waitcnt vmcnt(7)
	ds_write_b128 v215, v[226:229] offset:9216
	s_waitcnt vmcnt(6)
	ds_write_b128 v215, v[230:233] offset:46080
	ds_read_b128 v[226:229], v208 offset:32
	ds_read_b128 v[230:233], v208 offset:4640
	s_waitcnt lgkmcnt(5)
	v_mfma_f32_32x32x16_bf16 v[80:95], v[234:237], v[218:221], v[80:95]
	v_mfma_f32_32x32x16_bf16 v[16:31], v[234:237], v[222:225], v[16:31]
	ds_read_b128 v[234:237], v205 offset:32
	s_waitcnt lgkmcnt(5)
	v_mfma_f32_32x32x16_bf16 v[64:79], v[238:241], v[218:221], v[64:79]
	v_mfma_f32_32x32x16_bf16 v[0:15], v[238:241], v[222:225], v[0:15]
	ds_read_b128 v[238:241], v205 offset:4640
	s_setprio 0
	global_load_dwordx4 v[218:221], v[194:195], off offset:1664
	global_load_dwordx4 v[222:225], v[196:197], off offset:1664
	s_setprio 1
	s_waitcnt lgkmcnt(1)
	v_mfma_f32_32x32x16_bf16 v[112:127], v[234:237], v[226:229], v[112:127]
	v_mfma_f32_32x32x16_bf16 v[48:63], v[234:237], v[230:233], v[48:63]
	s_waitcnt lgkmcnt(0)
	v_mfma_f32_32x32x16_bf16 v[96:111], v[238:241], v[226:229], v[96:111]
	v_mfma_f32_32x32x16_bf16 v[32:47], v[238:241], v[230:233], v[32:47]
	ds_read_b128 v[234:237], v205 offset:9248
	ds_read_b128 v[238:241], v205 offset:13856
	s_waitcnt vmcnt(7)
	ds_write_b128 v215, v[176:179] offset:18432
	s_waitcnt vmcnt(6)
	ds_write_b128 v215, v[180:183] offset:55296
	ds_read_b128 v[176:179], v208 offset:64
	ds_read_b128 v[180:183], v208 offset:4672
	s_waitcnt lgkmcnt(5)
	v_mfma_f32_32x32x16_bf16 v[80:95], v[234:237], v[226:229], v[80:95]
	v_mfma_f32_32x32x16_bf16 v[16:31], v[234:237], v[230:233], v[16:31]
	ds_read_b128 v[234:237], v205 offset:64
	s_waitcnt lgkmcnt(5)
	v_mfma_f32_32x32x16_bf16 v[64:79], v[238:241], v[226:229], v[64:79]
	v_mfma_f32_32x32x16_bf16 v[0:15], v[238:241], v[230:233], v[0:15]
	ds_read_b128 v[238:241], v205 offset:4672
	s_setprio 0
	global_load_dwordx4 v[226:229], v[184:185], off offset:1664
	global_load_dwordx4 v[230:233], v[186:187], off offset:1664
	s_setprio 1
	s_waitcnt lgkmcnt(1)
	v_mfma_f32_32x32x16_bf16 v[112:127], v[234:237], v[176:179], v[112:127]
	v_mfma_f32_32x32x16_bf16 v[48:63], v[234:237], v[180:183], v[48:63]
	s_waitcnt lgkmcnt(0)
	v_mfma_f32_32x32x16_bf16 v[96:111], v[238:241], v[176:179], v[96:111]
	v_mfma_f32_32x32x16_bf16 v[32:47], v[238:241], v[180:183], v[32:47]
	ds_read_b128 v[234:237], v205 offset:9280
	ds_read_b128 v[238:241], v205 offset:13888
	s_waitcnt vmcnt(7)
	ds_write_b128 v215, v[168:171] offset:27648
	s_waitcnt vmcnt(6)
	ds_write_b128 v215, v[172:175] offset:64512
	ds_read_b128 v[168:171], v208 offset:96
	ds_read_b128 v[172:175], v208 offset:4704
	s_waitcnt lgkmcnt(5)
	v_mfma_f32_32x32x16_bf16 v[80:95], v[234:237], v[176:179], v[80:95]
	v_mfma_f32_32x32x16_bf16 v[16:31], v[234:237], v[180:183], v[16:31]
	ds_read_b128 v[234:237], v205 offset:96
	s_waitcnt lgkmcnt(5)
	v_mfma_f32_32x32x16_bf16 v[64:79], v[238:241], v[176:179], v[64:79]
	v_mfma_f32_32x32x16_bf16 v[0:15], v[238:241], v[180:183], v[0:15]
	ds_read_b128 v[238:241], v205 offset:4704
	s_setprio 0
	global_load_dwordx4 v[176:179], v[198:199], off offset:1664
	global_load_dwordx4 v[180:183], v[200:201], off offset:1664
	s_setprio 1
	s_waitcnt lgkmcnt(1)
	v_mfma_f32_32x32x16_bf16 v[112:127], v[234:237], v[168:171], v[112:127]
	v_mfma_f32_32x32x16_bf16 v[48:63], v[234:237], v[172:175], v[48:63]
	s_waitcnt lgkmcnt(0)
	v_mfma_f32_32x32x16_bf16 v[96:111], v[238:241], v[168:171], v[96:111]
	v_mfma_f32_32x32x16_bf16 v[32:47], v[238:241], v[172:175], v[32:47]
	ds_read_b128 v[234:237], v205 offset:9312
	ds_read_b128 v[238:241], v205 offset:13920
	s_waitcnt lgkmcnt(1)
	v_mfma_f32_32x32x16_bf16 v[80:95], v[234:237], v[168:171], v[80:95]
	v_mfma_f32_32x32x16_bf16 v[16:31], v[234:237], v[172:175], v[16:31]
	s_waitcnt lgkmcnt(0)
	v_mfma_f32_32x32x16_bf16 v[64:79], v[238:241], v[168:171], v[64:79]
	v_mfma_f32_32x32x16_bf16 v[0:15], v[238:241], v[172:175], v[0:15]
	s_setprio 0
	s_barrier
	global_load_dwordx4 v[168:171], v[190:191], off offset:1792
	global_load_dwordx4 v[172:175], v[188:189], off offset:1792
	s_waitcnt vmcnt(9)
	ds_write_b128 v209, v[160:163]
	s_waitcnt vmcnt(8)
	ds_write_b128 v210, v[164:167]
	ds_read_b128 v[160:163], v204 offset:36864
	ds_read_b128 v[164:167], v204 offset:41472
	ds_read_b128 v[234:237], v192
	ds_read_b128 v[238:241], v192 offset:4608
	s_setprio 1
	s_waitcnt lgkmcnt(1)
	v_mfma_f32_32x32x16_bf16 v[112:127], v[234:237], v[160:163], v[112:127]
	v_mfma_f32_32x32x16_bf16 v[48:63], v[234:237], v[164:167], v[48:63]
	s_waitcnt lgkmcnt(0)
	v_mfma_f32_32x32x16_bf16 v[96:111], v[238:241], v[160:163], v[96:111]
	v_mfma_f32_32x32x16_bf16 v[32:47], v[238:241], v[164:167], v[32:47]
	ds_read_b128 v[234:237], v192 offset:9216
	ds_read_b128 v[238:241], v192 offset:13824
	s_waitcnt vmcnt(7)
	ds_write_b128 v212, v[218:221]
	s_waitcnt vmcnt(6)
	ds_write_b128 v211, v[222:225]
	ds_read_b128 v[218:221], v204 offset:36896
	ds_read_b128 v[222:225], v204 offset:41504
	s_waitcnt lgkmcnt(5)
	v_mfma_f32_32x32x16_bf16 v[80:95], v[234:237], v[160:163], v[80:95]
	v_mfma_f32_32x32x16_bf16 v[16:31], v[234:237], v[164:167], v[16:31]
	ds_read_b128 v[234:237], v192 offset:32
	s_waitcnt lgkmcnt(5)
	v_mfma_f32_32x32x16_bf16 v[64:79], v[238:241], v[160:163], v[64:79]
	v_mfma_f32_32x32x16_bf16 v[0:15], v[238:241], v[164:167], v[0:15]
	ds_read_b128 v[238:241], v192 offset:4640
	s_setprio 0
	global_load_dwordx4 v[160:163], v[194:195], off offset:1792
	global_load_dwordx4 v[164:167], v[196:197], off offset:1792
	s_setprio 1
	s_waitcnt lgkmcnt(1)
	v_mfma_f32_32x32x16_bf16 v[112:127], v[234:237], v[218:221], v[112:127]
	v_mfma_f32_32x32x16_bf16 v[48:63], v[234:237], v[222:225], v[48:63]
	s_waitcnt lgkmcnt(0)
	v_mfma_f32_32x32x16_bf16 v[96:111], v[238:241], v[218:221], v[96:111]
	v_mfma_f32_32x32x16_bf16 v[32:47], v[238:241], v[222:225], v[32:47]
	ds_read_b128 v[234:237], v192 offset:9248
	ds_read_b128 v[238:241], v192 offset:13856
	s_waitcnt vmcnt(7)
	ds_write_b128 v214, v[226:229]
	s_waitcnt vmcnt(6)
	ds_write_b128 v213, v[230:233]
	ds_read_b128 v[226:229], v204 offset:36928
	ds_read_b128 v[230:233], v204 offset:41536
	s_waitcnt lgkmcnt(5)
	v_mfma_f32_32x32x16_bf16 v[80:95], v[234:237], v[218:221], v[80:95]
	v_mfma_f32_32x32x16_bf16 v[16:31], v[234:237], v[222:225], v[16:31]
	ds_read_b128 v[234:237], v192 offset:64
	s_waitcnt lgkmcnt(5)
	v_mfma_f32_32x32x16_bf16 v[64:79], v[238:241], v[218:221], v[64:79]
	v_mfma_f32_32x32x16_bf16 v[0:15], v[238:241], v[222:225], v[0:15]
	ds_read_b128 v[238:241], v192 offset:4672
	s_setprio 0
	global_load_dwordx4 v[218:221], v[184:185], off offset:1792
	global_load_dwordx4 v[222:225], v[186:187], off offset:1792
	s_setprio 1
	s_waitcnt lgkmcnt(1)
	v_mfma_f32_32x32x16_bf16 v[112:127], v[234:237], v[226:229], v[112:127]
	v_mfma_f32_32x32x16_bf16 v[48:63], v[234:237], v[230:233], v[48:63]
	s_waitcnt lgkmcnt(0)
	v_mfma_f32_32x32x16_bf16 v[96:111], v[238:241], v[226:229], v[96:111]
	v_mfma_f32_32x32x16_bf16 v[32:47], v[238:241], v[230:233], v[32:47]
	ds_read_b128 v[234:237], v192 offset:9280
	ds_read_b128 v[238:241], v192 offset:13888
	s_waitcnt vmcnt(7)
	ds_write_b128 v217, v[176:179]
	s_waitcnt vmcnt(6)
	ds_write_b128 v216, v[180:183]
	ds_read_b128 v[176:179], v204 offset:36960
	ds_read_b128 v[180:183], v204 offset:41568
	s_waitcnt lgkmcnt(5)
	v_mfma_f32_32x32x16_bf16 v[80:95], v[234:237], v[226:229], v[80:95]
	v_mfma_f32_32x32x16_bf16 v[16:31], v[234:237], v[230:233], v[16:31]
	ds_read_b128 v[234:237], v192 offset:96
	s_waitcnt lgkmcnt(5)
	v_mfma_f32_32x32x16_bf16 v[64:79], v[238:241], v[226:229], v[64:79]
	v_mfma_f32_32x32x16_bf16 v[0:15], v[238:241], v[230:233], v[0:15]
	ds_read_b128 v[238:241], v192 offset:4704
	s_setprio 0
	global_load_dwordx4 v[226:229], v[198:199], off offset:1792
	global_load_dwordx4 v[230:233], v[200:201], off offset:1792
	s_setprio 1
	s_waitcnt lgkmcnt(1)
	v_mfma_f32_32x32x16_bf16 v[112:127], v[234:237], v[176:179], v[112:127]
	v_mfma_f32_32x32x16_bf16 v[48:63], v[234:237], v[180:183], v[48:63]
	s_waitcnt lgkmcnt(0)
	v_mfma_f32_32x32x16_bf16 v[96:111], v[238:241], v[176:179], v[96:111]
	v_mfma_f32_32x32x16_bf16 v[32:47], v[238:241], v[180:183], v[32:47]
	ds_read_b128 v[234:237], v192 offset:9312
	ds_read_b128 v[238:241], v192 offset:13920
	s_waitcnt lgkmcnt(1)
	v_mfma_f32_32x32x16_bf16 v[80:95], v[234:237], v[176:179], v[80:95]
	v_mfma_f32_32x32x16_bf16 v[16:31], v[234:237], v[180:183], v[16:31]
	s_waitcnt lgkmcnt(0)
	v_mfma_f32_32x32x16_bf16 v[64:79], v[238:241], v[176:179], v[64:79]
	v_mfma_f32_32x32x16_bf16 v[0:15], v[238:241], v[180:183], v[0:15]
	s_setprio 0
	s_barrier
	global_load_dwordx4 v[176:179], v[190:191], off offset:1920
	global_load_dwordx4 v[180:183], v[188:189], off offset:1920
	s_waitcnt vmcnt(9)
	ds_write_b128 v215, v[168:171]
	s_waitcnt vmcnt(8)
	ds_write_b128 v215, v[172:175] offset:36864
	ds_read_b128 v[168:171], v208
	ds_read_b128 v[172:175], v208 offset:4608
	ds_read_b128 v[234:237], v205
	ds_read_b128 v[238:241], v205 offset:4608
	s_setprio 1
	s_waitcnt lgkmcnt(1)
	v_mfma_f32_32x32x16_bf16 v[112:127], v[234:237], v[168:171], v[112:127]
	v_mfma_f32_32x32x16_bf16 v[48:63], v[234:237], v[172:175], v[48:63]
	s_waitcnt lgkmcnt(0)
	v_mfma_f32_32x32x16_bf16 v[96:111], v[238:241], v[168:171], v[96:111]
	v_mfma_f32_32x32x16_bf16 v[32:47], v[238:241], v[172:175], v[32:47]
	ds_read_b128 v[234:237], v205 offset:9216
	ds_read_b128 v[238:241], v205 offset:13824
	s_waitcnt vmcnt(7)
	ds_write_b128 v215, v[160:163] offset:9216
	s_waitcnt vmcnt(6)
	ds_write_b128 v215, v[164:167] offset:46080
	ds_read_b128 v[160:163], v208 offset:32
	ds_read_b128 v[164:167], v208 offset:4640
	s_waitcnt lgkmcnt(5)
	v_mfma_f32_32x32x16_bf16 v[80:95], v[234:237], v[168:171], v[80:95]
	v_mfma_f32_32x32x16_bf16 v[16:31], v[234:237], v[172:175], v[16:31]
	ds_read_b128 v[234:237], v205 offset:32
	s_waitcnt lgkmcnt(5)
	v_mfma_f32_32x32x16_bf16 v[64:79], v[238:241], v[168:171], v[64:79]
	v_mfma_f32_32x32x16_bf16 v[0:15], v[238:241], v[172:175], v[0:15]
	ds_read_b128 v[238:241], v205 offset:4640
	s_setprio 0
	global_load_dwordx4 v[168:171], v[194:195], off offset:1920
	global_load_dwordx4 v[172:175], v[196:197], off offset:1920
	s_setprio 1
	s_waitcnt lgkmcnt(1)
	v_mfma_f32_32x32x16_bf16 v[112:127], v[234:237], v[160:163], v[112:127]
	v_mfma_f32_32x32x16_bf16 v[48:63], v[234:237], v[164:167], v[48:63]
	s_waitcnt lgkmcnt(0)
	v_mfma_f32_32x32x16_bf16 v[96:111], v[238:241], v[160:163], v[96:111]
	v_mfma_f32_32x32x16_bf16 v[32:47], v[238:241], v[164:167], v[32:47]
	ds_read_b128 v[234:237], v205 offset:9248
	ds_read_b128 v[238:241], v205 offset:13856
	s_waitcnt vmcnt(7)
	ds_write_b128 v215, v[218:221] offset:18432
	s_waitcnt vmcnt(6)
	ds_write_b128 v215, v[222:225] offset:55296
	ds_read_b128 v[218:221], v208 offset:64
	ds_read_b128 v[222:225], v208 offset:4672
	s_waitcnt lgkmcnt(5)
	v_mfma_f32_32x32x16_bf16 v[80:95], v[234:237], v[160:163], v[80:95]
	v_mfma_f32_32x32x16_bf16 v[16:31], v[234:237], v[164:167], v[16:31]
	ds_read_b128 v[234:237], v205 offset:64
	s_waitcnt lgkmcnt(5)
	v_mfma_f32_32x32x16_bf16 v[64:79], v[238:241], v[160:163], v[64:79]
	v_mfma_f32_32x32x16_bf16 v[0:15], v[238:241], v[164:167], v[0:15]
	ds_read_b128 v[238:241], v205 offset:4672
	s_setprio 0
	global_load_dwordx4 v[160:163], v[184:185], off offset:1920
	global_load_dwordx4 v[164:167], v[186:187], off offset:1920
	s_setprio 1
	s_waitcnt lgkmcnt(1)
	v_mfma_f32_32x32x16_bf16 v[112:127], v[234:237], v[218:221], v[112:127]
	v_mfma_f32_32x32x16_bf16 v[48:63], v[234:237], v[222:225], v[48:63]
	s_waitcnt lgkmcnt(0)
	v_mfma_f32_32x32x16_bf16 v[96:111], v[238:241], v[218:221], v[96:111]
	v_mfma_f32_32x32x16_bf16 v[32:47], v[238:241], v[222:225], v[32:47]
	ds_read_b128 v[234:237], v205 offset:9280
	ds_read_b128 v[238:241], v205 offset:13888
	s_waitcnt vmcnt(7)
	ds_write_b128 v215, v[226:229] offset:27648
	s_waitcnt vmcnt(6)
	ds_write_b128 v215, v[230:233] offset:64512
	ds_read_b128 v[226:229], v208 offset:96
	ds_read_b128 v[230:233], v208 offset:4704
	s_waitcnt lgkmcnt(5)
	v_mfma_f32_32x32x16_bf16 v[80:95], v[234:237], v[218:221], v[80:95]
	v_mfma_f32_32x32x16_bf16 v[16:31], v[234:237], v[222:225], v[16:31]
	ds_read_b128 v[234:237], v205 offset:96
	s_waitcnt lgkmcnt(5)
	v_mfma_f32_32x32x16_bf16 v[64:79], v[238:241], v[218:221], v[64:79]
	v_mfma_f32_32x32x16_bf16 v[0:15], v[238:241], v[222:225], v[0:15]
	ds_read_b128 v[238:241], v205 offset:4704
	s_setprio 0
	global_load_dwordx4 v[218:221], v[198:199], off offset:1920
	global_load_dwordx4 v[222:225], v[200:201], off offset:1920
	s_setprio 1
	s_waitcnt lgkmcnt(1)
	v_mfma_f32_32x32x16_bf16 v[112:127], v[234:237], v[226:229], v[112:127]
	v_mfma_f32_32x32x16_bf16 v[48:63], v[234:237], v[230:233], v[48:63]
	s_waitcnt lgkmcnt(0)
	v_mfma_f32_32x32x16_bf16 v[96:111], v[238:241], v[226:229], v[96:111]
	v_mfma_f32_32x32x16_bf16 v[32:47], v[238:241], v[230:233], v[32:47]
	ds_read_b128 v[234:237], v205 offset:9312
	ds_read_b128 v[238:241], v205 offset:13920
	s_waitcnt lgkmcnt(1)
	v_mfma_f32_32x32x16_bf16 v[80:95], v[234:237], v[226:229], v[80:95]
	v_mfma_f32_32x32x16_bf16 v[16:31], v[234:237], v[230:233], v[16:31]
	s_waitcnt lgkmcnt(0)
	v_mfma_f32_32x32x16_bf16 v[64:79], v[238:241], v[226:229], v[64:79]
	v_mfma_f32_32x32x16_bf16 v[0:15], v[238:241], v[230:233], v[0:15]
	s_setprio 0
	s_barrier
	global_load_dwordx4 v[226:229], v[190:191], off offset:2048
	global_load_dwordx4 v[230:233], v[188:189], off offset:2048
	s_waitcnt vmcnt(9)
	ds_write_b128 v209, v[176:179]
	s_waitcnt vmcnt(8)
	ds_write_b128 v210, v[180:183]
	ds_read_b128 v[176:179], v204 offset:36864
	ds_read_b128 v[180:183], v204 offset:41472
	ds_read_b128 v[234:237], v192
	ds_read_b128 v[238:241], v192 offset:4608
	s_setprio 1
	s_waitcnt lgkmcnt(1)
	v_mfma_f32_32x32x16_bf16 v[112:127], v[234:237], v[176:179], v[112:127]
	v_mfma_f32_32x32x16_bf16 v[48:63], v[234:237], v[180:183], v[48:63]
	s_waitcnt lgkmcnt(0)
	v_mfma_f32_32x32x16_bf16 v[96:111], v[238:241], v[176:179], v[96:111]
	v_mfma_f32_32x32x16_bf16 v[32:47], v[238:241], v[180:183], v[32:47]
	ds_read_b128 v[234:237], v192 offset:9216
	ds_read_b128 v[238:241], v192 offset:13824
	s_waitcnt vmcnt(7)
	ds_write_b128 v212, v[168:171]
	s_waitcnt vmcnt(6)
	ds_write_b128 v211, v[172:175]
	ds_read_b128 v[168:171], v204 offset:36896
	ds_read_b128 v[172:175], v204 offset:41504
	s_waitcnt lgkmcnt(5)
	v_mfma_f32_32x32x16_bf16 v[80:95], v[234:237], v[176:179], v[80:95]
	v_mfma_f32_32x32x16_bf16 v[16:31], v[234:237], v[180:183], v[16:31]
	ds_read_b128 v[234:237], v192 offset:32
	s_waitcnt lgkmcnt(5)
	v_mfma_f32_32x32x16_bf16 v[64:79], v[238:241], v[176:179], v[64:79]
	v_mfma_f32_32x32x16_bf16 v[0:15], v[238:241], v[180:183], v[0:15]
	ds_read_b128 v[238:241], v192 offset:4640
	s_setprio 0
	global_load_dwordx4 v[176:179], v[194:195], off offset:2048
	global_load_dwordx4 v[180:183], v[196:197], off offset:2048
	s_setprio 1
	s_waitcnt lgkmcnt(1)
	v_mfma_f32_32x32x16_bf16 v[112:127], v[234:237], v[168:171], v[112:127]
	v_mfma_f32_32x32x16_bf16 v[48:63], v[234:237], v[172:175], v[48:63]
	s_waitcnt lgkmcnt(0)
	v_mfma_f32_32x32x16_bf16 v[96:111], v[238:241], v[168:171], v[96:111]
	v_mfma_f32_32x32x16_bf16 v[32:47], v[238:241], v[172:175], v[32:47]
	ds_read_b128 v[234:237], v192 offset:9248
	ds_read_b128 v[238:241], v192 offset:13856
	s_waitcnt vmcnt(7)
	ds_write_b128 v214, v[160:163]
	s_waitcnt vmcnt(6)
	ds_write_b128 v213, v[164:167]
	ds_read_b128 v[160:163], v204 offset:36928
	ds_read_b128 v[164:167], v204 offset:41536
	s_waitcnt lgkmcnt(5)
	v_mfma_f32_32x32x16_bf16 v[80:95], v[234:237], v[168:171], v[80:95]
	v_mfma_f32_32x32x16_bf16 v[16:31], v[234:237], v[172:175], v[16:31]
	ds_read_b128 v[234:237], v192 offset:64
	s_waitcnt lgkmcnt(5)
	v_mfma_f32_32x32x16_bf16 v[64:79], v[238:241], v[168:171], v[64:79]
	v_mfma_f32_32x32x16_bf16 v[0:15], v[238:241], v[172:175], v[0:15]
	ds_read_b128 v[238:241], v192 offset:4672
	s_setprio 0
	global_load_dwordx4 v[168:171], v[184:185], off offset:2048
	global_load_dwordx4 v[172:175], v[186:187], off offset:2048
	s_setprio 1
	s_waitcnt lgkmcnt(1)
	v_mfma_f32_32x32x16_bf16 v[112:127], v[234:237], v[160:163], v[112:127]
	v_mfma_f32_32x32x16_bf16 v[48:63], v[234:237], v[164:167], v[48:63]
	s_waitcnt lgkmcnt(0)
	v_mfma_f32_32x32x16_bf16 v[96:111], v[238:241], v[160:163], v[96:111]
	v_mfma_f32_32x32x16_bf16 v[32:47], v[238:241], v[164:167], v[32:47]
	ds_read_b128 v[234:237], v192 offset:9280
	ds_read_b128 v[238:241], v192 offset:13888
	s_waitcnt vmcnt(7)
	ds_write_b128 v217, v[218:221]
	s_waitcnt vmcnt(6)
	ds_write_b128 v216, v[222:225]
	ds_read_b128 v[218:221], v204 offset:36960
	ds_read_b128 v[222:225], v204 offset:41568
	s_waitcnt lgkmcnt(5)
	v_mfma_f32_32x32x16_bf16 v[80:95], v[234:237], v[160:163], v[80:95]
	v_mfma_f32_32x32x16_bf16 v[16:31], v[234:237], v[164:167], v[16:31]
	ds_read_b128 v[234:237], v192 offset:96
	s_waitcnt lgkmcnt(5)
	v_mfma_f32_32x32x16_bf16 v[64:79], v[238:241], v[160:163], v[64:79]
	v_mfma_f32_32x32x16_bf16 v[0:15], v[238:241], v[164:167], v[0:15]
	ds_read_b128 v[238:241], v192 offset:4704
	s_setprio 0
	global_load_dwordx4 v[160:163], v[198:199], off offset:2048
	global_load_dwordx4 v[164:167], v[200:201], off offset:2048
	s_setprio 1
	s_waitcnt lgkmcnt(1)
	v_mfma_f32_32x32x16_bf16 v[112:127], v[234:237], v[218:221], v[112:127]
	v_mfma_f32_32x32x16_bf16 v[48:63], v[234:237], v[222:225], v[48:63]
	s_waitcnt lgkmcnt(0)
	v_mfma_f32_32x32x16_bf16 v[96:111], v[238:241], v[218:221], v[96:111]
	v_mfma_f32_32x32x16_bf16 v[32:47], v[238:241], v[222:225], v[32:47]
	ds_read_b128 v[234:237], v192 offset:9312
	ds_read_b128 v[238:241], v192 offset:13920
	s_waitcnt lgkmcnt(1)
	v_mfma_f32_32x32x16_bf16 v[80:95], v[234:237], v[218:221], v[80:95]
	v_mfma_f32_32x32x16_bf16 v[16:31], v[234:237], v[222:225], v[16:31]
	s_waitcnt lgkmcnt(0)
	v_mfma_f32_32x32x16_bf16 v[64:79], v[238:241], v[218:221], v[64:79]
	v_mfma_f32_32x32x16_bf16 v[0:15], v[238:241], v[222:225], v[0:15]
	s_setprio 0
	s_barrier
	global_load_dwordx4 v[218:221], v[190:191], off offset:2176
	global_load_dwordx4 v[222:225], v[188:189], off offset:2176
	s_waitcnt vmcnt(9)
	ds_write_b128 v215, v[226:229]
	s_waitcnt vmcnt(8)
	ds_write_b128 v215, v[230:233] offset:36864
	ds_read_b128 v[226:229], v208
	ds_read_b128 v[230:233], v208 offset:4608
	ds_read_b128 v[234:237], v205
	ds_read_b128 v[238:241], v205 offset:4608
	s_setprio 1
	s_waitcnt lgkmcnt(1)
	v_mfma_f32_32x32x16_bf16 v[112:127], v[234:237], v[226:229], v[112:127]
	v_mfma_f32_32x32x16_bf16 v[48:63], v[234:237], v[230:233], v[48:63]
	s_waitcnt lgkmcnt(0)
	v_mfma_f32_32x32x16_bf16 v[96:111], v[238:241], v[226:229], v[96:111]
	v_mfma_f32_32x32x16_bf16 v[32:47], v[238:241], v[230:233], v[32:47]
	ds_read_b128 v[234:237], v205 offset:9216
	ds_read_b128 v[238:241], v205 offset:13824
	s_waitcnt vmcnt(7)
	ds_write_b128 v215, v[176:179] offset:9216
	s_waitcnt vmcnt(6)
	ds_write_b128 v215, v[180:183] offset:46080
	ds_read_b128 v[176:179], v208 offset:32
	ds_read_b128 v[180:183], v208 offset:4640
	s_waitcnt lgkmcnt(5)
	v_mfma_f32_32x32x16_bf16 v[80:95], v[234:237], v[226:229], v[80:95]
	v_mfma_f32_32x32x16_bf16 v[16:31], v[234:237], v[230:233], v[16:31]
	ds_read_b128 v[234:237], v205 offset:32
	s_waitcnt lgkmcnt(5)
	v_mfma_f32_32x32x16_bf16 v[64:79], v[238:241], v[226:229], v[64:79]
	v_mfma_f32_32x32x16_bf16 v[0:15], v[238:241], v[230:233], v[0:15]
	ds_read_b128 v[238:241], v205 offset:4640
	s_setprio 0
	global_load_dwordx4 v[226:229], v[194:195], off offset:2176
	global_load_dwordx4 v[230:233], v[196:197], off offset:2176
	s_setprio 1
	s_waitcnt lgkmcnt(1)
	v_mfma_f32_32x32x16_bf16 v[112:127], v[234:237], v[176:179], v[112:127]
	v_mfma_f32_32x32x16_bf16 v[48:63], v[234:237], v[180:183], v[48:63]
	s_waitcnt lgkmcnt(0)
	v_mfma_f32_32x32x16_bf16 v[96:111], v[238:241], v[176:179], v[96:111]
	v_mfma_f32_32x32x16_bf16 v[32:47], v[238:241], v[180:183], v[32:47]
	ds_read_b128 v[234:237], v205 offset:9248
	ds_read_b128 v[238:241], v205 offset:13856
	s_waitcnt vmcnt(7)
	ds_write_b128 v215, v[168:171] offset:18432
	s_waitcnt vmcnt(6)
	ds_write_b128 v215, v[172:175] offset:55296
	ds_read_b128 v[168:171], v208 offset:64
	ds_read_b128 v[172:175], v208 offset:4672
	s_waitcnt lgkmcnt(5)
	v_mfma_f32_32x32x16_bf16 v[80:95], v[234:237], v[176:179], v[80:95]
	v_mfma_f32_32x32x16_bf16 v[16:31], v[234:237], v[180:183], v[16:31]
	ds_read_b128 v[234:237], v205 offset:64
	s_waitcnt lgkmcnt(5)
	v_mfma_f32_32x32x16_bf16 v[64:79], v[238:241], v[176:179], v[64:79]
	v_mfma_f32_32x32x16_bf16 v[0:15], v[238:241], v[180:183], v[0:15]
	ds_read_b128 v[238:241], v205 offset:4672
	s_setprio 0
	global_load_dwordx4 v[176:179], v[184:185], off offset:2176
	global_load_dwordx4 v[180:183], v[186:187], off offset:2176
	s_setprio 1
	s_waitcnt lgkmcnt(1)
	v_mfma_f32_32x32x16_bf16 v[112:127], v[234:237], v[168:171], v[112:127]
	v_mfma_f32_32x32x16_bf16 v[48:63], v[234:237], v[172:175], v[48:63]
	s_waitcnt lgkmcnt(0)
	v_mfma_f32_32x32x16_bf16 v[96:111], v[238:241], v[168:171], v[96:111]
	v_mfma_f32_32x32x16_bf16 v[32:47], v[238:241], v[172:175], v[32:47]
	ds_read_b128 v[234:237], v205 offset:9280
	ds_read_b128 v[238:241], v205 offset:13888
	s_waitcnt vmcnt(7)
	ds_write_b128 v215, v[160:163] offset:27648
	s_waitcnt vmcnt(6)
	ds_write_b128 v215, v[164:167] offset:64512
	ds_read_b128 v[160:163], v208 offset:96
	ds_read_b128 v[164:167], v208 offset:4704
	s_waitcnt lgkmcnt(5)
	v_mfma_f32_32x32x16_bf16 v[80:95], v[234:237], v[168:171], v[80:95]
	v_mfma_f32_32x32x16_bf16 v[16:31], v[234:237], v[172:175], v[16:31]
	ds_read_b128 v[234:237], v205 offset:96
	s_waitcnt lgkmcnt(5)
	v_mfma_f32_32x32x16_bf16 v[64:79], v[238:241], v[168:171], v[64:79]
	v_mfma_f32_32x32x16_bf16 v[0:15], v[238:241], v[172:175], v[0:15]
	ds_read_b128 v[238:241], v205 offset:4704
	s_setprio 0
	global_load_dwordx4 v[168:171], v[198:199], off offset:2176
	global_load_dwordx4 v[172:175], v[200:201], off offset:2176
	s_setprio 1
	s_waitcnt lgkmcnt(1)
	v_mfma_f32_32x32x16_bf16 v[112:127], v[234:237], v[160:163], v[112:127]
	v_mfma_f32_32x32x16_bf16 v[48:63], v[234:237], v[164:167], v[48:63]
	s_waitcnt lgkmcnt(0)
	v_mfma_f32_32x32x16_bf16 v[96:111], v[238:241], v[160:163], v[96:111]
	v_mfma_f32_32x32x16_bf16 v[32:47], v[238:241], v[164:167], v[32:47]
	ds_read_b128 v[234:237], v205 offset:9312
	ds_read_b128 v[238:241], v205 offset:13920
	s_waitcnt lgkmcnt(1)
	v_mfma_f32_32x32x16_bf16 v[80:95], v[234:237], v[160:163], v[80:95]
	v_mfma_f32_32x32x16_bf16 v[16:31], v[234:237], v[164:167], v[16:31]
	s_waitcnt lgkmcnt(0)
	v_mfma_f32_32x32x16_bf16 v[64:79], v[238:241], v[160:163], v[64:79]
	v_mfma_f32_32x32x16_bf16 v[0:15], v[238:241], v[164:167], v[0:15]
	s_setprio 0
	s_barrier
	global_load_dwordx4 v[160:163], v[190:191], off offset:2304
	global_load_dwordx4 v[164:167], v[188:189], off offset:2304
	s_waitcnt vmcnt(9)
	ds_write_b128 v209, v[218:221]
	s_waitcnt vmcnt(8)
	ds_write_b128 v210, v[222:225]
	ds_read_b128 v[218:221], v204 offset:36864
	ds_read_b128 v[222:225], v204 offset:41472
	ds_read_b128 v[234:237], v192
	ds_read_b128 v[238:241], v192 offset:4608
	s_setprio 1
	s_waitcnt lgkmcnt(1)
	v_mfma_f32_32x32x16_bf16 v[112:127], v[234:237], v[218:221], v[112:127]
	v_mfma_f32_32x32x16_bf16 v[48:63], v[234:237], v[222:225], v[48:63]
	s_waitcnt lgkmcnt(0)
	v_mfma_f32_32x32x16_bf16 v[96:111], v[238:241], v[218:221], v[96:111]
	v_mfma_f32_32x32x16_bf16 v[32:47], v[238:241], v[222:225], v[32:47]
	ds_read_b128 v[234:237], v192 offset:9216
	ds_read_b128 v[238:241], v192 offset:13824
	s_waitcnt vmcnt(7)
	ds_write_b128 v212, v[226:229]
	s_waitcnt vmcnt(6)
	ds_write_b128 v211, v[230:233]
	ds_read_b128 v[226:229], v204 offset:36896
	ds_read_b128 v[230:233], v204 offset:41504
	s_waitcnt lgkmcnt(5)
	v_mfma_f32_32x32x16_bf16 v[80:95], v[234:237], v[218:221], v[80:95]
	v_mfma_f32_32x32x16_bf16 v[16:31], v[234:237], v[222:225], v[16:31]
	ds_read_b128 v[234:237], v192 offset:32
	s_waitcnt lgkmcnt(5)
	v_mfma_f32_32x32x16_bf16 v[64:79], v[238:241], v[218:221], v[64:79]
	v_mfma_f32_32x32x16_bf16 v[0:15], v[238:241], v[222:225], v[0:15]
	ds_read_b128 v[238:241], v192 offset:4640
	s_setprio 0
	global_load_dwordx4 v[218:221], v[194:195], off offset:2304
	global_load_dwordx4 v[222:225], v[196:197], off offset:2304
	s_setprio 1
	s_waitcnt lgkmcnt(1)
	v_mfma_f32_32x32x16_bf16 v[112:127], v[234:237], v[226:229], v[112:127]
	v_mfma_f32_32x32x16_bf16 v[48:63], v[234:237], v[230:233], v[48:63]
	s_waitcnt lgkmcnt(0)
	v_mfma_f32_32x32x16_bf16 v[96:111], v[238:241], v[226:229], v[96:111]
	v_mfma_f32_32x32x16_bf16 v[32:47], v[238:241], v[230:233], v[32:47]
	ds_read_b128 v[234:237], v192 offset:9248
	ds_read_b128 v[238:241], v192 offset:13856
	s_waitcnt vmcnt(7)
	ds_write_b128 v214, v[176:179]
	s_waitcnt vmcnt(6)
	ds_write_b128 v213, v[180:183]
	ds_read_b128 v[176:179], v204 offset:36928
	ds_read_b128 v[180:183], v204 offset:41536
	s_waitcnt lgkmcnt(5)
	v_mfma_f32_32x32x16_bf16 v[80:95], v[234:237], v[226:229], v[80:95]
	v_mfma_f32_32x32x16_bf16 v[16:31], v[234:237], v[230:233], v[16:31]
	ds_read_b128 v[234:237], v192 offset:64
	s_waitcnt lgkmcnt(5)
	v_mfma_f32_32x32x16_bf16 v[64:79], v[238:241], v[226:229], v[64:79]
	v_mfma_f32_32x32x16_bf16 v[0:15], v[238:241], v[230:233], v[0:15]
	ds_read_b128 v[238:241], v192 offset:4672
	s_setprio 0
	global_load_dwordx4 v[226:229], v[184:185], off offset:2304
	global_load_dwordx4 v[230:233], v[186:187], off offset:2304
	s_setprio 1
	s_waitcnt lgkmcnt(1)
	v_mfma_f32_32x32x16_bf16 v[112:127], v[234:237], v[176:179], v[112:127]
	v_mfma_f32_32x32x16_bf16 v[48:63], v[234:237], v[180:183], v[48:63]
	s_waitcnt lgkmcnt(0)
	v_mfma_f32_32x32x16_bf16 v[96:111], v[238:241], v[176:179], v[96:111]
	v_mfma_f32_32x32x16_bf16 v[32:47], v[238:241], v[180:183], v[32:47]
	ds_read_b128 v[234:237], v192 offset:9280
	ds_read_b128 v[238:241], v192 offset:13888
	s_waitcnt vmcnt(7)
	ds_write_b128 v217, v[168:171]
	s_waitcnt vmcnt(6)
	ds_write_b128 v216, v[172:175]
	ds_read_b128 v[168:171], v204 offset:36960
	ds_read_b128 v[172:175], v204 offset:41568
	s_waitcnt lgkmcnt(5)
	v_mfma_f32_32x32x16_bf16 v[80:95], v[234:237], v[176:179], v[80:95]
	v_mfma_f32_32x32x16_bf16 v[16:31], v[234:237], v[180:183], v[16:31]
	ds_read_b128 v[234:237], v192 offset:96
	s_waitcnt lgkmcnt(5)
	v_mfma_f32_32x32x16_bf16 v[64:79], v[238:241], v[176:179], v[64:79]
	v_mfma_f32_32x32x16_bf16 v[0:15], v[238:241], v[180:183], v[0:15]
	ds_read_b128 v[238:241], v192 offset:4704
	s_setprio 0
	global_load_dwordx4 v[176:179], v[198:199], off offset:2304
	global_load_dwordx4 v[180:183], v[200:201], off offset:2304
	s_setprio 1
	s_waitcnt lgkmcnt(1)
	v_mfma_f32_32x32x16_bf16 v[112:127], v[234:237], v[168:171], v[112:127]
	v_mfma_f32_32x32x16_bf16 v[48:63], v[234:237], v[172:175], v[48:63]
	s_waitcnt lgkmcnt(0)
	v_mfma_f32_32x32x16_bf16 v[96:111], v[238:241], v[168:171], v[96:111]
	v_mfma_f32_32x32x16_bf16 v[32:47], v[238:241], v[172:175], v[32:47]
	ds_read_b128 v[234:237], v192 offset:9312
	ds_read_b128 v[238:241], v192 offset:13920
	s_waitcnt lgkmcnt(1)
	v_mfma_f32_32x32x16_bf16 v[80:95], v[234:237], v[168:171], v[80:95]
	v_mfma_f32_32x32x16_bf16 v[16:31], v[234:237], v[172:175], v[16:31]
	s_waitcnt lgkmcnt(0)
	v_mfma_f32_32x32x16_bf16 v[64:79], v[238:241], v[168:171], v[64:79]
	v_mfma_f32_32x32x16_bf16 v[0:15], v[238:241], v[172:175], v[0:15]
	s_setprio 0
	s_barrier
	global_load_dwordx4 v[168:171], v[190:191], off offset:2432
	global_load_dwordx4 v[172:175], v[188:189], off offset:2432
	s_waitcnt vmcnt(9)
	ds_write_b128 v215, v[160:163]
	s_waitcnt vmcnt(8)
	ds_write_b128 v215, v[164:167] offset:36864
	ds_read_b128 v[160:163], v208
	ds_read_b128 v[164:167], v208 offset:4608
	ds_read_b128 v[234:237], v205
	ds_read_b128 v[238:241], v205 offset:4608
	s_setprio 1
	s_waitcnt lgkmcnt(1)
	v_mfma_f32_32x32x16_bf16 v[112:127], v[234:237], v[160:163], v[112:127]
	v_mfma_f32_32x32x16_bf16 v[48:63], v[234:237], v[164:167], v[48:63]
	s_waitcnt lgkmcnt(0)
	v_mfma_f32_32x32x16_bf16 v[96:111], v[238:241], v[160:163], v[96:111]
	v_mfma_f32_32x32x16_bf16 v[32:47], v[238:241], v[164:167], v[32:47]
	ds_read_b128 v[234:237], v205 offset:9216
	ds_read_b128 v[238:241], v205 offset:13824
	s_waitcnt vmcnt(7)
	ds_write_b128 v215, v[218:221] offset:9216
	s_waitcnt vmcnt(6)
	ds_write_b128 v215, v[222:225] offset:46080
	ds_read_b128 v[218:221], v208 offset:32
	ds_read_b128 v[222:225], v208 offset:4640
	s_waitcnt lgkmcnt(5)
	v_mfma_f32_32x32x16_bf16 v[80:95], v[234:237], v[160:163], v[80:95]
	v_mfma_f32_32x32x16_bf16 v[16:31], v[234:237], v[164:167], v[16:31]
	ds_read_b128 v[234:237], v205 offset:32
	s_waitcnt lgkmcnt(5)
	v_mfma_f32_32x32x16_bf16 v[64:79], v[238:241], v[160:163], v[64:79]
	v_mfma_f32_32x32x16_bf16 v[0:15], v[238:241], v[164:167], v[0:15]
	ds_read_b128 v[238:241], v205 offset:4640
	s_setprio 0
	global_load_dwordx4 v[160:163], v[194:195], off offset:2432
	global_load_dwordx4 v[164:167], v[196:197], off offset:2432
	s_setprio 1
	s_waitcnt lgkmcnt(1)
	v_mfma_f32_32x32x16_bf16 v[112:127], v[234:237], v[218:221], v[112:127]
	v_mfma_f32_32x32x16_bf16 v[48:63], v[234:237], v[222:225], v[48:63]
	s_waitcnt lgkmcnt(0)
	v_mfma_f32_32x32x16_bf16 v[96:111], v[238:241], v[218:221], v[96:111]
	v_mfma_f32_32x32x16_bf16 v[32:47], v[238:241], v[222:225], v[32:47]
	ds_read_b128 v[234:237], v205 offset:9248
	ds_read_b128 v[238:241], v205 offset:13856
	s_waitcnt vmcnt(7)
	ds_write_b128 v215, v[226:229] offset:18432
	s_waitcnt vmcnt(6)
	ds_write_b128 v215, v[230:233] offset:55296
	ds_read_b128 v[226:229], v208 offset:64
	ds_read_b128 v[230:233], v208 offset:4672
	s_waitcnt lgkmcnt(5)
	v_mfma_f32_32x32x16_bf16 v[80:95], v[234:237], v[218:221], v[80:95]
	v_mfma_f32_32x32x16_bf16 v[16:31], v[234:237], v[222:225], v[16:31]
	ds_read_b128 v[234:237], v205 offset:64
	s_waitcnt lgkmcnt(5)
	v_mfma_f32_32x32x16_bf16 v[64:79], v[238:241], v[218:221], v[64:79]
	v_mfma_f32_32x32x16_bf16 v[0:15], v[238:241], v[222:225], v[0:15]
	ds_read_b128 v[238:241], v205 offset:4672
	s_setprio 0
	global_load_dwordx4 v[218:221], v[184:185], off offset:2432
	global_load_dwordx4 v[222:225], v[186:187], off offset:2432
	s_setprio 1
	s_waitcnt lgkmcnt(1)
	v_mfma_f32_32x32x16_bf16 v[112:127], v[234:237], v[226:229], v[112:127]
	v_mfma_f32_32x32x16_bf16 v[48:63], v[234:237], v[230:233], v[48:63]
	s_waitcnt lgkmcnt(0)
	v_mfma_f32_32x32x16_bf16 v[96:111], v[238:241], v[226:229], v[96:111]
	v_mfma_f32_32x32x16_bf16 v[32:47], v[238:241], v[230:233], v[32:47]
	ds_read_b128 v[234:237], v205 offset:9280
	ds_read_b128 v[238:241], v205 offset:13888
	s_waitcnt vmcnt(7)
	ds_write_b128 v215, v[176:179] offset:27648
	s_waitcnt vmcnt(6)
	ds_write_b128 v215, v[180:183] offset:64512
	ds_read_b128 v[176:179], v208 offset:96
	ds_read_b128 v[180:183], v208 offset:4704
	s_waitcnt lgkmcnt(5)
	v_mfma_f32_32x32x16_bf16 v[80:95], v[234:237], v[226:229], v[80:95]
	v_mfma_f32_32x32x16_bf16 v[16:31], v[234:237], v[230:233], v[16:31]
	ds_read_b128 v[234:237], v205 offset:96
	s_waitcnt lgkmcnt(5)
	v_mfma_f32_32x32x16_bf16 v[64:79], v[238:241], v[226:229], v[64:79]
	v_mfma_f32_32x32x16_bf16 v[0:15], v[238:241], v[230:233], v[0:15]
	ds_read_b128 v[238:241], v205 offset:4704
	s_setprio 0
	global_load_dwordx4 v[226:229], v[198:199], off offset:2432
	global_load_dwordx4 v[230:233], v[200:201], off offset:2432
	s_setprio 1
	s_waitcnt lgkmcnt(1)
	v_mfma_f32_32x32x16_bf16 v[112:127], v[234:237], v[176:179], v[112:127]
	v_mfma_f32_32x32x16_bf16 v[48:63], v[234:237], v[180:183], v[48:63]
	s_waitcnt lgkmcnt(0)
	v_mfma_f32_32x32x16_bf16 v[96:111], v[238:241], v[176:179], v[96:111]
	v_mfma_f32_32x32x16_bf16 v[32:47], v[238:241], v[180:183], v[32:47]
	ds_read_b128 v[234:237], v205 offset:9312
	ds_read_b128 v[238:241], v205 offset:13920
	s_waitcnt lgkmcnt(1)
	v_mfma_f32_32x32x16_bf16 v[80:95], v[234:237], v[176:179], v[80:95]
	v_mfma_f32_32x32x16_bf16 v[16:31], v[234:237], v[180:183], v[16:31]
	s_waitcnt lgkmcnt(0)
	v_mfma_f32_32x32x16_bf16 v[64:79], v[238:241], v[176:179], v[64:79]
	v_mfma_f32_32x32x16_bf16 v[0:15], v[238:241], v[180:183], v[0:15]
	s_setprio 0
	s_barrier
	global_load_dwordx4 v[176:179], v[190:191], off offset:2560
	global_load_dwordx4 v[180:183], v[188:189], off offset:2560
	s_waitcnt vmcnt(9)
	ds_write_b128 v209, v[168:171]
	s_waitcnt vmcnt(8)
	ds_write_b128 v210, v[172:175]
	ds_read_b128 v[168:171], v204 offset:36864
	ds_read_b128 v[172:175], v204 offset:41472
	ds_read_b128 v[234:237], v192
	ds_read_b128 v[238:241], v192 offset:4608
	s_setprio 1
	s_waitcnt lgkmcnt(1)
	v_mfma_f32_32x32x16_bf16 v[112:127], v[234:237], v[168:171], v[112:127]
	v_mfma_f32_32x32x16_bf16 v[48:63], v[234:237], v[172:175], v[48:63]
	s_waitcnt lgkmcnt(0)
	v_mfma_f32_32x32x16_bf16 v[96:111], v[238:241], v[168:171], v[96:111]
	v_mfma_f32_32x32x16_bf16 v[32:47], v[238:241], v[172:175], v[32:47]
	ds_read_b128 v[234:237], v192 offset:9216
	ds_read_b128 v[238:241], v192 offset:13824
	s_waitcnt vmcnt(7)
	ds_write_b128 v212, v[160:163]
	s_waitcnt vmcnt(6)
	ds_write_b128 v211, v[164:167]
	ds_read_b128 v[160:163], v204 offset:36896
	ds_read_b128 v[164:167], v204 offset:41504
	s_waitcnt lgkmcnt(5)
	v_mfma_f32_32x32x16_bf16 v[80:95], v[234:237], v[168:171], v[80:95]
	v_mfma_f32_32x32x16_bf16 v[16:31], v[234:237], v[172:175], v[16:31]
	ds_read_b128 v[234:237], v192 offset:32
	s_waitcnt lgkmcnt(5)
	v_mfma_f32_32x32x16_bf16 v[64:79], v[238:241], v[168:171], v[64:79]
	v_mfma_f32_32x32x16_bf16 v[0:15], v[238:241], v[172:175], v[0:15]
	ds_read_b128 v[238:241], v192 offset:4640
	s_setprio 0
	global_load_dwordx4 v[168:171], v[194:195], off offset:2560
	global_load_dwordx4 v[172:175], v[196:197], off offset:2560
	s_setprio 1
	s_waitcnt lgkmcnt(1)
	v_mfma_f32_32x32x16_bf16 v[112:127], v[234:237], v[160:163], v[112:127]
	v_mfma_f32_32x32x16_bf16 v[48:63], v[234:237], v[164:167], v[48:63]
	s_waitcnt lgkmcnt(0)
	v_mfma_f32_32x32x16_bf16 v[96:111], v[238:241], v[160:163], v[96:111]
	v_mfma_f32_32x32x16_bf16 v[32:47], v[238:241], v[164:167], v[32:47]
	ds_read_b128 v[234:237], v192 offset:9248
	ds_read_b128 v[238:241], v192 offset:13856
	s_waitcnt vmcnt(7)
	ds_write_b128 v214, v[218:221]
	s_waitcnt vmcnt(6)
	ds_write_b128 v213, v[222:225]
	ds_read_b128 v[218:221], v204 offset:36928
	ds_read_b128 v[222:225], v204 offset:41536
	s_waitcnt lgkmcnt(5)
	v_mfma_f32_32x32x16_bf16 v[80:95], v[234:237], v[160:163], v[80:95]
	v_mfma_f32_32x32x16_bf16 v[16:31], v[234:237], v[164:167], v[16:31]
	ds_read_b128 v[234:237], v192 offset:64
	s_waitcnt lgkmcnt(5)
	v_mfma_f32_32x32x16_bf16 v[64:79], v[238:241], v[160:163], v[64:79]
	v_mfma_f32_32x32x16_bf16 v[0:15], v[238:241], v[164:167], v[0:15]
	ds_read_b128 v[238:241], v192 offset:4672
	s_setprio 0
	global_load_dwordx4 v[160:163], v[184:185], off offset:2560
	global_load_dwordx4 v[164:167], v[186:187], off offset:2560
	s_setprio 1
	s_waitcnt lgkmcnt(1)
	v_mfma_f32_32x32x16_bf16 v[112:127], v[234:237], v[218:221], v[112:127]
	v_mfma_f32_32x32x16_bf16 v[48:63], v[234:237], v[222:225], v[48:63]
	s_waitcnt lgkmcnt(0)
	v_mfma_f32_32x32x16_bf16 v[96:111], v[238:241], v[218:221], v[96:111]
	v_mfma_f32_32x32x16_bf16 v[32:47], v[238:241], v[222:225], v[32:47]
	ds_read_b128 v[234:237], v192 offset:9280
	ds_read_b128 v[238:241], v192 offset:13888
	s_waitcnt vmcnt(7)
	ds_write_b128 v217, v[226:229]
	s_waitcnt vmcnt(6)
	ds_write_b128 v216, v[230:233]
	ds_read_b128 v[226:229], v204 offset:36960
	ds_read_b128 v[230:233], v204 offset:41568
	s_waitcnt lgkmcnt(5)
	v_mfma_f32_32x32x16_bf16 v[80:95], v[234:237], v[218:221], v[80:95]
	v_mfma_f32_32x32x16_bf16 v[16:31], v[234:237], v[222:225], v[16:31]
	ds_read_b128 v[234:237], v192 offset:96
	s_waitcnt lgkmcnt(5)
	v_mfma_f32_32x32x16_bf16 v[64:79], v[238:241], v[218:221], v[64:79]
	v_mfma_f32_32x32x16_bf16 v[0:15], v[238:241], v[222:225], v[0:15]
	ds_read_b128 v[238:241], v192 offset:4704
	s_setprio 0
	global_load_dwordx4 v[218:221], v[198:199], off offset:2560
	global_load_dwordx4 v[222:225], v[200:201], off offset:2560
	s_setprio 1
	s_waitcnt lgkmcnt(1)
	v_mfma_f32_32x32x16_bf16 v[112:127], v[234:237], v[226:229], v[112:127]
	v_mfma_f32_32x32x16_bf16 v[48:63], v[234:237], v[230:233], v[48:63]
	s_waitcnt lgkmcnt(0)
	v_mfma_f32_32x32x16_bf16 v[96:111], v[238:241], v[226:229], v[96:111]
	v_mfma_f32_32x32x16_bf16 v[32:47], v[238:241], v[230:233], v[32:47]
	ds_read_b128 v[234:237], v192 offset:9312
	ds_read_b128 v[238:241], v192 offset:13920
	s_waitcnt lgkmcnt(1)
	v_mfma_f32_32x32x16_bf16 v[80:95], v[234:237], v[226:229], v[80:95]
	v_mfma_f32_32x32x16_bf16 v[16:31], v[234:237], v[230:233], v[16:31]
	s_waitcnt lgkmcnt(0)
	v_mfma_f32_32x32x16_bf16 v[64:79], v[238:241], v[226:229], v[64:79]
	v_mfma_f32_32x32x16_bf16 v[0:15], v[238:241], v[230:233], v[0:15]
	s_setprio 0
	s_barrier
	global_load_dwordx4 v[226:229], v[190:191], off offset:2688
	global_load_dwordx4 v[230:233], v[188:189], off offset:2688
	s_waitcnt vmcnt(9)
	ds_write_b128 v215, v[176:179]
	s_waitcnt vmcnt(8)
	ds_write_b128 v215, v[180:183] offset:36864
	ds_read_b128 v[176:179], v208
	ds_read_b128 v[180:183], v208 offset:4608
	ds_read_b128 v[234:237], v205
	ds_read_b128 v[238:241], v205 offset:4608
	s_setprio 1
	s_waitcnt lgkmcnt(1)
	v_mfma_f32_32x32x16_bf16 v[112:127], v[234:237], v[176:179], v[112:127]
	v_mfma_f32_32x32x16_bf16 v[48:63], v[234:237], v[180:183], v[48:63]
	s_waitcnt lgkmcnt(0)
	v_mfma_f32_32x32x16_bf16 v[96:111], v[238:241], v[176:179], v[96:111]
	v_mfma_f32_32x32x16_bf16 v[32:47], v[238:241], v[180:183], v[32:47]
	ds_read_b128 v[234:237], v205 offset:9216
	ds_read_b128 v[238:241], v205 offset:13824
	s_waitcnt vmcnt(7)
	ds_write_b128 v215, v[168:171] offset:9216
	s_waitcnt vmcnt(6)
	ds_write_b128 v215, v[172:175] offset:46080
	ds_read_b128 v[168:171], v208 offset:32
	ds_read_b128 v[172:175], v208 offset:4640
	s_waitcnt lgkmcnt(5)
	v_mfma_f32_32x32x16_bf16 v[80:95], v[234:237], v[176:179], v[80:95]
	v_mfma_f32_32x32x16_bf16 v[16:31], v[234:237], v[180:183], v[16:31]
	ds_read_b128 v[234:237], v205 offset:32
	s_waitcnt lgkmcnt(5)
	v_mfma_f32_32x32x16_bf16 v[64:79], v[238:241], v[176:179], v[64:79]
	v_mfma_f32_32x32x16_bf16 v[0:15], v[238:241], v[180:183], v[0:15]
	ds_read_b128 v[238:241], v205 offset:4640
	s_setprio 0
	global_load_dwordx4 v[176:179], v[194:195], off offset:2688
	global_load_dwordx4 v[180:183], v[196:197], off offset:2688
	s_setprio 1
	s_waitcnt lgkmcnt(1)
	v_mfma_f32_32x32x16_bf16 v[112:127], v[234:237], v[168:171], v[112:127]
	v_mfma_f32_32x32x16_bf16 v[48:63], v[234:237], v[172:175], v[48:63]
	s_waitcnt lgkmcnt(0)
	v_mfma_f32_32x32x16_bf16 v[96:111], v[238:241], v[168:171], v[96:111]
	v_mfma_f32_32x32x16_bf16 v[32:47], v[238:241], v[172:175], v[32:47]
	ds_read_b128 v[234:237], v205 offset:9248
	ds_read_b128 v[238:241], v205 offset:13856
	s_waitcnt vmcnt(7)
	ds_write_b128 v215, v[160:163] offset:18432
	s_waitcnt vmcnt(6)
	ds_write_b128 v215, v[164:167] offset:55296
	ds_read_b128 v[160:163], v208 offset:64
	ds_read_b128 v[164:167], v208 offset:4672
	s_waitcnt lgkmcnt(5)
	v_mfma_f32_32x32x16_bf16 v[80:95], v[234:237], v[168:171], v[80:95]
	v_mfma_f32_32x32x16_bf16 v[16:31], v[234:237], v[172:175], v[16:31]
	ds_read_b128 v[234:237], v205 offset:64
	s_waitcnt lgkmcnt(5)
	v_mfma_f32_32x32x16_bf16 v[64:79], v[238:241], v[168:171], v[64:79]
	v_mfma_f32_32x32x16_bf16 v[0:15], v[238:241], v[172:175], v[0:15]
	ds_read_b128 v[238:241], v205 offset:4672
	s_setprio 0
	global_load_dwordx4 v[168:171], v[184:185], off offset:2688
	global_load_dwordx4 v[172:175], v[186:187], off offset:2688
	s_setprio 1
	s_waitcnt lgkmcnt(1)
	v_mfma_f32_32x32x16_bf16 v[112:127], v[234:237], v[160:163], v[112:127]
	v_mfma_f32_32x32x16_bf16 v[48:63], v[234:237], v[164:167], v[48:63]
	s_waitcnt lgkmcnt(0)
	v_mfma_f32_32x32x16_bf16 v[96:111], v[238:241], v[160:163], v[96:111]
	v_mfma_f32_32x32x16_bf16 v[32:47], v[238:241], v[164:167], v[32:47]
	ds_read_b128 v[234:237], v205 offset:9280
	ds_read_b128 v[238:241], v205 offset:13888
	s_waitcnt vmcnt(7)
	ds_write_b128 v215, v[218:221] offset:27648
	s_waitcnt vmcnt(6)
	ds_write_b128 v215, v[222:225] offset:64512
	ds_read_b128 v[218:221], v208 offset:96
	ds_read_b128 v[222:225], v208 offset:4704
	s_waitcnt lgkmcnt(5)
	v_mfma_f32_32x32x16_bf16 v[80:95], v[234:237], v[160:163], v[80:95]
	v_mfma_f32_32x32x16_bf16 v[16:31], v[234:237], v[164:167], v[16:31]
	ds_read_b128 v[234:237], v205 offset:96
	s_waitcnt lgkmcnt(5)
	v_mfma_f32_32x32x16_bf16 v[64:79], v[238:241], v[160:163], v[64:79]
	v_mfma_f32_32x32x16_bf16 v[0:15], v[238:241], v[164:167], v[0:15]
	ds_read_b128 v[238:241], v205 offset:4704
	s_setprio 0
	global_load_dwordx4 v[160:163], v[198:199], off offset:2688
	global_load_dwordx4 v[164:167], v[200:201], off offset:2688
	s_setprio 1
	s_waitcnt lgkmcnt(1)
	v_mfma_f32_32x32x16_bf16 v[112:127], v[234:237], v[218:221], v[112:127]
	v_mfma_f32_32x32x16_bf16 v[48:63], v[234:237], v[222:225], v[48:63]
	s_waitcnt lgkmcnt(0)
	v_mfma_f32_32x32x16_bf16 v[96:111], v[238:241], v[218:221], v[96:111]
	v_mfma_f32_32x32x16_bf16 v[32:47], v[238:241], v[222:225], v[32:47]
	ds_read_b128 v[234:237], v205 offset:9312
	ds_read_b128 v[238:241], v205 offset:13920
	s_waitcnt lgkmcnt(1)
	v_mfma_f32_32x32x16_bf16 v[80:95], v[234:237], v[218:221], v[80:95]
	v_mfma_f32_32x32x16_bf16 v[16:31], v[234:237], v[222:225], v[16:31]
	s_waitcnt lgkmcnt(0)
	v_mfma_f32_32x32x16_bf16 v[64:79], v[238:241], v[218:221], v[64:79]
	v_mfma_f32_32x32x16_bf16 v[0:15], v[238:241], v[222:225], v[0:15]
	s_setprio 0
	s_barrier
	global_load_dwordx4 v[218:221], v[190:191], off offset:2816
	global_load_dwordx4 v[222:225], v[188:189], off offset:2816
	s_waitcnt vmcnt(9)
	ds_write_b128 v209, v[226:229]
	s_waitcnt vmcnt(8)
	ds_write_b128 v210, v[230:233]
	ds_read_b128 v[226:229], v204 offset:36864
	ds_read_b128 v[230:233], v204 offset:41472
	ds_read_b128 v[234:237], v192
	ds_read_b128 v[238:241], v192 offset:4608
	s_setprio 1
	s_waitcnt lgkmcnt(1)
	v_mfma_f32_32x32x16_bf16 v[112:127], v[234:237], v[226:229], v[112:127]
	v_mfma_f32_32x32x16_bf16 v[48:63], v[234:237], v[230:233], v[48:63]
	s_waitcnt lgkmcnt(0)
	v_mfma_f32_32x32x16_bf16 v[96:111], v[238:241], v[226:229], v[96:111]
	v_mfma_f32_32x32x16_bf16 v[32:47], v[238:241], v[230:233], v[32:47]
	ds_read_b128 v[234:237], v192 offset:9216
	ds_read_b128 v[238:241], v192 offset:13824
	s_waitcnt vmcnt(7)
	ds_write_b128 v212, v[176:179]
	s_waitcnt vmcnt(6)
	ds_write_b128 v211, v[180:183]
	ds_read_b128 v[176:179], v204 offset:36896
	ds_read_b128 v[180:183], v204 offset:41504
	s_waitcnt lgkmcnt(5)
	v_mfma_f32_32x32x16_bf16 v[80:95], v[234:237], v[226:229], v[80:95]
	v_mfma_f32_32x32x16_bf16 v[16:31], v[234:237], v[230:233], v[16:31]
	ds_read_b128 v[234:237], v192 offset:32
	s_waitcnt lgkmcnt(5)
	v_mfma_f32_32x32x16_bf16 v[64:79], v[238:241], v[226:229], v[64:79]
	v_mfma_f32_32x32x16_bf16 v[0:15], v[238:241], v[230:233], v[0:15]
	ds_read_b128 v[238:241], v192 offset:4640
	s_setprio 0
	global_load_dwordx4 v[226:229], v[194:195], off offset:2816
	global_load_dwordx4 v[230:233], v[196:197], off offset:2816
	s_setprio 1
	s_waitcnt lgkmcnt(1)
	v_mfma_f32_32x32x16_bf16 v[112:127], v[234:237], v[176:179], v[112:127]
	v_mfma_f32_32x32x16_bf16 v[48:63], v[234:237], v[180:183], v[48:63]
	s_waitcnt lgkmcnt(0)
	v_mfma_f32_32x32x16_bf16 v[96:111], v[238:241], v[176:179], v[96:111]
	v_mfma_f32_32x32x16_bf16 v[32:47], v[238:241], v[180:183], v[32:47]
	ds_read_b128 v[234:237], v192 offset:9248
	ds_read_b128 v[238:241], v192 offset:13856
	s_waitcnt vmcnt(7)
	ds_write_b128 v214, v[168:171]
	s_waitcnt vmcnt(6)
	ds_write_b128 v213, v[172:175]
	ds_read_b128 v[168:171], v204 offset:36928
	ds_read_b128 v[172:175], v204 offset:41536
	s_waitcnt lgkmcnt(5)
	v_mfma_f32_32x32x16_bf16 v[80:95], v[234:237], v[176:179], v[80:95]
	v_mfma_f32_32x32x16_bf16 v[16:31], v[234:237], v[180:183], v[16:31]
	ds_read_b128 v[234:237], v192 offset:64
	s_waitcnt lgkmcnt(5)
	v_mfma_f32_32x32x16_bf16 v[64:79], v[238:241], v[176:179], v[64:79]
	v_mfma_f32_32x32x16_bf16 v[0:15], v[238:241], v[180:183], v[0:15]
	ds_read_b128 v[238:241], v192 offset:4672
	s_setprio 0
	global_load_dwordx4 v[176:179], v[184:185], off offset:2816
	global_load_dwordx4 v[180:183], v[186:187], off offset:2816
	s_setprio 1
	s_waitcnt lgkmcnt(1)
	v_mfma_f32_32x32x16_bf16 v[112:127], v[234:237], v[168:171], v[112:127]
	v_mfma_f32_32x32x16_bf16 v[48:63], v[234:237], v[172:175], v[48:63]
	s_waitcnt lgkmcnt(0)
	v_mfma_f32_32x32x16_bf16 v[96:111], v[238:241], v[168:171], v[96:111]
	v_mfma_f32_32x32x16_bf16 v[32:47], v[238:241], v[172:175], v[32:47]
	ds_read_b128 v[234:237], v192 offset:9280
	ds_read_b128 v[238:241], v192 offset:13888
	s_waitcnt vmcnt(7)
	ds_write_b128 v217, v[160:163]
	s_waitcnt vmcnt(6)
	ds_write_b128 v216, v[164:167]
	ds_read_b128 v[160:163], v204 offset:36960
	ds_read_b128 v[164:167], v204 offset:41568
	s_waitcnt lgkmcnt(5)
	v_mfma_f32_32x32x16_bf16 v[80:95], v[234:237], v[168:171], v[80:95]
	v_mfma_f32_32x32x16_bf16 v[16:31], v[234:237], v[172:175], v[16:31]
	ds_read_b128 v[234:237], v192 offset:96
	s_waitcnt lgkmcnt(5)
	v_mfma_f32_32x32x16_bf16 v[64:79], v[238:241], v[168:171], v[64:79]
	v_mfma_f32_32x32x16_bf16 v[0:15], v[238:241], v[172:175], v[0:15]
	ds_read_b128 v[238:241], v192 offset:4704
	s_setprio 0
	global_load_dwordx4 v[168:171], v[198:199], off offset:2816
	global_load_dwordx4 v[172:175], v[200:201], off offset:2816
	s_setprio 1
	s_waitcnt lgkmcnt(1)
	v_mfma_f32_32x32x16_bf16 v[112:127], v[234:237], v[160:163], v[112:127]
	v_mfma_f32_32x32x16_bf16 v[48:63], v[234:237], v[164:167], v[48:63]
	s_waitcnt lgkmcnt(0)
	v_mfma_f32_32x32x16_bf16 v[96:111], v[238:241], v[160:163], v[96:111]
	v_mfma_f32_32x32x16_bf16 v[32:47], v[238:241], v[164:167], v[32:47]
	ds_read_b128 v[234:237], v192 offset:9312
	ds_read_b128 v[238:241], v192 offset:13920
	s_waitcnt lgkmcnt(1)
	v_mfma_f32_32x32x16_bf16 v[80:95], v[234:237], v[160:163], v[80:95]
	v_mfma_f32_32x32x16_bf16 v[16:31], v[234:237], v[164:167], v[16:31]
	s_waitcnt lgkmcnt(0)
	v_mfma_f32_32x32x16_bf16 v[64:79], v[238:241], v[160:163], v[64:79]
	v_mfma_f32_32x32x16_bf16 v[0:15], v[238:241], v[164:167], v[0:15]
	s_setprio 0
	s_barrier
	global_load_dwordx4 v[160:163], v[190:191], off offset:2944
	global_load_dwordx4 v[164:167], v[188:189], off offset:2944
	s_waitcnt vmcnt(9)
	ds_write_b128 v215, v[218:221]
	s_waitcnt vmcnt(8)
	ds_write_b128 v215, v[222:225] offset:36864
	ds_read_b128 v[218:221], v208
	ds_read_b128 v[222:225], v208 offset:4608
	ds_read_b128 v[234:237], v205
	ds_read_b128 v[238:241], v205 offset:4608
	s_setprio 1
	s_waitcnt lgkmcnt(1)
	v_mfma_f32_32x32x16_bf16 v[112:127], v[234:237], v[218:221], v[112:127]
	v_mfma_f32_32x32x16_bf16 v[48:63], v[234:237], v[222:225], v[48:63]
	s_waitcnt lgkmcnt(0)
	v_mfma_f32_32x32x16_bf16 v[96:111], v[238:241], v[218:221], v[96:111]
	v_mfma_f32_32x32x16_bf16 v[32:47], v[238:241], v[222:225], v[32:47]
	ds_read_b128 v[234:237], v205 offset:9216
	ds_read_b128 v[238:241], v205 offset:13824
	s_waitcnt vmcnt(7)
	ds_write_b128 v215, v[226:229] offset:9216
	s_waitcnt vmcnt(6)
	ds_write_b128 v215, v[230:233] offset:46080
	ds_read_b128 v[226:229], v208 offset:32
	ds_read_b128 v[230:233], v208 offset:4640
	s_waitcnt lgkmcnt(5)
	v_mfma_f32_32x32x16_bf16 v[80:95], v[234:237], v[218:221], v[80:95]
	v_mfma_f32_32x32x16_bf16 v[16:31], v[234:237], v[222:225], v[16:31]
	ds_read_b128 v[234:237], v205 offset:32
	s_waitcnt lgkmcnt(5)
	v_mfma_f32_32x32x16_bf16 v[64:79], v[238:241], v[218:221], v[64:79]
	v_mfma_f32_32x32x16_bf16 v[0:15], v[238:241], v[222:225], v[0:15]
	ds_read_b128 v[238:241], v205 offset:4640
	s_setprio 0
	global_load_dwordx4 v[218:221], v[194:195], off offset:2944
	global_load_dwordx4 v[222:225], v[196:197], off offset:2944
	s_setprio 1
	s_waitcnt lgkmcnt(1)
	v_mfma_f32_32x32x16_bf16 v[112:127], v[234:237], v[226:229], v[112:127]
	v_mfma_f32_32x32x16_bf16 v[48:63], v[234:237], v[230:233], v[48:63]
	s_waitcnt lgkmcnt(0)
	v_mfma_f32_32x32x16_bf16 v[96:111], v[238:241], v[226:229], v[96:111]
	v_mfma_f32_32x32x16_bf16 v[32:47], v[238:241], v[230:233], v[32:47]
	ds_read_b128 v[234:237], v205 offset:9248
	ds_read_b128 v[238:241], v205 offset:13856
	s_waitcnt vmcnt(7)
	ds_write_b128 v215, v[176:179] offset:18432
	s_waitcnt vmcnt(6)
	ds_write_b128 v215, v[180:183] offset:55296
	ds_read_b128 v[176:179], v208 offset:64
	ds_read_b128 v[180:183], v208 offset:4672
	s_waitcnt lgkmcnt(5)
	v_mfma_f32_32x32x16_bf16 v[80:95], v[234:237], v[226:229], v[80:95]
	v_mfma_f32_32x32x16_bf16 v[16:31], v[234:237], v[230:233], v[16:31]
	ds_read_b128 v[234:237], v205 offset:64
	s_waitcnt lgkmcnt(5)
	v_mfma_f32_32x32x16_bf16 v[64:79], v[238:241], v[226:229], v[64:79]
	v_mfma_f32_32x32x16_bf16 v[0:15], v[238:241], v[230:233], v[0:15]
	ds_read_b128 v[238:241], v205 offset:4672
	s_setprio 0
	global_load_dwordx4 v[226:229], v[184:185], off offset:2944
	global_load_dwordx4 v[230:233], v[186:187], off offset:2944
	s_setprio 1
	s_waitcnt lgkmcnt(1)
	v_mfma_f32_32x32x16_bf16 v[112:127], v[234:237], v[176:179], v[112:127]
	v_mfma_f32_32x32x16_bf16 v[48:63], v[234:237], v[180:183], v[48:63]
	s_waitcnt lgkmcnt(0)
	v_mfma_f32_32x32x16_bf16 v[96:111], v[238:241], v[176:179], v[96:111]
	v_mfma_f32_32x32x16_bf16 v[32:47], v[238:241], v[180:183], v[32:47]
	ds_read_b128 v[234:237], v205 offset:9280
	ds_read_b128 v[238:241], v205 offset:13888
	s_waitcnt vmcnt(7)
	ds_write_b128 v215, v[168:171] offset:27648
	s_waitcnt vmcnt(6)
	ds_write_b128 v215, v[172:175] offset:64512
	ds_read_b128 v[168:171], v208 offset:96
	ds_read_b128 v[172:175], v208 offset:4704
	s_waitcnt lgkmcnt(5)
	v_mfma_f32_32x32x16_bf16 v[80:95], v[234:237], v[176:179], v[80:95]
	v_mfma_f32_32x32x16_bf16 v[16:31], v[234:237], v[180:183], v[16:31]
	ds_read_b128 v[234:237], v205 offset:96
	s_waitcnt lgkmcnt(5)
	v_mfma_f32_32x32x16_bf16 v[64:79], v[238:241], v[176:179], v[64:79]
	v_mfma_f32_32x32x16_bf16 v[0:15], v[238:241], v[180:183], v[0:15]
	ds_read_b128 v[238:241], v205 offset:4704
	s_setprio 0
	global_load_dwordx4 v[176:179], v[198:199], off offset:2944
	global_load_dwordx4 v[180:183], v[200:201], off offset:2944
	s_setprio 1
	s_waitcnt lgkmcnt(1)
	v_mfma_f32_32x32x16_bf16 v[112:127], v[234:237], v[168:171], v[112:127]
	v_mfma_f32_32x32x16_bf16 v[48:63], v[234:237], v[172:175], v[48:63]
	s_waitcnt lgkmcnt(0)
	v_mfma_f32_32x32x16_bf16 v[96:111], v[238:241], v[168:171], v[96:111]
	v_mfma_f32_32x32x16_bf16 v[32:47], v[238:241], v[172:175], v[32:47]
	ds_read_b128 v[234:237], v205 offset:9312
	ds_read_b128 v[238:241], v205 offset:13920
	s_waitcnt lgkmcnt(1)
	v_mfma_f32_32x32x16_bf16 v[80:95], v[234:237], v[168:171], v[80:95]
	v_mfma_f32_32x32x16_bf16 v[16:31], v[234:237], v[172:175], v[16:31]
	s_waitcnt lgkmcnt(0)
	v_mfma_f32_32x32x16_bf16 v[64:79], v[238:241], v[168:171], v[64:79]
	v_mfma_f32_32x32x16_bf16 v[0:15], v[238:241], v[172:175], v[0:15]
	s_setprio 0
	s_barrier
	global_load_dwordx4 v[168:171], v[190:191], off offset:3072
	global_load_dwordx4 v[172:175], v[188:189], off offset:3072
	s_waitcnt vmcnt(9)
	ds_write_b128 v209, v[160:163]
	s_waitcnt vmcnt(8)
	ds_write_b128 v210, v[164:167]
	ds_read_b128 v[160:163], v204 offset:36864
	ds_read_b128 v[164:167], v204 offset:41472
	ds_read_b128 v[234:237], v192
	ds_read_b128 v[238:241], v192 offset:4608
	s_setprio 1
	s_waitcnt lgkmcnt(1)
	v_mfma_f32_32x32x16_bf16 v[112:127], v[234:237], v[160:163], v[112:127]
	v_mfma_f32_32x32x16_bf16 v[48:63], v[234:237], v[164:167], v[48:63]
	s_waitcnt lgkmcnt(0)
	v_mfma_f32_32x32x16_bf16 v[96:111], v[238:241], v[160:163], v[96:111]
	v_mfma_f32_32x32x16_bf16 v[32:47], v[238:241], v[164:167], v[32:47]
	ds_read_b128 v[234:237], v192 offset:9216
	ds_read_b128 v[238:241], v192 offset:13824
	s_waitcnt vmcnt(7)
	ds_write_b128 v212, v[218:221]
	s_waitcnt vmcnt(6)
	ds_write_b128 v211, v[222:225]
	ds_read_b128 v[218:221], v204 offset:36896
	ds_read_b128 v[222:225], v204 offset:41504
	s_waitcnt lgkmcnt(5)
	v_mfma_f32_32x32x16_bf16 v[80:95], v[234:237], v[160:163], v[80:95]
	v_mfma_f32_32x32x16_bf16 v[16:31], v[234:237], v[164:167], v[16:31]
	ds_read_b128 v[234:237], v192 offset:32
	s_waitcnt lgkmcnt(5)
	v_mfma_f32_32x32x16_bf16 v[64:79], v[238:241], v[160:163], v[64:79]
	v_mfma_f32_32x32x16_bf16 v[0:15], v[238:241], v[164:167], v[0:15]
	ds_read_b128 v[238:241], v192 offset:4640
	s_setprio 0
	global_load_dwordx4 v[160:163], v[194:195], off offset:3072
	global_load_dwordx4 v[164:167], v[196:197], off offset:3072
	s_setprio 1
	s_waitcnt lgkmcnt(1)
	v_mfma_f32_32x32x16_bf16 v[112:127], v[234:237], v[218:221], v[112:127]
	v_mfma_f32_32x32x16_bf16 v[48:63], v[234:237], v[222:225], v[48:63]
	s_waitcnt lgkmcnt(0)
	v_mfma_f32_32x32x16_bf16 v[96:111], v[238:241], v[218:221], v[96:111]
	v_mfma_f32_32x32x16_bf16 v[32:47], v[238:241], v[222:225], v[32:47]
	ds_read_b128 v[234:237], v192 offset:9248
	ds_read_b128 v[238:241], v192 offset:13856
	s_waitcnt vmcnt(7)
	ds_write_b128 v214, v[226:229]
	s_waitcnt vmcnt(6)
	ds_write_b128 v213, v[230:233]
	ds_read_b128 v[226:229], v204 offset:36928
	ds_read_b128 v[230:233], v204 offset:41536
	s_waitcnt lgkmcnt(5)
	v_mfma_f32_32x32x16_bf16 v[80:95], v[234:237], v[218:221], v[80:95]
	v_mfma_f32_32x32x16_bf16 v[16:31], v[234:237], v[222:225], v[16:31]
	ds_read_b128 v[234:237], v192 offset:64
	s_waitcnt lgkmcnt(5)
	v_mfma_f32_32x32x16_bf16 v[64:79], v[238:241], v[218:221], v[64:79]
	v_mfma_f32_32x32x16_bf16 v[0:15], v[238:241], v[222:225], v[0:15]
	ds_read_b128 v[238:241], v192 offset:4672
	s_setprio 0
	global_load_dwordx4 v[218:221], v[184:185], off offset:3072
	global_load_dwordx4 v[222:225], v[186:187], off offset:3072
	s_setprio 1
	s_waitcnt lgkmcnt(1)
	v_mfma_f32_32x32x16_bf16 v[112:127], v[234:237], v[226:229], v[112:127]
	v_mfma_f32_32x32x16_bf16 v[48:63], v[234:237], v[230:233], v[48:63]
	s_waitcnt lgkmcnt(0)
	v_mfma_f32_32x32x16_bf16 v[96:111], v[238:241], v[226:229], v[96:111]
	v_mfma_f32_32x32x16_bf16 v[32:47], v[238:241], v[230:233], v[32:47]
	ds_read_b128 v[234:237], v192 offset:9280
	ds_read_b128 v[238:241], v192 offset:13888
	s_waitcnt vmcnt(7)
	ds_write_b128 v217, v[176:179]
	s_waitcnt vmcnt(6)
	ds_write_b128 v216, v[180:183]
	ds_read_b128 v[176:179], v204 offset:36960
	ds_read_b128 v[180:183], v204 offset:41568
	s_waitcnt lgkmcnt(5)
	v_mfma_f32_32x32x16_bf16 v[80:95], v[234:237], v[226:229], v[80:95]
	v_mfma_f32_32x32x16_bf16 v[16:31], v[234:237], v[230:233], v[16:31]
	ds_read_b128 v[234:237], v192 offset:96
	s_waitcnt lgkmcnt(5)
	v_mfma_f32_32x32x16_bf16 v[64:79], v[238:241], v[226:229], v[64:79]
	v_mfma_f32_32x32x16_bf16 v[0:15], v[238:241], v[230:233], v[0:15]
	ds_read_b128 v[238:241], v192 offset:4704
	s_setprio 0
	global_load_dwordx4 v[226:229], v[198:199], off offset:3072
	global_load_dwordx4 v[230:233], v[200:201], off offset:3072
	s_setprio 1
	s_waitcnt lgkmcnt(1)
	v_mfma_f32_32x32x16_bf16 v[112:127], v[234:237], v[176:179], v[112:127]
	v_mfma_f32_32x32x16_bf16 v[48:63], v[234:237], v[180:183], v[48:63]
	s_waitcnt lgkmcnt(0)
	v_mfma_f32_32x32x16_bf16 v[96:111], v[238:241], v[176:179], v[96:111]
	v_mfma_f32_32x32x16_bf16 v[32:47], v[238:241], v[180:183], v[32:47]
	ds_read_b128 v[234:237], v192 offset:9312
	ds_read_b128 v[238:241], v192 offset:13920
	s_waitcnt lgkmcnt(1)
	v_mfma_f32_32x32x16_bf16 v[80:95], v[234:237], v[176:179], v[80:95]
	v_mfma_f32_32x32x16_bf16 v[16:31], v[234:237], v[180:183], v[16:31]
	s_waitcnt lgkmcnt(0)
	v_mfma_f32_32x32x16_bf16 v[64:79], v[238:241], v[176:179], v[64:79]
	v_mfma_f32_32x32x16_bf16 v[0:15], v[238:241], v[180:183], v[0:15]
	s_setprio 0
	s_barrier
	global_load_dwordx4 v[176:179], v[190:191], off offset:3200
	global_load_dwordx4 v[180:183], v[188:189], off offset:3200
	s_waitcnt vmcnt(9)
	ds_write_b128 v215, v[168:171]
	s_waitcnt vmcnt(8)
	ds_write_b128 v215, v[172:175] offset:36864
	ds_read_b128 v[168:171], v208
	ds_read_b128 v[172:175], v208 offset:4608
	ds_read_b128 v[234:237], v205
	ds_read_b128 v[238:241], v205 offset:4608
	s_setprio 1
	s_waitcnt lgkmcnt(1)
	v_mfma_f32_32x32x16_bf16 v[112:127], v[234:237], v[168:171], v[112:127]
	v_mfma_f32_32x32x16_bf16 v[48:63], v[234:237], v[172:175], v[48:63]
	s_waitcnt lgkmcnt(0)
	v_mfma_f32_32x32x16_bf16 v[96:111], v[238:241], v[168:171], v[96:111]
	v_mfma_f32_32x32x16_bf16 v[32:47], v[238:241], v[172:175], v[32:47]
	ds_read_b128 v[234:237], v205 offset:9216
	ds_read_b128 v[238:241], v205 offset:13824
	s_waitcnt vmcnt(7)
	ds_write_b128 v215, v[160:163] offset:9216
	s_waitcnt vmcnt(6)
	ds_write_b128 v215, v[164:167] offset:46080
	ds_read_b128 v[160:163], v208 offset:32
	ds_read_b128 v[164:167], v208 offset:4640
	s_waitcnt lgkmcnt(5)
	v_mfma_f32_32x32x16_bf16 v[80:95], v[234:237], v[168:171], v[80:95]
	v_mfma_f32_32x32x16_bf16 v[16:31], v[234:237], v[172:175], v[16:31]
	ds_read_b128 v[234:237], v205 offset:32
	s_waitcnt lgkmcnt(5)
	v_mfma_f32_32x32x16_bf16 v[64:79], v[238:241], v[168:171], v[64:79]
	v_mfma_f32_32x32x16_bf16 v[0:15], v[238:241], v[172:175], v[0:15]
	ds_read_b128 v[238:241], v205 offset:4640
	s_setprio 0
	global_load_dwordx4 v[168:171], v[194:195], off offset:3200
	global_load_dwordx4 v[172:175], v[196:197], off offset:3200
	s_setprio 1
	s_waitcnt lgkmcnt(1)
	v_mfma_f32_32x32x16_bf16 v[112:127], v[234:237], v[160:163], v[112:127]
	v_mfma_f32_32x32x16_bf16 v[48:63], v[234:237], v[164:167], v[48:63]
	s_waitcnt lgkmcnt(0)
	v_mfma_f32_32x32x16_bf16 v[96:111], v[238:241], v[160:163], v[96:111]
	v_mfma_f32_32x32x16_bf16 v[32:47], v[238:241], v[164:167], v[32:47]
	ds_read_b128 v[234:237], v205 offset:9248
	ds_read_b128 v[238:241], v205 offset:13856
	s_waitcnt vmcnt(7)
	ds_write_b128 v215, v[218:221] offset:18432
	s_waitcnt vmcnt(6)
	ds_write_b128 v215, v[222:225] offset:55296
	ds_read_b128 v[218:221], v208 offset:64
	ds_read_b128 v[222:225], v208 offset:4672
	s_waitcnt lgkmcnt(5)
	v_mfma_f32_32x32x16_bf16 v[80:95], v[234:237], v[160:163], v[80:95]
	v_mfma_f32_32x32x16_bf16 v[16:31], v[234:237], v[164:167], v[16:31]
	ds_read_b128 v[234:237], v205 offset:64
	s_waitcnt lgkmcnt(5)
	v_mfma_f32_32x32x16_bf16 v[64:79], v[238:241], v[160:163], v[64:79]
	v_mfma_f32_32x32x16_bf16 v[0:15], v[238:241], v[164:167], v[0:15]
	ds_read_b128 v[238:241], v205 offset:4672
	s_setprio 0
	global_load_dwordx4 v[160:163], v[184:185], off offset:3200
	global_load_dwordx4 v[164:167], v[186:187], off offset:3200
	s_setprio 1
	s_waitcnt lgkmcnt(1)
	v_mfma_f32_32x32x16_bf16 v[112:127], v[234:237], v[218:221], v[112:127]
	v_mfma_f32_32x32x16_bf16 v[48:63], v[234:237], v[222:225], v[48:63]
	s_waitcnt lgkmcnt(0)
	v_mfma_f32_32x32x16_bf16 v[96:111], v[238:241], v[218:221], v[96:111]
	v_mfma_f32_32x32x16_bf16 v[32:47], v[238:241], v[222:225], v[32:47]
	ds_read_b128 v[234:237], v205 offset:9280
	ds_read_b128 v[238:241], v205 offset:13888
	s_waitcnt vmcnt(7)
	ds_write_b128 v215, v[226:229] offset:27648
	s_waitcnt vmcnt(6)
	ds_write_b128 v215, v[230:233] offset:64512
	ds_read_b128 v[226:229], v208 offset:96
	ds_read_b128 v[230:233], v208 offset:4704
	s_waitcnt lgkmcnt(5)
	v_mfma_f32_32x32x16_bf16 v[80:95], v[234:237], v[218:221], v[80:95]
	v_mfma_f32_32x32x16_bf16 v[16:31], v[234:237], v[222:225], v[16:31]
	ds_read_b128 v[234:237], v205 offset:96
	s_waitcnt lgkmcnt(5)
	v_mfma_f32_32x32x16_bf16 v[64:79], v[238:241], v[218:221], v[64:79]
	v_mfma_f32_32x32x16_bf16 v[0:15], v[238:241], v[222:225], v[0:15]
	ds_read_b128 v[238:241], v205 offset:4704
	s_setprio 0
	global_load_dwordx4 v[218:221], v[198:199], off offset:3200
	global_load_dwordx4 v[222:225], v[200:201], off offset:3200
	s_setprio 1
	s_waitcnt lgkmcnt(1)
	v_mfma_f32_32x32x16_bf16 v[112:127], v[234:237], v[226:229], v[112:127]
	v_mfma_f32_32x32x16_bf16 v[48:63], v[234:237], v[230:233], v[48:63]
	s_waitcnt lgkmcnt(0)
	v_mfma_f32_32x32x16_bf16 v[96:111], v[238:241], v[226:229], v[96:111]
	v_mfma_f32_32x32x16_bf16 v[32:47], v[238:241], v[230:233], v[32:47]
	ds_read_b128 v[234:237], v205 offset:9312
	ds_read_b128 v[238:241], v205 offset:13920
	s_waitcnt lgkmcnt(1)
	v_mfma_f32_32x32x16_bf16 v[80:95], v[234:237], v[226:229], v[80:95]
	v_mfma_f32_32x32x16_bf16 v[16:31], v[234:237], v[230:233], v[16:31]
	s_waitcnt lgkmcnt(0)
	v_mfma_f32_32x32x16_bf16 v[64:79], v[238:241], v[226:229], v[64:79]
	v_mfma_f32_32x32x16_bf16 v[0:15], v[238:241], v[230:233], v[0:15]
	s_setprio 0
	s_barrier
	global_load_dwordx4 v[226:229], v[190:191], off offset:3328
	global_load_dwordx4 v[230:233], v[188:189], off offset:3328
	s_waitcnt vmcnt(9)
	ds_write_b128 v209, v[176:179]
	s_waitcnt vmcnt(8)
	ds_write_b128 v210, v[180:183]
	ds_read_b128 v[176:179], v204 offset:36864
	ds_read_b128 v[180:183], v204 offset:41472
	ds_read_b128 v[234:237], v192
	ds_read_b128 v[238:241], v192 offset:4608
	s_setprio 1
	s_waitcnt lgkmcnt(1)
	v_mfma_f32_32x32x16_bf16 v[112:127], v[234:237], v[176:179], v[112:127]
	v_mfma_f32_32x32x16_bf16 v[48:63], v[234:237], v[180:183], v[48:63]
	s_waitcnt lgkmcnt(0)
	v_mfma_f32_32x32x16_bf16 v[96:111], v[238:241], v[176:179], v[96:111]
	v_mfma_f32_32x32x16_bf16 v[32:47], v[238:241], v[180:183], v[32:47]
	ds_read_b128 v[234:237], v192 offset:9216
	ds_read_b128 v[238:241], v192 offset:13824
	s_waitcnt vmcnt(7)
	ds_write_b128 v212, v[168:171]
	s_waitcnt vmcnt(6)
	ds_write_b128 v211, v[172:175]
	ds_read_b128 v[168:171], v204 offset:36896
	ds_read_b128 v[172:175], v204 offset:41504
	s_waitcnt lgkmcnt(5)
	v_mfma_f32_32x32x16_bf16 v[80:95], v[234:237], v[176:179], v[80:95]
	v_mfma_f32_32x32x16_bf16 v[16:31], v[234:237], v[180:183], v[16:31]
	ds_read_b128 v[234:237], v192 offset:32
	s_waitcnt lgkmcnt(5)
	v_mfma_f32_32x32x16_bf16 v[64:79], v[238:241], v[176:179], v[64:79]
	v_mfma_f32_32x32x16_bf16 v[0:15], v[238:241], v[180:183], v[0:15]
	ds_read_b128 v[238:241], v192 offset:4640
	s_setprio 0
	global_load_dwordx4 v[176:179], v[194:195], off offset:3328
	global_load_dwordx4 v[180:183], v[196:197], off offset:3328
	s_setprio 1
	s_waitcnt lgkmcnt(1)
	v_mfma_f32_32x32x16_bf16 v[112:127], v[234:237], v[168:171], v[112:127]
	v_mfma_f32_32x32x16_bf16 v[48:63], v[234:237], v[172:175], v[48:63]
	s_waitcnt lgkmcnt(0)
	v_mfma_f32_32x32x16_bf16 v[96:111], v[238:241], v[168:171], v[96:111]
	v_mfma_f32_32x32x16_bf16 v[32:47], v[238:241], v[172:175], v[32:47]
	ds_read_b128 v[234:237], v192 offset:9248
	ds_read_b128 v[238:241], v192 offset:13856
	s_waitcnt vmcnt(7)
	ds_write_b128 v214, v[160:163]
	s_waitcnt vmcnt(6)
	ds_write_b128 v213, v[164:167]
	ds_read_b128 v[160:163], v204 offset:36928
	ds_read_b128 v[164:167], v204 offset:41536
	s_waitcnt lgkmcnt(5)
	v_mfma_f32_32x32x16_bf16 v[80:95], v[234:237], v[168:171], v[80:95]
	v_mfma_f32_32x32x16_bf16 v[16:31], v[234:237], v[172:175], v[16:31]
	ds_read_b128 v[234:237], v192 offset:64
	s_waitcnt lgkmcnt(5)
	v_mfma_f32_32x32x16_bf16 v[64:79], v[238:241], v[168:171], v[64:79]
	v_mfma_f32_32x32x16_bf16 v[0:15], v[238:241], v[172:175], v[0:15]
	ds_read_b128 v[238:241], v192 offset:4672
	s_setprio 0
	global_load_dwordx4 v[168:171], v[184:185], off offset:3328
	global_load_dwordx4 v[172:175], v[186:187], off offset:3328
	s_setprio 1
	s_waitcnt lgkmcnt(1)
	v_mfma_f32_32x32x16_bf16 v[112:127], v[234:237], v[160:163], v[112:127]
	v_mfma_f32_32x32x16_bf16 v[48:63], v[234:237], v[164:167], v[48:63]
	s_waitcnt lgkmcnt(0)
	v_mfma_f32_32x32x16_bf16 v[96:111], v[238:241], v[160:163], v[96:111]
	v_mfma_f32_32x32x16_bf16 v[32:47], v[238:241], v[164:167], v[32:47]
	ds_read_b128 v[234:237], v192 offset:9280
	ds_read_b128 v[238:241], v192 offset:13888
	s_waitcnt vmcnt(7)
	ds_write_b128 v217, v[218:221]
	s_waitcnt vmcnt(6)
	ds_write_b128 v216, v[222:225]
	ds_read_b128 v[218:221], v204 offset:36960
	ds_read_b128 v[222:225], v204 offset:41568
	s_waitcnt lgkmcnt(5)
	v_mfma_f32_32x32x16_bf16 v[80:95], v[234:237], v[160:163], v[80:95]
	v_mfma_f32_32x32x16_bf16 v[16:31], v[234:237], v[164:167], v[16:31]
	ds_read_b128 v[234:237], v192 offset:96
	s_waitcnt lgkmcnt(5)
	v_mfma_f32_32x32x16_bf16 v[64:79], v[238:241], v[160:163], v[64:79]
	v_mfma_f32_32x32x16_bf16 v[0:15], v[238:241], v[164:167], v[0:15]
	ds_read_b128 v[238:241], v192 offset:4704
	s_setprio 0
	global_load_dwordx4 v[160:163], v[198:199], off offset:3328
	global_load_dwordx4 v[164:167], v[200:201], off offset:3328
	s_setprio 1
	s_waitcnt lgkmcnt(1)
	v_mfma_f32_32x32x16_bf16 v[112:127], v[234:237], v[218:221], v[112:127]
	v_mfma_f32_32x32x16_bf16 v[48:63], v[234:237], v[222:225], v[48:63]
	s_waitcnt lgkmcnt(0)
	v_mfma_f32_32x32x16_bf16 v[96:111], v[238:241], v[218:221], v[96:111]
	v_mfma_f32_32x32x16_bf16 v[32:47], v[238:241], v[222:225], v[32:47]
	ds_read_b128 v[234:237], v192 offset:9312
	ds_read_b128 v[238:241], v192 offset:13920
	s_waitcnt lgkmcnt(1)
	v_mfma_f32_32x32x16_bf16 v[80:95], v[234:237], v[218:221], v[80:95]
	v_mfma_f32_32x32x16_bf16 v[16:31], v[234:237], v[222:225], v[16:31]
	s_waitcnt lgkmcnt(0)
	v_mfma_f32_32x32x16_bf16 v[64:79], v[238:241], v[218:221], v[64:79]
	v_mfma_f32_32x32x16_bf16 v[0:15], v[238:241], v[222:225], v[0:15]
	s_setprio 0
	s_barrier
	global_load_dwordx4 v[218:221], v[190:191], off offset:3456
	global_load_dwordx4 v[222:225], v[188:189], off offset:3456
	s_waitcnt vmcnt(9)
	ds_write_b128 v215, v[226:229]
	s_waitcnt vmcnt(8)
	ds_write_b128 v215, v[230:233] offset:36864
	ds_read_b128 v[226:229], v208
	ds_read_b128 v[230:233], v208 offset:4608
	ds_read_b128 v[234:237], v205
	ds_read_b128 v[238:241], v205 offset:4608
	s_setprio 1
	s_waitcnt lgkmcnt(1)
	v_mfma_f32_32x32x16_bf16 v[112:127], v[234:237], v[226:229], v[112:127]
	v_mfma_f32_32x32x16_bf16 v[48:63], v[234:237], v[230:233], v[48:63]
	s_waitcnt lgkmcnt(0)
	v_mfma_f32_32x32x16_bf16 v[96:111], v[238:241], v[226:229], v[96:111]
	v_mfma_f32_32x32x16_bf16 v[32:47], v[238:241], v[230:233], v[32:47]
	ds_read_b128 v[234:237], v205 offset:9216
	ds_read_b128 v[238:241], v205 offset:13824
	s_waitcnt vmcnt(7)
	ds_write_b128 v215, v[176:179] offset:9216
	s_waitcnt vmcnt(6)
	ds_write_b128 v215, v[180:183] offset:46080
	ds_read_b128 v[176:179], v208 offset:32
	ds_read_b128 v[180:183], v208 offset:4640
	s_waitcnt lgkmcnt(5)
	v_mfma_f32_32x32x16_bf16 v[80:95], v[234:237], v[226:229], v[80:95]
	v_mfma_f32_32x32x16_bf16 v[16:31], v[234:237], v[230:233], v[16:31]
	ds_read_b128 v[234:237], v205 offset:32
	s_waitcnt lgkmcnt(5)
	v_mfma_f32_32x32x16_bf16 v[64:79], v[238:241], v[226:229], v[64:79]
	v_mfma_f32_32x32x16_bf16 v[0:15], v[238:241], v[230:233], v[0:15]
	ds_read_b128 v[238:241], v205 offset:4640
	s_setprio 0
	global_load_dwordx4 v[226:229], v[194:195], off offset:3456
	global_load_dwordx4 v[230:233], v[196:197], off offset:3456
	s_setprio 1
	s_waitcnt lgkmcnt(1)
	v_mfma_f32_32x32x16_bf16 v[112:127], v[234:237], v[176:179], v[112:127]
	v_mfma_f32_32x32x16_bf16 v[48:63], v[234:237], v[180:183], v[48:63]
	s_waitcnt lgkmcnt(0)
	v_mfma_f32_32x32x16_bf16 v[96:111], v[238:241], v[176:179], v[96:111]
	v_mfma_f32_32x32x16_bf16 v[32:47], v[238:241], v[180:183], v[32:47]
	ds_read_b128 v[234:237], v205 offset:9248
	ds_read_b128 v[238:241], v205 offset:13856
	s_waitcnt vmcnt(7)
	ds_write_b128 v215, v[168:171] offset:18432
	s_waitcnt vmcnt(6)
	ds_write_b128 v215, v[172:175] offset:55296
	ds_read_b128 v[168:171], v208 offset:64
	ds_read_b128 v[172:175], v208 offset:4672
	s_waitcnt lgkmcnt(5)
	v_mfma_f32_32x32x16_bf16 v[80:95], v[234:237], v[176:179], v[80:95]
	v_mfma_f32_32x32x16_bf16 v[16:31], v[234:237], v[180:183], v[16:31]
	ds_read_b128 v[234:237], v205 offset:64
	s_waitcnt lgkmcnt(5)
	v_mfma_f32_32x32x16_bf16 v[64:79], v[238:241], v[176:179], v[64:79]
	v_mfma_f32_32x32x16_bf16 v[0:15], v[238:241], v[180:183], v[0:15]
	ds_read_b128 v[238:241], v205 offset:4672
	s_setprio 0
	global_load_dwordx4 v[176:179], v[184:185], off offset:3456
	global_load_dwordx4 v[180:183], v[186:187], off offset:3456
	s_setprio 1
	s_waitcnt lgkmcnt(1)
	v_mfma_f32_32x32x16_bf16 v[112:127], v[234:237], v[168:171], v[112:127]
	v_mfma_f32_32x32x16_bf16 v[48:63], v[234:237], v[172:175], v[48:63]
	s_waitcnt lgkmcnt(0)
	v_mfma_f32_32x32x16_bf16 v[96:111], v[238:241], v[168:171], v[96:111]
	v_mfma_f32_32x32x16_bf16 v[32:47], v[238:241], v[172:175], v[32:47]
	ds_read_b128 v[234:237], v205 offset:9280
	ds_read_b128 v[238:241], v205 offset:13888
	s_waitcnt vmcnt(7)
	ds_write_b128 v215, v[160:163] offset:27648
	s_waitcnt vmcnt(6)
	ds_write_b128 v215, v[164:167] offset:64512
	ds_read_b128 v[160:163], v208 offset:96
	ds_read_b128 v[164:167], v208 offset:4704
	s_waitcnt lgkmcnt(5)
	v_mfma_f32_32x32x16_bf16 v[80:95], v[234:237], v[168:171], v[80:95]
	v_mfma_f32_32x32x16_bf16 v[16:31], v[234:237], v[172:175], v[16:31]
	ds_read_b128 v[234:237], v205 offset:96
	s_waitcnt lgkmcnt(5)
	v_mfma_f32_32x32x16_bf16 v[64:79], v[238:241], v[168:171], v[64:79]
	v_mfma_f32_32x32x16_bf16 v[0:15], v[238:241], v[172:175], v[0:15]
	ds_read_b128 v[238:241], v205 offset:4704
	s_setprio 0
	global_load_dwordx4 v[168:171], v[198:199], off offset:3456
	global_load_dwordx4 v[172:175], v[200:201], off offset:3456
	s_setprio 1
	s_waitcnt lgkmcnt(1)
	v_mfma_f32_32x32x16_bf16 v[112:127], v[234:237], v[160:163], v[112:127]
	v_mfma_f32_32x32x16_bf16 v[48:63], v[234:237], v[164:167], v[48:63]
	s_waitcnt lgkmcnt(0)
	v_mfma_f32_32x32x16_bf16 v[96:111], v[238:241], v[160:163], v[96:111]
	v_mfma_f32_32x32x16_bf16 v[32:47], v[238:241], v[164:167], v[32:47]
	ds_read_b128 v[234:237], v205 offset:9312
	ds_read_b128 v[238:241], v205 offset:13920
	s_waitcnt lgkmcnt(1)
	v_mfma_f32_32x32x16_bf16 v[80:95], v[234:237], v[160:163], v[80:95]
	v_mfma_f32_32x32x16_bf16 v[16:31], v[234:237], v[164:167], v[16:31]
	s_waitcnt lgkmcnt(0)
	v_mfma_f32_32x32x16_bf16 v[64:79], v[238:241], v[160:163], v[64:79]
	v_mfma_f32_32x32x16_bf16 v[0:15], v[238:241], v[164:167], v[0:15]
	s_setprio 0
	s_barrier
	global_load_dwordx4 v[160:163], v[190:191], off offset:3584
	global_load_dwordx4 v[164:167], v[188:189], off offset:3584
	s_waitcnt vmcnt(9)
	ds_write_b128 v209, v[218:221]
	s_waitcnt vmcnt(8)
	ds_write_b128 v210, v[222:225]
	ds_read_b128 v[218:221], v204 offset:36864
	ds_read_b128 v[222:225], v204 offset:41472
	ds_read_b128 v[234:237], v192
	ds_read_b128 v[238:241], v192 offset:4608
	s_setprio 1
	s_waitcnt lgkmcnt(1)
	v_mfma_f32_32x32x16_bf16 v[112:127], v[234:237], v[218:221], v[112:127]
	v_mfma_f32_32x32x16_bf16 v[48:63], v[234:237], v[222:225], v[48:63]
	s_waitcnt lgkmcnt(0)
	v_mfma_f32_32x32x16_bf16 v[96:111], v[238:241], v[218:221], v[96:111]
	v_mfma_f32_32x32x16_bf16 v[32:47], v[238:241], v[222:225], v[32:47]
	ds_read_b128 v[234:237], v192 offset:9216
	ds_read_b128 v[238:241], v192 offset:13824
	s_waitcnt vmcnt(7)
	ds_write_b128 v212, v[226:229]
	s_waitcnt vmcnt(6)
	ds_write_b128 v211, v[230:233]
	ds_read_b128 v[226:229], v204 offset:36896
	ds_read_b128 v[230:233], v204 offset:41504
	s_waitcnt lgkmcnt(5)
	v_mfma_f32_32x32x16_bf16 v[80:95], v[234:237], v[218:221], v[80:95]
	v_mfma_f32_32x32x16_bf16 v[16:31], v[234:237], v[222:225], v[16:31]
	ds_read_b128 v[234:237], v192 offset:32
	s_waitcnt lgkmcnt(5)
	v_mfma_f32_32x32x16_bf16 v[64:79], v[238:241], v[218:221], v[64:79]
	v_mfma_f32_32x32x16_bf16 v[0:15], v[238:241], v[222:225], v[0:15]
	ds_read_b128 v[238:241], v192 offset:4640
	s_setprio 0
	global_load_dwordx4 v[218:221], v[194:195], off offset:3584
	global_load_dwordx4 v[222:225], v[196:197], off offset:3584
	s_setprio 1
	s_waitcnt lgkmcnt(1)
	v_mfma_f32_32x32x16_bf16 v[112:127], v[234:237], v[226:229], v[112:127]
	v_mfma_f32_32x32x16_bf16 v[48:63], v[234:237], v[230:233], v[48:63]
	s_waitcnt lgkmcnt(0)
	v_mfma_f32_32x32x16_bf16 v[96:111], v[238:241], v[226:229], v[96:111]
	v_mfma_f32_32x32x16_bf16 v[32:47], v[238:241], v[230:233], v[32:47]
	ds_read_b128 v[234:237], v192 offset:9248
	ds_read_b128 v[238:241], v192 offset:13856
	s_waitcnt vmcnt(7)
	ds_write_b128 v214, v[176:179]
	s_waitcnt vmcnt(6)
	ds_write_b128 v213, v[180:183]
	ds_read_b128 v[176:179], v204 offset:36928
	ds_read_b128 v[180:183], v204 offset:41536
	s_waitcnt lgkmcnt(5)
	v_mfma_f32_32x32x16_bf16 v[80:95], v[234:237], v[226:229], v[80:95]
	v_mfma_f32_32x32x16_bf16 v[16:31], v[234:237], v[230:233], v[16:31]
	ds_read_b128 v[234:237], v192 offset:64
	s_waitcnt lgkmcnt(5)
	v_mfma_f32_32x32x16_bf16 v[64:79], v[238:241], v[226:229], v[64:79]
	v_mfma_f32_32x32x16_bf16 v[0:15], v[238:241], v[230:233], v[0:15]
	ds_read_b128 v[238:241], v192 offset:4672
	s_setprio 0
	global_load_dwordx4 v[226:229], v[184:185], off offset:3584
	global_load_dwordx4 v[230:233], v[186:187], off offset:3584
	s_setprio 1
	s_waitcnt lgkmcnt(1)
	v_mfma_f32_32x32x16_bf16 v[112:127], v[234:237], v[176:179], v[112:127]
	v_mfma_f32_32x32x16_bf16 v[48:63], v[234:237], v[180:183], v[48:63]
	s_waitcnt lgkmcnt(0)
	v_mfma_f32_32x32x16_bf16 v[96:111], v[238:241], v[176:179], v[96:111]
	v_mfma_f32_32x32x16_bf16 v[32:47], v[238:241], v[180:183], v[32:47]
	ds_read_b128 v[234:237], v192 offset:9280
	ds_read_b128 v[238:241], v192 offset:13888
	s_waitcnt vmcnt(7)
	ds_write_b128 v217, v[168:171]
	s_waitcnt vmcnt(6)
	ds_write_b128 v216, v[172:175]
	ds_read_b128 v[168:171], v204 offset:36960
	ds_read_b128 v[172:175], v204 offset:41568
	s_waitcnt lgkmcnt(5)
	v_mfma_f32_32x32x16_bf16 v[80:95], v[234:237], v[176:179], v[80:95]
	v_mfma_f32_32x32x16_bf16 v[16:31], v[234:237], v[180:183], v[16:31]
	ds_read_b128 v[234:237], v192 offset:96
	s_waitcnt lgkmcnt(5)
	v_mfma_f32_32x32x16_bf16 v[64:79], v[238:241], v[176:179], v[64:79]
	v_mfma_f32_32x32x16_bf16 v[0:15], v[238:241], v[180:183], v[0:15]
	ds_read_b128 v[238:241], v192 offset:4704
	s_setprio 0
	global_load_dwordx4 v[176:179], v[198:199], off offset:3584
	global_load_dwordx4 v[180:183], v[200:201], off offset:3584
	s_setprio 1
	s_waitcnt lgkmcnt(1)
	v_mfma_f32_32x32x16_bf16 v[112:127], v[234:237], v[168:171], v[112:127]
	v_mfma_f32_32x32x16_bf16 v[48:63], v[234:237], v[172:175], v[48:63]
	s_waitcnt lgkmcnt(0)
	v_mfma_f32_32x32x16_bf16 v[96:111], v[238:241], v[168:171], v[96:111]
	v_mfma_f32_32x32x16_bf16 v[32:47], v[238:241], v[172:175], v[32:47]
	ds_read_b128 v[234:237], v192 offset:9312
	ds_read_b128 v[238:241], v192 offset:13920
	s_waitcnt lgkmcnt(1)
	v_mfma_f32_32x32x16_bf16 v[80:95], v[234:237], v[168:171], v[80:95]
	v_mfma_f32_32x32x16_bf16 v[16:31], v[234:237], v[172:175], v[16:31]
	s_waitcnt lgkmcnt(0)
	v_mfma_f32_32x32x16_bf16 v[64:79], v[238:241], v[168:171], v[64:79]
	v_mfma_f32_32x32x16_bf16 v[0:15], v[238:241], v[172:175], v[0:15]
	s_setprio 0
	s_barrier
	global_load_dwordx4 v[168:171], v[190:191], off offset:3712
	global_load_dwordx4 v[172:175], v[188:189], off offset:3712
	s_waitcnt vmcnt(9)
	ds_write_b128 v215, v[160:163]
	s_waitcnt vmcnt(8)
	ds_write_b128 v215, v[164:167] offset:36864
	ds_read_b128 v[160:163], v208
	ds_read_b128 v[164:167], v208 offset:4608
	ds_read_b128 v[234:237], v205
	ds_read_b128 v[238:241], v205 offset:4608
	s_setprio 1
	s_waitcnt lgkmcnt(1)
	v_mfma_f32_32x32x16_bf16 v[112:127], v[234:237], v[160:163], v[112:127]
	v_mfma_f32_32x32x16_bf16 v[48:63], v[234:237], v[164:167], v[48:63]
	s_waitcnt lgkmcnt(0)
	v_mfma_f32_32x32x16_bf16 v[96:111], v[238:241], v[160:163], v[96:111]
	v_mfma_f32_32x32x16_bf16 v[32:47], v[238:241], v[164:167], v[32:47]
	ds_read_b128 v[234:237], v205 offset:9216
	ds_read_b128 v[238:241], v205 offset:13824
	s_waitcnt vmcnt(7)
	ds_write_b128 v215, v[218:221] offset:9216
	s_waitcnt vmcnt(6)
	ds_write_b128 v215, v[222:225] offset:46080
	ds_read_b128 v[218:221], v208 offset:32
	ds_read_b128 v[222:225], v208 offset:4640
	s_waitcnt lgkmcnt(5)
	v_mfma_f32_32x32x16_bf16 v[80:95], v[234:237], v[160:163], v[80:95]
	v_mfma_f32_32x32x16_bf16 v[16:31], v[234:237], v[164:167], v[16:31]
	ds_read_b128 v[234:237], v205 offset:32
	s_waitcnt lgkmcnt(5)
	v_mfma_f32_32x32x16_bf16 v[64:79], v[238:241], v[160:163], v[64:79]
	v_mfma_f32_32x32x16_bf16 v[0:15], v[238:241], v[164:167], v[0:15]
	ds_read_b128 v[238:241], v205 offset:4640
	s_setprio 0
	global_load_dwordx4 v[160:163], v[194:195], off offset:3712
	global_load_dwordx4 v[164:167], v[196:197], off offset:3712
	s_setprio 1
	s_waitcnt lgkmcnt(1)
	v_mfma_f32_32x32x16_bf16 v[112:127], v[234:237], v[218:221], v[112:127]
	v_mfma_f32_32x32x16_bf16 v[48:63], v[234:237], v[222:225], v[48:63]
	s_waitcnt lgkmcnt(0)
	v_mfma_f32_32x32x16_bf16 v[96:111], v[238:241], v[218:221], v[96:111]
	v_mfma_f32_32x32x16_bf16 v[32:47], v[238:241], v[222:225], v[32:47]
	ds_read_b128 v[234:237], v205 offset:9248
	ds_read_b128 v[238:241], v205 offset:13856
	s_waitcnt vmcnt(7)
	ds_write_b128 v215, v[226:229] offset:18432
	s_waitcnt vmcnt(6)
	ds_write_b128 v215, v[230:233] offset:55296
	ds_read_b128 v[226:229], v208 offset:64
	ds_read_b128 v[230:233], v208 offset:4672
	s_waitcnt lgkmcnt(5)
	v_mfma_f32_32x32x16_bf16 v[80:95], v[234:237], v[218:221], v[80:95]
	v_mfma_f32_32x32x16_bf16 v[16:31], v[234:237], v[222:225], v[16:31]
	ds_read_b128 v[234:237], v205 offset:64
	s_waitcnt lgkmcnt(5)
	v_mfma_f32_32x32x16_bf16 v[64:79], v[238:241], v[218:221], v[64:79]
	v_mfma_f32_32x32x16_bf16 v[0:15], v[238:241], v[222:225], v[0:15]
	ds_read_b128 v[238:241], v205 offset:4672
	s_setprio 0
	global_load_dwordx4 v[218:221], v[184:185], off offset:3712
	global_load_dwordx4 v[222:225], v[186:187], off offset:3712
	s_setprio 1
	s_waitcnt lgkmcnt(1)
	v_mfma_f32_32x32x16_bf16 v[112:127], v[234:237], v[226:229], v[112:127]
	v_mfma_f32_32x32x16_bf16 v[48:63], v[234:237], v[230:233], v[48:63]
	s_waitcnt lgkmcnt(0)
	v_mfma_f32_32x32x16_bf16 v[96:111], v[238:241], v[226:229], v[96:111]
	v_mfma_f32_32x32x16_bf16 v[32:47], v[238:241], v[230:233], v[32:47]
	ds_read_b128 v[234:237], v205 offset:9280
	ds_read_b128 v[238:241], v205 offset:13888
	s_waitcnt vmcnt(7)
	ds_write_b128 v215, v[176:179] offset:27648
	s_waitcnt vmcnt(6)
	ds_write_b128 v215, v[180:183] offset:64512
	ds_read_b128 v[176:179], v208 offset:96
	ds_read_b128 v[180:183], v208 offset:4704
	s_waitcnt lgkmcnt(5)
	v_mfma_f32_32x32x16_bf16 v[80:95], v[234:237], v[226:229], v[80:95]
	v_mfma_f32_32x32x16_bf16 v[16:31], v[234:237], v[230:233], v[16:31]
	ds_read_b128 v[234:237], v205 offset:96
	s_waitcnt lgkmcnt(5)
	v_mfma_f32_32x32x16_bf16 v[64:79], v[238:241], v[226:229], v[64:79]
	v_mfma_f32_32x32x16_bf16 v[0:15], v[238:241], v[230:233], v[0:15]
	ds_read_b128 v[238:241], v205 offset:4704
	s_setprio 0
	global_load_dwordx4 v[226:229], v[198:199], off offset:3712
	global_load_dwordx4 v[230:233], v[200:201], off offset:3712
	s_setprio 1
	s_waitcnt lgkmcnt(1)
	v_mfma_f32_32x32x16_bf16 v[112:127], v[234:237], v[176:179], v[112:127]
	v_mfma_f32_32x32x16_bf16 v[48:63], v[234:237], v[180:183], v[48:63]
	s_waitcnt lgkmcnt(0)
	v_mfma_f32_32x32x16_bf16 v[96:111], v[238:241], v[176:179], v[96:111]
	v_mfma_f32_32x32x16_bf16 v[32:47], v[238:241], v[180:183], v[32:47]
	ds_read_b128 v[234:237], v205 offset:9312
	ds_read_b128 v[238:241], v205 offset:13920
	s_waitcnt lgkmcnt(1)
	v_mfma_f32_32x32x16_bf16 v[80:95], v[234:237], v[176:179], v[80:95]
	v_mfma_f32_32x32x16_bf16 v[16:31], v[234:237], v[180:183], v[16:31]
	s_waitcnt lgkmcnt(0)
	v_mfma_f32_32x32x16_bf16 v[64:79], v[238:241], v[176:179], v[64:79]
	v_mfma_f32_32x32x16_bf16 v[0:15], v[238:241], v[180:183], v[0:15]
	s_setprio 0
	s_barrier
	global_load_dwordx4 v[176:179], v[190:191], off offset:3840
	global_load_dwordx4 v[180:183], v[188:189], off offset:3840
	s_waitcnt vmcnt(9)
	ds_write_b128 v209, v[168:171]
	s_waitcnt vmcnt(8)
	ds_write_b128 v210, v[172:175]
	ds_read_b128 v[168:171], v204 offset:36864
	ds_read_b128 v[172:175], v204 offset:41472
	ds_read_b128 v[234:237], v192
	ds_read_b128 v[238:241], v192 offset:4608
	s_setprio 1
	s_waitcnt lgkmcnt(1)
	v_mfma_f32_32x32x16_bf16 v[112:127], v[234:237], v[168:171], v[112:127]
	v_mfma_f32_32x32x16_bf16 v[48:63], v[234:237], v[172:175], v[48:63]
	s_waitcnt lgkmcnt(0)
	v_mfma_f32_32x32x16_bf16 v[96:111], v[238:241], v[168:171], v[96:111]
	v_mfma_f32_32x32x16_bf16 v[32:47], v[238:241], v[172:175], v[32:47]
	ds_read_b128 v[234:237], v192 offset:9216
	ds_read_b128 v[238:241], v192 offset:13824
	s_waitcnt lgkmcnt(1)
	v_mfma_f32_32x32x16_bf16 v[80:95], v[234:237], v[168:171], v[80:95]
	v_mfma_f32_32x32x16_bf16 v[16:31], v[234:237], v[172:175], v[16:31]
	s_waitcnt lgkmcnt(0)
	v_mfma_f32_32x32x16_bf16 v[64:79], v[238:241], v[168:171], v[64:79]
	v_mfma_f32_32x32x16_bf16 v[0:15], v[238:241], v[172:175], v[0:15]
	s_setprio 0
	global_load_dwordx4 v[234:237], v[194:195], off offset:3840
	global_load_dwordx4 v[238:241], v[196:197], off offset:3840
	s_waitcnt vmcnt(9)
	ds_write_b128 v212, v[160:163]
	s_waitcnt vmcnt(8)
	ds_write_b128 v211, v[164:167]
	ds_read_b128 v[160:163], v204 offset:36896
	ds_read_b128 v[164:167], v204 offset:41504
	ds_read_b128 v[168:171], v192 offset:32
	ds_read_b128 v[172:175], v192 offset:4640
	s_setprio 1
	s_waitcnt lgkmcnt(1)
	v_mfma_f32_32x32x16_bf16 v[112:127], v[168:171], v[160:163], v[112:127]
	v_mfma_f32_32x32x16_bf16 v[48:63], v[168:171], v[164:167], v[48:63]
	s_waitcnt lgkmcnt(0)
	v_mfma_f32_32x32x16_bf16 v[96:111], v[172:175], v[160:163], v[96:111]
	v_mfma_f32_32x32x16_bf16 v[32:47], v[172:175], v[164:167], v[32:47]
	ds_read_b128 v[168:171], v192 offset:9248
	ds_read_b128 v[172:175], v192 offset:13856
	s_waitcnt lgkmcnt(1)
	v_mfma_f32_32x32x16_bf16 v[80:95], v[168:171], v[160:163], v[80:95]
	v_mfma_f32_32x32x16_bf16 v[16:31], v[168:171], v[164:167], v[16:31]
	s_waitcnt lgkmcnt(0)
	v_mfma_f32_32x32x16_bf16 v[64:79], v[172:175], v[160:163], v[64:79]
	v_mfma_f32_32x32x16_bf16 v[0:15], v[172:175], v[164:167], v[0:15]
	s_setprio 0
	global_load_dwordx4 v[242:245], v[184:185], off offset:3840
	global_load_dwordx4 v[246:249], v[186:187], off offset:3840
	s_waitcnt vmcnt(9)
	ds_write_b128 v214, v[218:221]
	s_waitcnt vmcnt(8)
	ds_write_b128 v213, v[222:225]
	ds_read_b128 v[160:163], v204 offset:36928
	ds_read_b128 v[164:167], v204 offset:41536
	ds_read_b128 v[168:171], v192 offset:64
	ds_read_b128 v[172:175], v192 offset:4672
	s_setprio 1
	s_waitcnt lgkmcnt(1)
	v_mfma_f32_32x32x16_bf16 v[112:127], v[168:171], v[160:163], v[112:127]
	v_mfma_f32_32x32x16_bf16 v[48:63], v[168:171], v[164:167], v[48:63]
	s_waitcnt lgkmcnt(0)
	v_mfma_f32_32x32x16_bf16 v[96:111], v[172:175], v[160:163], v[96:111]
	v_mfma_f32_32x32x16_bf16 v[32:47], v[172:175], v[164:167], v[32:47]
	ds_read_b128 v[168:171], v192 offset:9280
	ds_read_b128 v[172:175], v192 offset:13888
	s_waitcnt lgkmcnt(1)
	v_mfma_f32_32x32x16_bf16 v[80:95], v[168:171], v[160:163], v[80:95]
	v_mfma_f32_32x32x16_bf16 v[16:31], v[168:171], v[164:167], v[16:31]
	s_waitcnt lgkmcnt(0)
	v_mfma_f32_32x32x16_bf16 v[64:79], v[172:175], v[160:163], v[64:79]
	v_mfma_f32_32x32x16_bf16 v[0:15], v[172:175], v[164:167], v[0:15]
	s_setprio 0
	global_load_dwordx4 v[218:221], v[198:199], off offset:3840
	global_load_dwordx4 v[222:225], v[200:201], off offset:3840
	s_waitcnt vmcnt(9)
	ds_write_b128 v217, v[226:229]
	s_waitcnt vmcnt(8)
	ds_write_b128 v216, v[230:233]
	ds_read_b128 v[160:163], v204 offset:36960
	ds_read_b128 v[164:167], v204 offset:41568
	ds_read_b128 v[168:171], v192 offset:96
	ds_read_b128 v[172:175], v192 offset:4704
	s_setprio 1
	s_waitcnt lgkmcnt(1)
	v_mfma_f32_32x32x16_bf16 v[112:127], v[168:171], v[160:163], v[112:127]
	v_mfma_f32_32x32x16_bf16 v[48:63], v[168:171], v[164:167], v[48:63]
	s_waitcnt lgkmcnt(0)
	v_mfma_f32_32x32x16_bf16 v[96:111], v[172:175], v[160:163], v[96:111]
	v_mfma_f32_32x32x16_bf16 v[32:47], v[172:175], v[164:167], v[32:47]
	ds_read_b128 v[168:171], v192 offset:9312
	ds_read_b128 v[172:175], v192 offset:13920
	s_waitcnt lgkmcnt(1)
	v_mfma_f32_32x32x16_bf16 v[80:95], v[168:171], v[160:163], v[80:95]
	v_mfma_f32_32x32x16_bf16 v[16:31], v[168:171], v[164:167], v[16:31]
	s_waitcnt lgkmcnt(0)
	v_mfma_f32_32x32x16_bf16 v[64:79], v[172:175], v[160:163], v[64:79]
	v_mfma_f32_32x32x16_bf16 v[0:15], v[172:175], v[164:167], v[0:15]
	s_setprio 0
	s_barrier
	global_load_dwordx4 v[160:163], v[190:191], off offset:3968
	global_load_dwordx4 v[164:167], v[188:189], off offset:3968
	s_waitcnt vmcnt(9)
	ds_write_b128 v215, v[176:179]
	s_waitcnt vmcnt(8)
	ds_write_b128 v215, v[180:183] offset:36864
	ds_read_b128 v[168:171], v208
	ds_read_b128 v[172:175], v208 offset:4608
	ds_read_b128 v[176:179], v205
	ds_read_b128 v[180:183], v205 offset:4608
	s_setprio 1
	s_waitcnt lgkmcnt(1)
	v_mfma_f32_32x32x16_bf16 v[112:127], v[176:179], v[168:171], v[112:127]
	v_mfma_f32_32x32x16_bf16 v[48:63], v[176:179], v[172:175], v[48:63]
	s_waitcnt lgkmcnt(0)
	v_mfma_f32_32x32x16_bf16 v[96:111], v[180:183], v[168:171], v[96:111]
	v_mfma_f32_32x32x16_bf16 v[32:47], v[180:183], v[172:175], v[32:47]
	ds_read_b128 v[176:179], v205 offset:9216
	ds_read_b128 v[180:183], v205 offset:13824
	s_waitcnt lgkmcnt(1)
	v_mfma_f32_32x32x16_bf16 v[80:95], v[176:179], v[168:171], v[80:95]
	v_mfma_f32_32x32x16_bf16 v[16:31], v[176:179], v[172:175], v[16:31]
	s_waitcnt lgkmcnt(0)
	v_mfma_f32_32x32x16_bf16 v[64:79], v[180:183], v[168:171], v[64:79]
	v_mfma_f32_32x32x16_bf16 v[0:15], v[180:183], v[172:175], v[0:15]
	s_setprio 0
	global_load_dwordx4 v[168:171], v[194:195], off offset:3968
	global_load_dwordx4 v[172:175], v[196:197], off offset:3968
	s_waitcnt vmcnt(9)
	ds_write_b128 v215, v[234:237] offset:9216
	s_waitcnt vmcnt(8)
	ds_write_b128 v215, v[238:241] offset:46080
	ds_read_b128 v[176:179], v208 offset:32
	ds_read_b128 v[180:183], v208 offset:4640
	ds_read_b128 v[188:191], v205 offset:32
	ds_read_b128 v[194:197], v205 offset:4640
	s_setprio 1
	s_waitcnt lgkmcnt(1)
	v_mfma_f32_32x32x16_bf16 v[112:127], v[188:191], v[176:179], v[112:127]
	v_mfma_f32_32x32x16_bf16 v[48:63], v[188:191], v[180:183], v[48:63]
	s_waitcnt lgkmcnt(0)
	v_mfma_f32_32x32x16_bf16 v[96:111], v[194:197], v[176:179], v[96:111]
	v_mfma_f32_32x32x16_bf16 v[32:47], v[194:197], v[180:183], v[32:47]
	ds_read_b128 v[188:191], v205 offset:9248
	ds_read_b128 v[194:197], v205 offset:13856
	s_waitcnt lgkmcnt(1)
	v_mfma_f32_32x32x16_bf16 v[80:95], v[188:191], v[176:179], v[80:95]
	v_mfma_f32_32x32x16_bf16 v[16:31], v[188:191], v[180:183], v[16:31]
	s_waitcnt lgkmcnt(0)
	v_mfma_f32_32x32x16_bf16 v[64:79], v[194:197], v[176:179], v[64:79]
	v_mfma_f32_32x32x16_bf16 v[0:15], v[194:197], v[180:183], v[0:15]
	s_setprio 0
	global_load_dwordx4 v[176:179], v[184:185], off offset:3968
	global_load_dwordx4 v[180:183], v[186:187], off offset:3968
	s_waitcnt vmcnt(9)
	ds_write_b128 v215, v[242:245] offset:18432
	s_waitcnt vmcnt(8)
	ds_write_b128 v215, v[246:249] offset:55296
	ds_read_b128 v[184:187], v208 offset:64
	ds_read_b128 v[188:191], v208 offset:4672
	ds_read_b128 v[194:197], v205 offset:64
	ds_read_b128 v[226:229], v205 offset:4672
	s_setprio 1
	s_waitcnt lgkmcnt(1)
	v_mfma_f32_32x32x16_bf16 v[112:127], v[194:197], v[184:187], v[112:127]
	v_mfma_f32_32x32x16_bf16 v[48:63], v[194:197], v[188:191], v[48:63]
	s_waitcnt lgkmcnt(0)
	v_mfma_f32_32x32x16_bf16 v[96:111], v[226:229], v[184:187], v[96:111]
	v_mfma_f32_32x32x16_bf16 v[32:47], v[226:229], v[188:191], v[32:47]
	ds_read_b128 v[194:197], v205 offset:9280
	ds_read_b128 v[226:229], v205 offset:13888
	s_waitcnt lgkmcnt(1)
	v_mfma_f32_32x32x16_bf16 v[80:95], v[194:197], v[184:187], v[80:95]
	v_mfma_f32_32x32x16_bf16 v[16:31], v[194:197], v[188:191], v[16:31]
	s_waitcnt lgkmcnt(0)
	v_mfma_f32_32x32x16_bf16 v[64:79], v[226:229], v[184:187], v[64:79]
	v_mfma_f32_32x32x16_bf16 v[0:15], v[226:229], v[188:191], v[0:15]
	s_setprio 0
	global_load_dwordx4 v[184:187], v[198:199], off offset:3968
	global_load_dwordx4 v[188:191], v[200:201], off offset:3968
	s_waitcnt vmcnt(9)
	ds_write_b128 v215, v[218:221] offset:27648
	s_waitcnt vmcnt(8)
	ds_write_b128 v215, v[222:225] offset:64512
	ds_read_b128 v[194:197], v208 offset:96
	ds_read_b128 v[198:201], v208 offset:4704
	ds_read_b128 v[218:221], v205 offset:96
	ds_read_b128 v[222:225], v205 offset:4704
	s_setprio 1
	s_waitcnt lgkmcnt(1)
	v_mfma_f32_32x32x16_bf16 v[112:127], v[218:221], v[194:197], v[112:127]
	v_mfma_f32_32x32x16_bf16 v[48:63], v[218:221], v[198:201], v[48:63]
	s_waitcnt lgkmcnt(0)
	v_mfma_f32_32x32x16_bf16 v[96:111], v[222:225], v[194:197], v[96:111]
	v_mfma_f32_32x32x16_bf16 v[32:47], v[222:225], v[198:201], v[32:47]
	ds_read_b128 v[218:221], v205 offset:9312
	ds_read_b128 v[222:225], v205 offset:13920
	s_waitcnt lgkmcnt(1)
	v_mfma_f32_32x32x16_bf16 v[80:95], v[218:221], v[194:197], v[80:95]
	v_mfma_f32_32x32x16_bf16 v[16:31], v[218:221], v[198:201], v[16:31]
	s_waitcnt lgkmcnt(0)
	v_mfma_f32_32x32x16_bf16 v[64:79], v[222:225], v[194:197], v[64:79]
	v_mfma_f32_32x32x16_bf16 v[0:15], v[222:225], v[198:201], v[0:15]
	s_setprio 0
	s_barrier
	s_waitcnt vmcnt(7)
	ds_write_b128 v209, v[160:163]
	s_waitcnt vmcnt(6)
	ds_write_b128 v210, v[164:167]
	ds_read_b128 v[194:197], v204 offset:36864
	ds_read_b128 v[198:201], v204 offset:41472
	ds_read_b128 v[218:221], v192
	ds_read_b128 v[222:225], v192 offset:4608
	s_setprio 1
	s_waitcnt lgkmcnt(1)
	v_mfma_f32_32x32x16_bf16 v[112:127], v[218:221], v[194:197], v[112:127]
	v_mfma_f32_32x32x16_bf16 v[48:63], v[218:221], v[198:201], v[48:63]
	s_waitcnt lgkmcnt(0)
	v_mfma_f32_32x32x16_bf16 v[96:111], v[222:225], v[194:197], v[96:111]
	v_mfma_f32_32x32x16_bf16 v[32:47], v[222:225], v[198:201], v[32:47]
	ds_read_b128 v[218:221], v192 offset:9216
	ds_read_b128 v[222:225], v192 offset:13824
	s_waitcnt lgkmcnt(1)
	v_mfma_f32_32x32x16_bf16 v[80:95], v[218:221], v[194:197], v[80:95]
	v_mfma_f32_32x32x16_bf16 v[16:31], v[218:221], v[198:201], v[16:31]
	s_waitcnt lgkmcnt(0)
	v_mfma_f32_32x32x16_bf16 v[64:79], v[222:225], v[194:197], v[64:79]
	v_mfma_f32_32x32x16_bf16 v[0:15], v[222:225], v[198:201], v[0:15]
	s_setprio 0
	s_waitcnt vmcnt(5)
	ds_write_b128 v212, v[168:171]
	s_waitcnt vmcnt(4)
	ds_write_b128 v211, v[172:175]
	ds_read_b128 v[194:197], v204 offset:36896
	ds_read_b128 v[198:201], v204 offset:41504
	ds_read_b128 v[218:221], v192 offset:32
	ds_read_b128 v[222:225], v192 offset:4640
	s_setprio 1
	s_waitcnt lgkmcnt(1)
	v_mfma_f32_32x32x16_bf16 v[112:127], v[218:221], v[194:197], v[112:127]
	v_mfma_f32_32x32x16_bf16 v[48:63], v[218:221], v[198:201], v[48:63]
	s_waitcnt lgkmcnt(0)
	v_mfma_f32_32x32x16_bf16 v[96:111], v[222:225], v[194:197], v[96:111]
	v_mfma_f32_32x32x16_bf16 v[32:47], v[222:225], v[198:201], v[32:47]
	ds_read_b128 v[218:221], v192 offset:9248
	ds_read_b128 v[222:225], v192 offset:13856
	s_waitcnt lgkmcnt(1)
	v_mfma_f32_32x32x16_bf16 v[80:95], v[218:221], v[194:197], v[80:95]
	v_mfma_f32_32x32x16_bf16 v[16:31], v[218:221], v[198:201], v[16:31]
	s_waitcnt lgkmcnt(0)
	v_mfma_f32_32x32x16_bf16 v[64:79], v[222:225], v[194:197], v[64:79]
	v_mfma_f32_32x32x16_bf16 v[0:15], v[222:225], v[198:201], v[0:15]
	s_setprio 0
	s_waitcnt vmcnt(3)
	ds_write_b128 v214, v[176:179]
	s_waitcnt vmcnt(2)
	ds_write_b128 v213, v[180:183]
	ds_read_b128 v[194:197], v204 offset:36928
	ds_read_b128 v[198:201], v204 offset:41536
	ds_read_b128 v[210:213], v192 offset:64
	ds_read_b128 v[218:221], v192 offset:4672
	s_setprio 1
	s_waitcnt lgkmcnt(1)
	v_mfma_f32_32x32x16_bf16 v[112:127], v[210:213], v[194:197], v[112:127]
	v_mfma_f32_32x32x16_bf16 v[48:63], v[210:213], v[198:201], v[48:63]
	s_waitcnt lgkmcnt(0)
	v_mfma_f32_32x32x16_bf16 v[96:111], v[218:221], v[194:197], v[96:111]
	v_mfma_f32_32x32x16_bf16 v[32:47], v[218:221], v[198:201], v[32:47]
	ds_read_b128 v[210:213], v192 offset:9280
	ds_read_b128 v[218:221], v192 offset:13888
	s_waitcnt lgkmcnt(1)
	v_mfma_f32_32x32x16_bf16 v[80:95], v[210:213], v[194:197], v[80:95]
	v_mfma_f32_32x32x16_bf16 v[16:31], v[210:213], v[198:201], v[16:31]
	s_waitcnt lgkmcnt(0)
	v_mfma_f32_32x32x16_bf16 v[64:79], v[218:221], v[194:197], v[64:79]
	v_mfma_f32_32x32x16_bf16 v[0:15], v[218:221], v[198:201], v[0:15]
	s_setprio 0
	s_waitcnt vmcnt(1)
	ds_write_b128 v217, v[184:187]
	s_waitcnt vmcnt(0)
	ds_write_b128 v216, v[188:191]
	ds_read_b128 v[194:197], v204 offset:36960
	ds_read_b128 v[198:201], v204 offset:41568
	ds_read_b128 v[210:213], v192 offset:96
	ds_read_b128 v[214:217], v192 offset:4704
	s_setprio 1
	s_waitcnt lgkmcnt(1)
	v_mfma_f32_32x32x16_bf16 v[112:127], v[210:213], v[194:197], v[112:127]
	v_mfma_f32_32x32x16_bf16 v[48:63], v[210:213], v[198:201], v[48:63]
	s_waitcnt lgkmcnt(0)
	v_mfma_f32_32x32x16_bf16 v[96:111], v[214:217], v[194:197], v[96:111]
	v_mfma_f32_32x32x16_bf16 v[32:47], v[214:217], v[198:201], v[32:47]
	ds_read_b128 v[210:213], v192 offset:9312
	ds_read_b128 v[214:217], v192 offset:13920
	s_waitcnt lgkmcnt(1)
	v_mfma_f32_32x32x16_bf16 v[80:95], v[210:213], v[194:197], v[80:95]
	v_mfma_f32_32x32x16_bf16 v[16:31], v[210:213], v[198:201], v[16:31]
	s_waitcnt lgkmcnt(0)
	v_mfma_f32_32x32x16_bf16 v[64:79], v[214:217], v[194:197], v[64:79]
	v_mfma_f32_32x32x16_bf16 v[0:15], v[214:217], v[198:201], v[0:15]
	s_setprio 0
	s_barrier
; template <bool trans>
; DI void gemm_core(const GTile& tl, const GTile& nx, bool has_next  , bool chain  , bool pre, u32x4 (&ra)[4], u32x4 (&rb)[4], char* smem, f32x16 (&acc)[2][4]) {
;     ...
;   const int nk = K / 64;
;   if (!pre) { G_LOAD(0); G_STORE(0); G_LOAD(1); }
;   for (int kt = 0; kt < nk; ++kt) {
;     __syncthreads();
;     G_COMPUTE(kt & 1, kt);
;   }
;   if (!has_next) __syncthreads();
	ds_read_b128 v[194:197], v208
	ds_read_b128 v[198:201], v208 offset:4608
	ds_read_b128 v[210:213], v205
	ds_read_b128 v[214:217], v205 offset:4608
	s_setprio 1
	s_waitcnt lgkmcnt(1)
	v_mfma_f32_32x32x16_bf16 v[112:127], v[210:213], v[194:197], v[112:127]
	v_mfma_f32_32x32x16_bf16 v[48:63], v[210:213], v[198:201], v[48:63]
	s_waitcnt lgkmcnt(0)
	v_mfma_f32_32x32x16_bf16 v[96:111], v[214:217], v[194:197], v[96:111]
	v_mfma_f32_32x32x16_bf16 v[32:47], v[214:217], v[198:201], v[32:47]
	ds_read_b128 v[210:213], v205 offset:9216
	ds_read_b128 v[214:217], v205 offset:13824
	s_waitcnt lgkmcnt(1)
	v_mfma_f32_32x32x16_bf16 v[80:95], v[210:213], v[194:197], v[80:95]
	v_mfma_f32_32x32x16_bf16 v[16:31], v[210:213], v[198:201], v[16:31]
	s_waitcnt lgkmcnt(0)
	v_mfma_f32_32x32x16_bf16 v[64:79], v[214:217], v[194:197], v[64:79]
	v_mfma_f32_32x32x16_bf16 v[0:15], v[214:217], v[198:201], v[0:15]
	s_setprio 0
	ds_read_b128 v[194:197], v208 offset:32
	ds_read_b128 v[198:201], v208 offset:4640
	ds_read_b128 v[210:213], v205 offset:32
	ds_read_b128 v[214:217], v205 offset:4640
	s_setprio 1
	s_waitcnt lgkmcnt(1)
	v_mfma_f32_32x32x16_bf16 v[112:127], v[210:213], v[194:197], v[112:127]
	v_mfma_f32_32x32x16_bf16 v[48:63], v[210:213], v[198:201], v[48:63]
	s_waitcnt lgkmcnt(0)
	v_mfma_f32_32x32x16_bf16 v[96:111], v[214:217], v[194:197], v[96:111]
	v_mfma_f32_32x32x16_bf16 v[32:47], v[214:217], v[198:201], v[32:47]
	ds_read_b128 v[210:213], v205 offset:9248
	ds_read_b128 v[214:217], v205 offset:13856
	s_waitcnt lgkmcnt(1)
	v_mfma_f32_32x32x16_bf16 v[80:95], v[210:213], v[194:197], v[80:95]
	v_mfma_f32_32x32x16_bf16 v[16:31], v[210:213], v[198:201], v[16:31]
	s_waitcnt lgkmcnt(0)
	v_mfma_f32_32x32x16_bf16 v[64:79], v[214:217], v[194:197], v[64:79]
	v_mfma_f32_32x32x16_bf16 v[0:15], v[214:217], v[198:201], v[0:15]
	s_setprio 0
	ds_read_b128 v[194:197], v208 offset:64
	ds_read_b128 v[198:201], v208 offset:4672
	ds_read_b128 v[210:213], v205 offset:64
	ds_read_b128 v[214:217], v205 offset:4672
	s_setprio 1
	s_waitcnt lgkmcnt(1)
	v_mfma_f32_32x32x16_bf16 v[112:127], v[210:213], v[194:197], v[112:127]
	v_mfma_f32_32x32x16_bf16 v[48:63], v[210:213], v[198:201], v[48:63]
	s_waitcnt lgkmcnt(0)
	v_mfma_f32_32x32x16_bf16 v[96:111], v[214:217], v[194:197], v[96:111]
	v_mfma_f32_32x32x16_bf16 v[32:47], v[214:217], v[198:201], v[32:47]
	ds_read_b128 v[210:213], v205 offset:9280
	ds_read_b128 v[214:217], v205 offset:13888
	s_waitcnt lgkmcnt(1)
	v_mfma_f32_32x32x16_bf16 v[80:95], v[210:213], v[194:197], v[80:95]
	v_mfma_f32_32x32x16_bf16 v[16:31], v[210:213], v[198:201], v[16:31]
	s_waitcnt lgkmcnt(0)
	v_mfma_f32_32x32x16_bf16 v[64:79], v[214:217], v[194:197], v[64:79]
	v_mfma_f32_32x32x16_bf16 v[0:15], v[214:217], v[198:201], v[0:15]
	s_setprio 0
	ds_read_b128 v[194:197], v208 offset:96
	ds_read_b128 v[198:201], v208 offset:4704
	ds_read_b128 v[208:211], v205 offset:96
	ds_read_b128 v[212:215], v205 offset:4704
	s_setprio 1
	s_waitcnt lgkmcnt(1)
	v_mfma_f32_32x32x16_bf16 v[112:127], v[208:211], v[194:197], v[112:127]
	v_mfma_f32_32x32x16_bf16 v[48:63], v[208:211], v[198:201], v[48:63]
	s_waitcnt lgkmcnt(0)
	v_mfma_f32_32x32x16_bf16 v[96:111], v[212:215], v[194:197], v[96:111]
	v_mfma_f32_32x32x16_bf16 v[32:47], v[212:215], v[198:201], v[32:47]
	ds_read_b128 v[208:211], v205 offset:9312
	ds_read_b128 v[212:215], v205 offset:13920
	s_waitcnt lgkmcnt(1)
	v_mfma_f32_32x32x16_bf16 v[80:95], v[208:211], v[194:197], v[80:95]
	v_mfma_f32_32x32x16_bf16 v[16:31], v[208:211], v[198:201], v[16:31]
	s_waitcnt lgkmcnt(0)
	v_mfma_f32_32x32x16_bf16 v[64:79], v[212:215], v[194:197], v[64:79]
	v_mfma_f32_32x32x16_bf16 v[0:15], v[212:215], v[198:201], v[0:15]
	s_setprio 0
	s_andn2_b64 vcc, exec, s[30:31]
	s_cbranch_vccnz .LBB0_884
	s_barrier

;   DI bf16_t* wt_in1() const { return (bf16_t*)(ws + OFF_WT_IN1); }
;   DI bf16_t* h() const { return (bf16_t*)(ws + OFF_H); }
; DI int in1_nt(int t) { return (t >> 6) < 23 ? (t >> 6) : 25; }
; template <bool trans>
; DI void gemm_core(const GTile& tl, const GTile& nx, bool has_next  , bool chain  , bool pre, u32x4 (&ra)[4], u32x4 (&rb)[4], char* smem, f32x16 (&acc)[2][4]) {
;     ...
;   const int lrow = tid >> 3, kc = tid & 7;
;   const unsigned aoff = (unsigned)(lrow * lda + kc * 8) * 2u, boff = (unsigned)(lrow * ldb + kc * 8) * 2u;
;   const char* ag = (const char*)(A + (size_t)m0 * lda);
;   const char* bg = (const char*)(Bt + (size_t)n0 * ldb);
;   const unsigned aoffn = (unsigned)(lrow * nx.lda + kc * 8) * 2u, boffn = (unsigned)(lrow * nx.ldb + kc * 8) * 2u;
;   const char* agn = (const char*)(nx.A + (size_t)nx.m0 * nx.lda);
;   const char* bgn = (const char*)(nx.Bt + (size_t)nx.n0 * nx.ldb);
;     ...
;   const int nk = K / 64;
;   if (!pre) { G_LOAD(0); G_STORE(0); G_LOAD(1); }
;   for (int kt = 0; kt < nk; ++kt) {
;     __syncthreads();
;     G_COMPUTE(kt & 1, kt);
; DI void phase_gemm_in1(const Params& p, char* smem) {
;     ...
;   for (int t = blockIdx.x; t < 64 * 24; t += gridDim.x) {
;     const int mt = t & 63, nt = in1_nt(t), tn = t + gridDim.x;
;     const bool has_next = tn < 64 * 24;
;     const GTile tl{p.h(), D, p.wt_in1(), D, D, mt * 256, nt * 256}, nx{p.h(), D, p.wt_in1(), D, D, (tn & 63) * 256, in1_nt(tn) * 256};
.LBB0_890:
	v_lshl_add_u64 v[136:137], s[2:3], 0, v[192:193]
	v_lshl_add_u64 v[138:139], s[16:17], 0, v[192:193]
	s_waitcnt lgkmcnt(0)
	s_barrier
	global_load_dwordx4 v[184:187], v[136:137], off offset:256
	global_load_dwordx4 v[188:191], v[138:139], off offset:256
	s_ashr_i32 s2, s56, 6
	s_lshl_b32 s3, s2, 8
	s_cmp_lt_i32 s2, 23
	s_cselect_b32 s2, s3, 0x1900
	s_and_b32 s3, s49, 0x1f80000
	s_and_b32 s16, s18, 0xc0
	s_lshl_b32 s3, s3, 1
	s_add_u32 s6, s24, s3
	s_addc_u32 s7, s25, 0
	s_ashr_i32 s3, s2, 31
	s_lshl_b64 s[2:3], s[2:3], 12
	s_add_u32 s2, s27, s2
	s_addc_u32 s3, s40, s3
	s_lshr_b32 s17, s18, 1
	v_and_b32_e32 v11, 31, v8
	s_and_b32 s17, s17, 0xfffff80
	v_or_b32_e32 v12, s17, v11
	v_or_b32_e32 v11, s16, v11
	v_add3_u32 v148, 16, v10, v9
	v_lshrrev_b32_e32 v8, 1, v8
	v_mul_u32_u24_e32 v150, 0x90, v11
	v_lshl_add_u64 v[130:131], s[6:7], 0, v[192:193]
	v_lshl_add_u64 v[128:129], s[2:3], 0, v[192:193]
	v_and_b32_e32 v204, 16, v8
	v_add_u32_e32 v192, 0x12000, v148
	v_mul_lo_u32 v149, v12, s54
	v_add3_u32 v152, 16, v150, v204
	v_add_u32_e32 v159, 0x1b000, v148
	ds_write_b128 v192, v[0:3]
	s_waitcnt vmcnt(5)
	ds_write_b128 v159, v[4:7]
	v_add3_u32 v151, 16, v149, v204
	ds_read_b128 v[0:3], v152 offset:36864
	ds_read_b128 v[16:19], v152 offset:41472
	ds_read_b128 v[4:7], v151
	ds_read_b128 v[8:11], v151 offset:4608
	v_lshl_add_u64 v[140:141], v[136:137], 0, s[12:13]
	v_lshl_add_u64 v[142:143], v[138:139], 0, s[12:13]
	v_lshl_add_u64 v[132:133], v[136:137], 0, s[14:15]
	v_lshl_add_u64 v[134:135], v[138:139], 0, s[14:15]
	s_setprio 1
	s_waitcnt lgkmcnt(1)
	v_mfma_f32_32x32x16_bf16 v[96:111], v[0:3], v[4:7], 0
	v_mfma_f32_32x32x16_bf16 v[112:127], v[16:19], v[4:7], 0
	ds_read_b128 v[4:7], v151 offset:9216
	ds_read_b128 v[20:23], v151 offset:13824
	s_waitcnt lgkmcnt(2)
	v_mfma_f32_32x32x16_bf16 v[64:79], v[0:3], v[8:11], 0
	v_mfma_f32_32x32x16_bf16 v[80:95], v[16:19], v[8:11], 0
	s_waitcnt lgkmcnt(1)
	v_mfma_f32_32x32x16_bf16 v[32:47], v[0:3], v[4:7], 0
	v_mfma_f32_32x32x16_bf16 v[48:63], v[16:19], v[4:7], 0
	s_waitcnt lgkmcnt(0)
	v_mfma_f32_32x32x16_bf16 v[0:15], v[0:3], v[20:23], 0
	v_mfma_f32_32x32x16_bf16 v[16:31], v[16:19], v[20:23], 0
	s_setprio 0
	global_load_dwordx4 v[194:197], v[140:141], off offset:256
	global_load_dwordx4 v[198:201], v[142:143], off offset:256
	v_add_u32_e32 v158, 0x14400, v148
	v_add_u32_e32 v157, 0x1d400, v148
	ds_write_b128 v158, v[176:179]
	s_waitcnt vmcnt(6)
	ds_write_b128 v157, v[180:183]
	ds_read_b128 v[144:147], v152 offset:36896
	ds_read_b128 v[176:179], v152 offset:41504
	ds_read_b128 v[180:183], v151 offset:32
	ds_read_b128 v[208:211], v151 offset:4640
	s_setprio 1
	s_waitcnt lgkmcnt(1)
	v_mfma_f32_32x32x16_bf16 v[96:111], v[144:147], v[180:183], v[96:111]
	v_mfma_f32_32x32x16_bf16 v[112:127], v[176:179], v[180:183], v[112:127]
	s_waitcnt lgkmcnt(0)
	v_mfma_f32_32x32x16_bf16 v[64:79], v[144:147], v[208:211], v[64:79]
	v_mfma_f32_32x32x16_bf16 v[80:95], v[176:179], v[208:211], v[80:95]
	ds_read_b128 v[180:183], v151 offset:9248
	ds_read_b128 v[208:211], v151 offset:13856
	s_waitcnt lgkmcnt(1)
	v_mfma_f32_32x32x16_bf16 v[32:47], v[144:147], v[180:183], v[32:47]
	v_mfma_f32_32x32x16_bf16 v[48:63], v[176:179], v[180:183], v[48:63]
	s_waitcnt lgkmcnt(0)
	v_mfma_f32_32x32x16_bf16 v[0:15], v[144:147], v[208:211], v[0:15]
	v_mfma_f32_32x32x16_bf16 v[16:31], v[176:179], v[208:211], v[16:31]
	s_setprio 0
	global_load_dwordx4 v[176:179], v[132:133], off offset:256
	global_load_dwordx4 v[180:183], v[134:135], off offset:256
	v_add_u32_e32 v154, 0x16800, v148
	v_add_u32_e32 v153, 0x1f800, v148
	ds_write_b128 v154, v[168:171]
	s_waitcnt vmcnt(7)
	ds_write_b128 v153, v[172:175]
	ds_read_b128 v[144:147], v152 offset:36928
	ds_read_b128 v[168:171], v152 offset:41536
	ds_read_b128 v[172:175], v151 offset:64
	ds_read_b128 v[208:211], v151 offset:4672
	s_setprio 1
	s_waitcnt lgkmcnt(1)
	v_mfma_f32_32x32x16_bf16 v[96:111], v[144:147], v[172:175], v[96:111]
	v_mfma_f32_32x32x16_bf16 v[112:127], v[168:171], v[172:175], v[112:127]
	s_waitcnt lgkmcnt(0)
	v_mfma_f32_32x32x16_bf16 v[64:79], v[144:147], v[208:211], v[64:79]
	v_mfma_f32_32x32x16_bf16 v[80:95], v[168:171], v[208:211], v[80:95]
	ds_read_b128 v[172:175], v151 offset:9280
	ds_read_b128 v[208:211], v151 offset:13888
	s_waitcnt lgkmcnt(1)
	v_mfma_f32_32x32x16_bf16 v[32:47], v[144:147], v[172:175], v[32:47]
	v_mfma_f32_32x32x16_bf16 v[48:63], v[168:171], v[172:175], v[48:63]
	s_waitcnt lgkmcnt(0)
	v_mfma_f32_32x32x16_bf16 v[0:15], v[144:147], v[208:211], v[0:15]
	v_mfma_f32_32x32x16_bf16 v[16:31], v[168:171], v[208:211], v[16:31]
	s_setprio 0
	v_add_co_u32_e32 v144, vcc, s53, v136
	v_add_u32_e32 v156, 0x18c00, v148
	s_nop 0
	v_addc_co_u32_e32 v145, vcc, 0, v137, vcc
	v_add_co_u32_e32 v146, vcc, s53, v138
	v_add_u32_e32 v155, 0x21c00, v148
	s_nop 0
	v_addc_co_u32_e32 v147, vcc, 0, v139, vcc
	global_load_dwordx4 v[168:171], v[144:145], off offset:256
	global_load_dwordx4 v[172:175], v[146:147], off offset:256
	ds_write_b128 v156, v[160:163]
	s_waitcnt vmcnt(8)
	ds_write_b128 v155, v[164:167]
	ds_read_b128 v[160:163], v152 offset:36960
	ds_read_b128 v[164:167], v152 offset:41568
	ds_read_b128 v[208:211], v151 offset:96
	ds_read_b128 v[212:215], v151 offset:4704
	s_setprio 1
	s_waitcnt lgkmcnt(1)
	v_mfma_f32_32x32x16_bf16 v[96:111], v[160:163], v[208:211], v[96:111]
	v_mfma_f32_32x32x16_bf16 v[112:127], v[164:167], v[208:211], v[112:127]
	s_waitcnt lgkmcnt(0)
	v_mfma_f32_32x32x16_bf16 v[64:79], v[160:163], v[212:215], v[64:79]
	v_mfma_f32_32x32x16_bf16 v[80:95], v[164:167], v[212:215], v[80:95]
	ds_read_b128 v[208:211], v151 offset:9312
	ds_read_b128 v[212:215], v151 offset:13920
	s_waitcnt lgkmcnt(1)
	v_mfma_f32_32x32x16_bf16 v[32:47], v[160:163], v[208:211], v[32:47]
	v_mfma_f32_32x32x16_bf16 v[48:63], v[164:167], v[208:211], v[48:63]
	s_waitcnt lgkmcnt(0)
	v_mfma_f32_32x32x16_bf16 v[0:15], v[160:163], v[212:215], v[0:15]
	v_mfma_f32_32x32x16_bf16 v[16:31], v[164:167], v[212:215], v[16:31]
	s_setprio 0
	s_barrier
; template <bool trans>
; DI void gemm_core(const GTile& tl, const GTile& nx, bool has_next  , bool chain  , bool pre, u32x4 (&ra)[4], u32x4 (&rb)[4], char* smem, f32x16 (&acc)[2][4]) {
;     ...
;   const int nk = K / 64;
;   if (!pre) { G_LOAD(0); G_STORE(0); G_LOAD(1); }
;   for (int kt = 0; kt < nk; ++kt) {
;     __syncthreads();
;     G_COMPUTE(kt & 1, kt);
	global_load_dwordx4 v[160:163], v[136:137], off offset:384
	global_load_dwordx4 v[164:167], v[138:139], off offset:384
	s_add_i32 s2, 16, 0x12000
	v_add3_u32 v149, s2, v149, v204
	s_add_i32 s2, 16, 0x1b000
	v_add3_u32 v150, s2, v150, v204
	s_waitcnt vmcnt(9)
	ds_write_b128 v148, v[184:187]
	s_waitcnt vmcnt(8)
	ds_write_b128 v148, v[188:191] offset:36864
	ds_read_b128 v[184:187], v150
	ds_read_b128 v[188:191], v150 offset:4608
	ds_read_b128 v[208:211], v149
	ds_read_b128 v[212:215], v149 offset:4608
	s_setprio 1
	s_waitcnt lgkmcnt(1)
	v_mfma_f32_32x32x16_bf16 v[96:111], v[184:187], v[208:211], v[96:111]
	v_mfma_f32_32x32x16_bf16 v[112:127], v[188:191], v[208:211], v[112:127]
	s_waitcnt lgkmcnt(0)
	v_mfma_f32_32x32x16_bf16 v[64:79], v[184:187], v[212:215], v[64:79]
	v_mfma_f32_32x32x16_bf16 v[80:95], v[188:191], v[212:215], v[80:95]
	ds_read_b128 v[208:211], v149 offset:9216
	ds_read_b128 v[212:215], v149 offset:13824
	s_waitcnt lgkmcnt(1)
	v_mfma_f32_32x32x16_bf16 v[32:47], v[184:187], v[208:211], v[32:47]
	v_mfma_f32_32x32x16_bf16 v[48:63], v[188:191], v[208:211], v[48:63]
	s_waitcnt lgkmcnt(0)
	v_mfma_f32_32x32x16_bf16 v[0:15], v[184:187], v[212:215], v[0:15]
	v_mfma_f32_32x32x16_bf16 v[16:31], v[188:191], v[212:215], v[16:31]
	s_setprio 0
	global_load_dwordx4 v[184:187], v[140:141], off offset:384
	global_load_dwordx4 v[188:191], v[142:143], off offset:384
	s_waitcnt vmcnt(9)
	ds_write_b128 v148, v[194:197] offset:9216
	s_waitcnt vmcnt(8)
	ds_write_b128 v148, v[198:201] offset:46080
	ds_read_b128 v[194:197], v150 offset:32
	ds_read_b128 v[198:201], v150 offset:4640
	ds_read_b128 v[208:211], v149 offset:32
	ds_read_b128 v[212:215], v149 offset:4640
	s_setprio 1
	s_waitcnt lgkmcnt(1)
	v_mfma_f32_32x32x16_bf16 v[96:111], v[194:197], v[208:211], v[96:111]
	v_mfma_f32_32x32x16_bf16 v[112:127], v[198:201], v[208:211], v[112:127]
	s_waitcnt lgkmcnt(0)
	v_mfma_f32_32x32x16_bf16 v[64:79], v[194:197], v[212:215], v[64:79]
	v_mfma_f32_32x32x16_bf16 v[80:95], v[198:201], v[212:215], v[80:95]
	ds_read_b128 v[208:211], v149 offset:9248
	ds_read_b128 v[212:215], v149 offset:13856
	s_waitcnt lgkmcnt(1)
	v_mfma_f32_32x32x16_bf16 v[32:47], v[194:197], v[208:211], v[32:47]
	v_mfma_f32_32x32x16_bf16 v[48:63], v[198:201], v[208:211], v[48:63]
	s_waitcnt lgkmcnt(0)
	v_mfma_f32_32x32x16_bf16 v[0:15], v[194:197], v[212:215], v[0:15]
	v_mfma_f32_32x32x16_bf16 v[16:31], v[198:201], v[212:215], v[16:31]
	s_setprio 0
	global_load_dwordx4 v[194:197], v[132:133], off offset:384
	global_load_dwordx4 v[198:201], v[134:135], off offset:384
	s_waitcnt vmcnt(9)
	ds_write_b128 v148, v[176:179] offset:18432
	s_waitcnt vmcnt(8)
	ds_write_b128 v148, v[180:183] offset:55296
	ds_read_b128 v[176:179], v150 offset:64
	ds_read_b128 v[180:183], v150 offset:4672
	ds_read_b128 v[208:211], v149 offset:64
	ds_read_b128 v[212:215], v149 offset:4672
	s_setprio 1
	s_waitcnt lgkmcnt(1)
	v_mfma_f32_32x32x16_bf16 v[96:111], v[176:179], v[208:211], v[96:111]
	v_mfma_f32_32x32x16_bf16 v[112:127], v[180:183], v[208:211], v[112:127]
	s_waitcnt lgkmcnt(0)
	v_mfma_f32_32x32x16_bf16 v[64:79], v[176:179], v[212:215], v[64:79]
	v_mfma_f32_32x32x16_bf16 v[80:95], v[180:183], v[212:215], v[80:95]
	ds_read_b128 v[208:211], v149 offset:9280
	ds_read_b128 v[212:215], v149 offset:13888
	s_waitcnt lgkmcnt(1)
	v_mfma_f32_32x32x16_bf16 v[32:47], v[176:179], v[208:211], v[32:47]
	v_mfma_f32_32x32x16_bf16 v[48:63], v[180:183], v[208:211], v[48:63]
	s_waitcnt lgkmcnt(0)
	v_mfma_f32_32x32x16_bf16 v[0:15], v[176:179], v[212:215], v[0:15]
	v_mfma_f32_32x32x16_bf16 v[16:31], v[180:183], v[212:215], v[16:31]
	s_setprio 0
	global_load_dwordx4 v[176:179], v[144:145], off offset:384
	global_load_dwordx4 v[180:183], v[146:147], off offset:384
	s_waitcnt vmcnt(9)
	ds_write_b128 v148, v[168:171] offset:27648
	s_waitcnt vmcnt(8)
	ds_write_b128 v148, v[172:175] offset:64512
	ds_read_b128 v[168:171], v150 offset:96
	ds_read_b128 v[172:175], v150 offset:4704
	ds_read_b128 v[208:211], v149 offset:96
	ds_read_b128 v[212:215], v149 offset:4704
	s_setprio 1
	s_waitcnt lgkmcnt(1)
	v_mfma_f32_32x32x16_bf16 v[96:111], v[168:171], v[208:211], v[96:111]
	v_mfma_f32_32x32x16_bf16 v[112:127], v[172:175], v[208:211], v[112:127]
	s_waitcnt lgkmcnt(0)
	v_mfma_f32_32x32x16_bf16 v[64:79], v[168:171], v[212:215], v[64:79]
	v_mfma_f32_32x32x16_bf16 v[80:95], v[172:175], v[212:215], v[80:95]
	ds_read_b128 v[208:211], v149 offset:9312
	ds_read_b128 v[212:215], v149 offset:13920
	s_waitcnt lgkmcnt(1)
	v_mfma_f32_32x32x16_bf16 v[32:47], v[168:171], v[208:211], v[32:47]
	v_mfma_f32_32x32x16_bf16 v[48:63], v[172:175], v[208:211], v[48:63]
	s_waitcnt lgkmcnt(0)
	v_mfma_f32_32x32x16_bf16 v[0:15], v[168:171], v[212:215], v[0:15]
	v_mfma_f32_32x32x16_bf16 v[16:31], v[172:175], v[212:215], v[16:31]
	s_setprio 0
	s_barrier
	global_load_dwordx4 v[168:171], v[136:137], off offset:512
	global_load_dwordx4 v[172:175], v[138:139], off offset:512
	s_waitcnt vmcnt(9)
	ds_write_b128 v192, v[160:163]
	s_waitcnt vmcnt(8)
	ds_write_b128 v159, v[164:167]
	ds_read_b128 v[160:163], v152 offset:36864
	ds_read_b128 v[164:167], v152 offset:41472
	ds_read_b128 v[208:211], v151
	ds_read_b128 v[212:215], v151 offset:4608
	s_setprio 1
	s_waitcnt lgkmcnt(1)
	v_mfma_f32_32x32x16_bf16 v[96:111], v[160:163], v[208:211], v[96:111]
	v_mfma_f32_32x32x16_bf16 v[112:127], v[164:167], v[208:211], v[112:127]
	s_waitcnt lgkmcnt(0)
	v_mfma_f32_32x32x16_bf16 v[64:79], v[160:163], v[212:215], v[64:79]
	v_mfma_f32_32x32x16_bf16 v[80:95], v[164:167], v[212:215], v[80:95]
	ds_read_b128 v[208:211], v151 offset:9216
	ds_read_b128 v[212:215], v151 offset:13824
	s_waitcnt vmcnt(7)
	ds_write_b128 v158, v[184:187]
	s_waitcnt vmcnt(6)
	ds_write_b128 v157, v[188:191]
	ds_read_b128 v[184:187], v152 offset:36896
	ds_read_b128 v[188:191], v152 offset:41504
	s_waitcnt lgkmcnt(5)
	v_mfma_f32_32x32x16_bf16 v[32:47], v[160:163], v[208:211], v[32:47]
	v_mfma_f32_32x32x16_bf16 v[48:63], v[164:167], v[208:211], v[48:63]
	ds_read_b128 v[208:211], v151 offset:32
	s_waitcnt lgkmcnt(5)
	v_mfma_f32_32x32x16_bf16 v[0:15], v[160:163], v[212:215], v[0:15]
	v_mfma_f32_32x32x16_bf16 v[16:31], v[164:167], v[212:215], v[16:31]
	ds_read_b128 v[212:215], v151 offset:4640
	s_setprio 0
	global_load_dwordx4 v[160:163], v[140:141], off offset:512
	global_load_dwordx4 v[164:167], v[142:143], off offset:512
	s_setprio 1
	s_waitcnt lgkmcnt(1)
	v_mfma_f32_32x32x16_bf16 v[96:111], v[184:187], v[208:211], v[96:111]
	v_mfma_f32_32x32x16_bf16 v[112:127], v[188:191], v[208:211], v[112:127]
	s_waitcnt lgkmcnt(0)
	v_mfma_f32_32x32x16_bf16 v[64:79], v[184:187], v[212:215], v[64:79]
	v_mfma_f32_32x32x16_bf16 v[80:95], v[188:191], v[212:215], v[80:95]
	ds_read_b128 v[208:211], v151 offset:9248
	ds_read_b128 v[212:215], v151 offset:13856
	s_waitcnt vmcnt(7)
	ds_write_b128 v154, v[194:197]
	s_waitcnt vmcnt(6)
	ds_write_b128 v153, v[198:201]
	ds_read_b128 v[194:197], v152 offset:36928
	ds_read_b128 v[198:201], v152 offset:41536
	s_waitcnt lgkmcnt(5)
	v_mfma_f32_32x32x16_bf16 v[32:47], v[184:187], v[208:211], v[32:47]
	v_mfma_f32_32x32x16_bf16 v[48:63], v[188:191], v[208:211], v[48:63]
	ds_read_b128 v[208:211], v151 offset:64
	s_waitcnt lgkmcnt(5)
	v_mfma_f32_32x32x16_bf16 v[0:15], v[184:187], v[212:215], v[0:15]
	v_mfma_f32_32x32x16_bf16 v[16:31], v[188:191], v[212:215], v[16:31]
	ds_read_b128 v[212:215], v151 offset:4672
	s_setprio 0
	global_load_dwordx4 v[184:187], v[132:133], off offset:512
	global_load_dwordx4 v[188:191], v[134:135], off offset:512
	s_setprio 1
	s_waitcnt lgkmcnt(1)
	v_mfma_f32_32x32x16_bf16 v[96:111], v[194:197], v[208:211], v[96:111]
	v_mfma_f32_32x32x16_bf16 v[112:127], v[198:201], v[208:211], v[112:127]
	s_waitcnt lgkmcnt(0)
	v_mfma_f32_32x32x16_bf16 v[64:79], v[194:197], v[212:215], v[64:79]
	v_mfma_f32_32x32x16_bf16 v[80:95], v[198:201], v[212:215], v[80:95]
	ds_read_b128 v[208:211], v151 offset:9280
	ds_read_b128 v[212:215], v151 offset:13888
	s_waitcnt vmcnt(7)
	ds_write_b128 v156, v[176:179]
	s_waitcnt vmcnt(6)
	ds_write_b128 v155, v[180:183]
	ds_read_b128 v[176:179], v152 offset:36960
	ds_read_b128 v[180:183], v152 offset:41568
	s_waitcnt lgkmcnt(5)
	v_mfma_f32_32x32x16_bf16 v[32:47], v[194:197], v[208:211], v[32:47]
	v_mfma_f32_32x32x16_bf16 v[48:63], v[198:201], v[208:211], v[48:63]
	ds_read_b128 v[208:211], v151 offset:96
	s_waitcnt lgkmcnt(5)
	v_mfma_f32_32x32x16_bf16 v[0:15], v[194:197], v[212:215], v[0:15]
	v_mfma_f32_32x32x16_bf16 v[16:31], v[198:201], v[212:215], v[16:31]
	ds_read_b128 v[212:215], v151 offset:4704
	s_setprio 0
	global_load_dwordx4 v[194:197], v[144:145], off offset:512
	global_load_dwordx4 v[198:201], v[146:147], off offset:512
	s_setprio 1
	s_waitcnt lgkmcnt(1)
	v_mfma_f32_32x32x16_bf16 v[96:111], v[176:179], v[208:211], v[96:111]
	v_mfma_f32_32x32x16_bf16 v[112:127], v[180:183], v[208:211], v[112:127]
	s_waitcnt lgkmcnt(0)
	v_mfma_f32_32x32x16_bf16 v[64:79], v[176:179], v[212:215], v[64:79]
	v_mfma_f32_32x32x16_bf16 v[80:95], v[180:183], v[212:215], v[80:95]
	ds_read_b128 v[208:211], v151 offset:9312
	ds_read_b128 v[212:215], v151 offset:13920
	s_waitcnt lgkmcnt(1)
	v_mfma_f32_32x32x16_bf16 v[32:47], v[176:179], v[208:211], v[32:47]
	v_mfma_f32_32x32x16_bf16 v[48:63], v[180:183], v[208:211], v[48:63]
	s_waitcnt lgkmcnt(0)
	v_mfma_f32_32x32x16_bf16 v[0:15], v[176:179], v[212:215], v[0:15]
	v_mfma_f32_32x32x16_bf16 v[16:31], v[180:183], v[212:215], v[16:31]
	s_setprio 0
	s_barrier
	global_load_dwordx4 v[176:179], v[136:137], off offset:640
	global_load_dwordx4 v[180:183], v[138:139], off offset:640
	s_waitcnt vmcnt(9)
	ds_write_b128 v148, v[168:171]
	s_waitcnt vmcnt(8)
	ds_write_b128 v148, v[172:175] offset:36864
	ds_read_b128 v[168:171], v150
	ds_read_b128 v[172:175], v150 offset:4608
	ds_read_b128 v[208:211], v149
	ds_read_b128 v[212:215], v149 offset:4608
	s_setprio 1
	s_waitcnt lgkmcnt(1)
	v_mfma_f32_32x32x16_bf16 v[96:111], v[168:171], v[208:211], v[96:111]
	v_mfma_f32_32x32x16_bf16 v[112:127], v[172:175], v[208:211], v[112:127]
	s_waitcnt lgkmcnt(0)
	v_mfma_f32_32x32x16_bf16 v[64:79], v[168:171], v[212:215], v[64:79]
	v_mfma_f32_32x32x16_bf16 v[80:95], v[172:175], v[212:215], v[80:95]
	ds_read_b128 v[208:211], v149 offset:9216
	ds_read_b128 v[212:215], v149 offset:13824
	s_waitcnt vmcnt(7)
	ds_write_b128 v148, v[160:163] offset:9216
	s_waitcnt vmcnt(6)
	ds_write_b128 v148, v[164:167] offset:46080
	ds_read_b128 v[160:163], v150 offset:32
	ds_read_b128 v[164:167], v150 offset:4640
	s_waitcnt lgkmcnt(5)
	v_mfma_f32_32x32x16_bf16 v[32:47], v[168:171], v[208:211], v[32:47]
	v_mfma_f32_32x32x16_bf16 v[48:63], v[172:175], v[208:211], v[48:63]
	ds_read_b128 v[208:211], v149 offset:32
	s_waitcnt lgkmcnt(5)
	v_mfma_f32_32x32x16_bf16 v[0:15], v[168:171], v[212:215], v[0:15]
	v_mfma_f32_32x32x16_bf16 v[16:31], v[172:175], v[212:215], v[16:31]
	ds_read_b128 v[212:215], v149 offset:4640
	s_setprio 0
	global_load_dwordx4 v[168:171], v[140:141], off offset:640
	global_load_dwordx4 v[172:175], v[142:143], off offset:640
	s_setprio 1
	s_waitcnt lgkmcnt(1)
	v_mfma_f32_32x32x16_bf16 v[96:111], v[160:163], v[208:211], v[96:111]
	v_mfma_f32_32x32x16_bf16 v[112:127], v[164:167], v[208:211], v[112:127]
	s_waitcnt lgkmcnt(0)
	v_mfma_f32_32x32x16_bf16 v[64:79], v[160:163], v[212:215], v[64:79]
	v_mfma_f32_32x32x16_bf16 v[80:95], v[164:167], v[212:215], v[80:95]
	ds_read_b128 v[208:211], v149 offset:9248
	ds_read_b128 v[212:215], v149 offset:13856
	s_waitcnt vmcnt(7)
	ds_write_b128 v148, v[184:187] offset:18432
	s_waitcnt vmcnt(6)
	ds_write_b128 v148, v[188:191] offset:55296
	ds_read_b128 v[184:187], v150 offset:64
	ds_read_b128 v[188:191], v150 offset:4672
	s_waitcnt lgkmcnt(5)
	v_mfma_f32_32x32x16_bf16 v[32:47], v[160:163], v[208:211], v[32:47]
	v_mfma_f32_32x32x16_bf16 v[48:63], v[164:167], v[208:211], v[48:63]
	ds_read_b128 v[208:211], v149 offset:64
	s_waitcnt lgkmcnt(5)
	v_mfma_f32_32x32x16_bf16 v[0:15], v[160:163], v[212:215], v[0:15]
	v_mfma_f32_32x32x16_bf16 v[16:31], v[164:167], v[212:215], v[16:31]
	ds_read_b128 v[212:215], v149 offset:4672
	s_setprio 0
	global_load_dwordx4 v[160:163], v[132:133], off offset:640
	global_load_dwordx4 v[164:167], v[134:135], off offset:640
	s_setprio 1
	s_waitcnt lgkmcnt(1)
	v_mfma_f32_32x32x16_bf16 v[96:111], v[184:187], v[208:211], v[96:111]
	v_mfma_f32_32x32x16_bf16 v[112:127], v[188:191], v[208:211], v[112:127]
	s_waitcnt lgkmcnt(0)
	v_mfma_f32_32x32x16_bf16 v[64:79], v[184:187], v[212:215], v[64:79]
	v_mfma_f32_32x32x16_bf16 v[80:95], v[188:191], v[212:215], v[80:95]
	ds_read_b128 v[208:211], v149 offset:9280
	ds_read_b128 v[212:215], v149 offset:13888
	s_waitcnt vmcnt(7)
	ds_write_b128 v148, v[194:197] offset:27648
	s_waitcnt vmcnt(6)
	ds_write_b128 v148, v[198:201] offset:64512
	ds_read_b128 v[194:197], v150 offset:96
	ds_read_b128 v[198:201], v150 offset:4704
	s_waitcnt lgkmcnt(5)
	v_mfma_f32_32x32x16_bf16 v[32:47], v[184:187], v[208:211], v[32:47]
	v_mfma_f32_32x32x16_bf16 v[48:63], v[188:191], v[208:211], v[48:63]
	ds_read_b128 v[208:211], v149 offset:96
	s_waitcnt lgkmcnt(5)
	v_mfma_f32_32x32x16_bf16 v[0:15], v[184:187], v[212:215], v[0:15]
	v_mfma_f32_32x32x16_bf16 v[16:31], v[188:191], v[212:215], v[16:31]
	ds_read_b128 v[212:215], v149 offset:4704
	s_setprio 0
	global_load_dwordx4 v[184:187], v[144:145], off offset:640
	global_load_dwordx4 v[188:191], v[146:147], off offset:640
	s_setprio 1
	s_waitcnt lgkmcnt(1)
	v_mfma_f32_32x32x16_bf16 v[96:111], v[194:197], v[208:211], v[96:111]
	v_mfma_f32_32x32x16_bf16 v[112:127], v[198:201], v[208:211], v[112:127]
	s_waitcnt lgkmcnt(0)
	v_mfma_f32_32x32x16_bf16 v[64:79], v[194:197], v[212:215], v[64:79]
	v_mfma_f32_32x32x16_bf16 v[80:95], v[198:201], v[212:215], v[80:95]
	ds_read_b128 v[208:211], v149 offset:9312
	ds_read_b128 v[212:215], v149 offset:13920
	s_waitcnt lgkmcnt(1)
	v_mfma_f32_32x32x16_bf16 v[32:47], v[194:197], v[208:211], v[32:47]
	v_mfma_f32_32x32x16_bf16 v[48:63], v[198:201], v[208:211], v[48:63]
	s_waitcnt lgkmcnt(0)
	v_mfma_f32_32x32x16_bf16 v[0:15], v[194:197], v[212:215], v[0:15]
	v_mfma_f32_32x32x16_bf16 v[16:31], v[198:201], v[212:215], v[16:31]
	s_setprio 0
	s_barrier
	global_load_dwordx4 v[194:197], v[136:137], off offset:768
	global_load_dwordx4 v[198:201], v[138:139], off offset:768
	s_waitcnt vmcnt(9)
	ds_write_b128 v192, v[176:179]
	s_waitcnt vmcnt(8)
	ds_write_b128 v159, v[180:183]
	ds_read_b128 v[176:179], v152 offset:36864
	ds_read_b128 v[180:183], v152 offset:41472
	ds_read_b128 v[208:211], v151
	ds_read_b128 v[212:215], v151 offset:4608
	s_setprio 1
	s_waitcnt lgkmcnt(1)
	v_mfma_f32_32x32x16_bf16 v[96:111], v[176:179], v[208:211], v[96:111]
	v_mfma_f32_32x32x16_bf16 v[112:127], v[180:183], v[208:211], v[112:127]
	s_waitcnt lgkmcnt(0)
	v_mfma_f32_32x32x16_bf16 v[64:79], v[176:179], v[212:215], v[64:79]
	v_mfma_f32_32x32x16_bf16 v[80:95], v[180:183], v[212:215], v[80:95]
	ds_read_b128 v[208:211], v151 offset:9216
	ds_read_b128 v[212:215], v151 offset:13824
	s_waitcnt vmcnt(7)
	ds_write_b128 v158, v[168:171]
	s_waitcnt vmcnt(6)
	ds_write_b128 v157, v[172:175]
	ds_read_b128 v[168:171], v152 offset:36896
	ds_read_b128 v[172:175], v152 offset:41504
	s_waitcnt lgkmcnt(5)
	v_mfma_f32_32x32x16_bf16 v[32:47], v[176:179], v[208:211], v[32:47]
	v_mfma_f32_32x32x16_bf16 v[48:63], v[180:183], v[208:211], v[48:63]
	ds_read_b128 v[208:211], v151 offset:32
	s_waitcnt lgkmcnt(5)
	v_mfma_f32_32x32x16_bf16 v[0:15], v[176:179], v[212:215], v[0:15]
	v_mfma_f32_32x32x16_bf16 v[16:31], v[180:183], v[212:215], v[16:31]
	ds_read_b128 v[212:215], v151 offset:4640
	s_setprio 0
	global_load_dwordx4 v[176:179], v[140:141], off offset:768
	global_load_dwordx4 v[180:183], v[142:143], off offset:768
	s_setprio 1
	s_waitcnt lgkmcnt(1)
	v_mfma_f32_32x32x16_bf16 v[96:111], v[168:171], v[208:211], v[96:111]
	v_mfma_f32_32x32x16_bf16 v[112:127], v[172:175], v[208:211], v[112:127]
	s_waitcnt lgkmcnt(0)
	v_mfma_f32_32x32x16_bf16 v[64:79], v[168:171], v[212:215], v[64:79]
	v_mfma_f32_32x32x16_bf16 v[80:95], v[172:175], v[212:215], v[80:95]
	ds_read_b128 v[208:211], v151 offset:9248
	ds_read_b128 v[212:215], v151 offset:13856
	s_waitcnt vmcnt(7)
	ds_write_b128 v154, v[160:163]
	s_waitcnt vmcnt(6)
	ds_write_b128 v153, v[164:167]
	ds_read_b128 v[160:163], v152 offset:36928
	ds_read_b128 v[164:167], v152 offset:41536
	s_waitcnt lgkmcnt(5)
	v_mfma_f32_32x32x16_bf16 v[32:47], v[168:171], v[208:211], v[32:47]
	v_mfma_f32_32x32x16_bf16 v[48:63], v[172:175], v[208:211], v[48:63]
	ds_read_b128 v[208:211], v151 offset:64
	s_waitcnt lgkmcnt(5)
	v_mfma_f32_32x32x16_bf16 v[0:15], v[168:171], v[212:215], v[0:15]
	v_mfma_f32_32x32x16_bf16 v[16:31], v[172:175], v[212:215], v[16:31]
	ds_read_b128 v[212:215], v151 offset:4672
	s_setprio 0
	global_load_dwordx4 v[168:171], v[132:133], off offset:768
	global_load_dwordx4 v[172:175], v[134:135], off offset:768
	s_setprio 1
	s_waitcnt lgkmcnt(1)
	v_mfma_f32_32x32x16_bf16 v[96:111], v[160:163], v[208:211], v[96:111]
	v_mfma_f32_32x32x16_bf16 v[112:127], v[164:167], v[208:211], v[112:127]
	s_waitcnt lgkmcnt(0)
	v_mfma_f32_32x32x16_bf16 v[64:79], v[160:163], v[212:215], v[64:79]
	v_mfma_f32_32x32x16_bf16 v[80:95], v[164:167], v[212:215], v[80:95]
	ds_read_b128 v[208:211], v151 offset:9280
	ds_read_b128 v[212:215], v151 offset:13888
	s_waitcnt vmcnt(7)
	ds_write_b128 v156, v[184:187]
	s_waitcnt vmcnt(6)
	ds_write_b128 v155, v[188:191]
	ds_read_b128 v[184:187], v152 offset:36960
	ds_read_b128 v[188:191], v152 offset:41568
	s_waitcnt lgkmcnt(5)
	v_mfma_f32_32x32x16_bf16 v[32:47], v[160:163], v[208:211], v[32:47]
	v_mfma_f32_32x32x16_bf16 v[48:63], v[164:167], v[208:211], v[48:63]
	ds_read_b128 v[208:211], v151 offset:96
	s_waitcnt lgkmcnt(5)
	v_mfma_f32_32x32x16_bf16 v[0:15], v[160:163], v[212:215], v[0:15]
	v_mfma_f32_32x32x16_bf16 v[16:31], v[164:167], v[212:215], v[16:31]
	ds_read_b128 v[212:215], v151 offset:4704
	s_setprio 0
	global_load_dwordx4 v[160:163], v[144:145], off offset:768
	global_load_dwordx4 v[164:167], v[146:147], off offset:768
	s_setprio 1
	s_waitcnt lgkmcnt(1)
	v_mfma_f32_32x32x16_bf16 v[96:111], v[184:187], v[208:211], v[96:111]
	v_mfma_f32_32x32x16_bf16 v[112:127], v[188:191], v[208:211], v[112:127]
	s_waitcnt lgkmcnt(0)
	v_mfma_f32_32x32x16_bf16 v[64:79], v[184:187], v[212:215], v[64:79]
	v_mfma_f32_32x32x16_bf16 v[80:95], v[188:191], v[212:215], v[80:95]
	ds_read_b128 v[208:211], v151 offset:9312
	ds_read_b128 v[212:215], v151 offset:13920
	s_waitcnt lgkmcnt(1)
	v_mfma_f32_32x32x16_bf16 v[32:47], v[184:187], v[208:211], v[32:47]
	v_mfma_f32_32x32x16_bf16 v[48:63], v[188:191], v[208:211], v[48:63]
	s_waitcnt lgkmcnt(0)
	v_mfma_f32_32x32x16_bf16 v[0:15], v[184:187], v[212:215], v[0:15]
	v_mfma_f32_32x32x16_bf16 v[16:31], v[188:191], v[212:215], v[16:31]
	s_setprio 0
	s_barrier
	global_load_dwordx4 v[184:187], v[136:137], off offset:896
	global_load_dwordx4 v[188:191], v[138:139], off offset:896
	s_waitcnt vmcnt(9)
	ds_write_b128 v148, v[194:197]
	s_waitcnt vmcnt(8)
	ds_write_b128 v148, v[198:201] offset:36864
	ds_read_b128 v[194:197], v150
	ds_read_b128 v[198:201], v150 offset:4608
	ds_read_b128 v[208:211], v149
	ds_read_b128 v[212:215], v149 offset:4608
	s_setprio 1
	s_waitcnt lgkmcnt(1)
	v_mfma_f32_32x32x16_bf16 v[96:111], v[194:197], v[208:211], v[96:111]
	v_mfma_f32_32x32x16_bf16 v[112:127], v[198:201], v[208:211], v[112:127]
	s_waitcnt lgkmcnt(0)
	v_mfma_f32_32x32x16_bf16 v[64:79], v[194:197], v[212:215], v[64:79]
	v_mfma_f32_32x32x16_bf16 v[80:95], v[198:201], v[212:215], v[80:95]
	ds_read_b128 v[208:211], v149 offset:9216
	ds_read_b128 v[212:215], v149 offset:13824
	s_waitcnt vmcnt(7)
	ds_write_b128 v148, v[176:179] offset:9216
	s_waitcnt vmcnt(6)
	ds_write_b128 v148, v[180:183] offset:46080
	ds_read_b128 v[176:179], v150 offset:32
	ds_read_b128 v[180:183], v150 offset:4640
	s_waitcnt lgkmcnt(5)
	v_mfma_f32_32x32x16_bf16 v[32:47], v[194:197], v[208:211], v[32:47]
	v_mfma_f32_32x32x16_bf16 v[48:63], v[198:201], v[208:211], v[48:63]
	ds_read_b128 v[208:211], v149 offset:32
	s_waitcnt lgkmcnt(5)
	v_mfma_f32_32x32x16_bf16 v[0:15], v[194:197], v[212:215], v[0:15]
	v_mfma_f32_32x32x16_bf16 v[16:31], v[198:201], v[212:215], v[16:31]
	ds_read_b128 v[212:215], v149 offset:4640
	s_setprio 0
	global_load_dwordx4 v[194:197], v[140:141], off offset:896
	global_load_dwordx4 v[198:201], v[142:143], off offset:896
	s_setprio 1
	s_waitcnt lgkmcnt(1)
	v_mfma_f32_32x32x16_bf16 v[96:111], v[176:179], v[208:211], v[96:111]
	v_mfma_f32_32x32x16_bf16 v[112:127], v[180:183], v[208:211], v[112:127]
	s_waitcnt lgkmcnt(0)
	v_mfma_f32_32x32x16_bf16 v[64:79], v[176:179], v[212:215], v[64:79]
	v_mfma_f32_32x32x16_bf16 v[80:95], v[180:183], v[212:215], v[80:95]
	ds_read_b128 v[208:211], v149 offset:9248
	ds_read_b128 v[212:215], v149 offset:13856
	s_waitcnt vmcnt(7)
	ds_write_b128 v148, v[168:171] offset:18432
	s_waitcnt vmcnt(6)
	ds_write_b128 v148, v[172:175] offset:55296
	ds_read_b128 v[168:171], v150 offset:64
	ds_read_b128 v[172:175], v150 offset:4672
	s_waitcnt lgkmcnt(5)
	v_mfma_f32_32x32x16_bf16 v[32:47], v[176:179], v[208:211], v[32:47]
	v_mfma_f32_32x32x16_bf16 v[48:63], v[180:183], v[208:211], v[48:63]
	ds_read_b128 v[208:211], v149 offset:64
	s_waitcnt lgkmcnt(5)
	v_mfma_f32_32x32x16_bf16 v[0:15], v[176:179], v[212:215], v[0:15]
	v_mfma_f32_32x32x16_bf16 v[16:31], v[180:183], v[212:215], v[16:31]
	ds_read_b128 v[212:215], v149 offset:4672
	s_setprio 0
	global_load_dwordx4 v[176:179], v[132:133], off offset:896
	global_load_dwordx4 v[180:183], v[134:135], off offset:896
	s_setprio 1
	s_waitcnt lgkmcnt(1)
	v_mfma_f32_32x32x16_bf16 v[96:111], v[168:171], v[208:211], v[96:111]
	v_mfma_f32_32x32x16_bf16 v[112:127], v[172:175], v[208:211], v[112:127]
	s_waitcnt lgkmcnt(0)
	v_mfma_f32_32x32x16_bf16 v[64:79], v[168:171], v[212:215], v[64:79]
	v_mfma_f32_32x32x16_bf16 v[80:95], v[172:175], v[212:215], v[80:95]
	ds_read_b128 v[208:211], v149 offset:9280
	ds_read_b128 v[212:215], v149 offset:13888
	s_waitcnt vmcnt(7)
	ds_write_b128 v148, v[160:163] offset:27648
	s_waitcnt vmcnt(6)
	ds_write_b128 v148, v[164:167] offset:64512
	ds_read_b128 v[160:163], v150 offset:96
	ds_read_b128 v[164:167], v150 offset:4704
	s_waitcnt lgkmcnt(5)
	v_mfma_f32_32x32x16_bf16 v[32:47], v[168:171], v[208:211], v[32:47]
	v_mfma_f32_32x32x16_bf16 v[48:63], v[172:175], v[208:211], v[48:63]
	ds_read_b128 v[208:211], v149 offset:96
	s_waitcnt lgkmcnt(5)
	v_mfma_f32_32x32x16_bf16 v[0:15], v[168:171], v[212:215], v[0:15]
	v_mfma_f32_32x32x16_bf16 v[16:31], v[172:175], v[212:215], v[16:31]
	ds_read_b128 v[212:215], v149 offset:4704
	s_setprio 0
	global_load_dwordx4 v[168:171], v[144:145], off offset:896
	global_load_dwordx4 v[172:175], v[146:147], off offset:896
	s_setprio 1
	s_waitcnt lgkmcnt(1)
	v_mfma_f32_32x32x16_bf16 v[96:111], v[160:163], v[208:211], v[96:111]
	v_mfma_f32_32x32x16_bf16 v[112:127], v[164:167], v[208:211], v[112:127]
	s_waitcnt lgkmcnt(0)
	v_mfma_f32_32x32x16_bf16 v[64:79], v[160:163], v[212:215], v[64:79]
	v_mfma_f32_32x32x16_bf16 v[80:95], v[164:167], v[212:215], v[80:95]
	ds_read_b128 v[208:211], v149 offset:9312
	ds_read_b128 v[212:215], v149 offset:13920
	s_waitcnt lgkmcnt(1)
	v_mfma_f32_32x32x16_bf16 v[32:47], v[160:163], v[208:211], v[32:47]
	v_mfma_f32_32x32x16_bf16 v[48:63], v[164:167], v[208:211], v[48:63]
	s_waitcnt lgkmcnt(0)
	v_mfma_f32_32x32x16_bf16 v[0:15], v[160:163], v[212:215], v[0:15]
	v_mfma_f32_32x32x16_bf16 v[16:31], v[164:167], v[212:215], v[16:31]
	s_setprio 0
	s_barrier
	global_load_dwordx4 v[160:163], v[136:137], off offset:1024
	global_load_dwordx4 v[164:167], v[138:139], off offset:1024
	s_waitcnt vmcnt(9)
	ds_write_b128 v192, v[184:187]
	s_waitcnt vmcnt(8)
	ds_write_b128 v159, v[188:191]
	ds_read_b128 v[184:187], v152 offset:36864
	ds_read_b128 v[188:191], v152 offset:41472
	ds_read_b128 v[208:211], v151
	ds_read_b128 v[212:215], v151 offset:4608
	s_setprio 1
	s_waitcnt lgkmcnt(1)
	v_mfma_f32_32x32x16_bf16 v[96:111], v[184:187], v[208:211], v[96:111]
	v_mfma_f32_32x32x16_bf16 v[112:127], v[188:191], v[208:211], v[112:127]
	s_waitcnt lgkmcnt(0)
	v_mfma_f32_32x32x16_bf16 v[64:79], v[184:187], v[212:215], v[64:79]
	v_mfma_f32_32x32x16_bf16 v[80:95], v[188:191], v[212:215], v[80:95]
	ds_read_b128 v[208:211], v151 offset:9216
	ds_read_b128 v[212:215], v151 offset:13824
	s_waitcnt vmcnt(7)
	ds_write_b128 v158, v[194:197]
	s_waitcnt vmcnt(6)
	ds_write_b128 v157, v[198:201]
	ds_read_b128 v[194:197], v152 offset:36896
	ds_read_b128 v[198:201], v152 offset:41504
	s_waitcnt lgkmcnt(5)
	v_mfma_f32_32x32x16_bf16 v[32:47], v[184:187], v[208:211], v[32:47]
	v_mfma_f32_32x32x16_bf16 v[48:63], v[188:191], v[208:211], v[48:63]
	ds_read_b128 v[208:211], v151 offset:32
	s_waitcnt lgkmcnt(5)
	v_mfma_f32_32x32x16_bf16 v[0:15], v[184:187], v[212:215], v[0:15]
	v_mfma_f32_32x32x16_bf16 v[16:31], v[188:191], v[212:215], v[16:31]
	ds_read_b128 v[212:215], v151 offset:4640
	s_setprio 0
	global_load_dwordx4 v[184:187], v[140:141], off offset:1024
	global_load_dwordx4 v[188:191], v[142:143], off offset:1024
	s_setprio 1
	s_waitcnt lgkmcnt(1)
	v_mfma_f32_32x32x16_bf16 v[96:111], v[194:197], v[208:211], v[96:111]
	v_mfma_f32_32x32x16_bf16 v[112:127], v[198:201], v[208:211], v[112:127]
	s_waitcnt lgkmcnt(0)
	v_mfma_f32_32x32x16_bf16 v[64:79], v[194:197], v[212:215], v[64:79]
	v_mfma_f32_32x32x16_bf16 v[80:95], v[198:201], v[212:215], v[80:95]
	ds_read_b128 v[208:211], v151 offset:9248
	ds_read_b128 v[212:215], v151 offset:13856
	s_waitcnt vmcnt(7)
	ds_write_b128 v154, v[176:179]
	s_waitcnt vmcnt(6)
	ds_write_b128 v153, v[180:183]
	ds_read_b128 v[176:179], v152 offset:36928
	ds_read_b128 v[180:183], v152 offset:41536
	s_waitcnt lgkmcnt(5)
	v_mfma_f32_32x32x16_bf16 v[32:47], v[194:197], v[208:211], v[32:47]
	v_mfma_f32_32x32x16_bf16 v[48:63], v[198:201], v[208:211], v[48:63]
	ds_read_b128 v[208:211], v151 offset:64
	s_waitcnt lgkmcnt(5)
	v_mfma_f32_32x32x16_bf16 v[0:15], v[194:197], v[212:215], v[0:15]
	v_mfma_f32_32x32x16_bf16 v[16:31], v[198:201], v[212:215], v[16:31]
	ds_read_b128 v[212:215], v151 offset:4672
	s_setprio 0
	global_load_dwordx4 v[194:197], v[132:133], off offset:1024
	global_load_dwordx4 v[198:201], v[134:135], off offset:1024
	s_setprio 1
	s_waitcnt lgkmcnt(1)
	v_mfma_f32_32x32x16_bf16 v[96:111], v[176:179], v[208:211], v[96:111]
	v_mfma_f32_32x32x16_bf16 v[112:127], v[180:183], v[208:211], v[112:127]
	s_waitcnt lgkmcnt(0)
	v_mfma_f32_32x32x16_bf16 v[64:79], v[176:179], v[212:215], v[64:79]
	v_mfma_f32_32x32x16_bf16 v[80:95], v[180:183], v[212:215], v[80:95]
	ds_read_b128 v[208:211], v151 offset:9280
	ds_read_b128 v[212:215], v151 offset:13888
	s_waitcnt vmcnt(7)
	ds_write_b128 v156, v[168:171]
	s_waitcnt vmcnt(6)
	ds_write_b128 v155, v[172:175]
	ds_read_b128 v[168:171], v152 offset:36960
	ds_read_b128 v[172:175], v152 offset:41568
	s_waitcnt lgkmcnt(5)
	v_mfma_f32_32x32x16_bf16 v[32:47], v[176:179], v[208:211], v[32:47]
	v_mfma_f32_32x32x16_bf16 v[48:63], v[180:183], v[208:211], v[48:63]
	ds_read_b128 v[208:211], v151 offset:96
	s_waitcnt lgkmcnt(5)
	v_mfma_f32_32x32x16_bf16 v[0:15], v[176:179], v[212:215], v[0:15]
	v_mfma_f32_32x32x16_bf16 v[16:31], v[180:183], v[212:215], v[16:31]
	ds_read_b128 v[212:215], v151 offset:4704
	s_setprio 0
	global_load_dwordx4 v[176:179], v[144:145], off offset:1024
	global_load_dwordx4 v[180:183], v[146:147], off offset:1024
	s_setprio 1
	s_waitcnt lgkmcnt(1)
	v_mfma_f32_32x32x16_bf16 v[96:111], v[168:171], v[208:211], v[96:111]
	v_mfma_f32_32x32x16_bf16 v[112:127], v[172:175], v[208:211], v[112:127]
	s_waitcnt lgkmcnt(0)
	v_mfma_f32_32x32x16_bf16 v[64:79], v[168:171], v[212:215], v[64:79]
	v_mfma_f32_32x32x16_bf16 v[80:95], v[172:175], v[212:215], v[80:95]
	ds_read_b128 v[208:211], v151 offset:9312
	ds_read_b128 v[212:215], v151 offset:13920
	s_waitcnt lgkmcnt(1)
	v_mfma_f32_32x32x16_bf16 v[32:47], v[168:171], v[208:211], v[32:47]
	v_mfma_f32_32x32x16_bf16 v[48:63], v[172:175], v[208:211], v[48:63]
	s_waitcnt lgkmcnt(0)
	v_mfma_f32_32x32x16_bf16 v[0:15], v[168:171], v[212:215], v[0:15]
	v_mfma_f32_32x32x16_bf16 v[16:31], v[172:175], v[212:215], v[16:31]
	s_setprio 0
	s_barrier
; template <bool trans>
; DI void gemm_core(const GTile& tl, const GTile& nx, bool has_next  , bool chain  , bool pre, u32x4 (&ra)[4], u32x4 (&rb)[4], char* smem, f32x16 (&acc)[2][4]) {
;     ...
;   const int nk = K / 64;
;   if (!pre) { G_LOAD(0); G_STORE(0); G_LOAD(1); }
;   for (int kt = 0; kt < nk; ++kt) {
;     __syncthreads();
;     G_COMPUTE(kt & 1, kt);
;   }
	global_load_dwordx4 v[168:171], v[136:137], off offset:1152
	global_load_dwordx4 v[172:175], v[138:139], off offset:1152
	s_waitcnt vmcnt(9)
	ds_write_b128 v148, v[160:163]
	s_waitcnt vmcnt(8)
	ds_write_b128 v148, v[164:167] offset:36864
	ds_read_b128 v[160:163], v150
	ds_read_b128 v[164:167], v150 offset:4608
	ds_read_b128 v[208:211], v149
	ds_read_b128 v[212:215], v149 offset:4608
	s_setprio 1
	s_waitcnt lgkmcnt(1)
	v_mfma_f32_32x32x16_bf16 v[96:111], v[160:163], v[208:211], v[96:111]
	v_mfma_f32_32x32x16_bf16 v[112:127], v[164:167], v[208:211], v[112:127]
	s_waitcnt lgkmcnt(0)
	v_mfma_f32_32x32x16_bf16 v[64:79], v[160:163], v[212:215], v[64:79]
	v_mfma_f32_32x32x16_bf16 v[80:95], v[164:167], v[212:215], v[80:95]
	ds_read_b128 v[208:211], v149 offset:9216
	ds_read_b128 v[212:215], v149 offset:13824
	s_waitcnt vmcnt(7)
	ds_write_b128 v148, v[184:187] offset:9216
	s_waitcnt vmcnt(6)
	ds_write_b128 v148, v[188:191] offset:46080
	ds_read_b128 v[184:187], v150 offset:32
	ds_read_b128 v[188:191], v150 offset:4640
	s_waitcnt lgkmcnt(5)
	v_mfma_f32_32x32x16_bf16 v[32:47], v[160:163], v[208:211], v[32:47]
	v_mfma_f32_32x32x16_bf16 v[48:63], v[164:167], v[208:211], v[48:63]
	ds_read_b128 v[208:211], v149 offset:32
	s_waitcnt lgkmcnt(5)
	v_mfma_f32_32x32x16_bf16 v[0:15], v[160:163], v[212:215], v[0:15]
	v_mfma_f32_32x32x16_bf16 v[16:31], v[164:167], v[212:215], v[16:31]
	ds_read_b128 v[212:215], v149 offset:4640
	s_setprio 0
	global_load_dwordx4 v[160:163], v[140:141], off offset:1152
	global_load_dwordx4 v[164:167], v[142:143], off offset:1152
	s_setprio 1
	s_waitcnt lgkmcnt(1)
	v_mfma_f32_32x32x16_bf16 v[96:111], v[184:187], v[208:211], v[96:111]
	v_mfma_f32_32x32x16_bf16 v[112:127], v[188:191], v[208:211], v[112:127]
	s_waitcnt lgkmcnt(0)
	v_mfma_f32_32x32x16_bf16 v[64:79], v[184:187], v[212:215], v[64:79]
	v_mfma_f32_32x32x16_bf16 v[80:95], v[188:191], v[212:215], v[80:95]
	ds_read_b128 v[208:211], v149 offset:9248
	ds_read_b128 v[212:215], v149 offset:13856
	s_waitcnt vmcnt(7)
	ds_write_b128 v148, v[194:197] offset:18432
	s_waitcnt vmcnt(6)
	ds_write_b128 v148, v[198:201] offset:55296
	ds_read_b128 v[194:197], v150 offset:64
	ds_read_b128 v[198:201], v150 offset:4672
	s_waitcnt lgkmcnt(5)
	v_mfma_f32_32x32x16_bf16 v[32:47], v[184:187], v[208:211], v[32:47]
	v_mfma_f32_32x32x16_bf16 v[48:63], v[188:191], v[208:211], v[48:63]
	ds_read_b128 v[208:211], v149 offset:64
	s_waitcnt lgkmcnt(5)
	v_mfma_f32_32x32x16_bf16 v[0:15], v[184:187], v[212:215], v[0:15]
	v_mfma_f32_32x32x16_bf16 v[16:31], v[188:191], v[212:215], v[16:31]
	ds_read_b128 v[212:215], v149 offset:4672
	s_setprio 0
	global_load_dwordx4 v[184:187], v[132:133], off offset:1152
	global_load_dwordx4 v[188:191], v[134:135], off offset:1152
	s_setprio 1
	s_waitcnt lgkmcnt(1)
	v_mfma_f32_32x32x16_bf16 v[96:111], v[194:197], v[208:211], v[96:111]
	v_mfma_f32_32x32x16_bf16 v[112:127], v[198:201], v[208:211], v[112:127]
	s_waitcnt lgkmcnt(0)
	v_mfma_f32_32x32x16_bf16 v[64:79], v[194:197], v[212:215], v[64:79]
	v_mfma_f32_32x32x16_bf16 v[80:95], v[198:201], v[212:215], v[80:95]
	ds_read_b128 v[208:211], v149 offset:9280
	ds_read_b128 v[212:215], v149 offset:13888
	s_waitcnt vmcnt(7)
	ds_write_b128 v148, v[176:179] offset:27648
	s_waitcnt vmcnt(6)
	ds_write_b128 v148, v[180:183] offset:64512
	ds_read_b128 v[176:179], v150 offset:96
	ds_read_b128 v[180:183], v150 offset:4704
	s_waitcnt lgkmcnt(5)
	v_mfma_f32_32x32x16_bf16 v[32:47], v[194:197], v[208:211], v[32:47]
	v_mfma_f32_32x32x16_bf16 v[48:63], v[198:201], v[208:211], v[48:63]
	ds_read_b128 v[208:211], v149 offset:96
	s_waitcnt lgkmcnt(5)
	v_mfma_f32_32x32x16_bf16 v[0:15], v[194:197], v[212:215], v[0:15]
	v_mfma_f32_32x32x16_bf16 v[16:31], v[198:201], v[212:215], v[16:31]
	ds_read_b128 v[212:215], v149 offset:4704
	s_setprio 0
	global_load_dwordx4 v[194:197], v[144:145], off offset:1152
	global_load_dwordx4 v[198:201], v[146:147], off offset:1152
	s_setprio 1
	s_waitcnt lgkmcnt(1)
	v_mfma_f32_32x32x16_bf16 v[96:111], v[176:179], v[208:211], v[96:111]
	v_mfma_f32_32x32x16_bf16 v[112:127], v[180:183], v[208:211], v[112:127]
	s_waitcnt lgkmcnt(0)
	v_mfma_f32_32x32x16_bf16 v[64:79], v[176:179], v[212:215], v[64:79]
	v_mfma_f32_32x32x16_bf16 v[80:95], v[180:183], v[212:215], v[80:95]
	ds_read_b128 v[208:211], v149 offset:9312
	ds_read_b128 v[212:215], v149 offset:13920
	s_waitcnt lgkmcnt(1)
	v_mfma_f32_32x32x16_bf16 v[32:47], v[176:179], v[208:211], v[32:47]
	v_mfma_f32_32x32x16_bf16 v[48:63], v[180:183], v[208:211], v[48:63]
	s_waitcnt lgkmcnt(0)
	v_mfma_f32_32x32x16_bf16 v[0:15], v[176:179], v[212:215], v[0:15]
	v_mfma_f32_32x32x16_bf16 v[16:31], v[180:183], v[212:215], v[16:31]
	s_setprio 0
	s_barrier
; template <bool trans>
; DI void gemm_core(const GTile& tl, const GTile& nx, bool has_next  , bool chain  , bool pre, u32x4 (&ra)[4], u32x4 (&rb)[4], char* smem, f32x16 (&acc)[2][4]) {
;     ...
;   const int nk = K / 64;
;   if (!pre) { G_LOAD(0); G_STORE(0); G_LOAD(1); }
;   for (int kt = 0; kt < nk; ++kt) {
;     __syncthreads();
;     G_COMPUTE(kt & 1, kt);
;   }
	global_load_dwordx4 v[176:179], v[136:137], off offset:1280
	global_load_dwordx4 v[180:183], v[138:139], off offset:1280
	s_waitcnt vmcnt(9)
	ds_write_b128 v192, v[168:171]
	s_waitcnt vmcnt(8)
	ds_write_b128 v159, v[172:175]
	ds_read_b128 v[168:171], v152 offset:36864
	ds_read_b128 v[172:175], v152 offset:41472
	ds_read_b128 v[208:211], v151
	ds_read_b128 v[212:215], v151 offset:4608
	s_setprio 1
	s_waitcnt lgkmcnt(1)
	v_mfma_f32_32x32x16_bf16 v[96:111], v[168:171], v[208:211], v[96:111]
	v_mfma_f32_32x32x16_bf16 v[112:127], v[172:175], v[208:211], v[112:127]
	s_waitcnt lgkmcnt(0)
	v_mfma_f32_32x32x16_bf16 v[64:79], v[168:171], v[212:215], v[64:79]
	v_mfma_f32_32x32x16_bf16 v[80:95], v[172:175], v[212:215], v[80:95]
	ds_read_b128 v[208:211], v151 offset:9216
	ds_read_b128 v[212:215], v151 offset:13824
	s_waitcnt vmcnt(7)
	ds_write_b128 v158, v[160:163]
	s_waitcnt vmcnt(6)
	ds_write_b128 v157, v[164:167]
	ds_read_b128 v[160:163], v152 offset:36896
	ds_read_b128 v[164:167], v152 offset:41504
	s_waitcnt lgkmcnt(5)
	v_mfma_f32_32x32x16_bf16 v[32:47], v[168:171], v[208:211], v[32:47]
	v_mfma_f32_32x32x16_bf16 v[48:63], v[172:175], v[208:211], v[48:63]
	ds_read_b128 v[208:211], v151 offset:32
	s_waitcnt lgkmcnt(5)
	v_mfma_f32_32x32x16_bf16 v[0:15], v[168:171], v[212:215], v[0:15]
	v_mfma_f32_32x32x16_bf16 v[16:31], v[172:175], v[212:215], v[16:31]
	ds_read_b128 v[212:215], v151 offset:4640
	s_setprio 0
	global_load_dwordx4 v[168:171], v[140:141], off offset:1280
	global_load_dwordx4 v[172:175], v[142:143], off offset:1280
	s_setprio 1
	s_waitcnt lgkmcnt(1)
	v_mfma_f32_32x32x16_bf16 v[96:111], v[160:163], v[208:211], v[96:111]
	v_mfma_f32_32x32x16_bf16 v[112:127], v[164:167], v[208:211], v[112:127]
	s_waitcnt lgkmcnt(0)
	v_mfma_f32_32x32x16_bf16 v[64:79], v[160:163], v[212:215], v[64:79]
	v_mfma_f32_32x32x16_bf16 v[80:95], v[164:167], v[212:215], v[80:95]
	ds_read_b128 v[208:211], v151 offset:9248
	ds_read_b128 v[212:215], v151 offset:13856
	s_waitcnt vmcnt(7)
	ds_write_b128 v154, v[184:187]
	s_waitcnt vmcnt(6)
	ds_write_b128 v153, v[188:191]
	ds_read_b128 v[184:187], v152 offset:36928
	ds_read_b128 v[188:191], v152 offset:41536
	s_waitcnt lgkmcnt(5)
	v_mfma_f32_32x32x16_bf16 v[32:47], v[160:163], v[208:211], v[32:47]
	v_mfma_f32_32x32x16_bf16 v[48:63], v[164:167], v[208:211], v[48:63]
	ds_read_b128 v[208:211], v151 offset:64
	s_waitcnt lgkmcnt(5)
	v_mfma_f32_32x32x16_bf16 v[0:15], v[160:163], v[212:215], v[0:15]
	v_mfma_f32_32x32x16_bf16 v[16:31], v[164:167], v[212:215], v[16:31]
	ds_read_b128 v[212:215], v151 offset:4672
	s_setprio 0
	global_load_dwordx4 v[160:163], v[132:133], off offset:1280
	global_load_dwordx4 v[164:167], v[134:135], off offset:1280
	s_setprio 1
	s_waitcnt lgkmcnt(1)
	v_mfma_f32_32x32x16_bf16 v[96:111], v[184:187], v[208:211], v[96:111]
	v_mfma_f32_32x32x16_bf16 v[112:127], v[188:191], v[208:211], v[112:127]
	s_waitcnt lgkmcnt(0)
	v_mfma_f32_32x32x16_bf16 v[64:79], v[184:187], v[212:215], v[64:79]
	v_mfma_f32_32x32x16_bf16 v[80:95], v[188:191], v[212:215], v[80:95]
	ds_read_b128 v[208:211], v151 offset:9280
	ds_read_b128 v[212:215], v151 offset:13888
	s_waitcnt vmcnt(7)
	ds_write_b128 v156, v[194:197]
	s_waitcnt vmcnt(6)
	ds_write_b128 v155, v[198:201]
	ds_read_b128 v[194:197], v152 offset:36960
	ds_read_b128 v[198:201], v152 offset:41568
	s_waitcnt lgkmcnt(5)
	v_mfma_f32_32x32x16_bf16 v[32:47], v[184:187], v[208:211], v[32:47]
	v_mfma_f32_32x32x16_bf16 v[48:63], v[188:191], v[208:211], v[48:63]
	ds_read_b128 v[208:211], v151 offset:96
	s_waitcnt lgkmcnt(5)
	v_mfma_f32_32x32x16_bf16 v[0:15], v[184:187], v[212:215], v[0:15]
	v_mfma_f32_32x32x16_bf16 v[16:31], v[188:191], v[212:215], v[16:31]
	ds_read_b128 v[212:215], v151 offset:4704
	s_setprio 0
	global_load_dwordx4 v[184:187], v[144:145], off offset:1280
	global_load_dwordx4 v[188:191], v[146:147], off offset:1280
	s_setprio 1
	s_waitcnt lgkmcnt(1)
	v_mfma_f32_32x32x16_bf16 v[96:111], v[194:197], v[208:211], v[96:111]
	v_mfma_f32_32x32x16_bf16 v[112:127], v[198:201], v[208:211], v[112:127]
	s_waitcnt lgkmcnt(0)
	v_mfma_f32_32x32x16_bf16 v[64:79], v[194:197], v[212:215], v[64:79]
	v_mfma_f32_32x32x16_bf16 v[80:95], v[198:201], v[212:215], v[80:95]
	ds_read_b128 v[208:211], v151 offset:9312
	ds_read_b128 v[212:215], v151 offset:13920
	s_waitcnt lgkmcnt(1)
	v_mfma_f32_32x32x16_bf16 v[32:47], v[194:197], v[208:211], v[32:47]
	v_mfma_f32_32x32x16_bf16 v[48:63], v[198:201], v[208:211], v[48:63]
	s_waitcnt lgkmcnt(0)
	v_mfma_f32_32x32x16_bf16 v[0:15], v[194:197], v[212:215], v[0:15]
	v_mfma_f32_32x32x16_bf16 v[16:31], v[198:201], v[212:215], v[16:31]
	s_setprio 0
	s_barrier
; template <bool trans>
; DI void gemm_core(const GTile& tl, const GTile& nx, bool has_next  , bool chain  , bool pre, u32x4 (&ra)[4], u32x4 (&rb)[4], char* smem, f32x16 (&acc)[2][4]) {
;     ...
;   const int nk = K / 64;
;   if (!pre) { G_LOAD(0); G_STORE(0); G_LOAD(1); }
;   for (int kt = 0; kt < nk; ++kt) {
;     __syncthreads();
;     G_COMPUTE(kt & 1, kt);
;   }
	global_load_dwordx4 v[194:197], v[136:137], off offset:1408
	global_load_dwordx4 v[198:201], v[138:139], off offset:1408
	s_waitcnt vmcnt(9)
	ds_write_b128 v148, v[176:179]
	s_waitcnt vmcnt(8)
	ds_write_b128 v148, v[180:183] offset:36864
	ds_read_b128 v[176:179], v150
	ds_read_b128 v[180:183], v150 offset:4608
	ds_read_b128 v[208:211], v149
	ds_read_b128 v[212:215], v149 offset:4608
	s_setprio 1
	s_waitcnt lgkmcnt(1)
	v_mfma_f32_32x32x16_bf16 v[96:111], v[176:179], v[208:211], v[96:111]
	v_mfma_f32_32x32x16_bf16 v[112:127], v[180:183], v[208:211], v[112:127]
	s_waitcnt lgkmcnt(0)
	v_mfma_f32_32x32x16_bf16 v[64:79], v[176:179], v[212:215], v[64:79]
	v_mfma_f32_32x32x16_bf16 v[80:95], v[180:183], v[212:215], v[80:95]
	ds_read_b128 v[208:211], v149 offset:9216
	ds_read_b128 v[212:215], v149 offset:13824
	s_waitcnt vmcnt(7)
	ds_write_b128 v148, v[168:171] offset:9216
	s_waitcnt vmcnt(6)
	ds_write_b128 v148, v[172:175] offset:46080
	ds_read_b128 v[168:171], v150 offset:32
	ds_read_b128 v[172:175], v150 offset:4640
	s_waitcnt lgkmcnt(5)
	v_mfma_f32_32x32x16_bf16 v[32:47], v[176:179], v[208:211], v[32:47]
	v_mfma_f32_32x32x16_bf16 v[48:63], v[180:183], v[208:211], v[48:63]
	ds_read_b128 v[208:211], v149 offset:32
	s_waitcnt lgkmcnt(5)
	v_mfma_f32_32x32x16_bf16 v[0:15], v[176:179], v[212:215], v[0:15]
	v_mfma_f32_32x32x16_bf16 v[16:31], v[180:183], v[212:215], v[16:31]
	ds_read_b128 v[212:215], v149 offset:4640
	s_setprio 0
	global_load_dwordx4 v[176:179], v[140:141], off offset:1408
	global_load_dwordx4 v[180:183], v[142:143], off offset:1408
	s_setprio 1
	s_waitcnt lgkmcnt(1)
	v_mfma_f32_32x32x16_bf16 v[96:111], v[168:171], v[208:211], v[96:111]
	v_mfma_f32_32x32x16_bf16 v[112:127], v[172:175], v[208:211], v[112:127]
	s_waitcnt lgkmcnt(0)
	v_mfma_f32_32x32x16_bf16 v[64:79], v[168:171], v[212:215], v[64:79]
	v_mfma_f32_32x32x16_bf16 v[80:95], v[172:175], v[212:215], v[80:95]
	ds_read_b128 v[208:211], v149 offset:9248
	ds_read_b128 v[212:215], v149 offset:13856
	s_waitcnt vmcnt(7)
	ds_write_b128 v148, v[160:163] offset:18432
	s_waitcnt vmcnt(6)
	ds_write_b128 v148, v[164:167] offset:55296
	ds_read_b128 v[160:163], v150 offset:64
	ds_read_b128 v[164:167], v150 offset:4672
	s_waitcnt lgkmcnt(5)
	v_mfma_f32_32x32x16_bf16 v[32:47], v[168:171], v[208:211], v[32:47]
	v_mfma_f32_32x32x16_bf16 v[48:63], v[172:175], v[208:211], v[48:63]
	ds_read_b128 v[208:211], v149 offset:64
	s_waitcnt lgkmcnt(5)
	v_mfma_f32_32x32x16_bf16 v[0:15], v[168:171], v[212:215], v[0:15]
	v_mfma_f32_32x32x16_bf16 v[16:31], v[172:175], v[212:215], v[16:31]
	ds_read_b128 v[212:215], v149 offset:4672
	s_setprio 0
	global_load_dwordx4 v[168:171], v[132:133], off offset:1408
	global_load_dwordx4 v[172:175], v[134:135], off offset:1408
	s_setprio 1
	s_waitcnt lgkmcnt(1)
	v_mfma_f32_32x32x16_bf16 v[96:111], v[160:163], v[208:211], v[96:111]
	v_mfma_f32_32x32x16_bf16 v[112:127], v[164:167], v[208:211], v[112:127]
	s_waitcnt lgkmcnt(0)
	v_mfma_f32_32x32x16_bf16 v[64:79], v[160:163], v[212:215], v[64:79]
	v_mfma_f32_32x32x16_bf16 v[80:95], v[164:167], v[212:215], v[80:95]
	ds_read_b128 v[208:211], v149 offset:9280
	ds_read_b128 v[212:215], v149 offset:13888
	s_waitcnt vmcnt(7)
	ds_write_b128 v148, v[184:187] offset:27648
	s_waitcnt vmcnt(6)
	ds_write_b128 v148, v[188:191] offset:64512
	ds_read_b128 v[184:187], v150 offset:96
	ds_read_b128 v[188:191], v150 offset:4704
	s_waitcnt lgkmcnt(5)
	v_mfma_f32_32x32x16_bf16 v[32:47], v[160:163], v[208:211], v[32:47]
	v_mfma_f32_32x32x16_bf16 v[48:63], v[164:167], v[208:211], v[48:63]
	ds_read_b128 v[208:211], v149 offset:96
	s_waitcnt lgkmcnt(5)
	v_mfma_f32_32x32x16_bf16 v[0:15], v[160:163], v[212:215], v[0:15]
	v_mfma_f32_32x32x16_bf16 v[16:31], v[164:167], v[212:215], v[16:31]
	ds_read_b128 v[212:215], v149 offset:4704
	s_setprio 0
	global_load_dwordx4 v[160:163], v[144:145], off offset:1408
	global_load_dwordx4 v[164:167], v[146:147], off offset:1408
	s_setprio 1
	s_waitcnt lgkmcnt(1)
	v_mfma_f32_32x32x16_bf16 v[96:111], v[184:187], v[208:211], v[96:111]
	v_mfma_f32_32x32x16_bf16 v[112:127], v[188:191], v[208:211], v[112:127]
	s_waitcnt lgkmcnt(0)
	v_mfma_f32_32x32x16_bf16 v[64:79], v[184:187], v[212:215], v[64:79]
	v_mfma_f32_32x32x16_bf16 v[80:95], v[188:191], v[212:215], v[80:95]
	ds_read_b128 v[208:211], v149 offset:9312
	ds_read_b128 v[212:215], v149 offset:13920
	s_waitcnt lgkmcnt(1)
	v_mfma_f32_32x32x16_bf16 v[32:47], v[184:187], v[208:211], v[32:47]
	v_mfma_f32_32x32x16_bf16 v[48:63], v[188:191], v[208:211], v[48:63]
	s_waitcnt lgkmcnt(0)
	v_mfma_f32_32x32x16_bf16 v[0:15], v[184:187], v[212:215], v[0:15]
	v_mfma_f32_32x32x16_bf16 v[16:31], v[188:191], v[212:215], v[16:31]
	s_setprio 0
	s_barrier
; template <bool trans>
; DI void gemm_core(const GTile& tl, const GTile& nx, bool has_next  , bool chain  , bool pre, u32x4 (&ra)[4], u32x4 (&rb)[4], char* smem, f32x16 (&acc)[2][4]) {
;     ...
;   const int nk = K / 64;
;   if (!pre) { G_LOAD(0); G_STORE(0); G_LOAD(1); }
;   for (int kt = 0; kt < nk; ++kt) {
;     __syncthreads();
;     G_COMPUTE(kt & 1, kt);
;   }
	global_load_dwordx4 v[184:187], v[136:137], off offset:1536
	global_load_dwordx4 v[188:191], v[138:139], off offset:1536
	s_waitcnt vmcnt(9)
	ds_write_b128 v192, v[194:197]
	s_waitcnt vmcnt(8)
	ds_write_b128 v159, v[198:201]
	ds_read_b128 v[194:197], v152 offset:36864
	ds_read_b128 v[198:201], v152 offset:41472
	ds_read_b128 v[208:211], v151
	ds_read_b128 v[212:215], v151 offset:4608
	s_setprio 1
	s_waitcnt lgkmcnt(1)
	v_mfma_f32_32x32x16_bf16 v[96:111], v[194:197], v[208:211], v[96:111]
	v_mfma_f32_32x32x16_bf16 v[112:127], v[198:201], v[208:211], v[112:127]
	s_waitcnt lgkmcnt(0)
	v_mfma_f32_32x32x16_bf16 v[64:79], v[194:197], v[212:215], v[64:79]
	v_mfma_f32_32x32x16_bf16 v[80:95], v[198:201], v[212:215], v[80:95]
	ds_read_b128 v[208:211], v151 offset:9216
	ds_read_b128 v[212:215], v151 offset:13824
	s_waitcnt vmcnt(7)
	ds_write_b128 v158, v[176:179]
	s_waitcnt vmcnt(6)
	ds_write_b128 v157, v[180:183]
	ds_read_b128 v[176:179], v152 offset:36896
	ds_read_b128 v[180:183], v152 offset:41504
	s_waitcnt lgkmcnt(5)
	v_mfma_f32_32x32x16_bf16 v[32:47], v[194:197], v[208:211], v[32:47]
	v_mfma_f32_32x32x16_bf16 v[48:63], v[198:201], v[208:211], v[48:63]
	ds_read_b128 v[208:211], v151 offset:32
	s_waitcnt lgkmcnt(5)
	v_mfma_f32_32x32x16_bf16 v[0:15], v[194:197], v[212:215], v[0:15]
	v_mfma_f32_32x32x16_bf16 v[16:31], v[198:201], v[212:215], v[16:31]
	ds_read_b128 v[212:215], v151 offset:4640
	s_setprio 0
	global_load_dwordx4 v[194:197], v[140:141], off offset:1536
	global_load_dwordx4 v[198:201], v[142:143], off offset:1536
	s_setprio 1
	s_waitcnt lgkmcnt(1)
	v_mfma_f32_32x32x16_bf16 v[96:111], v[176:179], v[208:211], v[96:111]
	v_mfma_f32_32x32x16_bf16 v[112:127], v[180:183], v[208:211], v[112:127]
	s_waitcnt lgkmcnt(0)
	v_mfma_f32_32x32x16_bf16 v[64:79], v[176:179], v[212:215], v[64:79]
	v_mfma_f32_32x32x16_bf16 v[80:95], v[180:183], v[212:215], v[80:95]
	ds_read_b128 v[208:211], v151 offset:9248
	ds_read_b128 v[212:215], v151 offset:13856
	s_waitcnt vmcnt(7)
	ds_write_b128 v154, v[168:171]
	s_waitcnt vmcnt(6)
	ds_write_b128 v153, v[172:175]
	ds_read_b128 v[168:171], v152 offset:36928
	ds_read_b128 v[172:175], v152 offset:41536
	s_waitcnt lgkmcnt(5)
	v_mfma_f32_32x32x16_bf16 v[32:47], v[176:179], v[208:211], v[32:47]
	v_mfma_f32_32x32x16_bf16 v[48:63], v[180:183], v[208:211], v[48:63]
	ds_read_b128 v[208:211], v151 offset:64
	s_waitcnt lgkmcnt(5)
	v_mfma_f32_32x32x16_bf16 v[0:15], v[176:179], v[212:215], v[0:15]
	v_mfma_f32_32x32x16_bf16 v[16:31], v[180:183], v[212:215], v[16:31]
	ds_read_b128 v[212:215], v151 offset:4672
	s_setprio 0
	global_load_dwordx4 v[176:179], v[132:133], off offset:1536
	global_load_dwordx4 v[180:183], v[134:135], off offset:1536
	s_setprio 1
	s_waitcnt lgkmcnt(1)
	v_mfma_f32_32x32x16_bf16 v[96:111], v[168:171], v[208:211], v[96:111]
	v_mfma_f32_32x32x16_bf16 v[112:127], v[172:175], v[208:211], v[112:127]
	s_waitcnt lgkmcnt(0)
	v_mfma_f32_32x32x16_bf16 v[64:79], v[168:171], v[212:215], v[64:79]
	v_mfma_f32_32x32x16_bf16 v[80:95], v[172:175], v[212:215], v[80:95]
	ds_read_b128 v[208:211], v151 offset:9280
	ds_read_b128 v[212:215], v151 offset:13888
	s_waitcnt vmcnt(7)
	ds_write_b128 v156, v[160:163]
	s_waitcnt vmcnt(6)
	ds_write_b128 v155, v[164:167]
	ds_read_b128 v[160:163], v152 offset:36960
	ds_read_b128 v[164:167], v152 offset:41568
	s_waitcnt lgkmcnt(5)
	v_mfma_f32_32x32x16_bf16 v[32:47], v[168:171], v[208:211], v[32:47]
	v_mfma_f32_32x32x16_bf16 v[48:63], v[172:175], v[208:211], v[48:63]
	ds_read_b128 v[208:211], v151 offset:96
	s_waitcnt lgkmcnt(5)
	v_mfma_f32_32x32x16_bf16 v[0:15], v[168:171], v[212:215], v[0:15]
	v_mfma_f32_32x32x16_bf16 v[16:31], v[172:175], v[212:215], v[16:31]
	ds_read_b128 v[212:215], v151 offset:4704
	s_setprio 0
	global_load_dwordx4 v[168:171], v[144:145], off offset:1536
	global_load_dwordx4 v[172:175], v[146:147], off offset:1536
	s_setprio 1
	s_waitcnt lgkmcnt(1)
	v_mfma_f32_32x32x16_bf16 v[96:111], v[160:163], v[208:211], v[96:111]
	v_mfma_f32_32x32x16_bf16 v[112:127], v[164:167], v[208:211], v[112:127]
	s_waitcnt lgkmcnt(0)
	v_mfma_f32_32x32x16_bf16 v[64:79], v[160:163], v[212:215], v[64:79]
	v_mfma_f32_32x32x16_bf16 v[80:95], v[164:167], v[212:215], v[80:95]
	ds_read_b128 v[208:211], v151 offset:9312
	ds_read_b128 v[212:215], v151 offset:13920
	s_waitcnt lgkmcnt(1)
	v_mfma_f32_32x32x16_bf16 v[32:47], v[160:163], v[208:211], v[32:47]
	v_mfma_f32_32x32x16_bf16 v[48:63], v[164:167], v[208:211], v[48:63]
	s_waitcnt lgkmcnt(0)
	v_mfma_f32_32x32x16_bf16 v[0:15], v[160:163], v[212:215], v[0:15]
	v_mfma_f32_32x32x16_bf16 v[16:31], v[164:167], v[212:215], v[16:31]
	s_setprio 0
	s_barrier
; template <bool trans>
; DI void gemm_core(const GTile& tl, const GTile& nx, bool has_next  , bool chain  , bool pre, u32x4 (&ra)[4], u32x4 (&rb)[4], char* smem, f32x16 (&acc)[2][4]) {
;     ...
;   const int nk = K / 64;
;   if (!pre) { G_LOAD(0); G_STORE(0); G_LOAD(1); }
;   for (int kt = 0; kt < nk; ++kt) {
;     __syncthreads();
;     G_COMPUTE(kt & 1, kt);
;   }
	global_load_dwordx4 v[160:163], v[136:137], off offset:1664
	global_load_dwordx4 v[164:167], v[138:139], off offset:1664
	s_waitcnt vmcnt(9)
	ds_write_b128 v148, v[184:187]
	s_waitcnt vmcnt(8)
	ds_write_b128 v148, v[188:191] offset:36864
	ds_read_b128 v[184:187], v150
	ds_read_b128 v[188:191], v150 offset:4608
	ds_read_b128 v[208:211], v149
	ds_read_b128 v[212:215], v149 offset:4608
	s_setprio 1
	s_waitcnt lgkmcnt(1)
	v_mfma_f32_32x32x16_bf16 v[96:111], v[184:187], v[208:211], v[96:111]
	v_mfma_f32_32x32x16_bf16 v[112:127], v[188:191], v[208:211], v[112:127]
	s_waitcnt lgkmcnt(0)
	v_mfma_f32_32x32x16_bf16 v[64:79], v[184:187], v[212:215], v[64:79]
	v_mfma_f32_32x32x16_bf16 v[80:95], v[188:191], v[212:215], v[80:95]
	ds_read_b128 v[208:211], v149 offset:9216
	ds_read_b128 v[212:215], v149 offset:13824
	s_waitcnt vmcnt(7)
	ds_write_b128 v148, v[194:197] offset:9216
	s_waitcnt vmcnt(6)
	ds_write_b128 v148, v[198:201] offset:46080
	ds_read_b128 v[194:197], v150 offset:32
	ds_read_b128 v[198:201], v150 offset:4640
	s_waitcnt lgkmcnt(5)
	v_mfma_f32_32x32x16_bf16 v[32:47], v[184:187], v[208:211], v[32:47]
	v_mfma_f32_32x32x16_bf16 v[48:63], v[188:191], v[208:211], v[48:63]
	ds_read_b128 v[208:211], v149 offset:32
	s_waitcnt lgkmcnt(5)
	v_mfma_f32_32x32x16_bf16 v[0:15], v[184:187], v[212:215], v[0:15]
	v_mfma_f32_32x32x16_bf16 v[16:31], v[188:191], v[212:215], v[16:31]
	ds_read_b128 v[212:215], v149 offset:4640
	s_setprio 0
	global_load_dwordx4 v[184:187], v[140:141], off offset:1664
	global_load_dwordx4 v[188:191], v[142:143], off offset:1664
	s_setprio 1
	s_waitcnt lgkmcnt(1)
	v_mfma_f32_32x32x16_bf16 v[96:111], v[194:197], v[208:211], v[96:111]
	v_mfma_f32_32x32x16_bf16 v[112:127], v[198:201], v[208:211], v[112:127]
	s_waitcnt lgkmcnt(0)
	v_mfma_f32_32x32x16_bf16 v[64:79], v[194:197], v[212:215], v[64:79]
	v_mfma_f32_32x32x16_bf16 v[80:95], v[198:201], v[212:215], v[80:95]
	ds_read_b128 v[208:211], v149 offset:9248
	ds_read_b128 v[212:215], v149 offset:13856
	s_waitcnt vmcnt(7)
	ds_write_b128 v148, v[176:179] offset:18432
	s_waitcnt vmcnt(6)
	ds_write_b128 v148, v[180:183] offset:55296
	ds_read_b128 v[176:179], v150 offset:64
	ds_read_b128 v[180:183], v150 offset:4672
	s_waitcnt lgkmcnt(5)
	v_mfma_f32_32x32x16_bf16 v[32:47], v[194:197], v[208:211], v[32:47]
	v_mfma_f32_32x32x16_bf16 v[48:63], v[198:201], v[208:211], v[48:63]
	ds_read_b128 v[208:211], v149 offset:64
	s_waitcnt lgkmcnt(5)
	v_mfma_f32_32x32x16_bf16 v[0:15], v[194:197], v[212:215], v[0:15]
	v_mfma_f32_32x32x16_bf16 v[16:31], v[198:201], v[212:215], v[16:31]
	ds_read_b128 v[212:215], v149 offset:4672
	s_setprio 0
	global_load_dwordx4 v[194:197], v[132:133], off offset:1664
	global_load_dwordx4 v[198:201], v[134:135], off offset:1664
	s_setprio 1
	s_waitcnt lgkmcnt(1)
	v_mfma_f32_32x32x16_bf16 v[96:111], v[176:179], v[208:211], v[96:111]
	v_mfma_f32_32x32x16_bf16 v[112:127], v[180:183], v[208:211], v[112:127]
	s_waitcnt lgkmcnt(0)
	v_mfma_f32_32x32x16_bf16 v[64:79], v[176:179], v[212:215], v[64:79]
	v_mfma_f32_32x32x16_bf16 v[80:95], v[180:183], v[212:215], v[80:95]
	ds_read_b128 v[208:211], v149 offset:9280
	ds_read_b128 v[212:215], v149 offset:13888
	s_waitcnt vmcnt(7)
	ds_write_b128 v148, v[168:171] offset:27648
	s_waitcnt vmcnt(6)
	ds_write_b128 v148, v[172:175] offset:64512
	ds_read_b128 v[168:171], v150 offset:96
	ds_read_b128 v[172:175], v150 offset:4704
	s_waitcnt lgkmcnt(5)
	v_mfma_f32_32x32x16_bf16 v[32:47], v[176:179], v[208:211], v[32:47]
	v_mfma_f32_32x32x16_bf16 v[48:63], v[180:183], v[208:211], v[48:63]
	ds_read_b128 v[208:211], v149 offset:96
	s_waitcnt lgkmcnt(5)
	v_mfma_f32_32x32x16_bf16 v[0:15], v[176:179], v[212:215], v[0:15]
	v_mfma_f32_32x32x16_bf16 v[16:31], v[180:183], v[212:215], v[16:31]
	ds_read_b128 v[212:215], v149 offset:4704
	s_setprio 0
	global_load_dwordx4 v[176:179], v[144:145], off offset:1664
	global_load_dwordx4 v[180:183], v[146:147], off offset:1664
	s_setprio 1
	s_waitcnt lgkmcnt(1)
	v_mfma_f32_32x32x16_bf16 v[96:111], v[168:171], v[208:211], v[96:111]
	v_mfma_f32_32x32x16_bf16 v[112:127], v[172:175], v[208:211], v[112:127]
	s_waitcnt lgkmcnt(0)
	v_mfma_f32_32x32x16_bf16 v[64:79], v[168:171], v[212:215], v[64:79]
	v_mfma_f32_32x32x16_bf16 v[80:95], v[172:175], v[212:215], v[80:95]
	ds_read_b128 v[208:211], v149 offset:9312
	ds_read_b128 v[212:215], v149 offset:13920
	s_waitcnt lgkmcnt(1)
	v_mfma_f32_32x32x16_bf16 v[32:47], v[168:171], v[208:211], v[32:47]
	v_mfma_f32_32x32x16_bf16 v[48:63], v[172:175], v[208:211], v[48:63]
	s_waitcnt lgkmcnt(0)
	v_mfma_f32_32x32x16_bf16 v[0:15], v[168:171], v[212:215], v[0:15]
	v_mfma_f32_32x32x16_bf16 v[16:31], v[172:175], v[212:215], v[16:31]
	s_setprio 0
	s_barrier
; template <bool trans>
; DI void gemm_core(const GTile& tl, const GTile& nx, bool has_next  , bool chain  , bool pre, u32x4 (&ra)[4], u32x4 (&rb)[4], char* smem, f32x16 (&acc)[2][4]) {
;     ...
;   const int nk = K / 64;
;   if (!pre) { G_LOAD(0); G_STORE(0); G_LOAD(1); }
;   for (int kt = 0; kt < nk; ++kt) {
;     __syncthreads();
;     G_COMPUTE(kt & 1, kt);
;   }
	global_load_dwordx4 v[168:171], v[136:137], off offset:1792
	global_load_dwordx4 v[172:175], v[138:139], off offset:1792
	s_waitcnt vmcnt(9)
	ds_write_b128 v192, v[160:163]
	s_waitcnt vmcnt(8)
	ds_write_b128 v159, v[164:167]
	ds_read_b128 v[160:163], v152 offset:36864
	ds_read_b128 v[164:167], v152 offset:41472
	ds_read_b128 v[208:211], v151
	ds_read_b128 v[212:215], v151 offset:4608
	s_setprio 1
	s_waitcnt lgkmcnt(1)
	v_mfma_f32_32x32x16_bf16 v[96:111], v[160:163], v[208:211], v[96:111]
	v_mfma_f32_32x32x16_bf16 v[112:127], v[164:167], v[208:211], v[112:127]
	s_waitcnt lgkmcnt(0)
	v_mfma_f32_32x32x16_bf16 v[64:79], v[160:163], v[212:215], v[64:79]
	v_mfma_f32_32x32x16_bf16 v[80:95], v[164:167], v[212:215], v[80:95]
	ds_read_b128 v[208:211], v151 offset:9216
	ds_read_b128 v[212:215], v151 offset:13824
	s_waitcnt vmcnt(7)
	ds_write_b128 v158, v[184:187]
	s_waitcnt vmcnt(6)
	ds_write_b128 v157, v[188:191]
	ds_read_b128 v[184:187], v152 offset:36896
	ds_read_b128 v[188:191], v152 offset:41504
	s_waitcnt lgkmcnt(5)
	v_mfma_f32_32x32x16_bf16 v[32:47], v[160:163], v[208:211], v[32:47]
	v_mfma_f32_32x32x16_bf16 v[48:63], v[164:167], v[208:211], v[48:63]
	ds_read_b128 v[208:211], v151 offset:32
	s_waitcnt lgkmcnt(5)
	v_mfma_f32_32x32x16_bf16 v[0:15], v[160:163], v[212:215], v[0:15]
	v_mfma_f32_32x32x16_bf16 v[16:31], v[164:167], v[212:215], v[16:31]
	ds_read_b128 v[212:215], v151 offset:4640
	s_setprio 0
	global_load_dwordx4 v[160:163], v[140:141], off offset:1792
	global_load_dwordx4 v[164:167], v[142:143], off offset:1792
	s_setprio 1
	s_waitcnt lgkmcnt(1)
	v_mfma_f32_32x32x16_bf16 v[96:111], v[184:187], v[208:211], v[96:111]
	v_mfma_f32_32x32x16_bf16 v[112:127], v[188:191], v[208:211], v[112:127]
	s_waitcnt lgkmcnt(0)
	v_mfma_f32_32x32x16_bf16 v[64:79], v[184:187], v[212:215], v[64:79]
	v_mfma_f32_32x32x16_bf16 v[80:95], v[188:191], v[212:215], v[80:95]
	ds_read_b128 v[208:211], v151 offset:9248
	ds_read_b128 v[212:215], v151 offset:13856
	s_waitcnt vmcnt(7)
	ds_write_b128 v154, v[194:197]
	s_waitcnt vmcnt(6)
	ds_write_b128 v153, v[198:201]
	ds_read_b128 v[194:197], v152 offset:36928
	ds_read_b128 v[198:201], v152 offset:41536
	s_waitcnt lgkmcnt(5)
	v_mfma_f32_32x32x16_bf16 v[32:47], v[184:187], v[208:211], v[32:47]
	v_mfma_f32_32x32x16_bf16 v[48:63], v[188:191], v[208:211], v[48:63]
	ds_read_b128 v[208:211], v151 offset:64
	s_waitcnt lgkmcnt(5)
	v_mfma_f32_32x32x16_bf16 v[0:15], v[184:187], v[212:215], v[0:15]
	v_mfma_f32_32x32x16_bf16 v[16:31], v[188:191], v[212:215], v[16:31]
	ds_read_b128 v[212:215], v151 offset:4672
	s_setprio 0
	global_load_dwordx4 v[184:187], v[132:133], off offset:1792
	global_load_dwordx4 v[188:191], v[134:135], off offset:1792
	s_setprio 1
	s_waitcnt lgkmcnt(1)
	v_mfma_f32_32x32x16_bf16 v[96:111], v[194:197], v[208:211], v[96:111]
	v_mfma_f32_32x32x16_bf16 v[112:127], v[198:201], v[208:211], v[112:127]
	s_waitcnt lgkmcnt(0)
	v_mfma_f32_32x32x16_bf16 v[64:79], v[194:197], v[212:215], v[64:79]
	v_mfma_f32_32x32x16_bf16 v[80:95], v[198:201], v[212:215], v[80:95]
	ds_read_b128 v[208:211], v151 offset:9280
	ds_read_b128 v[212:215], v151 offset:13888
	s_waitcnt vmcnt(7)
	ds_write_b128 v156, v[176:179]
	s_waitcnt vmcnt(6)
	ds_write_b128 v155, v[180:183]
	ds_read_b128 v[176:179], v152 offset:36960
	ds_read_b128 v[180:183], v152 offset:41568
	s_waitcnt lgkmcnt(5)
	v_mfma_f32_32x32x16_bf16 v[32:47], v[194:197], v[208:211], v[32:47]
	v_mfma_f32_32x32x16_bf16 v[48:63], v[198:201], v[208:211], v[48:63]
	ds_read_b128 v[208:211], v151 offset:96
	s_waitcnt lgkmcnt(5)
	v_mfma_f32_32x32x16_bf16 v[0:15], v[194:197], v[212:215], v[0:15]
	v_mfma_f32_32x32x16_bf16 v[16:31], v[198:201], v[212:215], v[16:31]
	ds_read_b128 v[212:215], v151 offset:4704
	s_setprio 0
	global_load_dwordx4 v[194:197], v[144:145], off offset:1792
	global_load_dwordx4 v[198:201], v[146:147], off offset:1792
	s_setprio 1
	s_waitcnt lgkmcnt(1)
	v_mfma_f32_32x32x16_bf16 v[96:111], v[176:179], v[208:211], v[96:111]
	v_mfma_f32_32x32x16_bf16 v[112:127], v[180:183], v[208:211], v[112:127]
	s_waitcnt lgkmcnt(0)
	v_mfma_f32_32x32x16_bf16 v[64:79], v[176:179], v[212:215], v[64:79]
	v_mfma_f32_32x32x16_bf16 v[80:95], v[180:183], v[212:215], v[80:95]
	ds_read_b128 v[208:211], v151 offset:9312
	ds_read_b128 v[212:215], v151 offset:13920
	s_waitcnt lgkmcnt(1)
	v_mfma_f32_32x32x16_bf16 v[32:47], v[176:179], v[208:211], v[32:47]
	v_mfma_f32_32x32x16_bf16 v[48:63], v[180:183], v[208:211], v[48:63]
	s_waitcnt lgkmcnt(0)
	v_mfma_f32_32x32x16_bf16 v[0:15], v[176:179], v[212:215], v[0:15]
	v_mfma_f32_32x32x16_bf16 v[16:31], v[180:183], v[212:215], v[16:31]
	s_setprio 0
	s_barrier
; template <bool trans>
; DI void gemm_core(const GTile& tl, const GTile& nx, bool has_next  , bool chain  , bool pre, u32x4 (&ra)[4], u32x4 (&rb)[4], char* smem, f32x16 (&acc)[2][4]) {
;     ...
;   const int nk = K / 64;
;   if (!pre) { G_LOAD(0); G_STORE(0); G_LOAD(1); }
;   for (int kt = 0; kt < nk; ++kt) {
;     __syncthreads();
;     G_COMPUTE(kt & 1, kt);
;   }
	global_load_dwordx4 v[176:179], v[136:137], off offset:1920
	global_load_dwordx4 v[180:183], v[138:139], off offset:1920
	s_waitcnt vmcnt(9)
	ds_write_b128 v148, v[168:171]
	s_waitcnt vmcnt(8)
	ds_write_b128 v148, v[172:175] offset:36864
	ds_read_b128 v[168:171], v150
	ds_read_b128 v[172:175], v150 offset:4608
	ds_read_b128 v[208:211], v149
	ds_read_b128 v[212:215], v149 offset:4608
	s_setprio 1
	s_waitcnt lgkmcnt(1)
	v_mfma_f32_32x32x16_bf16 v[96:111], v[168:171], v[208:211], v[96:111]
	v_mfma_f32_32x32x16_bf16 v[112:127], v[172:175], v[208:211], v[112:127]
	s_waitcnt lgkmcnt(0)
	v_mfma_f32_32x32x16_bf16 v[64:79], v[168:171], v[212:215], v[64:79]
	v_mfma_f32_32x32x16_bf16 v[80:95], v[172:175], v[212:215], v[80:95]
	ds_read_b128 v[208:211], v149 offset:9216
	ds_read_b128 v[212:215], v149 offset:13824
	s_waitcnt vmcnt(7)
	ds_write_b128 v148, v[160:163] offset:9216
	s_waitcnt vmcnt(6)
	ds_write_b128 v148, v[164:167] offset:46080
	ds_read_b128 v[160:163], v150 offset:32
	ds_read_b128 v[164:167], v150 offset:4640
	s_waitcnt lgkmcnt(5)
	v_mfma_f32_32x32x16_bf16 v[32:47], v[168:171], v[208:211], v[32:47]
	v_mfma_f32_32x32x16_bf16 v[48:63], v[172:175], v[208:211], v[48:63]
	ds_read_b128 v[208:211], v149 offset:32
	s_waitcnt lgkmcnt(5)
	v_mfma_f32_32x32x16_bf16 v[0:15], v[168:171], v[212:215], v[0:15]
	v_mfma_f32_32x32x16_bf16 v[16:31], v[172:175], v[212:215], v[16:31]
	ds_read_b128 v[212:215], v149 offset:4640
	s_setprio 0
	global_load_dwordx4 v[168:171], v[140:141], off offset:1920
	global_load_dwordx4 v[172:175], v[142:143], off offset:1920
	s_setprio 1
	s_waitcnt lgkmcnt(1)
	v_mfma_f32_32x32x16_bf16 v[96:111], v[160:163], v[208:211], v[96:111]
	v_mfma_f32_32x32x16_bf16 v[112:127], v[164:167], v[208:211], v[112:127]
	s_waitcnt lgkmcnt(0)
	v_mfma_f32_32x32x16_bf16 v[64:79], v[160:163], v[212:215], v[64:79]
	v_mfma_f32_32x32x16_bf16 v[80:95], v[164:167], v[212:215], v[80:95]
	ds_read_b128 v[208:211], v149 offset:9248
	ds_read_b128 v[212:215], v149 offset:13856
	s_waitcnt vmcnt(7)
	ds_write_b128 v148, v[184:187] offset:18432
	s_waitcnt vmcnt(6)
	ds_write_b128 v148, v[188:191] offset:55296
	ds_read_b128 v[184:187], v150 offset:64
	ds_read_b128 v[188:191], v150 offset:4672
	s_waitcnt lgkmcnt(5)
	v_mfma_f32_32x32x16_bf16 v[32:47], v[160:163], v[208:211], v[32:47]
	v_mfma_f32_32x32x16_bf16 v[48:63], v[164:167], v[208:211], v[48:63]
	ds_read_b128 v[208:211], v149 offset:64
	s_waitcnt lgkmcnt(5)
	v_mfma_f32_32x32x16_bf16 v[0:15], v[160:163], v[212:215], v[0:15]
	v_mfma_f32_32x32x16_bf16 v[16:31], v[164:167], v[212:215], v[16:31]
	ds_read_b128 v[212:215], v149 offset:4672
	s_setprio 0
	global_load_dwordx4 v[160:163], v[132:133], off offset:1920
	global_load_dwordx4 v[164:167], v[134:135], off offset:1920
	s_setprio 1
	s_waitcnt lgkmcnt(1)
	v_mfma_f32_32x32x16_bf16 v[96:111], v[184:187], v[208:211], v[96:111]
	v_mfma_f32_32x32x16_bf16 v[112:127], v[188:191], v[208:211], v[112:127]
	s_waitcnt lgkmcnt(0)
	v_mfma_f32_32x32x16_bf16 v[64:79], v[184:187], v[212:215], v[64:79]
	v_mfma_f32_32x32x16_bf16 v[80:95], v[188:191], v[212:215], v[80:95]
	ds_read_b128 v[208:211], v149 offset:9280
	ds_read_b128 v[212:215], v149 offset:13888
	s_waitcnt vmcnt(7)
	ds_write_b128 v148, v[194:197] offset:27648
	s_waitcnt vmcnt(6)
	ds_write_b128 v148, v[198:201] offset:64512
	ds_read_b128 v[194:197], v150 offset:96
	ds_read_b128 v[198:201], v150 offset:4704
	s_waitcnt lgkmcnt(5)
	v_mfma_f32_32x32x16_bf16 v[32:47], v[184:187], v[208:211], v[32:47]
	v_mfma_f32_32x32x16_bf16 v[48:63], v[188:191], v[208:211], v[48:63]
	ds_read_b128 v[208:211], v149 offset:96
	s_waitcnt lgkmcnt(5)
	v_mfma_f32_32x32x16_bf16 v[0:15], v[184:187], v[212:215], v[0:15]
	v_mfma_f32_32x32x16_bf16 v[16:31], v[188:191], v[212:215], v[16:31]
	ds_read_b128 v[212:215], v149 offset:4704
	s_setprio 0
	global_load_dwordx4 v[184:187], v[144:145], off offset:1920
	global_load_dwordx4 v[188:191], v[146:147], off offset:1920
	s_setprio 1
	s_waitcnt lgkmcnt(1)
	v_mfma_f32_32x32x16_bf16 v[96:111], v[194:197], v[208:211], v[96:111]
	v_mfma_f32_32x32x16_bf16 v[112:127], v[198:201], v[208:211], v[112:127]
	s_waitcnt lgkmcnt(0)
	v_mfma_f32_32x32x16_bf16 v[64:79], v[194:197], v[212:215], v[64:79]
	v_mfma_f32_32x32x16_bf16 v[80:95], v[198:201], v[212:215], v[80:95]
	ds_read_b128 v[208:211], v149 offset:9312
	ds_read_b128 v[212:215], v149 offset:13920
	s_waitcnt lgkmcnt(1)
	v_mfma_f32_32x32x16_bf16 v[32:47], v[194:197], v[208:211], v[32:47]
	v_mfma_f32_32x32x16_bf16 v[48:63], v[198:201], v[208:211], v[48:63]
	s_waitcnt lgkmcnt(0)
	v_mfma_f32_32x32x16_bf16 v[0:15], v[194:197], v[212:215], v[0:15]
	v_mfma_f32_32x32x16_bf16 v[16:31], v[198:201], v[212:215], v[16:31]
	s_setprio 0
	s_barrier
; template <bool trans>
; DI void gemm_core(const GTile& tl, const GTile& nx, bool has_next  , bool chain  , bool pre, u32x4 (&ra)[4], u32x4 (&rb)[4], char* smem, f32x16 (&acc)[2][4]) {
;     ...
;   const int nk = K / 64;
;   if (!pre) { G_LOAD(0); G_STORE(0); G_LOAD(1); }
;   for (int kt = 0; kt < nk; ++kt) {
;     __syncthreads();
;     G_COMPUTE(kt & 1, kt);
;   }
	global_load_dwordx4 v[194:197], v[136:137], off offset:2048
	global_load_dwordx4 v[198:201], v[138:139], off offset:2048
	s_waitcnt vmcnt(9)
	ds_write_b128 v192, v[176:179]
	s_waitcnt vmcnt(8)
	ds_write_b128 v159, v[180:183]
	ds_read_b128 v[176:179], v152 offset:36864
	ds_read_b128 v[180:183], v152 offset:41472
	ds_read_b128 v[208:211], v151
	ds_read_b128 v[212:215], v151 offset:4608
	s_setprio 1
	s_waitcnt lgkmcnt(1)
	v_mfma_f32_32x32x16_bf16 v[96:111], v[176:179], v[208:211], v[96:111]
	v_mfma_f32_32x32x16_bf16 v[112:127], v[180:183], v[208:211], v[112:127]
	s_waitcnt lgkmcnt(0)
	v_mfma_f32_32x32x16_bf16 v[64:79], v[176:179], v[212:215], v[64:79]
	v_mfma_f32_32x32x16_bf16 v[80:95], v[180:183], v[212:215], v[80:95]
	ds_read_b128 v[208:211], v151 offset:9216
	ds_read_b128 v[212:215], v151 offset:13824
	s_waitcnt vmcnt(7)
	ds_write_b128 v158, v[168:171]
	s_waitcnt vmcnt(6)
	ds_write_b128 v157, v[172:175]
	ds_read_b128 v[168:171], v152 offset:36896
	ds_read_b128 v[172:175], v152 offset:41504
	s_waitcnt lgkmcnt(5)
	v_mfma_f32_32x32x16_bf16 v[32:47], v[176:179], v[208:211], v[32:47]
	v_mfma_f32_32x32x16_bf16 v[48:63], v[180:183], v[208:211], v[48:63]
	ds_read_b128 v[208:211], v151 offset:32
	s_waitcnt lgkmcnt(5)
	v_mfma_f32_32x32x16_bf16 v[0:15], v[176:179], v[212:215], v[0:15]
	v_mfma_f32_32x32x16_bf16 v[16:31], v[180:183], v[212:215], v[16:31]
	ds_read_b128 v[212:215], v151 offset:4640
	s_setprio 0
	global_load_dwordx4 v[176:179], v[140:141], off offset:2048
	global_load_dwordx4 v[180:183], v[142:143], off offset:2048
	s_setprio 1
	s_waitcnt lgkmcnt(1)
	v_mfma_f32_32x32x16_bf16 v[96:111], v[168:171], v[208:211], v[96:111]
	v_mfma_f32_32x32x16_bf16 v[112:127], v[172:175], v[208:211], v[112:127]
	s_waitcnt lgkmcnt(0)
	v_mfma_f32_32x32x16_bf16 v[64:79], v[168:171], v[212:215], v[64:79]
	v_mfma_f32_32x32x16_bf16 v[80:95], v[172:175], v[212:215], v[80:95]
	ds_read_b128 v[208:211], v151 offset:9248
	ds_read_b128 v[212:215], v151 offset:13856
	s_waitcnt vmcnt(7)
	ds_write_b128 v154, v[160:163]
	s_waitcnt vmcnt(6)
	ds_write_b128 v153, v[164:167]
	ds_read_b128 v[160:163], v152 offset:36928
	ds_read_b128 v[164:167], v152 offset:41536
	s_waitcnt lgkmcnt(5)
	v_mfma_f32_32x32x16_bf16 v[32:47], v[168:171], v[208:211], v[32:47]
	v_mfma_f32_32x32x16_bf16 v[48:63], v[172:175], v[208:211], v[48:63]
	ds_read_b128 v[208:211], v151 offset:64
	s_waitcnt lgkmcnt(5)
	v_mfma_f32_32x32x16_bf16 v[0:15], v[168:171], v[212:215], v[0:15]
	v_mfma_f32_32x32x16_bf16 v[16:31], v[172:175], v[212:215], v[16:31]
	ds_read_b128 v[212:215], v151 offset:4672
	s_setprio 0
	global_load_dwordx4 v[168:171], v[132:133], off offset:2048
	global_load_dwordx4 v[172:175], v[134:135], off offset:2048
	s_setprio 1
	s_waitcnt lgkmcnt(1)
	v_mfma_f32_32x32x16_bf16 v[96:111], v[160:163], v[208:211], v[96:111]
	v_mfma_f32_32x32x16_bf16 v[112:127], v[164:167], v[208:211], v[112:127]
	s_waitcnt lgkmcnt(0)
	v_mfma_f32_32x32x16_bf16 v[64:79], v[160:163], v[212:215], v[64:79]
	v_mfma_f32_32x32x16_bf16 v[80:95], v[164:167], v[212:215], v[80:95]
	ds_read_b128 v[208:211], v151 offset:9280
	ds_read_b128 v[212:215], v151 offset:13888
	s_waitcnt vmcnt(7)
	ds_write_b128 v156, v[184:187]
	s_waitcnt vmcnt(6)
	ds_write_b128 v155, v[188:191]
	ds_read_b128 v[184:187], v152 offset:36960
	ds_read_b128 v[188:191], v152 offset:41568
	s_waitcnt lgkmcnt(5)
	v_mfma_f32_32x32x16_bf16 v[32:47], v[160:163], v[208:211], v[32:47]
	v_mfma_f32_32x32x16_bf16 v[48:63], v[164:167], v[208:211], v[48:63]
	ds_read_b128 v[208:211], v151 offset:96
	s_waitcnt lgkmcnt(5)
	v_mfma_f32_32x32x16_bf16 v[0:15], v[160:163], v[212:215], v[0:15]
	v_mfma_f32_32x32x16_bf16 v[16:31], v[164:167], v[212:215], v[16:31]
	ds_read_b128 v[212:215], v151 offset:4704
	s_setprio 0
	global_load_dwordx4 v[160:163], v[144:145], off offset:2048
	global_load_dwordx4 v[164:167], v[146:147], off offset:2048
	s_setprio 1
	s_waitcnt lgkmcnt(1)
	v_mfma_f32_32x32x16_bf16 v[96:111], v[184:187], v[208:211], v[96:111]
	v_mfma_f32_32x32x16_bf16 v[112:127], v[188:191], v[208:211], v[112:127]
	s_waitcnt lgkmcnt(0)
	v_mfma_f32_32x32x16_bf16 v[64:79], v[184:187], v[212:215], v[64:79]
	v_mfma_f32_32x32x16_bf16 v[80:95], v[188:191], v[212:215], v[80:95]
	ds_read_b128 v[208:211], v151 offset:9312
	ds_read_b128 v[212:215], v151 offset:13920
	s_waitcnt lgkmcnt(1)
	v_mfma_f32_32x32x16_bf16 v[32:47], v[184:187], v[208:211], v[32:47]
	v_mfma_f32_32x32x16_bf16 v[48:63], v[188:191], v[208:211], v[48:63]
	s_waitcnt lgkmcnt(0)
	v_mfma_f32_32x32x16_bf16 v[0:15], v[184:187], v[212:215], v[0:15]
	v_mfma_f32_32x32x16_bf16 v[16:31], v[188:191], v[212:215], v[16:31]
	s_setprio 0
	s_barrier
; template <bool trans>
; DI void gemm_core(const GTile& tl, const GTile& nx, bool has_next  , bool chain  , bool pre, u32x4 (&ra)[4], u32x4 (&rb)[4], char* smem, f32x16 (&acc)[2][4]) {
;     ...
;   const int nk = K / 64;
;   if (!pre) { G_LOAD(0); G_STORE(0); G_LOAD(1); }
;   for (int kt = 0; kt < nk; ++kt) {
;     __syncthreads();
;     G_COMPUTE(kt & 1, kt);
;   }
	global_load_dwordx4 v[184:187], v[136:137], off offset:2176
	global_load_dwordx4 v[188:191], v[138:139], off offset:2176
	s_waitcnt vmcnt(9)
	ds_write_b128 v148, v[194:197]
	s_waitcnt vmcnt(8)
	ds_write_b128 v148, v[198:201] offset:36864
	ds_read_b128 v[194:197], v150
	ds_read_b128 v[198:201], v150 offset:4608
	ds_read_b128 v[208:211], v149
	ds_read_b128 v[212:215], v149 offset:4608
	s_setprio 1
	s_waitcnt lgkmcnt(1)
	v_mfma_f32_32x32x16_bf16 v[96:111], v[194:197], v[208:211], v[96:111]
	v_mfma_f32_32x32x16_bf16 v[112:127], v[198:201], v[208:211], v[112:127]
	s_waitcnt lgkmcnt(0)
	v_mfma_f32_32x32x16_bf16 v[64:79], v[194:197], v[212:215], v[64:79]
	v_mfma_f32_32x32x16_bf16 v[80:95], v[198:201], v[212:215], v[80:95]
	ds_read_b128 v[208:211], v149 offset:9216
	ds_read_b128 v[212:215], v149 offset:13824
	s_waitcnt vmcnt(7)
	ds_write_b128 v148, v[176:179] offset:9216
	s_waitcnt vmcnt(6)
	ds_write_b128 v148, v[180:183] offset:46080
	ds_read_b128 v[176:179], v150 offset:32
	ds_read_b128 v[180:183], v150 offset:4640
	s_waitcnt lgkmcnt(5)
	v_mfma_f32_32x32x16_bf16 v[32:47], v[194:197], v[208:211], v[32:47]
	v_mfma_f32_32x32x16_bf16 v[48:63], v[198:201], v[208:211], v[48:63]
	ds_read_b128 v[208:211], v149 offset:32
	s_waitcnt lgkmcnt(5)
	v_mfma_f32_32x32x16_bf16 v[0:15], v[194:197], v[212:215], v[0:15]
	v_mfma_f32_32x32x16_bf16 v[16:31], v[198:201], v[212:215], v[16:31]
	ds_read_b128 v[212:215], v149 offset:4640
	s_setprio 0
	global_load_dwordx4 v[194:197], v[140:141], off offset:2176
	global_load_dwordx4 v[198:201], v[142:143], off offset:2176
	s_setprio 1
	s_waitcnt lgkmcnt(1)
	v_mfma_f32_32x32x16_bf16 v[96:111], v[176:179], v[208:211], v[96:111]
	v_mfma_f32_32x32x16_bf16 v[112:127], v[180:183], v[208:211], v[112:127]
	s_waitcnt lgkmcnt(0)
	v_mfma_f32_32x32x16_bf16 v[64:79], v[176:179], v[212:215], v[64:79]
	v_mfma_f32_32x32x16_bf16 v[80:95], v[180:183], v[212:215], v[80:95]
	ds_read_b128 v[208:211], v149 offset:9248
	ds_read_b128 v[212:215], v149 offset:13856
	s_waitcnt vmcnt(7)
	ds_write_b128 v148, v[168:171] offset:18432
	s_waitcnt vmcnt(6)
	ds_write_b128 v148, v[172:175] offset:55296
	ds_read_b128 v[168:171], v150 offset:64
	ds_read_b128 v[172:175], v150 offset:4672
	s_waitcnt lgkmcnt(5)
	v_mfma_f32_32x32x16_bf16 v[32:47], v[176:179], v[208:211], v[32:47]
	v_mfma_f32_32x32x16_bf16 v[48:63], v[180:183], v[208:211], v[48:63]
	ds_read_b128 v[208:211], v149 offset:64
	s_waitcnt lgkmcnt(5)
	v_mfma_f32_32x32x16_bf16 v[0:15], v[176:179], v[212:215], v[0:15]
	v_mfma_f32_32x32x16_bf16 v[16:31], v[180:183], v[212:215], v[16:31]
	ds_read_b128 v[212:215], v149 offset:4672
	s_setprio 0
	global_load_dwordx4 v[176:179], v[132:133], off offset:2176
	global_load_dwordx4 v[180:183], v[134:135], off offset:2176
	s_setprio 1
	s_waitcnt lgkmcnt(1)
	v_mfma_f32_32x32x16_bf16 v[96:111], v[168:171], v[208:211], v[96:111]
	v_mfma_f32_32x32x16_bf16 v[112:127], v[172:175], v[208:211], v[112:127]
	s_waitcnt lgkmcnt(0)
	v_mfma_f32_32x32x16_bf16 v[64:79], v[168:171], v[212:215], v[64:79]
	v_mfma_f32_32x32x16_bf16 v[80:95], v[172:175], v[212:215], v[80:95]
	ds_read_b128 v[208:211], v149 offset:9280
	ds_read_b128 v[212:215], v149 offset:13888
	s_waitcnt vmcnt(7)
	ds_write_b128 v148, v[160:163] offset:27648
	s_waitcnt vmcnt(6)
	ds_write_b128 v148, v[164:167] offset:64512
	ds_read_b128 v[160:163], v150 offset:96
	ds_read_b128 v[164:167], v150 offset:4704
	s_waitcnt lgkmcnt(5)
	v_mfma_f32_32x32x16_bf16 v[32:47], v[168:171], v[208:211], v[32:47]
	v_mfma_f32_32x32x16_bf16 v[48:63], v[172:175], v[208:211], v[48:63]
	ds_read_b128 v[208:211], v149 offset:96
	s_waitcnt lgkmcnt(5)
	v_mfma_f32_32x32x16_bf16 v[0:15], v[168:171], v[212:215], v[0:15]
	v_mfma_f32_32x32x16_bf16 v[16:31], v[172:175], v[212:215], v[16:31]
	ds_read_b128 v[212:215], v149 offset:4704
	s_setprio 0
	global_load_dwordx4 v[168:171], v[144:145], off offset:2176
	global_load_dwordx4 v[172:175], v[146:147], off offset:2176
	s_setprio 1
	s_waitcnt lgkmcnt(1)
	v_mfma_f32_32x32x16_bf16 v[96:111], v[160:163], v[208:211], v[96:111]
	v_mfma_f32_32x32x16_bf16 v[112:127], v[164:167], v[208:211], v[112:127]
	s_waitcnt lgkmcnt(0)
	v_mfma_f32_32x32x16_bf16 v[64:79], v[160:163], v[212:215], v[64:79]
	v_mfma_f32_32x32x16_bf16 v[80:95], v[164:167], v[212:215], v[80:95]
	ds_read_b128 v[208:211], v149 offset:9312
	ds_read_b128 v[212:215], v149 offset:13920
	s_waitcnt lgkmcnt(1)
	v_mfma_f32_32x32x16_bf16 v[32:47], v[160:163], v[208:211], v[32:47]
	v_mfma_f32_32x32x16_bf16 v[48:63], v[164:167], v[208:211], v[48:63]
	s_waitcnt lgkmcnt(0)
	v_mfma_f32_32x32x16_bf16 v[0:15], v[160:163], v[212:215], v[0:15]
	v_mfma_f32_32x32x16_bf16 v[16:31], v[164:167], v[212:215], v[16:31]
	s_setprio 0
	s_barrier
; template <bool trans>
; DI void gemm_core(const GTile& tl, const GTile& nx, bool has_next  , bool chain  , bool pre, u32x4 (&ra)[4], u32x4 (&rb)[4], char* smem, f32x16 (&acc)[2][4]) {
;     ...
;   const int nk = K / 64;
;   if (!pre) { G_LOAD(0); G_STORE(0); G_LOAD(1); }
;   for (int kt = 0; kt < nk; ++kt) {
;     __syncthreads();
;     G_COMPUTE(kt & 1, kt);
;   }
	global_load_dwordx4 v[160:163], v[136:137], off offset:2304
	global_load_dwordx4 v[164:167], v[138:139], off offset:2304
	s_waitcnt vmcnt(9)
	ds_write_b128 v192, v[184:187]
	s_waitcnt vmcnt(8)
	ds_write_b128 v159, v[188:191]
	ds_read_b128 v[184:187], v152 offset:36864
	ds_read_b128 v[188:191], v152 offset:41472
	ds_read_b128 v[208:211], v151
	ds_read_b128 v[212:215], v151 offset:4608
	s_setprio 1
	s_waitcnt lgkmcnt(1)
	v_mfma_f32_32x32x16_bf16 v[96:111], v[184:187], v[208:211], v[96:111]
	v_mfma_f32_32x32x16_bf16 v[112:127], v[188:191], v[208:211], v[112:127]
	s_waitcnt lgkmcnt(0)
	v_mfma_f32_32x32x16_bf16 v[64:79], v[184:187], v[212:215], v[64:79]
	v_mfma_f32_32x32x16_bf16 v[80:95], v[188:191], v[212:215], v[80:95]
	ds_read_b128 v[208:211], v151 offset:9216
	ds_read_b128 v[212:215], v151 offset:13824
	s_waitcnt vmcnt(7)
	ds_write_b128 v158, v[194:197]
	s_waitcnt vmcnt(6)
	ds_write_b128 v157, v[198:201]
	ds_read_b128 v[194:197], v152 offset:36896
	ds_read_b128 v[198:201], v152 offset:41504
	s_waitcnt lgkmcnt(5)
	v_mfma_f32_32x32x16_bf16 v[32:47], v[184:187], v[208:211], v[32:47]
	v_mfma_f32_32x32x16_bf16 v[48:63], v[188:191], v[208:211], v[48:63]
	ds_read_b128 v[208:211], v151 offset:32
	s_waitcnt lgkmcnt(5)
	v_mfma_f32_32x32x16_bf16 v[0:15], v[184:187], v[212:215], v[0:15]
	v_mfma_f32_32x32x16_bf16 v[16:31], v[188:191], v[212:215], v[16:31]
	ds_read_b128 v[212:215], v151 offset:4640
	s_setprio 0
	global_load_dwordx4 v[184:187], v[140:141], off offset:2304
	global_load_dwordx4 v[188:191], v[142:143], off offset:2304
	s_setprio 1
	s_waitcnt lgkmcnt(1)
	v_mfma_f32_32x32x16_bf16 v[96:111], v[194:197], v[208:211], v[96:111]
	v_mfma_f32_32x32x16_bf16 v[112:127], v[198:201], v[208:211], v[112:127]
	s_waitcnt lgkmcnt(0)
	v_mfma_f32_32x32x16_bf16 v[64:79], v[194:197], v[212:215], v[64:79]
	v_mfma_f32_32x32x16_bf16 v[80:95], v[198:201], v[212:215], v[80:95]
	ds_read_b128 v[208:211], v151 offset:9248
	ds_read_b128 v[212:215], v151 offset:13856
	s_waitcnt vmcnt(7)
	ds_write_b128 v154, v[176:179]
	s_waitcnt vmcnt(6)
	ds_write_b128 v153, v[180:183]
	ds_read_b128 v[176:179], v152 offset:36928
	ds_read_b128 v[180:183], v152 offset:41536
	s_waitcnt lgkmcnt(5)
	v_mfma_f32_32x32x16_bf16 v[32:47], v[194:197], v[208:211], v[32:47]
	v_mfma_f32_32x32x16_bf16 v[48:63], v[198:201], v[208:211], v[48:63]
	ds_read_b128 v[208:211], v151 offset:64
	s_waitcnt lgkmcnt(5)
	v_mfma_f32_32x32x16_bf16 v[0:15], v[194:197], v[212:215], v[0:15]
	v_mfma_f32_32x32x16_bf16 v[16:31], v[198:201], v[212:215], v[16:31]
	ds_read_b128 v[212:215], v151 offset:4672
	s_setprio 0
	global_load_dwordx4 v[194:197], v[132:133], off offset:2304
	global_load_dwordx4 v[198:201], v[134:135], off offset:2304
	s_setprio 1
	s_waitcnt lgkmcnt(1)
	v_mfma_f32_32x32x16_bf16 v[96:111], v[176:179], v[208:211], v[96:111]
	v_mfma_f32_32x32x16_bf16 v[112:127], v[180:183], v[208:211], v[112:127]
	s_waitcnt lgkmcnt(0)
	v_mfma_f32_32x32x16_bf16 v[64:79], v[176:179], v[212:215], v[64:79]
	v_mfma_f32_32x32x16_bf16 v[80:95], v[180:183], v[212:215], v[80:95]
	ds_read_b128 v[208:211], v151 offset:9280
	ds_read_b128 v[212:215], v151 offset:13888
	s_waitcnt vmcnt(7)
	ds_write_b128 v156, v[168:171]
	s_waitcnt vmcnt(6)
	ds_write_b128 v155, v[172:175]
	ds_read_b128 v[168:171], v152 offset:36960
	ds_read_b128 v[172:175], v152 offset:41568
	s_waitcnt lgkmcnt(5)
	v_mfma_f32_32x32x16_bf16 v[32:47], v[176:179], v[208:211], v[32:47]
	v_mfma_f32_32x32x16_bf16 v[48:63], v[180:183], v[208:211], v[48:63]
	ds_read_b128 v[208:211], v151 offset:96
	s_waitcnt lgkmcnt(5)
	v_mfma_f32_32x32x16_bf16 v[0:15], v[176:179], v[212:215], v[0:15]
	v_mfma_f32_32x32x16_bf16 v[16:31], v[180:183], v[212:215], v[16:31]
	ds_read_b128 v[212:215], v151 offset:4704
	s_setprio 0
	global_load_dwordx4 v[176:179], v[144:145], off offset:2304
	global_load_dwordx4 v[180:183], v[146:147], off offset:2304
	s_setprio 1
	s_waitcnt lgkmcnt(1)
	v_mfma_f32_32x32x16_bf16 v[96:111], v[168:171], v[208:211], v[96:111]
	v_mfma_f32_32x32x16_bf16 v[112:127], v[172:175], v[208:211], v[112:127]
	s_waitcnt lgkmcnt(0)
	v_mfma_f32_32x32x16_bf16 v[64:79], v[168:171], v[212:215], v[64:79]
	v_mfma_f32_32x32x16_bf16 v[80:95], v[172:175], v[212:215], v[80:95]
	ds_read_b128 v[208:211], v151 offset:9312
	ds_read_b128 v[212:215], v151 offset:13920
	s_waitcnt lgkmcnt(1)
	v_mfma_f32_32x32x16_bf16 v[32:47], v[168:171], v[208:211], v[32:47]
	v_mfma_f32_32x32x16_bf16 v[48:63], v[172:175], v[208:211], v[48:63]
	s_waitcnt lgkmcnt(0)
	v_mfma_f32_32x32x16_bf16 v[0:15], v[168:171], v[212:215], v[0:15]
	v_mfma_f32_32x32x16_bf16 v[16:31], v[172:175], v[212:215], v[16:31]
	s_setprio 0
	s_barrier
; template <bool trans>
; DI void gemm_core(const GTile& tl, const GTile& nx, bool has_next  , bool chain  , bool pre, u32x4 (&ra)[4], u32x4 (&rb)[4], char* smem, f32x16 (&acc)[2][4]) {
;     ...
;   const int nk = K / 64;
;   if (!pre) { G_LOAD(0); G_STORE(0); G_LOAD(1); }
;   for (int kt = 0; kt < nk; ++kt) {
;     __syncthreads();
;     G_COMPUTE(kt & 1, kt);
;   }
	global_load_dwordx4 v[168:171], v[136:137], off offset:2432
	global_load_dwordx4 v[172:175], v[138:139], off offset:2432
	s_waitcnt vmcnt(9)
	ds_write_b128 v148, v[160:163]
	s_waitcnt vmcnt(8)
	ds_write_b128 v148, v[164:167] offset:36864
	ds_read_b128 v[160:163], v150
	ds_read_b128 v[164:167], v150 offset:4608
	ds_read_b128 v[208:211], v149
	ds_read_b128 v[212:215], v149 offset:4608
	s_setprio 1
	s_waitcnt lgkmcnt(1)
	v_mfma_f32_32x32x16_bf16 v[96:111], v[160:163], v[208:211], v[96:111]
	v_mfma_f32_32x32x16_bf16 v[112:127], v[164:167], v[208:211], v[112:127]
	s_waitcnt lgkmcnt(0)
	v_mfma_f32_32x32x16_bf16 v[64:79], v[160:163], v[212:215], v[64:79]
	v_mfma_f32_32x32x16_bf16 v[80:95], v[164:167], v[212:215], v[80:95]
	ds_read_b128 v[208:211], v149 offset:9216
	ds_read_b128 v[212:215], v149 offset:13824
	s_waitcnt vmcnt(7)
	ds_write_b128 v148, v[184:187] offset:9216
	s_waitcnt vmcnt(6)
	ds_write_b128 v148, v[188:191] offset:46080
	ds_read_b128 v[184:187], v150 offset:32
	ds_read_b128 v[188:191], v150 offset:4640
	s_waitcnt lgkmcnt(5)
	v_mfma_f32_32x32x16_bf16 v[32:47], v[160:163], v[208:211], v[32:47]
	v_mfma_f32_32x32x16_bf16 v[48:63], v[164:167], v[208:211], v[48:63]
	ds_read_b128 v[208:211], v149 offset:32
	s_waitcnt lgkmcnt(5)
	v_mfma_f32_32x32x16_bf16 v[0:15], v[160:163], v[212:215], v[0:15]
	v_mfma_f32_32x32x16_bf16 v[16:31], v[164:167], v[212:215], v[16:31]
	ds_read_b128 v[212:215], v149 offset:4640
	s_setprio 0
	global_load_dwordx4 v[160:163], v[140:141], off offset:2432
	global_load_dwordx4 v[164:167], v[142:143], off offset:2432
	s_setprio 1
	s_waitcnt lgkmcnt(1)
	v_mfma_f32_32x32x16_bf16 v[96:111], v[184:187], v[208:211], v[96:111]
	v_mfma_f32_32x32x16_bf16 v[112:127], v[188:191], v[208:211], v[112:127]
	s_waitcnt lgkmcnt(0)
	v_mfma_f32_32x32x16_bf16 v[64:79], v[184:187], v[212:215], v[64:79]
	v_mfma_f32_32x32x16_bf16 v[80:95], v[188:191], v[212:215], v[80:95]
	ds_read_b128 v[208:211], v149 offset:9248
	ds_read_b128 v[212:215], v149 offset:13856
	s_waitcnt vmcnt(7)
	ds_write_b128 v148, v[194:197] offset:18432
	s_waitcnt vmcnt(6)
	ds_write_b128 v148, v[198:201] offset:55296
	ds_read_b128 v[194:197], v150 offset:64
	ds_read_b128 v[198:201], v150 offset:4672
	s_waitcnt lgkmcnt(5)
	v_mfma_f32_32x32x16_bf16 v[32:47], v[184:187], v[208:211], v[32:47]
	v_mfma_f32_32x32x16_bf16 v[48:63], v[188:191], v[208:211], v[48:63]
	ds_read_b128 v[208:211], v149 offset:64
	s_waitcnt lgkmcnt(5)
	v_mfma_f32_32x32x16_bf16 v[0:15], v[184:187], v[212:215], v[0:15]
	v_mfma_f32_32x32x16_bf16 v[16:31], v[188:191], v[212:215], v[16:31]
	ds_read_b128 v[212:215], v149 offset:4672
	s_setprio 0
	global_load_dwordx4 v[184:187], v[132:133], off offset:2432
	global_load_dwordx4 v[188:191], v[134:135], off offset:2432
	s_setprio 1
	s_waitcnt lgkmcnt(1)
	v_mfma_f32_32x32x16_bf16 v[96:111], v[194:197], v[208:211], v[96:111]
	v_mfma_f32_32x32x16_bf16 v[112:127], v[198:201], v[208:211], v[112:127]
	s_waitcnt lgkmcnt(0)
	v_mfma_f32_32x32x16_bf16 v[64:79], v[194:197], v[212:215], v[64:79]
	v_mfma_f32_32x32x16_bf16 v[80:95], v[198:201], v[212:215], v[80:95]
	ds_read_b128 v[208:211], v149 offset:9280
	ds_read_b128 v[212:215], v149 offset:13888
	s_waitcnt vmcnt(7)
	ds_write_b128 v148, v[176:179] offset:27648
	s_waitcnt vmcnt(6)
	ds_write_b128 v148, v[180:183] offset:64512
	ds_read_b128 v[176:179], v150 offset:96
	ds_read_b128 v[180:183], v150 offset:4704
	s_waitcnt lgkmcnt(5)
	v_mfma_f32_32x32x16_bf16 v[32:47], v[194:197], v[208:211], v[32:47]
	v_mfma_f32_32x32x16_bf16 v[48:63], v[198:201], v[208:211], v[48:63]
	ds_read_b128 v[208:211], v149 offset:96
	s_waitcnt lgkmcnt(5)
	v_mfma_f32_32x32x16_bf16 v[0:15], v[194:197], v[212:215], v[0:15]
	v_mfma_f32_32x32x16_bf16 v[16:31], v[198:201], v[212:215], v[16:31]
	ds_read_b128 v[212:215], v149 offset:4704
	s_setprio 0
	global_load_dwordx4 v[194:197], v[144:145], off offset:2432
	global_load_dwordx4 v[198:201], v[146:147], off offset:2432
	s_setprio 1
	s_waitcnt lgkmcnt(1)
	v_mfma_f32_32x32x16_bf16 v[96:111], v[176:179], v[208:211], v[96:111]
	v_mfma_f32_32x32x16_bf16 v[112:127], v[180:183], v[208:211], v[112:127]
	s_waitcnt lgkmcnt(0)
	v_mfma_f32_32x32x16_bf16 v[64:79], v[176:179], v[212:215], v[64:79]
	v_mfma_f32_32x32x16_bf16 v[80:95], v[180:183], v[212:215], v[80:95]
	ds_read_b128 v[208:211], v149 offset:9312
	ds_read_b128 v[212:215], v149 offset:13920
	s_waitcnt lgkmcnt(1)
	v_mfma_f32_32x32x16_bf16 v[32:47], v[176:179], v[208:211], v[32:47]
	v_mfma_f32_32x32x16_bf16 v[48:63], v[180:183], v[208:211], v[48:63]
	s_waitcnt lgkmcnt(0)
	v_mfma_f32_32x32x16_bf16 v[0:15], v[176:179], v[212:215], v[0:15]
	v_mfma_f32_32x32x16_bf16 v[16:31], v[180:183], v[212:215], v[16:31]
	s_setprio 0
	s_barrier
; template <bool trans>
; DI void gemm_core(const GTile& tl, const GTile& nx, bool has_next  , bool chain  , bool pre, u32x4 (&ra)[4], u32x4 (&rb)[4], char* smem, f32x16 (&acc)[2][4]) {
;     ...
;   const int nk = K / 64;
;   if (!pre) { G_LOAD(0); G_STORE(0); G_LOAD(1); }
;   for (int kt = 0; kt < nk; ++kt) {
;     __syncthreads();
;     G_COMPUTE(kt & 1, kt);
;   }
	global_load_dwordx4 v[176:179], v[136:137], off offset:2560
	global_load_dwordx4 v[180:183], v[138:139], off offset:2560
	s_waitcnt vmcnt(9)
	ds_write_b128 v192, v[168:171]
	s_waitcnt vmcnt(8)
	ds_write_b128 v159, v[172:175]
	ds_read_b128 v[168:171], v152 offset:36864
	ds_read_b128 v[172:175], v152 offset:41472
	ds_read_b128 v[208:211], v151
	ds_read_b128 v[212:215], v151 offset:4608
	s_setprio 1
	s_waitcnt lgkmcnt(1)
	v_mfma_f32_32x32x16_bf16 v[96:111], v[168:171], v[208:211], v[96:111]
	v_mfma_f32_32x32x16_bf16 v[112:127], v[172:175], v[208:211], v[112:127]
	s_waitcnt lgkmcnt(0)
	v_mfma_f32_32x32x16_bf16 v[64:79], v[168:171], v[212:215], v[64:79]
	v_mfma_f32_32x32x16_bf16 v[80:95], v[172:175], v[212:215], v[80:95]
	ds_read_b128 v[208:211], v151 offset:9216
	ds_read_b128 v[212:215], v151 offset:13824
	s_waitcnt vmcnt(7)
	ds_write_b128 v158, v[160:163]
	s_waitcnt vmcnt(6)
	ds_write_b128 v157, v[164:167]
	ds_read_b128 v[160:163], v152 offset:36896
	ds_read_b128 v[164:167], v152 offset:41504
	s_waitcnt lgkmcnt(5)
	v_mfma_f32_32x32x16_bf16 v[32:47], v[168:171], v[208:211], v[32:47]
	v_mfma_f32_32x32x16_bf16 v[48:63], v[172:175], v[208:211], v[48:63]
	ds_read_b128 v[208:211], v151 offset:32
	s_waitcnt lgkmcnt(5)
	v_mfma_f32_32x32x16_bf16 v[0:15], v[168:171], v[212:215], v[0:15]
	v_mfma_f32_32x32x16_bf16 v[16:31], v[172:175], v[212:215], v[16:31]
	ds_read_b128 v[212:215], v151 offset:4640
	s_setprio 0
	global_load_dwordx4 v[168:171], v[140:141], off offset:2560
	global_load_dwordx4 v[172:175], v[142:143], off offset:2560
	s_setprio 1
	s_waitcnt lgkmcnt(1)
	v_mfma_f32_32x32x16_bf16 v[96:111], v[160:163], v[208:211], v[96:111]
	v_mfma_f32_32x32x16_bf16 v[112:127], v[164:167], v[208:211], v[112:127]
	s_waitcnt lgkmcnt(0)
	v_mfma_f32_32x32x16_bf16 v[64:79], v[160:163], v[212:215], v[64:79]
	v_mfma_f32_32x32x16_bf16 v[80:95], v[164:167], v[212:215], v[80:95]
	ds_read_b128 v[208:211], v151 offset:9248
	ds_read_b128 v[212:215], v151 offset:13856
	s_waitcnt vmcnt(7)
	ds_write_b128 v154, v[184:187]
	s_waitcnt vmcnt(6)
	ds_write_b128 v153, v[188:191]
	ds_read_b128 v[184:187], v152 offset:36928
	ds_read_b128 v[188:191], v152 offset:41536
	s_waitcnt lgkmcnt(5)
	v_mfma_f32_32x32x16_bf16 v[32:47], v[160:163], v[208:211], v[32:47]
	v_mfma_f32_32x32x16_bf16 v[48:63], v[164:167], v[208:211], v[48:63]
	ds_read_b128 v[208:211], v151 offset:64
	s_waitcnt lgkmcnt(5)
	v_mfma_f32_32x32x16_bf16 v[0:15], v[160:163], v[212:215], v[0:15]
	v_mfma_f32_32x32x16_bf16 v[16:31], v[164:167], v[212:215], v[16:31]
	ds_read_b128 v[212:215], v151 offset:4672
	s_setprio 0
	global_load_dwordx4 v[160:163], v[132:133], off offset:2560
	global_load_dwordx4 v[164:167], v[134:135], off offset:2560
	s_setprio 1
	s_waitcnt lgkmcnt(1)
	v_mfma_f32_32x32x16_bf16 v[96:111], v[184:187], v[208:211], v[96:111]
	v_mfma_f32_32x32x16_bf16 v[112:127], v[188:191], v[208:211], v[112:127]
	s_waitcnt lgkmcnt(0)
	v_mfma_f32_32x32x16_bf16 v[64:79], v[184:187], v[212:215], v[64:79]
	v_mfma_f32_32x32x16_bf16 v[80:95], v[188:191], v[212:215], v[80:95]
	ds_read_b128 v[208:211], v151 offset:9280
	ds_read_b128 v[212:215], v151 offset:13888
	s_waitcnt vmcnt(7)
	ds_write_b128 v156, v[194:197]
	s_waitcnt vmcnt(6)
	ds_write_b128 v155, v[198:201]
	ds_read_b128 v[194:197], v152 offset:36960
	ds_read_b128 v[198:201], v152 offset:41568
	s_waitcnt lgkmcnt(5)
	v_mfma_f32_32x32x16_bf16 v[32:47], v[184:187], v[208:211], v[32:47]
	v_mfma_f32_32x32x16_bf16 v[48:63], v[188:191], v[208:211], v[48:63]
	ds_read_b128 v[208:211], v151 offset:96
	s_waitcnt lgkmcnt(5)
	v_mfma_f32_32x32x16_bf16 v[0:15], v[184:187], v[212:215], v[0:15]
	v_mfma_f32_32x32x16_bf16 v[16:31], v[188:191], v[212:215], v[16:31]
	ds_read_b128 v[212:215], v151 offset:4704
	s_setprio 0
	global_load_dwordx4 v[184:187], v[144:145], off offset:2560
	global_load_dwordx4 v[188:191], v[146:147], off offset:2560
	s_setprio 1
	s_waitcnt lgkmcnt(1)
	v_mfma_f32_32x32x16_bf16 v[96:111], v[194:197], v[208:211], v[96:111]
	v_mfma_f32_32x32x16_bf16 v[112:127], v[198:201], v[208:211], v[112:127]
	s_waitcnt lgkmcnt(0)
	v_mfma_f32_32x32x16_bf16 v[64:79], v[194:197], v[212:215], v[64:79]
	v_mfma_f32_32x32x16_bf16 v[80:95], v[198:201], v[212:215], v[80:95]
	ds_read_b128 v[208:211], v151 offset:9312
	ds_read_b128 v[212:215], v151 offset:13920
	s_waitcnt lgkmcnt(1)
	v_mfma_f32_32x32x16_bf16 v[32:47], v[194:197], v[208:211], v[32:47]
	v_mfma_f32_32x32x16_bf16 v[48:63], v[198:201], v[208:211], v[48:63]
	s_waitcnt lgkmcnt(0)
	v_mfma_f32_32x32x16_bf16 v[0:15], v[194:197], v[212:215], v[0:15]
	v_mfma_f32_32x32x16_bf16 v[16:31], v[198:201], v[212:215], v[16:31]
	s_setprio 0
	s_barrier
; template <bool trans>
; DI void gemm_core(const GTile& tl, const GTile& nx, bool has_next  , bool chain  , bool pre, u32x4 (&ra)[4], u32x4 (&rb)[4], char* smem, f32x16 (&acc)[2][4]) {
;     ...
;   const int nk = K / 64;
;   if (!pre) { G_LOAD(0); G_STORE(0); G_LOAD(1); }
;   for (int kt = 0; kt < nk; ++kt) {
;     __syncthreads();
;     G_COMPUTE(kt & 1, kt);
;   }
	global_load_dwordx4 v[194:197], v[136:137], off offset:2688
	global_load_dwordx4 v[198:201], v[138:139], off offset:2688
	s_waitcnt vmcnt(9)
	ds_write_b128 v148, v[176:179]
	s_waitcnt vmcnt(8)
	ds_write_b128 v148, v[180:183] offset:36864
	ds_read_b128 v[176:179], v150
	ds_read_b128 v[180:183], v150 offset:4608
	ds_read_b128 v[208:211], v149
	ds_read_b128 v[212:215], v149 offset:4608
	s_setprio 1
	s_waitcnt lgkmcnt(1)
	v_mfma_f32_32x32x16_bf16 v[96:111], v[176:179], v[208:211], v[96:111]
	v_mfma_f32_32x32x16_bf16 v[112:127], v[180:183], v[208:211], v[112:127]
	s_waitcnt lgkmcnt(0)
	v_mfma_f32_32x32x16_bf16 v[64:79], v[176:179], v[212:215], v[64:79]
	v_mfma_f32_32x32x16_bf16 v[80:95], v[180:183], v[212:215], v[80:95]
	ds_read_b128 v[208:211], v149 offset:9216
	ds_read_b128 v[212:215], v149 offset:13824
	s_waitcnt vmcnt(7)
	ds_write_b128 v148, v[168:171] offset:9216
	s_waitcnt vmcnt(6)
	ds_write_b128 v148, v[172:175] offset:46080
	ds_read_b128 v[168:171], v150 offset:32
	ds_read_b128 v[172:175], v150 offset:4640
	s_waitcnt lgkmcnt(5)
	v_mfma_f32_32x32x16_bf16 v[32:47], v[176:179], v[208:211], v[32:47]
	v_mfma_f32_32x32x16_bf16 v[48:63], v[180:183], v[208:211], v[48:63]
	ds_read_b128 v[208:211], v149 offset:32
	s_waitcnt lgkmcnt(5)
	v_mfma_f32_32x32x16_bf16 v[0:15], v[176:179], v[212:215], v[0:15]
	v_mfma_f32_32x32x16_bf16 v[16:31], v[180:183], v[212:215], v[16:31]
	ds_read_b128 v[212:215], v149 offset:4640
	s_setprio 0
	global_load_dwordx4 v[176:179], v[140:141], off offset:2688
	global_load_dwordx4 v[180:183], v[142:143], off offset:2688
	s_setprio 1
	s_waitcnt lgkmcnt(1)
	v_mfma_f32_32x32x16_bf16 v[96:111], v[168:171], v[208:211], v[96:111]
	v_mfma_f32_32x32x16_bf16 v[112:127], v[172:175], v[208:211], v[112:127]
	s_waitcnt lgkmcnt(0)
	v_mfma_f32_32x32x16_bf16 v[64:79], v[168:171], v[212:215], v[64:79]
	v_mfma_f32_32x32x16_bf16 v[80:95], v[172:175], v[212:215], v[80:95]
	ds_read_b128 v[208:211], v149 offset:9248
	ds_read_b128 v[212:215], v149 offset:13856
	s_waitcnt vmcnt(7)
	ds_write_b128 v148, v[160:163] offset:18432
	s_waitcnt vmcnt(6)
	ds_write_b128 v148, v[164:167] offset:55296
	ds_read_b128 v[160:163], v150 offset:64
	ds_read_b128 v[164:167], v150 offset:4672
	s_waitcnt lgkmcnt(5)
	v_mfma_f32_32x32x16_bf16 v[32:47], v[168:171], v[208:211], v[32:47]
	v_mfma_f32_32x32x16_bf16 v[48:63], v[172:175], v[208:211], v[48:63]
	ds_read_b128 v[208:211], v149 offset:64
	s_waitcnt lgkmcnt(5)
	v_mfma_f32_32x32x16_bf16 v[0:15], v[168:171], v[212:215], v[0:15]
	v_mfma_f32_32x32x16_bf16 v[16:31], v[172:175], v[212:215], v[16:31]
	ds_read_b128 v[212:215], v149 offset:4672
	s_setprio 0
	global_load_dwordx4 v[168:171], v[132:133], off offset:2688
	global_load_dwordx4 v[172:175], v[134:135], off offset:2688
	s_setprio 1
	s_waitcnt lgkmcnt(1)
	v_mfma_f32_32x32x16_bf16 v[96:111], v[160:163], v[208:211], v[96:111]
	v_mfma_f32_32x32x16_bf16 v[112:127], v[164:167], v[208:211], v[112:127]
	s_waitcnt lgkmcnt(0)
	v_mfma_f32_32x32x16_bf16 v[64:79], v[160:163], v[212:215], v[64:79]
	v_mfma_f32_32x32x16_bf16 v[80:95], v[164:167], v[212:215], v[80:95]
	ds_read_b128 v[208:211], v149 offset:9280
	ds_read_b128 v[212:215], v149 offset:13888
	s_waitcnt vmcnt(7)
	ds_write_b128 v148, v[184:187] offset:27648
	s_waitcnt vmcnt(6)
	ds_write_b128 v148, v[188:191] offset:64512
	ds_read_b128 v[184:187], v150 offset:96
	ds_read_b128 v[188:191], v150 offset:4704
	s_waitcnt lgkmcnt(5)
	v_mfma_f32_32x32x16_bf16 v[32:47], v[160:163], v[208:211], v[32:47]
	v_mfma_f32_32x32x16_bf16 v[48:63], v[164:167], v[208:211], v[48:63]
	ds_read_b128 v[208:211], v149 offset:96
	s_waitcnt lgkmcnt(5)
	v_mfma_f32_32x32x16_bf16 v[0:15], v[160:163], v[212:215], v[0:15]
	v_mfma_f32_32x32x16_bf16 v[16:31], v[164:167], v[212:215], v[16:31]
	ds_read_b128 v[212:215], v149 offset:4704
	s_setprio 0
	global_load_dwordx4 v[160:163], v[144:145], off offset:2688
	global_load_dwordx4 v[164:167], v[146:147], off offset:2688
	s_setprio 1
	s_waitcnt lgkmcnt(1)
	v_mfma_f32_32x32x16_bf16 v[96:111], v[184:187], v[208:211], v[96:111]
	v_mfma_f32_32x32x16_bf16 v[112:127], v[188:191], v[208:211], v[112:127]
	s_waitcnt lgkmcnt(0)
	v_mfma_f32_32x32x16_bf16 v[64:79], v[184:187], v[212:215], v[64:79]
	v_mfma_f32_32x32x16_bf16 v[80:95], v[188:191], v[212:215], v[80:95]
	ds_read_b128 v[208:211], v149 offset:9312
	ds_read_b128 v[212:215], v149 offset:13920
	s_waitcnt lgkmcnt(1)
	v_mfma_f32_32x32x16_bf16 v[32:47], v[184:187], v[208:211], v[32:47]
	v_mfma_f32_32x32x16_bf16 v[48:63], v[188:191], v[208:211], v[48:63]
	s_waitcnt lgkmcnt(0)
	v_mfma_f32_32x32x16_bf16 v[0:15], v[184:187], v[212:215], v[0:15]
	v_mfma_f32_32x32x16_bf16 v[16:31], v[188:191], v[212:215], v[16:31]
	s_setprio 0
	s_barrier
; template <bool trans>
; DI void gemm_core(const GTile& tl, const GTile& nx, bool has_next  , bool chain  , bool pre, u32x4 (&ra)[4], u32x4 (&rb)[4], char* smem, f32x16 (&acc)[2][4]) {
;     ...
;   const int nk = K / 64;
;   if (!pre) { G_LOAD(0); G_STORE(0); G_LOAD(1); }
;   for (int kt = 0; kt < nk; ++kt) {
;     __syncthreads();
;     G_COMPUTE(kt & 1, kt);
;   }
	global_load_dwordx4 v[184:187], v[136:137], off offset:2816
	global_load_dwordx4 v[188:191], v[138:139], off offset:2816
	s_waitcnt vmcnt(9)
	ds_write_b128 v192, v[194:197]
	s_waitcnt vmcnt(8)
	ds_write_b128 v159, v[198:201]
	ds_read_b128 v[194:197], v152 offset:36864
	ds_read_b128 v[198:201], v152 offset:41472
	ds_read_b128 v[208:211], v151
	ds_read_b128 v[212:215], v151 offset:4608
	s_setprio 1
	s_waitcnt lgkmcnt(1)
	v_mfma_f32_32x32x16_bf16 v[96:111], v[194:197], v[208:211], v[96:111]
	v_mfma_f32_32x32x16_bf16 v[112:127], v[198:201], v[208:211], v[112:127]
	s_waitcnt lgkmcnt(0)
	v_mfma_f32_32x32x16_bf16 v[64:79], v[194:197], v[212:215], v[64:79]
	v_mfma_f32_32x32x16_bf16 v[80:95], v[198:201], v[212:215], v[80:95]
	ds_read_b128 v[208:211], v151 offset:9216
	ds_read_b128 v[212:215], v151 offset:13824
	s_waitcnt vmcnt(7)
	ds_write_b128 v158, v[176:179]
	s_waitcnt vmcnt(6)
	ds_write_b128 v157, v[180:183]
	ds_read_b128 v[176:179], v152 offset:36896
	ds_read_b128 v[180:183], v152 offset:41504
	s_waitcnt lgkmcnt(5)
	v_mfma_f32_32x32x16_bf16 v[32:47], v[194:197], v[208:211], v[32:47]
	v_mfma_f32_32x32x16_bf16 v[48:63], v[198:201], v[208:211], v[48:63]
	ds_read_b128 v[208:211], v151 offset:32
	s_waitcnt lgkmcnt(5)
	v_mfma_f32_32x32x16_bf16 v[0:15], v[194:197], v[212:215], v[0:15]
	v_mfma_f32_32x32x16_bf16 v[16:31], v[198:201], v[212:215], v[16:31]
	ds_read_b128 v[212:215], v151 offset:4640
	s_setprio 0
	global_load_dwordx4 v[194:197], v[140:141], off offset:2816
	global_load_dwordx4 v[198:201], v[142:143], off offset:2816
	s_setprio 1
	s_waitcnt lgkmcnt(1)
	v_mfma_f32_32x32x16_bf16 v[96:111], v[176:179], v[208:211], v[96:111]
	v_mfma_f32_32x32x16_bf16 v[112:127], v[180:183], v[208:211], v[112:127]
	s_waitcnt lgkmcnt(0)
	v_mfma_f32_32x32x16_bf16 v[64:79], v[176:179], v[212:215], v[64:79]
	v_mfma_f32_32x32x16_bf16 v[80:95], v[180:183], v[212:215], v[80:95]
	ds_read_b128 v[208:211], v151 offset:9248
	ds_read_b128 v[212:215], v151 offset:13856
	s_waitcnt vmcnt(7)
	ds_write_b128 v154, v[168:171]
	s_waitcnt vmcnt(6)
	ds_write_b128 v153, v[172:175]
	ds_read_b128 v[168:171], v152 offset:36928
	ds_read_b128 v[172:175], v152 offset:41536
	s_waitcnt lgkmcnt(5)
	v_mfma_f32_32x32x16_bf16 v[32:47], v[176:179], v[208:211], v[32:47]
	v_mfma_f32_32x32x16_bf16 v[48:63], v[180:183], v[208:211], v[48:63]
	ds_read_b128 v[208:211], v151 offset:64
	s_waitcnt lgkmcnt(5)
	v_mfma_f32_32x32x16_bf16 v[0:15], v[176:179], v[212:215], v[0:15]
	v_mfma_f32_32x32x16_bf16 v[16:31], v[180:183], v[212:215], v[16:31]
	ds_read_b128 v[212:215], v151 offset:4672
	s_setprio 0
	global_load_dwordx4 v[176:179], v[132:133], off offset:2816
	global_load_dwordx4 v[180:183], v[134:135], off offset:2816
	s_setprio 1
	s_waitcnt lgkmcnt(1)
	v_mfma_f32_32x32x16_bf16 v[96:111], v[168:171], v[208:211], v[96:111]
	v_mfma_f32_32x32x16_bf16 v[112:127], v[172:175], v[208:211], v[112:127]
	s_waitcnt lgkmcnt(0)
	v_mfma_f32_32x32x16_bf16 v[64:79], v[168:171], v[212:215], v[64:79]
	v_mfma_f32_32x32x16_bf16 v[80:95], v[172:175], v[212:215], v[80:95]
	ds_read_b128 v[208:211], v151 offset:9280
	ds_read_b128 v[212:215], v151 offset:13888
	s_waitcnt vmcnt(7)
	ds_write_b128 v156, v[160:163]
	s_waitcnt vmcnt(6)
	ds_write_b128 v155, v[164:167]
	ds_read_b128 v[160:163], v152 offset:36960
	ds_read_b128 v[164:167], v152 offset:41568
	s_waitcnt lgkmcnt(5)
	v_mfma_f32_32x32x16_bf16 v[32:47], v[168:171], v[208:211], v[32:47]
	v_mfma_f32_32x32x16_bf16 v[48:63], v[172:175], v[208:211], v[48:63]
	ds_read_b128 v[208:211], v151 offset:96
	s_waitcnt lgkmcnt(5)
	v_mfma_f32_32x32x16_bf16 v[0:15], v[168:171], v[212:215], v[0:15]
	v_mfma_f32_32x32x16_bf16 v[16:31], v[172:175], v[212:215], v[16:31]
	ds_read_b128 v[212:215], v151 offset:4704
	s_setprio 0
	global_load_dwordx4 v[168:171], v[144:145], off offset:2816
	global_load_dwordx4 v[172:175], v[146:147], off offset:2816
	s_setprio 1
	s_waitcnt lgkmcnt(1)
	v_mfma_f32_32x32x16_bf16 v[96:111], v[160:163], v[208:211], v[96:111]
	v_mfma_f32_32x32x16_bf16 v[112:127], v[164:167], v[208:211], v[112:127]
	s_waitcnt lgkmcnt(0)
	v_mfma_f32_32x32x16_bf16 v[64:79], v[160:163], v[212:215], v[64:79]
	v_mfma_f32_32x32x16_bf16 v[80:95], v[164:167], v[212:215], v[80:95]
	ds_read_b128 v[208:211], v151 offset:9312
	ds_read_b128 v[212:215], v151 offset:13920
	s_waitcnt lgkmcnt(1)
	v_mfma_f32_32x32x16_bf16 v[32:47], v[160:163], v[208:211], v[32:47]
	v_mfma_f32_32x32x16_bf16 v[48:63], v[164:167], v[208:211], v[48:63]
	s_waitcnt lgkmcnt(0)
	v_mfma_f32_32x32x16_bf16 v[0:15], v[160:163], v[212:215], v[0:15]
	v_mfma_f32_32x32x16_bf16 v[16:31], v[164:167], v[212:215], v[16:31]
	s_setprio 0
	s_barrier
; template <bool trans>
; DI void gemm_core(const GTile& tl, const GTile& nx, bool has_next  , bool chain  , bool pre, u32x4 (&ra)[4], u32x4 (&rb)[4], char* smem, f32x16 (&acc)[2][4]) {
;     ...
;   const int nk = K / 64;
;   if (!pre) { G_LOAD(0); G_STORE(0); G_LOAD(1); }
;   for (int kt = 0; kt < nk; ++kt) {
;     __syncthreads();
;     G_COMPUTE(kt & 1, kt);
;   }
	global_load_dwordx4 v[160:163], v[136:137], off offset:2944
	global_load_dwordx4 v[164:167], v[138:139], off offset:2944
	s_waitcnt vmcnt(9)
	ds_write_b128 v148, v[184:187]
	s_waitcnt vmcnt(8)
	ds_write_b128 v148, v[188:191] offset:36864
	ds_read_b128 v[184:187], v150
	ds_read_b128 v[188:191], v150 offset:4608
	ds_read_b128 v[208:211], v149
	ds_read_b128 v[212:215], v149 offset:4608
	s_setprio 1
	s_waitcnt lgkmcnt(1)
	v_mfma_f32_32x32x16_bf16 v[96:111], v[184:187], v[208:211], v[96:111]
	v_mfma_f32_32x32x16_bf16 v[112:127], v[188:191], v[208:211], v[112:127]
	s_waitcnt lgkmcnt(0)
	v_mfma_f32_32x32x16_bf16 v[64:79], v[184:187], v[212:215], v[64:79]
	v_mfma_f32_32x32x16_bf16 v[80:95], v[188:191], v[212:215], v[80:95]
	ds_read_b128 v[208:211], v149 offset:9216
	ds_read_b128 v[212:215], v149 offset:13824
	s_waitcnt vmcnt(7)
	ds_write_b128 v148, v[194:197] offset:9216
	s_waitcnt vmcnt(6)
	ds_write_b128 v148, v[198:201] offset:46080
	ds_read_b128 v[194:197], v150 offset:32
	ds_read_b128 v[198:201], v150 offset:4640
	s_waitcnt lgkmcnt(5)
	v_mfma_f32_32x32x16_bf16 v[32:47], v[184:187], v[208:211], v[32:47]
	v_mfma_f32_32x32x16_bf16 v[48:63], v[188:191], v[208:211], v[48:63]
	ds_read_b128 v[208:211], v149 offset:32
	s_waitcnt lgkmcnt(5)
	v_mfma_f32_32x32x16_bf16 v[0:15], v[184:187], v[212:215], v[0:15]
	v_mfma_f32_32x32x16_bf16 v[16:31], v[188:191], v[212:215], v[16:31]
	ds_read_b128 v[212:215], v149 offset:4640
	s_setprio 0
	global_load_dwordx4 v[184:187], v[140:141], off offset:2944
	global_load_dwordx4 v[188:191], v[142:143], off offset:2944
	s_setprio 1
	s_waitcnt lgkmcnt(1)
	v_mfma_f32_32x32x16_bf16 v[96:111], v[194:197], v[208:211], v[96:111]
	v_mfma_f32_32x32x16_bf16 v[112:127], v[198:201], v[208:211], v[112:127]
	s_waitcnt lgkmcnt(0)
	v_mfma_f32_32x32x16_bf16 v[64:79], v[194:197], v[212:215], v[64:79]
	v_mfma_f32_32x32x16_bf16 v[80:95], v[198:201], v[212:215], v[80:95]
	ds_read_b128 v[208:211], v149 offset:9248
	ds_read_b128 v[212:215], v149 offset:13856
	s_waitcnt vmcnt(7)
	ds_write_b128 v148, v[176:179] offset:18432
	s_waitcnt vmcnt(6)
	ds_write_b128 v148, v[180:183] offset:55296
	ds_read_b128 v[176:179], v150 offset:64
	ds_read_b128 v[180:183], v150 offset:4672
	s_waitcnt lgkmcnt(5)
	v_mfma_f32_32x32x16_bf16 v[32:47], v[194:197], v[208:211], v[32:47]
	v_mfma_f32_32x32x16_bf16 v[48:63], v[198:201], v[208:211], v[48:63]
	ds_read_b128 v[208:211], v149 offset:64
	s_waitcnt lgkmcnt(5)
	v_mfma_f32_32x32x16_bf16 v[0:15], v[194:197], v[212:215], v[0:15]
	v_mfma_f32_32x32x16_bf16 v[16:31], v[198:201], v[212:215], v[16:31]
	ds_read_b128 v[212:215], v149 offset:4672
	s_setprio 0
	global_load_dwordx4 v[194:197], v[132:133], off offset:2944
	global_load_dwordx4 v[198:201], v[134:135], off offset:2944
	s_setprio 1
	s_waitcnt lgkmcnt(1)
	v_mfma_f32_32x32x16_bf16 v[96:111], v[176:179], v[208:211], v[96:111]
	v_mfma_f32_32x32x16_bf16 v[112:127], v[180:183], v[208:211], v[112:127]
	s_waitcnt lgkmcnt(0)
	v_mfma_f32_32x32x16_bf16 v[64:79], v[176:179], v[212:215], v[64:79]
	v_mfma_f32_32x32x16_bf16 v[80:95], v[180:183], v[212:215], v[80:95]
	ds_read_b128 v[208:211], v149 offset:9280
	ds_read_b128 v[212:215], v149 offset:13888
	s_waitcnt vmcnt(7)
	ds_write_b128 v148, v[168:171] offset:27648
	s_waitcnt vmcnt(6)
	ds_write_b128 v148, v[172:175] offset:64512
	ds_read_b128 v[168:171], v150 offset:96
	ds_read_b128 v[172:175], v150 offset:4704
	s_waitcnt lgkmcnt(5)
	v_mfma_f32_32x32x16_bf16 v[32:47], v[176:179], v[208:211], v[32:47]
	v_mfma_f32_32x32x16_bf16 v[48:63], v[180:183], v[208:211], v[48:63]
	ds_read_b128 v[208:211], v149 offset:96
	s_waitcnt lgkmcnt(5)
	v_mfma_f32_32x32x16_bf16 v[0:15], v[176:179], v[212:215], v[0:15]
	v_mfma_f32_32x32x16_bf16 v[16:31], v[180:183], v[212:215], v[16:31]
	ds_read_b128 v[212:215], v149 offset:4704
	s_setprio 0
	global_load_dwordx4 v[176:179], v[144:145], off offset:2944
	global_load_dwordx4 v[180:183], v[146:147], off offset:2944
	s_setprio 1
	s_waitcnt lgkmcnt(1)
	v_mfma_f32_32x32x16_bf16 v[96:111], v[168:171], v[208:211], v[96:111]
	v_mfma_f32_32x32x16_bf16 v[112:127], v[172:175], v[208:211], v[112:127]
	s_waitcnt lgkmcnt(0)
	v_mfma_f32_32x32x16_bf16 v[64:79], v[168:171], v[212:215], v[64:79]
	v_mfma_f32_32x32x16_bf16 v[80:95], v[172:175], v[212:215], v[80:95]
	ds_read_b128 v[208:211], v149 offset:9312
	ds_read_b128 v[212:215], v149 offset:13920
	s_waitcnt lgkmcnt(1)
	v_mfma_f32_32x32x16_bf16 v[32:47], v[168:171], v[208:211], v[32:47]
	v_mfma_f32_32x32x16_bf16 v[48:63], v[172:175], v[208:211], v[48:63]
	s_waitcnt lgkmcnt(0)
	v_mfma_f32_32x32x16_bf16 v[0:15], v[168:171], v[212:215], v[0:15]
	v_mfma_f32_32x32x16_bf16 v[16:31], v[172:175], v[212:215], v[16:31]
	s_setprio 0
	s_barrier
; template <bool trans>
; DI void gemm_core(const GTile& tl, const GTile& nx, bool has_next  , bool chain  , bool pre, u32x4 (&ra)[4], u32x4 (&rb)[4], char* smem, f32x16 (&acc)[2][4]) {
;     ...
;   const int nk = K / 64;
;   if (!pre) { G_LOAD(0); G_STORE(0); G_LOAD(1); }
;   for (int kt = 0; kt < nk; ++kt) {
;     __syncthreads();
;     G_COMPUTE(kt & 1, kt);
;   }
	global_load_dwordx4 v[168:171], v[136:137], off offset:3072
	global_load_dwordx4 v[172:175], v[138:139], off offset:3072
	s_waitcnt vmcnt(9)
	ds_write_b128 v192, v[160:163]
	s_waitcnt vmcnt(8)
	ds_write_b128 v159, v[164:167]
	ds_read_b128 v[160:163], v152 offset:36864
	ds_read_b128 v[164:167], v152 offset:41472
	ds_read_b128 v[208:211], v151
	ds_read_b128 v[212:215], v151 offset:4608
	s_setprio 1
	s_waitcnt lgkmcnt(1)
	v_mfma_f32_32x32x16_bf16 v[96:111], v[160:163], v[208:211], v[96:111]
	v_mfma_f32_32x32x16_bf16 v[112:127], v[164:167], v[208:211], v[112:127]
	s_waitcnt lgkmcnt(0)
	v_mfma_f32_32x32x16_bf16 v[64:79], v[160:163], v[212:215], v[64:79]
	v_mfma_f32_32x32x16_bf16 v[80:95], v[164:167], v[212:215], v[80:95]
	ds_read_b128 v[208:211], v151 offset:9216
	ds_read_b128 v[212:215], v151 offset:13824
	s_waitcnt vmcnt(7)
	ds_write_b128 v158, v[184:187]
	s_waitcnt vmcnt(6)
	ds_write_b128 v157, v[188:191]
	ds_read_b128 v[184:187], v152 offset:36896
	ds_read_b128 v[188:191], v152 offset:41504
	s_waitcnt lgkmcnt(5)
	v_mfma_f32_32x32x16_bf16 v[32:47], v[160:163], v[208:211], v[32:47]
	v_mfma_f32_32x32x16_bf16 v[48:63], v[164:167], v[208:211], v[48:63]
	ds_read_b128 v[208:211], v151 offset:32
	s_waitcnt lgkmcnt(5)
	v_mfma_f32_32x32x16_bf16 v[0:15], v[160:163], v[212:215], v[0:15]
	v_mfma_f32_32x32x16_bf16 v[16:31], v[164:167], v[212:215], v[16:31]
	ds_read_b128 v[212:215], v151 offset:4640
	s_setprio 0
	global_load_dwordx4 v[160:163], v[140:141], off offset:3072
	global_load_dwordx4 v[164:167], v[142:143], off offset:3072
	s_setprio 1
	s_waitcnt lgkmcnt(1)
	v_mfma_f32_32x32x16_bf16 v[96:111], v[184:187], v[208:211], v[96:111]
	v_mfma_f32_32x32x16_bf16 v[112:127], v[188:191], v[208:211], v[112:127]
	s_waitcnt lgkmcnt(0)
	v_mfma_f32_32x32x16_bf16 v[64:79], v[184:187], v[212:215], v[64:79]
	v_mfma_f32_32x32x16_bf16 v[80:95], v[188:191], v[212:215], v[80:95]
	ds_read_b128 v[208:211], v151 offset:9248
	ds_read_b128 v[212:215], v151 offset:13856
	s_waitcnt vmcnt(7)
	ds_write_b128 v154, v[194:197]
	s_waitcnt vmcnt(6)
	ds_write_b128 v153, v[198:201]
	ds_read_b128 v[194:197], v152 offset:36928
	ds_read_b128 v[198:201], v152 offset:41536
	s_waitcnt lgkmcnt(5)
	v_mfma_f32_32x32x16_bf16 v[32:47], v[184:187], v[208:211], v[32:47]
	v_mfma_f32_32x32x16_bf16 v[48:63], v[188:191], v[208:211], v[48:63]
	ds_read_b128 v[208:211], v151 offset:64
	s_waitcnt lgkmcnt(5)
	v_mfma_f32_32x32x16_bf16 v[0:15], v[184:187], v[212:215], v[0:15]
	v_mfma_f32_32x32x16_bf16 v[16:31], v[188:191], v[212:215], v[16:31]
	ds_read_b128 v[212:215], v151 offset:4672
	s_setprio 0
	global_load_dwordx4 v[184:187], v[132:133], off offset:3072
	global_load_dwordx4 v[188:191], v[134:135], off offset:3072
	s_setprio 1
	s_waitcnt lgkmcnt(1)
	v_mfma_f32_32x32x16_bf16 v[96:111], v[194:197], v[208:211], v[96:111]
	v_mfma_f32_32x32x16_bf16 v[112:127], v[198:201], v[208:211], v[112:127]
	s_waitcnt lgkmcnt(0)
	v_mfma_f32_32x32x16_bf16 v[64:79], v[194:197], v[212:215], v[64:79]
	v_mfma_f32_32x32x16_bf16 v[80:95], v[198:201], v[212:215], v[80:95]
	ds_read_b128 v[208:211], v151 offset:9280
	ds_read_b128 v[212:215], v151 offset:13888
	s_waitcnt vmcnt(7)
	ds_write_b128 v156, v[176:179]
	s_waitcnt vmcnt(6)
	ds_write_b128 v155, v[180:183]
	ds_read_b128 v[176:179], v152 offset:36960
	ds_read_b128 v[180:183], v152 offset:41568
	s_waitcnt lgkmcnt(5)
	v_mfma_f32_32x32x16_bf16 v[32:47], v[194:197], v[208:211], v[32:47]
	v_mfma_f32_32x32x16_bf16 v[48:63], v[198:201], v[208:211], v[48:63]
	ds_read_b128 v[208:211], v151 offset:96
	s_waitcnt lgkmcnt(5)
	v_mfma_f32_32x32x16_bf16 v[0:15], v[194:197], v[212:215], v[0:15]
	v_mfma_f32_32x32x16_bf16 v[16:31], v[198:201], v[212:215], v[16:31]
	ds_read_b128 v[212:215], v151 offset:4704
	s_setprio 0
	global_load_dwordx4 v[194:197], v[144:145], off offset:3072
	global_load_dwordx4 v[198:201], v[146:147], off offset:3072
	s_setprio 1
	s_waitcnt lgkmcnt(1)
	v_mfma_f32_32x32x16_bf16 v[96:111], v[176:179], v[208:211], v[96:111]
	v_mfma_f32_32x32x16_bf16 v[112:127], v[180:183], v[208:211], v[112:127]
	s_waitcnt lgkmcnt(0)
	v_mfma_f32_32x32x16_bf16 v[64:79], v[176:179], v[212:215], v[64:79]
	v_mfma_f32_32x32x16_bf16 v[80:95], v[180:183], v[212:215], v[80:95]
	ds_read_b128 v[208:211], v151 offset:9312
	ds_read_b128 v[212:215], v151 offset:13920
	s_waitcnt lgkmcnt(1)
	v_mfma_f32_32x32x16_bf16 v[32:47], v[176:179], v[208:211], v[32:47]
	v_mfma_f32_32x32x16_bf16 v[48:63], v[180:183], v[208:211], v[48:63]
	s_waitcnt lgkmcnt(0)
	v_mfma_f32_32x32x16_bf16 v[0:15], v[176:179], v[212:215], v[0:15]
	v_mfma_f32_32x32x16_bf16 v[16:31], v[180:183], v[212:215], v[16:31]
	s_setprio 0
	s_barrier
; template <bool trans>
; DI void gemm_core(const GTile& tl, const GTile& nx, bool has_next  , bool chain  , bool pre, u32x4 (&ra)[4], u32x4 (&rb)[4], char* smem, f32x16 (&acc)[2][4]) {
;     ...
;   const int nk = K / 64;
;   if (!pre) { G_LOAD(0); G_STORE(0); G_LOAD(1); }
;   for (int kt = 0; kt < nk; ++kt) {
;     __syncthreads();
;     G_COMPUTE(kt & 1, kt);
;   }
	global_load_dwordx4 v[176:179], v[136:137], off offset:3200
	global_load_dwordx4 v[180:183], v[138:139], off offset:3200
	s_waitcnt vmcnt(9)
	ds_write_b128 v148, v[168:171]
	s_waitcnt vmcnt(8)
	ds_write_b128 v148, v[172:175] offset:36864
	ds_read_b128 v[168:171], v150
	ds_read_b128 v[172:175], v150 offset:4608
	ds_read_b128 v[208:211], v149
	ds_read_b128 v[212:215], v149 offset:4608
	s_setprio 1
	s_waitcnt lgkmcnt(1)
	v_mfma_f32_32x32x16_bf16 v[96:111], v[168:171], v[208:211], v[96:111]
	v_mfma_f32_32x32x16_bf16 v[112:127], v[172:175], v[208:211], v[112:127]
	s_waitcnt lgkmcnt(0)
	v_mfma_f32_32x32x16_bf16 v[64:79], v[168:171], v[212:215], v[64:79]
	v_mfma_f32_32x32x16_bf16 v[80:95], v[172:175], v[212:215], v[80:95]
	ds_read_b128 v[208:211], v149 offset:9216
	ds_read_b128 v[212:215], v149 offset:13824
	s_waitcnt vmcnt(7)
	ds_write_b128 v148, v[160:163] offset:9216
	s_waitcnt vmcnt(6)
	ds_write_b128 v148, v[164:167] offset:46080
	ds_read_b128 v[160:163], v150 offset:32
	ds_read_b128 v[164:167], v150 offset:4640
	s_waitcnt lgkmcnt(5)
	v_mfma_f32_32x32x16_bf16 v[32:47], v[168:171], v[208:211], v[32:47]
	v_mfma_f32_32x32x16_bf16 v[48:63], v[172:175], v[208:211], v[48:63]
	ds_read_b128 v[208:211], v149 offset:32
	s_waitcnt lgkmcnt(5)
	v_mfma_f32_32x32x16_bf16 v[0:15], v[168:171], v[212:215], v[0:15]
	v_mfma_f32_32x32x16_bf16 v[16:31], v[172:175], v[212:215], v[16:31]
	ds_read_b128 v[212:215], v149 offset:4640
	s_setprio 0
	global_load_dwordx4 v[168:171], v[140:141], off offset:3200
	global_load_dwordx4 v[172:175], v[142:143], off offset:3200
	s_setprio 1
	s_waitcnt lgkmcnt(1)
	v_mfma_f32_32x32x16_bf16 v[96:111], v[160:163], v[208:211], v[96:111]
	v_mfma_f32_32x32x16_bf16 v[112:127], v[164:167], v[208:211], v[112:127]
	s_waitcnt lgkmcnt(0)
	v_mfma_f32_32x32x16_bf16 v[64:79], v[160:163], v[212:215], v[64:79]
	v_mfma_f32_32x32x16_bf16 v[80:95], v[164:167], v[212:215], v[80:95]
	ds_read_b128 v[208:211], v149 offset:9248
	ds_read_b128 v[212:215], v149 offset:13856
	s_waitcnt vmcnt(7)
	ds_write_b128 v148, v[184:187] offset:18432
	s_waitcnt vmcnt(6)
	ds_write_b128 v148, v[188:191] offset:55296
	ds_read_b128 v[184:187], v150 offset:64
	ds_read_b128 v[188:191], v150 offset:4672
	s_waitcnt lgkmcnt(5)
	v_mfma_f32_32x32x16_bf16 v[32:47], v[160:163], v[208:211], v[32:47]
	v_mfma_f32_32x32x16_bf16 v[48:63], v[164:167], v[208:211], v[48:63]
	ds_read_b128 v[208:211], v149 offset:64
	s_waitcnt lgkmcnt(5)
	v_mfma_f32_32x32x16_bf16 v[0:15], v[160:163], v[212:215], v[0:15]
	v_mfma_f32_32x32x16_bf16 v[16:31], v[164:167], v[212:215], v[16:31]
	ds_read_b128 v[212:215], v149 offset:4672
	s_setprio 0
	global_load_dwordx4 v[160:163], v[132:133], off offset:3200
	global_load_dwordx4 v[164:167], v[134:135], off offset:3200
	s_setprio 1
	s_waitcnt lgkmcnt(1)
	v_mfma_f32_32x32x16_bf16 v[96:111], v[184:187], v[208:211], v[96:111]
	v_mfma_f32_32x32x16_bf16 v[112:127], v[188:191], v[208:211], v[112:127]
	s_waitcnt lgkmcnt(0)
	v_mfma_f32_32x32x16_bf16 v[64:79], v[184:187], v[212:215], v[64:79]
	v_mfma_f32_32x32x16_bf16 v[80:95], v[188:191], v[212:215], v[80:95]
	ds_read_b128 v[208:211], v149 offset:9280
	ds_read_b128 v[212:215], v149 offset:13888
	s_waitcnt vmcnt(7)
	ds_write_b128 v148, v[194:197] offset:27648
	s_waitcnt vmcnt(6)
	ds_write_b128 v148, v[198:201] offset:64512
	ds_read_b128 v[194:197], v150 offset:96
	ds_read_b128 v[198:201], v150 offset:4704
	s_waitcnt lgkmcnt(5)
	v_mfma_f32_32x32x16_bf16 v[32:47], v[184:187], v[208:211], v[32:47]
	v_mfma_f32_32x32x16_bf16 v[48:63], v[188:191], v[208:211], v[48:63]
	ds_read_b128 v[208:211], v149 offset:96
	s_waitcnt lgkmcnt(5)
	v_mfma_f32_32x32x16_bf16 v[0:15], v[184:187], v[212:215], v[0:15]
	v_mfma_f32_32x32x16_bf16 v[16:31], v[188:191], v[212:215], v[16:31]
	ds_read_b128 v[212:215], v149 offset:4704
	s_setprio 0
	global_load_dwordx4 v[184:187], v[144:145], off offset:3200
	global_load_dwordx4 v[188:191], v[146:147], off offset:3200
	s_setprio 1
	s_waitcnt lgkmcnt(1)
	v_mfma_f32_32x32x16_bf16 v[96:111], v[194:197], v[208:211], v[96:111]
	v_mfma_f32_32x32x16_bf16 v[112:127], v[198:201], v[208:211], v[112:127]
	s_waitcnt lgkmcnt(0)
	v_mfma_f32_32x32x16_bf16 v[64:79], v[194:197], v[212:215], v[64:79]
	v_mfma_f32_32x32x16_bf16 v[80:95], v[198:201], v[212:215], v[80:95]
	ds_read_b128 v[208:211], v149 offset:9312
	ds_read_b128 v[212:215], v149 offset:13920
	s_waitcnt lgkmcnt(1)
	v_mfma_f32_32x32x16_bf16 v[32:47], v[194:197], v[208:211], v[32:47]
	v_mfma_f32_32x32x16_bf16 v[48:63], v[198:201], v[208:211], v[48:63]
	s_waitcnt lgkmcnt(0)
	v_mfma_f32_32x32x16_bf16 v[0:15], v[194:197], v[212:215], v[0:15]
	v_mfma_f32_32x32x16_bf16 v[16:31], v[198:201], v[212:215], v[16:31]
	s_setprio 0
	s_barrier
; template <bool trans>
; DI void gemm_core(const GTile& tl, const GTile& nx, bool has_next  , bool chain  , bool pre, u32x4 (&ra)[4], u32x4 (&rb)[4], char* smem, f32x16 (&acc)[2][4]) {
;     ...
;   const int nk = K / 64;
;   if (!pre) { G_LOAD(0); G_STORE(0); G_LOAD(1); }
;   for (int kt = 0; kt < nk; ++kt) {
;     __syncthreads();
;     G_COMPUTE(kt & 1, kt);
;   }
	global_load_dwordx4 v[194:197], v[136:137], off offset:3328
	global_load_dwordx4 v[198:201], v[138:139], off offset:3328
	s_waitcnt vmcnt(9)
	ds_write_b128 v192, v[176:179]
	s_waitcnt vmcnt(8)
	ds_write_b128 v159, v[180:183]
	ds_read_b128 v[176:179], v152 offset:36864
	ds_read_b128 v[180:183], v152 offset:41472
	ds_read_b128 v[208:211], v151
	ds_read_b128 v[212:215], v151 offset:4608
	s_setprio 1
	s_waitcnt lgkmcnt(1)
	v_mfma_f32_32x32x16_bf16 v[96:111], v[176:179], v[208:211], v[96:111]
	v_mfma_f32_32x32x16_bf16 v[112:127], v[180:183], v[208:211], v[112:127]
	s_waitcnt lgkmcnt(0)
	v_mfma_f32_32x32x16_bf16 v[64:79], v[176:179], v[212:215], v[64:79]
	v_mfma_f32_32x32x16_bf16 v[80:95], v[180:183], v[212:215], v[80:95]
	ds_read_b128 v[208:211], v151 offset:9216
	ds_read_b128 v[212:215], v151 offset:13824
	s_waitcnt vmcnt(7)
	ds_write_b128 v158, v[168:171]
	s_waitcnt vmcnt(6)
	ds_write_b128 v157, v[172:175]
	ds_read_b128 v[168:171], v152 offset:36896
	ds_read_b128 v[172:175], v152 offset:41504
	s_waitcnt lgkmcnt(5)
	v_mfma_f32_32x32x16_bf16 v[32:47], v[176:179], v[208:211], v[32:47]
	v_mfma_f32_32x32x16_bf16 v[48:63], v[180:183], v[208:211], v[48:63]
	ds_read_b128 v[208:211], v151 offset:32
	s_waitcnt lgkmcnt(5)
	v_mfma_f32_32x32x16_bf16 v[0:15], v[176:179], v[212:215], v[0:15]
	v_mfma_f32_32x32x16_bf16 v[16:31], v[180:183], v[212:215], v[16:31]
	ds_read_b128 v[212:215], v151 offset:4640
	s_setprio 0
	global_load_dwordx4 v[176:179], v[140:141], off offset:3328
	global_load_dwordx4 v[180:183], v[142:143], off offset:3328
	s_setprio 1
	s_waitcnt lgkmcnt(1)
	v_mfma_f32_32x32x16_bf16 v[96:111], v[168:171], v[208:211], v[96:111]
	v_mfma_f32_32x32x16_bf16 v[112:127], v[172:175], v[208:211], v[112:127]
	s_waitcnt lgkmcnt(0)
	v_mfma_f32_32x32x16_bf16 v[64:79], v[168:171], v[212:215], v[64:79]
	v_mfma_f32_32x32x16_bf16 v[80:95], v[172:175], v[212:215], v[80:95]
	ds_read_b128 v[208:211], v151 offset:9248
	ds_read_b128 v[212:215], v151 offset:13856
	s_waitcnt vmcnt(7)
	ds_write_b128 v154, v[160:163]
	s_waitcnt vmcnt(6)
	ds_write_b128 v153, v[164:167]
	ds_read_b128 v[160:163], v152 offset:36928
	ds_read_b128 v[164:167], v152 offset:41536
	s_waitcnt lgkmcnt(5)
	v_mfma_f32_32x32x16_bf16 v[32:47], v[168:171], v[208:211], v[32:47]
	v_mfma_f32_32x32x16_bf16 v[48:63], v[172:175], v[208:211], v[48:63]
	ds_read_b128 v[208:211], v151 offset:64
	s_waitcnt lgkmcnt(5)
	v_mfma_f32_32x32x16_bf16 v[0:15], v[168:171], v[212:215], v[0:15]
	v_mfma_f32_32x32x16_bf16 v[16:31], v[172:175], v[212:215], v[16:31]
	ds_read_b128 v[212:215], v151 offset:4672
	s_setprio 0
	global_load_dwordx4 v[168:171], v[132:133], off offset:3328
	global_load_dwordx4 v[172:175], v[134:135], off offset:3328
	s_setprio 1
	s_waitcnt lgkmcnt(1)
	v_mfma_f32_32x32x16_bf16 v[96:111], v[160:163], v[208:211], v[96:111]
	v_mfma_f32_32x32x16_bf16 v[112:127], v[164:167], v[208:211], v[112:127]
	s_waitcnt lgkmcnt(0)
	v_mfma_f32_32x32x16_bf16 v[64:79], v[160:163], v[212:215], v[64:79]
	v_mfma_f32_32x32x16_bf16 v[80:95], v[164:167], v[212:215], v[80:95]
	ds_read_b128 v[208:211], v151 offset:9280
	ds_read_b128 v[212:215], v151 offset:13888
	s_waitcnt vmcnt(7)
	ds_write_b128 v156, v[184:187]
	s_waitcnt vmcnt(6)
	ds_write_b128 v155, v[188:191]
	ds_read_b128 v[184:187], v152 offset:36960
	ds_read_b128 v[188:191], v152 offset:41568
	s_waitcnt lgkmcnt(5)
	v_mfma_f32_32x32x16_bf16 v[32:47], v[160:163], v[208:211], v[32:47]
	v_mfma_f32_32x32x16_bf16 v[48:63], v[164:167], v[208:211], v[48:63]
	ds_read_b128 v[208:211], v151 offset:96
	s_waitcnt lgkmcnt(5)
	v_mfma_f32_32x32x16_bf16 v[0:15], v[160:163], v[212:215], v[0:15]
	v_mfma_f32_32x32x16_bf16 v[16:31], v[164:167], v[212:215], v[16:31]
	ds_read_b128 v[212:215], v151 offset:4704
	s_setprio 0
	global_load_dwordx4 v[160:163], v[144:145], off offset:3328
	global_load_dwordx4 v[164:167], v[146:147], off offset:3328
	s_setprio 1
	s_waitcnt lgkmcnt(1)
	v_mfma_f32_32x32x16_bf16 v[96:111], v[184:187], v[208:211], v[96:111]
	v_mfma_f32_32x32x16_bf16 v[112:127], v[188:191], v[208:211], v[112:127]
	s_waitcnt lgkmcnt(0)
	v_mfma_f32_32x32x16_bf16 v[64:79], v[184:187], v[212:215], v[64:79]
	v_mfma_f32_32x32x16_bf16 v[80:95], v[188:191], v[212:215], v[80:95]
	ds_read_b128 v[208:211], v151 offset:9312
	ds_read_b128 v[212:215], v151 offset:13920
	s_waitcnt lgkmcnt(1)
	v_mfma_f32_32x32x16_bf16 v[32:47], v[184:187], v[208:211], v[32:47]
	v_mfma_f32_32x32x16_bf16 v[48:63], v[188:191], v[208:211], v[48:63]
	s_waitcnt lgkmcnt(0)
	v_mfma_f32_32x32x16_bf16 v[0:15], v[184:187], v[212:215], v[0:15]
	v_mfma_f32_32x32x16_bf16 v[16:31], v[188:191], v[212:215], v[16:31]
	s_setprio 0
	s_barrier
; template <bool trans>
; DI void gemm_core(const GTile& tl, const GTile& nx, bool has_next  , bool chain  , bool pre, u32x4 (&ra)[4], u32x4 (&rb)[4], char* smem, f32x16 (&acc)[2][4]) {
;     ...
;   const int nk = K / 64;
;   if (!pre) { G_LOAD(0); G_STORE(0); G_LOAD(1); }
;   for (int kt = 0; kt < nk; ++kt) {
;     __syncthreads();
;     G_COMPUTE(kt & 1, kt);
;   }
	global_load_dwordx4 v[184:187], v[136:137], off offset:3456
	global_load_dwordx4 v[188:191], v[138:139], off offset:3456
	s_waitcnt vmcnt(9)
	ds_write_b128 v148, v[194:197]
	s_waitcnt vmcnt(8)
	ds_write_b128 v148, v[198:201] offset:36864
	ds_read_b128 v[194:197], v150
	ds_read_b128 v[198:201], v150 offset:4608
	ds_read_b128 v[208:211], v149
	ds_read_b128 v[212:215], v149 offset:4608
	s_setprio 1
	s_waitcnt lgkmcnt(1)
	v_mfma_f32_32x32x16_bf16 v[96:111], v[194:197], v[208:211], v[96:111]
	v_mfma_f32_32x32x16_bf16 v[112:127], v[198:201], v[208:211], v[112:127]
	s_waitcnt lgkmcnt(0)
	v_mfma_f32_32x32x16_bf16 v[64:79], v[194:197], v[212:215], v[64:79]
	v_mfma_f32_32x32x16_bf16 v[80:95], v[198:201], v[212:215], v[80:95]
	ds_read_b128 v[208:211], v149 offset:9216
	ds_read_b128 v[212:215], v149 offset:13824
	s_waitcnt vmcnt(7)
	ds_write_b128 v148, v[176:179] offset:9216
	s_waitcnt vmcnt(6)
	ds_write_b128 v148, v[180:183] offset:46080
	ds_read_b128 v[176:179], v150 offset:32
	ds_read_b128 v[180:183], v150 offset:4640
	s_waitcnt lgkmcnt(5)
	v_mfma_f32_32x32x16_bf16 v[32:47], v[194:197], v[208:211], v[32:47]
	v_mfma_f32_32x32x16_bf16 v[48:63], v[198:201], v[208:211], v[48:63]
	ds_read_b128 v[208:211], v149 offset:32
	s_waitcnt lgkmcnt(5)
	v_mfma_f32_32x32x16_bf16 v[0:15], v[194:197], v[212:215], v[0:15]
	v_mfma_f32_32x32x16_bf16 v[16:31], v[198:201], v[212:215], v[16:31]
	ds_read_b128 v[212:215], v149 offset:4640
	s_setprio 0
	global_load_dwordx4 v[194:197], v[140:141], off offset:3456
	global_load_dwordx4 v[198:201], v[142:143], off offset:3456
	s_setprio 1
	s_waitcnt lgkmcnt(1)
	v_mfma_f32_32x32x16_bf16 v[96:111], v[176:179], v[208:211], v[96:111]
	v_mfma_f32_32x32x16_bf16 v[112:127], v[180:183], v[208:211], v[112:127]
	s_waitcnt lgkmcnt(0)
	v_mfma_f32_32x32x16_bf16 v[64:79], v[176:179], v[212:215], v[64:79]
	v_mfma_f32_32x32x16_bf16 v[80:95], v[180:183], v[212:215], v[80:95]
	ds_read_b128 v[208:211], v149 offset:9248
	ds_read_b128 v[212:215], v149 offset:13856
	s_waitcnt vmcnt(7)
	ds_write_b128 v148, v[168:171] offset:18432
	s_waitcnt vmcnt(6)
	ds_write_b128 v148, v[172:175] offset:55296
	ds_read_b128 v[168:171], v150 offset:64
	ds_read_b128 v[172:175], v150 offset:4672
	s_waitcnt lgkmcnt(5)
	v_mfma_f32_32x32x16_bf16 v[32:47], v[176:179], v[208:211], v[32:47]
	v_mfma_f32_32x32x16_bf16 v[48:63], v[180:183], v[208:211], v[48:63]
	ds_read_b128 v[208:211], v149 offset:64
	s_waitcnt lgkmcnt(5)
	v_mfma_f32_32x32x16_bf16 v[0:15], v[176:179], v[212:215], v[0:15]
	v_mfma_f32_32x32x16_bf16 v[16:31], v[180:183], v[212:215], v[16:31]
	ds_read_b128 v[212:215], v149 offset:4672
	s_setprio 0
	global_load_dwordx4 v[176:179], v[132:133], off offset:3456
	global_load_dwordx4 v[180:183], v[134:135], off offset:3456
	s_setprio 1
	s_waitcnt lgkmcnt(1)
	v_mfma_f32_32x32x16_bf16 v[96:111], v[168:171], v[208:211], v[96:111]
	v_mfma_f32_32x32x16_bf16 v[112:127], v[172:175], v[208:211], v[112:127]
	s_waitcnt lgkmcnt(0)
	v_mfma_f32_32x32x16_bf16 v[64:79], v[168:171], v[212:215], v[64:79]
	v_mfma_f32_32x32x16_bf16 v[80:95], v[172:175], v[212:215], v[80:95]
	ds_read_b128 v[208:211], v149 offset:9280
	ds_read_b128 v[212:215], v149 offset:13888
	s_waitcnt vmcnt(7)
	ds_write_b128 v148, v[160:163] offset:27648
	s_waitcnt vmcnt(6)
	ds_write_b128 v148, v[164:167] offset:64512
	ds_read_b128 v[160:163], v150 offset:96
	ds_read_b128 v[164:167], v150 offset:4704
	s_waitcnt lgkmcnt(5)
	v_mfma_f32_32x32x16_bf16 v[32:47], v[168:171], v[208:211], v[32:47]
	v_mfma_f32_32x32x16_bf16 v[48:63], v[172:175], v[208:211], v[48:63]
	ds_read_b128 v[208:211], v149 offset:96
	s_waitcnt lgkmcnt(5)
	v_mfma_f32_32x32x16_bf16 v[0:15], v[168:171], v[212:215], v[0:15]
	v_mfma_f32_32x32x16_bf16 v[16:31], v[172:175], v[212:215], v[16:31]
	ds_read_b128 v[212:215], v149 offset:4704
	s_setprio 0
	global_load_dwordx4 v[168:171], v[144:145], off offset:3456
	global_load_dwordx4 v[172:175], v[146:147], off offset:3456
	s_setprio 1
	s_waitcnt lgkmcnt(1)
	v_mfma_f32_32x32x16_bf16 v[96:111], v[160:163], v[208:211], v[96:111]
	v_mfma_f32_32x32x16_bf16 v[112:127], v[164:167], v[208:211], v[112:127]
	s_waitcnt lgkmcnt(0)
	v_mfma_f32_32x32x16_bf16 v[64:79], v[160:163], v[212:215], v[64:79]
	v_mfma_f32_32x32x16_bf16 v[80:95], v[164:167], v[212:215], v[80:95]
	ds_read_b128 v[208:211], v149 offset:9312
	ds_read_b128 v[212:215], v149 offset:13920
	s_waitcnt lgkmcnt(1)
	v_mfma_f32_32x32x16_bf16 v[32:47], v[160:163], v[208:211], v[32:47]
	v_mfma_f32_32x32x16_bf16 v[48:63], v[164:167], v[208:211], v[48:63]
	s_waitcnt lgkmcnt(0)
	v_mfma_f32_32x32x16_bf16 v[0:15], v[160:163], v[212:215], v[0:15]
	v_mfma_f32_32x32x16_bf16 v[16:31], v[164:167], v[212:215], v[16:31]
	s_setprio 0
	s_barrier
; template <bool trans>
; DI void gemm_core(const GTile& tl, const GTile& nx, bool has_next  , bool chain  , bool pre, u32x4 (&ra)[4], u32x4 (&rb)[4], char* smem, f32x16 (&acc)[2][4]) {
;     ...
;   const int nk = K / 64;
;   if (!pre) { G_LOAD(0); G_STORE(0); G_LOAD(1); }
;   for (int kt = 0; kt < nk; ++kt) {
;     __syncthreads();
;     G_COMPUTE(kt & 1, kt);
;   }
	global_load_dwordx4 v[160:163], v[136:137], off offset:3584
	global_load_dwordx4 v[164:167], v[138:139], off offset:3584
	s_waitcnt vmcnt(9)
	ds_write_b128 v192, v[184:187]
	s_waitcnt vmcnt(8)
	ds_write_b128 v159, v[188:191]
	ds_read_b128 v[184:187], v152 offset:36864
	ds_read_b128 v[188:191], v152 offset:41472
	ds_read_b128 v[208:211], v151
	ds_read_b128 v[212:215], v151 offset:4608
	s_setprio 1
	s_waitcnt lgkmcnt(1)
	v_mfma_f32_32x32x16_bf16 v[96:111], v[184:187], v[208:211], v[96:111]
	v_mfma_f32_32x32x16_bf16 v[112:127], v[188:191], v[208:211], v[112:127]
	s_waitcnt lgkmcnt(0)
	v_mfma_f32_32x32x16_bf16 v[64:79], v[184:187], v[212:215], v[64:79]
	v_mfma_f32_32x32x16_bf16 v[80:95], v[188:191], v[212:215], v[80:95]
	ds_read_b128 v[208:211], v151 offset:9216
	ds_read_b128 v[212:215], v151 offset:13824
	s_waitcnt vmcnt(7)
	ds_write_b128 v158, v[194:197]
	s_waitcnt vmcnt(6)
	ds_write_b128 v157, v[198:201]
	ds_read_b128 v[194:197], v152 offset:36896
	ds_read_b128 v[198:201], v152 offset:41504
	s_waitcnt lgkmcnt(5)
	v_mfma_f32_32x32x16_bf16 v[32:47], v[184:187], v[208:211], v[32:47]
	v_mfma_f32_32x32x16_bf16 v[48:63], v[188:191], v[208:211], v[48:63]
	ds_read_b128 v[208:211], v151 offset:32
	s_waitcnt lgkmcnt(5)
	v_mfma_f32_32x32x16_bf16 v[0:15], v[184:187], v[212:215], v[0:15]
	v_mfma_f32_32x32x16_bf16 v[16:31], v[188:191], v[212:215], v[16:31]
	ds_read_b128 v[212:215], v151 offset:4640
	s_setprio 0
	global_load_dwordx4 v[184:187], v[140:141], off offset:3584
	global_load_dwordx4 v[188:191], v[142:143], off offset:3584
	s_setprio 1
	s_waitcnt lgkmcnt(1)
	v_mfma_f32_32x32x16_bf16 v[96:111], v[194:197], v[208:211], v[96:111]
	v_mfma_f32_32x32x16_bf16 v[112:127], v[198:201], v[208:211], v[112:127]
	s_waitcnt lgkmcnt(0)
	v_mfma_f32_32x32x16_bf16 v[64:79], v[194:197], v[212:215], v[64:79]
	v_mfma_f32_32x32x16_bf16 v[80:95], v[198:201], v[212:215], v[80:95]
	ds_read_b128 v[208:211], v151 offset:9248
	ds_read_b128 v[212:215], v151 offset:13856
	s_waitcnt vmcnt(7)
	ds_write_b128 v154, v[176:179]
	s_waitcnt vmcnt(6)
	ds_write_b128 v153, v[180:183]
	ds_read_b128 v[176:179], v152 offset:36928
	ds_read_b128 v[180:183], v152 offset:41536
	s_waitcnt lgkmcnt(5)
	v_mfma_f32_32x32x16_bf16 v[32:47], v[194:197], v[208:211], v[32:47]
	v_mfma_f32_32x32x16_bf16 v[48:63], v[198:201], v[208:211], v[48:63]
	ds_read_b128 v[208:211], v151 offset:64
	s_waitcnt lgkmcnt(5)
	v_mfma_f32_32x32x16_bf16 v[0:15], v[194:197], v[212:215], v[0:15]
	v_mfma_f32_32x32x16_bf16 v[16:31], v[198:201], v[212:215], v[16:31]
	ds_read_b128 v[212:215], v151 offset:4672
	s_setprio 0
	global_load_dwordx4 v[194:197], v[132:133], off offset:3584
	global_load_dwordx4 v[198:201], v[134:135], off offset:3584
	s_setprio 1
	s_waitcnt lgkmcnt(1)
	v_mfma_f32_32x32x16_bf16 v[96:111], v[176:179], v[208:211], v[96:111]
	v_mfma_f32_32x32x16_bf16 v[112:127], v[180:183], v[208:211], v[112:127]
	s_waitcnt lgkmcnt(0)
	v_mfma_f32_32x32x16_bf16 v[64:79], v[176:179], v[212:215], v[64:79]
	v_mfma_f32_32x32x16_bf16 v[80:95], v[180:183], v[212:215], v[80:95]
	ds_read_b128 v[208:211], v151 offset:9280
	ds_read_b128 v[212:215], v151 offset:13888
	s_waitcnt vmcnt(7)
	ds_write_b128 v156, v[168:171]
	s_waitcnt vmcnt(6)
	ds_write_b128 v155, v[172:175]
	ds_read_b128 v[168:171], v152 offset:36960
	ds_read_b128 v[172:175], v152 offset:41568
	s_waitcnt lgkmcnt(5)
	v_mfma_f32_32x32x16_bf16 v[32:47], v[176:179], v[208:211], v[32:47]
	v_mfma_f32_32x32x16_bf16 v[48:63], v[180:183], v[208:211], v[48:63]
	ds_read_b128 v[208:211], v151 offset:96
	s_waitcnt lgkmcnt(5)
	v_mfma_f32_32x32x16_bf16 v[0:15], v[176:179], v[212:215], v[0:15]
	v_mfma_f32_32x32x16_bf16 v[16:31], v[180:183], v[212:215], v[16:31]
	ds_read_b128 v[212:215], v151 offset:4704
	s_setprio 0
	global_load_dwordx4 v[176:179], v[144:145], off offset:3584
	global_load_dwordx4 v[180:183], v[146:147], off offset:3584
	s_setprio 1
	s_waitcnt lgkmcnt(1)
	v_mfma_f32_32x32x16_bf16 v[96:111], v[168:171], v[208:211], v[96:111]
	v_mfma_f32_32x32x16_bf16 v[112:127], v[172:175], v[208:211], v[112:127]
	s_waitcnt lgkmcnt(0)
	v_mfma_f32_32x32x16_bf16 v[64:79], v[168:171], v[212:215], v[64:79]
	v_mfma_f32_32x32x16_bf16 v[80:95], v[172:175], v[212:215], v[80:95]
	ds_read_b128 v[208:211], v151 offset:9312
	ds_read_b128 v[212:215], v151 offset:13920
	s_waitcnt lgkmcnt(1)
	v_mfma_f32_32x32x16_bf16 v[32:47], v[168:171], v[208:211], v[32:47]
	v_mfma_f32_32x32x16_bf16 v[48:63], v[172:175], v[208:211], v[48:63]
	s_waitcnt lgkmcnt(0)
	v_mfma_f32_32x32x16_bf16 v[0:15], v[168:171], v[212:215], v[0:15]
	v_mfma_f32_32x32x16_bf16 v[16:31], v[172:175], v[212:215], v[16:31]
	s_setprio 0
	s_barrier
; template <bool trans>
; DI void gemm_core(const GTile& tl, const GTile& nx, bool has_next  , bool chain  , bool pre, u32x4 (&ra)[4], u32x4 (&rb)[4], char* smem, f32x16 (&acc)[2][4]) {
;     ...
;   const int nk = K / 64;
;   if (!pre) { G_LOAD(0); G_STORE(0); G_LOAD(1); }
;   for (int kt = 0; kt < nk; ++kt) {
;     __syncthreads();
;     G_COMPUTE(kt & 1, kt);
;   }
	global_load_dwordx4 v[168:171], v[136:137], off offset:3712
	global_load_dwordx4 v[172:175], v[138:139], off offset:3712
	s_waitcnt vmcnt(9)
	ds_write_b128 v148, v[160:163]
	s_waitcnt vmcnt(8)
	ds_write_b128 v148, v[164:167] offset:36864
	ds_read_b128 v[160:163], v150
	ds_read_b128 v[164:167], v150 offset:4608
	ds_read_b128 v[208:211], v149
	ds_read_b128 v[212:215], v149 offset:4608
	s_setprio 1
	s_waitcnt lgkmcnt(1)
	v_mfma_f32_32x32x16_bf16 v[96:111], v[160:163], v[208:211], v[96:111]
	v_mfma_f32_32x32x16_bf16 v[112:127], v[164:167], v[208:211], v[112:127]
	s_waitcnt lgkmcnt(0)
	v_mfma_f32_32x32x16_bf16 v[64:79], v[160:163], v[212:215], v[64:79]
	v_mfma_f32_32x32x16_bf16 v[80:95], v[164:167], v[212:215], v[80:95]
	ds_read_b128 v[208:211], v149 offset:9216
	ds_read_b128 v[212:215], v149 offset:13824
	s_waitcnt vmcnt(7)
	ds_write_b128 v148, v[184:187] offset:9216
	s_waitcnt vmcnt(6)
	ds_write_b128 v148, v[188:191] offset:46080
	ds_read_b128 v[184:187], v150 offset:32
	ds_read_b128 v[188:191], v150 offset:4640
	s_waitcnt lgkmcnt(5)
	v_mfma_f32_32x32x16_bf16 v[32:47], v[160:163], v[208:211], v[32:47]
	v_mfma_f32_32x32x16_bf16 v[48:63], v[164:167], v[208:211], v[48:63]
	ds_read_b128 v[208:211], v149 offset:32
	s_waitcnt lgkmcnt(5)
	v_mfma_f32_32x32x16_bf16 v[0:15], v[160:163], v[212:215], v[0:15]
	v_mfma_f32_32x32x16_bf16 v[16:31], v[164:167], v[212:215], v[16:31]
	ds_read_b128 v[212:215], v149 offset:4640
	s_setprio 0
	global_load_dwordx4 v[160:163], v[140:141], off offset:3712
	global_load_dwordx4 v[164:167], v[142:143], off offset:3712
	s_setprio 1
	s_waitcnt lgkmcnt(1)
	v_mfma_f32_32x32x16_bf16 v[96:111], v[184:187], v[208:211], v[96:111]
	v_mfma_f32_32x32x16_bf16 v[112:127], v[188:191], v[208:211], v[112:127]
	s_waitcnt lgkmcnt(0)
	v_mfma_f32_32x32x16_bf16 v[64:79], v[184:187], v[212:215], v[64:79]
	v_mfma_f32_32x32x16_bf16 v[80:95], v[188:191], v[212:215], v[80:95]
	ds_read_b128 v[208:211], v149 offset:9248
	ds_read_b128 v[212:215], v149 offset:13856
	s_waitcnt vmcnt(7)
	ds_write_b128 v148, v[194:197] offset:18432
	s_waitcnt vmcnt(6)
	ds_write_b128 v148, v[198:201] offset:55296
	ds_read_b128 v[194:197], v150 offset:64
	ds_read_b128 v[198:201], v150 offset:4672
	s_waitcnt lgkmcnt(5)
	v_mfma_f32_32x32x16_bf16 v[32:47], v[184:187], v[208:211], v[32:47]
	v_mfma_f32_32x32x16_bf16 v[48:63], v[188:191], v[208:211], v[48:63]
	ds_read_b128 v[208:211], v149 offset:64
	s_waitcnt lgkmcnt(5)
	v_mfma_f32_32x32x16_bf16 v[0:15], v[184:187], v[212:215], v[0:15]
	v_mfma_f32_32x32x16_bf16 v[16:31], v[188:191], v[212:215], v[16:31]
	ds_read_b128 v[212:215], v149 offset:4672
	s_setprio 0
	global_load_dwordx4 v[184:187], v[132:133], off offset:3712
	global_load_dwordx4 v[188:191], v[134:135], off offset:3712
	s_setprio 1
	s_waitcnt lgkmcnt(1)
	v_mfma_f32_32x32x16_bf16 v[96:111], v[194:197], v[208:211], v[96:111]
	v_mfma_f32_32x32x16_bf16 v[112:127], v[198:201], v[208:211], v[112:127]
	s_waitcnt lgkmcnt(0)
	v_mfma_f32_32x32x16_bf16 v[64:79], v[194:197], v[212:215], v[64:79]
	v_mfma_f32_32x32x16_bf16 v[80:95], v[198:201], v[212:215], v[80:95]
	ds_read_b128 v[208:211], v149 offset:9280
	ds_read_b128 v[212:215], v149 offset:13888
	s_waitcnt vmcnt(7)
	ds_write_b128 v148, v[176:179] offset:27648
	s_waitcnt vmcnt(6)
	ds_write_b128 v148, v[180:183] offset:64512
	ds_read_b128 v[176:179], v150 offset:96
	ds_read_b128 v[180:183], v150 offset:4704
	s_waitcnt lgkmcnt(5)
	v_mfma_f32_32x32x16_bf16 v[32:47], v[194:197], v[208:211], v[32:47]
	v_mfma_f32_32x32x16_bf16 v[48:63], v[198:201], v[208:211], v[48:63]
	ds_read_b128 v[208:211], v149 offset:96
	s_waitcnt lgkmcnt(5)
	v_mfma_f32_32x32x16_bf16 v[0:15], v[194:197], v[212:215], v[0:15]
	v_mfma_f32_32x32x16_bf16 v[16:31], v[198:201], v[212:215], v[16:31]
	ds_read_b128 v[212:215], v149 offset:4704
	s_setprio 0
	global_load_dwordx4 v[194:197], v[144:145], off offset:3712
	global_load_dwordx4 v[198:201], v[146:147], off offset:3712
	s_setprio 1
	s_waitcnt lgkmcnt(1)
	v_mfma_f32_32x32x16_bf16 v[96:111], v[176:179], v[208:211], v[96:111]
	v_mfma_f32_32x32x16_bf16 v[112:127], v[180:183], v[208:211], v[112:127]
	s_waitcnt lgkmcnt(0)
	v_mfma_f32_32x32x16_bf16 v[64:79], v[176:179], v[212:215], v[64:79]
	v_mfma_f32_32x32x16_bf16 v[80:95], v[180:183], v[212:215], v[80:95]
	ds_read_b128 v[208:211], v149 offset:9312
	ds_read_b128 v[212:215], v149 offset:13920
	s_waitcnt lgkmcnt(1)
	v_mfma_f32_32x32x16_bf16 v[32:47], v[176:179], v[208:211], v[32:47]
	v_mfma_f32_32x32x16_bf16 v[48:63], v[180:183], v[208:211], v[48:63]
	s_waitcnt lgkmcnt(0)
	v_mfma_f32_32x32x16_bf16 v[0:15], v[176:179], v[212:215], v[0:15]
	v_mfma_f32_32x32x16_bf16 v[16:31], v[180:183], v[212:215], v[16:31]
	s_setprio 0
	s_barrier
; template <bool trans>
; DI void gemm_core(const GTile& tl, const GTile& nx, bool has_next  , bool chain  , bool pre, u32x4 (&ra)[4], u32x4 (&rb)[4], char* smem, f32x16 (&acc)[2][4]) {
;     ...
;   const int nk = K / 64;
;   if (!pre) { G_LOAD(0); G_STORE(0); G_LOAD(1); }
;   for (int kt = 0; kt < nk; ++kt) {
;     __syncthreads();
;     G_COMPUTE(kt & 1, kt);
;   }
	global_load_dwordx4 v[176:179], v[136:137], off offset:3840
	global_load_dwordx4 v[180:183], v[138:139], off offset:3840
	s_waitcnt vmcnt(9)
	ds_write_b128 v192, v[168:171]
	s_waitcnt vmcnt(8)
	ds_write_b128 v159, v[172:175]
	ds_read_b128 v[168:171], v152 offset:36864
	ds_read_b128 v[172:175], v152 offset:41472
	ds_read_b128 v[208:211], v151
	ds_read_b128 v[212:215], v151 offset:4608
	s_setprio 1
	s_waitcnt lgkmcnt(1)
	v_mfma_f32_32x32x16_bf16 v[96:111], v[168:171], v[208:211], v[96:111]
	v_mfma_f32_32x32x16_bf16 v[112:127], v[172:175], v[208:211], v[112:127]
	s_waitcnt lgkmcnt(0)
	v_mfma_f32_32x32x16_bf16 v[64:79], v[168:171], v[212:215], v[64:79]
	v_mfma_f32_32x32x16_bf16 v[80:95], v[172:175], v[212:215], v[80:95]
	ds_read_b128 v[208:211], v151 offset:9216
	ds_read_b128 v[212:215], v151 offset:13824
	s_waitcnt lgkmcnt(1)
	v_mfma_f32_32x32x16_bf16 v[32:47], v[168:171], v[208:211], v[32:47]
	v_mfma_f32_32x32x16_bf16 v[48:63], v[172:175], v[208:211], v[48:63]
	s_waitcnt lgkmcnt(0)
	v_mfma_f32_32x32x16_bf16 v[0:15], v[168:171], v[212:215], v[0:15]
	v_mfma_f32_32x32x16_bf16 v[16:31], v[172:175], v[212:215], v[16:31]
	s_setprio 0
	global_load_dwordx4 v[208:211], v[140:141], off offset:3840
	global_load_dwordx4 v[212:215], v[142:143], off offset:3840
	s_waitcnt vmcnt(9)
	ds_write_b128 v158, v[160:163]
	s_waitcnt vmcnt(8)
	ds_write_b128 v157, v[164:167]
	ds_read_b128 v[160:163], v152 offset:36896
	ds_read_b128 v[164:167], v152 offset:41504
	ds_read_b128 v[168:171], v151 offset:32
	ds_read_b128 v[172:175], v151 offset:4640
	s_setprio 1
	s_waitcnt lgkmcnt(1)
	v_mfma_f32_32x32x16_bf16 v[96:111], v[160:163], v[168:171], v[96:111]
	v_mfma_f32_32x32x16_bf16 v[112:127], v[164:167], v[168:171], v[112:127]
	s_waitcnt lgkmcnt(0)
	v_mfma_f32_32x32x16_bf16 v[64:79], v[160:163], v[172:175], v[64:79]
	v_mfma_f32_32x32x16_bf16 v[80:95], v[164:167], v[172:175], v[80:95]
	ds_read_b128 v[168:171], v151 offset:9248
	ds_read_b128 v[172:175], v151 offset:13856
	s_waitcnt lgkmcnt(1)
	v_mfma_f32_32x32x16_bf16 v[32:47], v[160:163], v[168:171], v[32:47]
	v_mfma_f32_32x32x16_bf16 v[48:63], v[164:167], v[168:171], v[48:63]
	s_waitcnt lgkmcnt(0)
	v_mfma_f32_32x32x16_bf16 v[0:15], v[160:163], v[172:175], v[0:15]
	v_mfma_f32_32x32x16_bf16 v[16:31], v[164:167], v[172:175], v[16:31]
	s_setprio 0
	global_load_dwordx4 v[216:219], v[132:133], off offset:3840
	global_load_dwordx4 v[220:223], v[134:135], off offset:3840
	s_waitcnt vmcnt(9)
	ds_write_b128 v154, v[184:187]
	s_waitcnt vmcnt(8)
	ds_write_b128 v153, v[188:191]
	ds_read_b128 v[160:163], v152 offset:36928
	ds_read_b128 v[164:167], v152 offset:41536
	ds_read_b128 v[168:171], v151 offset:64
	ds_read_b128 v[172:175], v151 offset:4672
	s_setprio 1
	s_waitcnt lgkmcnt(1)
	v_mfma_f32_32x32x16_bf16 v[96:111], v[160:163], v[168:171], v[96:111]
	v_mfma_f32_32x32x16_bf16 v[112:127], v[164:167], v[168:171], v[112:127]
	s_waitcnt lgkmcnt(0)
	v_mfma_f32_32x32x16_bf16 v[64:79], v[160:163], v[172:175], v[64:79]
	v_mfma_f32_32x32x16_bf16 v[80:95], v[164:167], v[172:175], v[80:95]
	ds_read_b128 v[168:171], v151 offset:9280
	ds_read_b128 v[172:175], v151 offset:13888
	s_waitcnt lgkmcnt(1)
	v_mfma_f32_32x32x16_bf16 v[32:47], v[160:163], v[168:171], v[32:47]
	v_mfma_f32_32x32x16_bf16 v[48:63], v[164:167], v[168:171], v[48:63]
	s_waitcnt lgkmcnt(0)
	v_mfma_f32_32x32x16_bf16 v[0:15], v[160:163], v[172:175], v[0:15]
	v_mfma_f32_32x32x16_bf16 v[16:31], v[164:167], v[172:175], v[16:31]
	s_setprio 0
	global_load_dwordx4 v[224:227], v[144:145], off offset:3840
	global_load_dwordx4 v[228:231], v[146:147], off offset:3840
	s_waitcnt vmcnt(9)
	ds_write_b128 v156, v[194:197]
	s_waitcnt vmcnt(8)
	ds_write_b128 v155, v[198:201]
	ds_read_b128 v[160:163], v152 offset:36960
	ds_read_b128 v[164:167], v152 offset:41568
	ds_read_b128 v[168:171], v151 offset:96
	ds_read_b128 v[172:175], v151 offset:4704
	s_setprio 1
	s_waitcnt lgkmcnt(1)
	v_mfma_f32_32x32x16_bf16 v[96:111], v[160:163], v[168:171], v[96:111]
	v_mfma_f32_32x32x16_bf16 v[112:127], v[164:167], v[168:171], v[112:127]
	s_waitcnt lgkmcnt(0)
	v_mfma_f32_32x32x16_bf16 v[64:79], v[160:163], v[172:175], v[64:79]
	v_mfma_f32_32x32x16_bf16 v[80:95], v[164:167], v[172:175], v[80:95]
	ds_read_b128 v[168:171], v151 offset:9312
	ds_read_b128 v[172:175], v151 offset:13920
	s_waitcnt lgkmcnt(1)
	v_mfma_f32_32x32x16_bf16 v[32:47], v[160:163], v[168:171], v[32:47]
	v_mfma_f32_32x32x16_bf16 v[48:63], v[164:167], v[168:171], v[48:63]
	s_waitcnt lgkmcnt(0)
	v_mfma_f32_32x32x16_bf16 v[0:15], v[160:163], v[172:175], v[0:15]
	v_mfma_f32_32x32x16_bf16 v[16:31], v[164:167], v[172:175], v[16:31]
	s_setprio 0
	s_barrier
; template <bool trans>
; DI void gemm_core(const GTile& tl, const GTile& nx, bool has_next  , bool chain  , bool pre, u32x4 (&ra)[4], u32x4 (&rb)[4], char* smem, f32x16 (&acc)[2][4]) {
;     ...
;   const int nk = K / 64;
;   if (!pre) { G_LOAD(0); G_STORE(0); G_LOAD(1); }
;   for (int kt = 0; kt < nk; ++kt) {
;     __syncthreads();
;     G_COMPUTE(kt & 1, kt);
;   }
	global_load_dwordx4 v[160:163], v[136:137], off offset:3968
	global_load_dwordx4 v[164:167], v[138:139], off offset:3968
	s_waitcnt vmcnt(9)
	ds_write_b128 v148, v[176:179]
	s_waitcnt vmcnt(8)
	ds_write_b128 v148, v[180:183] offset:36864
	ds_read_b128 v[136:139], v150
	ds_read_b128 v[168:171], v150 offset:4608
	ds_read_b128 v[172:175], v149
	ds_read_b128 v[176:179], v149 offset:4608
	s_setprio 1
	s_waitcnt lgkmcnt(1)
	v_mfma_f32_32x32x16_bf16 v[96:111], v[136:139], v[172:175], v[96:111]
	v_mfma_f32_32x32x16_bf16 v[112:127], v[168:171], v[172:175], v[112:127]
	s_waitcnt lgkmcnt(0)
	v_mfma_f32_32x32x16_bf16 v[64:79], v[136:139], v[176:179], v[64:79]
	v_mfma_f32_32x32x16_bf16 v[80:95], v[168:171], v[176:179], v[80:95]
	ds_read_b128 v[172:175], v149 offset:9216
	ds_read_b128 v[176:179], v149 offset:13824
	s_waitcnt lgkmcnt(1)
	v_mfma_f32_32x32x16_bf16 v[32:47], v[136:139], v[172:175], v[32:47]
	v_mfma_f32_32x32x16_bf16 v[48:63], v[168:171], v[172:175], v[48:63]
	s_waitcnt lgkmcnt(0)
	v_mfma_f32_32x32x16_bf16 v[0:15], v[136:139], v[176:179], v[0:15]
	v_mfma_f32_32x32x16_bf16 v[16:31], v[168:171], v[176:179], v[16:31]
	s_setprio 0
	global_load_dwordx4 v[168:171], v[140:141], off offset:3968
	global_load_dwordx4 v[172:175], v[142:143], off offset:3968
	s_waitcnt vmcnt(9)
	ds_write_b128 v148, v[208:211] offset:9216
	s_waitcnt vmcnt(8)
	ds_write_b128 v148, v[212:215] offset:46080
	ds_read_b128 v[136:139], v150 offset:32
	ds_read_b128 v[140:143], v150 offset:4640
	ds_read_b128 v[176:179], v149 offset:32
	ds_read_b128 v[180:183], v149 offset:4640
	s_setprio 1
	s_waitcnt lgkmcnt(1)
	v_mfma_f32_32x32x16_bf16 v[96:111], v[136:139], v[176:179], v[96:111]
	v_mfma_f32_32x32x16_bf16 v[112:127], v[140:143], v[176:179], v[112:127]
	s_waitcnt lgkmcnt(0)
	v_mfma_f32_32x32x16_bf16 v[64:79], v[136:139], v[180:183], v[64:79]
	v_mfma_f32_32x32x16_bf16 v[80:95], v[140:143], v[180:183], v[80:95]
	ds_read_b128 v[176:179], v149 offset:9248
	ds_read_b128 v[180:183], v149 offset:13856
	s_waitcnt lgkmcnt(1)
	v_mfma_f32_32x32x16_bf16 v[32:47], v[136:139], v[176:179], v[32:47]
	v_mfma_f32_32x32x16_bf16 v[48:63], v[140:143], v[176:179], v[48:63]
	s_waitcnt lgkmcnt(0)
	v_mfma_f32_32x32x16_bf16 v[0:15], v[136:139], v[180:183], v[0:15]
	v_mfma_f32_32x32x16_bf16 v[16:31], v[140:143], v[180:183], v[16:31]
	s_setprio 0
	global_load_dwordx4 v[176:179], v[132:133], off offset:3968
	global_load_dwordx4 v[180:183], v[134:135], off offset:3968
	s_waitcnt vmcnt(9)
	ds_write_b128 v148, v[216:219] offset:18432
	s_waitcnt vmcnt(8)
	ds_write_b128 v148, v[220:223] offset:55296
	ds_read_b128 v[132:135], v150 offset:64
	ds_read_b128 v[136:139], v150 offset:4672
	ds_read_b128 v[140:143], v149 offset:64
	ds_read_b128 v[184:187], v149 offset:4672
	s_setprio 1
	s_waitcnt lgkmcnt(1)
	v_mfma_f32_32x32x16_bf16 v[96:111], v[132:135], v[140:143], v[96:111]
	v_mfma_f32_32x32x16_bf16 v[112:127], v[136:139], v[140:143], v[112:127]
	s_waitcnt lgkmcnt(0)
	v_mfma_f32_32x32x16_bf16 v[64:79], v[132:135], v[184:187], v[64:79]
	v_mfma_f32_32x32x16_bf16 v[80:95], v[136:139], v[184:187], v[80:95]
	ds_read_b128 v[140:143], v149 offset:9280
	ds_read_b128 v[184:187], v149 offset:13888
	s_waitcnt lgkmcnt(1)
	v_mfma_f32_32x32x16_bf16 v[32:47], v[132:135], v[140:143], v[32:47]
	v_mfma_f32_32x32x16_bf16 v[48:63], v[136:139], v[140:143], v[48:63]
	s_waitcnt lgkmcnt(0)
	v_mfma_f32_32x32x16_bf16 v[0:15], v[132:135], v[184:187], v[0:15]
	v_mfma_f32_32x32x16_bf16 v[16:31], v[136:139], v[184:187], v[16:31]
	s_setprio 0
	global_load_dwordx4 v[184:187], v[144:145], off offset:3968
	global_load_dwordx4 v[188:191], v[146:147], off offset:3968
	s_waitcnt vmcnt(9)
	ds_write_b128 v148, v[224:227] offset:27648
	s_waitcnt vmcnt(8)
	ds_write_b128 v148, v[228:231] offset:64512
	ds_read_b128 v[132:135], v150 offset:96
	ds_read_b128 v[136:139], v150 offset:4704
	ds_read_b128 v[140:143], v149 offset:96
	ds_read_b128 v[144:147], v149 offset:4704
	s_setprio 1
	s_waitcnt lgkmcnt(1)
	v_mfma_f32_32x32x16_bf16 v[96:111], v[132:135], v[140:143], v[96:111]
	v_mfma_f32_32x32x16_bf16 v[112:127], v[136:139], v[140:143], v[112:127]
	s_waitcnt lgkmcnt(0)
	v_mfma_f32_32x32x16_bf16 v[64:79], v[132:135], v[144:147], v[64:79]
	v_mfma_f32_32x32x16_bf16 v[80:95], v[136:139], v[144:147], v[80:95]
	ds_read_b128 v[140:143], v149 offset:9312
	ds_read_b128 v[144:147], v149 offset:13920
	s_waitcnt lgkmcnt(1)
	v_mfma_f32_32x32x16_bf16 v[32:47], v[132:135], v[140:143], v[32:47]
	v_mfma_f32_32x32x16_bf16 v[48:63], v[136:139], v[140:143], v[48:63]
	s_waitcnt lgkmcnt(0)
	v_mfma_f32_32x32x16_bf16 v[0:15], v[132:135], v[144:147], v[0:15]
	v_mfma_f32_32x32x16_bf16 v[16:31], v[136:139], v[144:147], v[16:31]
	s_setprio 0
	v_cndmask_b32_e64 v132, 0, 1, s[34:35]
	v_cmp_ne_u32_e64 s[6:7], 1, v132
	s_andn2_b64 vcc, exec, s[34:35]
	s_barrier
	s_waitcnt vmcnt(7)
	ds_write_b128 v192, v[160:163]
	s_waitcnt vmcnt(6)
	ds_write_b128 v159, v[164:167]
	s_cbranch_vccnz .LBB0_892
	global_load_dwordx4 v[160:163], v[130:131], off
	global_load_dwordx4 v[164:167], v[128:129], off

;   DI bf16_t* h() const { return (bf16_t*)(ws + OFF_H); }
; template <bool trans>
; DI void gemm_core(const GTile& tl, const GTile& nx, bool has_next  , bool chain  , bool pre, u32x4 (&ra)[4], u32x4 (&rb)[4], char* smem, f32x16 (&acc)[2][4]) {
;     ...
;   const int nk = K / 64;
;   if (!pre) { G_LOAD(0); G_STORE(0); G_LOAD(1); }
;   for (int kt = 0; kt < nk; ++kt) {
;     __syncthreads();
;     G_COMPUTE(kt & 1, kt);
; DI void phase_gemm_out(const Params& p, char* smem, const bf16_t* Wt, const float* R, float* O) {
;     ...
;   for (int t = blockIdx.x; t < 64 * 8; t += gridDim.x) {
;     const int mt = t & 63, nt = t >> 6, tn = t + gridDim.x;
;     const bool has_next = tn < 64 * 8;
;     const GTile tl{p.h(), D, Wt, D, D, mt * 256, nt * 256}, nx{p.h(), D, Wt, D, D, (tn & 63) * 256, (tn >> 6) * 256};
.LBB0_1637:
	v_lshl_add_u64 v[128:129], s[2:3], 0, v[184:185]
	v_lshl_add_u64 v[132:133], s[4:5], 0, v[184:185]
	s_waitcnt lgkmcnt(0)
	s_barrier
	global_load_dwordx4 v[200:203], v[128:129], off offset:256
	global_load_dwordx4 v[208:211], v[132:133], off offset:256
	s_add_i32 s84, s84, s96
	s_cmpk_lt_i32 s84, 0x200
	s_cselect_b64 s[12:13], -1, 0
	s_cmpk_gt_i32 s84, 0x1ff
	s_cselect_b64 s[10:11], -1, 0
	s_and_b32 s3, s24, 0x1f80000
	s_add_i32 s16, s17, s16
	s_and_b32 s2, s16, 0xffffff00
	s_and_b32 s38, s37, 0xc0
	s_lshl_b32 s3, s3, 1
	s_add_u32 s4, s28, s3
	s_addc_u32 s5, s29, 0
	s_ashr_i32 s3, s2, 31
	s_lshl_b64 s[2:3], s[2:3], 12
	s_add_u32 s2, s14, s2
	s_addc_u32 s3, s15, s3
	s_lshr_b32 s37, s37, 1
	v_and_b32_e32 v11, 31, v8
	s_and_b32 s37, s37, 0xfffff80
	v_or_b32_e32 v12, s37, v11
	v_or_b32_e32 v11, s38, v11
	v_add3_u32 v191, 16, v10, v9
	v_lshrrev_b32_e32 v8, 1, v8
	v_mul_u32_u24_e32 v131, 0x90, v11
	v_and_b32_e32 v134, 16, v8
	v_add_u32_e32 v195, 0x12000, v191
	v_mul_lo_u32 v130, v12, s33
	v_add3_u32 v192, 16, v131, v134
	v_add_u32_e32 v196, 0x1b000, v191
	ds_write_b128 v195, v[0:3]
	s_waitcnt vmcnt(5)
	ds_write_b128 v196, v[4:7]
	v_lshl_add_u64 v[188:189], s[4:5], 0, v[184:185]
	v_lshl_add_u64 v[186:187], s[2:3], 0, v[184:185]
	v_add3_u32 v184, 16, v130, v134
	ds_read_b128 v[0:3], v192 offset:36864
	ds_read_b128 v[4:7], v192 offset:41472
	ds_read_b128 v[8:11], v184
	ds_read_b128 v[12:15], v184 offset:4608
	v_lshl_add_u64 v[136:137], v[128:129], 0, s[0:1]
	v_lshl_add_u64 v[140:141], v[132:133], 0, s[0:1]
	v_lshl_add_u64 v[144:145], v[128:129], 0, s[6:7]
	v_lshl_add_u64 v[148:149], v[132:133], 0, s[6:7]
	s_setprio 1
	s_waitcnt lgkmcnt(1)
	v_mfma_f32_32x32x16_bf16 v[112:127], v[0:3], v[8:11], 0
	v_mfma_f32_32x32x16_bf16 v[48:63], v[4:7], v[8:11], 0
	s_waitcnt lgkmcnt(0)
	v_mfma_f32_32x32x16_bf16 v[96:111], v[0:3], v[12:15], 0
	v_mfma_f32_32x32x16_bf16 v[32:47], v[4:7], v[12:15], 0
	ds_read_b128 v[8:11], v184 offset:9216
	ds_read_b128 v[12:15], v184 offset:13824
	s_waitcnt lgkmcnt(1)
	v_mfma_f32_32x32x16_bf16 v[80:95], v[0:3], v[8:11], 0
	v_mfma_f32_32x32x16_bf16 v[16:31], v[4:7], v[8:11], 0
	s_waitcnt lgkmcnt(0)
	v_mfma_f32_32x32x16_bf16 v[64:79], v[0:3], v[12:15], 0
	v_mfma_f32_32x32x16_bf16 v[0:15], v[4:7], v[12:15], 0
	s_setprio 0
	global_load_dwordx4 v[212:215], v[136:137], off offset:256
	global_load_dwordx4 v[216:219], v[140:141], off offset:256
	v_add_u32_e32 v194, 0x14400, v191
	v_add_u32_e32 v193, 0x1d400, v191
	ds_write_b128 v194, v[176:179]
	s_waitcnt vmcnt(6)
	ds_write_b128 v193, v[180:183]
	ds_read_b128 v[150:153], v192 offset:36896
	ds_read_b128 v[154:157], v192 offset:41504
	ds_read_b128 v[176:179], v184 offset:32
	ds_read_b128 v[180:183], v184 offset:4640
	s_setprio 1
	s_waitcnt lgkmcnt(1)
	v_mfma_f32_32x32x16_bf16 v[112:127], v[150:153], v[176:179], v[112:127]
	v_mfma_f32_32x32x16_bf16 v[48:63], v[154:157], v[176:179], v[48:63]
	s_waitcnt lgkmcnt(0)
	v_mfma_f32_32x32x16_bf16 v[96:111], v[150:153], v[180:183], v[96:111]
	v_mfma_f32_32x32x16_bf16 v[32:47], v[154:157], v[180:183], v[32:47]
	ds_read_b128 v[176:179], v184 offset:9248
	ds_read_b128 v[180:183], v184 offset:13856
	s_waitcnt lgkmcnt(1)
	v_mfma_f32_32x32x16_bf16 v[80:95], v[150:153], v[176:179], v[80:95]
	v_mfma_f32_32x32x16_bf16 v[16:31], v[154:157], v[176:179], v[16:31]
	s_waitcnt lgkmcnt(0)
	v_mfma_f32_32x32x16_bf16 v[64:79], v[150:153], v[180:183], v[64:79]
	v_mfma_f32_32x32x16_bf16 v[0:15], v[154:157], v[180:183], v[0:15]
	s_setprio 0
	global_load_dwordx4 v[178:181], v[144:145], off offset:256
	global_load_dwordx4 v[220:223], v[148:149], off offset:256
	v_add_u32_e32 v177, 0x16800, v191
	v_add_u32_e32 v176, 0x1f800, v191
	ds_write_b128 v177, v[168:171]
	s_waitcnt vmcnt(7)
	ds_write_b128 v176, v[172:175]
	ds_read_b128 v[150:153], v192 offset:36928
	ds_read_b128 v[154:157], v192 offset:41536
	ds_read_b128 v[168:171], v184 offset:64
	ds_read_b128 v[172:175], v184 offset:4672
	s_setprio 1
	s_waitcnt lgkmcnt(1)
	v_mfma_f32_32x32x16_bf16 v[112:127], v[150:153], v[168:171], v[112:127]
	v_mfma_f32_32x32x16_bf16 v[48:63], v[154:157], v[168:171], v[48:63]
	s_waitcnt lgkmcnt(0)
	v_mfma_f32_32x32x16_bf16 v[96:111], v[150:153], v[172:175], v[96:111]
	v_mfma_f32_32x32x16_bf16 v[32:47], v[154:157], v[172:175], v[32:47]
	ds_read_b128 v[168:171], v184 offset:9280
	ds_read_b128 v[172:175], v184 offset:13888
	s_waitcnt lgkmcnt(1)
	v_mfma_f32_32x32x16_bf16 v[80:95], v[150:153], v[168:171], v[80:95]
	v_mfma_f32_32x32x16_bf16 v[16:31], v[154:157], v[168:171], v[16:31]
	s_waitcnt lgkmcnt(0)
	v_mfma_f32_32x32x16_bf16 v[64:79], v[150:153], v[172:175], v[64:79]
	v_mfma_f32_32x32x16_bf16 v[0:15], v[154:157], v[172:175], v[0:15]
	s_setprio 0
	v_add_co_u32_e32 v152, vcc, s31, v128
	v_add_u32_e32 v171, 0x18c00, v191
	s_nop 0
	v_addc_co_u32_e32 v153, vcc, 0, v129, vcc
	v_add_co_u32_e32 v156, vcc, s31, v132
	v_add_u32_e32 v170, 0x21c00, v191
	s_nop 0
	v_addc_co_u32_e32 v157, vcc, 0, v133, vcc
	global_load_dwordx4 v[172:175], v[152:153], off offset:256
	global_load_dwordx4 v[224:227], v[156:157], off offset:256
	ds_write_b128 v171, v[160:163]
	s_waitcnt vmcnt(8)
	ds_write_b128 v170, v[164:167]
	ds_read_b128 v[158:161], v192 offset:36960
	ds_read_b128 v[162:165], v192 offset:41568
	ds_read_b128 v[166:169], v184 offset:96
	ds_read_b128 v[228:231], v184 offset:4704
	s_setprio 1
	s_waitcnt lgkmcnt(1)
	v_mfma_f32_32x32x16_bf16 v[112:127], v[158:161], v[166:169], v[112:127]
	v_mfma_f32_32x32x16_bf16 v[48:63], v[162:165], v[166:169], v[48:63]
	s_waitcnt lgkmcnt(0)
	v_mfma_f32_32x32x16_bf16 v[96:111], v[158:161], v[228:231], v[96:111]
	v_mfma_f32_32x32x16_bf16 v[32:47], v[162:165], v[228:231], v[32:47]
	ds_read_b128 v[166:169], v184 offset:9312
	ds_read_b128 v[228:231], v184 offset:13920
	s_waitcnt lgkmcnt(1)
	v_mfma_f32_32x32x16_bf16 v[80:95], v[158:161], v[166:169], v[80:95]
	v_mfma_f32_32x32x16_bf16 v[16:31], v[162:165], v[166:169], v[16:31]
	s_waitcnt lgkmcnt(0)
	v_mfma_f32_32x32x16_bf16 v[64:79], v[158:161], v[228:231], v[64:79]
	v_mfma_f32_32x32x16_bf16 v[0:15], v[162:165], v[228:231], v[0:15]
	s_setprio 0
	s_barrier
	global_load_dwordx4 v[158:161], v[128:129], off offset:384
	global_load_dwordx4 v[162:165], v[132:133], off offset:384
	v_add3_u32 v169, s35, v131, v134
	s_waitcnt vmcnt(9)
	ds_write_b128 v191, v[200:203]
	s_waitcnt vmcnt(8)
	ds_write_b128 v191, v[208:211] offset:36864
	v_add3_u32 v168, s34, v130, v134
	ds_read_b128 v[200:203], v169
	ds_read_b128 v[208:211], v169 offset:4608
	ds_read_b128 v[228:231], v168
	ds_read_b128 v[232:235], v168 offset:4608
	s_setprio 1
	s_waitcnt lgkmcnt(1)
	v_mfma_f32_32x32x16_bf16 v[112:127], v[200:203], v[228:231], v[112:127]
	v_mfma_f32_32x32x16_bf16 v[48:63], v[208:211], v[228:231], v[48:63]
	s_waitcnt lgkmcnt(0)
	v_mfma_f32_32x32x16_bf16 v[96:111], v[200:203], v[232:235], v[96:111]
	v_mfma_f32_32x32x16_bf16 v[32:47], v[208:211], v[232:235], v[32:47]
	ds_read_b128 v[228:231], v168 offset:9216
	ds_read_b128 v[232:235], v168 offset:13824
	s_waitcnt lgkmcnt(1)
	v_mfma_f32_32x32x16_bf16 v[80:95], v[200:203], v[228:231], v[80:95]
	v_mfma_f32_32x32x16_bf16 v[16:31], v[208:211], v[228:231], v[16:31]
	s_waitcnt lgkmcnt(0)
	v_mfma_f32_32x32x16_bf16 v[64:79], v[200:203], v[232:235], v[64:79]
	v_mfma_f32_32x32x16_bf16 v[0:15], v[208:211], v[232:235], v[0:15]
	s_setprio 0
	global_load_dwordx4 v[200:203], v[136:137], off offset:384
	global_load_dwordx4 v[208:211], v[140:141], off offset:384
	s_waitcnt vmcnt(9)
	ds_write_b128 v191, v[212:215] offset:9216
	s_waitcnt vmcnt(8)
	ds_write_b128 v191, v[216:219] offset:46080
	ds_read_b128 v[212:215], v169 offset:32
	ds_read_b128 v[216:219], v169 offset:4640
	ds_read_b128 v[228:231], v168 offset:32
	ds_read_b128 v[232:235], v168 offset:4640
	s_setprio 1
	s_waitcnt lgkmcnt(1)
	v_mfma_f32_32x32x16_bf16 v[112:127], v[212:215], v[228:231], v[112:127]
	v_mfma_f32_32x32x16_bf16 v[48:63], v[216:219], v[228:231], v[48:63]
	s_waitcnt lgkmcnt(0)
	v_mfma_f32_32x32x16_bf16 v[96:111], v[212:215], v[232:235], v[96:111]
	v_mfma_f32_32x32x16_bf16 v[32:47], v[216:219], v[232:235], v[32:47]
	ds_read_b128 v[228:231], v168 offset:9248
	ds_read_b128 v[232:235], v168 offset:13856
	s_waitcnt lgkmcnt(1)
	v_mfma_f32_32x32x16_bf16 v[80:95], v[212:215], v[228:231], v[80:95]
	v_mfma_f32_32x32x16_bf16 v[16:31], v[216:219], v[228:231], v[16:31]
	s_waitcnt lgkmcnt(0)
	v_mfma_f32_32x32x16_bf16 v[64:79], v[212:215], v[232:235], v[64:79]
	v_mfma_f32_32x32x16_bf16 v[0:15], v[216:219], v[232:235], v[0:15]
	s_setprio 0
	global_load_dwordx4 v[212:215], v[144:145], off offset:384
	global_load_dwordx4 v[216:219], v[148:149], off offset:384
	s_waitcnt vmcnt(9)
	ds_write_b128 v191, v[178:181] offset:18432
	s_waitcnt vmcnt(8)
	ds_write_b128 v191, v[220:223] offset:55296
	ds_read_b128 v[178:181], v169 offset:64
	ds_read_b128 v[220:223], v169 offset:4672
	ds_read_b128 v[228:231], v168 offset:64
	ds_read_b128 v[232:235], v168 offset:4672
	s_setprio 1
	s_waitcnt lgkmcnt(1)
	v_mfma_f32_32x32x16_bf16 v[112:127], v[178:181], v[228:231], v[112:127]
	v_mfma_f32_32x32x16_bf16 v[48:63], v[220:223], v[228:231], v[48:63]
	s_waitcnt lgkmcnt(0)
	v_mfma_f32_32x32x16_bf16 v[96:111], v[178:181], v[232:235], v[96:111]
	v_mfma_f32_32x32x16_bf16 v[32:47], v[220:223], v[232:235], v[32:47]
	ds_read_b128 v[228:231], v168 offset:9280
	ds_read_b128 v[232:235], v168 offset:13888
	s_waitcnt lgkmcnt(1)
	v_mfma_f32_32x32x16_bf16 v[80:95], v[178:181], v[228:231], v[80:95]
	v_mfma_f32_32x32x16_bf16 v[16:31], v[220:223], v[228:231], v[16:31]
	s_waitcnt lgkmcnt(0)
	v_mfma_f32_32x32x16_bf16 v[64:79], v[178:181], v[232:235], v[64:79]
	v_mfma_f32_32x32x16_bf16 v[0:15], v[220:223], v[232:235], v[0:15]
	s_setprio 0
	global_load_dwordx4 v[178:181], v[152:153], off offset:384
	global_load_dwordx4 v[220:223], v[156:157], off offset:384
	s_waitcnt vmcnt(9)
	ds_write_b128 v191, v[172:175] offset:27648
	s_waitcnt vmcnt(8)
	ds_write_b128 v191, v[224:227] offset:64512
	ds_read_b128 v[172:175], v169 offset:96
	ds_read_b128 v[224:227], v169 offset:4704
	ds_read_b128 v[228:231], v168 offset:96
	ds_read_b128 v[232:235], v168 offset:4704
	s_setprio 1
	s_waitcnt lgkmcnt(1)
	v_mfma_f32_32x32x16_bf16 v[112:127], v[172:175], v[228:231], v[112:127]
	v_mfma_f32_32x32x16_bf16 v[48:63], v[224:227], v[228:231], v[48:63]
	s_waitcnt lgkmcnt(0)
	v_mfma_f32_32x32x16_bf16 v[96:111], v[172:175], v[232:235], v[96:111]
	v_mfma_f32_32x32x16_bf16 v[32:47], v[224:227], v[232:235], v[32:47]
	ds_read_b128 v[228:231], v168 offset:9312
	ds_read_b128 v[232:235], v168 offset:13920
	s_waitcnt lgkmcnt(1)
	v_mfma_f32_32x32x16_bf16 v[80:95], v[172:175], v[228:231], v[80:95]
	v_mfma_f32_32x32x16_bf16 v[16:31], v[224:227], v[228:231], v[16:31]
	s_waitcnt lgkmcnt(0)
	v_mfma_f32_32x32x16_bf16 v[64:79], v[172:175], v[232:235], v[64:79]
	v_mfma_f32_32x32x16_bf16 v[0:15], v[224:227], v[232:235], v[0:15]
	s_setprio 0
	s_barrier
	global_load_dwordx4 v[172:175], v[128:129], off offset:512
	global_load_dwordx4 v[224:227], v[132:133], off offset:512
	s_waitcnt vmcnt(9)
	ds_write_b128 v195, v[158:161]
	s_waitcnt vmcnt(8)
	ds_write_b128 v196, v[162:165]
	ds_read_b128 v[158:161], v192 offset:36864
	ds_read_b128 v[162:165], v192 offset:41472
	ds_read_b128 v[228:231], v184
	ds_read_b128 v[232:235], v184 offset:4608
	s_setprio 1
	s_waitcnt lgkmcnt(1)
	v_mfma_f32_32x32x16_bf16 v[112:127], v[158:161], v[228:231], v[112:127]
	v_mfma_f32_32x32x16_bf16 v[48:63], v[162:165], v[228:231], v[48:63]
	s_waitcnt lgkmcnt(0)
	v_mfma_f32_32x32x16_bf16 v[96:111], v[158:161], v[232:235], v[96:111]
	v_mfma_f32_32x32x16_bf16 v[32:47], v[162:165], v[232:235], v[32:47]
	ds_read_b128 v[228:231], v184 offset:9216
	ds_read_b128 v[232:235], v184 offset:13824
	s_waitcnt vmcnt(7)
	ds_write_b128 v194, v[200:203]
	s_waitcnt vmcnt(6)
	ds_write_b128 v193, v[208:211]
	ds_read_b128 v[200:203], v192 offset:36896
	ds_read_b128 v[208:211], v192 offset:41504
	s_waitcnt lgkmcnt(5)
	v_mfma_f32_32x32x16_bf16 v[80:95], v[158:161], v[228:231], v[80:95]
	v_mfma_f32_32x32x16_bf16 v[16:31], v[162:165], v[228:231], v[16:31]
	ds_read_b128 v[228:231], v184 offset:32
	s_waitcnt lgkmcnt(5)
	v_mfma_f32_32x32x16_bf16 v[64:79], v[158:161], v[232:235], v[64:79]
	v_mfma_f32_32x32x16_bf16 v[0:15], v[162:165], v[232:235], v[0:15]
	ds_read_b128 v[232:235], v184 offset:4640
	s_setprio 0
	global_load_dwordx4 v[158:161], v[136:137], off offset:512
	global_load_dwordx4 v[162:165], v[140:141], off offset:512
	s_setprio 1
	s_waitcnt lgkmcnt(1)
	v_mfma_f32_32x32x16_bf16 v[112:127], v[200:203], v[228:231], v[112:127]
	v_mfma_f32_32x32x16_bf16 v[48:63], v[208:211], v[228:231], v[48:63]
	s_waitcnt lgkmcnt(0)
	v_mfma_f32_32x32x16_bf16 v[96:111], v[200:203], v[232:235], v[96:111]
	v_mfma_f32_32x32x16_bf16 v[32:47], v[208:211], v[232:235], v[32:47]
	ds_read_b128 v[228:231], v184 offset:9248
	ds_read_b128 v[232:235], v184 offset:13856
	s_waitcnt vmcnt(7)
	ds_write_b128 v177, v[212:215]
	s_waitcnt vmcnt(6)
	ds_write_b128 v176, v[216:219]
	ds_read_b128 v[212:215], v192 offset:36928
	ds_read_b128 v[216:219], v192 offset:41536
	s_waitcnt lgkmcnt(5)
	v_mfma_f32_32x32x16_bf16 v[80:95], v[200:203], v[228:231], v[80:95]
	v_mfma_f32_32x32x16_bf16 v[16:31], v[208:211], v[228:231], v[16:31]
	ds_read_b128 v[228:231], v184 offset:64
	s_waitcnt lgkmcnt(5)
	v_mfma_f32_32x32x16_bf16 v[64:79], v[200:203], v[232:235], v[64:79]
	v_mfma_f32_32x32x16_bf16 v[0:15], v[208:211], v[232:235], v[0:15]
	ds_read_b128 v[232:235], v184 offset:4672
	s_setprio 0
	global_load_dwordx4 v[200:203], v[144:145], off offset:512
	global_load_dwordx4 v[208:211], v[148:149], off offset:512
	s_setprio 1
	s_waitcnt lgkmcnt(1)
	v_mfma_f32_32x32x16_bf16 v[112:127], v[212:215], v[228:231], v[112:127]
	v_mfma_f32_32x32x16_bf16 v[48:63], v[216:219], v[228:231], v[48:63]
	s_waitcnt lgkmcnt(0)
	v_mfma_f32_32x32x16_bf16 v[96:111], v[212:215], v[232:235], v[96:111]
	v_mfma_f32_32x32x16_bf16 v[32:47], v[216:219], v[232:235], v[32:47]
	ds_read_b128 v[228:231], v184 offset:9280
	ds_read_b128 v[232:235], v184 offset:13888
	s_waitcnt vmcnt(7)
	ds_write_b128 v171, v[178:181]
	s_waitcnt vmcnt(6)
	ds_write_b128 v170, v[220:223]
	ds_read_b128 v[178:181], v192 offset:36960
	ds_read_b128 v[220:223], v192 offset:41568
	s_waitcnt lgkmcnt(5)
	v_mfma_f32_32x32x16_bf16 v[80:95], v[212:215], v[228:231], v[80:95]
	v_mfma_f32_32x32x16_bf16 v[16:31], v[216:219], v[228:231], v[16:31]
	ds_read_b128 v[228:231], v184 offset:96
	s_waitcnt lgkmcnt(5)
	v_mfma_f32_32x32x16_bf16 v[64:79], v[212:215], v[232:235], v[64:79]
	v_mfma_f32_32x32x16_bf16 v[0:15], v[216:219], v[232:235], v[0:15]
	ds_read_b128 v[232:235], v184 offset:4704
	s_setprio 0
	global_load_dwordx4 v[212:215], v[152:153], off offset:512
	global_load_dwordx4 v[216:219], v[156:157], off offset:512
	s_setprio 1
	s_waitcnt lgkmcnt(1)
	v_mfma_f32_32x32x16_bf16 v[112:127], v[178:181], v[228:231], v[112:127]
	v_mfma_f32_32x32x16_bf16 v[48:63], v[220:223], v[228:231], v[48:63]
	s_waitcnt lgkmcnt(0)
	v_mfma_f32_32x32x16_bf16 v[96:111], v[178:181], v[232:235], v[96:111]
	v_mfma_f32_32x32x16_bf16 v[32:47], v[220:223], v[232:235], v[32:47]
	ds_read_b128 v[228:231], v184 offset:9312
	ds_read_b128 v[232:235], v184 offset:13920
	s_waitcnt lgkmcnt(1)
	v_mfma_f32_32x32x16_bf16 v[80:95], v[178:181], v[228:231], v[80:95]
	v_mfma_f32_32x32x16_bf16 v[16:31], v[220:223], v[228:231], v[16:31]
	s_waitcnt lgkmcnt(0)
	v_mfma_f32_32x32x16_bf16 v[64:79], v[178:181], v[232:235], v[64:79]
	v_mfma_f32_32x32x16_bf16 v[0:15], v[220:223], v[232:235], v[0:15]
	s_setprio 0
	s_barrier
	global_load_dwordx4 v[178:181], v[128:129], off offset:640
	global_load_dwordx4 v[220:223], v[132:133], off offset:640
	s_waitcnt vmcnt(9)
	ds_write_b128 v191, v[172:175]
	s_waitcnt vmcnt(8)
	ds_write_b128 v191, v[224:227] offset:36864
	ds_read_b128 v[172:175], v169
	ds_read_b128 v[224:227], v169 offset:4608
	ds_read_b128 v[228:231], v168
	ds_read_b128 v[232:235], v168 offset:4608
	s_setprio 1
	s_waitcnt lgkmcnt(1)
	v_mfma_f32_32x32x16_bf16 v[112:127], v[172:175], v[228:231], v[112:127]
	v_mfma_f32_32x32x16_bf16 v[48:63], v[224:227], v[228:231], v[48:63]
	s_waitcnt lgkmcnt(0)
	v_mfma_f32_32x32x16_bf16 v[96:111], v[172:175], v[232:235], v[96:111]
	v_mfma_f32_32x32x16_bf16 v[32:47], v[224:227], v[232:235], v[32:47]
	ds_read_b128 v[228:231], v168 offset:9216
	ds_read_b128 v[232:235], v168 offset:13824
	s_waitcnt vmcnt(7)
	ds_write_b128 v191, v[158:161] offset:9216
	s_waitcnt vmcnt(6)
	ds_write_b128 v191, v[162:165] offset:46080
	ds_read_b128 v[158:161], v169 offset:32
	ds_read_b128 v[162:165], v169 offset:4640
	s_waitcnt lgkmcnt(5)
	v_mfma_f32_32x32x16_bf16 v[80:95], v[172:175], v[228:231], v[80:95]
	v_mfma_f32_32x32x16_bf16 v[16:31], v[224:227], v[228:231], v[16:31]
	ds_read_b128 v[228:231], v168 offset:32
	s_waitcnt lgkmcnt(5)
	v_mfma_f32_32x32x16_bf16 v[64:79], v[172:175], v[232:235], v[64:79]
	v_mfma_f32_32x32x16_bf16 v[0:15], v[224:227], v[232:235], v[0:15]
	ds_read_b128 v[232:235], v168 offset:4640
	s_setprio 0
	global_load_dwordx4 v[172:175], v[136:137], off offset:640
	global_load_dwordx4 v[224:227], v[140:141], off offset:640
	s_setprio 1
	s_waitcnt lgkmcnt(1)
	v_mfma_f32_32x32x16_bf16 v[112:127], v[158:161], v[228:231], v[112:127]
	v_mfma_f32_32x32x16_bf16 v[48:63], v[162:165], v[228:231], v[48:63]
	s_waitcnt lgkmcnt(0)
	v_mfma_f32_32x32x16_bf16 v[96:111], v[158:161], v[232:235], v[96:111]
	v_mfma_f32_32x32x16_bf16 v[32:47], v[162:165], v[232:235], v[32:47]
	ds_read_b128 v[228:231], v168 offset:9248
	ds_read_b128 v[232:235], v168 offset:13856
	s_waitcnt vmcnt(7)
	ds_write_b128 v191, v[200:203] offset:18432
	s_waitcnt vmcnt(6)
	ds_write_b128 v191, v[208:211] offset:55296
	ds_read_b128 v[200:203], v169 offset:64
	ds_read_b128 v[208:211], v169 offset:4672
	s_waitcnt lgkmcnt(5)
	v_mfma_f32_32x32x16_bf16 v[80:95], v[158:161], v[228:231], v[80:95]
	v_mfma_f32_32x32x16_bf16 v[16:31], v[162:165], v[228:231], v[16:31]
	ds_read_b128 v[228:231], v168 offset:64
	s_waitcnt lgkmcnt(5)
	v_mfma_f32_32x32x16_bf16 v[64:79], v[158:161], v[232:235], v[64:79]
	v_mfma_f32_32x32x16_bf16 v[0:15], v[162:165], v[232:235], v[0:15]
	ds_read_b128 v[232:235], v168 offset:4672
	s_setprio 0
	global_load_dwordx4 v[158:161], v[144:145], off offset:640
	global_load_dwordx4 v[162:165], v[148:149], off offset:640
	s_setprio 1
	s_waitcnt lgkmcnt(1)
	v_mfma_f32_32x32x16_bf16 v[112:127], v[200:203], v[228:231], v[112:127]
	v_mfma_f32_32x32x16_bf16 v[48:63], v[208:211], v[228:231], v[48:63]
	s_waitcnt lgkmcnt(0)
	v_mfma_f32_32x32x16_bf16 v[96:111], v[200:203], v[232:235], v[96:111]
	v_mfma_f32_32x32x16_bf16 v[32:47], v[208:211], v[232:235], v[32:47]
	ds_read_b128 v[228:231], v168 offset:9280
	ds_read_b128 v[232:235], v168 offset:13888
	s_waitcnt vmcnt(7)
	ds_write_b128 v191, v[212:215] offset:27648
	s_waitcnt vmcnt(6)
	ds_write_b128 v191, v[216:219] offset:64512
	ds_read_b128 v[212:215], v169 offset:96
	ds_read_b128 v[216:219], v169 offset:4704
	s_waitcnt lgkmcnt(5)
	v_mfma_f32_32x32x16_bf16 v[80:95], v[200:203], v[228:231], v[80:95]
	v_mfma_f32_32x32x16_bf16 v[16:31], v[208:211], v[228:231], v[16:31]
	ds_read_b128 v[228:231], v168 offset:96
	s_waitcnt lgkmcnt(5)
	v_mfma_f32_32x32x16_bf16 v[64:79], v[200:203], v[232:235], v[64:79]
	v_mfma_f32_32x32x16_bf16 v[0:15], v[208:211], v[232:235], v[0:15]
	ds_read_b128 v[232:235], v168 offset:4704
	s_setprio 0
	global_load_dwordx4 v[200:203], v[152:153], off offset:640
	global_load_dwordx4 v[208:211], v[156:157], off offset:640
	s_setprio 1
	s_waitcnt lgkmcnt(1)
	v_mfma_f32_32x32x16_bf16 v[112:127], v[212:215], v[228:231], v[112:127]
	v_mfma_f32_32x32x16_bf16 v[48:63], v[216:219], v[228:231], v[48:63]
	s_waitcnt lgkmcnt(0)
	v_mfma_f32_32x32x16_bf16 v[96:111], v[212:215], v[232:235], v[96:111]
	v_mfma_f32_32x32x16_bf16 v[32:47], v[216:219], v[232:235], v[32:47]
	ds_read_b128 v[228:231], v168 offset:9312
	ds_read_b128 v[232:235], v168 offset:13920
	s_waitcnt lgkmcnt(1)
	v_mfma_f32_32x32x16_bf16 v[80:95], v[212:215], v[228:231], v[80:95]
	v_mfma_f32_32x32x16_bf16 v[16:31], v[216:219], v[228:231], v[16:31]
	s_waitcnt lgkmcnt(0)
	v_mfma_f32_32x32x16_bf16 v[64:79], v[212:215], v[232:235], v[64:79]
	v_mfma_f32_32x32x16_bf16 v[0:15], v[216:219], v[232:235], v[0:15]
	s_setprio 0
	s_barrier
	global_load_dwordx4 v[212:215], v[128:129], off offset:768
	global_load_dwordx4 v[216:219], v[132:133], off offset:768
	s_waitcnt vmcnt(9)
	ds_write_b128 v195, v[178:181]
	s_waitcnt vmcnt(8)
	ds_write_b128 v196, v[220:223]
	ds_read_b128 v[178:181], v192 offset:36864
	ds_read_b128 v[220:223], v192 offset:41472
	ds_read_b128 v[228:231], v184
	ds_read_b128 v[232:235], v184 offset:4608
	s_setprio 1
	s_waitcnt lgkmcnt(1)
	v_mfma_f32_32x32x16_bf16 v[112:127], v[178:181], v[228:231], v[112:127]
	v_mfma_f32_32x32x16_bf16 v[48:63], v[220:223], v[228:231], v[48:63]
	s_waitcnt lgkmcnt(0)
	v_mfma_f32_32x32x16_bf16 v[96:111], v[178:181], v[232:235], v[96:111]
	v_mfma_f32_32x32x16_bf16 v[32:47], v[220:223], v[232:235], v[32:47]
	ds_read_b128 v[228:231], v184 offset:9216
	ds_read_b128 v[232:235], v184 offset:13824
	s_waitcnt vmcnt(7)
	ds_write_b128 v194, v[172:175]
	s_waitcnt vmcnt(6)
	ds_write_b128 v193, v[224:227]
	ds_read_b128 v[172:175], v192 offset:36896
	ds_read_b128 v[224:227], v192 offset:41504
	s_waitcnt lgkmcnt(5)
	v_mfma_f32_32x32x16_bf16 v[80:95], v[178:181], v[228:231], v[80:95]
	v_mfma_f32_32x32x16_bf16 v[16:31], v[220:223], v[228:231], v[16:31]
	ds_read_b128 v[228:231], v184 offset:32
	s_waitcnt lgkmcnt(5)
	v_mfma_f32_32x32x16_bf16 v[64:79], v[178:181], v[232:235], v[64:79]
	v_mfma_f32_32x32x16_bf16 v[0:15], v[220:223], v[232:235], v[0:15]
	ds_read_b128 v[232:235], v184 offset:4640
	s_setprio 0
	global_load_dwordx4 v[178:181], v[136:137], off offset:768
	global_load_dwordx4 v[220:223], v[140:141], off offset:768
	s_setprio 1
	s_waitcnt lgkmcnt(1)
	v_mfma_f32_32x32x16_bf16 v[112:127], v[172:175], v[228:231], v[112:127]
	v_mfma_f32_32x32x16_bf16 v[48:63], v[224:227], v[228:231], v[48:63]
	s_waitcnt lgkmcnt(0)
	v_mfma_f32_32x32x16_bf16 v[96:111], v[172:175], v[232:235], v[96:111]
	v_mfma_f32_32x32x16_bf16 v[32:47], v[224:227], v[232:235], v[32:47]
	ds_read_b128 v[228:231], v184 offset:9248
	ds_read_b128 v[232:235], v184 offset:13856
	s_waitcnt vmcnt(7)
	ds_write_b128 v177, v[158:161]
	s_waitcnt vmcnt(6)
	ds_write_b128 v176, v[162:165]
	ds_read_b128 v[158:161], v192 offset:36928
	ds_read_b128 v[162:165], v192 offset:41536
	s_waitcnt lgkmcnt(5)
	v_mfma_f32_32x32x16_bf16 v[80:95], v[172:175], v[228:231], v[80:95]
	v_mfma_f32_32x32x16_bf16 v[16:31], v[224:227], v[228:231], v[16:31]
	ds_read_b128 v[228:231], v184 offset:64
	s_waitcnt lgkmcnt(5)
	v_mfma_f32_32x32x16_bf16 v[64:79], v[172:175], v[232:235], v[64:79]
	v_mfma_f32_32x32x16_bf16 v[0:15], v[224:227], v[232:235], v[0:15]
	ds_read_b128 v[232:235], v184 offset:4672
	s_setprio 0
	global_load_dwordx4 v[172:175], v[144:145], off offset:768
	global_load_dwordx4 v[224:227], v[148:149], off offset:768
	s_setprio 1
	s_waitcnt lgkmcnt(1)
	v_mfma_f32_32x32x16_bf16 v[112:127], v[158:161], v[228:231], v[112:127]
	v_mfma_f32_32x32x16_bf16 v[48:63], v[162:165], v[228:231], v[48:63]
	s_waitcnt lgkmcnt(0)
	v_mfma_f32_32x32x16_bf16 v[96:111], v[158:161], v[232:235], v[96:111]
	v_mfma_f32_32x32x16_bf16 v[32:47], v[162:165], v[232:235], v[32:47]
	ds_read_b128 v[228:231], v184 offset:9280
	ds_read_b128 v[232:235], v184 offset:13888
	s_waitcnt vmcnt(7)
	ds_write_b128 v171, v[200:203]
	s_waitcnt vmcnt(6)
	ds_write_b128 v170, v[208:211]
	ds_read_b128 v[200:203], v192 offset:36960
	ds_read_b128 v[208:211], v192 offset:41568
	s_waitcnt lgkmcnt(5)
	v_mfma_f32_32x32x16_bf16 v[80:95], v[158:161], v[228:231], v[80:95]
	v_mfma_f32_32x32x16_bf16 v[16:31], v[162:165], v[228:231], v[16:31]
	ds_read_b128 v[228:231], v184 offset:96
	s_waitcnt lgkmcnt(5)
	v_mfma_f32_32x32x16_bf16 v[64:79], v[158:161], v[232:235], v[64:79]
	v_mfma_f32_32x32x16_bf16 v[0:15], v[162:165], v[232:235], v[0:15]
	ds_read_b128 v[232:235], v184 offset:4704
	s_setprio 0
	global_load_dwordx4 v[158:161], v[152:153], off offset:768
	global_load_dwordx4 v[162:165], v[156:157], off offset:768
	s_setprio 1
	s_waitcnt lgkmcnt(1)
	v_mfma_f32_32x32x16_bf16 v[112:127], v[200:203], v[228:231], v[112:127]
	v_mfma_f32_32x32x16_bf16 v[48:63], v[208:211], v[228:231], v[48:63]
	s_waitcnt lgkmcnt(0)
	v_mfma_f32_32x32x16_bf16 v[96:111], v[200:203], v[232:235], v[96:111]
	v_mfma_f32_32x32x16_bf16 v[32:47], v[208:211], v[232:235], v[32:47]
	ds_read_b128 v[228:231], v184 offset:9312
	ds_read_b128 v[232:235], v184 offset:13920
	s_waitcnt lgkmcnt(1)
	v_mfma_f32_32x32x16_bf16 v[80:95], v[200:203], v[228:231], v[80:95]
	v_mfma_f32_32x32x16_bf16 v[16:31], v[208:211], v[228:231], v[16:31]
	s_waitcnt lgkmcnt(0)
	v_mfma_f32_32x32x16_bf16 v[64:79], v[200:203], v[232:235], v[64:79]
	v_mfma_f32_32x32x16_bf16 v[0:15], v[208:211], v[232:235], v[0:15]
	s_setprio 0
	s_barrier
	global_load_dwordx4 v[200:203], v[128:129], off offset:896
	global_load_dwordx4 v[208:211], v[132:133], off offset:896
	s_waitcnt vmcnt(9)
	ds_write_b128 v191, v[212:215]
	s_waitcnt vmcnt(8)
	ds_write_b128 v191, v[216:219] offset:36864
	ds_read_b128 v[212:215], v169
	ds_read_b128 v[216:219], v169 offset:4608
	ds_read_b128 v[228:231], v168
	ds_read_b128 v[232:235], v168 offset:4608
	s_setprio 1
	s_waitcnt lgkmcnt(1)
	v_mfma_f32_32x32x16_bf16 v[112:127], v[212:215], v[228:231], v[112:127]
	v_mfma_f32_32x32x16_bf16 v[48:63], v[216:219], v[228:231], v[48:63]
	s_waitcnt lgkmcnt(0)
	v_mfma_f32_32x32x16_bf16 v[96:111], v[212:215], v[232:235], v[96:111]
	v_mfma_f32_32x32x16_bf16 v[32:47], v[216:219], v[232:235], v[32:47]
	ds_read_b128 v[228:231], v168 offset:9216
	ds_read_b128 v[232:235], v168 offset:13824
	s_waitcnt vmcnt(7)
	ds_write_b128 v191, v[178:181] offset:9216
	s_waitcnt vmcnt(6)
	ds_write_b128 v191, v[220:223] offset:46080
	ds_read_b128 v[178:181], v169 offset:32
	ds_read_b128 v[220:223], v169 offset:4640
	s_waitcnt lgkmcnt(5)
	v_mfma_f32_32x32x16_bf16 v[80:95], v[212:215], v[228:231], v[80:95]
	v_mfma_f32_32x32x16_bf16 v[16:31], v[216:219], v[228:231], v[16:31]
	ds_read_b128 v[228:231], v168 offset:32
	s_waitcnt lgkmcnt(5)
	v_mfma_f32_32x32x16_bf16 v[64:79], v[212:215], v[232:235], v[64:79]
	v_mfma_f32_32x32x16_bf16 v[0:15], v[216:219], v[232:235], v[0:15]
	ds_read_b128 v[232:235], v168 offset:4640
	s_setprio 0
	global_load_dwordx4 v[212:215], v[136:137], off offset:896
	global_load_dwordx4 v[216:219], v[140:141], off offset:896
	s_setprio 1
	s_waitcnt lgkmcnt(1)
	v_mfma_f32_32x32x16_bf16 v[112:127], v[178:181], v[228:231], v[112:127]
	v_mfma_f32_32x32x16_bf16 v[48:63], v[220:223], v[228:231], v[48:63]
	s_waitcnt lgkmcnt(0)
	v_mfma_f32_32x32x16_bf16 v[96:111], v[178:181], v[232:235], v[96:111]
	v_mfma_f32_32x32x16_bf16 v[32:47], v[220:223], v[232:235], v[32:47]
	ds_read_b128 v[228:231], v168 offset:9248
	ds_read_b128 v[232:235], v168 offset:13856
	s_waitcnt vmcnt(7)
	ds_write_b128 v191, v[172:175] offset:18432
	s_waitcnt vmcnt(6)
	ds_write_b128 v191, v[224:227] offset:55296
	ds_read_b128 v[172:175], v169 offset:64
	ds_read_b128 v[224:227], v169 offset:4672
	s_waitcnt lgkmcnt(5)
	v_mfma_f32_32x32x16_bf16 v[80:95], v[178:181], v[228:231], v[80:95]
	v_mfma_f32_32x32x16_bf16 v[16:31], v[220:223], v[228:231], v[16:31]
	ds_read_b128 v[228:231], v168 offset:64
	s_waitcnt lgkmcnt(5)
	v_mfma_f32_32x32x16_bf16 v[64:79], v[178:181], v[232:235], v[64:79]
	v_mfma_f32_32x32x16_bf16 v[0:15], v[220:223], v[232:235], v[0:15]
	ds_read_b128 v[232:235], v168 offset:4672
	s_setprio 0
	global_load_dwordx4 v[178:181], v[144:145], off offset:896
	global_load_dwordx4 v[220:223], v[148:149], off offset:896
	s_setprio 1
	s_waitcnt lgkmcnt(1)
	v_mfma_f32_32x32x16_bf16 v[112:127], v[172:175], v[228:231], v[112:127]
	v_mfma_f32_32x32x16_bf16 v[48:63], v[224:227], v[228:231], v[48:63]
	s_waitcnt lgkmcnt(0)
	v_mfma_f32_32x32x16_bf16 v[96:111], v[172:175], v[232:235], v[96:111]
	v_mfma_f32_32x32x16_bf16 v[32:47], v[224:227], v[232:235], v[32:47]
	ds_read_b128 v[228:231], v168 offset:9280
	ds_read_b128 v[232:235], v168 offset:13888
	s_waitcnt vmcnt(7)
	ds_write_b128 v191, v[158:161] offset:27648
	s_waitcnt vmcnt(6)
	ds_write_b128 v191, v[162:165] offset:64512
	ds_read_b128 v[158:161], v169 offset:96
	ds_read_b128 v[162:165], v169 offset:4704
	s_waitcnt lgkmcnt(5)
	v_mfma_f32_32x32x16_bf16 v[80:95], v[172:175], v[228:231], v[80:95]
	v_mfma_f32_32x32x16_bf16 v[16:31], v[224:227], v[228:231], v[16:31]
	ds_read_b128 v[228:231], v168 offset:96
	s_waitcnt lgkmcnt(5)
	v_mfma_f32_32x32x16_bf16 v[64:79], v[172:175], v[232:235], v[64:79]
	v_mfma_f32_32x32x16_bf16 v[0:15], v[224:227], v[232:235], v[0:15]
	ds_read_b128 v[232:235], v168 offset:4704
	s_setprio 0
	global_load_dwordx4 v[172:175], v[152:153], off offset:896
	global_load_dwordx4 v[224:227], v[156:157], off offset:896
	s_setprio 1
	s_waitcnt lgkmcnt(1)
	v_mfma_f32_32x32x16_bf16 v[112:127], v[158:161], v[228:231], v[112:127]
	v_mfma_f32_32x32x16_bf16 v[48:63], v[162:165], v[228:231], v[48:63]
	s_waitcnt lgkmcnt(0)
	v_mfma_f32_32x32x16_bf16 v[96:111], v[158:161], v[232:235], v[96:111]
	v_mfma_f32_32x32x16_bf16 v[32:47], v[162:165], v[232:235], v[32:47]
	ds_read_b128 v[228:231], v168 offset:9312
	ds_read_b128 v[232:235], v168 offset:13920
	s_waitcnt lgkmcnt(1)
	v_mfma_f32_32x32x16_bf16 v[80:95], v[158:161], v[228:231], v[80:95]
	v_mfma_f32_32x32x16_bf16 v[16:31], v[162:165], v[228:231], v[16:31]
	s_waitcnt lgkmcnt(0)
	v_mfma_f32_32x32x16_bf16 v[64:79], v[158:161], v[232:235], v[64:79]
	v_mfma_f32_32x32x16_bf16 v[0:15], v[162:165], v[232:235], v[0:15]
	s_setprio 0
	s_barrier
	global_load_dwordx4 v[158:161], v[128:129], off offset:1024
	global_load_dwordx4 v[162:165], v[132:133], off offset:1024
	s_waitcnt vmcnt(9)
	ds_write_b128 v195, v[200:203]
	s_waitcnt vmcnt(8)
	ds_write_b128 v196, v[208:211]
	ds_read_b128 v[200:203], v192 offset:36864
	ds_read_b128 v[208:211], v192 offset:41472
	ds_read_b128 v[228:231], v184
	ds_read_b128 v[232:235], v184 offset:4608
	s_setprio 1
	s_waitcnt lgkmcnt(1)
	v_mfma_f32_32x32x16_bf16 v[112:127], v[200:203], v[228:231], v[112:127]
	v_mfma_f32_32x32x16_bf16 v[48:63], v[208:211], v[228:231], v[48:63]
	s_waitcnt lgkmcnt(0)
	v_mfma_f32_32x32x16_bf16 v[96:111], v[200:203], v[232:235], v[96:111]
	v_mfma_f32_32x32x16_bf16 v[32:47], v[208:211], v[232:235], v[32:47]
	ds_read_b128 v[228:231], v184 offset:9216
	ds_read_b128 v[232:235], v184 offset:13824
	s_waitcnt vmcnt(7)
	ds_write_b128 v194, v[212:215]
	s_waitcnt vmcnt(6)
	ds_write_b128 v193, v[216:219]
	ds_read_b128 v[212:215], v192 offset:36896
	ds_read_b128 v[216:219], v192 offset:41504
	s_waitcnt lgkmcnt(5)
	v_mfma_f32_32x32x16_bf16 v[80:95], v[200:203], v[228:231], v[80:95]
	v_mfma_f32_32x32x16_bf16 v[16:31], v[208:211], v[228:231], v[16:31]
	ds_read_b128 v[228:231], v184 offset:32
	s_waitcnt lgkmcnt(5)
	v_mfma_f32_32x32x16_bf16 v[64:79], v[200:203], v[232:235], v[64:79]
	v_mfma_f32_32x32x16_bf16 v[0:15], v[208:211], v[232:235], v[0:15]
	ds_read_b128 v[232:235], v184 offset:4640
	s_setprio 0
	global_load_dwordx4 v[200:203], v[136:137], off offset:1024
	global_load_dwordx4 v[208:211], v[140:141], off offset:1024
	s_setprio 1
	s_waitcnt lgkmcnt(1)
	v_mfma_f32_32x32x16_bf16 v[112:127], v[212:215], v[228:231], v[112:127]
	v_mfma_f32_32x32x16_bf16 v[48:63], v[216:219], v[228:231], v[48:63]
	s_waitcnt lgkmcnt(0)
	v_mfma_f32_32x32x16_bf16 v[96:111], v[212:215], v[232:235], v[96:111]
	v_mfma_f32_32x32x16_bf16 v[32:47], v[216:219], v[232:235], v[32:47]
	ds_read_b128 v[228:231], v184 offset:9248
	ds_read_b128 v[232:235], v184 offset:13856
	s_waitcnt vmcnt(7)
	ds_write_b128 v177, v[178:181]
	s_waitcnt vmcnt(6)
	ds_write_b128 v176, v[220:223]
	ds_read_b128 v[178:181], v192 offset:36928
	ds_read_b128 v[220:223], v192 offset:41536
	s_waitcnt lgkmcnt(5)
	v_mfma_f32_32x32x16_bf16 v[80:95], v[212:215], v[228:231], v[80:95]
	v_mfma_f32_32x32x16_bf16 v[16:31], v[216:219], v[228:231], v[16:31]
	ds_read_b128 v[228:231], v184 offset:64
	s_waitcnt lgkmcnt(5)
	v_mfma_f32_32x32x16_bf16 v[64:79], v[212:215], v[232:235], v[64:79]
	v_mfma_f32_32x32x16_bf16 v[0:15], v[216:219], v[232:235], v[0:15]
	ds_read_b128 v[232:235], v184 offset:4672
	s_setprio 0
	global_load_dwordx4 v[212:215], v[144:145], off offset:1024
	global_load_dwordx4 v[216:219], v[148:149], off offset:1024
	s_setprio 1
	s_waitcnt lgkmcnt(1)
	v_mfma_f32_32x32x16_bf16 v[112:127], v[178:181], v[228:231], v[112:127]
	v_mfma_f32_32x32x16_bf16 v[48:63], v[220:223], v[228:231], v[48:63]
	s_waitcnt lgkmcnt(0)
	v_mfma_f32_32x32x16_bf16 v[96:111], v[178:181], v[232:235], v[96:111]
	v_mfma_f32_32x32x16_bf16 v[32:47], v[220:223], v[232:235], v[32:47]
	ds_read_b128 v[228:231], v184 offset:9280
	ds_read_b128 v[232:235], v184 offset:13888
	s_waitcnt vmcnt(7)
	ds_write_b128 v171, v[172:175]
	s_waitcnt vmcnt(6)
	ds_write_b128 v170, v[224:227]
	ds_read_b128 v[172:175], v192 offset:36960
	ds_read_b128 v[224:227], v192 offset:41568
	s_waitcnt lgkmcnt(5)
	v_mfma_f32_32x32x16_bf16 v[80:95], v[178:181], v[228:231], v[80:95]
	v_mfma_f32_32x32x16_bf16 v[16:31], v[220:223], v[228:231], v[16:31]
	ds_read_b128 v[228:231], v184 offset:96
	s_waitcnt lgkmcnt(5)
	v_mfma_f32_32x32x16_bf16 v[64:79], v[178:181], v[232:235], v[64:79]
	v_mfma_f32_32x32x16_bf16 v[0:15], v[220:223], v[232:235], v[0:15]
	ds_read_b128 v[232:235], v184 offset:4704
	s_setprio 0
	global_load_dwordx4 v[178:181], v[152:153], off offset:1024
	global_load_dwordx4 v[220:223], v[156:157], off offset:1024
	s_setprio 1
	s_waitcnt lgkmcnt(1)
	v_mfma_f32_32x32x16_bf16 v[112:127], v[172:175], v[228:231], v[112:127]
	v_mfma_f32_32x32x16_bf16 v[48:63], v[224:227], v[228:231], v[48:63]
	s_waitcnt lgkmcnt(0)
	v_mfma_f32_32x32x16_bf16 v[96:111], v[172:175], v[232:235], v[96:111]
	v_mfma_f32_32x32x16_bf16 v[32:47], v[224:227], v[232:235], v[32:47]
	ds_read_b128 v[228:231], v184 offset:9312
	ds_read_b128 v[232:235], v184 offset:13920
	s_waitcnt lgkmcnt(1)
	v_mfma_f32_32x32x16_bf16 v[80:95], v[172:175], v[228:231], v[80:95]
	v_mfma_f32_32x32x16_bf16 v[16:31], v[224:227], v[228:231], v[16:31]
	s_waitcnt lgkmcnt(0)
	v_mfma_f32_32x32x16_bf16 v[64:79], v[172:175], v[232:235], v[64:79]
	v_mfma_f32_32x32x16_bf16 v[0:15], v[224:227], v[232:235], v[0:15]
	s_setprio 0
	s_barrier
	global_load_dwordx4 v[172:175], v[128:129], off offset:1152
	global_load_dwordx4 v[224:227], v[132:133], off offset:1152
	s_waitcnt vmcnt(9)
	ds_write_b128 v191, v[158:161]
	s_waitcnt vmcnt(8)
	ds_write_b128 v191, v[162:165] offset:36864
	ds_read_b128 v[158:161], v169
	ds_read_b128 v[162:165], v169 offset:4608
	ds_read_b128 v[228:231], v168
	ds_read_b128 v[232:235], v168 offset:4608
	s_setprio 1
	s_waitcnt lgkmcnt(1)
	v_mfma_f32_32x32x16_bf16 v[112:127], v[158:161], v[228:231], v[112:127]
	v_mfma_f32_32x32x16_bf16 v[48:63], v[162:165], v[228:231], v[48:63]
	s_waitcnt lgkmcnt(0)
	v_mfma_f32_32x32x16_bf16 v[96:111], v[158:161], v[232:235], v[96:111]
	v_mfma_f32_32x32x16_bf16 v[32:47], v[162:165], v[232:235], v[32:47]
	ds_read_b128 v[228:231], v168 offset:9216
	ds_read_b128 v[232:235], v168 offset:13824
	s_waitcnt vmcnt(7)
	ds_write_b128 v191, v[200:203] offset:9216
	s_waitcnt vmcnt(6)
	ds_write_b128 v191, v[208:211] offset:46080
	ds_read_b128 v[200:203], v169 offset:32
	ds_read_b128 v[208:211], v169 offset:4640
	s_waitcnt lgkmcnt(5)
	v_mfma_f32_32x32x16_bf16 v[80:95], v[158:161], v[228:231], v[80:95]
	v_mfma_f32_32x32x16_bf16 v[16:31], v[162:165], v[228:231], v[16:31]
	ds_read_b128 v[228:231], v168 offset:32
	s_waitcnt lgkmcnt(5)
	v_mfma_f32_32x32x16_bf16 v[64:79], v[158:161], v[232:235], v[64:79]
	v_mfma_f32_32x32x16_bf16 v[0:15], v[162:165], v[232:235], v[0:15]
	ds_read_b128 v[232:235], v168 offset:4640
	s_setprio 0
	global_load_dwordx4 v[158:161], v[136:137], off offset:1152
	global_load_dwordx4 v[162:165], v[140:141], off offset:1152
	s_setprio 1
	s_waitcnt lgkmcnt(1)
	v_mfma_f32_32x32x16_bf16 v[112:127], v[200:203], v[228:231], v[112:127]
	v_mfma_f32_32x32x16_bf16 v[48:63], v[208:211], v[228:231], v[48:63]
	s_waitcnt lgkmcnt(0)
	v_mfma_f32_32x32x16_bf16 v[96:111], v[200:203], v[232:235], v[96:111]
	v_mfma_f32_32x32x16_bf16 v[32:47], v[208:211], v[232:235], v[32:47]
	ds_read_b128 v[228:231], v168 offset:9248
	ds_read_b128 v[232:235], v168 offset:13856
	s_waitcnt vmcnt(7)
	ds_write_b128 v191, v[212:215] offset:18432
	s_waitcnt vmcnt(6)
	ds_write_b128 v191, v[216:219] offset:55296
	ds_read_b128 v[212:215], v169 offset:64
	ds_read_b128 v[216:219], v169 offset:4672
	s_waitcnt lgkmcnt(5)
	v_mfma_f32_32x32x16_bf16 v[80:95], v[200:203], v[228:231], v[80:95]
	v_mfma_f32_32x32x16_bf16 v[16:31], v[208:211], v[228:231], v[16:31]
	ds_read_b128 v[228:231], v168 offset:64
	s_waitcnt lgkmcnt(5)
	v_mfma_f32_32x32x16_bf16 v[64:79], v[200:203], v[232:235], v[64:79]
	v_mfma_f32_32x32x16_bf16 v[0:15], v[208:211], v[232:235], v[0:15]
	ds_read_b128 v[232:235], v168 offset:4672
	s_setprio 0
	global_load_dwordx4 v[200:203], v[144:145], off offset:1152
	global_load_dwordx4 v[208:211], v[148:149], off offset:1152
	s_setprio 1
	s_waitcnt lgkmcnt(1)
	v_mfma_f32_32x32x16_bf16 v[112:127], v[212:215], v[228:231], v[112:127]
	v_mfma_f32_32x32x16_bf16 v[48:63], v[216:219], v[228:231], v[48:63]
	s_waitcnt lgkmcnt(0)
	v_mfma_f32_32x32x16_bf16 v[96:111], v[212:215], v[232:235], v[96:111]
	v_mfma_f32_32x32x16_bf16 v[32:47], v[216:219], v[232:235], v[32:47]
	ds_read_b128 v[228:231], v168 offset:9280
	ds_read_b128 v[232:235], v168 offset:13888
	s_waitcnt vmcnt(7)
	ds_write_b128 v191, v[178:181] offset:27648
	s_waitcnt vmcnt(6)
	ds_write_b128 v191, v[220:223] offset:64512
	ds_read_b128 v[178:181], v169 offset:96
	ds_read_b128 v[220:223], v169 offset:4704
	s_waitcnt lgkmcnt(5)
	v_mfma_f32_32x32x16_bf16 v[80:95], v[212:215], v[228:231], v[80:95]
	v_mfma_f32_32x32x16_bf16 v[16:31], v[216:219], v[228:231], v[16:31]
	ds_read_b128 v[228:231], v168 offset:96
	s_waitcnt lgkmcnt(5)
	v_mfma_f32_32x32x16_bf16 v[64:79], v[212:215], v[232:235], v[64:79]
	v_mfma_f32_32x32x16_bf16 v[0:15], v[216:219], v[232:235], v[0:15]
	ds_read_b128 v[232:235], v168 offset:4704
	s_setprio 0
	global_load_dwordx4 v[212:215], v[152:153], off offset:1152
	global_load_dwordx4 v[216:219], v[156:157], off offset:1152
	s_setprio 1
	s_waitcnt lgkmcnt(1)
	v_mfma_f32_32x32x16_bf16 v[112:127], v[178:181], v[228:231], v[112:127]
	v_mfma_f32_32x32x16_bf16 v[48:63], v[220:223], v[228:231], v[48:63]
	s_waitcnt lgkmcnt(0)
	v_mfma_f32_32x32x16_bf16 v[96:111], v[178:181], v[232:235], v[96:111]
	v_mfma_f32_32x32x16_bf16 v[32:47], v[220:223], v[232:235], v[32:47]
	ds_read_b128 v[228:231], v168 offset:9312
	ds_read_b128 v[232:235], v168 offset:13920
	s_waitcnt lgkmcnt(1)
	v_mfma_f32_32x32x16_bf16 v[80:95], v[178:181], v[228:231], v[80:95]
	v_mfma_f32_32x32x16_bf16 v[16:31], v[220:223], v[228:231], v[16:31]
	s_waitcnt lgkmcnt(0)
	v_mfma_f32_32x32x16_bf16 v[64:79], v[178:181], v[232:235], v[64:79]
	v_mfma_f32_32x32x16_bf16 v[0:15], v[220:223], v[232:235], v[0:15]
	s_setprio 0
	s_barrier
	global_load_dwordx4 v[178:181], v[128:129], off offset:1280
	global_load_dwordx4 v[220:223], v[132:133], off offset:1280
	s_waitcnt vmcnt(9)
	ds_write_b128 v195, v[172:175]
	s_waitcnt vmcnt(8)
	ds_write_b128 v196, v[224:227]
	ds_read_b128 v[172:175], v192 offset:36864
	ds_read_b128 v[224:227], v192 offset:41472
	ds_read_b128 v[228:231], v184
	ds_read_b128 v[232:235], v184 offset:4608
	s_setprio 1
	s_waitcnt lgkmcnt(1)
	v_mfma_f32_32x32x16_bf16 v[112:127], v[172:175], v[228:231], v[112:127]
	v_mfma_f32_32x32x16_bf16 v[48:63], v[224:227], v[228:231], v[48:63]
	s_waitcnt lgkmcnt(0)
	v_mfma_f32_32x32x16_bf16 v[96:111], v[172:175], v[232:235], v[96:111]
	v_mfma_f32_32x32x16_bf16 v[32:47], v[224:227], v[232:235], v[32:47]
	ds_read_b128 v[228:231], v184 offset:9216
	ds_read_b128 v[232:235], v184 offset:13824
	s_waitcnt vmcnt(7)
	ds_write_b128 v194, v[158:161]
	s_waitcnt vmcnt(6)
	ds_write_b128 v193, v[162:165]
	ds_read_b128 v[158:161], v192 offset:36896
	ds_read_b128 v[162:165], v192 offset:41504
	s_waitcnt lgkmcnt(5)
	v_mfma_f32_32x32x16_bf16 v[80:95], v[172:175], v[228:231], v[80:95]
	v_mfma_f32_32x32x16_bf16 v[16:31], v[224:227], v[228:231], v[16:31]
	ds_read_b128 v[228:231], v184 offset:32
	s_waitcnt lgkmcnt(5)
	v_mfma_f32_32x32x16_bf16 v[64:79], v[172:175], v[232:235], v[64:79]
	v_mfma_f32_32x32x16_bf16 v[0:15], v[224:227], v[232:235], v[0:15]
	ds_read_b128 v[232:235], v184 offset:4640
	s_setprio 0
	global_load_dwordx4 v[172:175], v[136:137], off offset:1280
	global_load_dwordx4 v[224:227], v[140:141], off offset:1280
	s_setprio 1
	s_waitcnt lgkmcnt(1)
	v_mfma_f32_32x32x16_bf16 v[112:127], v[158:161], v[228:231], v[112:127]
	v_mfma_f32_32x32x16_bf16 v[48:63], v[162:165], v[228:231], v[48:63]
	s_waitcnt lgkmcnt(0)
	v_mfma_f32_32x32x16_bf16 v[96:111], v[158:161], v[232:235], v[96:111]
	v_mfma_f32_32x32x16_bf16 v[32:47], v[162:165], v[232:235], v[32:47]
	ds_read_b128 v[228:231], v184 offset:9248
	ds_read_b128 v[232:235], v184 offset:13856
	s_waitcnt vmcnt(7)
	ds_write_b128 v177, v[200:203]
	s_waitcnt vmcnt(6)
	ds_write_b128 v176, v[208:211]
	ds_read_b128 v[200:203], v192 offset:36928
	ds_read_b128 v[208:211], v192 offset:41536
	s_waitcnt lgkmcnt(5)
	v_mfma_f32_32x32x16_bf16 v[80:95], v[158:161], v[228:231], v[80:95]
	v_mfma_f32_32x32x16_bf16 v[16:31], v[162:165], v[228:231], v[16:31]
	ds_read_b128 v[228:231], v184 offset:64
	s_waitcnt lgkmcnt(5)
	v_mfma_f32_32x32x16_bf16 v[64:79], v[158:161], v[232:235], v[64:79]
	v_mfma_f32_32x32x16_bf16 v[0:15], v[162:165], v[232:235], v[0:15]
	ds_read_b128 v[232:235], v184 offset:4672
	s_setprio 0
	global_load_dwordx4 v[158:161], v[144:145], off offset:1280
	global_load_dwordx4 v[162:165], v[148:149], off offset:1280
	s_setprio 1
	s_waitcnt lgkmcnt(1)
	v_mfma_f32_32x32x16_bf16 v[112:127], v[200:203], v[228:231], v[112:127]
	v_mfma_f32_32x32x16_bf16 v[48:63], v[208:211], v[228:231], v[48:63]
	s_waitcnt lgkmcnt(0)
	v_mfma_f32_32x32x16_bf16 v[96:111], v[200:203], v[232:235], v[96:111]
	v_mfma_f32_32x32x16_bf16 v[32:47], v[208:211], v[232:235], v[32:47]
	ds_read_b128 v[228:231], v184 offset:9280
	ds_read_b128 v[232:235], v184 offset:13888
	s_waitcnt vmcnt(7)
	ds_write_b128 v171, v[212:215]
	s_waitcnt vmcnt(6)
	ds_write_b128 v170, v[216:219]
	ds_read_b128 v[212:215], v192 offset:36960
	ds_read_b128 v[216:219], v192 offset:41568
	s_waitcnt lgkmcnt(5)
	v_mfma_f32_32x32x16_bf16 v[80:95], v[200:203], v[228:231], v[80:95]
	v_mfma_f32_32x32x16_bf16 v[16:31], v[208:211], v[228:231], v[16:31]
	ds_read_b128 v[228:231], v184 offset:96
	s_waitcnt lgkmcnt(5)
	v_mfma_f32_32x32x16_bf16 v[64:79], v[200:203], v[232:235], v[64:79]
	v_mfma_f32_32x32x16_bf16 v[0:15], v[208:211], v[232:235], v[0:15]
	ds_read_b128 v[232:235], v184 offset:4704
	s_setprio 0
	global_load_dwordx4 v[200:203], v[152:153], off offset:1280
	global_load_dwordx4 v[208:211], v[156:157], off offset:1280
	s_setprio 1
	s_waitcnt lgkmcnt(1)
	v_mfma_f32_32x32x16_bf16 v[112:127], v[212:215], v[228:231], v[112:127]
	v_mfma_f32_32x32x16_bf16 v[48:63], v[216:219], v[228:231], v[48:63]
	s_waitcnt lgkmcnt(0)
	v_mfma_f32_32x32x16_bf16 v[96:111], v[212:215], v[232:235], v[96:111]
	v_mfma_f32_32x32x16_bf16 v[32:47], v[216:219], v[232:235], v[32:47]
	ds_read_b128 v[228:231], v184 offset:9312
	ds_read_b128 v[232:235], v184 offset:13920
	s_waitcnt lgkmcnt(1)
	v_mfma_f32_32x32x16_bf16 v[80:95], v[212:215], v[228:231], v[80:95]
	v_mfma_f32_32x32x16_bf16 v[16:31], v[216:219], v[228:231], v[16:31]
	s_waitcnt lgkmcnt(0)
	v_mfma_f32_32x32x16_bf16 v[64:79], v[212:215], v[232:235], v[64:79]
	v_mfma_f32_32x32x16_bf16 v[0:15], v[216:219], v[232:235], v[0:15]
	s_setprio 0
	s_barrier
	global_load_dwordx4 v[212:215], v[128:129], off offset:1408
	global_load_dwordx4 v[216:219], v[132:133], off offset:1408
	s_waitcnt vmcnt(9)
	ds_write_b128 v191, v[178:181]
	s_waitcnt vmcnt(8)
	ds_write_b128 v191, v[220:223] offset:36864
	ds_read_b128 v[178:181], v169
	ds_read_b128 v[220:223], v169 offset:4608
	ds_read_b128 v[228:231], v168
	ds_read_b128 v[232:235], v168 offset:4608
	s_setprio 1
	s_waitcnt lgkmcnt(1)
	v_mfma_f32_32x32x16_bf16 v[112:127], v[178:181], v[228:231], v[112:127]
	v_mfma_f32_32x32x16_bf16 v[48:63], v[220:223], v[228:231], v[48:63]
	s_waitcnt lgkmcnt(0)
	v_mfma_f32_32x32x16_bf16 v[96:111], v[178:181], v[232:235], v[96:111]
	v_mfma_f32_32x32x16_bf16 v[32:47], v[220:223], v[232:235], v[32:47]
	ds_read_b128 v[228:231], v168 offset:9216
	ds_read_b128 v[232:235], v168 offset:13824
	s_waitcnt vmcnt(7)
	ds_write_b128 v191, v[172:175] offset:9216
	s_waitcnt vmcnt(6)
	ds_write_b128 v191, v[224:227] offset:46080
	ds_read_b128 v[172:175], v169 offset:32
	ds_read_b128 v[224:227], v169 offset:4640
	s_waitcnt lgkmcnt(5)
	v_mfma_f32_32x32x16_bf16 v[80:95], v[178:181], v[228:231], v[80:95]
	v_mfma_f32_32x32x16_bf16 v[16:31], v[220:223], v[228:231], v[16:31]
	ds_read_b128 v[228:231], v168 offset:32
	s_waitcnt lgkmcnt(5)
	v_mfma_f32_32x32x16_bf16 v[64:79], v[178:181], v[232:235], v[64:79]
	v_mfma_f32_32x32x16_bf16 v[0:15], v[220:223], v[232:235], v[0:15]
	ds_read_b128 v[232:235], v168 offset:4640
	s_setprio 0
	global_load_dwordx4 v[178:181], v[136:137], off offset:1408
	global_load_dwordx4 v[220:223], v[140:141], off offset:1408
	s_setprio 1
	s_waitcnt lgkmcnt(1)
	v_mfma_f32_32x32x16_bf16 v[112:127], v[172:175], v[228:231], v[112:127]
	v_mfma_f32_32x32x16_bf16 v[48:63], v[224:227], v[228:231], v[48:63]
	s_waitcnt lgkmcnt(0)
	v_mfma_f32_32x32x16_bf16 v[96:111], v[172:175], v[232:235], v[96:111]
	v_mfma_f32_32x32x16_bf16 v[32:47], v[224:227], v[232:235], v[32:47]
	ds_read_b128 v[228:231], v168 offset:9248
	ds_read_b128 v[232:235], v168 offset:13856
	s_waitcnt vmcnt(7)
	ds_write_b128 v191, v[158:161] offset:18432
	s_waitcnt vmcnt(6)
	ds_write_b128 v191, v[162:165] offset:55296
	ds_read_b128 v[158:161], v169 offset:64
	ds_read_b128 v[162:165], v169 offset:4672
	s_waitcnt lgkmcnt(5)
	v_mfma_f32_32x32x16_bf16 v[80:95], v[172:175], v[228:231], v[80:95]
	v_mfma_f32_32x32x16_bf16 v[16:31], v[224:227], v[228:231], v[16:31]
	ds_read_b128 v[228:231], v168 offset:64
	s_waitcnt lgkmcnt(5)
	v_mfma_f32_32x32x16_bf16 v[64:79], v[172:175], v[232:235], v[64:79]
	v_mfma_f32_32x32x16_bf16 v[0:15], v[224:227], v[232:235], v[0:15]
	ds_read_b128 v[232:235], v168 offset:4672
	s_setprio 0
	global_load_dwordx4 v[172:175], v[144:145], off offset:1408
	global_load_dwordx4 v[224:227], v[148:149], off offset:1408
	s_setprio 1
	s_waitcnt lgkmcnt(1)
	v_mfma_f32_32x32x16_bf16 v[112:127], v[158:161], v[228:231], v[112:127]
	v_mfma_f32_32x32x16_bf16 v[48:63], v[162:165], v[228:231], v[48:63]
	s_waitcnt lgkmcnt(0)
	v_mfma_f32_32x32x16_bf16 v[96:111], v[158:161], v[232:235], v[96:111]
	v_mfma_f32_32x32x16_bf16 v[32:47], v[162:165], v[232:235], v[32:47]
	ds_read_b128 v[228:231], v168 offset:9280
	ds_read_b128 v[232:235], v168 offset:13888
	s_waitcnt vmcnt(7)
	ds_write_b128 v191, v[200:203] offset:27648
	s_waitcnt vmcnt(6)
	ds_write_b128 v191, v[208:211] offset:64512
	ds_read_b128 v[200:203], v169 offset:96
	ds_read_b128 v[208:211], v169 offset:4704
	s_waitcnt lgkmcnt(5)
	v_mfma_f32_32x32x16_bf16 v[80:95], v[158:161], v[228:231], v[80:95]
	v_mfma_f32_32x32x16_bf16 v[16:31], v[162:165], v[228:231], v[16:31]
	ds_read_b128 v[228:231], v168 offset:96
	s_waitcnt lgkmcnt(5)
	v_mfma_f32_32x32x16_bf16 v[64:79], v[158:161], v[232:235], v[64:79]
	v_mfma_f32_32x32x16_bf16 v[0:15], v[162:165], v[232:235], v[0:15]
	ds_read_b128 v[232:235], v168 offset:4704
	s_setprio 0
	global_load_dwordx4 v[158:161], v[152:153], off offset:1408
	global_load_dwordx4 v[162:165], v[156:157], off offset:1408
	s_setprio 1
	s_waitcnt lgkmcnt(1)
	v_mfma_f32_32x32x16_bf16 v[112:127], v[200:203], v[228:231], v[112:127]
	v_mfma_f32_32x32x16_bf16 v[48:63], v[208:211], v[228:231], v[48:63]
	s_waitcnt lgkmcnt(0)
	v_mfma_f32_32x32x16_bf16 v[96:111], v[200:203], v[232:235], v[96:111]
	v_mfma_f32_32x32x16_bf16 v[32:47], v[208:211], v[232:235], v[32:47]
	ds_read_b128 v[228:231], v168 offset:9312
	ds_read_b128 v[232:235], v168 offset:13920
	s_waitcnt lgkmcnt(1)
	v_mfma_f32_32x32x16_bf16 v[80:95], v[200:203], v[228:231], v[80:95]
	v_mfma_f32_32x32x16_bf16 v[16:31], v[208:211], v[228:231], v[16:31]
	s_waitcnt lgkmcnt(0)
	v_mfma_f32_32x32x16_bf16 v[64:79], v[200:203], v[232:235], v[64:79]
	v_mfma_f32_32x32x16_bf16 v[0:15], v[208:211], v[232:235], v[0:15]
	s_setprio 0
	s_barrier
	global_load_dwordx4 v[200:203], v[128:129], off offset:1536
	global_load_dwordx4 v[208:211], v[132:133], off offset:1536
	s_waitcnt vmcnt(9)
	ds_write_b128 v195, v[212:215]
	s_waitcnt vmcnt(8)
	ds_write_b128 v196, v[216:219]
	ds_read_b128 v[212:215], v192 offset:36864
	ds_read_b128 v[216:219], v192 offset:41472
	ds_read_b128 v[228:231], v184
	ds_read_b128 v[232:235], v184 offset:4608
	s_setprio 1
	s_waitcnt lgkmcnt(1)
	v_mfma_f32_32x32x16_bf16 v[112:127], v[212:215], v[228:231], v[112:127]
	v_mfma_f32_32x32x16_bf16 v[48:63], v[216:219], v[228:231], v[48:63]
	s_waitcnt lgkmcnt(0)
	v_mfma_f32_32x32x16_bf16 v[96:111], v[212:215], v[232:235], v[96:111]
	v_mfma_f32_32x32x16_bf16 v[32:47], v[216:219], v[232:235], v[32:47]
	ds_read_b128 v[228:231], v184 offset:9216
	ds_read_b128 v[232:235], v184 offset:13824
	s_waitcnt vmcnt(7)
	ds_write_b128 v194, v[178:181]
	s_waitcnt vmcnt(6)
	ds_write_b128 v193, v[220:223]
	ds_read_b128 v[178:181], v192 offset:36896
	ds_read_b128 v[220:223], v192 offset:41504
	s_waitcnt lgkmcnt(5)
	v_mfma_f32_32x32x16_bf16 v[80:95], v[212:215], v[228:231], v[80:95]
	v_mfma_f32_32x32x16_bf16 v[16:31], v[216:219], v[228:231], v[16:31]
	ds_read_b128 v[228:231], v184 offset:32
	s_waitcnt lgkmcnt(5)
	v_mfma_f32_32x32x16_bf16 v[64:79], v[212:215], v[232:235], v[64:79]
	v_mfma_f32_32x32x16_bf16 v[0:15], v[216:219], v[232:235], v[0:15]
	ds_read_b128 v[232:235], v184 offset:4640
	s_setprio 0
	global_load_dwordx4 v[212:215], v[136:137], off offset:1536
	global_load_dwordx4 v[216:219], v[140:141], off offset:1536
	s_setprio 1
	s_waitcnt lgkmcnt(1)
	v_mfma_f32_32x32x16_bf16 v[112:127], v[178:181], v[228:231], v[112:127]
	v_mfma_f32_32x32x16_bf16 v[48:63], v[220:223], v[228:231], v[48:63]
	s_waitcnt lgkmcnt(0)
	v_mfma_f32_32x32x16_bf16 v[96:111], v[178:181], v[232:235], v[96:111]
	v_mfma_f32_32x32x16_bf16 v[32:47], v[220:223], v[232:235], v[32:47]
	ds_read_b128 v[228:231], v184 offset:9248
	ds_read_b128 v[232:235], v184 offset:13856
	s_waitcnt vmcnt(7)
	ds_write_b128 v177, v[172:175]
	s_waitcnt vmcnt(6)
	ds_write_b128 v176, v[224:227]
	ds_read_b128 v[172:175], v192 offset:36928
	ds_read_b128 v[224:227], v192 offset:41536
	s_waitcnt lgkmcnt(5)
	v_mfma_f32_32x32x16_bf16 v[80:95], v[178:181], v[228:231], v[80:95]
	v_mfma_f32_32x32x16_bf16 v[16:31], v[220:223], v[228:231], v[16:31]
	ds_read_b128 v[228:231], v184 offset:64
	s_waitcnt lgkmcnt(5)
	v_mfma_f32_32x32x16_bf16 v[64:79], v[178:181], v[232:235], v[64:79]
	v_mfma_f32_32x32x16_bf16 v[0:15], v[220:223], v[232:235], v[0:15]
	ds_read_b128 v[232:235], v184 offset:4672
	s_setprio 0
	global_load_dwordx4 v[178:181], v[144:145], off offset:1536
	global_load_dwordx4 v[220:223], v[148:149], off offset:1536
	s_setprio 1
	s_waitcnt lgkmcnt(1)
	v_mfma_f32_32x32x16_bf16 v[112:127], v[172:175], v[228:231], v[112:127]
	v_mfma_f32_32x32x16_bf16 v[48:63], v[224:227], v[228:231], v[48:63]
	s_waitcnt lgkmcnt(0)
	v_mfma_f32_32x32x16_bf16 v[96:111], v[172:175], v[232:235], v[96:111]
	v_mfma_f32_32x32x16_bf16 v[32:47], v[224:227], v[232:235], v[32:47]
	ds_read_b128 v[228:231], v184 offset:9280
	ds_read_b128 v[232:235], v184 offset:13888
	s_waitcnt vmcnt(7)
	ds_write_b128 v171, v[158:161]
	s_waitcnt vmcnt(6)
	ds_write_b128 v170, v[162:165]
	ds_read_b128 v[158:161], v192 offset:36960
	ds_read_b128 v[162:165], v192 offset:41568
	s_waitcnt lgkmcnt(5)
	v_mfma_f32_32x32x16_bf16 v[80:95], v[172:175], v[228:231], v[80:95]
	v_mfma_f32_32x32x16_bf16 v[16:31], v[224:227], v[228:231], v[16:31]
	ds_read_b128 v[228:231], v184 offset:96
	s_waitcnt lgkmcnt(5)
	v_mfma_f32_32x32x16_bf16 v[64:79], v[172:175], v[232:235], v[64:79]
	v_mfma_f32_32x32x16_bf16 v[0:15], v[224:227], v[232:235], v[0:15]
	ds_read_b128 v[232:235], v184 offset:4704
	s_setprio 0
	global_load_dwordx4 v[172:175], v[152:153], off offset:1536
	global_load_dwordx4 v[224:227], v[156:157], off offset:1536
	s_setprio 1
	s_waitcnt lgkmcnt(1)
	v_mfma_f32_32x32x16_bf16 v[112:127], v[158:161], v[228:231], v[112:127]
	v_mfma_f32_32x32x16_bf16 v[48:63], v[162:165], v[228:231], v[48:63]
	s_waitcnt lgkmcnt(0)
	v_mfma_f32_32x32x16_bf16 v[96:111], v[158:161], v[232:235], v[96:111]
	v_mfma_f32_32x32x16_bf16 v[32:47], v[162:165], v[232:235], v[32:47]
	ds_read_b128 v[228:231], v184 offset:9312
	ds_read_b128 v[232:235], v184 offset:13920
	s_waitcnt lgkmcnt(1)
	v_mfma_f32_32x32x16_bf16 v[80:95], v[158:161], v[228:231], v[80:95]
	v_mfma_f32_32x32x16_bf16 v[16:31], v[162:165], v[228:231], v[16:31]
	s_waitcnt lgkmcnt(0)
	v_mfma_f32_32x32x16_bf16 v[64:79], v[158:161], v[232:235], v[64:79]
	v_mfma_f32_32x32x16_bf16 v[0:15], v[162:165], v[232:235], v[0:15]
	s_setprio 0
	s_barrier
	global_load_dwordx4 v[158:161], v[128:129], off offset:1664
	global_load_dwordx4 v[162:165], v[132:133], off offset:1664
	s_waitcnt vmcnt(9)
	ds_write_b128 v191, v[200:203]
	s_waitcnt vmcnt(8)
	ds_write_b128 v191, v[208:211] offset:36864
	ds_read_b128 v[200:203], v169
	ds_read_b128 v[208:211], v169 offset:4608
	ds_read_b128 v[228:231], v168
	ds_read_b128 v[232:235], v168 offset:4608
	s_setprio 1
	s_waitcnt lgkmcnt(1)
	v_mfma_f32_32x32x16_bf16 v[112:127], v[200:203], v[228:231], v[112:127]
	v_mfma_f32_32x32x16_bf16 v[48:63], v[208:211], v[228:231], v[48:63]
	s_waitcnt lgkmcnt(0)
	v_mfma_f32_32x32x16_bf16 v[96:111], v[200:203], v[232:235], v[96:111]
	v_mfma_f32_32x32x16_bf16 v[32:47], v[208:211], v[232:235], v[32:47]
	ds_read_b128 v[228:231], v168 offset:9216
	ds_read_b128 v[232:235], v168 offset:13824
	s_waitcnt vmcnt(7)
	ds_write_b128 v191, v[212:215] offset:9216
	s_waitcnt vmcnt(6)
	ds_write_b128 v191, v[216:219] offset:46080
	ds_read_b128 v[212:215], v169 offset:32
	ds_read_b128 v[216:219], v169 offset:4640
	s_waitcnt lgkmcnt(5)
	v_mfma_f32_32x32x16_bf16 v[80:95], v[200:203], v[228:231], v[80:95]
	v_mfma_f32_32x32x16_bf16 v[16:31], v[208:211], v[228:231], v[16:31]
	ds_read_b128 v[228:231], v168 offset:32
	s_waitcnt lgkmcnt(5)
	v_mfma_f32_32x32x16_bf16 v[64:79], v[200:203], v[232:235], v[64:79]
	v_mfma_f32_32x32x16_bf16 v[0:15], v[208:211], v[232:235], v[0:15]
	ds_read_b128 v[232:235], v168 offset:4640
	s_setprio 0
	global_load_dwordx4 v[200:203], v[136:137], off offset:1664
	global_load_dwordx4 v[208:211], v[140:141], off offset:1664
	s_setprio 1
	s_waitcnt lgkmcnt(1)
	v_mfma_f32_32x32x16_bf16 v[112:127], v[212:215], v[228:231], v[112:127]
	v_mfma_f32_32x32x16_bf16 v[48:63], v[216:219], v[228:231], v[48:63]
	s_waitcnt lgkmcnt(0)
	v_mfma_f32_32x32x16_bf16 v[96:111], v[212:215], v[232:235], v[96:111]
	v_mfma_f32_32x32x16_bf16 v[32:47], v[216:219], v[232:235], v[32:47]
	ds_read_b128 v[228:231], v168 offset:9248
	ds_read_b128 v[232:235], v168 offset:13856
	s_waitcnt vmcnt(7)
	ds_write_b128 v191, v[178:181] offset:18432
	s_waitcnt vmcnt(6)
	ds_write_b128 v191, v[220:223] offset:55296
	ds_read_b128 v[178:181], v169 offset:64
	ds_read_b128 v[220:223], v169 offset:4672
	s_waitcnt lgkmcnt(5)
	v_mfma_f32_32x32x16_bf16 v[80:95], v[212:215], v[228:231], v[80:95]
	v_mfma_f32_32x32x16_bf16 v[16:31], v[216:219], v[228:231], v[16:31]
	ds_read_b128 v[228:231], v168 offset:64
	s_waitcnt lgkmcnt(5)
	v_mfma_f32_32x32x16_bf16 v[64:79], v[212:215], v[232:235], v[64:79]
	v_mfma_f32_32x32x16_bf16 v[0:15], v[216:219], v[232:235], v[0:15]
	ds_read_b128 v[232:235], v168 offset:4672
	s_setprio 0
	global_load_dwordx4 v[212:215], v[144:145], off offset:1664
	global_load_dwordx4 v[216:219], v[148:149], off offset:1664
	s_setprio 1
	s_waitcnt lgkmcnt(1)
	v_mfma_f32_32x32x16_bf16 v[112:127], v[178:181], v[228:231], v[112:127]
	v_mfma_f32_32x32x16_bf16 v[48:63], v[220:223], v[228:231], v[48:63]
	s_waitcnt lgkmcnt(0)
	v_mfma_f32_32x32x16_bf16 v[96:111], v[178:181], v[232:235], v[96:111]
	v_mfma_f32_32x32x16_bf16 v[32:47], v[220:223], v[232:235], v[32:47]
	ds_read_b128 v[228:231], v168 offset:9280
	ds_read_b128 v[232:235], v168 offset:13888
	s_waitcnt vmcnt(7)
	ds_write_b128 v191, v[172:175] offset:27648
	s_waitcnt vmcnt(6)
	ds_write_b128 v191, v[224:227] offset:64512
	ds_read_b128 v[172:175], v169 offset:96
	ds_read_b128 v[224:227], v169 offset:4704
	s_waitcnt lgkmcnt(5)
	v_mfma_f32_32x32x16_bf16 v[80:95], v[178:181], v[228:231], v[80:95]
	v_mfma_f32_32x32x16_bf16 v[16:31], v[220:223], v[228:231], v[16:31]
	ds_read_b128 v[228:231], v168 offset:96
	s_waitcnt lgkmcnt(5)
	v_mfma_f32_32x32x16_bf16 v[64:79], v[178:181], v[232:235], v[64:79]
	v_mfma_f32_32x32x16_bf16 v[0:15], v[220:223], v[232:235], v[0:15]
	ds_read_b128 v[232:235], v168 offset:4704
	s_setprio 0
	global_load_dwordx4 v[178:181], v[152:153], off offset:1664
	global_load_dwordx4 v[220:223], v[156:157], off offset:1664
	s_setprio 1
	s_waitcnt lgkmcnt(1)
	v_mfma_f32_32x32x16_bf16 v[112:127], v[172:175], v[228:231], v[112:127]
	v_mfma_f32_32x32x16_bf16 v[48:63], v[224:227], v[228:231], v[48:63]
	s_waitcnt lgkmcnt(0)
	v_mfma_f32_32x32x16_bf16 v[96:111], v[172:175], v[232:235], v[96:111]
	v_mfma_f32_32x32x16_bf16 v[32:47], v[224:227], v[232:235], v[32:47]
	ds_read_b128 v[228:231], v168 offset:9312
	ds_read_b128 v[232:235], v168 offset:13920
	s_waitcnt lgkmcnt(1)
	v_mfma_f32_32x32x16_bf16 v[80:95], v[172:175], v[228:231], v[80:95]
	v_mfma_f32_32x32x16_bf16 v[16:31], v[224:227], v[228:231], v[16:31]
	s_waitcnt lgkmcnt(0)
	v_mfma_f32_32x32x16_bf16 v[64:79], v[172:175], v[232:235], v[64:79]
	v_mfma_f32_32x32x16_bf16 v[0:15], v[224:227], v[232:235], v[0:15]
	s_setprio 0
	s_barrier
	global_load_dwordx4 v[172:175], v[128:129], off offset:1792
	global_load_dwordx4 v[224:227], v[132:133], off offset:1792
	s_waitcnt vmcnt(9)
	ds_write_b128 v195, v[158:161]
	s_waitcnt vmcnt(8)
	ds_write_b128 v196, v[162:165]
	ds_read_b128 v[158:161], v192 offset:36864
	ds_read_b128 v[162:165], v192 offset:41472
	ds_read_b128 v[228:231], v184
	ds_read_b128 v[232:235], v184 offset:4608
	s_setprio 1
	s_waitcnt lgkmcnt(1)
	v_mfma_f32_32x32x16_bf16 v[112:127], v[158:161], v[228:231], v[112:127]
	v_mfma_f32_32x32x16_bf16 v[48:63], v[162:165], v[228:231], v[48:63]
	s_waitcnt lgkmcnt(0)
	v_mfma_f32_32x32x16_bf16 v[96:111], v[158:161], v[232:235], v[96:111]
	v_mfma_f32_32x32x16_bf16 v[32:47], v[162:165], v[232:235], v[32:47]
	ds_read_b128 v[228:231], v184 offset:9216
	ds_read_b128 v[232:235], v184 offset:13824
	s_waitcnt vmcnt(7)
	ds_write_b128 v194, v[200:203]
	s_waitcnt vmcnt(6)
	ds_write_b128 v193, v[208:211]
	ds_read_b128 v[200:203], v192 offset:36896
	ds_read_b128 v[208:211], v192 offset:41504
	s_waitcnt lgkmcnt(5)
	v_mfma_f32_32x32x16_bf16 v[80:95], v[158:161], v[228:231], v[80:95]
	v_mfma_f32_32x32x16_bf16 v[16:31], v[162:165], v[228:231], v[16:31]
	ds_read_b128 v[228:231], v184 offset:32
	s_waitcnt lgkmcnt(5)
	v_mfma_f32_32x32x16_bf16 v[64:79], v[158:161], v[232:235], v[64:79]
	v_mfma_f32_32x32x16_bf16 v[0:15], v[162:165], v[232:235], v[0:15]
	ds_read_b128 v[232:235], v184 offset:4640
	s_setprio 0
	global_load_dwordx4 v[158:161], v[136:137], off offset:1792
	global_load_dwordx4 v[162:165], v[140:141], off offset:1792
	s_setprio 1
	s_waitcnt lgkmcnt(1)
	v_mfma_f32_32x32x16_bf16 v[112:127], v[200:203], v[228:231], v[112:127]
	v_mfma_f32_32x32x16_bf16 v[48:63], v[208:211], v[228:231], v[48:63]
	s_waitcnt lgkmcnt(0)
	v_mfma_f32_32x32x16_bf16 v[96:111], v[200:203], v[232:235], v[96:111]
	v_mfma_f32_32x32x16_bf16 v[32:47], v[208:211], v[232:235], v[32:47]
	ds_read_b128 v[228:231], v184 offset:9248
	ds_read_b128 v[232:235], v184 offset:13856
	s_waitcnt vmcnt(7)
	ds_write_b128 v177, v[212:215]
	s_waitcnt vmcnt(6)
	ds_write_b128 v176, v[216:219]
	ds_read_b128 v[212:215], v192 offset:36928
	ds_read_b128 v[216:219], v192 offset:41536
	s_waitcnt lgkmcnt(5)
	v_mfma_f32_32x32x16_bf16 v[80:95], v[200:203], v[228:231], v[80:95]
	v_mfma_f32_32x32x16_bf16 v[16:31], v[208:211], v[228:231], v[16:31]
	ds_read_b128 v[228:231], v184 offset:64
	s_waitcnt lgkmcnt(5)
	v_mfma_f32_32x32x16_bf16 v[64:79], v[200:203], v[232:235], v[64:79]
	v_mfma_f32_32x32x16_bf16 v[0:15], v[208:211], v[232:235], v[0:15]
	ds_read_b128 v[232:235], v184 offset:4672
	s_setprio 0
	global_load_dwordx4 v[200:203], v[144:145], off offset:1792
	global_load_dwordx4 v[208:211], v[148:149], off offset:1792
	s_setprio 1
	s_waitcnt lgkmcnt(1)
	v_mfma_f32_32x32x16_bf16 v[112:127], v[212:215], v[228:231], v[112:127]
	v_mfma_f32_32x32x16_bf16 v[48:63], v[216:219], v[228:231], v[48:63]
	s_waitcnt lgkmcnt(0)
	v_mfma_f32_32x32x16_bf16 v[96:111], v[212:215], v[232:235], v[96:111]
	v_mfma_f32_32x32x16_bf16 v[32:47], v[216:219], v[232:235], v[32:47]
	ds_read_b128 v[228:231], v184 offset:9280
	ds_read_b128 v[232:235], v184 offset:13888
	s_waitcnt vmcnt(7)
	ds_write_b128 v171, v[178:181]
	s_waitcnt vmcnt(6)
	ds_write_b128 v170, v[220:223]
	ds_read_b128 v[178:181], v192 offset:36960
	ds_read_b128 v[220:223], v192 offset:41568
	s_waitcnt lgkmcnt(5)
	v_mfma_f32_32x32x16_bf16 v[80:95], v[212:215], v[228:231], v[80:95]
	v_mfma_f32_32x32x16_bf16 v[16:31], v[216:219], v[228:231], v[16:31]
	ds_read_b128 v[228:231], v184 offset:96
	s_waitcnt lgkmcnt(5)
	v_mfma_f32_32x32x16_bf16 v[64:79], v[212:215], v[232:235], v[64:79]
	v_mfma_f32_32x32x16_bf16 v[0:15], v[216:219], v[232:235], v[0:15]
	ds_read_b128 v[232:235], v184 offset:4704
	s_setprio 0
	global_load_dwordx4 v[212:215], v[152:153], off offset:1792
	global_load_dwordx4 v[216:219], v[156:157], off offset:1792
	s_setprio 1
	s_waitcnt lgkmcnt(1)
	v_mfma_f32_32x32x16_bf16 v[112:127], v[178:181], v[228:231], v[112:127]
	v_mfma_f32_32x32x16_bf16 v[48:63], v[220:223], v[228:231], v[48:63]
	s_waitcnt lgkmcnt(0)
	v_mfma_f32_32x32x16_bf16 v[96:111], v[178:181], v[232:235], v[96:111]
	v_mfma_f32_32x32x16_bf16 v[32:47], v[220:223], v[232:235], v[32:47]
	ds_read_b128 v[228:231], v184 offset:9312
	ds_read_b128 v[232:235], v184 offset:13920
	s_waitcnt lgkmcnt(1)
	v_mfma_f32_32x32x16_bf16 v[80:95], v[178:181], v[228:231], v[80:95]
	v_mfma_f32_32x32x16_bf16 v[16:31], v[220:223], v[228:231], v[16:31]
	s_waitcnt lgkmcnt(0)
	v_mfma_f32_32x32x16_bf16 v[64:79], v[178:181], v[232:235], v[64:79]
	v_mfma_f32_32x32x16_bf16 v[0:15], v[220:223], v[232:235], v[0:15]
	s_setprio 0
	s_barrier
	global_load_dwordx4 v[178:181], v[128:129], off offset:1920
	global_load_dwordx4 v[220:223], v[132:133], off offset:1920
	s_waitcnt vmcnt(9)
	ds_write_b128 v191, v[172:175]
	s_waitcnt vmcnt(8)
	ds_write_b128 v191, v[224:227] offset:36864
	ds_read_b128 v[172:175], v169
	ds_read_b128 v[224:227], v169 offset:4608
	ds_read_b128 v[228:231], v168
	ds_read_b128 v[232:235], v168 offset:4608
	s_setprio 1
	s_waitcnt lgkmcnt(1)
	v_mfma_f32_32x32x16_bf16 v[112:127], v[172:175], v[228:231], v[112:127]
	v_mfma_f32_32x32x16_bf16 v[48:63], v[224:227], v[228:231], v[48:63]
	s_waitcnt lgkmcnt(0)
	v_mfma_f32_32x32x16_bf16 v[96:111], v[172:175], v[232:235], v[96:111]
	v_mfma_f32_32x32x16_bf16 v[32:47], v[224:227], v[232:235], v[32:47]
	ds_read_b128 v[228:231], v168 offset:9216
	ds_read_b128 v[232:235], v168 offset:13824
	s_waitcnt vmcnt(7)
	ds_write_b128 v191, v[158:161] offset:9216
	s_waitcnt vmcnt(6)
	ds_write_b128 v191, v[162:165] offset:46080
	ds_read_b128 v[158:161], v169 offset:32
	ds_read_b128 v[162:165], v169 offset:4640
	s_waitcnt lgkmcnt(5)
	v_mfma_f32_32x32x16_bf16 v[80:95], v[172:175], v[228:231], v[80:95]
	v_mfma_f32_32x32x16_bf16 v[16:31], v[224:227], v[228:231], v[16:31]
	ds_read_b128 v[228:231], v168 offset:32
	s_waitcnt lgkmcnt(5)
	v_mfma_f32_32x32x16_bf16 v[64:79], v[172:175], v[232:235], v[64:79]
	v_mfma_f32_32x32x16_bf16 v[0:15], v[224:227], v[232:235], v[0:15]
	ds_read_b128 v[232:235], v168 offset:4640
	s_setprio 0
	global_load_dwordx4 v[172:175], v[136:137], off offset:1920
	global_load_dwordx4 v[224:227], v[140:141], off offset:1920
	s_setprio 1
	s_waitcnt lgkmcnt(1)
	v_mfma_f32_32x32x16_bf16 v[112:127], v[158:161], v[228:231], v[112:127]
	v_mfma_f32_32x32x16_bf16 v[48:63], v[162:165], v[228:231], v[48:63]
	s_waitcnt lgkmcnt(0)
	v_mfma_f32_32x32x16_bf16 v[96:111], v[158:161], v[232:235], v[96:111]
	v_mfma_f32_32x32x16_bf16 v[32:47], v[162:165], v[232:235], v[32:47]
	ds_read_b128 v[228:231], v168 offset:9248
	ds_read_b128 v[232:235], v168 offset:13856
	s_waitcnt vmcnt(7)
	ds_write_b128 v191, v[200:203] offset:18432
	s_waitcnt vmcnt(6)
	ds_write_b128 v191, v[208:211] offset:55296
	ds_read_b128 v[200:203], v169 offset:64
	ds_read_b128 v[208:211], v169 offset:4672
	s_waitcnt lgkmcnt(5)
	v_mfma_f32_32x32x16_bf16 v[80:95], v[158:161], v[228:231], v[80:95]
	v_mfma_f32_32x32x16_bf16 v[16:31], v[162:165], v[228:231], v[16:31]
	ds_read_b128 v[228:231], v168 offset:64
	s_waitcnt lgkmcnt(5)
	v_mfma_f32_32x32x16_bf16 v[64:79], v[158:161], v[232:235], v[64:79]
	v_mfma_f32_32x32x16_bf16 v[0:15], v[162:165], v[232:235], v[0:15]
	ds_read_b128 v[232:235], v168 offset:4672
	s_setprio 0
	global_load_dwordx4 v[158:161], v[144:145], off offset:1920
	global_load_dwordx4 v[162:165], v[148:149], off offset:1920
	s_setprio 1
	s_waitcnt lgkmcnt(1)
	v_mfma_f32_32x32x16_bf16 v[112:127], v[200:203], v[228:231], v[112:127]
	v_mfma_f32_32x32x16_bf16 v[48:63], v[208:211], v[228:231], v[48:63]
	s_waitcnt lgkmcnt(0)
	v_mfma_f32_32x32x16_bf16 v[96:111], v[200:203], v[232:235], v[96:111]
	v_mfma_f32_32x32x16_bf16 v[32:47], v[208:211], v[232:235], v[32:47]
	ds_read_b128 v[228:231], v168 offset:9280
	ds_read_b128 v[232:235], v168 offset:13888
	s_waitcnt vmcnt(7)
	ds_write_b128 v191, v[212:215] offset:27648
	s_waitcnt vmcnt(6)
	ds_write_b128 v191, v[216:219] offset:64512
	ds_read_b128 v[212:215], v169 offset:96
	ds_read_b128 v[216:219], v169 offset:4704
	s_waitcnt lgkmcnt(5)
	v_mfma_f32_32x32x16_bf16 v[80:95], v[200:203], v[228:231], v[80:95]
	v_mfma_f32_32x32x16_bf16 v[16:31], v[208:211], v[228:231], v[16:31]
	ds_read_b128 v[228:231], v168 offset:96
	s_waitcnt lgkmcnt(5)
	v_mfma_f32_32x32x16_bf16 v[64:79], v[200:203], v[232:235], v[64:79]
	v_mfma_f32_32x32x16_bf16 v[0:15], v[208:211], v[232:235], v[0:15]
	ds_read_b128 v[232:235], v168 offset:4704
	s_setprio 0
	global_load_dwordx4 v[200:203], v[152:153], off offset:1920
	global_load_dwordx4 v[208:211], v[156:157], off offset:1920
	s_setprio 1
	s_waitcnt lgkmcnt(1)
	v_mfma_f32_32x32x16_bf16 v[112:127], v[212:215], v[228:231], v[112:127]
	v_mfma_f32_32x32x16_bf16 v[48:63], v[216:219], v[228:231], v[48:63]
	s_waitcnt lgkmcnt(0)
	v_mfma_f32_32x32x16_bf16 v[96:111], v[212:215], v[232:235], v[96:111]
	v_mfma_f32_32x32x16_bf16 v[32:47], v[216:219], v[232:235], v[32:47]
	ds_read_b128 v[228:231], v168 offset:9312
	ds_read_b128 v[232:235], v168 offset:13920
	s_waitcnt lgkmcnt(1)
	v_mfma_f32_32x32x16_bf16 v[80:95], v[212:215], v[228:231], v[80:95]
	v_mfma_f32_32x32x16_bf16 v[16:31], v[216:219], v[228:231], v[16:31]
	s_waitcnt lgkmcnt(0)
	v_mfma_f32_32x32x16_bf16 v[64:79], v[212:215], v[232:235], v[64:79]
	v_mfma_f32_32x32x16_bf16 v[0:15], v[216:219], v[232:235], v[0:15]
	s_setprio 0
	s_barrier
	global_load_dwordx4 v[212:215], v[128:129], off offset:2048
	global_load_dwordx4 v[216:219], v[132:133], off offset:2048
	s_waitcnt vmcnt(9)
	ds_write_b128 v195, v[178:181]
	s_waitcnt vmcnt(8)
	ds_write_b128 v196, v[220:223]
	ds_read_b128 v[178:181], v192 offset:36864
	ds_read_b128 v[220:223], v192 offset:41472
	ds_read_b128 v[228:231], v184
	ds_read_b128 v[232:235], v184 offset:4608
	s_setprio 1
	s_waitcnt lgkmcnt(1)
	v_mfma_f32_32x32x16_bf16 v[112:127], v[178:181], v[228:231], v[112:127]
	v_mfma_f32_32x32x16_bf16 v[48:63], v[220:223], v[228:231], v[48:63]
	s_waitcnt lgkmcnt(0)
	v_mfma_f32_32x32x16_bf16 v[96:111], v[178:181], v[232:235], v[96:111]
	v_mfma_f32_32x32x16_bf16 v[32:47], v[220:223], v[232:235], v[32:47]
	ds_read_b128 v[228:231], v184 offset:9216
	ds_read_b128 v[232:235], v184 offset:13824
	s_waitcnt vmcnt(7)
	ds_write_b128 v194, v[172:175]
	s_waitcnt vmcnt(6)
	ds_write_b128 v193, v[224:227]
	ds_read_b128 v[172:175], v192 offset:36896
	ds_read_b128 v[224:227], v192 offset:41504
	s_waitcnt lgkmcnt(5)
	v_mfma_f32_32x32x16_bf16 v[80:95], v[178:181], v[228:231], v[80:95]
	v_mfma_f32_32x32x16_bf16 v[16:31], v[220:223], v[228:231], v[16:31]
	ds_read_b128 v[228:231], v184 offset:32
	s_waitcnt lgkmcnt(5)
	v_mfma_f32_32x32x16_bf16 v[64:79], v[178:181], v[232:235], v[64:79]
	v_mfma_f32_32x32x16_bf16 v[0:15], v[220:223], v[232:235], v[0:15]
	ds_read_b128 v[232:235], v184 offset:4640
	s_setprio 0
	global_load_dwordx4 v[178:181], v[136:137], off offset:2048
	global_load_dwordx4 v[220:223], v[140:141], off offset:2048
	s_setprio 1
	s_waitcnt lgkmcnt(1)
	v_mfma_f32_32x32x16_bf16 v[112:127], v[172:175], v[228:231], v[112:127]
	v_mfma_f32_32x32x16_bf16 v[48:63], v[224:227], v[228:231], v[48:63]
	s_waitcnt lgkmcnt(0)
	v_mfma_f32_32x32x16_bf16 v[96:111], v[172:175], v[232:235], v[96:111]
	v_mfma_f32_32x32x16_bf16 v[32:47], v[224:227], v[232:235], v[32:47]
	ds_read_b128 v[228:231], v184 offset:9248
	ds_read_b128 v[232:235], v184 offset:13856
	s_waitcnt vmcnt(7)
	ds_write_b128 v177, v[158:161]
	s_waitcnt vmcnt(6)
	ds_write_b128 v176, v[162:165]
	ds_read_b128 v[158:161], v192 offset:36928
	ds_read_b128 v[162:165], v192 offset:41536
	s_waitcnt lgkmcnt(5)
	v_mfma_f32_32x32x16_bf16 v[80:95], v[172:175], v[228:231], v[80:95]
	v_mfma_f32_32x32x16_bf16 v[16:31], v[224:227], v[228:231], v[16:31]
	ds_read_b128 v[228:231], v184 offset:64
	s_waitcnt lgkmcnt(5)
	v_mfma_f32_32x32x16_bf16 v[64:79], v[172:175], v[232:235], v[64:79]
	v_mfma_f32_32x32x16_bf16 v[0:15], v[224:227], v[232:235], v[0:15]
	ds_read_b128 v[232:235], v184 offset:4672
	s_setprio 0
	global_load_dwordx4 v[172:175], v[144:145], off offset:2048
	global_load_dwordx4 v[224:227], v[148:149], off offset:2048
	s_setprio 1
	s_waitcnt lgkmcnt(1)
	v_mfma_f32_32x32x16_bf16 v[112:127], v[158:161], v[228:231], v[112:127]
	v_mfma_f32_32x32x16_bf16 v[48:63], v[162:165], v[228:231], v[48:63]
	s_waitcnt lgkmcnt(0)
	v_mfma_f32_32x32x16_bf16 v[96:111], v[158:161], v[232:235], v[96:111]
	v_mfma_f32_32x32x16_bf16 v[32:47], v[162:165], v[232:235], v[32:47]
	ds_read_b128 v[228:231], v184 offset:9280
	ds_read_b128 v[232:235], v184 offset:13888
	s_waitcnt vmcnt(7)
	ds_write_b128 v171, v[200:203]
	s_waitcnt vmcnt(6)
	ds_write_b128 v170, v[208:211]
	ds_read_b128 v[200:203], v192 offset:36960
	ds_read_b128 v[208:211], v192 offset:41568
	s_waitcnt lgkmcnt(5)
	v_mfma_f32_32x32x16_bf16 v[80:95], v[158:161], v[228:231], v[80:95]
	v_mfma_f32_32x32x16_bf16 v[16:31], v[162:165], v[228:231], v[16:31]
	ds_read_b128 v[228:231], v184 offset:96
	s_waitcnt lgkmcnt(5)
	v_mfma_f32_32x32x16_bf16 v[64:79], v[158:161], v[232:235], v[64:79]
	v_mfma_f32_32x32x16_bf16 v[0:15], v[162:165], v[232:235], v[0:15]
	ds_read_b128 v[232:235], v184 offset:4704
	s_setprio 0
	global_load_dwordx4 v[158:161], v[152:153], off offset:2048
	global_load_dwordx4 v[162:165], v[156:157], off offset:2048
	s_setprio 1
	s_waitcnt lgkmcnt(1)
	v_mfma_f32_32x32x16_bf16 v[112:127], v[200:203], v[228:231], v[112:127]
	v_mfma_f32_32x32x16_bf16 v[48:63], v[208:211], v[228:231], v[48:63]
	s_waitcnt lgkmcnt(0)
	v_mfma_f32_32x32x16_bf16 v[96:111], v[200:203], v[232:235], v[96:111]
	v_mfma_f32_32x32x16_bf16 v[32:47], v[208:211], v[232:235], v[32:47]
	ds_read_b128 v[228:231], v184 offset:9312
	ds_read_b128 v[232:235], v184 offset:13920
	s_waitcnt lgkmcnt(1)
	v_mfma_f32_32x32x16_bf16 v[80:95], v[200:203], v[228:231], v[80:95]
	v_mfma_f32_32x32x16_bf16 v[16:31], v[208:211], v[228:231], v[16:31]
	s_waitcnt lgkmcnt(0)
	v_mfma_f32_32x32x16_bf16 v[64:79], v[200:203], v[232:235], v[64:79]
	v_mfma_f32_32x32x16_bf16 v[0:15], v[208:211], v[232:235], v[0:15]
	s_setprio 0
	s_barrier
	global_load_dwordx4 v[200:203], v[128:129], off offset:2176
	global_load_dwordx4 v[208:211], v[132:133], off offset:2176
	s_waitcnt vmcnt(9)
	ds_write_b128 v191, v[212:215]
	s_waitcnt vmcnt(8)
	ds_write_b128 v191, v[216:219] offset:36864
	ds_read_b128 v[212:215], v169
	ds_read_b128 v[216:219], v169 offset:4608
	ds_read_b128 v[228:231], v168
	ds_read_b128 v[232:235], v168 offset:4608
	s_setprio 1
	s_waitcnt lgkmcnt(1)
	v_mfma_f32_32x32x16_bf16 v[112:127], v[212:215], v[228:231], v[112:127]
	v_mfma_f32_32x32x16_bf16 v[48:63], v[216:219], v[228:231], v[48:63]
	s_waitcnt lgkmcnt(0)
	v_mfma_f32_32x32x16_bf16 v[96:111], v[212:215], v[232:235], v[96:111]
	v_mfma_f32_32x32x16_bf16 v[32:47], v[216:219], v[232:235], v[32:47]
	ds_read_b128 v[228:231], v168 offset:9216
	ds_read_b128 v[232:235], v168 offset:13824
	s_waitcnt vmcnt(7)
	ds_write_b128 v191, v[178:181] offset:9216
	s_waitcnt vmcnt(6)
	ds_write_b128 v191, v[220:223] offset:46080
	ds_read_b128 v[178:181], v169 offset:32
	ds_read_b128 v[220:223], v169 offset:4640
	s_waitcnt lgkmcnt(5)
	v_mfma_f32_32x32x16_bf16 v[80:95], v[212:215], v[228:231], v[80:95]
	v_mfma_f32_32x32x16_bf16 v[16:31], v[216:219], v[228:231], v[16:31]
	ds_read_b128 v[228:231], v168 offset:32
	s_waitcnt lgkmcnt(5)
	v_mfma_f32_32x32x16_bf16 v[64:79], v[212:215], v[232:235], v[64:79]
	v_mfma_f32_32x32x16_bf16 v[0:15], v[216:219], v[232:235], v[0:15]
	ds_read_b128 v[232:235], v168 offset:4640
	s_setprio 0
	global_load_dwordx4 v[212:215], v[136:137], off offset:2176
	global_load_dwordx4 v[216:219], v[140:141], off offset:2176
	s_setprio 1
	s_waitcnt lgkmcnt(1)
	v_mfma_f32_32x32x16_bf16 v[112:127], v[178:181], v[228:231], v[112:127]
	v_mfma_f32_32x32x16_bf16 v[48:63], v[220:223], v[228:231], v[48:63]
	s_waitcnt lgkmcnt(0)
	v_mfma_f32_32x32x16_bf16 v[96:111], v[178:181], v[232:235], v[96:111]
	v_mfma_f32_32x32x16_bf16 v[32:47], v[220:223], v[232:235], v[32:47]
	ds_read_b128 v[228:231], v168 offset:9248
	ds_read_b128 v[232:235], v168 offset:13856
	s_waitcnt vmcnt(7)
	ds_write_b128 v191, v[172:175] offset:18432
	s_waitcnt vmcnt(6)
	ds_write_b128 v191, v[224:227] offset:55296
	ds_read_b128 v[172:175], v169 offset:64
	ds_read_b128 v[224:227], v169 offset:4672
	s_waitcnt lgkmcnt(5)
	v_mfma_f32_32x32x16_bf16 v[80:95], v[178:181], v[228:231], v[80:95]
	v_mfma_f32_32x32x16_bf16 v[16:31], v[220:223], v[228:231], v[16:31]
	ds_read_b128 v[228:231], v168 offset:64
	s_waitcnt lgkmcnt(5)
	v_mfma_f32_32x32x16_bf16 v[64:79], v[178:181], v[232:235], v[64:79]
	v_mfma_f32_32x32x16_bf16 v[0:15], v[220:223], v[232:235], v[0:15]
	ds_read_b128 v[232:235], v168 offset:4672
	s_setprio 0
	global_load_dwordx4 v[178:181], v[144:145], off offset:2176
	global_load_dwordx4 v[220:223], v[148:149], off offset:2176
	s_setprio 1
	s_waitcnt lgkmcnt(1)
	v_mfma_f32_32x32x16_bf16 v[112:127], v[172:175], v[228:231], v[112:127]
	v_mfma_f32_32x32x16_bf16 v[48:63], v[224:227], v[228:231], v[48:63]
	s_waitcnt lgkmcnt(0)
	v_mfma_f32_32x32x16_bf16 v[96:111], v[172:175], v[232:235], v[96:111]
	v_mfma_f32_32x32x16_bf16 v[32:47], v[224:227], v[232:235], v[32:47]
	ds_read_b128 v[228:231], v168 offset:9280
	ds_read_b128 v[232:235], v168 offset:13888
	s_waitcnt vmcnt(7)
	ds_write_b128 v191, v[158:161] offset:27648
	s_waitcnt vmcnt(6)
	ds_write_b128 v191, v[162:165] offset:64512
	ds_read_b128 v[158:161], v169 offset:96
	ds_read_b128 v[162:165], v169 offset:4704
	s_waitcnt lgkmcnt(5)
	v_mfma_f32_32x32x16_bf16 v[80:95], v[172:175], v[228:231], v[80:95]
	v_mfma_f32_32x32x16_bf16 v[16:31], v[224:227], v[228:231], v[16:31]
	ds_read_b128 v[228:231], v168 offset:96
	s_waitcnt lgkmcnt(5)
	v_mfma_f32_32x32x16_bf16 v[64:79], v[172:175], v[232:235], v[64:79]
	v_mfma_f32_32x32x16_bf16 v[0:15], v[224:227], v[232:235], v[0:15]
	ds_read_b128 v[232:235], v168 offset:4704
	s_setprio 0
	global_load_dwordx4 v[172:175], v[152:153], off offset:2176
	global_load_dwordx4 v[224:227], v[156:157], off offset:2176
	s_setprio 1
	s_waitcnt lgkmcnt(1)
	v_mfma_f32_32x32x16_bf16 v[112:127], v[158:161], v[228:231], v[112:127]
	v_mfma_f32_32x32x16_bf16 v[48:63], v[162:165], v[228:231], v[48:63]
	s_waitcnt lgkmcnt(0)
	v_mfma_f32_32x32x16_bf16 v[96:111], v[158:161], v[232:235], v[96:111]
	v_mfma_f32_32x32x16_bf16 v[32:47], v[162:165], v[232:235], v[32:47]
	ds_read_b128 v[228:231], v168 offset:9312
	ds_read_b128 v[232:235], v168 offset:13920
	s_waitcnt lgkmcnt(1)
	v_mfma_f32_32x32x16_bf16 v[80:95], v[158:161], v[228:231], v[80:95]
	v_mfma_f32_32x32x16_bf16 v[16:31], v[162:165], v[228:231], v[16:31]
	s_waitcnt lgkmcnt(0)
	v_mfma_f32_32x32x16_bf16 v[64:79], v[158:161], v[232:235], v[64:79]
	v_mfma_f32_32x32x16_bf16 v[0:15], v[162:165], v[232:235], v[0:15]
	s_setprio 0
	s_barrier
	global_load_dwordx4 v[158:161], v[128:129], off offset:2304
	global_load_dwordx4 v[162:165], v[132:133], off offset:2304
	s_waitcnt vmcnt(9)
	ds_write_b128 v195, v[200:203]
	s_waitcnt vmcnt(8)
	ds_write_b128 v196, v[208:211]
	ds_read_b128 v[200:203], v192 offset:36864
	ds_read_b128 v[208:211], v192 offset:41472
	ds_read_b128 v[228:231], v184
	ds_read_b128 v[232:235], v184 offset:4608
	s_setprio 1
	s_waitcnt lgkmcnt(1)
	v_mfma_f32_32x32x16_bf16 v[112:127], v[200:203], v[228:231], v[112:127]
	v_mfma_f32_32x32x16_bf16 v[48:63], v[208:211], v[228:231], v[48:63]
	s_waitcnt lgkmcnt(0)
	v_mfma_f32_32x32x16_bf16 v[96:111], v[200:203], v[232:235], v[96:111]
	v_mfma_f32_32x32x16_bf16 v[32:47], v[208:211], v[232:235], v[32:47]
	ds_read_b128 v[228:231], v184 offset:9216
	ds_read_b128 v[232:235], v184 offset:13824
	s_waitcnt vmcnt(7)
	ds_write_b128 v194, v[212:215]
	s_waitcnt vmcnt(6)
	ds_write_b128 v193, v[216:219]
	ds_read_b128 v[212:215], v192 offset:36896
	ds_read_b128 v[216:219], v192 offset:41504
	s_waitcnt lgkmcnt(5)
	v_mfma_f32_32x32x16_bf16 v[80:95], v[200:203], v[228:231], v[80:95]
	v_mfma_f32_32x32x16_bf16 v[16:31], v[208:211], v[228:231], v[16:31]
	ds_read_b128 v[228:231], v184 offset:32
	s_waitcnt lgkmcnt(5)
	v_mfma_f32_32x32x16_bf16 v[64:79], v[200:203], v[232:235], v[64:79]
	v_mfma_f32_32x32x16_bf16 v[0:15], v[208:211], v[232:235], v[0:15]
	ds_read_b128 v[232:235], v184 offset:4640
	s_setprio 0
	global_load_dwordx4 v[200:203], v[136:137], off offset:2304
	global_load_dwordx4 v[208:211], v[140:141], off offset:2304
	s_setprio 1
	s_waitcnt lgkmcnt(1)
	v_mfma_f32_32x32x16_bf16 v[112:127], v[212:215], v[228:231], v[112:127]
	v_mfma_f32_32x32x16_bf16 v[48:63], v[216:219], v[228:231], v[48:63]
	s_waitcnt lgkmcnt(0)
	v_mfma_f32_32x32x16_bf16 v[96:111], v[212:215], v[232:235], v[96:111]
	v_mfma_f32_32x32x16_bf16 v[32:47], v[216:219], v[232:235], v[32:47]
	ds_read_b128 v[228:231], v184 offset:9248
	ds_read_b128 v[232:235], v184 offset:13856
	s_waitcnt vmcnt(7)
	ds_write_b128 v177, v[178:181]
	s_waitcnt vmcnt(6)
	ds_write_b128 v176, v[220:223]
	ds_read_b128 v[178:181], v192 offset:36928
	ds_read_b128 v[220:223], v192 offset:41536
	s_waitcnt lgkmcnt(5)
	v_mfma_f32_32x32x16_bf16 v[80:95], v[212:215], v[228:231], v[80:95]
	v_mfma_f32_32x32x16_bf16 v[16:31], v[216:219], v[228:231], v[16:31]
	ds_read_b128 v[228:231], v184 offset:64
	s_waitcnt lgkmcnt(5)
	v_mfma_f32_32x32x16_bf16 v[64:79], v[212:215], v[232:235], v[64:79]
	v_mfma_f32_32x32x16_bf16 v[0:15], v[216:219], v[232:235], v[0:15]
	ds_read_b128 v[232:235], v184 offset:4672
	s_setprio 0
	global_load_dwordx4 v[212:215], v[144:145], off offset:2304
	global_load_dwordx4 v[216:219], v[148:149], off offset:2304
	s_setprio 1
	s_waitcnt lgkmcnt(1)
	v_mfma_f32_32x32x16_bf16 v[112:127], v[178:181], v[228:231], v[112:127]
	v_mfma_f32_32x32x16_bf16 v[48:63], v[220:223], v[228:231], v[48:63]
	s_waitcnt lgkmcnt(0)
	v_mfma_f32_32x32x16_bf16 v[96:111], v[178:181], v[232:235], v[96:111]
	v_mfma_f32_32x32x16_bf16 v[32:47], v[220:223], v[232:235], v[32:47]
	ds_read_b128 v[228:231], v184 offset:9280
	ds_read_b128 v[232:235], v184 offset:13888
	s_waitcnt vmcnt(7)
	ds_write_b128 v171, v[172:175]
	s_waitcnt vmcnt(6)
	ds_write_b128 v170, v[224:227]
	ds_read_b128 v[172:175], v192 offset:36960
	ds_read_b128 v[224:227], v192 offset:41568
	s_waitcnt lgkmcnt(5)
	v_mfma_f32_32x32x16_bf16 v[80:95], v[178:181], v[228:231], v[80:95]
	v_mfma_f32_32x32x16_bf16 v[16:31], v[220:223], v[228:231], v[16:31]
	ds_read_b128 v[228:231], v184 offset:96
	s_waitcnt lgkmcnt(5)
	v_mfma_f32_32x32x16_bf16 v[64:79], v[178:181], v[232:235], v[64:79]
	v_mfma_f32_32x32x16_bf16 v[0:15], v[220:223], v[232:235], v[0:15]
	ds_read_b128 v[232:235], v184 offset:4704
	s_setprio 0
	global_load_dwordx4 v[178:181], v[152:153], off offset:2304
	global_load_dwordx4 v[220:223], v[156:157], off offset:2304
	s_setprio 1
	s_waitcnt lgkmcnt(1)
	v_mfma_f32_32x32x16_bf16 v[112:127], v[172:175], v[228:231], v[112:127]
	v_mfma_f32_32x32x16_bf16 v[48:63], v[224:227], v[228:231], v[48:63]
	s_waitcnt lgkmcnt(0)
	v_mfma_f32_32x32x16_bf16 v[96:111], v[172:175], v[232:235], v[96:111]
	v_mfma_f32_32x32x16_bf16 v[32:47], v[224:227], v[232:235], v[32:47]
	ds_read_b128 v[228:231], v184 offset:9312
	ds_read_b128 v[232:235], v184 offset:13920
	s_waitcnt lgkmcnt(1)
	v_mfma_f32_32x32x16_bf16 v[80:95], v[172:175], v[228:231], v[80:95]
	v_mfma_f32_32x32x16_bf16 v[16:31], v[224:227], v[228:231], v[16:31]
	s_waitcnt lgkmcnt(0)
	v_mfma_f32_32x32x16_bf16 v[64:79], v[172:175], v[232:235], v[64:79]
	v_mfma_f32_32x32x16_bf16 v[0:15], v[224:227], v[232:235], v[0:15]
	s_setprio 0
	s_barrier
	global_load_dwordx4 v[172:175], v[128:129], off offset:2432
	global_load_dwordx4 v[224:227], v[132:133], off offset:2432
	s_waitcnt vmcnt(9)
	ds_write_b128 v191, v[158:161]
	s_waitcnt vmcnt(8)
	ds_write_b128 v191, v[162:165] offset:36864
	ds_read_b128 v[158:161], v169
	ds_read_b128 v[162:165], v169 offset:4608
	ds_read_b128 v[228:231], v168
	ds_read_b128 v[232:235], v168 offset:4608
	s_setprio 1
	s_waitcnt lgkmcnt(1)
	v_mfma_f32_32x32x16_bf16 v[112:127], v[158:161], v[228:231], v[112:127]
	v_mfma_f32_32x32x16_bf16 v[48:63], v[162:165], v[228:231], v[48:63]
	s_waitcnt lgkmcnt(0)
	v_mfma_f32_32x32x16_bf16 v[96:111], v[158:161], v[232:235], v[96:111]
	v_mfma_f32_32x32x16_bf16 v[32:47], v[162:165], v[232:235], v[32:47]
	ds_read_b128 v[228:231], v168 offset:9216
	ds_read_b128 v[232:235], v168 offset:13824
	s_waitcnt vmcnt(7)
	ds_write_b128 v191, v[200:203] offset:9216
	s_waitcnt vmcnt(6)
	ds_write_b128 v191, v[208:211] offset:46080
	ds_read_b128 v[200:203], v169 offset:32
	ds_read_b128 v[208:211], v169 offset:4640
	s_waitcnt lgkmcnt(5)
	v_mfma_f32_32x32x16_bf16 v[80:95], v[158:161], v[228:231], v[80:95]
	v_mfma_f32_32x32x16_bf16 v[16:31], v[162:165], v[228:231], v[16:31]
	ds_read_b128 v[228:231], v168 offset:32
	s_waitcnt lgkmcnt(5)
	v_mfma_f32_32x32x16_bf16 v[64:79], v[158:161], v[232:235], v[64:79]
	v_mfma_f32_32x32x16_bf16 v[0:15], v[162:165], v[232:235], v[0:15]
	ds_read_b128 v[232:235], v168 offset:4640
	s_setprio 0
	global_load_dwordx4 v[158:161], v[136:137], off offset:2432
	global_load_dwordx4 v[162:165], v[140:141], off offset:2432
	s_setprio 1
	s_waitcnt lgkmcnt(1)
	v_mfma_f32_32x32x16_bf16 v[112:127], v[200:203], v[228:231], v[112:127]
	v_mfma_f32_32x32x16_bf16 v[48:63], v[208:211], v[228:231], v[48:63]
	s_waitcnt lgkmcnt(0)
	v_mfma_f32_32x32x16_bf16 v[96:111], v[200:203], v[232:235], v[96:111]
	v_mfma_f32_32x32x16_bf16 v[32:47], v[208:211], v[232:235], v[32:47]
	ds_read_b128 v[228:231], v168 offset:9248
	ds_read_b128 v[232:235], v168 offset:13856
	s_waitcnt vmcnt(7)
	ds_write_b128 v191, v[212:215] offset:18432
	s_waitcnt vmcnt(6)
	ds_write_b128 v191, v[216:219] offset:55296
	ds_read_b128 v[212:215], v169 offset:64
	ds_read_b128 v[216:219], v169 offset:4672
	s_waitcnt lgkmcnt(5)
	v_mfma_f32_32x32x16_bf16 v[80:95], v[200:203], v[228:231], v[80:95]
	v_mfma_f32_32x32x16_bf16 v[16:31], v[208:211], v[228:231], v[16:31]
	ds_read_b128 v[228:231], v168 offset:64
	s_waitcnt lgkmcnt(5)
	v_mfma_f32_32x32x16_bf16 v[64:79], v[200:203], v[232:235], v[64:79]
	v_mfma_f32_32x32x16_bf16 v[0:15], v[208:211], v[232:235], v[0:15]
	ds_read_b128 v[232:235], v168 offset:4672
	s_setprio 0
	global_load_dwordx4 v[200:203], v[144:145], off offset:2432
	global_load_dwordx4 v[208:211], v[148:149], off offset:2432
	s_setprio 1
	s_waitcnt lgkmcnt(1)
	v_mfma_f32_32x32x16_bf16 v[112:127], v[212:215], v[228:231], v[112:127]
	v_mfma_f32_32x32x16_bf16 v[48:63], v[216:219], v[228:231], v[48:63]
	s_waitcnt lgkmcnt(0)
	v_mfma_f32_32x32x16_bf16 v[96:111], v[212:215], v[232:235], v[96:111]
	v_mfma_f32_32x32x16_bf16 v[32:47], v[216:219], v[232:235], v[32:47]
	ds_read_b128 v[228:231], v168 offset:9280
	ds_read_b128 v[232:235], v168 offset:13888
	s_waitcnt vmcnt(7)
	ds_write_b128 v191, v[178:181] offset:27648
	s_waitcnt vmcnt(6)
	ds_write_b128 v191, v[220:223] offset:64512
	ds_read_b128 v[178:181], v169 offset:96
	ds_read_b128 v[220:223], v169 offset:4704
	s_waitcnt lgkmcnt(5)
	v_mfma_f32_32x32x16_bf16 v[80:95], v[212:215], v[228:231], v[80:95]
	v_mfma_f32_32x32x16_bf16 v[16:31], v[216:219], v[228:231], v[16:31]
	ds_read_b128 v[228:231], v168 offset:96
	s_waitcnt lgkmcnt(5)
	v_mfma_f32_32x32x16_bf16 v[64:79], v[212:215], v[232:235], v[64:79]
	v_mfma_f32_32x32x16_bf16 v[0:15], v[216:219], v[232:235], v[0:15]
	ds_read_b128 v[232:235], v168 offset:4704
	s_setprio 0
	global_load_dwordx4 v[212:215], v[152:153], off offset:2432
	global_load_dwordx4 v[216:219], v[156:157], off offset:2432
	s_setprio 1
	s_waitcnt lgkmcnt(1)
	v_mfma_f32_32x32x16_bf16 v[112:127], v[178:181], v[228:231], v[112:127]
	v_mfma_f32_32x32x16_bf16 v[48:63], v[220:223], v[228:231], v[48:63]
	s_waitcnt lgkmcnt(0)
	v_mfma_f32_32x32x16_bf16 v[96:111], v[178:181], v[232:235], v[96:111]
	v_mfma_f32_32x32x16_bf16 v[32:47], v[220:223], v[232:235], v[32:47]
	ds_read_b128 v[228:231], v168 offset:9312
	ds_read_b128 v[232:235], v168 offset:13920
	s_waitcnt lgkmcnt(1)
	v_mfma_f32_32x32x16_bf16 v[80:95], v[178:181], v[228:231], v[80:95]
	v_mfma_f32_32x32x16_bf16 v[16:31], v[220:223], v[228:231], v[16:31]
	s_waitcnt lgkmcnt(0)
	v_mfma_f32_32x32x16_bf16 v[64:79], v[178:181], v[232:235], v[64:79]
	v_mfma_f32_32x32x16_bf16 v[0:15], v[220:223], v[232:235], v[0:15]
	s_setprio 0
	s_barrier
	global_load_dwordx4 v[178:181], v[128:129], off offset:2560
	global_load_dwordx4 v[220:223], v[132:133], off offset:2560
	s_waitcnt vmcnt(9)
	ds_write_b128 v195, v[172:175]
	s_waitcnt vmcnt(8)
	ds_write_b128 v196, v[224:227]
	ds_read_b128 v[172:175], v192 offset:36864
	ds_read_b128 v[224:227], v192 offset:41472
	ds_read_b128 v[228:231], v184
	ds_read_b128 v[232:235], v184 offset:4608
	s_setprio 1
	s_waitcnt lgkmcnt(1)
	v_mfma_f32_32x32x16_bf16 v[112:127], v[172:175], v[228:231], v[112:127]
	v_mfma_f32_32x32x16_bf16 v[48:63], v[224:227], v[228:231], v[48:63]
	s_waitcnt lgkmcnt(0)
	v_mfma_f32_32x32x16_bf16 v[96:111], v[172:175], v[232:235], v[96:111]
	v_mfma_f32_32x32x16_bf16 v[32:47], v[224:227], v[232:235], v[32:47]
	ds_read_b128 v[228:231], v184 offset:9216
	ds_read_b128 v[232:235], v184 offset:13824
	s_waitcnt vmcnt(7)
	ds_write_b128 v194, v[158:161]
	s_waitcnt vmcnt(6)
	ds_write_b128 v193, v[162:165]
	ds_read_b128 v[158:161], v192 offset:36896
	ds_read_b128 v[162:165], v192 offset:41504
	s_waitcnt lgkmcnt(5)
	v_mfma_f32_32x32x16_bf16 v[80:95], v[172:175], v[228:231], v[80:95]
	v_mfma_f32_32x32x16_bf16 v[16:31], v[224:227], v[228:231], v[16:31]
	ds_read_b128 v[228:231], v184 offset:32
	s_waitcnt lgkmcnt(5)
	v_mfma_f32_32x32x16_bf16 v[64:79], v[172:175], v[232:235], v[64:79]
	v_mfma_f32_32x32x16_bf16 v[0:15], v[224:227], v[232:235], v[0:15]
	ds_read_b128 v[232:235], v184 offset:4640
	s_setprio 0
	global_load_dwordx4 v[172:175], v[136:137], off offset:2560
	global_load_dwordx4 v[224:227], v[140:141], off offset:2560
	s_setprio 1
	s_waitcnt lgkmcnt(1)
	v_mfma_f32_32x32x16_bf16 v[112:127], v[158:161], v[228:231], v[112:127]
	v_mfma_f32_32x32x16_bf16 v[48:63], v[162:165], v[228:231], v[48:63]
	s_waitcnt lgkmcnt(0)
	v_mfma_f32_32x32x16_bf16 v[96:111], v[158:161], v[232:235], v[96:111]
	v_mfma_f32_32x32x16_bf16 v[32:47], v[162:165], v[232:235], v[32:47]
	ds_read_b128 v[228:231], v184 offset:9248
	ds_read_b128 v[232:235], v184 offset:13856
	s_waitcnt vmcnt(7)
	ds_write_b128 v177, v[200:203]
	s_waitcnt vmcnt(6)
	ds_write_b128 v176, v[208:211]
	ds_read_b128 v[200:203], v192 offset:36928
	ds_read_b128 v[208:211], v192 offset:41536
	s_waitcnt lgkmcnt(5)
	v_mfma_f32_32x32x16_bf16 v[80:95], v[158:161], v[228:231], v[80:95]
	v_mfma_f32_32x32x16_bf16 v[16:31], v[162:165], v[228:231], v[16:31]
	ds_read_b128 v[228:231], v184 offset:64
	s_waitcnt lgkmcnt(5)
	v_mfma_f32_32x32x16_bf16 v[64:79], v[158:161], v[232:235], v[64:79]
	v_mfma_f32_32x32x16_bf16 v[0:15], v[162:165], v[232:235], v[0:15]
	ds_read_b128 v[232:235], v184 offset:4672
	s_setprio 0
	global_load_dwordx4 v[158:161], v[144:145], off offset:2560
	global_load_dwordx4 v[162:165], v[148:149], off offset:2560
	s_setprio 1
	s_waitcnt lgkmcnt(1)
	v_mfma_f32_32x32x16_bf16 v[112:127], v[200:203], v[228:231], v[112:127]
	v_mfma_f32_32x32x16_bf16 v[48:63], v[208:211], v[228:231], v[48:63]
	s_waitcnt lgkmcnt(0)
	v_mfma_f32_32x32x16_bf16 v[96:111], v[200:203], v[232:235], v[96:111]
	v_mfma_f32_32x32x16_bf16 v[32:47], v[208:211], v[232:235], v[32:47]
	ds_read_b128 v[228:231], v184 offset:9280
	ds_read_b128 v[232:235], v184 offset:13888
	s_waitcnt vmcnt(7)
	ds_write_b128 v171, v[212:215]
	s_waitcnt vmcnt(6)
	ds_write_b128 v170, v[216:219]
	ds_read_b128 v[212:215], v192 offset:36960
	ds_read_b128 v[216:219], v192 offset:41568
	s_waitcnt lgkmcnt(5)
	v_mfma_f32_32x32x16_bf16 v[80:95], v[200:203], v[228:231], v[80:95]
	v_mfma_f32_32x32x16_bf16 v[16:31], v[208:211], v[228:231], v[16:31]
	ds_read_b128 v[228:231], v184 offset:96
	s_waitcnt lgkmcnt(5)
	v_mfma_f32_32x32x16_bf16 v[64:79], v[200:203], v[232:235], v[64:79]
	v_mfma_f32_32x32x16_bf16 v[0:15], v[208:211], v[232:235], v[0:15]
	ds_read_b128 v[232:235], v184 offset:4704
	s_setprio 0
	global_load_dwordx4 v[200:203], v[152:153], off offset:2560
	global_load_dwordx4 v[208:211], v[156:157], off offset:2560
	s_setprio 1
	s_waitcnt lgkmcnt(1)
	v_mfma_f32_32x32x16_bf16 v[112:127], v[212:215], v[228:231], v[112:127]
	v_mfma_f32_32x32x16_bf16 v[48:63], v[216:219], v[228:231], v[48:63]
	s_waitcnt lgkmcnt(0)
	v_mfma_f32_32x32x16_bf16 v[96:111], v[212:215], v[232:235], v[96:111]
	v_mfma_f32_32x32x16_bf16 v[32:47], v[216:219], v[232:235], v[32:47]
	ds_read_b128 v[228:231], v184 offset:9312
	ds_read_b128 v[232:235], v184 offset:13920
	s_waitcnt lgkmcnt(1)
	v_mfma_f32_32x32x16_bf16 v[80:95], v[212:215], v[228:231], v[80:95]
	v_mfma_f32_32x32x16_bf16 v[16:31], v[216:219], v[228:231], v[16:31]
	s_waitcnt lgkmcnt(0)
	v_mfma_f32_32x32x16_bf16 v[64:79], v[212:215], v[232:235], v[64:79]
	v_mfma_f32_32x32x16_bf16 v[0:15], v[216:219], v[232:235], v[0:15]
	s_setprio 0
	s_barrier
	global_load_dwordx4 v[212:215], v[128:129], off offset:2688
	global_load_dwordx4 v[216:219], v[132:133], off offset:2688
	s_waitcnt vmcnt(9)
	ds_write_b128 v191, v[178:181]
	s_waitcnt vmcnt(8)
	ds_write_b128 v191, v[220:223] offset:36864
	ds_read_b128 v[178:181], v169
	ds_read_b128 v[220:223], v169 offset:4608
	ds_read_b128 v[228:231], v168
	ds_read_b128 v[232:235], v168 offset:4608
	s_setprio 1
	s_waitcnt lgkmcnt(1)
	v_mfma_f32_32x32x16_bf16 v[112:127], v[178:181], v[228:231], v[112:127]
	v_mfma_f32_32x32x16_bf16 v[48:63], v[220:223], v[228:231], v[48:63]
	s_waitcnt lgkmcnt(0)
	v_mfma_f32_32x32x16_bf16 v[96:111], v[178:181], v[232:235], v[96:111]
	v_mfma_f32_32x32x16_bf16 v[32:47], v[220:223], v[232:235], v[32:47]
	ds_read_b128 v[228:231], v168 offset:9216
	ds_read_b128 v[232:235], v168 offset:13824
	s_waitcnt vmcnt(7)
	ds_write_b128 v191, v[172:175] offset:9216
	s_waitcnt vmcnt(6)
	ds_write_b128 v191, v[224:227] offset:46080
	ds_read_b128 v[172:175], v169 offset:32
	ds_read_b128 v[224:227], v169 offset:4640
	s_waitcnt lgkmcnt(5)
	v_mfma_f32_32x32x16_bf16 v[80:95], v[178:181], v[228:231], v[80:95]
	v_mfma_f32_32x32x16_bf16 v[16:31], v[220:223], v[228:231], v[16:31]
	ds_read_b128 v[228:231], v168 offset:32
	s_waitcnt lgkmcnt(5)
	v_mfma_f32_32x32x16_bf16 v[64:79], v[178:181], v[232:235], v[64:79]
	v_mfma_f32_32x32x16_bf16 v[0:15], v[220:223], v[232:235], v[0:15]
	ds_read_b128 v[232:235], v168 offset:4640
	s_setprio 0
	global_load_dwordx4 v[178:181], v[136:137], off offset:2688
	global_load_dwordx4 v[220:223], v[140:141], off offset:2688
	s_setprio 1
	s_waitcnt lgkmcnt(1)
	v_mfma_f32_32x32x16_bf16 v[112:127], v[172:175], v[228:231], v[112:127]
	v_mfma_f32_32x32x16_bf16 v[48:63], v[224:227], v[228:231], v[48:63]
	s_waitcnt lgkmcnt(0)
	v_mfma_f32_32x32x16_bf16 v[96:111], v[172:175], v[232:235], v[96:111]
	v_mfma_f32_32x32x16_bf16 v[32:47], v[224:227], v[232:235], v[32:47]
	ds_read_b128 v[228:231], v168 offset:9248
	ds_read_b128 v[232:235], v168 offset:13856
	s_waitcnt vmcnt(7)
	ds_write_b128 v191, v[158:161] offset:18432
	s_waitcnt vmcnt(6)
	ds_write_b128 v191, v[162:165] offset:55296
	ds_read_b128 v[158:161], v169 offset:64
	ds_read_b128 v[162:165], v169 offset:4672
	s_waitcnt lgkmcnt(5)
	v_mfma_f32_32x32x16_bf16 v[80:95], v[172:175], v[228:231], v[80:95]
	v_mfma_f32_32x32x16_bf16 v[16:31], v[224:227], v[228:231], v[16:31]
	ds_read_b128 v[228:231], v168 offset:64
	s_waitcnt lgkmcnt(5)
	v_mfma_f32_32x32x16_bf16 v[64:79], v[172:175], v[232:235], v[64:79]
	v_mfma_f32_32x32x16_bf16 v[0:15], v[224:227], v[232:235], v[0:15]
	ds_read_b128 v[232:235], v168 offset:4672
	s_setprio 0
	global_load_dwordx4 v[172:175], v[144:145], off offset:2688
	global_load_dwordx4 v[224:227], v[148:149], off offset:2688
	s_setprio 1
	s_waitcnt lgkmcnt(1)
	v_mfma_f32_32x32x16_bf16 v[112:127], v[158:161], v[228:231], v[112:127]
	v_mfma_f32_32x32x16_bf16 v[48:63], v[162:165], v[228:231], v[48:63]
	s_waitcnt lgkmcnt(0)
	v_mfma_f32_32x32x16_bf16 v[96:111], v[158:161], v[232:235], v[96:111]
	v_mfma_f32_32x32x16_bf16 v[32:47], v[162:165], v[232:235], v[32:47]
	ds_read_b128 v[228:231], v168 offset:9280
	ds_read_b128 v[232:235], v168 offset:13888
	s_waitcnt vmcnt(7)
	ds_write_b128 v191, v[200:203] offset:27648
	s_waitcnt vmcnt(6)
	ds_write_b128 v191, v[208:211] offset:64512
	ds_read_b128 v[200:203], v169 offset:96
	ds_read_b128 v[208:211], v169 offset:4704
	s_waitcnt lgkmcnt(5)
	v_mfma_f32_32x32x16_bf16 v[80:95], v[158:161], v[228:231], v[80:95]
	v_mfma_f32_32x32x16_bf16 v[16:31], v[162:165], v[228:231], v[16:31]
	ds_read_b128 v[228:231], v168 offset:96
	s_waitcnt lgkmcnt(5)
	v_mfma_f32_32x32x16_bf16 v[64:79], v[158:161], v[232:235], v[64:79]
	v_mfma_f32_32x32x16_bf16 v[0:15], v[162:165], v[232:235], v[0:15]
	ds_read_b128 v[232:235], v168 offset:4704
	s_setprio 0
	global_load_dwordx4 v[158:161], v[152:153], off offset:2688
	global_load_dwordx4 v[162:165], v[156:157], off offset:2688
	s_setprio 1
	s_waitcnt lgkmcnt(1)
	v_mfma_f32_32x32x16_bf16 v[112:127], v[200:203], v[228:231], v[112:127]
	v_mfma_f32_32x32x16_bf16 v[48:63], v[208:211], v[228:231], v[48:63]
	s_waitcnt lgkmcnt(0)
	v_mfma_f32_32x32x16_bf16 v[96:111], v[200:203], v[232:235], v[96:111]
	v_mfma_f32_32x32x16_bf16 v[32:47], v[208:211], v[232:235], v[32:47]
	ds_read_b128 v[228:231], v168 offset:9312
	ds_read_b128 v[232:235], v168 offset:13920
	s_waitcnt lgkmcnt(1)
	v_mfma_f32_32x32x16_bf16 v[80:95], v[200:203], v[228:231], v[80:95]
	v_mfma_f32_32x32x16_bf16 v[16:31], v[208:211], v[228:231], v[16:31]
	s_waitcnt lgkmcnt(0)
	v_mfma_f32_32x32x16_bf16 v[64:79], v[200:203], v[232:235], v[64:79]
	v_mfma_f32_32x32x16_bf16 v[0:15], v[208:211], v[232:235], v[0:15]
	s_setprio 0
	s_barrier
	global_load_dwordx4 v[200:203], v[128:129], off offset:2816
	global_load_dwordx4 v[208:211], v[132:133], off offset:2816
	s_waitcnt vmcnt(9)
	ds_write_b128 v195, v[212:215]
	s_waitcnt vmcnt(8)
	ds_write_b128 v196, v[216:219]
	ds_read_b128 v[212:215], v192 offset:36864
	ds_read_b128 v[216:219], v192 offset:41472
	ds_read_b128 v[228:231], v184
	ds_read_b128 v[232:235], v184 offset:4608
	s_setprio 1
	s_waitcnt lgkmcnt(1)
	v_mfma_f32_32x32x16_bf16 v[112:127], v[212:215], v[228:231], v[112:127]
	v_mfma_f32_32x32x16_bf16 v[48:63], v[216:219], v[228:231], v[48:63]
	s_waitcnt lgkmcnt(0)
	v_mfma_f32_32x32x16_bf16 v[96:111], v[212:215], v[232:235], v[96:111]
	v_mfma_f32_32x32x16_bf16 v[32:47], v[216:219], v[232:235], v[32:47]
	ds_read_b128 v[228:231], v184 offset:9216
	ds_read_b128 v[232:235], v184 offset:13824
	s_waitcnt vmcnt(7)
	ds_write_b128 v194, v[178:181]
	s_waitcnt vmcnt(6)
	ds_write_b128 v193, v[220:223]
	ds_read_b128 v[178:181], v192 offset:36896
	ds_read_b128 v[220:223], v192 offset:41504
	s_waitcnt lgkmcnt(5)
	v_mfma_f32_32x32x16_bf16 v[80:95], v[212:215], v[228:231], v[80:95]
	v_mfma_f32_32x32x16_bf16 v[16:31], v[216:219], v[228:231], v[16:31]
	ds_read_b128 v[228:231], v184 offset:32
	s_waitcnt lgkmcnt(5)
	v_mfma_f32_32x32x16_bf16 v[64:79], v[212:215], v[232:235], v[64:79]
	v_mfma_f32_32x32x16_bf16 v[0:15], v[216:219], v[232:235], v[0:15]
	ds_read_b128 v[232:235], v184 offset:4640
	s_setprio 0
	global_load_dwordx4 v[212:215], v[136:137], off offset:2816
	global_load_dwordx4 v[216:219], v[140:141], off offset:2816
	s_setprio 1
	s_waitcnt lgkmcnt(1)
	v_mfma_f32_32x32x16_bf16 v[112:127], v[178:181], v[228:231], v[112:127]
	v_mfma_f32_32x32x16_bf16 v[48:63], v[220:223], v[228:231], v[48:63]
	s_waitcnt lgkmcnt(0)
	v_mfma_f32_32x32x16_bf16 v[96:111], v[178:181], v[232:235], v[96:111]
	v_mfma_f32_32x32x16_bf16 v[32:47], v[220:223], v[232:235], v[32:47]
	ds_read_b128 v[228:231], v184 offset:9248
	ds_read_b128 v[232:235], v184 offset:13856
	s_waitcnt vmcnt(7)
	ds_write_b128 v177, v[172:175]
	s_waitcnt vmcnt(6)
	ds_write_b128 v176, v[224:227]
	ds_read_b128 v[172:175], v192 offset:36928
	ds_read_b128 v[224:227], v192 offset:41536
	s_waitcnt lgkmcnt(5)
	v_mfma_f32_32x32x16_bf16 v[80:95], v[178:181], v[228:231], v[80:95]
	v_mfma_f32_32x32x16_bf16 v[16:31], v[220:223], v[228:231], v[16:31]
	ds_read_b128 v[228:231], v184 offset:64
	s_waitcnt lgkmcnt(5)
	v_mfma_f32_32x32x16_bf16 v[64:79], v[178:181], v[232:235], v[64:79]
	v_mfma_f32_32x32x16_bf16 v[0:15], v[220:223], v[232:235], v[0:15]
	ds_read_b128 v[232:235], v184 offset:4672
	s_setprio 0
	global_load_dwordx4 v[178:181], v[144:145], off offset:2816
	global_load_dwordx4 v[220:223], v[148:149], off offset:2816
	s_setprio 1
	s_waitcnt lgkmcnt(1)
	v_mfma_f32_32x32x16_bf16 v[112:127], v[172:175], v[228:231], v[112:127]
	v_mfma_f32_32x32x16_bf16 v[48:63], v[224:227], v[228:231], v[48:63]
	s_waitcnt lgkmcnt(0)
	v_mfma_f32_32x32x16_bf16 v[96:111], v[172:175], v[232:235], v[96:111]
	v_mfma_f32_32x32x16_bf16 v[32:47], v[224:227], v[232:235], v[32:47]
	ds_read_b128 v[228:231], v184 offset:9280
	ds_read_b128 v[232:235], v184 offset:13888
	s_waitcnt vmcnt(7)
	ds_write_b128 v171, v[158:161]
	s_waitcnt vmcnt(6)
	ds_write_b128 v170, v[162:165]
	ds_read_b128 v[158:161], v192 offset:36960
	ds_read_b128 v[162:165], v192 offset:41568
	s_waitcnt lgkmcnt(5)
	v_mfma_f32_32x32x16_bf16 v[80:95], v[172:175], v[228:231], v[80:95]
	v_mfma_f32_32x32x16_bf16 v[16:31], v[224:227], v[228:231], v[16:31]
	ds_read_b128 v[228:231], v184 offset:96
	s_waitcnt lgkmcnt(5)
	v_mfma_f32_32x32x16_bf16 v[64:79], v[172:175], v[232:235], v[64:79]
	v_mfma_f32_32x32x16_bf16 v[0:15], v[224:227], v[232:235], v[0:15]
	ds_read_b128 v[232:235], v184 offset:4704
	s_setprio 0
	global_load_dwordx4 v[172:175], v[152:153], off offset:2816
	global_load_dwordx4 v[224:227], v[156:157], off offset:2816
	s_setprio 1
	s_waitcnt lgkmcnt(1)
	v_mfma_f32_32x32x16_bf16 v[112:127], v[158:161], v[228:231], v[112:127]
	v_mfma_f32_32x32x16_bf16 v[48:63], v[162:165], v[228:231], v[48:63]
	s_waitcnt lgkmcnt(0)
	v_mfma_f32_32x32x16_bf16 v[96:111], v[158:161], v[232:235], v[96:111]
	v_mfma_f32_32x32x16_bf16 v[32:47], v[162:165], v[232:235], v[32:47]
	ds_read_b128 v[228:231], v184 offset:9312
	ds_read_b128 v[232:235], v184 offset:13920
	s_waitcnt lgkmcnt(1)
	v_mfma_f32_32x32x16_bf16 v[80:95], v[158:161], v[228:231], v[80:95]
	v_mfma_f32_32x32x16_bf16 v[16:31], v[162:165], v[228:231], v[16:31]
	s_waitcnt lgkmcnt(0)
	v_mfma_f32_32x32x16_bf16 v[64:79], v[158:161], v[232:235], v[64:79]
	v_mfma_f32_32x32x16_bf16 v[0:15], v[162:165], v[232:235], v[0:15]
	s_setprio 0
	s_barrier
	global_load_dwordx4 v[158:161], v[128:129], off offset:2944
	global_load_dwordx4 v[162:165], v[132:133], off offset:2944
	s_waitcnt vmcnt(9)
	ds_write_b128 v191, v[200:203]
	s_waitcnt vmcnt(8)
	ds_write_b128 v191, v[208:211] offset:36864
	ds_read_b128 v[200:203], v169
	ds_read_b128 v[208:211], v169 offset:4608
	ds_read_b128 v[228:231], v168
	ds_read_b128 v[232:235], v168 offset:4608
	s_setprio 1
	s_waitcnt lgkmcnt(1)
	v_mfma_f32_32x32x16_bf16 v[112:127], v[200:203], v[228:231], v[112:127]
	v_mfma_f32_32x32x16_bf16 v[48:63], v[208:211], v[228:231], v[48:63]
	s_waitcnt lgkmcnt(0)
	v_mfma_f32_32x32x16_bf16 v[96:111], v[200:203], v[232:235], v[96:111]
	v_mfma_f32_32x32x16_bf16 v[32:47], v[208:211], v[232:235], v[32:47]
	ds_read_b128 v[228:231], v168 offset:9216
	ds_read_b128 v[232:235], v168 offset:13824
	s_waitcnt vmcnt(7)
	ds_write_b128 v191, v[212:215] offset:9216
	s_waitcnt vmcnt(6)
	ds_write_b128 v191, v[216:219] offset:46080
	ds_read_b128 v[212:215], v169 offset:32
	ds_read_b128 v[216:219], v169 offset:4640
	s_waitcnt lgkmcnt(5)
	v_mfma_f32_32x32x16_bf16 v[80:95], v[200:203], v[228:231], v[80:95]
	v_mfma_f32_32x32x16_bf16 v[16:31], v[208:211], v[228:231], v[16:31]
	ds_read_b128 v[228:231], v168 offset:32
	s_waitcnt lgkmcnt(5)
	v_mfma_f32_32x32x16_bf16 v[64:79], v[200:203], v[232:235], v[64:79]
	v_mfma_f32_32x32x16_bf16 v[0:15], v[208:211], v[232:235], v[0:15]
	ds_read_b128 v[232:235], v168 offset:4640
	s_setprio 0
	global_load_dwordx4 v[200:203], v[136:137], off offset:2944
	global_load_dwordx4 v[208:211], v[140:141], off offset:2944
	s_setprio 1
	s_waitcnt lgkmcnt(1)
	v_mfma_f32_32x32x16_bf16 v[112:127], v[212:215], v[228:231], v[112:127]
	v_mfma_f32_32x32x16_bf16 v[48:63], v[216:219], v[228:231], v[48:63]
	s_waitcnt lgkmcnt(0)
	v_mfma_f32_32x32x16_bf16 v[96:111], v[212:215], v[232:235], v[96:111]
	v_mfma_f32_32x32x16_bf16 v[32:47], v[216:219], v[232:235], v[32:47]
	ds_read_b128 v[228:231], v168 offset:9248
	ds_read_b128 v[232:235], v168 offset:13856
	s_waitcnt vmcnt(7)
	ds_write_b128 v191, v[178:181] offset:18432
	s_waitcnt vmcnt(6)
	ds_write_b128 v191, v[220:223] offset:55296
	ds_read_b128 v[178:181], v169 offset:64
	ds_read_b128 v[220:223], v169 offset:4672
	s_waitcnt lgkmcnt(5)
	v_mfma_f32_32x32x16_bf16 v[80:95], v[212:215], v[228:231], v[80:95]
	v_mfma_f32_32x32x16_bf16 v[16:31], v[216:219], v[228:231], v[16:31]
	ds_read_b128 v[228:231], v168 offset:64
	s_waitcnt lgkmcnt(5)
	v_mfma_f32_32x32x16_bf16 v[64:79], v[212:215], v[232:235], v[64:79]
	v_mfma_f32_32x32x16_bf16 v[0:15], v[216:219], v[232:235], v[0:15]
	ds_read_b128 v[232:235], v168 offset:4672
	s_setprio 0
	global_load_dwordx4 v[212:215], v[144:145], off offset:2944
	global_load_dwordx4 v[216:219], v[148:149], off offset:2944
	s_setprio 1
	s_waitcnt lgkmcnt(1)
	v_mfma_f32_32x32x16_bf16 v[112:127], v[178:181], v[228:231], v[112:127]
	v_mfma_f32_32x32x16_bf16 v[48:63], v[220:223], v[228:231], v[48:63]
	s_waitcnt lgkmcnt(0)
	v_mfma_f32_32x32x16_bf16 v[96:111], v[178:181], v[232:235], v[96:111]
	v_mfma_f32_32x32x16_bf16 v[32:47], v[220:223], v[232:235], v[32:47]
	ds_read_b128 v[228:231], v168 offset:9280
	ds_read_b128 v[232:235], v168 offset:13888
	s_waitcnt vmcnt(7)
	ds_write_b128 v191, v[172:175] offset:27648
	s_waitcnt vmcnt(6)
	ds_write_b128 v191, v[224:227] offset:64512
	ds_read_b128 v[172:175], v169 offset:96
	ds_read_b128 v[224:227], v169 offset:4704
	s_waitcnt lgkmcnt(5)
	v_mfma_f32_32x32x16_bf16 v[80:95], v[178:181], v[228:231], v[80:95]
	v_mfma_f32_32x32x16_bf16 v[16:31], v[220:223], v[228:231], v[16:31]
	ds_read_b128 v[228:231], v168 offset:96
	s_waitcnt lgkmcnt(5)
	v_mfma_f32_32x32x16_bf16 v[64:79], v[178:181], v[232:235], v[64:79]
	v_mfma_f32_32x32x16_bf16 v[0:15], v[220:223], v[232:235], v[0:15]
	ds_read_b128 v[232:235], v168 offset:4704
	s_setprio 0
	global_load_dwordx4 v[178:181], v[152:153], off offset:2944
	global_load_dwordx4 v[220:223], v[156:157], off offset:2944
	s_setprio 1
	s_waitcnt lgkmcnt(1)
	v_mfma_f32_32x32x16_bf16 v[112:127], v[172:175], v[228:231], v[112:127]
	v_mfma_f32_32x32x16_bf16 v[48:63], v[224:227], v[228:231], v[48:63]
	s_waitcnt lgkmcnt(0)
	v_mfma_f32_32x32x16_bf16 v[96:111], v[172:175], v[232:235], v[96:111]
	v_mfma_f32_32x32x16_bf16 v[32:47], v[224:227], v[232:235], v[32:47]
	ds_read_b128 v[228:231], v168 offset:9312
	ds_read_b128 v[232:235], v168 offset:13920
	s_waitcnt lgkmcnt(1)
	v_mfma_f32_32x32x16_bf16 v[80:95], v[172:175], v[228:231], v[80:95]
	v_mfma_f32_32x32x16_bf16 v[16:31], v[224:227], v[228:231], v[16:31]
	s_waitcnt lgkmcnt(0)
	v_mfma_f32_32x32x16_bf16 v[64:79], v[172:175], v[232:235], v[64:79]
	v_mfma_f32_32x32x16_bf16 v[0:15], v[224:227], v[232:235], v[0:15]
	s_setprio 0
	s_barrier
	global_load_dwordx4 v[172:175], v[128:129], off offset:3072
	global_load_dwordx4 v[224:227], v[132:133], off offset:3072
	s_waitcnt vmcnt(9)
	ds_write_b128 v195, v[158:161]
	s_waitcnt vmcnt(8)
	ds_write_b128 v196, v[162:165]
	ds_read_b128 v[158:161], v192 offset:36864
	ds_read_b128 v[162:165], v192 offset:41472
	ds_read_b128 v[228:231], v184
	ds_read_b128 v[232:235], v184 offset:4608
	s_setprio 1
	s_waitcnt lgkmcnt(1)
	v_mfma_f32_32x32x16_bf16 v[112:127], v[158:161], v[228:231], v[112:127]
	v_mfma_f32_32x32x16_bf16 v[48:63], v[162:165], v[228:231], v[48:63]
	s_waitcnt lgkmcnt(0)
	v_mfma_f32_32x32x16_bf16 v[96:111], v[158:161], v[232:235], v[96:111]
	v_mfma_f32_32x32x16_bf16 v[32:47], v[162:165], v[232:235], v[32:47]
	ds_read_b128 v[228:231], v184 offset:9216
	ds_read_b128 v[232:235], v184 offset:13824
	s_waitcnt vmcnt(7)
	ds_write_b128 v194, v[200:203]
	s_waitcnt vmcnt(6)
	ds_write_b128 v193, v[208:211]
	ds_read_b128 v[200:203], v192 offset:36896
	ds_read_b128 v[208:211], v192 offset:41504
	s_waitcnt lgkmcnt(5)
	v_mfma_f32_32x32x16_bf16 v[80:95], v[158:161], v[228:231], v[80:95]
	v_mfma_f32_32x32x16_bf16 v[16:31], v[162:165], v[228:231], v[16:31]
	ds_read_b128 v[228:231], v184 offset:32
	s_waitcnt lgkmcnt(5)
	v_mfma_f32_32x32x16_bf16 v[64:79], v[158:161], v[232:235], v[64:79]
	v_mfma_f32_32x32x16_bf16 v[0:15], v[162:165], v[232:235], v[0:15]
	ds_read_b128 v[232:235], v184 offset:4640
	s_setprio 0
	global_load_dwordx4 v[158:161], v[136:137], off offset:3072
	global_load_dwordx4 v[162:165], v[140:141], off offset:3072
	s_setprio 1
	s_waitcnt lgkmcnt(1)
	v_mfma_f32_32x32x16_bf16 v[112:127], v[200:203], v[228:231], v[112:127]
	v_mfma_f32_32x32x16_bf16 v[48:63], v[208:211], v[228:231], v[48:63]
	s_waitcnt lgkmcnt(0)
	v_mfma_f32_32x32x16_bf16 v[96:111], v[200:203], v[232:235], v[96:111]
	v_mfma_f32_32x32x16_bf16 v[32:47], v[208:211], v[232:235], v[32:47]
	ds_read_b128 v[228:231], v184 offset:9248
	ds_read_b128 v[232:235], v184 offset:13856
	s_waitcnt vmcnt(7)
	ds_write_b128 v177, v[212:215]
	s_waitcnt vmcnt(6)
	ds_write_b128 v176, v[216:219]
	ds_read_b128 v[212:215], v192 offset:36928
	ds_read_b128 v[216:219], v192 offset:41536
	s_waitcnt lgkmcnt(5)
	v_mfma_f32_32x32x16_bf16 v[80:95], v[200:203], v[228:231], v[80:95]
	v_mfma_f32_32x32x16_bf16 v[16:31], v[208:211], v[228:231], v[16:31]
	ds_read_b128 v[228:231], v184 offset:64
	s_waitcnt lgkmcnt(5)
	v_mfma_f32_32x32x16_bf16 v[64:79], v[200:203], v[232:235], v[64:79]
	v_mfma_f32_32x32x16_bf16 v[0:15], v[208:211], v[232:235], v[0:15]
	ds_read_b128 v[232:235], v184 offset:4672
	s_setprio 0
	global_load_dwordx4 v[200:203], v[144:145], off offset:3072
	global_load_dwordx4 v[208:211], v[148:149], off offset:3072
	s_setprio 1
	s_waitcnt lgkmcnt(1)
	v_mfma_f32_32x32x16_bf16 v[112:127], v[212:215], v[228:231], v[112:127]
	v_mfma_f32_32x32x16_bf16 v[48:63], v[216:219], v[228:231], v[48:63]
	s_waitcnt lgkmcnt(0)
	v_mfma_f32_32x32x16_bf16 v[96:111], v[212:215], v[232:235], v[96:111]
	v_mfma_f32_32x32x16_bf16 v[32:47], v[216:219], v[232:235], v[32:47]
	ds_read_b128 v[228:231], v184 offset:9280
	ds_read_b128 v[232:235], v184 offset:13888
	s_waitcnt vmcnt(7)
	ds_write_b128 v171, v[178:181]
	s_waitcnt vmcnt(6)
	ds_write_b128 v170, v[220:223]
	ds_read_b128 v[178:181], v192 offset:36960
	ds_read_b128 v[220:223], v192 offset:41568
	s_waitcnt lgkmcnt(5)
	v_mfma_f32_32x32x16_bf16 v[80:95], v[212:215], v[228:231], v[80:95]
	v_mfma_f32_32x32x16_bf16 v[16:31], v[216:219], v[228:231], v[16:31]
	ds_read_b128 v[228:231], v184 offset:96
	s_waitcnt lgkmcnt(5)
	v_mfma_f32_32x32x16_bf16 v[64:79], v[212:215], v[232:235], v[64:79]
	v_mfma_f32_32x32x16_bf16 v[0:15], v[216:219], v[232:235], v[0:15]
	ds_read_b128 v[232:235], v184 offset:4704
	s_setprio 0
	global_load_dwordx4 v[212:215], v[152:153], off offset:3072
	global_load_dwordx4 v[216:219], v[156:157], off offset:3072
	s_setprio 1
	s_waitcnt lgkmcnt(1)
	v_mfma_f32_32x32x16_bf16 v[112:127], v[178:181], v[228:231], v[112:127]
	v_mfma_f32_32x32x16_bf16 v[48:63], v[220:223], v[228:231], v[48:63]
	s_waitcnt lgkmcnt(0)
	v_mfma_f32_32x32x16_bf16 v[96:111], v[178:181], v[232:235], v[96:111]
	v_mfma_f32_32x32x16_bf16 v[32:47], v[220:223], v[232:235], v[32:47]
	ds_read_b128 v[228:231], v184 offset:9312
	ds_read_b128 v[232:235], v184 offset:13920
	s_waitcnt lgkmcnt(1)
	v_mfma_f32_32x32x16_bf16 v[80:95], v[178:181], v[228:231], v[80:95]
	v_mfma_f32_32x32x16_bf16 v[16:31], v[220:223], v[228:231], v[16:31]
	s_waitcnt lgkmcnt(0)
	v_mfma_f32_32x32x16_bf16 v[64:79], v[178:181], v[232:235], v[64:79]
	v_mfma_f32_32x32x16_bf16 v[0:15], v[220:223], v[232:235], v[0:15]
	s_setprio 0
	s_barrier
	global_load_dwordx4 v[178:181], v[128:129], off offset:3200
	global_load_dwordx4 v[220:223], v[132:133], off offset:3200
	s_waitcnt vmcnt(9)
	ds_write_b128 v191, v[172:175]
	s_waitcnt vmcnt(8)
	ds_write_b128 v191, v[224:227] offset:36864
	ds_read_b128 v[172:175], v169
	ds_read_b128 v[224:227], v169 offset:4608
	ds_read_b128 v[228:231], v168
	ds_read_b128 v[232:235], v168 offset:4608
	s_setprio 1
	s_waitcnt lgkmcnt(1)
	v_mfma_f32_32x32x16_bf16 v[112:127], v[172:175], v[228:231], v[112:127]
	v_mfma_f32_32x32x16_bf16 v[48:63], v[224:227], v[228:231], v[48:63]
	s_waitcnt lgkmcnt(0)
	v_mfma_f32_32x32x16_bf16 v[96:111], v[172:175], v[232:235], v[96:111]
	v_mfma_f32_32x32x16_bf16 v[32:47], v[224:227], v[232:235], v[32:47]
	ds_read_b128 v[228:231], v168 offset:9216
	ds_read_b128 v[232:235], v168 offset:13824
	s_waitcnt vmcnt(7)
	ds_write_b128 v191, v[158:161] offset:9216
	s_waitcnt vmcnt(6)
	ds_write_b128 v191, v[162:165] offset:46080
	ds_read_b128 v[158:161], v169 offset:32
	ds_read_b128 v[162:165], v169 offset:4640
	s_waitcnt lgkmcnt(5)
	v_mfma_f32_32x32x16_bf16 v[80:95], v[172:175], v[228:231], v[80:95]
	v_mfma_f32_32x32x16_bf16 v[16:31], v[224:227], v[228:231], v[16:31]
	ds_read_b128 v[228:231], v168 offset:32
	s_waitcnt lgkmcnt(5)
	v_mfma_f32_32x32x16_bf16 v[64:79], v[172:175], v[232:235], v[64:79]
	v_mfma_f32_32x32x16_bf16 v[0:15], v[224:227], v[232:235], v[0:15]
	ds_read_b128 v[232:235], v168 offset:4640
	s_setprio 0
	global_load_dwordx4 v[172:175], v[136:137], off offset:3200
	global_load_dwordx4 v[224:227], v[140:141], off offset:3200
	s_setprio 1
	s_waitcnt lgkmcnt(1)
	v_mfma_f32_32x32x16_bf16 v[112:127], v[158:161], v[228:231], v[112:127]
	v_mfma_f32_32x32x16_bf16 v[48:63], v[162:165], v[228:231], v[48:63]
	s_waitcnt lgkmcnt(0)
	v_mfma_f32_32x32x16_bf16 v[96:111], v[158:161], v[232:235], v[96:111]
	v_mfma_f32_32x32x16_bf16 v[32:47], v[162:165], v[232:235], v[32:47]
	ds_read_b128 v[228:231], v168 offset:9248
	ds_read_b128 v[232:235], v168 offset:13856
	s_waitcnt vmcnt(7)
	ds_write_b128 v191, v[200:203] offset:18432
	s_waitcnt vmcnt(6)
	ds_write_b128 v191, v[208:211] offset:55296
	ds_read_b128 v[200:203], v169 offset:64
	ds_read_b128 v[208:211], v169 offset:4672
	s_waitcnt lgkmcnt(5)
	v_mfma_f32_32x32x16_bf16 v[80:95], v[158:161], v[228:231], v[80:95]
	v_mfma_f32_32x32x16_bf16 v[16:31], v[162:165], v[228:231], v[16:31]
	ds_read_b128 v[228:231], v168 offset:64
	s_waitcnt lgkmcnt(5)
	v_mfma_f32_32x32x16_bf16 v[64:79], v[158:161], v[232:235], v[64:79]
	v_mfma_f32_32x32x16_bf16 v[0:15], v[162:165], v[232:235], v[0:15]
	ds_read_b128 v[232:235], v168 offset:4672
	s_setprio 0
	global_load_dwordx4 v[158:161], v[144:145], off offset:3200
	global_load_dwordx4 v[162:165], v[148:149], off offset:3200
	s_setprio 1
	s_waitcnt lgkmcnt(1)
	v_mfma_f32_32x32x16_bf16 v[112:127], v[200:203], v[228:231], v[112:127]
	v_mfma_f32_32x32x16_bf16 v[48:63], v[208:211], v[228:231], v[48:63]
	s_waitcnt lgkmcnt(0)
	v_mfma_f32_32x32x16_bf16 v[96:111], v[200:203], v[232:235], v[96:111]
	v_mfma_f32_32x32x16_bf16 v[32:47], v[208:211], v[232:235], v[32:47]
	ds_read_b128 v[228:231], v168 offset:9280
	ds_read_b128 v[232:235], v168 offset:13888
	s_waitcnt vmcnt(7)
	ds_write_b128 v191, v[212:215] offset:27648
	s_waitcnt vmcnt(6)
	ds_write_b128 v191, v[216:219] offset:64512
	ds_read_b128 v[212:215], v169 offset:96
	ds_read_b128 v[216:219], v169 offset:4704
	s_waitcnt lgkmcnt(5)
	v_mfma_f32_32x32x16_bf16 v[80:95], v[200:203], v[228:231], v[80:95]
	v_mfma_f32_32x32x16_bf16 v[16:31], v[208:211], v[228:231], v[16:31]
	ds_read_b128 v[228:231], v168 offset:96
	s_waitcnt lgkmcnt(5)
	v_mfma_f32_32x32x16_bf16 v[64:79], v[200:203], v[232:235], v[64:79]
	v_mfma_f32_32x32x16_bf16 v[0:15], v[208:211], v[232:235], v[0:15]
	ds_read_b128 v[232:235], v168 offset:4704
	s_setprio 0
	global_load_dwordx4 v[200:203], v[152:153], off offset:3200
	global_load_dwordx4 v[208:211], v[156:157], off offset:3200
	s_setprio 1
	s_waitcnt lgkmcnt(1)
	v_mfma_f32_32x32x16_bf16 v[112:127], v[212:215], v[228:231], v[112:127]
	v_mfma_f32_32x32x16_bf16 v[48:63], v[216:219], v[228:231], v[48:63]
	s_waitcnt lgkmcnt(0)
	v_mfma_f32_32x32x16_bf16 v[96:111], v[212:215], v[232:235], v[96:111]
	v_mfma_f32_32x32x16_bf16 v[32:47], v[216:219], v[232:235], v[32:47]
	ds_read_b128 v[228:231], v168 offset:9312
	ds_read_b128 v[232:235], v168 offset:13920
	s_waitcnt lgkmcnt(1)
	v_mfma_f32_32x32x16_bf16 v[80:95], v[212:215], v[228:231], v[80:95]
	v_mfma_f32_32x32x16_bf16 v[16:31], v[216:219], v[228:231], v[16:31]
	s_waitcnt lgkmcnt(0)
	v_mfma_f32_32x32x16_bf16 v[64:79], v[212:215], v[232:235], v[64:79]
	v_mfma_f32_32x32x16_bf16 v[0:15], v[216:219], v[232:235], v[0:15]
	s_setprio 0
	s_barrier
	global_load_dwordx4 v[212:215], v[128:129], off offset:3328
	global_load_dwordx4 v[216:219], v[132:133], off offset:3328
	s_waitcnt vmcnt(9)
	ds_write_b128 v195, v[178:181]
	s_waitcnt vmcnt(8)
	ds_write_b128 v196, v[220:223]
	ds_read_b128 v[178:181], v192 offset:36864
	ds_read_b128 v[220:223], v192 offset:41472
	ds_read_b128 v[228:231], v184
	ds_read_b128 v[232:235], v184 offset:4608
	s_setprio 1
	s_waitcnt lgkmcnt(1)
	v_mfma_f32_32x32x16_bf16 v[112:127], v[178:181], v[228:231], v[112:127]
	v_mfma_f32_32x32x16_bf16 v[48:63], v[220:223], v[228:231], v[48:63]
	s_waitcnt lgkmcnt(0)
	v_mfma_f32_32x32x16_bf16 v[96:111], v[178:181], v[232:235], v[96:111]
	v_mfma_f32_32x32x16_bf16 v[32:47], v[220:223], v[232:235], v[32:47]
	ds_read_b128 v[228:231], v184 offset:9216
	ds_read_b128 v[232:235], v184 offset:13824
	s_waitcnt vmcnt(7)
	ds_write_b128 v194, v[172:175]
	s_waitcnt vmcnt(6)
	ds_write_b128 v193, v[224:227]
	ds_read_b128 v[172:175], v192 offset:36896
	ds_read_b128 v[224:227], v192 offset:41504
	s_waitcnt lgkmcnt(5)
	v_mfma_f32_32x32x16_bf16 v[80:95], v[178:181], v[228:231], v[80:95]
	v_mfma_f32_32x32x16_bf16 v[16:31], v[220:223], v[228:231], v[16:31]
	ds_read_b128 v[228:231], v184 offset:32
	s_waitcnt lgkmcnt(5)
	v_mfma_f32_32x32x16_bf16 v[64:79], v[178:181], v[232:235], v[64:79]
	v_mfma_f32_32x32x16_bf16 v[0:15], v[220:223], v[232:235], v[0:15]
	ds_read_b128 v[232:235], v184 offset:4640
	s_setprio 0
	global_load_dwordx4 v[178:181], v[136:137], off offset:3328
	global_load_dwordx4 v[220:223], v[140:141], off offset:3328
	s_setprio 1
	s_waitcnt lgkmcnt(1)
	v_mfma_f32_32x32x16_bf16 v[112:127], v[172:175], v[228:231], v[112:127]
	v_mfma_f32_32x32x16_bf16 v[48:63], v[224:227], v[228:231], v[48:63]
	s_waitcnt lgkmcnt(0)
	v_mfma_f32_32x32x16_bf16 v[96:111], v[172:175], v[232:235], v[96:111]
	v_mfma_f32_32x32x16_bf16 v[32:47], v[224:227], v[232:235], v[32:47]
	ds_read_b128 v[228:231], v184 offset:9248
	ds_read_b128 v[232:235], v184 offset:13856
	s_waitcnt vmcnt(7)
	ds_write_b128 v177, v[158:161]
	s_waitcnt vmcnt(6)
	ds_write_b128 v176, v[162:165]
	ds_read_b128 v[158:161], v192 offset:36928
	ds_read_b128 v[162:165], v192 offset:41536
	s_waitcnt lgkmcnt(5)
	v_mfma_f32_32x32x16_bf16 v[80:95], v[172:175], v[228:231], v[80:95]
	v_mfma_f32_32x32x16_bf16 v[16:31], v[224:227], v[228:231], v[16:31]
	ds_read_b128 v[228:231], v184 offset:64
	s_waitcnt lgkmcnt(5)
	v_mfma_f32_32x32x16_bf16 v[64:79], v[172:175], v[232:235], v[64:79]
	v_mfma_f32_32x32x16_bf16 v[0:15], v[224:227], v[232:235], v[0:15]
	ds_read_b128 v[232:235], v184 offset:4672
	s_setprio 0
	global_load_dwordx4 v[172:175], v[144:145], off offset:3328
	global_load_dwordx4 v[224:227], v[148:149], off offset:3328
	s_setprio 1
	s_waitcnt lgkmcnt(1)
	v_mfma_f32_32x32x16_bf16 v[112:127], v[158:161], v[228:231], v[112:127]
	v_mfma_f32_32x32x16_bf16 v[48:63], v[162:165], v[228:231], v[48:63]
	s_waitcnt lgkmcnt(0)
	v_mfma_f32_32x32x16_bf16 v[96:111], v[158:161], v[232:235], v[96:111]
	v_mfma_f32_32x32x16_bf16 v[32:47], v[162:165], v[232:235], v[32:47]
	ds_read_b128 v[228:231], v184 offset:9280
	ds_read_b128 v[232:235], v184 offset:13888
	s_waitcnt vmcnt(7)
	ds_write_b128 v171, v[200:203]
	s_waitcnt vmcnt(6)
	ds_write_b128 v170, v[208:211]
	ds_read_b128 v[200:203], v192 offset:36960
	ds_read_b128 v[208:211], v192 offset:41568
	s_waitcnt lgkmcnt(5)
	v_mfma_f32_32x32x16_bf16 v[80:95], v[158:161], v[228:231], v[80:95]
	v_mfma_f32_32x32x16_bf16 v[16:31], v[162:165], v[228:231], v[16:31]
	ds_read_b128 v[228:231], v184 offset:96
	s_waitcnt lgkmcnt(5)
	v_mfma_f32_32x32x16_bf16 v[64:79], v[158:161], v[232:235], v[64:79]
	v_mfma_f32_32x32x16_bf16 v[0:15], v[162:165], v[232:235], v[0:15]
	ds_read_b128 v[232:235], v184 offset:4704
	s_setprio 0
	global_load_dwordx4 v[158:161], v[152:153], off offset:3328
	global_load_dwordx4 v[162:165], v[156:157], off offset:3328
	s_setprio 1
	s_waitcnt lgkmcnt(1)
	v_mfma_f32_32x32x16_bf16 v[112:127], v[200:203], v[228:231], v[112:127]
	v_mfma_f32_32x32x16_bf16 v[48:63], v[208:211], v[228:231], v[48:63]
	s_waitcnt lgkmcnt(0)
	v_mfma_f32_32x32x16_bf16 v[96:111], v[200:203], v[232:235], v[96:111]
	v_mfma_f32_32x32x16_bf16 v[32:47], v[208:211], v[232:235], v[32:47]
	ds_read_b128 v[228:231], v184 offset:9312
	ds_read_b128 v[232:235], v184 offset:13920
	s_waitcnt lgkmcnt(1)
	v_mfma_f32_32x32x16_bf16 v[80:95], v[200:203], v[228:231], v[80:95]
	v_mfma_f32_32x32x16_bf16 v[16:31], v[208:211], v[228:231], v[16:31]
	s_waitcnt lgkmcnt(0)
	v_mfma_f32_32x32x16_bf16 v[64:79], v[200:203], v[232:235], v[64:79]
	v_mfma_f32_32x32x16_bf16 v[0:15], v[208:211], v[232:235], v[0:15]
	s_setprio 0
	s_barrier
	global_load_dwordx4 v[200:203], v[128:129], off offset:3456
	global_load_dwordx4 v[208:211], v[132:133], off offset:3456
	s_waitcnt vmcnt(9)
	ds_write_b128 v191, v[212:215]
	s_waitcnt vmcnt(8)
	ds_write_b128 v191, v[216:219] offset:36864
	ds_read_b128 v[212:215], v169
	ds_read_b128 v[216:219], v169 offset:4608
	ds_read_b128 v[228:231], v168
	ds_read_b128 v[232:235], v168 offset:4608
	s_setprio 1
	s_waitcnt lgkmcnt(1)
	v_mfma_f32_32x32x16_bf16 v[112:127], v[212:215], v[228:231], v[112:127]
	v_mfma_f32_32x32x16_bf16 v[48:63], v[216:219], v[228:231], v[48:63]
	s_waitcnt lgkmcnt(0)
	v_mfma_f32_32x32x16_bf16 v[96:111], v[212:215], v[232:235], v[96:111]
	v_mfma_f32_32x32x16_bf16 v[32:47], v[216:219], v[232:235], v[32:47]
	ds_read_b128 v[228:231], v168 offset:9216
	ds_read_b128 v[232:235], v168 offset:13824
	s_waitcnt vmcnt(7)
	ds_write_b128 v191, v[178:181] offset:9216
	s_waitcnt vmcnt(6)
	ds_write_b128 v191, v[220:223] offset:46080
	ds_read_b128 v[178:181], v169 offset:32
	ds_read_b128 v[220:223], v169 offset:4640
	s_waitcnt lgkmcnt(5)
	v_mfma_f32_32x32x16_bf16 v[80:95], v[212:215], v[228:231], v[80:95]
	v_mfma_f32_32x32x16_bf16 v[16:31], v[216:219], v[228:231], v[16:31]
	ds_read_b128 v[228:231], v168 offset:32
	s_waitcnt lgkmcnt(5)
	v_mfma_f32_32x32x16_bf16 v[64:79], v[212:215], v[232:235], v[64:79]
	v_mfma_f32_32x32x16_bf16 v[0:15], v[216:219], v[232:235], v[0:15]
	ds_read_b128 v[232:235], v168 offset:4640
	s_setprio 0
	global_load_dwordx4 v[212:215], v[136:137], off offset:3456
	global_load_dwordx4 v[216:219], v[140:141], off offset:3456
	s_setprio 1
	s_waitcnt lgkmcnt(1)
	v_mfma_f32_32x32x16_bf16 v[112:127], v[178:181], v[228:231], v[112:127]
	v_mfma_f32_32x32x16_bf16 v[48:63], v[220:223], v[228:231], v[48:63]
	s_waitcnt lgkmcnt(0)
	v_mfma_f32_32x32x16_bf16 v[96:111], v[178:181], v[232:235], v[96:111]
	v_mfma_f32_32x32x16_bf16 v[32:47], v[220:223], v[232:235], v[32:47]
	ds_read_b128 v[228:231], v168 offset:9248
	ds_read_b128 v[232:235], v168 offset:13856
	s_waitcnt vmcnt(7)
	ds_write_b128 v191, v[172:175] offset:18432
	s_waitcnt vmcnt(6)
	ds_write_b128 v191, v[224:227] offset:55296
	ds_read_b128 v[172:175], v169 offset:64
	ds_read_b128 v[224:227], v169 offset:4672
	s_waitcnt lgkmcnt(5)
	v_mfma_f32_32x32x16_bf16 v[80:95], v[178:181], v[228:231], v[80:95]
	v_mfma_f32_32x32x16_bf16 v[16:31], v[220:223], v[228:231], v[16:31]
	ds_read_b128 v[228:231], v168 offset:64
	s_waitcnt lgkmcnt(5)
	v_mfma_f32_32x32x16_bf16 v[64:79], v[178:181], v[232:235], v[64:79]
	v_mfma_f32_32x32x16_bf16 v[0:15], v[220:223], v[232:235], v[0:15]
	ds_read_b128 v[232:235], v168 offset:4672
	s_setprio 0
	global_load_dwordx4 v[178:181], v[144:145], off offset:3456
	global_load_dwordx4 v[220:223], v[148:149], off offset:3456
	s_setprio 1
	s_waitcnt lgkmcnt(1)
	v_mfma_f32_32x32x16_bf16 v[112:127], v[172:175], v[228:231], v[112:127]
	v_mfma_f32_32x32x16_bf16 v[48:63], v[224:227], v[228:231], v[48:63]
	s_waitcnt lgkmcnt(0)
	v_mfma_f32_32x32x16_bf16 v[96:111], v[172:175], v[232:235], v[96:111]
	v_mfma_f32_32x32x16_bf16 v[32:47], v[224:227], v[232:235], v[32:47]
	ds_read_b128 v[228:231], v168 offset:9280
	ds_read_b128 v[232:235], v168 offset:13888
	s_waitcnt vmcnt(7)
	ds_write_b128 v191, v[158:161] offset:27648
	s_waitcnt vmcnt(6)
	ds_write_b128 v191, v[162:165] offset:64512
	ds_read_b128 v[158:161], v169 offset:96
	ds_read_b128 v[162:165], v169 offset:4704
	s_waitcnt lgkmcnt(5)
	v_mfma_f32_32x32x16_bf16 v[80:95], v[172:175], v[228:231], v[80:95]
	v_mfma_f32_32x32x16_bf16 v[16:31], v[224:227], v[228:231], v[16:31]
	ds_read_b128 v[228:231], v168 offset:96
	s_waitcnt lgkmcnt(5)
	v_mfma_f32_32x32x16_bf16 v[64:79], v[172:175], v[232:235], v[64:79]
	v_mfma_f32_32x32x16_bf16 v[0:15], v[224:227], v[232:235], v[0:15]
	ds_read_b128 v[232:235], v168 offset:4704
	s_setprio 0
	global_load_dwordx4 v[172:175], v[152:153], off offset:3456
	global_load_dwordx4 v[224:227], v[156:157], off offset:3456
	s_setprio 1
	s_waitcnt lgkmcnt(1)
	v_mfma_f32_32x32x16_bf16 v[112:127], v[158:161], v[228:231], v[112:127]
	v_mfma_f32_32x32x16_bf16 v[48:63], v[162:165], v[228:231], v[48:63]
	s_waitcnt lgkmcnt(0)
	v_mfma_f32_32x32x16_bf16 v[96:111], v[158:161], v[232:235], v[96:111]
	v_mfma_f32_32x32x16_bf16 v[32:47], v[162:165], v[232:235], v[32:47]
	ds_read_b128 v[228:231], v168 offset:9312
	ds_read_b128 v[232:235], v168 offset:13920
	s_waitcnt lgkmcnt(1)
	v_mfma_f32_32x32x16_bf16 v[80:95], v[158:161], v[228:231], v[80:95]
	v_mfma_f32_32x32x16_bf16 v[16:31], v[162:165], v[228:231], v[16:31]
	s_waitcnt lgkmcnt(0)
	v_mfma_f32_32x32x16_bf16 v[64:79], v[158:161], v[232:235], v[64:79]
	v_mfma_f32_32x32x16_bf16 v[0:15], v[162:165], v[232:235], v[0:15]
	s_setprio 0
	s_barrier
	global_load_dwordx4 v[158:161], v[128:129], off offset:3584
	global_load_dwordx4 v[162:165], v[132:133], off offset:3584
	s_waitcnt vmcnt(9)
	ds_write_b128 v195, v[200:203]
	s_waitcnt vmcnt(8)
	ds_write_b128 v196, v[208:211]
	ds_read_b128 v[200:203], v192 offset:36864
	ds_read_b128 v[208:211], v192 offset:41472
	ds_read_b128 v[228:231], v184
	ds_read_b128 v[232:235], v184 offset:4608
	s_setprio 1
	s_waitcnt lgkmcnt(1)
	v_mfma_f32_32x32x16_bf16 v[112:127], v[200:203], v[228:231], v[112:127]
	v_mfma_f32_32x32x16_bf16 v[48:63], v[208:211], v[228:231], v[48:63]
	s_waitcnt lgkmcnt(0)
	v_mfma_f32_32x32x16_bf16 v[96:111], v[200:203], v[232:235], v[96:111]
	v_mfma_f32_32x32x16_bf16 v[32:47], v[208:211], v[232:235], v[32:47]
	ds_read_b128 v[228:231], v184 offset:9216
	ds_read_b128 v[232:235], v184 offset:13824
	s_waitcnt vmcnt(7)
	ds_write_b128 v194, v[212:215]
	s_waitcnt vmcnt(6)
	ds_write_b128 v193, v[216:219]
	ds_read_b128 v[212:215], v192 offset:36896
	ds_read_b128 v[216:219], v192 offset:41504
	s_waitcnt lgkmcnt(5)
	v_mfma_f32_32x32x16_bf16 v[80:95], v[200:203], v[228:231], v[80:95]
	v_mfma_f32_32x32x16_bf16 v[16:31], v[208:211], v[228:231], v[16:31]
	ds_read_b128 v[228:231], v184 offset:32
	s_waitcnt lgkmcnt(5)
	v_mfma_f32_32x32x16_bf16 v[64:79], v[200:203], v[232:235], v[64:79]
	v_mfma_f32_32x32x16_bf16 v[0:15], v[208:211], v[232:235], v[0:15]
	ds_read_b128 v[232:235], v184 offset:4640
	s_setprio 0
	global_load_dwordx4 v[200:203], v[136:137], off offset:3584
	global_load_dwordx4 v[208:211], v[140:141], off offset:3584
	s_setprio 1
	s_waitcnt lgkmcnt(1)
	v_mfma_f32_32x32x16_bf16 v[112:127], v[212:215], v[228:231], v[112:127]
	v_mfma_f32_32x32x16_bf16 v[48:63], v[216:219], v[228:231], v[48:63]
	s_waitcnt lgkmcnt(0)
	v_mfma_f32_32x32x16_bf16 v[96:111], v[212:215], v[232:235], v[96:111]
	v_mfma_f32_32x32x16_bf16 v[32:47], v[216:219], v[232:235], v[32:47]
	ds_read_b128 v[228:231], v184 offset:9248
	ds_read_b128 v[232:235], v184 offset:13856
	s_waitcnt vmcnt(7)
	ds_write_b128 v177, v[178:181]
	s_waitcnt vmcnt(6)
	ds_write_b128 v176, v[220:223]
	ds_read_b128 v[178:181], v192 offset:36928
	ds_read_b128 v[220:223], v192 offset:41536
	s_waitcnt lgkmcnt(5)
	v_mfma_f32_32x32x16_bf16 v[80:95], v[212:215], v[228:231], v[80:95]
	v_mfma_f32_32x32x16_bf16 v[16:31], v[216:219], v[228:231], v[16:31]
	ds_read_b128 v[228:231], v184 offset:64
	s_waitcnt lgkmcnt(5)
	v_mfma_f32_32x32x16_bf16 v[64:79], v[212:215], v[232:235], v[64:79]
	v_mfma_f32_32x32x16_bf16 v[0:15], v[216:219], v[232:235], v[0:15]
	ds_read_b128 v[232:235], v184 offset:4672
	s_setprio 0
	global_load_dwordx4 v[212:215], v[144:145], off offset:3584
	global_load_dwordx4 v[216:219], v[148:149], off offset:3584
	s_setprio 1
	s_waitcnt lgkmcnt(1)
	v_mfma_f32_32x32x16_bf16 v[112:127], v[178:181], v[228:231], v[112:127]
	v_mfma_f32_32x32x16_bf16 v[48:63], v[220:223], v[228:231], v[48:63]
	s_waitcnt lgkmcnt(0)
	v_mfma_f32_32x32x16_bf16 v[96:111], v[178:181], v[232:235], v[96:111]
	v_mfma_f32_32x32x16_bf16 v[32:47], v[220:223], v[232:235], v[32:47]
	ds_read_b128 v[228:231], v184 offset:9280
	ds_read_b128 v[232:235], v184 offset:13888
	s_waitcnt vmcnt(7)
	ds_write_b128 v171, v[172:175]
	s_waitcnt vmcnt(6)
	ds_write_b128 v170, v[224:227]
	ds_read_b128 v[172:175], v192 offset:36960
	ds_read_b128 v[224:227], v192 offset:41568
	s_waitcnt lgkmcnt(5)
	v_mfma_f32_32x32x16_bf16 v[80:95], v[178:181], v[228:231], v[80:95]
	v_mfma_f32_32x32x16_bf16 v[16:31], v[220:223], v[228:231], v[16:31]
	ds_read_b128 v[228:231], v184 offset:96
	s_waitcnt lgkmcnt(5)
	v_mfma_f32_32x32x16_bf16 v[64:79], v[178:181], v[232:235], v[64:79]
	v_mfma_f32_32x32x16_bf16 v[0:15], v[220:223], v[232:235], v[0:15]
	ds_read_b128 v[232:235], v184 offset:4704
	s_setprio 0
	global_load_dwordx4 v[178:181], v[152:153], off offset:3584
	global_load_dwordx4 v[220:223], v[156:157], off offset:3584
	s_setprio 1
	s_waitcnt lgkmcnt(1)
	v_mfma_f32_32x32x16_bf16 v[112:127], v[172:175], v[228:231], v[112:127]
	v_mfma_f32_32x32x16_bf16 v[48:63], v[224:227], v[228:231], v[48:63]
	s_waitcnt lgkmcnt(0)
	v_mfma_f32_32x32x16_bf16 v[96:111], v[172:175], v[232:235], v[96:111]
	v_mfma_f32_32x32x16_bf16 v[32:47], v[224:227], v[232:235], v[32:47]
	ds_read_b128 v[228:231], v184 offset:9312
	ds_read_b128 v[232:235], v184 offset:13920
	s_waitcnt lgkmcnt(1)
	v_mfma_f32_32x32x16_bf16 v[80:95], v[172:175], v[228:231], v[80:95]
	v_mfma_f32_32x32x16_bf16 v[16:31], v[224:227], v[228:231], v[16:31]
	s_waitcnt lgkmcnt(0)
	v_mfma_f32_32x32x16_bf16 v[64:79], v[172:175], v[232:235], v[64:79]
	v_mfma_f32_32x32x16_bf16 v[0:15], v[224:227], v[232:235], v[0:15]
	s_setprio 0
	s_barrier
	global_load_dwordx4 v[172:175], v[128:129], off offset:3712
	global_load_dwordx4 v[224:227], v[132:133], off offset:3712
	s_waitcnt vmcnt(9)
	ds_write_b128 v191, v[158:161]
	s_waitcnt vmcnt(8)
	ds_write_b128 v191, v[162:165] offset:36864
	ds_read_b128 v[158:161], v169
	ds_read_b128 v[162:165], v169 offset:4608
	ds_read_b128 v[228:231], v168
	ds_read_b128 v[232:235], v168 offset:4608
	s_setprio 1
	s_waitcnt lgkmcnt(1)
	v_mfma_f32_32x32x16_bf16 v[112:127], v[158:161], v[228:231], v[112:127]
	v_mfma_f32_32x32x16_bf16 v[48:63], v[162:165], v[228:231], v[48:63]
	s_waitcnt lgkmcnt(0)
	v_mfma_f32_32x32x16_bf16 v[96:111], v[158:161], v[232:235], v[96:111]
	v_mfma_f32_32x32x16_bf16 v[32:47], v[162:165], v[232:235], v[32:47]
	ds_read_b128 v[228:231], v168 offset:9216
	ds_read_b128 v[232:235], v168 offset:13824
	s_waitcnt vmcnt(7)
	ds_write_b128 v191, v[200:203] offset:9216
	s_waitcnt vmcnt(6)
	ds_write_b128 v191, v[208:211] offset:46080
	ds_read_b128 v[200:203], v169 offset:32
	ds_read_b128 v[208:211], v169 offset:4640
	s_waitcnt lgkmcnt(5)
	v_mfma_f32_32x32x16_bf16 v[80:95], v[158:161], v[228:231], v[80:95]
	v_mfma_f32_32x32x16_bf16 v[16:31], v[162:165], v[228:231], v[16:31]
	ds_read_b128 v[228:231], v168 offset:32
	s_waitcnt lgkmcnt(5)
	v_mfma_f32_32x32x16_bf16 v[64:79], v[158:161], v[232:235], v[64:79]
	v_mfma_f32_32x32x16_bf16 v[0:15], v[162:165], v[232:235], v[0:15]
	ds_read_b128 v[232:235], v168 offset:4640
	s_setprio 0
	global_load_dwordx4 v[158:161], v[136:137], off offset:3712
	global_load_dwordx4 v[162:165], v[140:141], off offset:3712
	s_setprio 1
	s_waitcnt lgkmcnt(1)
	v_mfma_f32_32x32x16_bf16 v[112:127], v[200:203], v[228:231], v[112:127]
	v_mfma_f32_32x32x16_bf16 v[48:63], v[208:211], v[228:231], v[48:63]
	s_waitcnt lgkmcnt(0)
	v_mfma_f32_32x32x16_bf16 v[96:111], v[200:203], v[232:235], v[96:111]
	v_mfma_f32_32x32x16_bf16 v[32:47], v[208:211], v[232:235], v[32:47]
	ds_read_b128 v[228:231], v168 offset:9248
	ds_read_b128 v[232:235], v168 offset:13856
	s_waitcnt vmcnt(7)
	ds_write_b128 v191, v[212:215] offset:18432
	s_waitcnt vmcnt(6)
	ds_write_b128 v191, v[216:219] offset:55296
	ds_read_b128 v[212:215], v169 offset:64
	ds_read_b128 v[216:219], v169 offset:4672
	s_waitcnt lgkmcnt(5)
	v_mfma_f32_32x32x16_bf16 v[80:95], v[200:203], v[228:231], v[80:95]
	v_mfma_f32_32x32x16_bf16 v[16:31], v[208:211], v[228:231], v[16:31]
	ds_read_b128 v[228:231], v168 offset:64
	s_waitcnt lgkmcnt(5)
	v_mfma_f32_32x32x16_bf16 v[64:79], v[200:203], v[232:235], v[64:79]
	v_mfma_f32_32x32x16_bf16 v[0:15], v[208:211], v[232:235], v[0:15]
	ds_read_b128 v[232:235], v168 offset:4672
	s_setprio 0
	global_load_dwordx4 v[200:203], v[144:145], off offset:3712
	global_load_dwordx4 v[208:211], v[148:149], off offset:3712
	s_setprio 1
	s_waitcnt lgkmcnt(1)
	v_mfma_f32_32x32x16_bf16 v[112:127], v[212:215], v[228:231], v[112:127]
	v_mfma_f32_32x32x16_bf16 v[48:63], v[216:219], v[228:231], v[48:63]
	s_waitcnt lgkmcnt(0)
	v_mfma_f32_32x32x16_bf16 v[96:111], v[212:215], v[232:235], v[96:111]
	v_mfma_f32_32x32x16_bf16 v[32:47], v[216:219], v[232:235], v[32:47]
	ds_read_b128 v[228:231], v168 offset:9280
	ds_read_b128 v[232:235], v168 offset:13888
	s_waitcnt vmcnt(7)
	ds_write_b128 v191, v[178:181] offset:27648
	s_waitcnt vmcnt(6)
	ds_write_b128 v191, v[220:223] offset:64512
	ds_read_b128 v[178:181], v169 offset:96
	ds_read_b128 v[220:223], v169 offset:4704
	s_waitcnt lgkmcnt(5)
	v_mfma_f32_32x32x16_bf16 v[80:95], v[212:215], v[228:231], v[80:95]
	v_mfma_f32_32x32x16_bf16 v[16:31], v[216:219], v[228:231], v[16:31]
	ds_read_b128 v[228:231], v168 offset:96
	s_waitcnt lgkmcnt(5)
	v_mfma_f32_32x32x16_bf16 v[64:79], v[212:215], v[232:235], v[64:79]
	v_mfma_f32_32x32x16_bf16 v[0:15], v[216:219], v[232:235], v[0:15]
	ds_read_b128 v[232:235], v168 offset:4704
	s_setprio 0
	global_load_dwordx4 v[212:215], v[152:153], off offset:3712
	global_load_dwordx4 v[216:219], v[156:157], off offset:3712
	s_setprio 1
	s_waitcnt lgkmcnt(1)
	v_mfma_f32_32x32x16_bf16 v[112:127], v[178:181], v[228:231], v[112:127]
	v_mfma_f32_32x32x16_bf16 v[48:63], v[220:223], v[228:231], v[48:63]
	s_waitcnt lgkmcnt(0)
	v_mfma_f32_32x32x16_bf16 v[96:111], v[178:181], v[232:235], v[96:111]
	v_mfma_f32_32x32x16_bf16 v[32:47], v[220:223], v[232:235], v[32:47]
	ds_read_b128 v[228:231], v168 offset:9312
	ds_read_b128 v[232:235], v168 offset:13920
	s_waitcnt lgkmcnt(1)
	v_mfma_f32_32x32x16_bf16 v[80:95], v[178:181], v[228:231], v[80:95]
	v_mfma_f32_32x32x16_bf16 v[16:31], v[220:223], v[228:231], v[16:31]
	s_waitcnt lgkmcnt(0)
	v_mfma_f32_32x32x16_bf16 v[64:79], v[178:181], v[232:235], v[64:79]
	v_mfma_f32_32x32x16_bf16 v[0:15], v[220:223], v[232:235], v[0:15]
	s_setprio 0
	s_barrier
	global_load_dwordx4 v[178:181], v[128:129], off offset:3840
	global_load_dwordx4 v[220:223], v[132:133], off offset:3840
	s_waitcnt vmcnt(9)
	ds_write_b128 v195, v[172:175]
	s_waitcnt vmcnt(8)
	ds_write_b128 v196, v[224:227]
	ds_read_b128 v[172:175], v192 offset:36864
	ds_read_b128 v[224:227], v192 offset:41472
	ds_read_b128 v[228:231], v184
	ds_read_b128 v[232:235], v184 offset:4608
	s_setprio 1
	s_waitcnt lgkmcnt(1)
	v_mfma_f32_32x32x16_bf16 v[112:127], v[172:175], v[228:231], v[112:127]
	v_mfma_f32_32x32x16_bf16 v[48:63], v[224:227], v[228:231], v[48:63]
	s_waitcnt lgkmcnt(0)
	v_mfma_f32_32x32x16_bf16 v[96:111], v[172:175], v[232:235], v[96:111]
	v_mfma_f32_32x32x16_bf16 v[32:47], v[224:227], v[232:235], v[32:47]
	ds_read_b128 v[228:231], v184 offset:9216
	ds_read_b128 v[232:235], v184 offset:13824
	s_waitcnt vmcnt(7)
	ds_write_b128 v194, v[158:161]
	s_waitcnt vmcnt(6)
	ds_write_b128 v193, v[162:165]
	ds_read_b128 v[158:161], v192 offset:36896
	ds_read_b128 v[162:165], v192 offset:41504
	s_waitcnt lgkmcnt(5)
	v_mfma_f32_32x32x16_bf16 v[80:95], v[172:175], v[228:231], v[80:95]
	v_mfma_f32_32x32x16_bf16 v[16:31], v[224:227], v[228:231], v[16:31]
	ds_read_b128 v[228:231], v184 offset:32
	s_waitcnt lgkmcnt(5)
	v_mfma_f32_32x32x16_bf16 v[64:79], v[172:175], v[232:235], v[64:79]
	v_mfma_f32_32x32x16_bf16 v[0:15], v[224:227], v[232:235], v[0:15]
	ds_read_b128 v[232:235], v184 offset:4640
	s_setprio 0
	global_load_dwordx4 v[172:175], v[136:137], off offset:3840
	global_load_dwordx4 v[224:227], v[140:141], off offset:3840
	s_setprio 1
	s_waitcnt lgkmcnt(1)
	v_mfma_f32_32x32x16_bf16 v[112:127], v[158:161], v[228:231], v[112:127]
	v_mfma_f32_32x32x16_bf16 v[48:63], v[162:165], v[228:231], v[48:63]
	s_waitcnt lgkmcnt(0)
	v_mfma_f32_32x32x16_bf16 v[96:111], v[158:161], v[232:235], v[96:111]
	v_mfma_f32_32x32x16_bf16 v[32:47], v[162:165], v[232:235], v[32:47]
	ds_read_b128 v[228:231], v184 offset:9248
	ds_read_b128 v[232:235], v184 offset:13856
	s_waitcnt vmcnt(7)
	ds_write_b128 v177, v[200:203]
	s_waitcnt vmcnt(6)
	ds_write_b128 v176, v[208:211]
	ds_read_b128 v[200:203], v192 offset:36928
	ds_read_b128 v[208:211], v192 offset:41536
	s_waitcnt lgkmcnt(5)
	v_mfma_f32_32x32x16_bf16 v[80:95], v[158:161], v[228:231], v[80:95]
	v_mfma_f32_32x32x16_bf16 v[16:31], v[162:165], v[228:231], v[16:31]
	ds_read_b128 v[228:231], v184 offset:64
	s_waitcnt lgkmcnt(5)
	v_mfma_f32_32x32x16_bf16 v[64:79], v[158:161], v[232:235], v[64:79]
	v_mfma_f32_32x32x16_bf16 v[0:15], v[162:165], v[232:235], v[0:15]
	ds_read_b128 v[232:235], v184 offset:4672
	s_setprio 0
	global_load_dwordx4 v[158:161], v[144:145], off offset:3840
	global_load_dwordx4 v[162:165], v[148:149], off offset:3840
	s_setprio 1
	s_waitcnt lgkmcnt(1)
	v_mfma_f32_32x32x16_bf16 v[112:127], v[200:203], v[228:231], v[112:127]
	v_mfma_f32_32x32x16_bf16 v[48:63], v[208:211], v[228:231], v[48:63]
	s_waitcnt lgkmcnt(0)
	v_mfma_f32_32x32x16_bf16 v[96:111], v[200:203], v[232:235], v[96:111]
	v_mfma_f32_32x32x16_bf16 v[32:47], v[208:211], v[232:235], v[32:47]
	ds_read_b128 v[228:231], v184 offset:9280
	ds_read_b128 v[232:235], v184 offset:13888
	s_waitcnt vmcnt(7)
	ds_write_b128 v171, v[212:215]
	s_waitcnt vmcnt(6)
	ds_write_b128 v170, v[216:219]
	ds_read_b128 v[212:215], v192 offset:36960
	ds_read_b128 v[216:219], v192 offset:41568
	s_waitcnt lgkmcnt(5)
	v_mfma_f32_32x32x16_bf16 v[80:95], v[200:203], v[228:231], v[80:95]
	v_mfma_f32_32x32x16_bf16 v[16:31], v[208:211], v[228:231], v[16:31]
	ds_read_b128 v[228:231], v184 offset:96
	s_waitcnt lgkmcnt(5)
	v_mfma_f32_32x32x16_bf16 v[64:79], v[200:203], v[232:235], v[64:79]
	v_mfma_f32_32x32x16_bf16 v[0:15], v[208:211], v[232:235], v[0:15]
	ds_read_b128 v[232:235], v184 offset:4704
	s_setprio 0
	global_load_dwordx4 v[200:203], v[152:153], off offset:3840
	global_load_dwordx4 v[208:211], v[156:157], off offset:3840
	s_setprio 1
	s_waitcnt lgkmcnt(1)
	v_mfma_f32_32x32x16_bf16 v[112:127], v[212:215], v[228:231], v[112:127]
	v_mfma_f32_32x32x16_bf16 v[48:63], v[216:219], v[228:231], v[48:63]
	s_waitcnt lgkmcnt(0)
	v_mfma_f32_32x32x16_bf16 v[96:111], v[212:215], v[232:235], v[96:111]
	v_mfma_f32_32x32x16_bf16 v[32:47], v[216:219], v[232:235], v[32:47]
	ds_read_b128 v[228:231], v184 offset:9312
	ds_read_b128 v[232:235], v184 offset:13920
	s_waitcnt lgkmcnt(1)
	v_mfma_f32_32x32x16_bf16 v[80:95], v[212:215], v[228:231], v[80:95]
	v_mfma_f32_32x32x16_bf16 v[16:31], v[216:219], v[228:231], v[16:31]
	s_waitcnt lgkmcnt(0)
	v_mfma_f32_32x32x16_bf16 v[64:79], v[212:215], v[232:235], v[64:79]
	v_mfma_f32_32x32x16_bf16 v[0:15], v[216:219], v[232:235], v[0:15]
	s_setprio 0
	s_barrier
; template <bool trans>
; DI void gemm_core(const GTile& tl, const GTile& nx, bool has_next  , bool chain  , bool pre, u32x4 (&ra)[4], u32x4 (&rb)[4], char* smem, f32x16 (&acc)[2][4]) {
;     ...
;   const int nk = K / 64;
;   if (!pre) { G_LOAD(0); G_STORE(0); G_LOAD(1); }
;   for (int kt = 0; kt < nk; ++kt) {
;     __syncthreads();
;     G_COMPUTE(kt & 1, kt);
;   }
	global_load_dwordx4 v[128:131], v[128:129], off offset:3968
	s_nop 0
	global_load_dwordx4 v[132:135], v[132:133], off offset:3968
	s_waitcnt vmcnt(9)
	ds_write_b128 v191, v[178:181]
	s_waitcnt vmcnt(8)
	ds_write_b128 v191, v[220:223] offset:36864
	ds_read_b128 v[178:181], v169
	ds_read_b128 v[212:215], v169 offset:4608
	ds_read_b128 v[216:219], v168
	ds_read_b128 v[220:223], v168 offset:4608
	s_setprio 1
	s_waitcnt lgkmcnt(1)
	v_mfma_f32_32x32x16_bf16 v[112:127], v[178:181], v[216:219], v[112:127]
	v_mfma_f32_32x32x16_bf16 v[48:63], v[212:215], v[216:219], v[48:63]
	s_waitcnt lgkmcnt(0)
	v_mfma_f32_32x32x16_bf16 v[96:111], v[178:181], v[220:223], v[96:111]
	v_mfma_f32_32x32x16_bf16 v[32:47], v[212:215], v[220:223], v[32:47]
	ds_read_b128 v[216:219], v168 offset:9216
	ds_read_b128 v[220:223], v168 offset:13824
	s_waitcnt lgkmcnt(1)
	v_mfma_f32_32x32x16_bf16 v[80:95], v[178:181], v[216:219], v[80:95]
	v_mfma_f32_32x32x16_bf16 v[16:31], v[212:215], v[216:219], v[16:31]
	s_waitcnt lgkmcnt(0)
	v_mfma_f32_32x32x16_bf16 v[64:79], v[178:181], v[220:223], v[64:79]
	v_mfma_f32_32x32x16_bf16 v[0:15], v[212:215], v[220:223], v[0:15]
	s_setprio 0
	global_load_dwordx4 v[136:139], v[136:137], off offset:3968
	s_nop 0
	global_load_dwordx4 v[140:143], v[140:141], off offset:3968
	s_waitcnt vmcnt(9)
	ds_write_b128 v191, v[172:175] offset:9216
	s_waitcnt vmcnt(8)
	ds_write_b128 v191, v[224:227] offset:46080
	ds_read_b128 v[172:175], v169 offset:32
	ds_read_b128 v[178:181], v169 offset:4640
	ds_read_b128 v[212:215], v168 offset:32
	ds_read_b128 v[216:219], v168 offset:4640
	s_setprio 1
	s_waitcnt lgkmcnt(1)
	v_mfma_f32_32x32x16_bf16 v[112:127], v[172:175], v[212:215], v[112:127]
	v_mfma_f32_32x32x16_bf16 v[48:63], v[178:181], v[212:215], v[48:63]
	s_waitcnt lgkmcnt(0)
	v_mfma_f32_32x32x16_bf16 v[96:111], v[172:175], v[216:219], v[96:111]
	v_mfma_f32_32x32x16_bf16 v[32:47], v[178:181], v[216:219], v[32:47]
	ds_read_b128 v[212:215], v168 offset:9248
	ds_read_b128 v[216:219], v168 offset:13856
	s_waitcnt lgkmcnt(1)
	v_mfma_f32_32x32x16_bf16 v[80:95], v[172:175], v[212:215], v[80:95]
	v_mfma_f32_32x32x16_bf16 v[16:31], v[178:181], v[212:215], v[16:31]
	s_waitcnt lgkmcnt(0)
	v_mfma_f32_32x32x16_bf16 v[64:79], v[172:175], v[216:219], v[64:79]
	v_mfma_f32_32x32x16_bf16 v[0:15], v[178:181], v[216:219], v[0:15]
	s_setprio 0
	global_load_dwordx4 v[144:147], v[144:145], off offset:3968
	s_nop 0
	global_load_dwordx4 v[148:151], v[148:149], off offset:3968
	s_waitcnt vmcnt(9)
	ds_write_b128 v191, v[158:161] offset:18432
	s_waitcnt vmcnt(8)
	ds_write_b128 v191, v[162:165] offset:55296
	ds_read_b128 v[158:161], v169 offset:64
	ds_read_b128 v[162:165], v169 offset:4672
	ds_read_b128 v[172:175], v168 offset:64
	ds_read_b128 v[178:181], v168 offset:4672
	s_setprio 1
	s_waitcnt lgkmcnt(1)
	v_mfma_f32_32x32x16_bf16 v[112:127], v[158:161], v[172:175], v[112:127]
	v_mfma_f32_32x32x16_bf16 v[48:63], v[162:165], v[172:175], v[48:63]
	s_waitcnt lgkmcnt(0)
	v_mfma_f32_32x32x16_bf16 v[96:111], v[158:161], v[178:181], v[96:111]
	v_mfma_f32_32x32x16_bf16 v[32:47], v[162:165], v[178:181], v[32:47]
	ds_read_b128 v[172:175], v168 offset:9280
	ds_read_b128 v[178:181], v168 offset:13888
	s_waitcnt lgkmcnt(1)
	v_mfma_f32_32x32x16_bf16 v[80:95], v[158:161], v[172:175], v[80:95]
	v_mfma_f32_32x32x16_bf16 v[16:31], v[162:165], v[172:175], v[16:31]
	s_waitcnt lgkmcnt(0)
	v_mfma_f32_32x32x16_bf16 v[64:79], v[158:161], v[178:181], v[64:79]
	v_mfma_f32_32x32x16_bf16 v[0:15], v[162:165], v[178:181], v[0:15]
	s_setprio 0
	global_load_dwordx4 v[152:155], v[152:153], off offset:3968
	s_nop 0
	global_load_dwordx4 v[156:159], v[156:157], off offset:3968
	s_waitcnt vmcnt(9)
	ds_write_b128 v191, v[200:203] offset:27648
	s_waitcnt vmcnt(8)
	ds_write_b128 v191, v[208:211] offset:64512
	ds_read_b128 v[160:163], v169 offset:96
	ds_read_b128 v[164:167], v169 offset:4704
	ds_read_b128 v[172:175], v168 offset:96
	ds_read_b128 v[178:181], v168 offset:4704
	s_setprio 1
	s_waitcnt lgkmcnt(1)
	v_mfma_f32_32x32x16_bf16 v[112:127], v[160:163], v[172:175], v[112:127]
	v_mfma_f32_32x32x16_bf16 v[48:63], v[164:167], v[172:175], v[48:63]
	s_waitcnt lgkmcnt(0)
	v_mfma_f32_32x32x16_bf16 v[96:111], v[160:163], v[178:181], v[96:111]
	v_mfma_f32_32x32x16_bf16 v[32:47], v[164:167], v[178:181], v[32:47]
	ds_read_b128 v[172:175], v168 offset:9312
	ds_read_b128 v[178:181], v168 offset:13920
	s_waitcnt lgkmcnt(1)
	v_mfma_f32_32x32x16_bf16 v[80:95], v[160:163], v[172:175], v[80:95]
	v_mfma_f32_32x32x16_bf16 v[16:31], v[164:167], v[172:175], v[16:31]
	s_waitcnt lgkmcnt(0)
	v_mfma_f32_32x32x16_bf16 v[64:79], v[160:163], v[178:181], v[64:79]
	v_mfma_f32_32x32x16_bf16 v[0:15], v[164:167], v[178:181], v[0:15]
	s_setprio 0
	s_and_b64 vcc, exec, s[10:11]
	s_barrier
	s_waitcnt vmcnt(7)
	ds_write_b128 v195, v[128:131]
	s_waitcnt vmcnt(6)
	ds_write_b128 v196, v[132:135]
	s_cbranch_vccnz .LBB0_1639
	global_load_dwordx4 v[128:131], v[188:189], off
	global_load_dwordx4 v[132:135], v[186:187], off
